# variant: keep s_setprio 1 across the 4 k-steps of each software-pipelined k-iteration (drop the per-k-step 0/1 toggles)
# baseline (speedup 1.0000x reference)
; template <bool trans>
; DI void gemm_core(const GTile& tl, const GTile& nx, bool has_next  , bool chain  , bool pre, u32x4 (&ra)[4], u32x4 (&rb)[4], char* smem, f32x16 (&acc)[2][4]) {
;     ...
;   const int nk = K / 64;
;   if (!pre) { G_LOAD(0); G_STORE(0); G_LOAD(1); }
;   for (int kt = 0; kt < nk; ++kt) {
;     __syncthreads();
;     G_COMPUTE(kt & 1, kt);
.LBB0_103:
	v_lshl_add_u64 v[190:191], s[0:1], 0, v[192:193]
	v_lshl_add_u64 v[188:189], s[6:7], 0, v[192:193]
	s_waitcnt lgkmcnt(0)
	s_barrier
	global_load_dwordx4 v[218:221], v[190:191], off offset:256
	global_load_dwordx4 v[222:225], v[188:189], off offset:256
	s_lshr_b32 s1, s33, 1
	s_and_b32 s0, s33, 0xc0
	v_and_b32_e32 v10, 31, v8
	s_and_b32 s1, s1, 0xfffff80
	v_or_b32_e32 v12, s1, v10
	v_or_b32_e32 v10, s0, v10
	v_add3_u32 v215, 16, v11, v9
	v_lshrrev_b32_e32 v8, 1, v8
	v_mul_u32_u24_e32 v242, 0x90, v10
	v_and_b32_e32 v243, 16, v8
	v_add_u32_e32 v209, 0x12000, v215
	v_mul_lo_u32 v208, v12, s45
	v_add3_u32 v205, 16, v242, v243
	v_add_u32_e32 v210, 0x1b000, v215
	ds_write_b128 v209, v[0:3]
	s_waitcnt vmcnt(6)
	ds_write_b128 v210, v[4:7]
	v_add3_u32 v204, 16, v208, v243
	ds_read_b128 v[0:3], v205 offset:36864
	ds_read_b128 v[4:7], v205 offset:41472
	ds_read_b128 v[8:11], v204
	ds_read_b128 v[12:15], v204 offset:4608
	v_lshl_add_u64 v[184:185], v[190:191], 0, s[42:43]
	v_lshl_add_u64 v[186:187], s[28:29], 0, v[192:193]
	v_lshl_add_u64 v[194:195], v[190:191], 0, s[34:35]
	v_lshl_add_u64 v[196:197], s[26:27], 0, v[192:193]
	s_setprio 1
	s_waitcnt lgkmcnt(1)
	v_mfma_f32_32x32x16_bf16 v[112:127], v[8:11], v[0:3], 0
	v_mfma_f32_32x32x16_bf16 v[48:63], v[8:11], v[4:7], 0
	s_waitcnt lgkmcnt(0)
	v_mfma_f32_32x32x16_bf16 v[96:111], v[12:15], v[0:3], 0
	v_mfma_f32_32x32x16_bf16 v[32:47], v[12:15], v[4:7], 0
	ds_read_b128 v[8:11], v204 offset:9216
	ds_read_b128 v[12:15], v204 offset:13824
	s_waitcnt lgkmcnt(1)
	v_mfma_f32_32x32x16_bf16 v[80:95], v[8:11], v[0:3], 0
	v_mfma_f32_32x32x16_bf16 v[16:31], v[8:11], v[4:7], 0
	s_waitcnt lgkmcnt(0)
	v_mfma_f32_32x32x16_bf16 v[64:79], v[12:15], v[0:3], 0
	v_mfma_f32_32x32x16_bf16 v[0:15], v[12:15], v[4:7], 0
	s_setprio 0
	global_load_dwordx4 v[226:229], v[194:195], off offset:256
	global_load_dwordx4 v[230:233], v[196:197], off offset:256
	v_add_u32_e32 v212, 0x14400, v215
	v_add_u32_e32 v211, 0x1d400, v215
	ds_write_b128 v212, v[176:179]
	s_waitcnt vmcnt(7)
	ds_write_b128 v211, v[180:183]
	ds_read_b128 v[176:179], v205 offset:36896
	ds_read_b128 v[180:183], v205 offset:41504
	ds_read_b128 v[198:201], v204 offset:32
	ds_read_b128 v[234:237], v204 offset:4640
	s_setprio 1
	s_waitcnt lgkmcnt(1)
	v_mfma_f32_32x32x16_bf16 v[112:127], v[198:201], v[176:179], v[112:127]
	v_mfma_f32_32x32x16_bf16 v[48:63], v[198:201], v[180:183], v[48:63]
	s_waitcnt lgkmcnt(0)
	v_mfma_f32_32x32x16_bf16 v[96:111], v[234:237], v[176:179], v[96:111]
	v_mfma_f32_32x32x16_bf16 v[32:47], v[234:237], v[180:183], v[32:47]
	ds_read_b128 v[198:201], v204 offset:9248
	ds_read_b128 v[234:237], v204 offset:13856
	s_waitcnt lgkmcnt(1)
	v_mfma_f32_32x32x16_bf16 v[80:95], v[198:201], v[176:179], v[80:95]
	v_mfma_f32_32x32x16_bf16 v[16:31], v[198:201], v[180:183], v[16:31]
	s_waitcnt lgkmcnt(0)
	v_mfma_f32_32x32x16_bf16 v[64:79], v[234:237], v[176:179], v[64:79]
	v_mfma_f32_32x32x16_bf16 v[0:15], v[234:237], v[180:183], v[0:15]
	s_setprio 0
	global_load_dwordx4 v[176:179], v[184:185], off offset:256
	global_load_dwordx4 v[180:183], v[186:187], off offset:256
	v_add_u32_e32 v214, 0x16800, v215
	v_add_u32_e32 v213, 0x1f800, v215
	ds_write_b128 v214, v[168:171]
	s_waitcnt vmcnt(8)
	ds_write_b128 v213, v[172:175]
	ds_read_b128 v[168:171], v205 offset:36928
	ds_read_b128 v[172:175], v205 offset:41536
	ds_read_b128 v[198:201], v204 offset:64
	ds_read_b128 v[234:237], v204 offset:4672
	s_setprio 1
	s_waitcnt lgkmcnt(1)
	v_mfma_f32_32x32x16_bf16 v[112:127], v[198:201], v[168:171], v[112:127]
	v_mfma_f32_32x32x16_bf16 v[48:63], v[198:201], v[172:175], v[48:63]
	s_waitcnt lgkmcnt(0)
	v_mfma_f32_32x32x16_bf16 v[96:111], v[234:237], v[168:171], v[96:111]
	v_mfma_f32_32x32x16_bf16 v[32:47], v[234:237], v[172:175], v[32:47]
	ds_read_b128 v[198:201], v204 offset:9280
	ds_read_b128 v[234:237], v204 offset:13888
	s_waitcnt lgkmcnt(1)
	v_mfma_f32_32x32x16_bf16 v[80:95], v[198:201], v[168:171], v[80:95]
	v_mfma_f32_32x32x16_bf16 v[16:31], v[198:201], v[172:175], v[16:31]
	s_waitcnt lgkmcnt(0)
	v_mfma_f32_32x32x16_bf16 v[64:79], v[234:237], v[168:171], v[64:79]
	v_mfma_f32_32x32x16_bf16 v[0:15], v[234:237], v[172:175], v[0:15]
	s_setprio 0
	v_add_co_u32_e32 v198, vcc, s44, v190
	v_add_u32_e32 v217, 0x18c00, v215
	s_nop 0
	v_addc_co_u32_e32 v199, vcc, 0, v191, vcc
	v_add_co_u32_e32 v200, vcc, s44, v188
	v_add_u32_e32 v216, 0x21c00, v215
	s_nop 0
	v_addc_co_u32_e32 v201, vcc, 0, v189, vcc
	global_load_dwordx4 v[168:171], v[198:199], off offset:256
	global_load_dwordx4 v[172:175], v[200:201], off offset:256
	s_waitcnt vmcnt(8)
	ds_write_b128 v217, v[164:167]
	ds_write_b128 v216, v[160:163]
	ds_read_b128 v[160:163], v205 offset:36960
	ds_read_b128 v[164:167], v205 offset:41568
	ds_read_b128 v[234:237], v204 offset:96
	ds_read_b128 v[238:241], v204 offset:4704
	s_setprio 1
	s_waitcnt lgkmcnt(1)
	v_mfma_f32_32x32x16_bf16 v[112:127], v[234:237], v[160:163], v[112:127]
	v_mfma_f32_32x32x16_bf16 v[48:63], v[234:237], v[164:167], v[48:63]
	s_waitcnt lgkmcnt(0)
	v_mfma_f32_32x32x16_bf16 v[96:111], v[238:241], v[160:163], v[96:111]
	v_mfma_f32_32x32x16_bf16 v[32:47], v[238:241], v[164:167], v[32:47]
	ds_read_b128 v[234:237], v204 offset:9312
	ds_read_b128 v[238:241], v204 offset:13920
	s_waitcnt lgkmcnt(1)
	v_mfma_f32_32x32x16_bf16 v[80:95], v[234:237], v[160:163], v[80:95]
	v_mfma_f32_32x32x16_bf16 v[16:31], v[234:237], v[164:167], v[16:31]
	s_waitcnt lgkmcnt(0)
	v_mfma_f32_32x32x16_bf16 v[64:79], v[238:241], v[160:163], v[64:79]
	v_mfma_f32_32x32x16_bf16 v[0:15], v[238:241], v[164:167], v[0:15]
	s_setprio 0
	s_barrier
	global_load_dwordx4 v[160:163], v[190:191], off offset:384
	global_load_dwordx4 v[164:167], v[188:189], off offset:384
	s_add_i32 s0, 16, 0x12000
	v_add3_u32 v192, s0, v208, v243
	s_add_i32 s0, 16, 0x1b000
	v_add3_u32 v208, s0, v242, v243
	s_waitcnt vmcnt(9)
	ds_write_b128 v215, v[218:221]
	s_waitcnt vmcnt(8)
	ds_write_b128 v215, v[222:225] offset:36864
	ds_read_b128 v[218:221], v208
	ds_read_b128 v[222:225], v208 offset:4608
	ds_read_b128 v[234:237], v192
	ds_read_b128 v[238:241], v192 offset:4608
	s_setprio 1
	s_waitcnt lgkmcnt(1)
	v_mfma_f32_32x32x16_bf16 v[112:127], v[234:237], v[218:221], v[112:127]
	v_mfma_f32_32x32x16_bf16 v[48:63], v[234:237], v[222:225], v[48:63]
	s_waitcnt lgkmcnt(0)
	v_mfma_f32_32x32x16_bf16 v[96:111], v[238:241], v[218:221], v[96:111]
	v_mfma_f32_32x32x16_bf16 v[32:47], v[238:241], v[222:225], v[32:47]
	ds_read_b128 v[234:237], v192 offset:9216
	ds_read_b128 v[238:241], v192 offset:13824
	s_waitcnt lgkmcnt(1)
	v_mfma_f32_32x32x16_bf16 v[80:95], v[234:237], v[218:221], v[80:95]
	v_mfma_f32_32x32x16_bf16 v[16:31], v[234:237], v[222:225], v[16:31]
	s_waitcnt lgkmcnt(0)
	v_mfma_f32_32x32x16_bf16 v[64:79], v[238:241], v[218:221], v[64:79]
	v_mfma_f32_32x32x16_bf16 v[0:15], v[238:241], v[222:225], v[0:15]
	s_setprio 0
	global_load_dwordx4 v[218:221], v[194:195], off offset:384
	global_load_dwordx4 v[222:225], v[196:197], off offset:384
	s_waitcnt vmcnt(9)
	ds_write_b128 v215, v[226:229] offset:9216
	s_waitcnt vmcnt(8)
	ds_write_b128 v215, v[230:233] offset:46080
	ds_read_b128 v[226:229], v208 offset:32
	ds_read_b128 v[230:233], v208 offset:4640
	ds_read_b128 v[234:237], v192 offset:32
	ds_read_b128 v[238:241], v192 offset:4640
	s_setprio 1
	s_waitcnt lgkmcnt(1)
	v_mfma_f32_32x32x16_bf16 v[112:127], v[234:237], v[226:229], v[112:127]
	v_mfma_f32_32x32x16_bf16 v[48:63], v[234:237], v[230:233], v[48:63]
	s_waitcnt lgkmcnt(0)
	v_mfma_f32_32x32x16_bf16 v[96:111], v[238:241], v[226:229], v[96:111]
	v_mfma_f32_32x32x16_bf16 v[32:47], v[238:241], v[230:233], v[32:47]
	ds_read_b128 v[234:237], v192 offset:9248
	ds_read_b128 v[238:241], v192 offset:13856
	s_waitcnt lgkmcnt(1)
	v_mfma_f32_32x32x16_bf16 v[80:95], v[234:237], v[226:229], v[80:95]
	v_mfma_f32_32x32x16_bf16 v[16:31], v[234:237], v[230:233], v[16:31]
	s_waitcnt lgkmcnt(0)
	v_mfma_f32_32x32x16_bf16 v[64:79], v[238:241], v[226:229], v[64:79]
	v_mfma_f32_32x32x16_bf16 v[0:15], v[238:241], v[230:233], v[0:15]
	s_setprio 0
	global_load_dwordx4 v[226:229], v[184:185], off offset:384
	global_load_dwordx4 v[230:233], v[186:187], off offset:384
	s_waitcnt vmcnt(9)
	ds_write_b128 v215, v[176:179] offset:18432
	s_waitcnt vmcnt(8)
	ds_write_b128 v215, v[180:183] offset:55296
	ds_read_b128 v[176:179], v208 offset:64
	ds_read_b128 v[180:183], v208 offset:4672
	ds_read_b128 v[234:237], v192 offset:64
	ds_read_b128 v[238:241], v192 offset:4672
	s_setprio 1
	s_waitcnt lgkmcnt(1)
	v_mfma_f32_32x32x16_bf16 v[112:127], v[234:237], v[176:179], v[112:127]
	v_mfma_f32_32x32x16_bf16 v[48:63], v[234:237], v[180:183], v[48:63]
	s_waitcnt lgkmcnt(0)
	v_mfma_f32_32x32x16_bf16 v[96:111], v[238:241], v[176:179], v[96:111]
	v_mfma_f32_32x32x16_bf16 v[32:47], v[238:241], v[180:183], v[32:47]
	ds_read_b128 v[234:237], v192 offset:9280
	ds_read_b128 v[238:241], v192 offset:13888
	s_waitcnt lgkmcnt(1)
	v_mfma_f32_32x32x16_bf16 v[80:95], v[234:237], v[176:179], v[80:95]
	v_mfma_f32_32x32x16_bf16 v[16:31], v[234:237], v[180:183], v[16:31]
	s_waitcnt lgkmcnt(0)
	v_mfma_f32_32x32x16_bf16 v[64:79], v[238:241], v[176:179], v[64:79]
	v_mfma_f32_32x32x16_bf16 v[0:15], v[238:241], v[180:183], v[0:15]
	s_setprio 0
	global_load_dwordx4 v[176:179], v[198:199], off offset:384
	global_load_dwordx4 v[180:183], v[200:201], off offset:384
	s_waitcnt vmcnt(9)
	ds_write_b128 v215, v[168:171] offset:27648
	s_waitcnt vmcnt(8)
	ds_write_b128 v215, v[172:175] offset:64512
	ds_read_b128 v[168:171], v208 offset:96
	ds_read_b128 v[172:175], v208 offset:4704
	ds_read_b128 v[234:237], v192 offset:96
	ds_read_b128 v[238:241], v192 offset:4704
	s_setprio 1
	s_waitcnt lgkmcnt(1)
	v_mfma_f32_32x32x16_bf16 v[112:127], v[234:237], v[168:171], v[112:127]
	v_mfma_f32_32x32x16_bf16 v[48:63], v[234:237], v[172:175], v[48:63]
	s_waitcnt lgkmcnt(0)
	v_mfma_f32_32x32x16_bf16 v[96:111], v[238:241], v[168:171], v[96:111]
	v_mfma_f32_32x32x16_bf16 v[32:47], v[238:241], v[172:175], v[32:47]
	ds_read_b128 v[234:237], v192 offset:9312
	ds_read_b128 v[238:241], v192 offset:13920
	s_waitcnt lgkmcnt(1)
	v_mfma_f32_32x32x16_bf16 v[80:95], v[234:237], v[168:171], v[80:95]
	v_mfma_f32_32x32x16_bf16 v[16:31], v[234:237], v[172:175], v[16:31]
	s_waitcnt lgkmcnt(0)
	v_mfma_f32_32x32x16_bf16 v[64:79], v[238:241], v[168:171], v[64:79]
	v_mfma_f32_32x32x16_bf16 v[0:15], v[238:241], v[172:175], v[0:15]
	s_setprio 0
	s_barrier
	global_load_dwordx4 v[168:171], v[190:191], off offset:512
	global_load_dwordx4 v[172:175], v[188:189], off offset:512
	s_waitcnt vmcnt(9)
	ds_write_b128 v209, v[160:163]
	s_waitcnt vmcnt(8)
	ds_write_b128 v210, v[164:167]
	ds_read_b128 v[160:163], v205 offset:36864
	ds_read_b128 v[164:167], v205 offset:41472
	ds_read_b128 v[234:237], v204
	ds_read_b128 v[238:241], v204 offset:4608
	s_setprio 1
	s_waitcnt lgkmcnt(1)
	v_mfma_f32_32x32x16_bf16 v[112:127], v[234:237], v[160:163], v[112:127]
	v_mfma_f32_32x32x16_bf16 v[48:63], v[234:237], v[164:167], v[48:63]
	s_waitcnt lgkmcnt(0)
	v_mfma_f32_32x32x16_bf16 v[96:111], v[238:241], v[160:163], v[96:111]
	v_mfma_f32_32x32x16_bf16 v[32:47], v[238:241], v[164:167], v[32:47]
	ds_read_b128 v[234:237], v204 offset:9216
	ds_read_b128 v[238:241], v204 offset:13824
	s_waitcnt vmcnt(7)
	ds_write_b128 v212, v[218:221]
	s_waitcnt vmcnt(6)
	ds_write_b128 v211, v[222:225]
	ds_read_b128 v[218:221], v205 offset:36896
	ds_read_b128 v[222:225], v205 offset:41504
	s_waitcnt lgkmcnt(5)
	v_mfma_f32_32x32x16_bf16 v[80:95], v[234:237], v[160:163], v[80:95]
	v_mfma_f32_32x32x16_bf16 v[16:31], v[234:237], v[164:167], v[16:31]
	ds_read_b128 v[234:237], v204 offset:32
	s_waitcnt lgkmcnt(5)
	v_mfma_f32_32x32x16_bf16 v[64:79], v[238:241], v[160:163], v[64:79]
	v_mfma_f32_32x32x16_bf16 v[0:15], v[238:241], v[164:167], v[0:15]
	ds_read_b128 v[238:241], v204 offset:4640
	global_load_dwordx4 v[160:163], v[194:195], off offset:512
	global_load_dwordx4 v[164:167], v[196:197], off offset:512
	s_waitcnt lgkmcnt(1)
	v_mfma_f32_32x32x16_bf16 v[112:127], v[234:237], v[218:221], v[112:127]
	v_mfma_f32_32x32x16_bf16 v[48:63], v[234:237], v[222:225], v[48:63]
	s_waitcnt lgkmcnt(0)
	v_mfma_f32_32x32x16_bf16 v[96:111], v[238:241], v[218:221], v[96:111]
	v_mfma_f32_32x32x16_bf16 v[32:47], v[238:241], v[222:225], v[32:47]
	ds_read_b128 v[234:237], v204 offset:9248
	ds_read_b128 v[238:241], v204 offset:13856
	s_waitcnt vmcnt(7)
	ds_write_b128 v214, v[226:229]
	s_waitcnt vmcnt(6)
	ds_write_b128 v213, v[230:233]
	ds_read_b128 v[226:229], v205 offset:36928
	ds_read_b128 v[230:233], v205 offset:41536
	s_waitcnt lgkmcnt(5)
	v_mfma_f32_32x32x16_bf16 v[80:95], v[234:237], v[218:221], v[80:95]
	v_mfma_f32_32x32x16_bf16 v[16:31], v[234:237], v[222:225], v[16:31]
	ds_read_b128 v[234:237], v204 offset:64
	s_waitcnt lgkmcnt(5)
	v_mfma_f32_32x32x16_bf16 v[64:79], v[238:241], v[218:221], v[64:79]
	v_mfma_f32_32x32x16_bf16 v[0:15], v[238:241], v[222:225], v[0:15]
	ds_read_b128 v[238:241], v204 offset:4672
	global_load_dwordx4 v[218:221], v[184:185], off offset:512
	global_load_dwordx4 v[222:225], v[186:187], off offset:512
	s_waitcnt lgkmcnt(1)
	v_mfma_f32_32x32x16_bf16 v[112:127], v[234:237], v[226:229], v[112:127]
	v_mfma_f32_32x32x16_bf16 v[48:63], v[234:237], v[230:233], v[48:63]
	s_waitcnt lgkmcnt(0)
	v_mfma_f32_32x32x16_bf16 v[96:111], v[238:241], v[226:229], v[96:111]
	v_mfma_f32_32x32x16_bf16 v[32:47], v[238:241], v[230:233], v[32:47]
	ds_read_b128 v[234:237], v204 offset:9280
	ds_read_b128 v[238:241], v204 offset:13888
	s_waitcnt vmcnt(7)
	ds_write_b128 v217, v[176:179]
	s_waitcnt vmcnt(6)
	ds_write_b128 v216, v[180:183]
	ds_read_b128 v[176:179], v205 offset:36960
	ds_read_b128 v[180:183], v205 offset:41568
	s_waitcnt lgkmcnt(5)
	v_mfma_f32_32x32x16_bf16 v[80:95], v[234:237], v[226:229], v[80:95]
	v_mfma_f32_32x32x16_bf16 v[16:31], v[234:237], v[230:233], v[16:31]
	ds_read_b128 v[234:237], v204 offset:96
	s_waitcnt lgkmcnt(5)
	v_mfma_f32_32x32x16_bf16 v[64:79], v[238:241], v[226:229], v[64:79]
	v_mfma_f32_32x32x16_bf16 v[0:15], v[238:241], v[230:233], v[0:15]
	ds_read_b128 v[238:241], v204 offset:4704
	global_load_dwordx4 v[226:229], v[198:199], off offset:512
	global_load_dwordx4 v[230:233], v[200:201], off offset:512
	s_waitcnt lgkmcnt(1)
	v_mfma_f32_32x32x16_bf16 v[112:127], v[234:237], v[176:179], v[112:127]
	v_mfma_f32_32x32x16_bf16 v[48:63], v[234:237], v[180:183], v[48:63]
	s_waitcnt lgkmcnt(0)
	v_mfma_f32_32x32x16_bf16 v[96:111], v[238:241], v[176:179], v[96:111]
	v_mfma_f32_32x32x16_bf16 v[32:47], v[238:241], v[180:183], v[32:47]
	ds_read_b128 v[234:237], v204 offset:9312
	ds_read_b128 v[238:241], v204 offset:13920
	s_waitcnt lgkmcnt(1)
	v_mfma_f32_32x32x16_bf16 v[80:95], v[234:237], v[176:179], v[80:95]
	v_mfma_f32_32x32x16_bf16 v[16:31], v[234:237], v[180:183], v[16:31]
	s_waitcnt lgkmcnt(0)
	v_mfma_f32_32x32x16_bf16 v[64:79], v[238:241], v[176:179], v[64:79]
	v_mfma_f32_32x32x16_bf16 v[0:15], v[238:241], v[180:183], v[0:15]
	s_setprio 0
	s_barrier
	global_load_dwordx4 v[176:179], v[190:191], off offset:640
	global_load_dwordx4 v[180:183], v[188:189], off offset:640
	s_waitcnt vmcnt(9)
	ds_write_b128 v215, v[168:171]
	s_waitcnt vmcnt(8)
	ds_write_b128 v215, v[172:175] offset:36864
	ds_read_b128 v[168:171], v208
	ds_read_b128 v[172:175], v208 offset:4608
	ds_read_b128 v[234:237], v192
	ds_read_b128 v[238:241], v192 offset:4608
	s_setprio 1
	s_waitcnt lgkmcnt(1)
	v_mfma_f32_32x32x16_bf16 v[112:127], v[234:237], v[168:171], v[112:127]
	v_mfma_f32_32x32x16_bf16 v[48:63], v[234:237], v[172:175], v[48:63]
	s_waitcnt lgkmcnt(0)
	v_mfma_f32_32x32x16_bf16 v[96:111], v[238:241], v[168:171], v[96:111]
	v_mfma_f32_32x32x16_bf16 v[32:47], v[238:241], v[172:175], v[32:47]
	ds_read_b128 v[234:237], v192 offset:9216
	ds_read_b128 v[238:241], v192 offset:13824
	s_waitcnt vmcnt(7)
	ds_write_b128 v215, v[160:163] offset:9216
	s_waitcnt vmcnt(6)
	ds_write_b128 v215, v[164:167] offset:46080
	ds_read_b128 v[160:163], v208 offset:32
	ds_read_b128 v[164:167], v208 offset:4640
	s_waitcnt lgkmcnt(5)
	v_mfma_f32_32x32x16_bf16 v[80:95], v[234:237], v[168:171], v[80:95]
	v_mfma_f32_32x32x16_bf16 v[16:31], v[234:237], v[172:175], v[16:31]
	ds_read_b128 v[234:237], v192 offset:32
	s_waitcnt lgkmcnt(5)
	v_mfma_f32_32x32x16_bf16 v[64:79], v[238:241], v[168:171], v[64:79]
	v_mfma_f32_32x32x16_bf16 v[0:15], v[238:241], v[172:175], v[0:15]
	ds_read_b128 v[238:241], v192 offset:4640
	global_load_dwordx4 v[168:171], v[194:195], off offset:640
	global_load_dwordx4 v[172:175], v[196:197], off offset:640
	s_waitcnt lgkmcnt(1)
	v_mfma_f32_32x32x16_bf16 v[112:127], v[234:237], v[160:163], v[112:127]
	v_mfma_f32_32x32x16_bf16 v[48:63], v[234:237], v[164:167], v[48:63]
	s_waitcnt lgkmcnt(0)
	v_mfma_f32_32x32x16_bf16 v[96:111], v[238:241], v[160:163], v[96:111]
	v_mfma_f32_32x32x16_bf16 v[32:47], v[238:241], v[164:167], v[32:47]
	ds_read_b128 v[234:237], v192 offset:9248
	ds_read_b128 v[238:241], v192 offset:13856
	s_waitcnt vmcnt(7)
	ds_write_b128 v215, v[218:221] offset:18432
	s_waitcnt vmcnt(6)
	ds_write_b128 v215, v[222:225] offset:55296
	ds_read_b128 v[218:221], v208 offset:64
	ds_read_b128 v[222:225], v208 offset:4672
	s_waitcnt lgkmcnt(5)
	v_mfma_f32_32x32x16_bf16 v[80:95], v[234:237], v[160:163], v[80:95]
	v_mfma_f32_32x32x16_bf16 v[16:31], v[234:237], v[164:167], v[16:31]
	ds_read_b128 v[234:237], v192 offset:64
	s_waitcnt lgkmcnt(5)
	v_mfma_f32_32x32x16_bf16 v[64:79], v[238:241], v[160:163], v[64:79]
	v_mfma_f32_32x32x16_bf16 v[0:15], v[238:241], v[164:167], v[0:15]
	ds_read_b128 v[238:241], v192 offset:4672
	global_load_dwordx4 v[160:163], v[184:185], off offset:640
	global_load_dwordx4 v[164:167], v[186:187], off offset:640
	s_waitcnt lgkmcnt(1)
	v_mfma_f32_32x32x16_bf16 v[112:127], v[234:237], v[218:221], v[112:127]
	v_mfma_f32_32x32x16_bf16 v[48:63], v[234:237], v[222:225], v[48:63]
	s_waitcnt lgkmcnt(0)
	v_mfma_f32_32x32x16_bf16 v[96:111], v[238:241], v[218:221], v[96:111]
	v_mfma_f32_32x32x16_bf16 v[32:47], v[238:241], v[222:225], v[32:47]
	ds_read_b128 v[234:237], v192 offset:9280
	ds_read_b128 v[238:241], v192 offset:13888
	s_waitcnt vmcnt(7)
	ds_write_b128 v215, v[226:229] offset:27648
	s_waitcnt vmcnt(6)
	ds_write_b128 v215, v[230:233] offset:64512
	ds_read_b128 v[226:229], v208 offset:96
	ds_read_b128 v[230:233], v208 offset:4704
	s_waitcnt lgkmcnt(5)
	v_mfma_f32_32x32x16_bf16 v[80:95], v[234:237], v[218:221], v[80:95]
	v_mfma_f32_32x32x16_bf16 v[16:31], v[234:237], v[222:225], v[16:31]
	ds_read_b128 v[234:237], v192 offset:96
	s_waitcnt lgkmcnt(5)
	v_mfma_f32_32x32x16_bf16 v[64:79], v[238:241], v[218:221], v[64:79]
	v_mfma_f32_32x32x16_bf16 v[0:15], v[238:241], v[222:225], v[0:15]
	ds_read_b128 v[238:241], v192 offset:4704
	global_load_dwordx4 v[218:221], v[198:199], off offset:640
	global_load_dwordx4 v[222:225], v[200:201], off offset:640
	s_waitcnt lgkmcnt(1)
	v_mfma_f32_32x32x16_bf16 v[112:127], v[234:237], v[226:229], v[112:127]
	v_mfma_f32_32x32x16_bf16 v[48:63], v[234:237], v[230:233], v[48:63]
	s_waitcnt lgkmcnt(0)
	v_mfma_f32_32x32x16_bf16 v[96:111], v[238:241], v[226:229], v[96:111]
	v_mfma_f32_32x32x16_bf16 v[32:47], v[238:241], v[230:233], v[32:47]
	ds_read_b128 v[234:237], v192 offset:9312
	ds_read_b128 v[238:241], v192 offset:13920
	s_waitcnt lgkmcnt(1)
	v_mfma_f32_32x32x16_bf16 v[80:95], v[234:237], v[226:229], v[80:95]
	v_mfma_f32_32x32x16_bf16 v[16:31], v[234:237], v[230:233], v[16:31]
	s_waitcnt lgkmcnt(0)
	v_mfma_f32_32x32x16_bf16 v[64:79], v[238:241], v[226:229], v[64:79]
	v_mfma_f32_32x32x16_bf16 v[0:15], v[238:241], v[230:233], v[0:15]
	s_setprio 0
	s_barrier
	global_load_dwordx4 v[226:229], v[190:191], off offset:768
	global_load_dwordx4 v[230:233], v[188:189], off offset:768
	s_waitcnt vmcnt(9)
	ds_write_b128 v209, v[176:179]
	s_waitcnt vmcnt(8)
	ds_write_b128 v210, v[180:183]
	ds_read_b128 v[176:179], v205 offset:36864
	ds_read_b128 v[180:183], v205 offset:41472
	ds_read_b128 v[234:237], v204
	ds_read_b128 v[238:241], v204 offset:4608
	s_setprio 1
	s_waitcnt lgkmcnt(1)
	v_mfma_f32_32x32x16_bf16 v[112:127], v[234:237], v[176:179], v[112:127]
	v_mfma_f32_32x32x16_bf16 v[48:63], v[234:237], v[180:183], v[48:63]
	s_waitcnt lgkmcnt(0)
	v_mfma_f32_32x32x16_bf16 v[96:111], v[238:241], v[176:179], v[96:111]
	v_mfma_f32_32x32x16_bf16 v[32:47], v[238:241], v[180:183], v[32:47]
	ds_read_b128 v[234:237], v204 offset:9216
	ds_read_b128 v[238:241], v204 offset:13824
	s_waitcnt vmcnt(7)
	ds_write_b128 v212, v[168:171]
	s_waitcnt vmcnt(6)
	ds_write_b128 v211, v[172:175]
	ds_read_b128 v[168:171], v205 offset:36896
	ds_read_b128 v[172:175], v205 offset:41504
	s_waitcnt lgkmcnt(5)
	v_mfma_f32_32x32x16_bf16 v[80:95], v[234:237], v[176:179], v[80:95]
	v_mfma_f32_32x32x16_bf16 v[16:31], v[234:237], v[180:183], v[16:31]
	ds_read_b128 v[234:237], v204 offset:32
	s_waitcnt lgkmcnt(5)
	v_mfma_f32_32x32x16_bf16 v[64:79], v[238:241], v[176:179], v[64:79]
	v_mfma_f32_32x32x16_bf16 v[0:15], v[238:241], v[180:183], v[0:15]
	ds_read_b128 v[238:241], v204 offset:4640
	global_load_dwordx4 v[176:179], v[194:195], off offset:768
	global_load_dwordx4 v[180:183], v[196:197], off offset:768
	s_waitcnt lgkmcnt(1)
	v_mfma_f32_32x32x16_bf16 v[112:127], v[234:237], v[168:171], v[112:127]
	v_mfma_f32_32x32x16_bf16 v[48:63], v[234:237], v[172:175], v[48:63]
	s_waitcnt lgkmcnt(0)
	v_mfma_f32_32x32x16_bf16 v[96:111], v[238:241], v[168:171], v[96:111]
	v_mfma_f32_32x32x16_bf16 v[32:47], v[238:241], v[172:175], v[32:47]
	ds_read_b128 v[234:237], v204 offset:9248
	ds_read_b128 v[238:241], v204 offset:13856
	s_waitcnt vmcnt(7)
	ds_write_b128 v214, v[160:163]
	s_waitcnt vmcnt(6)
	ds_write_b128 v213, v[164:167]
	ds_read_b128 v[160:163], v205 offset:36928
	ds_read_b128 v[164:167], v205 offset:41536
	s_waitcnt lgkmcnt(5)
	v_mfma_f32_32x32x16_bf16 v[80:95], v[234:237], v[168:171], v[80:95]
	v_mfma_f32_32x32x16_bf16 v[16:31], v[234:237], v[172:175], v[16:31]
	ds_read_b128 v[234:237], v204 offset:64
	s_waitcnt lgkmcnt(5)
	v_mfma_f32_32x32x16_bf16 v[64:79], v[238:241], v[168:171], v[64:79]
	v_mfma_f32_32x32x16_bf16 v[0:15], v[238:241], v[172:175], v[0:15]
	ds_read_b128 v[238:241], v204 offset:4672
	global_load_dwordx4 v[168:171], v[184:185], off offset:768
	global_load_dwordx4 v[172:175], v[186:187], off offset:768
	s_waitcnt lgkmcnt(1)
	v_mfma_f32_32x32x16_bf16 v[112:127], v[234:237], v[160:163], v[112:127]
	v_mfma_f32_32x32x16_bf16 v[48:63], v[234:237], v[164:167], v[48:63]
	s_waitcnt lgkmcnt(0)
	v_mfma_f32_32x32x16_bf16 v[96:111], v[238:241], v[160:163], v[96:111]
	v_mfma_f32_32x32x16_bf16 v[32:47], v[238:241], v[164:167], v[32:47]
	ds_read_b128 v[234:237], v204 offset:9280
	ds_read_b128 v[238:241], v204 offset:13888
	s_waitcnt vmcnt(7)
	ds_write_b128 v217, v[218:221]
	s_waitcnt vmcnt(6)
	ds_write_b128 v216, v[222:225]
	ds_read_b128 v[218:221], v205 offset:36960
	ds_read_b128 v[222:225], v205 offset:41568
	s_waitcnt lgkmcnt(5)
	v_mfma_f32_32x32x16_bf16 v[80:95], v[234:237], v[160:163], v[80:95]
	v_mfma_f32_32x32x16_bf16 v[16:31], v[234:237], v[164:167], v[16:31]
	ds_read_b128 v[234:237], v204 offset:96
	s_waitcnt lgkmcnt(5)
	v_mfma_f32_32x32x16_bf16 v[64:79], v[238:241], v[160:163], v[64:79]
	v_mfma_f32_32x32x16_bf16 v[0:15], v[238:241], v[164:167], v[0:15]
	ds_read_b128 v[238:241], v204 offset:4704
	global_load_dwordx4 v[160:163], v[198:199], off offset:768
	global_load_dwordx4 v[164:167], v[200:201], off offset:768
	s_waitcnt lgkmcnt(1)
	v_mfma_f32_32x32x16_bf16 v[112:127], v[234:237], v[218:221], v[112:127]
	v_mfma_f32_32x32x16_bf16 v[48:63], v[234:237], v[222:225], v[48:63]
	s_waitcnt lgkmcnt(0)
	v_mfma_f32_32x32x16_bf16 v[96:111], v[238:241], v[218:221], v[96:111]
	v_mfma_f32_32x32x16_bf16 v[32:47], v[238:241], v[222:225], v[32:47]
	ds_read_b128 v[234:237], v204 offset:9312
	ds_read_b128 v[238:241], v204 offset:13920
	s_waitcnt lgkmcnt(1)
	v_mfma_f32_32x32x16_bf16 v[80:95], v[234:237], v[218:221], v[80:95]
	v_mfma_f32_32x32x16_bf16 v[16:31], v[234:237], v[222:225], v[16:31]
	s_waitcnt lgkmcnt(0)
	v_mfma_f32_32x32x16_bf16 v[64:79], v[238:241], v[218:221], v[64:79]
	v_mfma_f32_32x32x16_bf16 v[0:15], v[238:241], v[222:225], v[0:15]
	s_setprio 0
	s_barrier
	global_load_dwordx4 v[218:221], v[190:191], off offset:896
	global_load_dwordx4 v[222:225], v[188:189], off offset:896
	s_waitcnt vmcnt(9)
	ds_write_b128 v215, v[226:229]
	s_waitcnt vmcnt(8)
	ds_write_b128 v215, v[230:233] offset:36864
	ds_read_b128 v[226:229], v208
	ds_read_b128 v[230:233], v208 offset:4608
	ds_read_b128 v[234:237], v192
	ds_read_b128 v[238:241], v192 offset:4608
	s_setprio 1
	s_waitcnt lgkmcnt(1)
	v_mfma_f32_32x32x16_bf16 v[112:127], v[234:237], v[226:229], v[112:127]
	v_mfma_f32_32x32x16_bf16 v[48:63], v[234:237], v[230:233], v[48:63]
	s_waitcnt lgkmcnt(0)
	v_mfma_f32_32x32x16_bf16 v[96:111], v[238:241], v[226:229], v[96:111]
	v_mfma_f32_32x32x16_bf16 v[32:47], v[238:241], v[230:233], v[32:47]
	ds_read_b128 v[234:237], v192 offset:9216
	ds_read_b128 v[238:241], v192 offset:13824
	s_waitcnt vmcnt(7)
	ds_write_b128 v215, v[176:179] offset:9216
	s_waitcnt vmcnt(6)
	ds_write_b128 v215, v[180:183] offset:46080
	ds_read_b128 v[176:179], v208 offset:32
	ds_read_b128 v[180:183], v208 offset:4640
	s_waitcnt lgkmcnt(5)
	v_mfma_f32_32x32x16_bf16 v[80:95], v[234:237], v[226:229], v[80:95]
	v_mfma_f32_32x32x16_bf16 v[16:31], v[234:237], v[230:233], v[16:31]
	ds_read_b128 v[234:237], v192 offset:32
	s_waitcnt lgkmcnt(5)
	v_mfma_f32_32x32x16_bf16 v[64:79], v[238:241], v[226:229], v[64:79]
	v_mfma_f32_32x32x16_bf16 v[0:15], v[238:241], v[230:233], v[0:15]
	ds_read_b128 v[238:241], v192 offset:4640
	global_load_dwordx4 v[226:229], v[194:195], off offset:896
	global_load_dwordx4 v[230:233], v[196:197], off offset:896
	s_waitcnt lgkmcnt(1)
	v_mfma_f32_32x32x16_bf16 v[112:127], v[234:237], v[176:179], v[112:127]
	v_mfma_f32_32x32x16_bf16 v[48:63], v[234:237], v[180:183], v[48:63]
	s_waitcnt lgkmcnt(0)
	v_mfma_f32_32x32x16_bf16 v[96:111], v[238:241], v[176:179], v[96:111]
	v_mfma_f32_32x32x16_bf16 v[32:47], v[238:241], v[180:183], v[32:47]
	ds_read_b128 v[234:237], v192 offset:9248
	ds_read_b128 v[238:241], v192 offset:13856
	s_waitcnt vmcnt(7)
	ds_write_b128 v215, v[168:171] offset:18432
	s_waitcnt vmcnt(6)
	ds_write_b128 v215, v[172:175] offset:55296
	ds_read_b128 v[168:171], v208 offset:64
	ds_read_b128 v[172:175], v208 offset:4672
	s_waitcnt lgkmcnt(5)
	v_mfma_f32_32x32x16_bf16 v[80:95], v[234:237], v[176:179], v[80:95]
	v_mfma_f32_32x32x16_bf16 v[16:31], v[234:237], v[180:183], v[16:31]
	ds_read_b128 v[234:237], v192 offset:64
	s_waitcnt lgkmcnt(5)
	v_mfma_f32_32x32x16_bf16 v[64:79], v[238:241], v[176:179], v[64:79]
	v_mfma_f32_32x32x16_bf16 v[0:15], v[238:241], v[180:183], v[0:15]
	ds_read_b128 v[238:241], v192 offset:4672
	global_load_dwordx4 v[176:179], v[184:185], off offset:896
	global_load_dwordx4 v[180:183], v[186:187], off offset:896
	s_waitcnt lgkmcnt(1)
	v_mfma_f32_32x32x16_bf16 v[112:127], v[234:237], v[168:171], v[112:127]
	v_mfma_f32_32x32x16_bf16 v[48:63], v[234:237], v[172:175], v[48:63]
	s_waitcnt lgkmcnt(0)
	v_mfma_f32_32x32x16_bf16 v[96:111], v[238:241], v[168:171], v[96:111]
	v_mfma_f32_32x32x16_bf16 v[32:47], v[238:241], v[172:175], v[32:47]
	ds_read_b128 v[234:237], v192 offset:9280
	ds_read_b128 v[238:241], v192 offset:13888
	s_waitcnt vmcnt(7)
	ds_write_b128 v215, v[160:163] offset:27648
	s_waitcnt vmcnt(6)
	ds_write_b128 v215, v[164:167] offset:64512
	ds_read_b128 v[160:163], v208 offset:96
	ds_read_b128 v[164:167], v208 offset:4704
	s_waitcnt lgkmcnt(5)
	v_mfma_f32_32x32x16_bf16 v[80:95], v[234:237], v[168:171], v[80:95]
	v_mfma_f32_32x32x16_bf16 v[16:31], v[234:237], v[172:175], v[16:31]
	ds_read_b128 v[234:237], v192 offset:96
	s_waitcnt lgkmcnt(5)
	v_mfma_f32_32x32x16_bf16 v[64:79], v[238:241], v[168:171], v[64:79]
	v_mfma_f32_32x32x16_bf16 v[0:15], v[238:241], v[172:175], v[0:15]
	ds_read_b128 v[238:241], v192 offset:4704
	global_load_dwordx4 v[168:171], v[198:199], off offset:896
	global_load_dwordx4 v[172:175], v[200:201], off offset:896
	s_waitcnt lgkmcnt(1)
	v_mfma_f32_32x32x16_bf16 v[112:127], v[234:237], v[160:163], v[112:127]
	v_mfma_f32_32x32x16_bf16 v[48:63], v[234:237], v[164:167], v[48:63]
	s_waitcnt lgkmcnt(0)
	v_mfma_f32_32x32x16_bf16 v[96:111], v[238:241], v[160:163], v[96:111]
	v_mfma_f32_32x32x16_bf16 v[32:47], v[238:241], v[164:167], v[32:47]
	ds_read_b128 v[234:237], v192 offset:9312
	ds_read_b128 v[238:241], v192 offset:13920
	s_waitcnt lgkmcnt(1)
	v_mfma_f32_32x32x16_bf16 v[80:95], v[234:237], v[160:163], v[80:95]
	v_mfma_f32_32x32x16_bf16 v[16:31], v[234:237], v[164:167], v[16:31]
	s_waitcnt lgkmcnt(0)
	v_mfma_f32_32x32x16_bf16 v[64:79], v[238:241], v[160:163], v[64:79]
	v_mfma_f32_32x32x16_bf16 v[0:15], v[238:241], v[164:167], v[0:15]
	s_setprio 0
	s_barrier
	global_load_dwordx4 v[160:163], v[190:191], off offset:1024
	global_load_dwordx4 v[164:167], v[188:189], off offset:1024
	s_waitcnt vmcnt(9)
	ds_write_b128 v209, v[218:221]
	s_waitcnt vmcnt(8)
	ds_write_b128 v210, v[222:225]
	ds_read_b128 v[218:221], v205 offset:36864
	ds_read_b128 v[222:225], v205 offset:41472
	ds_read_b128 v[234:237], v204
	ds_read_b128 v[238:241], v204 offset:4608
	s_setprio 1
	s_waitcnt lgkmcnt(1)
	v_mfma_f32_32x32x16_bf16 v[112:127], v[234:237], v[218:221], v[112:127]
	v_mfma_f32_32x32x16_bf16 v[48:63], v[234:237], v[222:225], v[48:63]
	s_waitcnt lgkmcnt(0)
	v_mfma_f32_32x32x16_bf16 v[96:111], v[238:241], v[218:221], v[96:111]
	v_mfma_f32_32x32x16_bf16 v[32:47], v[238:241], v[222:225], v[32:47]
	ds_read_b128 v[234:237], v204 offset:9216
	ds_read_b128 v[238:241], v204 offset:13824
	s_waitcnt vmcnt(7)
	ds_write_b128 v212, v[226:229]
	s_waitcnt vmcnt(6)
	ds_write_b128 v211, v[230:233]
	ds_read_b128 v[226:229], v205 offset:36896
	ds_read_b128 v[230:233], v205 offset:41504
	s_waitcnt lgkmcnt(5)
	v_mfma_f32_32x32x16_bf16 v[80:95], v[234:237], v[218:221], v[80:95]
	v_mfma_f32_32x32x16_bf16 v[16:31], v[234:237], v[222:225], v[16:31]
	ds_read_b128 v[234:237], v204 offset:32
	s_waitcnt lgkmcnt(5)
	v_mfma_f32_32x32x16_bf16 v[64:79], v[238:241], v[218:221], v[64:79]
	v_mfma_f32_32x32x16_bf16 v[0:15], v[238:241], v[222:225], v[0:15]
	ds_read_b128 v[238:241], v204 offset:4640
	global_load_dwordx4 v[218:221], v[194:195], off offset:1024
	global_load_dwordx4 v[222:225], v[196:197], off offset:1024
	s_waitcnt lgkmcnt(1)
	v_mfma_f32_32x32x16_bf16 v[112:127], v[234:237], v[226:229], v[112:127]
	v_mfma_f32_32x32x16_bf16 v[48:63], v[234:237], v[230:233], v[48:63]
	s_waitcnt lgkmcnt(0)
	v_mfma_f32_32x32x16_bf16 v[96:111], v[238:241], v[226:229], v[96:111]
	v_mfma_f32_32x32x16_bf16 v[32:47], v[238:241], v[230:233], v[32:47]
	ds_read_b128 v[234:237], v204 offset:9248
	ds_read_b128 v[238:241], v204 offset:13856
	s_waitcnt vmcnt(7)
	ds_write_b128 v214, v[176:179]
	s_waitcnt vmcnt(6)
	ds_write_b128 v213, v[180:183]
	ds_read_b128 v[176:179], v205 offset:36928
	ds_read_b128 v[180:183], v205 offset:41536
	s_waitcnt lgkmcnt(5)
	v_mfma_f32_32x32x16_bf16 v[80:95], v[234:237], v[226:229], v[80:95]
	v_mfma_f32_32x32x16_bf16 v[16:31], v[234:237], v[230:233], v[16:31]
	ds_read_b128 v[234:237], v204 offset:64
	s_waitcnt lgkmcnt(5)
	v_mfma_f32_32x32x16_bf16 v[64:79], v[238:241], v[226:229], v[64:79]
	v_mfma_f32_32x32x16_bf16 v[0:15], v[238:241], v[230:233], v[0:15]
	ds_read_b128 v[238:241], v204 offset:4672
	global_load_dwordx4 v[226:229], v[184:185], off offset:1024
	global_load_dwordx4 v[230:233], v[186:187], off offset:1024
	s_waitcnt lgkmcnt(1)
	v_mfma_f32_32x32x16_bf16 v[112:127], v[234:237], v[176:179], v[112:127]
	v_mfma_f32_32x32x16_bf16 v[48:63], v[234:237], v[180:183], v[48:63]
	s_waitcnt lgkmcnt(0)
	v_mfma_f32_32x32x16_bf16 v[96:111], v[238:241], v[176:179], v[96:111]
	v_mfma_f32_32x32x16_bf16 v[32:47], v[238:241], v[180:183], v[32:47]
	ds_read_b128 v[234:237], v204 offset:9280
	ds_read_b128 v[238:241], v204 offset:13888
	s_waitcnt vmcnt(7)
	ds_write_b128 v217, v[168:171]
	s_waitcnt vmcnt(6)
	ds_write_b128 v216, v[172:175]
	ds_read_b128 v[168:171], v205 offset:36960
	ds_read_b128 v[172:175], v205 offset:41568
	s_waitcnt lgkmcnt(5)
	v_mfma_f32_32x32x16_bf16 v[80:95], v[234:237], v[176:179], v[80:95]
	v_mfma_f32_32x32x16_bf16 v[16:31], v[234:237], v[180:183], v[16:31]
	ds_read_b128 v[234:237], v204 offset:96
	s_waitcnt lgkmcnt(5)
	v_mfma_f32_32x32x16_bf16 v[64:79], v[238:241], v[176:179], v[64:79]
	v_mfma_f32_32x32x16_bf16 v[0:15], v[238:241], v[180:183], v[0:15]
	ds_read_b128 v[238:241], v204 offset:4704
	global_load_dwordx4 v[176:179], v[198:199], off offset:1024
	global_load_dwordx4 v[180:183], v[200:201], off offset:1024
	s_waitcnt lgkmcnt(1)
	v_mfma_f32_32x32x16_bf16 v[112:127], v[234:237], v[168:171], v[112:127]
	v_mfma_f32_32x32x16_bf16 v[48:63], v[234:237], v[172:175], v[48:63]
	s_waitcnt lgkmcnt(0)
	v_mfma_f32_32x32x16_bf16 v[96:111], v[238:241], v[168:171], v[96:111]
	v_mfma_f32_32x32x16_bf16 v[32:47], v[238:241], v[172:175], v[32:47]
	ds_read_b128 v[234:237], v204 offset:9312
	ds_read_b128 v[238:241], v204 offset:13920
	s_waitcnt lgkmcnt(1)
	v_mfma_f32_32x32x16_bf16 v[80:95], v[234:237], v[168:171], v[80:95]
	v_mfma_f32_32x32x16_bf16 v[16:31], v[234:237], v[172:175], v[16:31]
	s_waitcnt lgkmcnt(0)
	v_mfma_f32_32x32x16_bf16 v[64:79], v[238:241], v[168:171], v[64:79]
	v_mfma_f32_32x32x16_bf16 v[0:15], v[238:241], v[172:175], v[0:15]
	s_setprio 0
	s_barrier
	global_load_dwordx4 v[168:171], v[190:191], off offset:1152
	global_load_dwordx4 v[172:175], v[188:189], off offset:1152
	s_waitcnt vmcnt(9)
	ds_write_b128 v215, v[160:163]
	s_waitcnt vmcnt(8)
	ds_write_b128 v215, v[164:167] offset:36864
	ds_read_b128 v[160:163], v208
	ds_read_b128 v[164:167], v208 offset:4608
	ds_read_b128 v[234:237], v192
	ds_read_b128 v[238:241], v192 offset:4608
	s_setprio 1
	s_waitcnt lgkmcnt(1)
	v_mfma_f32_32x32x16_bf16 v[112:127], v[234:237], v[160:163], v[112:127]
	v_mfma_f32_32x32x16_bf16 v[48:63], v[234:237], v[164:167], v[48:63]
	s_waitcnt lgkmcnt(0)
	v_mfma_f32_32x32x16_bf16 v[96:111], v[238:241], v[160:163], v[96:111]
	v_mfma_f32_32x32x16_bf16 v[32:47], v[238:241], v[164:167], v[32:47]
	ds_read_b128 v[234:237], v192 offset:9216
	ds_read_b128 v[238:241], v192 offset:13824
	s_waitcnt vmcnt(7)
	ds_write_b128 v215, v[218:221] offset:9216
	s_waitcnt vmcnt(6)
	ds_write_b128 v215, v[222:225] offset:46080
	ds_read_b128 v[218:221], v208 offset:32
	ds_read_b128 v[222:225], v208 offset:4640
	s_waitcnt lgkmcnt(5)
	v_mfma_f32_32x32x16_bf16 v[80:95], v[234:237], v[160:163], v[80:95]
	v_mfma_f32_32x32x16_bf16 v[16:31], v[234:237], v[164:167], v[16:31]
	ds_read_b128 v[234:237], v192 offset:32
	s_waitcnt lgkmcnt(5)
	v_mfma_f32_32x32x16_bf16 v[64:79], v[238:241], v[160:163], v[64:79]
	v_mfma_f32_32x32x16_bf16 v[0:15], v[238:241], v[164:167], v[0:15]
	ds_read_b128 v[238:241], v192 offset:4640
	global_load_dwordx4 v[160:163], v[194:195], off offset:1152
	global_load_dwordx4 v[164:167], v[196:197], off offset:1152
	s_waitcnt lgkmcnt(1)
	v_mfma_f32_32x32x16_bf16 v[112:127], v[234:237], v[218:221], v[112:127]
	v_mfma_f32_32x32x16_bf16 v[48:63], v[234:237], v[222:225], v[48:63]
	s_waitcnt lgkmcnt(0)
	v_mfma_f32_32x32x16_bf16 v[96:111], v[238:241], v[218:221], v[96:111]
	v_mfma_f32_32x32x16_bf16 v[32:47], v[238:241], v[222:225], v[32:47]
	ds_read_b128 v[234:237], v192 offset:9248
	ds_read_b128 v[238:241], v192 offset:13856
	s_waitcnt vmcnt(7)
	ds_write_b128 v215, v[226:229] offset:18432
	s_waitcnt vmcnt(6)
	ds_write_b128 v215, v[230:233] offset:55296
	ds_read_b128 v[226:229], v208 offset:64
	ds_read_b128 v[230:233], v208 offset:4672
	s_waitcnt lgkmcnt(5)
	v_mfma_f32_32x32x16_bf16 v[80:95], v[234:237], v[218:221], v[80:95]
	v_mfma_f32_32x32x16_bf16 v[16:31], v[234:237], v[222:225], v[16:31]
	ds_read_b128 v[234:237], v192 offset:64
	s_waitcnt lgkmcnt(5)
	v_mfma_f32_32x32x16_bf16 v[64:79], v[238:241], v[218:221], v[64:79]
	v_mfma_f32_32x32x16_bf16 v[0:15], v[238:241], v[222:225], v[0:15]
	ds_read_b128 v[238:241], v192 offset:4672
	global_load_dwordx4 v[218:221], v[184:185], off offset:1152
	global_load_dwordx4 v[222:225], v[186:187], off offset:1152
	s_waitcnt lgkmcnt(1)
	v_mfma_f32_32x32x16_bf16 v[112:127], v[234:237], v[226:229], v[112:127]
	v_mfma_f32_32x32x16_bf16 v[48:63], v[234:237], v[230:233], v[48:63]
	s_waitcnt lgkmcnt(0)
	v_mfma_f32_32x32x16_bf16 v[96:111], v[238:241], v[226:229], v[96:111]
	v_mfma_f32_32x32x16_bf16 v[32:47], v[238:241], v[230:233], v[32:47]
	ds_read_b128 v[234:237], v192 offset:9280
	ds_read_b128 v[238:241], v192 offset:13888
	s_waitcnt vmcnt(7)
	ds_write_b128 v215, v[176:179] offset:27648
	s_waitcnt vmcnt(6)
	ds_write_b128 v215, v[180:183] offset:64512
	ds_read_b128 v[176:179], v208 offset:96
	ds_read_b128 v[180:183], v208 offset:4704
	s_waitcnt lgkmcnt(5)
	v_mfma_f32_32x32x16_bf16 v[80:95], v[234:237], v[226:229], v[80:95]
	v_mfma_f32_32x32x16_bf16 v[16:31], v[234:237], v[230:233], v[16:31]
	ds_read_b128 v[234:237], v192 offset:96
	s_waitcnt lgkmcnt(5)
	v_mfma_f32_32x32x16_bf16 v[64:79], v[238:241], v[226:229], v[64:79]
	v_mfma_f32_32x32x16_bf16 v[0:15], v[238:241], v[230:233], v[0:15]
	ds_read_b128 v[238:241], v192 offset:4704
	global_load_dwordx4 v[226:229], v[198:199], off offset:1152
	global_load_dwordx4 v[230:233], v[200:201], off offset:1152
	s_waitcnt lgkmcnt(1)
	v_mfma_f32_32x32x16_bf16 v[112:127], v[234:237], v[176:179], v[112:127]
	v_mfma_f32_32x32x16_bf16 v[48:63], v[234:237], v[180:183], v[48:63]
	s_waitcnt lgkmcnt(0)
	v_mfma_f32_32x32x16_bf16 v[96:111], v[238:241], v[176:179], v[96:111]
	v_mfma_f32_32x32x16_bf16 v[32:47], v[238:241], v[180:183], v[32:47]
	ds_read_b128 v[234:237], v192 offset:9312
	ds_read_b128 v[238:241], v192 offset:13920
	s_waitcnt lgkmcnt(1)
	v_mfma_f32_32x32x16_bf16 v[80:95], v[234:237], v[176:179], v[80:95]
	v_mfma_f32_32x32x16_bf16 v[16:31], v[234:237], v[180:183], v[16:31]
	s_waitcnt lgkmcnt(0)
	v_mfma_f32_32x32x16_bf16 v[64:79], v[238:241], v[176:179], v[64:79]
	v_mfma_f32_32x32x16_bf16 v[0:15], v[238:241], v[180:183], v[0:15]
	s_setprio 0
	s_barrier
	global_load_dwordx4 v[176:179], v[190:191], off offset:1280
	global_load_dwordx4 v[180:183], v[188:189], off offset:1280
	s_waitcnt vmcnt(9)
	ds_write_b128 v209, v[168:171]
	s_waitcnt vmcnt(8)
	ds_write_b128 v210, v[172:175]
	ds_read_b128 v[168:171], v205 offset:36864
	ds_read_b128 v[172:175], v205 offset:41472
	ds_read_b128 v[234:237], v204
	ds_read_b128 v[238:241], v204 offset:4608
	s_setprio 1
	s_waitcnt lgkmcnt(1)
	v_mfma_f32_32x32x16_bf16 v[112:127], v[234:237], v[168:171], v[112:127]
	v_mfma_f32_32x32x16_bf16 v[48:63], v[234:237], v[172:175], v[48:63]
	s_waitcnt lgkmcnt(0)
	v_mfma_f32_32x32x16_bf16 v[96:111], v[238:241], v[168:171], v[96:111]
	v_mfma_f32_32x32x16_bf16 v[32:47], v[238:241], v[172:175], v[32:47]
	ds_read_b128 v[234:237], v204 offset:9216
	ds_read_b128 v[238:241], v204 offset:13824
	s_waitcnt vmcnt(7)
	ds_write_b128 v212, v[160:163]
	s_waitcnt vmcnt(6)
	ds_write_b128 v211, v[164:167]
	ds_read_b128 v[160:163], v205 offset:36896
	ds_read_b128 v[164:167], v205 offset:41504
	s_waitcnt lgkmcnt(5)
	v_mfma_f32_32x32x16_bf16 v[80:95], v[234:237], v[168:171], v[80:95]
	v_mfma_f32_32x32x16_bf16 v[16:31], v[234:237], v[172:175], v[16:31]
	ds_read_b128 v[234:237], v204 offset:32
	s_waitcnt lgkmcnt(5)
	v_mfma_f32_32x32x16_bf16 v[64:79], v[238:241], v[168:171], v[64:79]
	v_mfma_f32_32x32x16_bf16 v[0:15], v[238:241], v[172:175], v[0:15]
	ds_read_b128 v[238:241], v204 offset:4640
	global_load_dwordx4 v[168:171], v[194:195], off offset:1280
	global_load_dwordx4 v[172:175], v[196:197], off offset:1280
	s_waitcnt lgkmcnt(1)
	v_mfma_f32_32x32x16_bf16 v[112:127], v[234:237], v[160:163], v[112:127]
	v_mfma_f32_32x32x16_bf16 v[48:63], v[234:237], v[164:167], v[48:63]
	s_waitcnt lgkmcnt(0)
	v_mfma_f32_32x32x16_bf16 v[96:111], v[238:241], v[160:163], v[96:111]
	v_mfma_f32_32x32x16_bf16 v[32:47], v[238:241], v[164:167], v[32:47]
	ds_read_b128 v[234:237], v204 offset:9248
	ds_read_b128 v[238:241], v204 offset:13856
	s_waitcnt vmcnt(7)
	ds_write_b128 v214, v[218:221]
	s_waitcnt vmcnt(6)
	ds_write_b128 v213, v[222:225]
	ds_read_b128 v[218:221], v205 offset:36928
	ds_read_b128 v[222:225], v205 offset:41536
	s_waitcnt lgkmcnt(5)
	v_mfma_f32_32x32x16_bf16 v[80:95], v[234:237], v[160:163], v[80:95]
	v_mfma_f32_32x32x16_bf16 v[16:31], v[234:237], v[164:167], v[16:31]
	ds_read_b128 v[234:237], v204 offset:64
	s_waitcnt lgkmcnt(5)
	v_mfma_f32_32x32x16_bf16 v[64:79], v[238:241], v[160:163], v[64:79]
	v_mfma_f32_32x32x16_bf16 v[0:15], v[238:241], v[164:167], v[0:15]
	ds_read_b128 v[238:241], v204 offset:4672
	global_load_dwordx4 v[160:163], v[184:185], off offset:1280
	global_load_dwordx4 v[164:167], v[186:187], off offset:1280
	s_waitcnt lgkmcnt(1)
	v_mfma_f32_32x32x16_bf16 v[112:127], v[234:237], v[218:221], v[112:127]
	v_mfma_f32_32x32x16_bf16 v[48:63], v[234:237], v[222:225], v[48:63]
	s_waitcnt lgkmcnt(0)
	v_mfma_f32_32x32x16_bf16 v[96:111], v[238:241], v[218:221], v[96:111]
	v_mfma_f32_32x32x16_bf16 v[32:47], v[238:241], v[222:225], v[32:47]
	ds_read_b128 v[234:237], v204 offset:9280
	ds_read_b128 v[238:241], v204 offset:13888
	s_waitcnt vmcnt(7)
	ds_write_b128 v217, v[226:229]
	s_waitcnt vmcnt(6)
	ds_write_b128 v216, v[230:233]
	ds_read_b128 v[226:229], v205 offset:36960
	ds_read_b128 v[230:233], v205 offset:41568
	s_waitcnt lgkmcnt(5)
	v_mfma_f32_32x32x16_bf16 v[80:95], v[234:237], v[218:221], v[80:95]
	v_mfma_f32_32x32x16_bf16 v[16:31], v[234:237], v[222:225], v[16:31]
	ds_read_b128 v[234:237], v204 offset:96
	s_waitcnt lgkmcnt(5)
	v_mfma_f32_32x32x16_bf16 v[64:79], v[238:241], v[218:221], v[64:79]
	v_mfma_f32_32x32x16_bf16 v[0:15], v[238:241], v[222:225], v[0:15]
	ds_read_b128 v[238:241], v204 offset:4704
	global_load_dwordx4 v[218:221], v[198:199], off offset:1280
	global_load_dwordx4 v[222:225], v[200:201], off offset:1280
	s_waitcnt lgkmcnt(1)
	v_mfma_f32_32x32x16_bf16 v[112:127], v[234:237], v[226:229], v[112:127]
	v_mfma_f32_32x32x16_bf16 v[48:63], v[234:237], v[230:233], v[48:63]
	s_waitcnt lgkmcnt(0)
	v_mfma_f32_32x32x16_bf16 v[96:111], v[238:241], v[226:229], v[96:111]
	v_mfma_f32_32x32x16_bf16 v[32:47], v[238:241], v[230:233], v[32:47]
	ds_read_b128 v[234:237], v204 offset:9312
	ds_read_b128 v[238:241], v204 offset:13920
	s_waitcnt lgkmcnt(1)
	v_mfma_f32_32x32x16_bf16 v[80:95], v[234:237], v[226:229], v[80:95]
	v_mfma_f32_32x32x16_bf16 v[16:31], v[234:237], v[230:233], v[16:31]
	s_waitcnt lgkmcnt(0)
	v_mfma_f32_32x32x16_bf16 v[64:79], v[238:241], v[226:229], v[64:79]
	v_mfma_f32_32x32x16_bf16 v[0:15], v[238:241], v[230:233], v[0:15]
	s_setprio 0
	s_barrier
	global_load_dwordx4 v[226:229], v[190:191], off offset:1408
	global_load_dwordx4 v[230:233], v[188:189], off offset:1408
	s_waitcnt vmcnt(9)
	ds_write_b128 v215, v[176:179]
	s_waitcnt vmcnt(8)
	ds_write_b128 v215, v[180:183] offset:36864
	ds_read_b128 v[176:179], v208
	ds_read_b128 v[180:183], v208 offset:4608
	ds_read_b128 v[234:237], v192
	ds_read_b128 v[238:241], v192 offset:4608
	s_setprio 1
	s_waitcnt lgkmcnt(1)
	v_mfma_f32_32x32x16_bf16 v[112:127], v[234:237], v[176:179], v[112:127]
	v_mfma_f32_32x32x16_bf16 v[48:63], v[234:237], v[180:183], v[48:63]
	s_waitcnt lgkmcnt(0)
	v_mfma_f32_32x32x16_bf16 v[96:111], v[238:241], v[176:179], v[96:111]
	v_mfma_f32_32x32x16_bf16 v[32:47], v[238:241], v[180:183], v[32:47]
	ds_read_b128 v[234:237], v192 offset:9216
	ds_read_b128 v[238:241], v192 offset:13824
	s_waitcnt vmcnt(7)
	ds_write_b128 v215, v[168:171] offset:9216
	s_waitcnt vmcnt(6)
	ds_write_b128 v215, v[172:175] offset:46080
	ds_read_b128 v[168:171], v208 offset:32
	ds_read_b128 v[172:175], v208 offset:4640
	s_waitcnt lgkmcnt(5)
	v_mfma_f32_32x32x16_bf16 v[80:95], v[234:237], v[176:179], v[80:95]
	v_mfma_f32_32x32x16_bf16 v[16:31], v[234:237], v[180:183], v[16:31]
	ds_read_b128 v[234:237], v192 offset:32
	s_waitcnt lgkmcnt(5)
	v_mfma_f32_32x32x16_bf16 v[64:79], v[238:241], v[176:179], v[64:79]
	v_mfma_f32_32x32x16_bf16 v[0:15], v[238:241], v[180:183], v[0:15]
	ds_read_b128 v[238:241], v192 offset:4640
	global_load_dwordx4 v[176:179], v[194:195], off offset:1408
	global_load_dwordx4 v[180:183], v[196:197], off offset:1408
	s_waitcnt lgkmcnt(1)
	v_mfma_f32_32x32x16_bf16 v[112:127], v[234:237], v[168:171], v[112:127]
	v_mfma_f32_32x32x16_bf16 v[48:63], v[234:237], v[172:175], v[48:63]
	s_waitcnt lgkmcnt(0)
	v_mfma_f32_32x32x16_bf16 v[96:111], v[238:241], v[168:171], v[96:111]
	v_mfma_f32_32x32x16_bf16 v[32:47], v[238:241], v[172:175], v[32:47]
	ds_read_b128 v[234:237], v192 offset:9248
	ds_read_b128 v[238:241], v192 offset:13856
	s_waitcnt vmcnt(7)
	ds_write_b128 v215, v[160:163] offset:18432
	s_waitcnt vmcnt(6)
	ds_write_b128 v215, v[164:167] offset:55296
	ds_read_b128 v[160:163], v208 offset:64
	ds_read_b128 v[164:167], v208 offset:4672
	s_waitcnt lgkmcnt(5)
	v_mfma_f32_32x32x16_bf16 v[80:95], v[234:237], v[168:171], v[80:95]
	v_mfma_f32_32x32x16_bf16 v[16:31], v[234:237], v[172:175], v[16:31]
	ds_read_b128 v[234:237], v192 offset:64
	s_waitcnt lgkmcnt(5)
	v_mfma_f32_32x32x16_bf16 v[64:79], v[238:241], v[168:171], v[64:79]
	v_mfma_f32_32x32x16_bf16 v[0:15], v[238:241], v[172:175], v[0:15]
	ds_read_b128 v[238:241], v192 offset:4672
	global_load_dwordx4 v[168:171], v[184:185], off offset:1408
	global_load_dwordx4 v[172:175], v[186:187], off offset:1408
	s_waitcnt lgkmcnt(1)
	v_mfma_f32_32x32x16_bf16 v[112:127], v[234:237], v[160:163], v[112:127]
	v_mfma_f32_32x32x16_bf16 v[48:63], v[234:237], v[164:167], v[48:63]
	s_waitcnt lgkmcnt(0)
	v_mfma_f32_32x32x16_bf16 v[96:111], v[238:241], v[160:163], v[96:111]
	v_mfma_f32_32x32x16_bf16 v[32:47], v[238:241], v[164:167], v[32:47]
	ds_read_b128 v[234:237], v192 offset:9280
	ds_read_b128 v[238:241], v192 offset:13888
	s_waitcnt vmcnt(7)
	ds_write_b128 v215, v[218:221] offset:27648
	s_waitcnt vmcnt(6)
	ds_write_b128 v215, v[222:225] offset:64512
	ds_read_b128 v[218:221], v208 offset:96
	ds_read_b128 v[222:225], v208 offset:4704
	s_waitcnt lgkmcnt(5)
	v_mfma_f32_32x32x16_bf16 v[80:95], v[234:237], v[160:163], v[80:95]
	v_mfma_f32_32x32x16_bf16 v[16:31], v[234:237], v[164:167], v[16:31]
	ds_read_b128 v[234:237], v192 offset:96
	s_waitcnt lgkmcnt(5)
	v_mfma_f32_32x32x16_bf16 v[64:79], v[238:241], v[160:163], v[64:79]
	v_mfma_f32_32x32x16_bf16 v[0:15], v[238:241], v[164:167], v[0:15]
	ds_read_b128 v[238:241], v192 offset:4704
	global_load_dwordx4 v[160:163], v[198:199], off offset:1408
	global_load_dwordx4 v[164:167], v[200:201], off offset:1408
	s_waitcnt lgkmcnt(1)
	v_mfma_f32_32x32x16_bf16 v[112:127], v[234:237], v[218:221], v[112:127]
	v_mfma_f32_32x32x16_bf16 v[48:63], v[234:237], v[222:225], v[48:63]
	s_waitcnt lgkmcnt(0)
	v_mfma_f32_32x32x16_bf16 v[96:111], v[238:241], v[218:221], v[96:111]
	v_mfma_f32_32x32x16_bf16 v[32:47], v[238:241], v[222:225], v[32:47]
	ds_read_b128 v[234:237], v192 offset:9312
	ds_read_b128 v[238:241], v192 offset:13920
	s_waitcnt lgkmcnt(1)
	v_mfma_f32_32x32x16_bf16 v[80:95], v[234:237], v[218:221], v[80:95]
	v_mfma_f32_32x32x16_bf16 v[16:31], v[234:237], v[222:225], v[16:31]
	s_waitcnt lgkmcnt(0)
	v_mfma_f32_32x32x16_bf16 v[64:79], v[238:241], v[218:221], v[64:79]
	v_mfma_f32_32x32x16_bf16 v[0:15], v[238:241], v[222:225], v[0:15]
	s_setprio 0
	s_barrier
	global_load_dwordx4 v[218:221], v[190:191], off offset:1536
	global_load_dwordx4 v[222:225], v[188:189], off offset:1536
	s_waitcnt vmcnt(9)
	ds_write_b128 v209, v[226:229]
	s_waitcnt vmcnt(8)
	ds_write_b128 v210, v[230:233]
	ds_read_b128 v[226:229], v205 offset:36864
	ds_read_b128 v[230:233], v205 offset:41472
	ds_read_b128 v[234:237], v204
	ds_read_b128 v[238:241], v204 offset:4608
	s_setprio 1
	s_waitcnt lgkmcnt(1)
	v_mfma_f32_32x32x16_bf16 v[112:127], v[234:237], v[226:229], v[112:127]
	v_mfma_f32_32x32x16_bf16 v[48:63], v[234:237], v[230:233], v[48:63]
	s_waitcnt lgkmcnt(0)
	v_mfma_f32_32x32x16_bf16 v[96:111], v[238:241], v[226:229], v[96:111]
	v_mfma_f32_32x32x16_bf16 v[32:47], v[238:241], v[230:233], v[32:47]
	ds_read_b128 v[234:237], v204 offset:9216
	ds_read_b128 v[238:241], v204 offset:13824
	s_waitcnt vmcnt(7)
	ds_write_b128 v212, v[176:179]
	s_waitcnt vmcnt(6)
	ds_write_b128 v211, v[180:183]
	ds_read_b128 v[176:179], v205 offset:36896
	ds_read_b128 v[180:183], v205 offset:41504
	s_waitcnt lgkmcnt(5)
	v_mfma_f32_32x32x16_bf16 v[80:95], v[234:237], v[226:229], v[80:95]
	v_mfma_f32_32x32x16_bf16 v[16:31], v[234:237], v[230:233], v[16:31]
	ds_read_b128 v[234:237], v204 offset:32
	s_waitcnt lgkmcnt(5)
	v_mfma_f32_32x32x16_bf16 v[64:79], v[238:241], v[226:229], v[64:79]
	v_mfma_f32_32x32x16_bf16 v[0:15], v[238:241], v[230:233], v[0:15]
	ds_read_b128 v[238:241], v204 offset:4640
	global_load_dwordx4 v[226:229], v[194:195], off offset:1536
	global_load_dwordx4 v[230:233], v[196:197], off offset:1536
	s_waitcnt lgkmcnt(1)
	v_mfma_f32_32x32x16_bf16 v[112:127], v[234:237], v[176:179], v[112:127]
	v_mfma_f32_32x32x16_bf16 v[48:63], v[234:237], v[180:183], v[48:63]
	s_waitcnt lgkmcnt(0)
	v_mfma_f32_32x32x16_bf16 v[96:111], v[238:241], v[176:179], v[96:111]
	v_mfma_f32_32x32x16_bf16 v[32:47], v[238:241], v[180:183], v[32:47]
	ds_read_b128 v[234:237], v204 offset:9248
	ds_read_b128 v[238:241], v204 offset:13856
	s_waitcnt vmcnt(7)
	ds_write_b128 v214, v[168:171]
	s_waitcnt vmcnt(6)
	ds_write_b128 v213, v[172:175]
	ds_read_b128 v[168:171], v205 offset:36928
	ds_read_b128 v[172:175], v205 offset:41536
	s_waitcnt lgkmcnt(5)
	v_mfma_f32_32x32x16_bf16 v[80:95], v[234:237], v[176:179], v[80:95]
	v_mfma_f32_32x32x16_bf16 v[16:31], v[234:237], v[180:183], v[16:31]
	ds_read_b128 v[234:237], v204 offset:64
	s_waitcnt lgkmcnt(5)
	v_mfma_f32_32x32x16_bf16 v[64:79], v[238:241], v[176:179], v[64:79]
	v_mfma_f32_32x32x16_bf16 v[0:15], v[238:241], v[180:183], v[0:15]
	ds_read_b128 v[238:241], v204 offset:4672
	global_load_dwordx4 v[176:179], v[184:185], off offset:1536
	global_load_dwordx4 v[180:183], v[186:187], off offset:1536
	s_waitcnt lgkmcnt(1)
	v_mfma_f32_32x32x16_bf16 v[112:127], v[234:237], v[168:171], v[112:127]
	v_mfma_f32_32x32x16_bf16 v[48:63], v[234:237], v[172:175], v[48:63]
	s_waitcnt lgkmcnt(0)
	v_mfma_f32_32x32x16_bf16 v[96:111], v[238:241], v[168:171], v[96:111]
	v_mfma_f32_32x32x16_bf16 v[32:47], v[238:241], v[172:175], v[32:47]
	ds_read_b128 v[234:237], v204 offset:9280
	ds_read_b128 v[238:241], v204 offset:13888
	s_waitcnt vmcnt(7)
	ds_write_b128 v217, v[160:163]
	s_waitcnt vmcnt(6)
	ds_write_b128 v216, v[164:167]
	ds_read_b128 v[160:163], v205 offset:36960
	ds_read_b128 v[164:167], v205 offset:41568
	s_waitcnt lgkmcnt(5)
	v_mfma_f32_32x32x16_bf16 v[80:95], v[234:237], v[168:171], v[80:95]
	v_mfma_f32_32x32x16_bf16 v[16:31], v[234:237], v[172:175], v[16:31]
	ds_read_b128 v[234:237], v204 offset:96
	s_waitcnt lgkmcnt(5)
	v_mfma_f32_32x32x16_bf16 v[64:79], v[238:241], v[168:171], v[64:79]
	v_mfma_f32_32x32x16_bf16 v[0:15], v[238:241], v[172:175], v[0:15]
	ds_read_b128 v[238:241], v204 offset:4704
	global_load_dwordx4 v[168:171], v[198:199], off offset:1536
	global_load_dwordx4 v[172:175], v[200:201], off offset:1536
	s_waitcnt lgkmcnt(1)
	v_mfma_f32_32x32x16_bf16 v[112:127], v[234:237], v[160:163], v[112:127]
	v_mfma_f32_32x32x16_bf16 v[48:63], v[234:237], v[164:167], v[48:63]
	s_waitcnt lgkmcnt(0)
	v_mfma_f32_32x32x16_bf16 v[96:111], v[238:241], v[160:163], v[96:111]
	v_mfma_f32_32x32x16_bf16 v[32:47], v[238:241], v[164:167], v[32:47]
	ds_read_b128 v[234:237], v204 offset:9312
	ds_read_b128 v[238:241], v204 offset:13920
	s_waitcnt lgkmcnt(1)
	v_mfma_f32_32x32x16_bf16 v[80:95], v[234:237], v[160:163], v[80:95]
	v_mfma_f32_32x32x16_bf16 v[16:31], v[234:237], v[164:167], v[16:31]
	s_waitcnt lgkmcnt(0)
	v_mfma_f32_32x32x16_bf16 v[64:79], v[238:241], v[160:163], v[64:79]
	v_mfma_f32_32x32x16_bf16 v[0:15], v[238:241], v[164:167], v[0:15]
	s_setprio 0
	s_barrier
	global_load_dwordx4 v[160:163], v[190:191], off offset:1664
	global_load_dwordx4 v[164:167], v[188:189], off offset:1664
	s_waitcnt vmcnt(9)
	ds_write_b128 v215, v[218:221]
	s_waitcnt vmcnt(8)
	ds_write_b128 v215, v[222:225] offset:36864
	ds_read_b128 v[218:221], v208
	ds_read_b128 v[222:225], v208 offset:4608
	ds_read_b128 v[234:237], v192
	ds_read_b128 v[238:241], v192 offset:4608
	s_setprio 1
	s_waitcnt lgkmcnt(1)
	v_mfma_f32_32x32x16_bf16 v[112:127], v[234:237], v[218:221], v[112:127]
	v_mfma_f32_32x32x16_bf16 v[48:63], v[234:237], v[222:225], v[48:63]
	s_waitcnt lgkmcnt(0)
	v_mfma_f32_32x32x16_bf16 v[96:111], v[238:241], v[218:221], v[96:111]
	v_mfma_f32_32x32x16_bf16 v[32:47], v[238:241], v[222:225], v[32:47]
	ds_read_b128 v[234:237], v192 offset:9216
	ds_read_b128 v[238:241], v192 offset:13824
	s_waitcnt vmcnt(7)
	ds_write_b128 v215, v[226:229] offset:9216
	s_waitcnt vmcnt(6)
	ds_write_b128 v215, v[230:233] offset:46080
	ds_read_b128 v[226:229], v208 offset:32
	ds_read_b128 v[230:233], v208 offset:4640
	s_waitcnt lgkmcnt(5)
	v_mfma_f32_32x32x16_bf16 v[80:95], v[234:237], v[218:221], v[80:95]
	v_mfma_f32_32x32x16_bf16 v[16:31], v[234:237], v[222:225], v[16:31]
	ds_read_b128 v[234:237], v192 offset:32
	s_waitcnt lgkmcnt(5)
	v_mfma_f32_32x32x16_bf16 v[64:79], v[238:241], v[218:221], v[64:79]
	v_mfma_f32_32x32x16_bf16 v[0:15], v[238:241], v[222:225], v[0:15]
	ds_read_b128 v[238:241], v192 offset:4640
	global_load_dwordx4 v[218:221], v[194:195], off offset:1664
	global_load_dwordx4 v[222:225], v[196:197], off offset:1664
	s_waitcnt lgkmcnt(1)
	v_mfma_f32_32x32x16_bf16 v[112:127], v[234:237], v[226:229], v[112:127]
	v_mfma_f32_32x32x16_bf16 v[48:63], v[234:237], v[230:233], v[48:63]
	s_waitcnt lgkmcnt(0)
	v_mfma_f32_32x32x16_bf16 v[96:111], v[238:241], v[226:229], v[96:111]
	v_mfma_f32_32x32x16_bf16 v[32:47], v[238:241], v[230:233], v[32:47]
	ds_read_b128 v[234:237], v192 offset:9248
	ds_read_b128 v[238:241], v192 offset:13856
	s_waitcnt vmcnt(7)
	ds_write_b128 v215, v[176:179] offset:18432
	s_waitcnt vmcnt(6)
	ds_write_b128 v215, v[180:183] offset:55296
	ds_read_b128 v[176:179], v208 offset:64
	ds_read_b128 v[180:183], v208 offset:4672
	s_waitcnt lgkmcnt(5)
	v_mfma_f32_32x32x16_bf16 v[80:95], v[234:237], v[226:229], v[80:95]
	v_mfma_f32_32x32x16_bf16 v[16:31], v[234:237], v[230:233], v[16:31]
	ds_read_b128 v[234:237], v192 offset:64
	s_waitcnt lgkmcnt(5)
	v_mfma_f32_32x32x16_bf16 v[64:79], v[238:241], v[226:229], v[64:79]
	v_mfma_f32_32x32x16_bf16 v[0:15], v[238:241], v[230:233], v[0:15]
	ds_read_b128 v[238:241], v192 offset:4672
	global_load_dwordx4 v[226:229], v[184:185], off offset:1664
	global_load_dwordx4 v[230:233], v[186:187], off offset:1664
	s_waitcnt lgkmcnt(1)
	v_mfma_f32_32x32x16_bf16 v[112:127], v[234:237], v[176:179], v[112:127]
	v_mfma_f32_32x32x16_bf16 v[48:63], v[234:237], v[180:183], v[48:63]
	s_waitcnt lgkmcnt(0)
	v_mfma_f32_32x32x16_bf16 v[96:111], v[238:241], v[176:179], v[96:111]
	v_mfma_f32_32x32x16_bf16 v[32:47], v[238:241], v[180:183], v[32:47]
	ds_read_b128 v[234:237], v192 offset:9280
	ds_read_b128 v[238:241], v192 offset:13888
	s_waitcnt vmcnt(7)
	ds_write_b128 v215, v[168:171] offset:27648
	s_waitcnt vmcnt(6)
	ds_write_b128 v215, v[172:175] offset:64512
	ds_read_b128 v[168:171], v208 offset:96
	ds_read_b128 v[172:175], v208 offset:4704
	s_waitcnt lgkmcnt(5)
	v_mfma_f32_32x32x16_bf16 v[80:95], v[234:237], v[176:179], v[80:95]
	v_mfma_f32_32x32x16_bf16 v[16:31], v[234:237], v[180:183], v[16:31]
	ds_read_b128 v[234:237], v192 offset:96
	s_waitcnt lgkmcnt(5)
	v_mfma_f32_32x32x16_bf16 v[64:79], v[238:241], v[176:179], v[64:79]
	v_mfma_f32_32x32x16_bf16 v[0:15], v[238:241], v[180:183], v[0:15]
	ds_read_b128 v[238:241], v192 offset:4704
	global_load_dwordx4 v[176:179], v[198:199], off offset:1664
	global_load_dwordx4 v[180:183], v[200:201], off offset:1664
	s_waitcnt lgkmcnt(1)
	v_mfma_f32_32x32x16_bf16 v[112:127], v[234:237], v[168:171], v[112:127]
	v_mfma_f32_32x32x16_bf16 v[48:63], v[234:237], v[172:175], v[48:63]
	s_waitcnt lgkmcnt(0)
	v_mfma_f32_32x32x16_bf16 v[96:111], v[238:241], v[168:171], v[96:111]
	v_mfma_f32_32x32x16_bf16 v[32:47], v[238:241], v[172:175], v[32:47]
	ds_read_b128 v[234:237], v192 offset:9312
	ds_read_b128 v[238:241], v192 offset:13920
	s_waitcnt lgkmcnt(1)
	v_mfma_f32_32x32x16_bf16 v[80:95], v[234:237], v[168:171], v[80:95]
	v_mfma_f32_32x32x16_bf16 v[16:31], v[234:237], v[172:175], v[16:31]
	s_waitcnt lgkmcnt(0)
	v_mfma_f32_32x32x16_bf16 v[64:79], v[238:241], v[168:171], v[64:79]
	v_mfma_f32_32x32x16_bf16 v[0:15], v[238:241], v[172:175], v[0:15]
	s_setprio 0
	s_barrier
	global_load_dwordx4 v[168:171], v[190:191], off offset:1792
	global_load_dwordx4 v[172:175], v[188:189], off offset:1792
	s_waitcnt vmcnt(9)
	ds_write_b128 v209, v[160:163]
	s_waitcnt vmcnt(8)
	ds_write_b128 v210, v[164:167]
	ds_read_b128 v[160:163], v205 offset:36864
	ds_read_b128 v[164:167], v205 offset:41472
	ds_read_b128 v[234:237], v204
	ds_read_b128 v[238:241], v204 offset:4608
	s_setprio 1
	s_waitcnt lgkmcnt(1)
	v_mfma_f32_32x32x16_bf16 v[112:127], v[234:237], v[160:163], v[112:127]
	v_mfma_f32_32x32x16_bf16 v[48:63], v[234:237], v[164:167], v[48:63]
	s_waitcnt lgkmcnt(0)
	v_mfma_f32_32x32x16_bf16 v[96:111], v[238:241], v[160:163], v[96:111]
	v_mfma_f32_32x32x16_bf16 v[32:47], v[238:241], v[164:167], v[32:47]
	ds_read_b128 v[234:237], v204 offset:9216
	ds_read_b128 v[238:241], v204 offset:13824
	s_waitcnt vmcnt(7)
	ds_write_b128 v212, v[218:221]
	s_waitcnt vmcnt(6)
	ds_write_b128 v211, v[222:225]
	ds_read_b128 v[218:221], v205 offset:36896
	ds_read_b128 v[222:225], v205 offset:41504
	s_waitcnt lgkmcnt(5)
	v_mfma_f32_32x32x16_bf16 v[80:95], v[234:237], v[160:163], v[80:95]
	v_mfma_f32_32x32x16_bf16 v[16:31], v[234:237], v[164:167], v[16:31]
	ds_read_b128 v[234:237], v204 offset:32
	s_waitcnt lgkmcnt(5)
	v_mfma_f32_32x32x16_bf16 v[64:79], v[238:241], v[160:163], v[64:79]
	v_mfma_f32_32x32x16_bf16 v[0:15], v[238:241], v[164:167], v[0:15]
	ds_read_b128 v[238:241], v204 offset:4640
	global_load_dwordx4 v[160:163], v[194:195], off offset:1792
	global_load_dwordx4 v[164:167], v[196:197], off offset:1792
	s_waitcnt lgkmcnt(1)
	v_mfma_f32_32x32x16_bf16 v[112:127], v[234:237], v[218:221], v[112:127]
	v_mfma_f32_32x32x16_bf16 v[48:63], v[234:237], v[222:225], v[48:63]
	s_waitcnt lgkmcnt(0)
	v_mfma_f32_32x32x16_bf16 v[96:111], v[238:241], v[218:221], v[96:111]
	v_mfma_f32_32x32x16_bf16 v[32:47], v[238:241], v[222:225], v[32:47]
	ds_read_b128 v[234:237], v204 offset:9248
	ds_read_b128 v[238:241], v204 offset:13856
	s_waitcnt vmcnt(7)
	ds_write_b128 v214, v[226:229]
	s_waitcnt vmcnt(6)
	ds_write_b128 v213, v[230:233]
	ds_read_b128 v[226:229], v205 offset:36928
	ds_read_b128 v[230:233], v205 offset:41536
	s_waitcnt lgkmcnt(5)
	v_mfma_f32_32x32x16_bf16 v[80:95], v[234:237], v[218:221], v[80:95]
	v_mfma_f32_32x32x16_bf16 v[16:31], v[234:237], v[222:225], v[16:31]
	ds_read_b128 v[234:237], v204 offset:64
	s_waitcnt lgkmcnt(5)
	v_mfma_f32_32x32x16_bf16 v[64:79], v[238:241], v[218:221], v[64:79]
	v_mfma_f32_32x32x16_bf16 v[0:15], v[238:241], v[222:225], v[0:15]
	ds_read_b128 v[238:241], v204 offset:4672
	global_load_dwordx4 v[218:221], v[184:185], off offset:1792
	global_load_dwordx4 v[222:225], v[186:187], off offset:1792
	s_waitcnt lgkmcnt(1)
	v_mfma_f32_32x32x16_bf16 v[112:127], v[234:237], v[226:229], v[112:127]
	v_mfma_f32_32x32x16_bf16 v[48:63], v[234:237], v[230:233], v[48:63]
	s_waitcnt lgkmcnt(0)
	v_mfma_f32_32x32x16_bf16 v[96:111], v[238:241], v[226:229], v[96:111]
	v_mfma_f32_32x32x16_bf16 v[32:47], v[238:241], v[230:233], v[32:47]
	ds_read_b128 v[234:237], v204 offset:9280
	ds_read_b128 v[238:241], v204 offset:13888
	s_waitcnt vmcnt(7)
	ds_write_b128 v217, v[176:179]
	s_waitcnt vmcnt(6)
	ds_write_b128 v216, v[180:183]
	ds_read_b128 v[176:179], v205 offset:36960
	ds_read_b128 v[180:183], v205 offset:41568
	s_waitcnt lgkmcnt(5)
	v_mfma_f32_32x32x16_bf16 v[80:95], v[234:237], v[226:229], v[80:95]
	v_mfma_f32_32x32x16_bf16 v[16:31], v[234:237], v[230:233], v[16:31]
	ds_read_b128 v[234:237], v204 offset:96
	s_waitcnt lgkmcnt(5)
	v_mfma_f32_32x32x16_bf16 v[64:79], v[238:241], v[226:229], v[64:79]
	v_mfma_f32_32x32x16_bf16 v[0:15], v[238:241], v[230:233], v[0:15]
	ds_read_b128 v[238:241], v204 offset:4704
	global_load_dwordx4 v[226:229], v[198:199], off offset:1792
	global_load_dwordx4 v[230:233], v[200:201], off offset:1792
	s_waitcnt lgkmcnt(1)
	v_mfma_f32_32x32x16_bf16 v[112:127], v[234:237], v[176:179], v[112:127]
	v_mfma_f32_32x32x16_bf16 v[48:63], v[234:237], v[180:183], v[48:63]
	s_waitcnt lgkmcnt(0)
	v_mfma_f32_32x32x16_bf16 v[96:111], v[238:241], v[176:179], v[96:111]
	v_mfma_f32_32x32x16_bf16 v[32:47], v[238:241], v[180:183], v[32:47]
	ds_read_b128 v[234:237], v204 offset:9312
	ds_read_b128 v[238:241], v204 offset:13920
	s_waitcnt lgkmcnt(1)
	v_mfma_f32_32x32x16_bf16 v[80:95], v[234:237], v[176:179], v[80:95]
	v_mfma_f32_32x32x16_bf16 v[16:31], v[234:237], v[180:183], v[16:31]
	s_waitcnt lgkmcnt(0)
	v_mfma_f32_32x32x16_bf16 v[64:79], v[238:241], v[176:179], v[64:79]
	v_mfma_f32_32x32x16_bf16 v[0:15], v[238:241], v[180:183], v[0:15]
	s_setprio 0
	s_barrier
	global_load_dwordx4 v[176:179], v[190:191], off offset:1920
	global_load_dwordx4 v[180:183], v[188:189], off offset:1920
	s_waitcnt vmcnt(9)
	ds_write_b128 v215, v[168:171]
	s_waitcnt vmcnt(8)
	ds_write_b128 v215, v[172:175] offset:36864
	ds_read_b128 v[168:171], v208
	ds_read_b128 v[172:175], v208 offset:4608
	ds_read_b128 v[234:237], v192
	ds_read_b128 v[238:241], v192 offset:4608
	s_setprio 1
	s_waitcnt lgkmcnt(1)
	v_mfma_f32_32x32x16_bf16 v[112:127], v[234:237], v[168:171], v[112:127]
	v_mfma_f32_32x32x16_bf16 v[48:63], v[234:237], v[172:175], v[48:63]
	s_waitcnt lgkmcnt(0)
	v_mfma_f32_32x32x16_bf16 v[96:111], v[238:241], v[168:171], v[96:111]
	v_mfma_f32_32x32x16_bf16 v[32:47], v[238:241], v[172:175], v[32:47]
	ds_read_b128 v[234:237], v192 offset:9216
	ds_read_b128 v[238:241], v192 offset:13824
	s_waitcnt vmcnt(7)
	ds_write_b128 v215, v[160:163] offset:9216
	s_waitcnt vmcnt(6)
	ds_write_b128 v215, v[164:167] offset:46080
	ds_read_b128 v[160:163], v208 offset:32
	ds_read_b128 v[164:167], v208 offset:4640
	s_waitcnt lgkmcnt(5)
	v_mfma_f32_32x32x16_bf16 v[80:95], v[234:237], v[168:171], v[80:95]
	v_mfma_f32_32x32x16_bf16 v[16:31], v[234:237], v[172:175], v[16:31]
	ds_read_b128 v[234:237], v192 offset:32
	s_waitcnt lgkmcnt(5)
	v_mfma_f32_32x32x16_bf16 v[64:79], v[238:241], v[168:171], v[64:79]
	v_mfma_f32_32x32x16_bf16 v[0:15], v[238:241], v[172:175], v[0:15]
	ds_read_b128 v[238:241], v192 offset:4640
	global_load_dwordx4 v[168:171], v[194:195], off offset:1920
	global_load_dwordx4 v[172:175], v[196:197], off offset:1920
	s_waitcnt lgkmcnt(1)
	v_mfma_f32_32x32x16_bf16 v[112:127], v[234:237], v[160:163], v[112:127]
	v_mfma_f32_32x32x16_bf16 v[48:63], v[234:237], v[164:167], v[48:63]
	s_waitcnt lgkmcnt(0)
	v_mfma_f32_32x32x16_bf16 v[96:111], v[238:241], v[160:163], v[96:111]
	v_mfma_f32_32x32x16_bf16 v[32:47], v[238:241], v[164:167], v[32:47]
	ds_read_b128 v[234:237], v192 offset:9248
	ds_read_b128 v[238:241], v192 offset:13856
	s_waitcnt vmcnt(7)
	ds_write_b128 v215, v[218:221] offset:18432
	s_waitcnt vmcnt(6)
	ds_write_b128 v215, v[222:225] offset:55296
	ds_read_b128 v[218:221], v208 offset:64
	ds_read_b128 v[222:225], v208 offset:4672
	s_waitcnt lgkmcnt(5)
	v_mfma_f32_32x32x16_bf16 v[80:95], v[234:237], v[160:163], v[80:95]
	v_mfma_f32_32x32x16_bf16 v[16:31], v[234:237], v[164:167], v[16:31]
	ds_read_b128 v[234:237], v192 offset:64
	s_waitcnt lgkmcnt(5)
	v_mfma_f32_32x32x16_bf16 v[64:79], v[238:241], v[160:163], v[64:79]
	v_mfma_f32_32x32x16_bf16 v[0:15], v[238:241], v[164:167], v[0:15]
	ds_read_b128 v[238:241], v192 offset:4672
	global_load_dwordx4 v[160:163], v[184:185], off offset:1920
	global_load_dwordx4 v[164:167], v[186:187], off offset:1920
	s_waitcnt lgkmcnt(1)
	v_mfma_f32_32x32x16_bf16 v[112:127], v[234:237], v[218:221], v[112:127]
	v_mfma_f32_32x32x16_bf16 v[48:63], v[234:237], v[222:225], v[48:63]
	s_waitcnt lgkmcnt(0)
	v_mfma_f32_32x32x16_bf16 v[96:111], v[238:241], v[218:221], v[96:111]
	v_mfma_f32_32x32x16_bf16 v[32:47], v[238:241], v[222:225], v[32:47]
	ds_read_b128 v[234:237], v192 offset:9280
	ds_read_b128 v[238:241], v192 offset:13888
	s_waitcnt vmcnt(7)
	ds_write_b128 v215, v[226:229] offset:27648
	s_waitcnt vmcnt(6)
	ds_write_b128 v215, v[230:233] offset:64512
	ds_read_b128 v[226:229], v208 offset:96
	ds_read_b128 v[230:233], v208 offset:4704
	s_waitcnt lgkmcnt(5)
	v_mfma_f32_32x32x16_bf16 v[80:95], v[234:237], v[218:221], v[80:95]
	v_mfma_f32_32x32x16_bf16 v[16:31], v[234:237], v[222:225], v[16:31]
	ds_read_b128 v[234:237], v192 offset:96
	s_waitcnt lgkmcnt(5)
	v_mfma_f32_32x32x16_bf16 v[64:79], v[238:241], v[218:221], v[64:79]
	v_mfma_f32_32x32x16_bf16 v[0:15], v[238:241], v[222:225], v[0:15]
	ds_read_b128 v[238:241], v192 offset:4704
	global_load_dwordx4 v[218:221], v[198:199], off offset:1920
	global_load_dwordx4 v[222:225], v[200:201], off offset:1920
	s_waitcnt lgkmcnt(1)
	v_mfma_f32_32x32x16_bf16 v[112:127], v[234:237], v[226:229], v[112:127]
	v_mfma_f32_32x32x16_bf16 v[48:63], v[234:237], v[230:233], v[48:63]
	s_waitcnt lgkmcnt(0)
	v_mfma_f32_32x32x16_bf16 v[96:111], v[238:241], v[226:229], v[96:111]
	v_mfma_f32_32x32x16_bf16 v[32:47], v[238:241], v[230:233], v[32:47]
	ds_read_b128 v[234:237], v192 offset:9312
	ds_read_b128 v[238:241], v192 offset:13920
	s_waitcnt lgkmcnt(1)
	v_mfma_f32_32x32x16_bf16 v[80:95], v[234:237], v[226:229], v[80:95]
	v_mfma_f32_32x32x16_bf16 v[16:31], v[234:237], v[230:233], v[16:31]
	s_waitcnt lgkmcnt(0)
	v_mfma_f32_32x32x16_bf16 v[64:79], v[238:241], v[226:229], v[64:79]
	v_mfma_f32_32x32x16_bf16 v[0:15], v[238:241], v[230:233], v[0:15]
	s_setprio 0
	s_barrier
	global_load_dwordx4 v[226:229], v[190:191], off offset:2048
	global_load_dwordx4 v[230:233], v[188:189], off offset:2048
	s_waitcnt vmcnt(9)
	ds_write_b128 v209, v[176:179]
	s_waitcnt vmcnt(8)
	ds_write_b128 v210, v[180:183]
	ds_read_b128 v[176:179], v205 offset:36864
	ds_read_b128 v[180:183], v205 offset:41472
	ds_read_b128 v[234:237], v204
	ds_read_b128 v[238:241], v204 offset:4608
	s_setprio 1
	s_waitcnt lgkmcnt(1)
	v_mfma_f32_32x32x16_bf16 v[112:127], v[234:237], v[176:179], v[112:127]
	v_mfma_f32_32x32x16_bf16 v[48:63], v[234:237], v[180:183], v[48:63]
	s_waitcnt lgkmcnt(0)
	v_mfma_f32_32x32x16_bf16 v[96:111], v[238:241], v[176:179], v[96:111]
	v_mfma_f32_32x32x16_bf16 v[32:47], v[238:241], v[180:183], v[32:47]
	ds_read_b128 v[234:237], v204 offset:9216
	ds_read_b128 v[238:241], v204 offset:13824
	s_waitcnt vmcnt(7)
	ds_write_b128 v212, v[168:171]
	s_waitcnt vmcnt(6)
	ds_write_b128 v211, v[172:175]
	ds_read_b128 v[168:171], v205 offset:36896
	ds_read_b128 v[172:175], v205 offset:41504
	s_waitcnt lgkmcnt(5)
	v_mfma_f32_32x32x16_bf16 v[80:95], v[234:237], v[176:179], v[80:95]
	v_mfma_f32_32x32x16_bf16 v[16:31], v[234:237], v[180:183], v[16:31]
	ds_read_b128 v[234:237], v204 offset:32
	s_waitcnt lgkmcnt(5)
	v_mfma_f32_32x32x16_bf16 v[64:79], v[238:241], v[176:179], v[64:79]
	v_mfma_f32_32x32x16_bf16 v[0:15], v[238:241], v[180:183], v[0:15]
	ds_read_b128 v[238:241], v204 offset:4640
	global_load_dwordx4 v[176:179], v[194:195], off offset:2048
	global_load_dwordx4 v[180:183], v[196:197], off offset:2048
	s_waitcnt lgkmcnt(1)
	v_mfma_f32_32x32x16_bf16 v[112:127], v[234:237], v[168:171], v[112:127]
	v_mfma_f32_32x32x16_bf16 v[48:63], v[234:237], v[172:175], v[48:63]
	s_waitcnt lgkmcnt(0)
	v_mfma_f32_32x32x16_bf16 v[96:111], v[238:241], v[168:171], v[96:111]
	v_mfma_f32_32x32x16_bf16 v[32:47], v[238:241], v[172:175], v[32:47]
	ds_read_b128 v[234:237], v204 offset:9248
	ds_read_b128 v[238:241], v204 offset:13856
	s_waitcnt vmcnt(7)
	ds_write_b128 v214, v[160:163]
	s_waitcnt vmcnt(6)
	ds_write_b128 v213, v[164:167]
	ds_read_b128 v[160:163], v205 offset:36928
	ds_read_b128 v[164:167], v205 offset:41536
	s_waitcnt lgkmcnt(5)
	v_mfma_f32_32x32x16_bf16 v[80:95], v[234:237], v[168:171], v[80:95]
	v_mfma_f32_32x32x16_bf16 v[16:31], v[234:237], v[172:175], v[16:31]
	ds_read_b128 v[234:237], v204 offset:64
	s_waitcnt lgkmcnt(5)
	v_mfma_f32_32x32x16_bf16 v[64:79], v[238:241], v[168:171], v[64:79]
	v_mfma_f32_32x32x16_bf16 v[0:15], v[238:241], v[172:175], v[0:15]
	ds_read_b128 v[238:241], v204 offset:4672
	global_load_dwordx4 v[168:171], v[184:185], off offset:2048
	global_load_dwordx4 v[172:175], v[186:187], off offset:2048
	s_waitcnt lgkmcnt(1)
	v_mfma_f32_32x32x16_bf16 v[112:127], v[234:237], v[160:163], v[112:127]
	v_mfma_f32_32x32x16_bf16 v[48:63], v[234:237], v[164:167], v[48:63]
	s_waitcnt lgkmcnt(0)
	v_mfma_f32_32x32x16_bf16 v[96:111], v[238:241], v[160:163], v[96:111]
	v_mfma_f32_32x32x16_bf16 v[32:47], v[238:241], v[164:167], v[32:47]
	ds_read_b128 v[234:237], v204 offset:9280
	ds_read_b128 v[238:241], v204 offset:13888
	s_waitcnt vmcnt(7)
	ds_write_b128 v217, v[218:221]
	s_waitcnt vmcnt(6)
	ds_write_b128 v216, v[222:225]
	ds_read_b128 v[218:221], v205 offset:36960
	ds_read_b128 v[222:225], v205 offset:41568
	s_waitcnt lgkmcnt(5)
	v_mfma_f32_32x32x16_bf16 v[80:95], v[234:237], v[160:163], v[80:95]
	v_mfma_f32_32x32x16_bf16 v[16:31], v[234:237], v[164:167], v[16:31]
	ds_read_b128 v[234:237], v204 offset:96
	s_waitcnt lgkmcnt(5)
	v_mfma_f32_32x32x16_bf16 v[64:79], v[238:241], v[160:163], v[64:79]
	v_mfma_f32_32x32x16_bf16 v[0:15], v[238:241], v[164:167], v[0:15]
	ds_read_b128 v[238:241], v204 offset:4704
	global_load_dwordx4 v[160:163], v[198:199], off offset:2048
	global_load_dwordx4 v[164:167], v[200:201], off offset:2048
	s_waitcnt lgkmcnt(1)
	v_mfma_f32_32x32x16_bf16 v[112:127], v[234:237], v[218:221], v[112:127]
	v_mfma_f32_32x32x16_bf16 v[48:63], v[234:237], v[222:225], v[48:63]
	s_waitcnt lgkmcnt(0)
	v_mfma_f32_32x32x16_bf16 v[96:111], v[238:241], v[218:221], v[96:111]
	v_mfma_f32_32x32x16_bf16 v[32:47], v[238:241], v[222:225], v[32:47]
	ds_read_b128 v[234:237], v204 offset:9312
	ds_read_b128 v[238:241], v204 offset:13920
	s_waitcnt lgkmcnt(1)
	v_mfma_f32_32x32x16_bf16 v[80:95], v[234:237], v[218:221], v[80:95]
	v_mfma_f32_32x32x16_bf16 v[16:31], v[234:237], v[222:225], v[16:31]
	s_waitcnt lgkmcnt(0)
	v_mfma_f32_32x32x16_bf16 v[64:79], v[238:241], v[218:221], v[64:79]
	v_mfma_f32_32x32x16_bf16 v[0:15], v[238:241], v[222:225], v[0:15]
	s_setprio 0
	s_barrier
; template <bool trans>
; DI void gemm_core(const GTile& tl, const GTile& nx, bool has_next  , bool chain  , bool pre, u32x4 (&ra)[4], u32x4 (&rb)[4], char* smem, f32x16 (&acc)[2][4]) {
;     ...
;   const int nk = K / 64;
;   if (!pre) { G_LOAD(0); G_STORE(0); G_LOAD(1); }
;   for (int kt = 0; kt < nk; ++kt) {
;     __syncthreads();
;     G_COMPUTE(kt & 1, kt);
;   }
	global_load_dwordx4 v[218:221], v[190:191], off offset:2176
	global_load_dwordx4 v[222:225], v[188:189], off offset:2176
	s_waitcnt vmcnt(9)
	ds_write_b128 v215, v[226:229]
	s_waitcnt vmcnt(8)
	ds_write_b128 v215, v[230:233] offset:36864
	ds_read_b128 v[226:229], v208
	ds_read_b128 v[230:233], v208 offset:4608
	ds_read_b128 v[234:237], v192
	ds_read_b128 v[238:241], v192 offset:4608
	s_setprio 1
	s_waitcnt lgkmcnt(1)
	v_mfma_f32_32x32x16_bf16 v[112:127], v[234:237], v[226:229], v[112:127]
	v_mfma_f32_32x32x16_bf16 v[48:63], v[234:237], v[230:233], v[48:63]
	s_waitcnt lgkmcnt(0)
	v_mfma_f32_32x32x16_bf16 v[96:111], v[238:241], v[226:229], v[96:111]
	v_mfma_f32_32x32x16_bf16 v[32:47], v[238:241], v[230:233], v[32:47]
	ds_read_b128 v[234:237], v192 offset:9216
	ds_read_b128 v[238:241], v192 offset:13824
	s_waitcnt vmcnt(7)
	ds_write_b128 v215, v[176:179] offset:9216
	s_waitcnt vmcnt(6)
	ds_write_b128 v215, v[180:183] offset:46080
	ds_read_b128 v[176:179], v208 offset:32
	ds_read_b128 v[180:183], v208 offset:4640
	s_waitcnt lgkmcnt(5)
	v_mfma_f32_32x32x16_bf16 v[80:95], v[234:237], v[226:229], v[80:95]
	v_mfma_f32_32x32x16_bf16 v[16:31], v[234:237], v[230:233], v[16:31]
	ds_read_b128 v[234:237], v192 offset:32
	s_waitcnt lgkmcnt(5)
	v_mfma_f32_32x32x16_bf16 v[64:79], v[238:241], v[226:229], v[64:79]
	v_mfma_f32_32x32x16_bf16 v[0:15], v[238:241], v[230:233], v[0:15]
	ds_read_b128 v[238:241], v192 offset:4640
	global_load_dwordx4 v[226:229], v[194:195], off offset:2176
	global_load_dwordx4 v[230:233], v[196:197], off offset:2176
	s_waitcnt lgkmcnt(1)
	v_mfma_f32_32x32x16_bf16 v[112:127], v[234:237], v[176:179], v[112:127]
	v_mfma_f32_32x32x16_bf16 v[48:63], v[234:237], v[180:183], v[48:63]
	s_waitcnt lgkmcnt(0)
	v_mfma_f32_32x32x16_bf16 v[96:111], v[238:241], v[176:179], v[96:111]
	v_mfma_f32_32x32x16_bf16 v[32:47], v[238:241], v[180:183], v[32:47]
	ds_read_b128 v[234:237], v192 offset:9248
	ds_read_b128 v[238:241], v192 offset:13856
	s_waitcnt vmcnt(7)
	ds_write_b128 v215, v[168:171] offset:18432
	s_waitcnt vmcnt(6)
	ds_write_b128 v215, v[172:175] offset:55296
	ds_read_b128 v[168:171], v208 offset:64
	ds_read_b128 v[172:175], v208 offset:4672
	s_waitcnt lgkmcnt(5)
	v_mfma_f32_32x32x16_bf16 v[80:95], v[234:237], v[176:179], v[80:95]
	v_mfma_f32_32x32x16_bf16 v[16:31], v[234:237], v[180:183], v[16:31]
	ds_read_b128 v[234:237], v192 offset:64
	s_waitcnt lgkmcnt(5)
	v_mfma_f32_32x32x16_bf16 v[64:79], v[238:241], v[176:179], v[64:79]
	v_mfma_f32_32x32x16_bf16 v[0:15], v[238:241], v[180:183], v[0:15]
	ds_read_b128 v[238:241], v192 offset:4672
	global_load_dwordx4 v[176:179], v[184:185], off offset:2176
	global_load_dwordx4 v[180:183], v[186:187], off offset:2176
	s_waitcnt lgkmcnt(1)
	v_mfma_f32_32x32x16_bf16 v[112:127], v[234:237], v[168:171], v[112:127]
	v_mfma_f32_32x32x16_bf16 v[48:63], v[234:237], v[172:175], v[48:63]
	s_waitcnt lgkmcnt(0)
	v_mfma_f32_32x32x16_bf16 v[96:111], v[238:241], v[168:171], v[96:111]
	v_mfma_f32_32x32x16_bf16 v[32:47], v[238:241], v[172:175], v[32:47]
	ds_read_b128 v[234:237], v192 offset:9280
	ds_read_b128 v[238:241], v192 offset:13888
	s_waitcnt vmcnt(7)
	ds_write_b128 v215, v[160:163] offset:27648
	s_waitcnt vmcnt(6)
	ds_write_b128 v215, v[164:167] offset:64512
	ds_read_b128 v[160:163], v208 offset:96
	ds_read_b128 v[164:167], v208 offset:4704
	s_waitcnt lgkmcnt(5)
	v_mfma_f32_32x32x16_bf16 v[80:95], v[234:237], v[168:171], v[80:95]
	v_mfma_f32_32x32x16_bf16 v[16:31], v[234:237], v[172:175], v[16:31]
	ds_read_b128 v[234:237], v192 offset:96
	s_waitcnt lgkmcnt(5)
	v_mfma_f32_32x32x16_bf16 v[64:79], v[238:241], v[168:171], v[64:79]
	v_mfma_f32_32x32x16_bf16 v[0:15], v[238:241], v[172:175], v[0:15]
	ds_read_b128 v[238:241], v192 offset:4704
	global_load_dwordx4 v[168:171], v[198:199], off offset:2176
	global_load_dwordx4 v[172:175], v[200:201], off offset:2176
	s_waitcnt lgkmcnt(1)
	v_mfma_f32_32x32x16_bf16 v[112:127], v[234:237], v[160:163], v[112:127]
	v_mfma_f32_32x32x16_bf16 v[48:63], v[234:237], v[164:167], v[48:63]
	s_waitcnt lgkmcnt(0)
	v_mfma_f32_32x32x16_bf16 v[96:111], v[238:241], v[160:163], v[96:111]
	v_mfma_f32_32x32x16_bf16 v[32:47], v[238:241], v[164:167], v[32:47]
	ds_read_b128 v[234:237], v192 offset:9312
	ds_read_b128 v[238:241], v192 offset:13920
	s_waitcnt lgkmcnt(1)
	v_mfma_f32_32x32x16_bf16 v[80:95], v[234:237], v[160:163], v[80:95]
	v_mfma_f32_32x32x16_bf16 v[16:31], v[234:237], v[164:167], v[16:31]
	s_waitcnt lgkmcnt(0)
	v_mfma_f32_32x32x16_bf16 v[64:79], v[238:241], v[160:163], v[64:79]
	v_mfma_f32_32x32x16_bf16 v[0:15], v[238:241], v[164:167], v[0:15]
	s_setprio 0
	s_barrier
; template <bool trans>
; DI void gemm_core(const GTile& tl, const GTile& nx, bool has_next  , bool chain  , bool pre, u32x4 (&ra)[4], u32x4 (&rb)[4], char* smem, f32x16 (&acc)[2][4]) {
;     ...
;   const int nk = K / 64;
;   if (!pre) { G_LOAD(0); G_STORE(0); G_LOAD(1); }
;   for (int kt = 0; kt < nk; ++kt) {
;     __syncthreads();
;     G_COMPUTE(kt & 1, kt);
;   }
	global_load_dwordx4 v[160:163], v[190:191], off offset:2304
	global_load_dwordx4 v[164:167], v[188:189], off offset:2304
	s_waitcnt vmcnt(9)
	ds_write_b128 v209, v[218:221]
	s_waitcnt vmcnt(8)
	ds_write_b128 v210, v[222:225]
	ds_read_b128 v[218:221], v205 offset:36864
	ds_read_b128 v[222:225], v205 offset:41472
	ds_read_b128 v[234:237], v204
	ds_read_b128 v[238:241], v204 offset:4608
	s_setprio 1
	s_waitcnt lgkmcnt(1)
	v_mfma_f32_32x32x16_bf16 v[112:127], v[234:237], v[218:221], v[112:127]
	v_mfma_f32_32x32x16_bf16 v[48:63], v[234:237], v[222:225], v[48:63]
	s_waitcnt lgkmcnt(0)
	v_mfma_f32_32x32x16_bf16 v[96:111], v[238:241], v[218:221], v[96:111]
	v_mfma_f32_32x32x16_bf16 v[32:47], v[238:241], v[222:225], v[32:47]
	ds_read_b128 v[234:237], v204 offset:9216
	ds_read_b128 v[238:241], v204 offset:13824
	s_waitcnt vmcnt(7)
	ds_write_b128 v212, v[226:229]
	s_waitcnt vmcnt(6)
	ds_write_b128 v211, v[230:233]
	ds_read_b128 v[226:229], v205 offset:36896
	ds_read_b128 v[230:233], v205 offset:41504
	s_waitcnt lgkmcnt(5)
	v_mfma_f32_32x32x16_bf16 v[80:95], v[234:237], v[218:221], v[80:95]
	v_mfma_f32_32x32x16_bf16 v[16:31], v[234:237], v[222:225], v[16:31]
	ds_read_b128 v[234:237], v204 offset:32
	s_waitcnt lgkmcnt(5)
	v_mfma_f32_32x32x16_bf16 v[64:79], v[238:241], v[218:221], v[64:79]
	v_mfma_f32_32x32x16_bf16 v[0:15], v[238:241], v[222:225], v[0:15]
	ds_read_b128 v[238:241], v204 offset:4640
	global_load_dwordx4 v[218:221], v[194:195], off offset:2304
	global_load_dwordx4 v[222:225], v[196:197], off offset:2304
	s_waitcnt lgkmcnt(1)
	v_mfma_f32_32x32x16_bf16 v[112:127], v[234:237], v[226:229], v[112:127]
	v_mfma_f32_32x32x16_bf16 v[48:63], v[234:237], v[230:233], v[48:63]
	s_waitcnt lgkmcnt(0)
	v_mfma_f32_32x32x16_bf16 v[96:111], v[238:241], v[226:229], v[96:111]
	v_mfma_f32_32x32x16_bf16 v[32:47], v[238:241], v[230:233], v[32:47]
	ds_read_b128 v[234:237], v204 offset:9248
	ds_read_b128 v[238:241], v204 offset:13856
	s_waitcnt vmcnt(7)
	ds_write_b128 v214, v[176:179]
	s_waitcnt vmcnt(6)
	ds_write_b128 v213, v[180:183]
	ds_read_b128 v[176:179], v205 offset:36928
	ds_read_b128 v[180:183], v205 offset:41536
	s_waitcnt lgkmcnt(5)
	v_mfma_f32_32x32x16_bf16 v[80:95], v[234:237], v[226:229], v[80:95]
	v_mfma_f32_32x32x16_bf16 v[16:31], v[234:237], v[230:233], v[16:31]
	ds_read_b128 v[234:237], v204 offset:64
	s_waitcnt lgkmcnt(5)
	v_mfma_f32_32x32x16_bf16 v[64:79], v[238:241], v[226:229], v[64:79]
	v_mfma_f32_32x32x16_bf16 v[0:15], v[238:241], v[230:233], v[0:15]
	ds_read_b128 v[238:241], v204 offset:4672
	global_load_dwordx4 v[226:229], v[184:185], off offset:2304
	global_load_dwordx4 v[230:233], v[186:187], off offset:2304
	s_waitcnt lgkmcnt(1)
	v_mfma_f32_32x32x16_bf16 v[112:127], v[234:237], v[176:179], v[112:127]
	v_mfma_f32_32x32x16_bf16 v[48:63], v[234:237], v[180:183], v[48:63]
	s_waitcnt lgkmcnt(0)
	v_mfma_f32_32x32x16_bf16 v[96:111], v[238:241], v[176:179], v[96:111]
	v_mfma_f32_32x32x16_bf16 v[32:47], v[238:241], v[180:183], v[32:47]
	ds_read_b128 v[234:237], v204 offset:9280
	ds_read_b128 v[238:241], v204 offset:13888
	s_waitcnt vmcnt(7)
	ds_write_b128 v217, v[168:171]
	s_waitcnt vmcnt(6)
	ds_write_b128 v216, v[172:175]
	ds_read_b128 v[168:171], v205 offset:36960
	ds_read_b128 v[172:175], v205 offset:41568
	s_waitcnt lgkmcnt(5)
	v_mfma_f32_32x32x16_bf16 v[80:95], v[234:237], v[176:179], v[80:95]
	v_mfma_f32_32x32x16_bf16 v[16:31], v[234:237], v[180:183], v[16:31]
	ds_read_b128 v[234:237], v204 offset:96
	s_waitcnt lgkmcnt(5)
	v_mfma_f32_32x32x16_bf16 v[64:79], v[238:241], v[176:179], v[64:79]
	v_mfma_f32_32x32x16_bf16 v[0:15], v[238:241], v[180:183], v[0:15]
	ds_read_b128 v[238:241], v204 offset:4704
	global_load_dwordx4 v[176:179], v[198:199], off offset:2304
	global_load_dwordx4 v[180:183], v[200:201], off offset:2304
	s_waitcnt lgkmcnt(1)
	v_mfma_f32_32x32x16_bf16 v[112:127], v[234:237], v[168:171], v[112:127]
	v_mfma_f32_32x32x16_bf16 v[48:63], v[234:237], v[172:175], v[48:63]
	s_waitcnt lgkmcnt(0)
	v_mfma_f32_32x32x16_bf16 v[96:111], v[238:241], v[168:171], v[96:111]
	v_mfma_f32_32x32x16_bf16 v[32:47], v[238:241], v[172:175], v[32:47]
	ds_read_b128 v[234:237], v204 offset:9312
	ds_read_b128 v[238:241], v204 offset:13920
	s_waitcnt lgkmcnt(1)
	v_mfma_f32_32x32x16_bf16 v[80:95], v[234:237], v[168:171], v[80:95]
	v_mfma_f32_32x32x16_bf16 v[16:31], v[234:237], v[172:175], v[16:31]
	s_waitcnt lgkmcnt(0)
	v_mfma_f32_32x32x16_bf16 v[64:79], v[238:241], v[168:171], v[64:79]
	v_mfma_f32_32x32x16_bf16 v[0:15], v[238:241], v[172:175], v[0:15]
	s_setprio 0
	s_barrier
; template <bool trans>
; DI void gemm_core(const GTile& tl, const GTile& nx, bool has_next  , bool chain  , bool pre, u32x4 (&ra)[4], u32x4 (&rb)[4], char* smem, f32x16 (&acc)[2][4]) {
;     ...
;   const int nk = K / 64;
;   if (!pre) { G_LOAD(0); G_STORE(0); G_LOAD(1); }
;   for (int kt = 0; kt < nk; ++kt) {
;     __syncthreads();
;     G_COMPUTE(kt & 1, kt);
;   }
	global_load_dwordx4 v[168:171], v[190:191], off offset:2432
	global_load_dwordx4 v[172:175], v[188:189], off offset:2432
	s_waitcnt vmcnt(9)
	ds_write_b128 v215, v[160:163]
	s_waitcnt vmcnt(8)
	ds_write_b128 v215, v[164:167] offset:36864
	ds_read_b128 v[160:163], v208
	ds_read_b128 v[164:167], v208 offset:4608
	ds_read_b128 v[234:237], v192
	ds_read_b128 v[238:241], v192 offset:4608
	s_setprio 1
	s_waitcnt lgkmcnt(1)
	v_mfma_f32_32x32x16_bf16 v[112:127], v[234:237], v[160:163], v[112:127]
	v_mfma_f32_32x32x16_bf16 v[48:63], v[234:237], v[164:167], v[48:63]
	s_waitcnt lgkmcnt(0)
	v_mfma_f32_32x32x16_bf16 v[96:111], v[238:241], v[160:163], v[96:111]
	v_mfma_f32_32x32x16_bf16 v[32:47], v[238:241], v[164:167], v[32:47]
	ds_read_b128 v[234:237], v192 offset:9216
	ds_read_b128 v[238:241], v192 offset:13824
	s_waitcnt vmcnt(7)
	ds_write_b128 v215, v[218:221] offset:9216
	s_waitcnt vmcnt(6)
	ds_write_b128 v215, v[222:225] offset:46080
	ds_read_b128 v[218:221], v208 offset:32
	ds_read_b128 v[222:225], v208 offset:4640
	s_waitcnt lgkmcnt(5)
	v_mfma_f32_32x32x16_bf16 v[80:95], v[234:237], v[160:163], v[80:95]
	v_mfma_f32_32x32x16_bf16 v[16:31], v[234:237], v[164:167], v[16:31]
	ds_read_b128 v[234:237], v192 offset:32
	s_waitcnt lgkmcnt(5)
	v_mfma_f32_32x32x16_bf16 v[64:79], v[238:241], v[160:163], v[64:79]
	v_mfma_f32_32x32x16_bf16 v[0:15], v[238:241], v[164:167], v[0:15]
	ds_read_b128 v[238:241], v192 offset:4640
	global_load_dwordx4 v[160:163], v[194:195], off offset:2432
	global_load_dwordx4 v[164:167], v[196:197], off offset:2432
	s_waitcnt lgkmcnt(1)
	v_mfma_f32_32x32x16_bf16 v[112:127], v[234:237], v[218:221], v[112:127]
	v_mfma_f32_32x32x16_bf16 v[48:63], v[234:237], v[222:225], v[48:63]
	s_waitcnt lgkmcnt(0)
	v_mfma_f32_32x32x16_bf16 v[96:111], v[238:241], v[218:221], v[96:111]
	v_mfma_f32_32x32x16_bf16 v[32:47], v[238:241], v[222:225], v[32:47]
	ds_read_b128 v[234:237], v192 offset:9248
	ds_read_b128 v[238:241], v192 offset:13856
	s_waitcnt vmcnt(7)
	ds_write_b128 v215, v[226:229] offset:18432
	s_waitcnt vmcnt(6)
	ds_write_b128 v215, v[230:233] offset:55296
	ds_read_b128 v[226:229], v208 offset:64
	ds_read_b128 v[230:233], v208 offset:4672
	s_waitcnt lgkmcnt(5)
	v_mfma_f32_32x32x16_bf16 v[80:95], v[234:237], v[218:221], v[80:95]
	v_mfma_f32_32x32x16_bf16 v[16:31], v[234:237], v[222:225], v[16:31]
	ds_read_b128 v[234:237], v192 offset:64
	s_waitcnt lgkmcnt(5)
	v_mfma_f32_32x32x16_bf16 v[64:79], v[238:241], v[218:221], v[64:79]
	v_mfma_f32_32x32x16_bf16 v[0:15], v[238:241], v[222:225], v[0:15]
	ds_read_b128 v[238:241], v192 offset:4672
	global_load_dwordx4 v[218:221], v[184:185], off offset:2432
	global_load_dwordx4 v[222:225], v[186:187], off offset:2432
	s_waitcnt lgkmcnt(1)
	v_mfma_f32_32x32x16_bf16 v[112:127], v[234:237], v[226:229], v[112:127]
	v_mfma_f32_32x32x16_bf16 v[48:63], v[234:237], v[230:233], v[48:63]
	s_waitcnt lgkmcnt(0)
	v_mfma_f32_32x32x16_bf16 v[96:111], v[238:241], v[226:229], v[96:111]
	v_mfma_f32_32x32x16_bf16 v[32:47], v[238:241], v[230:233], v[32:47]
	ds_read_b128 v[234:237], v192 offset:9280
	ds_read_b128 v[238:241], v192 offset:13888
	s_waitcnt vmcnt(7)
	ds_write_b128 v215, v[176:179] offset:27648
	s_waitcnt vmcnt(6)
	ds_write_b128 v215, v[180:183] offset:64512
	ds_read_b128 v[176:179], v208 offset:96
	ds_read_b128 v[180:183], v208 offset:4704
	s_waitcnt lgkmcnt(5)
	v_mfma_f32_32x32x16_bf16 v[80:95], v[234:237], v[226:229], v[80:95]
	v_mfma_f32_32x32x16_bf16 v[16:31], v[234:237], v[230:233], v[16:31]
	ds_read_b128 v[234:237], v192 offset:96
	s_waitcnt lgkmcnt(5)
	v_mfma_f32_32x32x16_bf16 v[64:79], v[238:241], v[226:229], v[64:79]
	v_mfma_f32_32x32x16_bf16 v[0:15], v[238:241], v[230:233], v[0:15]
	ds_read_b128 v[238:241], v192 offset:4704
	global_load_dwordx4 v[226:229], v[198:199], off offset:2432
	global_load_dwordx4 v[230:233], v[200:201], off offset:2432
	s_waitcnt lgkmcnt(1)
	v_mfma_f32_32x32x16_bf16 v[112:127], v[234:237], v[176:179], v[112:127]
	v_mfma_f32_32x32x16_bf16 v[48:63], v[234:237], v[180:183], v[48:63]
	s_waitcnt lgkmcnt(0)
	v_mfma_f32_32x32x16_bf16 v[96:111], v[238:241], v[176:179], v[96:111]
	v_mfma_f32_32x32x16_bf16 v[32:47], v[238:241], v[180:183], v[32:47]
	ds_read_b128 v[234:237], v192 offset:9312
	ds_read_b128 v[238:241], v192 offset:13920
	s_waitcnt lgkmcnt(1)
	v_mfma_f32_32x32x16_bf16 v[80:95], v[234:237], v[176:179], v[80:95]
	v_mfma_f32_32x32x16_bf16 v[16:31], v[234:237], v[180:183], v[16:31]
	s_waitcnt lgkmcnt(0)
	v_mfma_f32_32x32x16_bf16 v[64:79], v[238:241], v[176:179], v[64:79]
	v_mfma_f32_32x32x16_bf16 v[0:15], v[238:241], v[180:183], v[0:15]
	s_setprio 0
	s_barrier
; template <bool trans>
; DI void gemm_core(const GTile& tl, const GTile& nx, bool has_next  , bool chain  , bool pre, u32x4 (&ra)[4], u32x4 (&rb)[4], char* smem, f32x16 (&acc)[2][4]) {
;     ...
;   const int nk = K / 64;
;   if (!pre) { G_LOAD(0); G_STORE(0); G_LOAD(1); }
;   for (int kt = 0; kt < nk; ++kt) {
;     __syncthreads();
;     G_COMPUTE(kt & 1, kt);
;   }
	global_load_dwordx4 v[176:179], v[190:191], off offset:2560
	global_load_dwordx4 v[180:183], v[188:189], off offset:2560
	s_waitcnt vmcnt(9)
	ds_write_b128 v209, v[168:171]
	s_waitcnt vmcnt(8)
	ds_write_b128 v210, v[172:175]
	ds_read_b128 v[168:171], v205 offset:36864
	ds_read_b128 v[172:175], v205 offset:41472
	ds_read_b128 v[234:237], v204
	ds_read_b128 v[238:241], v204 offset:4608
	s_setprio 1
	s_waitcnt lgkmcnt(1)
	v_mfma_f32_32x32x16_bf16 v[112:127], v[234:237], v[168:171], v[112:127]
	v_mfma_f32_32x32x16_bf16 v[48:63], v[234:237], v[172:175], v[48:63]
	s_waitcnt lgkmcnt(0)
	v_mfma_f32_32x32x16_bf16 v[96:111], v[238:241], v[168:171], v[96:111]
	v_mfma_f32_32x32x16_bf16 v[32:47], v[238:241], v[172:175], v[32:47]
	ds_read_b128 v[234:237], v204 offset:9216
	ds_read_b128 v[238:241], v204 offset:13824
	s_waitcnt vmcnt(7)
	ds_write_b128 v212, v[160:163]
	s_waitcnt vmcnt(6)
	ds_write_b128 v211, v[164:167]
	ds_read_b128 v[160:163], v205 offset:36896
	ds_read_b128 v[164:167], v205 offset:41504
	s_waitcnt lgkmcnt(5)
	v_mfma_f32_32x32x16_bf16 v[80:95], v[234:237], v[168:171], v[80:95]
	v_mfma_f32_32x32x16_bf16 v[16:31], v[234:237], v[172:175], v[16:31]
	ds_read_b128 v[234:237], v204 offset:32
	s_waitcnt lgkmcnt(5)
	v_mfma_f32_32x32x16_bf16 v[64:79], v[238:241], v[168:171], v[64:79]
	v_mfma_f32_32x32x16_bf16 v[0:15], v[238:241], v[172:175], v[0:15]
	ds_read_b128 v[238:241], v204 offset:4640
	global_load_dwordx4 v[168:171], v[194:195], off offset:2560
	global_load_dwordx4 v[172:175], v[196:197], off offset:2560
	s_waitcnt lgkmcnt(1)
	v_mfma_f32_32x32x16_bf16 v[112:127], v[234:237], v[160:163], v[112:127]
	v_mfma_f32_32x32x16_bf16 v[48:63], v[234:237], v[164:167], v[48:63]
	s_waitcnt lgkmcnt(0)
	v_mfma_f32_32x32x16_bf16 v[96:111], v[238:241], v[160:163], v[96:111]
	v_mfma_f32_32x32x16_bf16 v[32:47], v[238:241], v[164:167], v[32:47]
	ds_read_b128 v[234:237], v204 offset:9248
	ds_read_b128 v[238:241], v204 offset:13856
	s_waitcnt vmcnt(7)
	ds_write_b128 v214, v[218:221]
	s_waitcnt vmcnt(6)
	ds_write_b128 v213, v[222:225]
	ds_read_b128 v[218:221], v205 offset:36928
	ds_read_b128 v[222:225], v205 offset:41536
	s_waitcnt lgkmcnt(5)
	v_mfma_f32_32x32x16_bf16 v[80:95], v[234:237], v[160:163], v[80:95]
	v_mfma_f32_32x32x16_bf16 v[16:31], v[234:237], v[164:167], v[16:31]
	ds_read_b128 v[234:237], v204 offset:64
	s_waitcnt lgkmcnt(5)
	v_mfma_f32_32x32x16_bf16 v[64:79], v[238:241], v[160:163], v[64:79]
	v_mfma_f32_32x32x16_bf16 v[0:15], v[238:241], v[164:167], v[0:15]
	ds_read_b128 v[238:241], v204 offset:4672
	global_load_dwordx4 v[160:163], v[184:185], off offset:2560
	global_load_dwordx4 v[164:167], v[186:187], off offset:2560
	s_waitcnt lgkmcnt(1)
	v_mfma_f32_32x32x16_bf16 v[112:127], v[234:237], v[218:221], v[112:127]
	v_mfma_f32_32x32x16_bf16 v[48:63], v[234:237], v[222:225], v[48:63]
	s_waitcnt lgkmcnt(0)
	v_mfma_f32_32x32x16_bf16 v[96:111], v[238:241], v[218:221], v[96:111]
	v_mfma_f32_32x32x16_bf16 v[32:47], v[238:241], v[222:225], v[32:47]
	ds_read_b128 v[234:237], v204 offset:9280
	ds_read_b128 v[238:241], v204 offset:13888
	s_waitcnt vmcnt(7)
	ds_write_b128 v217, v[226:229]
	s_waitcnt vmcnt(6)
	ds_write_b128 v216, v[230:233]
	ds_read_b128 v[226:229], v205 offset:36960
	ds_read_b128 v[230:233], v205 offset:41568
	s_waitcnt lgkmcnt(5)
	v_mfma_f32_32x32x16_bf16 v[80:95], v[234:237], v[218:221], v[80:95]
	v_mfma_f32_32x32x16_bf16 v[16:31], v[234:237], v[222:225], v[16:31]
	ds_read_b128 v[234:237], v204 offset:96
	s_waitcnt lgkmcnt(5)
	v_mfma_f32_32x32x16_bf16 v[64:79], v[238:241], v[218:221], v[64:79]
	v_mfma_f32_32x32x16_bf16 v[0:15], v[238:241], v[222:225], v[0:15]
	ds_read_b128 v[238:241], v204 offset:4704
	global_load_dwordx4 v[218:221], v[198:199], off offset:2560
	global_load_dwordx4 v[222:225], v[200:201], off offset:2560
	s_waitcnt lgkmcnt(1)
	v_mfma_f32_32x32x16_bf16 v[112:127], v[234:237], v[226:229], v[112:127]
	v_mfma_f32_32x32x16_bf16 v[48:63], v[234:237], v[230:233], v[48:63]
	s_waitcnt lgkmcnt(0)
	v_mfma_f32_32x32x16_bf16 v[96:111], v[238:241], v[226:229], v[96:111]
	v_mfma_f32_32x32x16_bf16 v[32:47], v[238:241], v[230:233], v[32:47]
	ds_read_b128 v[234:237], v204 offset:9312
	ds_read_b128 v[238:241], v204 offset:13920
	s_waitcnt lgkmcnt(1)
	v_mfma_f32_32x32x16_bf16 v[80:95], v[234:237], v[226:229], v[80:95]
	v_mfma_f32_32x32x16_bf16 v[16:31], v[234:237], v[230:233], v[16:31]
	s_waitcnt lgkmcnt(0)
	v_mfma_f32_32x32x16_bf16 v[64:79], v[238:241], v[226:229], v[64:79]
	v_mfma_f32_32x32x16_bf16 v[0:15], v[238:241], v[230:233], v[0:15]
	s_setprio 0
	s_barrier
; template <bool trans>
; DI void gemm_core(const GTile& tl, const GTile& nx, bool has_next  , bool chain  , bool pre, u32x4 (&ra)[4], u32x4 (&rb)[4], char* smem, f32x16 (&acc)[2][4]) {
;     ...
;   const int nk = K / 64;
;   if (!pre) { G_LOAD(0); G_STORE(0); G_LOAD(1); }
;   for (int kt = 0; kt < nk; ++kt) {
;     __syncthreads();
;     G_COMPUTE(kt & 1, kt);
;   }
	global_load_dwordx4 v[226:229], v[190:191], off offset:2688
	global_load_dwordx4 v[230:233], v[188:189], off offset:2688
	s_waitcnt vmcnt(9)
	ds_write_b128 v215, v[176:179]
	s_waitcnt vmcnt(8)
	ds_write_b128 v215, v[180:183] offset:36864
	ds_read_b128 v[176:179], v208
	ds_read_b128 v[180:183], v208 offset:4608
	ds_read_b128 v[234:237], v192
	ds_read_b128 v[238:241], v192 offset:4608
	s_setprio 1
	s_waitcnt lgkmcnt(1)
	v_mfma_f32_32x32x16_bf16 v[112:127], v[234:237], v[176:179], v[112:127]
	v_mfma_f32_32x32x16_bf16 v[48:63], v[234:237], v[180:183], v[48:63]
	s_waitcnt lgkmcnt(0)
	v_mfma_f32_32x32x16_bf16 v[96:111], v[238:241], v[176:179], v[96:111]
	v_mfma_f32_32x32x16_bf16 v[32:47], v[238:241], v[180:183], v[32:47]
	ds_read_b128 v[234:237], v192 offset:9216
	ds_read_b128 v[238:241], v192 offset:13824
	s_waitcnt vmcnt(7)
	ds_write_b128 v215, v[168:171] offset:9216
	s_waitcnt vmcnt(6)
	ds_write_b128 v215, v[172:175] offset:46080
	ds_read_b128 v[168:171], v208 offset:32
	ds_read_b128 v[172:175], v208 offset:4640
	s_waitcnt lgkmcnt(5)
	v_mfma_f32_32x32x16_bf16 v[80:95], v[234:237], v[176:179], v[80:95]
	v_mfma_f32_32x32x16_bf16 v[16:31], v[234:237], v[180:183], v[16:31]
	ds_read_b128 v[234:237], v192 offset:32
	s_waitcnt lgkmcnt(5)
	v_mfma_f32_32x32x16_bf16 v[64:79], v[238:241], v[176:179], v[64:79]
	v_mfma_f32_32x32x16_bf16 v[0:15], v[238:241], v[180:183], v[0:15]
	ds_read_b128 v[238:241], v192 offset:4640
	global_load_dwordx4 v[176:179], v[194:195], off offset:2688
	global_load_dwordx4 v[180:183], v[196:197], off offset:2688
	s_waitcnt lgkmcnt(1)
	v_mfma_f32_32x32x16_bf16 v[112:127], v[234:237], v[168:171], v[112:127]
	v_mfma_f32_32x32x16_bf16 v[48:63], v[234:237], v[172:175], v[48:63]
	s_waitcnt lgkmcnt(0)
	v_mfma_f32_32x32x16_bf16 v[96:111], v[238:241], v[168:171], v[96:111]
	v_mfma_f32_32x32x16_bf16 v[32:47], v[238:241], v[172:175], v[32:47]
	ds_read_b128 v[234:237], v192 offset:9248
	ds_read_b128 v[238:241], v192 offset:13856
	s_waitcnt vmcnt(7)
	ds_write_b128 v215, v[160:163] offset:18432
	s_waitcnt vmcnt(6)
	ds_write_b128 v215, v[164:167] offset:55296
	ds_read_b128 v[160:163], v208 offset:64
	ds_read_b128 v[164:167], v208 offset:4672
	s_waitcnt lgkmcnt(5)
	v_mfma_f32_32x32x16_bf16 v[80:95], v[234:237], v[168:171], v[80:95]
	v_mfma_f32_32x32x16_bf16 v[16:31], v[234:237], v[172:175], v[16:31]
	ds_read_b128 v[234:237], v192 offset:64
	s_waitcnt lgkmcnt(5)
	v_mfma_f32_32x32x16_bf16 v[64:79], v[238:241], v[168:171], v[64:79]
	v_mfma_f32_32x32x16_bf16 v[0:15], v[238:241], v[172:175], v[0:15]
	ds_read_b128 v[238:241], v192 offset:4672
	global_load_dwordx4 v[168:171], v[184:185], off offset:2688
	global_load_dwordx4 v[172:175], v[186:187], off offset:2688
	s_waitcnt lgkmcnt(1)
	v_mfma_f32_32x32x16_bf16 v[112:127], v[234:237], v[160:163], v[112:127]
	v_mfma_f32_32x32x16_bf16 v[48:63], v[234:237], v[164:167], v[48:63]
	s_waitcnt lgkmcnt(0)
	v_mfma_f32_32x32x16_bf16 v[96:111], v[238:241], v[160:163], v[96:111]
	v_mfma_f32_32x32x16_bf16 v[32:47], v[238:241], v[164:167], v[32:47]
	ds_read_b128 v[234:237], v192 offset:9280
	ds_read_b128 v[238:241], v192 offset:13888
	s_waitcnt vmcnt(7)
	ds_write_b128 v215, v[218:221] offset:27648
	s_waitcnt vmcnt(6)
	ds_write_b128 v215, v[222:225] offset:64512
	ds_read_b128 v[218:221], v208 offset:96
	ds_read_b128 v[222:225], v208 offset:4704
	s_waitcnt lgkmcnt(5)
	v_mfma_f32_32x32x16_bf16 v[80:95], v[234:237], v[160:163], v[80:95]
	v_mfma_f32_32x32x16_bf16 v[16:31], v[234:237], v[164:167], v[16:31]
	ds_read_b128 v[234:237], v192 offset:96
	s_waitcnt lgkmcnt(5)
	v_mfma_f32_32x32x16_bf16 v[64:79], v[238:241], v[160:163], v[64:79]
	v_mfma_f32_32x32x16_bf16 v[0:15], v[238:241], v[164:167], v[0:15]
	ds_read_b128 v[238:241], v192 offset:4704
	global_load_dwordx4 v[160:163], v[198:199], off offset:2688
	global_load_dwordx4 v[164:167], v[200:201], off offset:2688
	s_waitcnt lgkmcnt(1)
	v_mfma_f32_32x32x16_bf16 v[112:127], v[234:237], v[218:221], v[112:127]
	v_mfma_f32_32x32x16_bf16 v[48:63], v[234:237], v[222:225], v[48:63]
	s_waitcnt lgkmcnt(0)
	v_mfma_f32_32x32x16_bf16 v[96:111], v[238:241], v[218:221], v[96:111]
	v_mfma_f32_32x32x16_bf16 v[32:47], v[238:241], v[222:225], v[32:47]
	ds_read_b128 v[234:237], v192 offset:9312
	ds_read_b128 v[238:241], v192 offset:13920
	s_waitcnt lgkmcnt(1)
	v_mfma_f32_32x32x16_bf16 v[80:95], v[234:237], v[218:221], v[80:95]
	v_mfma_f32_32x32x16_bf16 v[16:31], v[234:237], v[222:225], v[16:31]
	s_waitcnt lgkmcnt(0)
	v_mfma_f32_32x32x16_bf16 v[64:79], v[238:241], v[218:221], v[64:79]
	v_mfma_f32_32x32x16_bf16 v[0:15], v[238:241], v[222:225], v[0:15]
	s_setprio 0
	s_barrier
; template <bool trans>
; DI void gemm_core(const GTile& tl, const GTile& nx, bool has_next  , bool chain  , bool pre, u32x4 (&ra)[4], u32x4 (&rb)[4], char* smem, f32x16 (&acc)[2][4]) {
;     ...
;   const int nk = K / 64;
;   if (!pre) { G_LOAD(0); G_STORE(0); G_LOAD(1); }
;   for (int kt = 0; kt < nk; ++kt) {
;     __syncthreads();
;     G_COMPUTE(kt & 1, kt);
;   }
	global_load_dwordx4 v[218:221], v[190:191], off offset:2816
	global_load_dwordx4 v[222:225], v[188:189], off offset:2816
	s_waitcnt vmcnt(9)
	ds_write_b128 v209, v[226:229]
	s_waitcnt vmcnt(8)
	ds_write_b128 v210, v[230:233]
	ds_read_b128 v[226:229], v205 offset:36864
	ds_read_b128 v[230:233], v205 offset:41472
	ds_read_b128 v[234:237], v204
	ds_read_b128 v[238:241], v204 offset:4608
	s_setprio 1
	s_waitcnt lgkmcnt(1)
	v_mfma_f32_32x32x16_bf16 v[112:127], v[234:237], v[226:229], v[112:127]
	v_mfma_f32_32x32x16_bf16 v[48:63], v[234:237], v[230:233], v[48:63]
	s_waitcnt lgkmcnt(0)
	v_mfma_f32_32x32x16_bf16 v[96:111], v[238:241], v[226:229], v[96:111]
	v_mfma_f32_32x32x16_bf16 v[32:47], v[238:241], v[230:233], v[32:47]
	ds_read_b128 v[234:237], v204 offset:9216
	ds_read_b128 v[238:241], v204 offset:13824
	s_waitcnt vmcnt(7)
	ds_write_b128 v212, v[176:179]
	s_waitcnt vmcnt(6)
	ds_write_b128 v211, v[180:183]
	ds_read_b128 v[176:179], v205 offset:36896
	ds_read_b128 v[180:183], v205 offset:41504
	s_waitcnt lgkmcnt(5)
	v_mfma_f32_32x32x16_bf16 v[80:95], v[234:237], v[226:229], v[80:95]
	v_mfma_f32_32x32x16_bf16 v[16:31], v[234:237], v[230:233], v[16:31]
	ds_read_b128 v[234:237], v204 offset:32
	s_waitcnt lgkmcnt(5)
	v_mfma_f32_32x32x16_bf16 v[64:79], v[238:241], v[226:229], v[64:79]
	v_mfma_f32_32x32x16_bf16 v[0:15], v[238:241], v[230:233], v[0:15]
	ds_read_b128 v[238:241], v204 offset:4640
	global_load_dwordx4 v[226:229], v[194:195], off offset:2816
	global_load_dwordx4 v[230:233], v[196:197], off offset:2816
	s_waitcnt lgkmcnt(1)
	v_mfma_f32_32x32x16_bf16 v[112:127], v[234:237], v[176:179], v[112:127]
	v_mfma_f32_32x32x16_bf16 v[48:63], v[234:237], v[180:183], v[48:63]
	s_waitcnt lgkmcnt(0)
	v_mfma_f32_32x32x16_bf16 v[96:111], v[238:241], v[176:179], v[96:111]
	v_mfma_f32_32x32x16_bf16 v[32:47], v[238:241], v[180:183], v[32:47]
	ds_read_b128 v[234:237], v204 offset:9248
	ds_read_b128 v[238:241], v204 offset:13856
	s_waitcnt vmcnt(7)
	ds_write_b128 v214, v[168:171]
	s_waitcnt vmcnt(6)
	ds_write_b128 v213, v[172:175]
	ds_read_b128 v[168:171], v205 offset:36928
	ds_read_b128 v[172:175], v205 offset:41536
	s_waitcnt lgkmcnt(5)
	v_mfma_f32_32x32x16_bf16 v[80:95], v[234:237], v[176:179], v[80:95]
	v_mfma_f32_32x32x16_bf16 v[16:31], v[234:237], v[180:183], v[16:31]
	ds_read_b128 v[234:237], v204 offset:64
	s_waitcnt lgkmcnt(5)
	v_mfma_f32_32x32x16_bf16 v[64:79], v[238:241], v[176:179], v[64:79]
	v_mfma_f32_32x32x16_bf16 v[0:15], v[238:241], v[180:183], v[0:15]
	ds_read_b128 v[238:241], v204 offset:4672
	global_load_dwordx4 v[176:179], v[184:185], off offset:2816
	global_load_dwordx4 v[180:183], v[186:187], off offset:2816
	s_waitcnt lgkmcnt(1)
	v_mfma_f32_32x32x16_bf16 v[112:127], v[234:237], v[168:171], v[112:127]
	v_mfma_f32_32x32x16_bf16 v[48:63], v[234:237], v[172:175], v[48:63]
	s_waitcnt lgkmcnt(0)
	v_mfma_f32_32x32x16_bf16 v[96:111], v[238:241], v[168:171], v[96:111]
	v_mfma_f32_32x32x16_bf16 v[32:47], v[238:241], v[172:175], v[32:47]
	ds_read_b128 v[234:237], v204 offset:9280
	ds_read_b128 v[238:241], v204 offset:13888
	s_waitcnt vmcnt(7)
	ds_write_b128 v217, v[160:163]
	s_waitcnt vmcnt(6)
	ds_write_b128 v216, v[164:167]
	ds_read_b128 v[160:163], v205 offset:36960
	ds_read_b128 v[164:167], v205 offset:41568
	s_waitcnt lgkmcnt(5)
	v_mfma_f32_32x32x16_bf16 v[80:95], v[234:237], v[168:171], v[80:95]
	v_mfma_f32_32x32x16_bf16 v[16:31], v[234:237], v[172:175], v[16:31]
	ds_read_b128 v[234:237], v204 offset:96
	s_waitcnt lgkmcnt(5)
	v_mfma_f32_32x32x16_bf16 v[64:79], v[238:241], v[168:171], v[64:79]
	v_mfma_f32_32x32x16_bf16 v[0:15], v[238:241], v[172:175], v[0:15]
	ds_read_b128 v[238:241], v204 offset:4704
	global_load_dwordx4 v[168:171], v[198:199], off offset:2816
	global_load_dwordx4 v[172:175], v[200:201], off offset:2816
	s_waitcnt lgkmcnt(1)
	v_mfma_f32_32x32x16_bf16 v[112:127], v[234:237], v[160:163], v[112:127]
	v_mfma_f32_32x32x16_bf16 v[48:63], v[234:237], v[164:167], v[48:63]
	s_waitcnt lgkmcnt(0)
	v_mfma_f32_32x32x16_bf16 v[96:111], v[238:241], v[160:163], v[96:111]
	v_mfma_f32_32x32x16_bf16 v[32:47], v[238:241], v[164:167], v[32:47]
	ds_read_b128 v[234:237], v204 offset:9312
	ds_read_b128 v[238:241], v204 offset:13920
	s_waitcnt lgkmcnt(1)
	v_mfma_f32_32x32x16_bf16 v[80:95], v[234:237], v[160:163], v[80:95]
	v_mfma_f32_32x32x16_bf16 v[16:31], v[234:237], v[164:167], v[16:31]
	s_waitcnt lgkmcnt(0)
	v_mfma_f32_32x32x16_bf16 v[64:79], v[238:241], v[160:163], v[64:79]
	v_mfma_f32_32x32x16_bf16 v[0:15], v[238:241], v[164:167], v[0:15]
	s_setprio 0
	s_barrier
; template <bool trans>
; DI void gemm_core(const GTile& tl, const GTile& nx, bool has_next  , bool chain  , bool pre, u32x4 (&ra)[4], u32x4 (&rb)[4], char* smem, f32x16 (&acc)[2][4]) {
;     ...
;   const int nk = K / 64;
;   if (!pre) { G_LOAD(0); G_STORE(0); G_LOAD(1); }
;   for (int kt = 0; kt < nk; ++kt) {
;     __syncthreads();
;     G_COMPUTE(kt & 1, kt);
;   }
	global_load_dwordx4 v[160:163], v[190:191], off offset:2944
	global_load_dwordx4 v[164:167], v[188:189], off offset:2944
	s_waitcnt vmcnt(9)
	ds_write_b128 v215, v[218:221]
	s_waitcnt vmcnt(8)
	ds_write_b128 v215, v[222:225] offset:36864
	ds_read_b128 v[218:221], v208
	ds_read_b128 v[222:225], v208 offset:4608
	ds_read_b128 v[234:237], v192
	ds_read_b128 v[238:241], v192 offset:4608
	s_setprio 1
	s_waitcnt lgkmcnt(1)
	v_mfma_f32_32x32x16_bf16 v[112:127], v[234:237], v[218:221], v[112:127]
	v_mfma_f32_32x32x16_bf16 v[48:63], v[234:237], v[222:225], v[48:63]
	s_waitcnt lgkmcnt(0)
	v_mfma_f32_32x32x16_bf16 v[96:111], v[238:241], v[218:221], v[96:111]
	v_mfma_f32_32x32x16_bf16 v[32:47], v[238:241], v[222:225], v[32:47]
	ds_read_b128 v[234:237], v192 offset:9216
	ds_read_b128 v[238:241], v192 offset:13824
	s_waitcnt vmcnt(7)
	ds_write_b128 v215, v[226:229] offset:9216
	s_waitcnt vmcnt(6)
	ds_write_b128 v215, v[230:233] offset:46080
	ds_read_b128 v[226:229], v208 offset:32
	ds_read_b128 v[230:233], v208 offset:4640
	s_waitcnt lgkmcnt(5)
	v_mfma_f32_32x32x16_bf16 v[80:95], v[234:237], v[218:221], v[80:95]
	v_mfma_f32_32x32x16_bf16 v[16:31], v[234:237], v[222:225], v[16:31]
	ds_read_b128 v[234:237], v192 offset:32
	s_waitcnt lgkmcnt(5)
	v_mfma_f32_32x32x16_bf16 v[64:79], v[238:241], v[218:221], v[64:79]
	v_mfma_f32_32x32x16_bf16 v[0:15], v[238:241], v[222:225], v[0:15]
	ds_read_b128 v[238:241], v192 offset:4640
	global_load_dwordx4 v[218:221], v[194:195], off offset:2944
	global_load_dwordx4 v[222:225], v[196:197], off offset:2944
	s_waitcnt lgkmcnt(1)
	v_mfma_f32_32x32x16_bf16 v[112:127], v[234:237], v[226:229], v[112:127]
	v_mfma_f32_32x32x16_bf16 v[48:63], v[234:237], v[230:233], v[48:63]
	s_waitcnt lgkmcnt(0)
	v_mfma_f32_32x32x16_bf16 v[96:111], v[238:241], v[226:229], v[96:111]
	v_mfma_f32_32x32x16_bf16 v[32:47], v[238:241], v[230:233], v[32:47]
	ds_read_b128 v[234:237], v192 offset:9248
	ds_read_b128 v[238:241], v192 offset:13856
	s_waitcnt vmcnt(7)
	ds_write_b128 v215, v[176:179] offset:18432
	s_waitcnt vmcnt(6)
	ds_write_b128 v215, v[180:183] offset:55296
	ds_read_b128 v[176:179], v208 offset:64
	ds_read_b128 v[180:183], v208 offset:4672
	s_waitcnt lgkmcnt(5)
	v_mfma_f32_32x32x16_bf16 v[80:95], v[234:237], v[226:229], v[80:95]
	v_mfma_f32_32x32x16_bf16 v[16:31], v[234:237], v[230:233], v[16:31]
	ds_read_b128 v[234:237], v192 offset:64
	s_waitcnt lgkmcnt(5)
	v_mfma_f32_32x32x16_bf16 v[64:79], v[238:241], v[226:229], v[64:79]
	v_mfma_f32_32x32x16_bf16 v[0:15], v[238:241], v[230:233], v[0:15]
	ds_read_b128 v[238:241], v192 offset:4672
	global_load_dwordx4 v[226:229], v[184:185], off offset:2944
	global_load_dwordx4 v[230:233], v[186:187], off offset:2944
	s_waitcnt lgkmcnt(1)
	v_mfma_f32_32x32x16_bf16 v[112:127], v[234:237], v[176:179], v[112:127]
	v_mfma_f32_32x32x16_bf16 v[48:63], v[234:237], v[180:183], v[48:63]
	s_waitcnt lgkmcnt(0)
	v_mfma_f32_32x32x16_bf16 v[96:111], v[238:241], v[176:179], v[96:111]
	v_mfma_f32_32x32x16_bf16 v[32:47], v[238:241], v[180:183], v[32:47]
	ds_read_b128 v[234:237], v192 offset:9280
	ds_read_b128 v[238:241], v192 offset:13888
	s_waitcnt vmcnt(7)
	ds_write_b128 v215, v[168:171] offset:27648
	s_waitcnt vmcnt(6)
	ds_write_b128 v215, v[172:175] offset:64512
	ds_read_b128 v[168:171], v208 offset:96
	ds_read_b128 v[172:175], v208 offset:4704
	s_waitcnt lgkmcnt(5)
	v_mfma_f32_32x32x16_bf16 v[80:95], v[234:237], v[176:179], v[80:95]
	v_mfma_f32_32x32x16_bf16 v[16:31], v[234:237], v[180:183], v[16:31]
	ds_read_b128 v[234:237], v192 offset:96
	s_waitcnt lgkmcnt(5)
	v_mfma_f32_32x32x16_bf16 v[64:79], v[238:241], v[176:179], v[64:79]
	v_mfma_f32_32x32x16_bf16 v[0:15], v[238:241], v[180:183], v[0:15]
	ds_read_b128 v[238:241], v192 offset:4704
	global_load_dwordx4 v[176:179], v[198:199], off offset:2944
	global_load_dwordx4 v[180:183], v[200:201], off offset:2944
	s_waitcnt lgkmcnt(1)
	v_mfma_f32_32x32x16_bf16 v[112:127], v[234:237], v[168:171], v[112:127]
	v_mfma_f32_32x32x16_bf16 v[48:63], v[234:237], v[172:175], v[48:63]
	s_waitcnt lgkmcnt(0)
	v_mfma_f32_32x32x16_bf16 v[96:111], v[238:241], v[168:171], v[96:111]
	v_mfma_f32_32x32x16_bf16 v[32:47], v[238:241], v[172:175], v[32:47]
	ds_read_b128 v[234:237], v192 offset:9312
	ds_read_b128 v[238:241], v192 offset:13920
	s_waitcnt lgkmcnt(1)
	v_mfma_f32_32x32x16_bf16 v[80:95], v[234:237], v[168:171], v[80:95]
	v_mfma_f32_32x32x16_bf16 v[16:31], v[234:237], v[172:175], v[16:31]
	s_waitcnt lgkmcnt(0)
	v_mfma_f32_32x32x16_bf16 v[64:79], v[238:241], v[168:171], v[64:79]
	v_mfma_f32_32x32x16_bf16 v[0:15], v[238:241], v[172:175], v[0:15]
	s_setprio 0
	s_barrier
; template <bool trans>
; DI void gemm_core(const GTile& tl, const GTile& nx, bool has_next  , bool chain  , bool pre, u32x4 (&ra)[4], u32x4 (&rb)[4], char* smem, f32x16 (&acc)[2][4]) {
;     ...
;   const int nk = K / 64;
;   if (!pre) { G_LOAD(0); G_STORE(0); G_LOAD(1); }
;   for (int kt = 0; kt < nk; ++kt) {
;     __syncthreads();
;     G_COMPUTE(kt & 1, kt);
;   }
	global_load_dwordx4 v[168:171], v[190:191], off offset:3072
	global_load_dwordx4 v[172:175], v[188:189], off offset:3072
	s_waitcnt vmcnt(9)
	ds_write_b128 v209, v[160:163]
	s_waitcnt vmcnt(8)
	ds_write_b128 v210, v[164:167]
	ds_read_b128 v[160:163], v205 offset:36864
	ds_read_b128 v[164:167], v205 offset:41472
	ds_read_b128 v[234:237], v204
	ds_read_b128 v[238:241], v204 offset:4608
	s_setprio 1
	s_waitcnt lgkmcnt(1)
	v_mfma_f32_32x32x16_bf16 v[112:127], v[234:237], v[160:163], v[112:127]
	v_mfma_f32_32x32x16_bf16 v[48:63], v[234:237], v[164:167], v[48:63]
	s_waitcnt lgkmcnt(0)
	v_mfma_f32_32x32x16_bf16 v[96:111], v[238:241], v[160:163], v[96:111]
	v_mfma_f32_32x32x16_bf16 v[32:47], v[238:241], v[164:167], v[32:47]
	ds_read_b128 v[234:237], v204 offset:9216
	ds_read_b128 v[238:241], v204 offset:13824
	s_waitcnt vmcnt(7)
	ds_write_b128 v212, v[218:221]
	s_waitcnt vmcnt(6)
	ds_write_b128 v211, v[222:225]
	ds_read_b128 v[218:221], v205 offset:36896
	ds_read_b128 v[222:225], v205 offset:41504
	s_waitcnt lgkmcnt(5)
	v_mfma_f32_32x32x16_bf16 v[80:95], v[234:237], v[160:163], v[80:95]
	v_mfma_f32_32x32x16_bf16 v[16:31], v[234:237], v[164:167], v[16:31]
	ds_read_b128 v[234:237], v204 offset:32
	s_waitcnt lgkmcnt(5)
	v_mfma_f32_32x32x16_bf16 v[64:79], v[238:241], v[160:163], v[64:79]
	v_mfma_f32_32x32x16_bf16 v[0:15], v[238:241], v[164:167], v[0:15]
	ds_read_b128 v[238:241], v204 offset:4640
	global_load_dwordx4 v[160:163], v[194:195], off offset:3072
	global_load_dwordx4 v[164:167], v[196:197], off offset:3072
	s_waitcnt lgkmcnt(1)
	v_mfma_f32_32x32x16_bf16 v[112:127], v[234:237], v[218:221], v[112:127]
	v_mfma_f32_32x32x16_bf16 v[48:63], v[234:237], v[222:225], v[48:63]
	s_waitcnt lgkmcnt(0)
	v_mfma_f32_32x32x16_bf16 v[96:111], v[238:241], v[218:221], v[96:111]
	v_mfma_f32_32x32x16_bf16 v[32:47], v[238:241], v[222:225], v[32:47]
	ds_read_b128 v[234:237], v204 offset:9248
	ds_read_b128 v[238:241], v204 offset:13856
	s_waitcnt vmcnt(7)
	ds_write_b128 v214, v[226:229]
	s_waitcnt vmcnt(6)
	ds_write_b128 v213, v[230:233]
	ds_read_b128 v[226:229], v205 offset:36928
	ds_read_b128 v[230:233], v205 offset:41536
	s_waitcnt lgkmcnt(5)
	v_mfma_f32_32x32x16_bf16 v[80:95], v[234:237], v[218:221], v[80:95]
	v_mfma_f32_32x32x16_bf16 v[16:31], v[234:237], v[222:225], v[16:31]
	ds_read_b128 v[234:237], v204 offset:64
	s_waitcnt lgkmcnt(5)
	v_mfma_f32_32x32x16_bf16 v[64:79], v[238:241], v[218:221], v[64:79]
	v_mfma_f32_32x32x16_bf16 v[0:15], v[238:241], v[222:225], v[0:15]
	ds_read_b128 v[238:241], v204 offset:4672
	global_load_dwordx4 v[218:221], v[184:185], off offset:3072
	global_load_dwordx4 v[222:225], v[186:187], off offset:3072
	s_waitcnt lgkmcnt(1)
	v_mfma_f32_32x32x16_bf16 v[112:127], v[234:237], v[226:229], v[112:127]
	v_mfma_f32_32x32x16_bf16 v[48:63], v[234:237], v[230:233], v[48:63]
	s_waitcnt lgkmcnt(0)
	v_mfma_f32_32x32x16_bf16 v[96:111], v[238:241], v[226:229], v[96:111]
	v_mfma_f32_32x32x16_bf16 v[32:47], v[238:241], v[230:233], v[32:47]
	ds_read_b128 v[234:237], v204 offset:9280
	ds_read_b128 v[238:241], v204 offset:13888
	s_waitcnt vmcnt(7)
	ds_write_b128 v217, v[176:179]
	s_waitcnt vmcnt(6)
	ds_write_b128 v216, v[180:183]
	ds_read_b128 v[176:179], v205 offset:36960
	ds_read_b128 v[180:183], v205 offset:41568
	s_waitcnt lgkmcnt(5)
	v_mfma_f32_32x32x16_bf16 v[80:95], v[234:237], v[226:229], v[80:95]
	v_mfma_f32_32x32x16_bf16 v[16:31], v[234:237], v[230:233], v[16:31]
	ds_read_b128 v[234:237], v204 offset:96
	s_waitcnt lgkmcnt(5)
	v_mfma_f32_32x32x16_bf16 v[64:79], v[238:241], v[226:229], v[64:79]
	v_mfma_f32_32x32x16_bf16 v[0:15], v[238:241], v[230:233], v[0:15]
	ds_read_b128 v[238:241], v204 offset:4704
	global_load_dwordx4 v[226:229], v[198:199], off offset:3072
	global_load_dwordx4 v[230:233], v[200:201], off offset:3072
	s_waitcnt lgkmcnt(1)
	v_mfma_f32_32x32x16_bf16 v[112:127], v[234:237], v[176:179], v[112:127]
	v_mfma_f32_32x32x16_bf16 v[48:63], v[234:237], v[180:183], v[48:63]
	s_waitcnt lgkmcnt(0)
	v_mfma_f32_32x32x16_bf16 v[96:111], v[238:241], v[176:179], v[96:111]
	v_mfma_f32_32x32x16_bf16 v[32:47], v[238:241], v[180:183], v[32:47]
	ds_read_b128 v[234:237], v204 offset:9312
	ds_read_b128 v[238:241], v204 offset:13920
	s_waitcnt lgkmcnt(1)
	v_mfma_f32_32x32x16_bf16 v[80:95], v[234:237], v[176:179], v[80:95]
	v_mfma_f32_32x32x16_bf16 v[16:31], v[234:237], v[180:183], v[16:31]
	s_waitcnt lgkmcnt(0)
	v_mfma_f32_32x32x16_bf16 v[64:79], v[238:241], v[176:179], v[64:79]
	v_mfma_f32_32x32x16_bf16 v[0:15], v[238:241], v[180:183], v[0:15]
	s_setprio 0
	s_barrier
; template <bool trans>
; DI void gemm_core(const GTile& tl, const GTile& nx, bool has_next  , bool chain  , bool pre, u32x4 (&ra)[4], u32x4 (&rb)[4], char* smem, f32x16 (&acc)[2][4]) {
;     ...
;   const int nk = K / 64;
;   if (!pre) { G_LOAD(0); G_STORE(0); G_LOAD(1); }
;   for (int kt = 0; kt < nk; ++kt) {
;     __syncthreads();
;     G_COMPUTE(kt & 1, kt);
;   }
	global_load_dwordx4 v[176:179], v[190:191], off offset:3200
	global_load_dwordx4 v[180:183], v[188:189], off offset:3200
	s_waitcnt vmcnt(9)
	ds_write_b128 v215, v[168:171]
	s_waitcnt vmcnt(8)
	ds_write_b128 v215, v[172:175] offset:36864
	ds_read_b128 v[168:171], v208
	ds_read_b128 v[172:175], v208 offset:4608
	ds_read_b128 v[234:237], v192
	ds_read_b128 v[238:241], v192 offset:4608
	s_setprio 1
	s_waitcnt lgkmcnt(1)
	v_mfma_f32_32x32x16_bf16 v[112:127], v[234:237], v[168:171], v[112:127]
	v_mfma_f32_32x32x16_bf16 v[48:63], v[234:237], v[172:175], v[48:63]
	s_waitcnt lgkmcnt(0)
	v_mfma_f32_32x32x16_bf16 v[96:111], v[238:241], v[168:171], v[96:111]
	v_mfma_f32_32x32x16_bf16 v[32:47], v[238:241], v[172:175], v[32:47]
	ds_read_b128 v[234:237], v192 offset:9216
	ds_read_b128 v[238:241], v192 offset:13824
	s_waitcnt vmcnt(7)
	ds_write_b128 v215, v[160:163] offset:9216
	s_waitcnt vmcnt(6)
	ds_write_b128 v215, v[164:167] offset:46080
	ds_read_b128 v[160:163], v208 offset:32
	ds_read_b128 v[164:167], v208 offset:4640
	s_waitcnt lgkmcnt(5)
	v_mfma_f32_32x32x16_bf16 v[80:95], v[234:237], v[168:171], v[80:95]
	v_mfma_f32_32x32x16_bf16 v[16:31], v[234:237], v[172:175], v[16:31]
	ds_read_b128 v[234:237], v192 offset:32
	s_waitcnt lgkmcnt(5)
	v_mfma_f32_32x32x16_bf16 v[64:79], v[238:241], v[168:171], v[64:79]
	v_mfma_f32_32x32x16_bf16 v[0:15], v[238:241], v[172:175], v[0:15]
	ds_read_b128 v[238:241], v192 offset:4640
	global_load_dwordx4 v[168:171], v[194:195], off offset:3200
	global_load_dwordx4 v[172:175], v[196:197], off offset:3200
	s_waitcnt lgkmcnt(1)
	v_mfma_f32_32x32x16_bf16 v[112:127], v[234:237], v[160:163], v[112:127]
	v_mfma_f32_32x32x16_bf16 v[48:63], v[234:237], v[164:167], v[48:63]
	s_waitcnt lgkmcnt(0)
	v_mfma_f32_32x32x16_bf16 v[96:111], v[238:241], v[160:163], v[96:111]
	v_mfma_f32_32x32x16_bf16 v[32:47], v[238:241], v[164:167], v[32:47]
	ds_read_b128 v[234:237], v192 offset:9248
	ds_read_b128 v[238:241], v192 offset:13856
	s_waitcnt vmcnt(7)
	ds_write_b128 v215, v[218:221] offset:18432
	s_waitcnt vmcnt(6)
	ds_write_b128 v215, v[222:225] offset:55296
	ds_read_b128 v[218:221], v208 offset:64
	ds_read_b128 v[222:225], v208 offset:4672
	s_waitcnt lgkmcnt(5)
	v_mfma_f32_32x32x16_bf16 v[80:95], v[234:237], v[160:163], v[80:95]
	v_mfma_f32_32x32x16_bf16 v[16:31], v[234:237], v[164:167], v[16:31]
	ds_read_b128 v[234:237], v192 offset:64
	s_waitcnt lgkmcnt(5)
	v_mfma_f32_32x32x16_bf16 v[64:79], v[238:241], v[160:163], v[64:79]
	v_mfma_f32_32x32x16_bf16 v[0:15], v[238:241], v[164:167], v[0:15]
	ds_read_b128 v[238:241], v192 offset:4672
	global_load_dwordx4 v[160:163], v[184:185], off offset:3200
	global_load_dwordx4 v[164:167], v[186:187], off offset:3200
	s_waitcnt lgkmcnt(1)
	v_mfma_f32_32x32x16_bf16 v[112:127], v[234:237], v[218:221], v[112:127]
	v_mfma_f32_32x32x16_bf16 v[48:63], v[234:237], v[222:225], v[48:63]
	s_waitcnt lgkmcnt(0)
	v_mfma_f32_32x32x16_bf16 v[96:111], v[238:241], v[218:221], v[96:111]
	v_mfma_f32_32x32x16_bf16 v[32:47], v[238:241], v[222:225], v[32:47]
	ds_read_b128 v[234:237], v192 offset:9280
	ds_read_b128 v[238:241], v192 offset:13888
	s_waitcnt vmcnt(7)
	ds_write_b128 v215, v[226:229] offset:27648
	s_waitcnt vmcnt(6)
	ds_write_b128 v215, v[230:233] offset:64512
	ds_read_b128 v[226:229], v208 offset:96
	ds_read_b128 v[230:233], v208 offset:4704
	s_waitcnt lgkmcnt(5)
	v_mfma_f32_32x32x16_bf16 v[80:95], v[234:237], v[218:221], v[80:95]
	v_mfma_f32_32x32x16_bf16 v[16:31], v[234:237], v[222:225], v[16:31]
	ds_read_b128 v[234:237], v192 offset:96
	s_waitcnt lgkmcnt(5)
	v_mfma_f32_32x32x16_bf16 v[64:79], v[238:241], v[218:221], v[64:79]
	v_mfma_f32_32x32x16_bf16 v[0:15], v[238:241], v[222:225], v[0:15]
	ds_read_b128 v[238:241], v192 offset:4704
	global_load_dwordx4 v[218:221], v[198:199], off offset:3200
	global_load_dwordx4 v[222:225], v[200:201], off offset:3200
	s_waitcnt lgkmcnt(1)
	v_mfma_f32_32x32x16_bf16 v[112:127], v[234:237], v[226:229], v[112:127]
	v_mfma_f32_32x32x16_bf16 v[48:63], v[234:237], v[230:233], v[48:63]
	s_waitcnt lgkmcnt(0)
	v_mfma_f32_32x32x16_bf16 v[96:111], v[238:241], v[226:229], v[96:111]
	v_mfma_f32_32x32x16_bf16 v[32:47], v[238:241], v[230:233], v[32:47]
	ds_read_b128 v[234:237], v192 offset:9312
	ds_read_b128 v[238:241], v192 offset:13920
	s_waitcnt lgkmcnt(1)
	v_mfma_f32_32x32x16_bf16 v[80:95], v[234:237], v[226:229], v[80:95]
	v_mfma_f32_32x32x16_bf16 v[16:31], v[234:237], v[230:233], v[16:31]
	s_waitcnt lgkmcnt(0)
	v_mfma_f32_32x32x16_bf16 v[64:79], v[238:241], v[226:229], v[64:79]
	v_mfma_f32_32x32x16_bf16 v[0:15], v[238:241], v[230:233], v[0:15]
	s_setprio 0
	s_barrier
; template <bool trans>
; DI void gemm_core(const GTile& tl, const GTile& nx, bool has_next  , bool chain  , bool pre, u32x4 (&ra)[4], u32x4 (&rb)[4], char* smem, f32x16 (&acc)[2][4]) {
;     ...
;   const int nk = K / 64;
;   if (!pre) { G_LOAD(0); G_STORE(0); G_LOAD(1); }
;   for (int kt = 0; kt < nk; ++kt) {
;     __syncthreads();
;     G_COMPUTE(kt & 1, kt);
;   }
	global_load_dwordx4 v[226:229], v[190:191], off offset:3328
	global_load_dwordx4 v[230:233], v[188:189], off offset:3328
	s_waitcnt vmcnt(9)
	ds_write_b128 v209, v[176:179]
	s_waitcnt vmcnt(8)
	ds_write_b128 v210, v[180:183]
	ds_read_b128 v[176:179], v205 offset:36864
	ds_read_b128 v[180:183], v205 offset:41472
	ds_read_b128 v[234:237], v204
	ds_read_b128 v[238:241], v204 offset:4608
	s_setprio 1
	s_waitcnt lgkmcnt(1)
	v_mfma_f32_32x32x16_bf16 v[112:127], v[234:237], v[176:179], v[112:127]
	v_mfma_f32_32x32x16_bf16 v[48:63], v[234:237], v[180:183], v[48:63]
	s_waitcnt lgkmcnt(0)
	v_mfma_f32_32x32x16_bf16 v[96:111], v[238:241], v[176:179], v[96:111]
	v_mfma_f32_32x32x16_bf16 v[32:47], v[238:241], v[180:183], v[32:47]
	ds_read_b128 v[234:237], v204 offset:9216
	ds_read_b128 v[238:241], v204 offset:13824
	s_waitcnt vmcnt(7)
	ds_write_b128 v212, v[168:171]
	s_waitcnt vmcnt(6)
	ds_write_b128 v211, v[172:175]
	ds_read_b128 v[168:171], v205 offset:36896
	ds_read_b128 v[172:175], v205 offset:41504
	s_waitcnt lgkmcnt(5)
	v_mfma_f32_32x32x16_bf16 v[80:95], v[234:237], v[176:179], v[80:95]
	v_mfma_f32_32x32x16_bf16 v[16:31], v[234:237], v[180:183], v[16:31]
	ds_read_b128 v[234:237], v204 offset:32
	s_waitcnt lgkmcnt(5)
	v_mfma_f32_32x32x16_bf16 v[64:79], v[238:241], v[176:179], v[64:79]
	v_mfma_f32_32x32x16_bf16 v[0:15], v[238:241], v[180:183], v[0:15]
	ds_read_b128 v[238:241], v204 offset:4640
	global_load_dwordx4 v[176:179], v[194:195], off offset:3328
	global_load_dwordx4 v[180:183], v[196:197], off offset:3328
	s_waitcnt lgkmcnt(1)
	v_mfma_f32_32x32x16_bf16 v[112:127], v[234:237], v[168:171], v[112:127]
	v_mfma_f32_32x32x16_bf16 v[48:63], v[234:237], v[172:175], v[48:63]
	s_waitcnt lgkmcnt(0)
	v_mfma_f32_32x32x16_bf16 v[96:111], v[238:241], v[168:171], v[96:111]
	v_mfma_f32_32x32x16_bf16 v[32:47], v[238:241], v[172:175], v[32:47]
	ds_read_b128 v[234:237], v204 offset:9248
	ds_read_b128 v[238:241], v204 offset:13856
	s_waitcnt vmcnt(7)
	ds_write_b128 v214, v[160:163]
	s_waitcnt vmcnt(6)
	ds_write_b128 v213, v[164:167]
	ds_read_b128 v[160:163], v205 offset:36928
	ds_read_b128 v[164:167], v205 offset:41536
	s_waitcnt lgkmcnt(5)
	v_mfma_f32_32x32x16_bf16 v[80:95], v[234:237], v[168:171], v[80:95]
	v_mfma_f32_32x32x16_bf16 v[16:31], v[234:237], v[172:175], v[16:31]
	ds_read_b128 v[234:237], v204 offset:64
	s_waitcnt lgkmcnt(5)
	v_mfma_f32_32x32x16_bf16 v[64:79], v[238:241], v[168:171], v[64:79]
	v_mfma_f32_32x32x16_bf16 v[0:15], v[238:241], v[172:175], v[0:15]
	ds_read_b128 v[238:241], v204 offset:4672
	global_load_dwordx4 v[168:171], v[184:185], off offset:3328
	global_load_dwordx4 v[172:175], v[186:187], off offset:3328
	s_waitcnt lgkmcnt(1)
	v_mfma_f32_32x32x16_bf16 v[112:127], v[234:237], v[160:163], v[112:127]
	v_mfma_f32_32x32x16_bf16 v[48:63], v[234:237], v[164:167], v[48:63]
	s_waitcnt lgkmcnt(0)
	v_mfma_f32_32x32x16_bf16 v[96:111], v[238:241], v[160:163], v[96:111]
	v_mfma_f32_32x32x16_bf16 v[32:47], v[238:241], v[164:167], v[32:47]
	ds_read_b128 v[234:237], v204 offset:9280
	ds_read_b128 v[238:241], v204 offset:13888
	s_waitcnt vmcnt(7)
	ds_write_b128 v217, v[218:221]
	s_waitcnt vmcnt(6)
	ds_write_b128 v216, v[222:225]
	ds_read_b128 v[218:221], v205 offset:36960
	ds_read_b128 v[222:225], v205 offset:41568
	s_waitcnt lgkmcnt(5)
	v_mfma_f32_32x32x16_bf16 v[80:95], v[234:237], v[160:163], v[80:95]
	v_mfma_f32_32x32x16_bf16 v[16:31], v[234:237], v[164:167], v[16:31]
	ds_read_b128 v[234:237], v204 offset:96
	s_waitcnt lgkmcnt(5)
	v_mfma_f32_32x32x16_bf16 v[64:79], v[238:241], v[160:163], v[64:79]
	v_mfma_f32_32x32x16_bf16 v[0:15], v[238:241], v[164:167], v[0:15]
	ds_read_b128 v[238:241], v204 offset:4704
	global_load_dwordx4 v[160:163], v[198:199], off offset:3328
	global_load_dwordx4 v[164:167], v[200:201], off offset:3328
	s_waitcnt lgkmcnt(1)
	v_mfma_f32_32x32x16_bf16 v[112:127], v[234:237], v[218:221], v[112:127]
	v_mfma_f32_32x32x16_bf16 v[48:63], v[234:237], v[222:225], v[48:63]
	s_waitcnt lgkmcnt(0)
	v_mfma_f32_32x32x16_bf16 v[96:111], v[238:241], v[218:221], v[96:111]
	v_mfma_f32_32x32x16_bf16 v[32:47], v[238:241], v[222:225], v[32:47]
	ds_read_b128 v[234:237], v204 offset:9312
	ds_read_b128 v[238:241], v204 offset:13920
	s_waitcnt lgkmcnt(1)
	v_mfma_f32_32x32x16_bf16 v[80:95], v[234:237], v[218:221], v[80:95]
	v_mfma_f32_32x32x16_bf16 v[16:31], v[234:237], v[222:225], v[16:31]
	s_waitcnt lgkmcnt(0)
	v_mfma_f32_32x32x16_bf16 v[64:79], v[238:241], v[218:221], v[64:79]
	v_mfma_f32_32x32x16_bf16 v[0:15], v[238:241], v[222:225], v[0:15]
	s_setprio 0
	s_barrier
; template <bool trans>
; DI void gemm_core(const GTile& tl, const GTile& nx, bool has_next  , bool chain  , bool pre, u32x4 (&ra)[4], u32x4 (&rb)[4], char* smem, f32x16 (&acc)[2][4]) {
;     ...
;   const int nk = K / 64;
;   if (!pre) { G_LOAD(0); G_STORE(0); G_LOAD(1); }
;   for (int kt = 0; kt < nk; ++kt) {
;     __syncthreads();
;     G_COMPUTE(kt & 1, kt);
;   }
	global_load_dwordx4 v[218:221], v[190:191], off offset:3456
	global_load_dwordx4 v[222:225], v[188:189], off offset:3456
	s_waitcnt vmcnt(9)
	ds_write_b128 v215, v[226:229]
	s_waitcnt vmcnt(8)
	ds_write_b128 v215, v[230:233] offset:36864
	ds_read_b128 v[226:229], v208
	ds_read_b128 v[230:233], v208 offset:4608
	ds_read_b128 v[234:237], v192
	ds_read_b128 v[238:241], v192 offset:4608
	s_setprio 1
	s_waitcnt lgkmcnt(1)
	v_mfma_f32_32x32x16_bf16 v[112:127], v[234:237], v[226:229], v[112:127]
	v_mfma_f32_32x32x16_bf16 v[48:63], v[234:237], v[230:233], v[48:63]
	s_waitcnt lgkmcnt(0)
	v_mfma_f32_32x32x16_bf16 v[96:111], v[238:241], v[226:229], v[96:111]
	v_mfma_f32_32x32x16_bf16 v[32:47], v[238:241], v[230:233], v[32:47]
	ds_read_b128 v[234:237], v192 offset:9216
	ds_read_b128 v[238:241], v192 offset:13824
	s_waitcnt vmcnt(7)
	ds_write_b128 v215, v[176:179] offset:9216
	s_waitcnt vmcnt(6)
	ds_write_b128 v215, v[180:183] offset:46080
	ds_read_b128 v[176:179], v208 offset:32
	ds_read_b128 v[180:183], v208 offset:4640
	s_waitcnt lgkmcnt(5)
	v_mfma_f32_32x32x16_bf16 v[80:95], v[234:237], v[226:229], v[80:95]
	v_mfma_f32_32x32x16_bf16 v[16:31], v[234:237], v[230:233], v[16:31]
	ds_read_b128 v[234:237], v192 offset:32
	s_waitcnt lgkmcnt(5)
	v_mfma_f32_32x32x16_bf16 v[64:79], v[238:241], v[226:229], v[64:79]
	v_mfma_f32_32x32x16_bf16 v[0:15], v[238:241], v[230:233], v[0:15]
	ds_read_b128 v[238:241], v192 offset:4640
	global_load_dwordx4 v[226:229], v[194:195], off offset:3456
	global_load_dwordx4 v[230:233], v[196:197], off offset:3456
	s_waitcnt lgkmcnt(1)
	v_mfma_f32_32x32x16_bf16 v[112:127], v[234:237], v[176:179], v[112:127]
	v_mfma_f32_32x32x16_bf16 v[48:63], v[234:237], v[180:183], v[48:63]
	s_waitcnt lgkmcnt(0)
	v_mfma_f32_32x32x16_bf16 v[96:111], v[238:241], v[176:179], v[96:111]
	v_mfma_f32_32x32x16_bf16 v[32:47], v[238:241], v[180:183], v[32:47]
	ds_read_b128 v[234:237], v192 offset:9248
	ds_read_b128 v[238:241], v192 offset:13856
	s_waitcnt vmcnt(7)
	ds_write_b128 v215, v[168:171] offset:18432
	s_waitcnt vmcnt(6)
	ds_write_b128 v215, v[172:175] offset:55296
	ds_read_b128 v[168:171], v208 offset:64
	ds_read_b128 v[172:175], v208 offset:4672
	s_waitcnt lgkmcnt(5)
	v_mfma_f32_32x32x16_bf16 v[80:95], v[234:237], v[176:179], v[80:95]
	v_mfma_f32_32x32x16_bf16 v[16:31], v[234:237], v[180:183], v[16:31]
	ds_read_b128 v[234:237], v192 offset:64
	s_waitcnt lgkmcnt(5)
	v_mfma_f32_32x32x16_bf16 v[64:79], v[238:241], v[176:179], v[64:79]
	v_mfma_f32_32x32x16_bf16 v[0:15], v[238:241], v[180:183], v[0:15]
	ds_read_b128 v[238:241], v192 offset:4672
	global_load_dwordx4 v[176:179], v[184:185], off offset:3456
	global_load_dwordx4 v[180:183], v[186:187], off offset:3456
	s_waitcnt lgkmcnt(1)
	v_mfma_f32_32x32x16_bf16 v[112:127], v[234:237], v[168:171], v[112:127]
	v_mfma_f32_32x32x16_bf16 v[48:63], v[234:237], v[172:175], v[48:63]
	s_waitcnt lgkmcnt(0)
	v_mfma_f32_32x32x16_bf16 v[96:111], v[238:241], v[168:171], v[96:111]
	v_mfma_f32_32x32x16_bf16 v[32:47], v[238:241], v[172:175], v[32:47]
	ds_read_b128 v[234:237], v192 offset:9280
	ds_read_b128 v[238:241], v192 offset:13888
	s_waitcnt vmcnt(7)
	ds_write_b128 v215, v[160:163] offset:27648
	s_waitcnt vmcnt(6)
	ds_write_b128 v215, v[164:167] offset:64512
	ds_read_b128 v[160:163], v208 offset:96
	ds_read_b128 v[164:167], v208 offset:4704
	s_waitcnt lgkmcnt(5)
	v_mfma_f32_32x32x16_bf16 v[80:95], v[234:237], v[168:171], v[80:95]
	v_mfma_f32_32x32x16_bf16 v[16:31], v[234:237], v[172:175], v[16:31]
	ds_read_b128 v[234:237], v192 offset:96
	s_waitcnt lgkmcnt(5)
	v_mfma_f32_32x32x16_bf16 v[64:79], v[238:241], v[168:171], v[64:79]
	v_mfma_f32_32x32x16_bf16 v[0:15], v[238:241], v[172:175], v[0:15]
	ds_read_b128 v[238:241], v192 offset:4704
	global_load_dwordx4 v[168:171], v[198:199], off offset:3456
	global_load_dwordx4 v[172:175], v[200:201], off offset:3456
	s_waitcnt lgkmcnt(1)
	v_mfma_f32_32x32x16_bf16 v[112:127], v[234:237], v[160:163], v[112:127]
	v_mfma_f32_32x32x16_bf16 v[48:63], v[234:237], v[164:167], v[48:63]
	s_waitcnt lgkmcnt(0)
	v_mfma_f32_32x32x16_bf16 v[96:111], v[238:241], v[160:163], v[96:111]
	v_mfma_f32_32x32x16_bf16 v[32:47], v[238:241], v[164:167], v[32:47]
	ds_read_b128 v[234:237], v192 offset:9312
	ds_read_b128 v[238:241], v192 offset:13920
	s_waitcnt lgkmcnt(1)
	v_mfma_f32_32x32x16_bf16 v[80:95], v[234:237], v[160:163], v[80:95]
	v_mfma_f32_32x32x16_bf16 v[16:31], v[234:237], v[164:167], v[16:31]
	s_waitcnt lgkmcnt(0)
	v_mfma_f32_32x32x16_bf16 v[64:79], v[238:241], v[160:163], v[64:79]
	v_mfma_f32_32x32x16_bf16 v[0:15], v[238:241], v[164:167], v[0:15]
	s_setprio 0
	s_barrier
; template <bool trans>
; DI void gemm_core(const GTile& tl, const GTile& nx, bool has_next  , bool chain  , bool pre, u32x4 (&ra)[4], u32x4 (&rb)[4], char* smem, f32x16 (&acc)[2][4]) {
;     ...
;   const int nk = K / 64;
;   if (!pre) { G_LOAD(0); G_STORE(0); G_LOAD(1); }
;   for (int kt = 0; kt < nk; ++kt) {
;     __syncthreads();
;     G_COMPUTE(kt & 1, kt);
;   }
	global_load_dwordx4 v[160:163], v[190:191], off offset:3584
	global_load_dwordx4 v[164:167], v[188:189], off offset:3584
	s_waitcnt vmcnt(9)
	ds_write_b128 v209, v[218:221]
	s_waitcnt vmcnt(8)
	ds_write_b128 v210, v[222:225]
	ds_read_b128 v[218:221], v205 offset:36864
	ds_read_b128 v[222:225], v205 offset:41472
	ds_read_b128 v[234:237], v204
	ds_read_b128 v[238:241], v204 offset:4608
	s_setprio 1
	s_waitcnt lgkmcnt(1)
	v_mfma_f32_32x32x16_bf16 v[112:127], v[234:237], v[218:221], v[112:127]
	v_mfma_f32_32x32x16_bf16 v[48:63], v[234:237], v[222:225], v[48:63]
	s_waitcnt lgkmcnt(0)
	v_mfma_f32_32x32x16_bf16 v[96:111], v[238:241], v[218:221], v[96:111]
	v_mfma_f32_32x32x16_bf16 v[32:47], v[238:241], v[222:225], v[32:47]
	ds_read_b128 v[234:237], v204 offset:9216
	ds_read_b128 v[238:241], v204 offset:13824
	s_waitcnt vmcnt(7)
	ds_write_b128 v212, v[226:229]
	s_waitcnt vmcnt(6)
	ds_write_b128 v211, v[230:233]
	ds_read_b128 v[226:229], v205 offset:36896
	ds_read_b128 v[230:233], v205 offset:41504
	s_waitcnt lgkmcnt(5)
	v_mfma_f32_32x32x16_bf16 v[80:95], v[234:237], v[218:221], v[80:95]
	v_mfma_f32_32x32x16_bf16 v[16:31], v[234:237], v[222:225], v[16:31]
	ds_read_b128 v[234:237], v204 offset:32
	s_waitcnt lgkmcnt(5)
	v_mfma_f32_32x32x16_bf16 v[64:79], v[238:241], v[218:221], v[64:79]
	v_mfma_f32_32x32x16_bf16 v[0:15], v[238:241], v[222:225], v[0:15]
	ds_read_b128 v[238:241], v204 offset:4640
	global_load_dwordx4 v[218:221], v[194:195], off offset:3584
	global_load_dwordx4 v[222:225], v[196:197], off offset:3584
	s_waitcnt lgkmcnt(1)
	v_mfma_f32_32x32x16_bf16 v[112:127], v[234:237], v[226:229], v[112:127]
	v_mfma_f32_32x32x16_bf16 v[48:63], v[234:237], v[230:233], v[48:63]
	s_waitcnt lgkmcnt(0)
	v_mfma_f32_32x32x16_bf16 v[96:111], v[238:241], v[226:229], v[96:111]
	v_mfma_f32_32x32x16_bf16 v[32:47], v[238:241], v[230:233], v[32:47]
	ds_read_b128 v[234:237], v204 offset:9248
	ds_read_b128 v[238:241], v204 offset:13856
	s_waitcnt vmcnt(7)
	ds_write_b128 v214, v[176:179]
	s_waitcnt vmcnt(6)
	ds_write_b128 v213, v[180:183]
	ds_read_b128 v[176:179], v205 offset:36928
	ds_read_b128 v[180:183], v205 offset:41536
	s_waitcnt lgkmcnt(5)
	v_mfma_f32_32x32x16_bf16 v[80:95], v[234:237], v[226:229], v[80:95]
	v_mfma_f32_32x32x16_bf16 v[16:31], v[234:237], v[230:233], v[16:31]
	ds_read_b128 v[234:237], v204 offset:64
	s_waitcnt lgkmcnt(5)
	v_mfma_f32_32x32x16_bf16 v[64:79], v[238:241], v[226:229], v[64:79]
	v_mfma_f32_32x32x16_bf16 v[0:15], v[238:241], v[230:233], v[0:15]
	ds_read_b128 v[238:241], v204 offset:4672
	global_load_dwordx4 v[226:229], v[184:185], off offset:3584
	global_load_dwordx4 v[230:233], v[186:187], off offset:3584
	s_waitcnt lgkmcnt(1)
	v_mfma_f32_32x32x16_bf16 v[112:127], v[234:237], v[176:179], v[112:127]
	v_mfma_f32_32x32x16_bf16 v[48:63], v[234:237], v[180:183], v[48:63]
	s_waitcnt lgkmcnt(0)
	v_mfma_f32_32x32x16_bf16 v[96:111], v[238:241], v[176:179], v[96:111]
	v_mfma_f32_32x32x16_bf16 v[32:47], v[238:241], v[180:183], v[32:47]
	ds_read_b128 v[234:237], v204 offset:9280
	ds_read_b128 v[238:241], v204 offset:13888
	s_waitcnt vmcnt(7)
	ds_write_b128 v217, v[168:171]
	s_waitcnt vmcnt(6)
	ds_write_b128 v216, v[172:175]
	ds_read_b128 v[168:171], v205 offset:36960
	ds_read_b128 v[172:175], v205 offset:41568
	s_waitcnt lgkmcnt(5)
	v_mfma_f32_32x32x16_bf16 v[80:95], v[234:237], v[176:179], v[80:95]
	v_mfma_f32_32x32x16_bf16 v[16:31], v[234:237], v[180:183], v[16:31]
	ds_read_b128 v[234:237], v204 offset:96
	s_waitcnt lgkmcnt(5)
	v_mfma_f32_32x32x16_bf16 v[64:79], v[238:241], v[176:179], v[64:79]
	v_mfma_f32_32x32x16_bf16 v[0:15], v[238:241], v[180:183], v[0:15]
	ds_read_b128 v[238:241], v204 offset:4704
	global_load_dwordx4 v[176:179], v[198:199], off offset:3584
	global_load_dwordx4 v[180:183], v[200:201], off offset:3584
	s_waitcnt lgkmcnt(1)
	v_mfma_f32_32x32x16_bf16 v[112:127], v[234:237], v[168:171], v[112:127]
	v_mfma_f32_32x32x16_bf16 v[48:63], v[234:237], v[172:175], v[48:63]
	s_waitcnt lgkmcnt(0)
	v_mfma_f32_32x32x16_bf16 v[96:111], v[238:241], v[168:171], v[96:111]
	v_mfma_f32_32x32x16_bf16 v[32:47], v[238:241], v[172:175], v[32:47]
	ds_read_b128 v[234:237], v204 offset:9312
	ds_read_b128 v[238:241], v204 offset:13920
	s_waitcnt lgkmcnt(1)
	v_mfma_f32_32x32x16_bf16 v[80:95], v[234:237], v[168:171], v[80:95]
	v_mfma_f32_32x32x16_bf16 v[16:31], v[234:237], v[172:175], v[16:31]
	s_waitcnt lgkmcnt(0)
	v_mfma_f32_32x32x16_bf16 v[64:79], v[238:241], v[168:171], v[64:79]
	v_mfma_f32_32x32x16_bf16 v[0:15], v[238:241], v[172:175], v[0:15]
	s_setprio 0
	s_barrier
; template <bool trans>
; DI void gemm_core(const GTile& tl, const GTile& nx, bool has_next  , bool chain  , bool pre, u32x4 (&ra)[4], u32x4 (&rb)[4], char* smem, f32x16 (&acc)[2][4]) {
;     ...
;   const int nk = K / 64;
;   if (!pre) { G_LOAD(0); G_STORE(0); G_LOAD(1); }
;   for (int kt = 0; kt < nk; ++kt) {
;     __syncthreads();
;     G_COMPUTE(kt & 1, kt);
;   }
	global_load_dwordx4 v[168:171], v[190:191], off offset:3712
	global_load_dwordx4 v[172:175], v[188:189], off offset:3712
	s_waitcnt vmcnt(9)
	ds_write_b128 v215, v[160:163]
	s_waitcnt vmcnt(8)
	ds_write_b128 v215, v[164:167] offset:36864
	ds_read_b128 v[160:163], v208
	ds_read_b128 v[164:167], v208 offset:4608
	ds_read_b128 v[234:237], v192
	ds_read_b128 v[238:241], v192 offset:4608
	s_setprio 1
	s_waitcnt lgkmcnt(1)
	v_mfma_f32_32x32x16_bf16 v[112:127], v[234:237], v[160:163], v[112:127]
	v_mfma_f32_32x32x16_bf16 v[48:63], v[234:237], v[164:167], v[48:63]
	s_waitcnt lgkmcnt(0)
	v_mfma_f32_32x32x16_bf16 v[96:111], v[238:241], v[160:163], v[96:111]
	v_mfma_f32_32x32x16_bf16 v[32:47], v[238:241], v[164:167], v[32:47]
	ds_read_b128 v[234:237], v192 offset:9216
	ds_read_b128 v[238:241], v192 offset:13824
	s_waitcnt vmcnt(7)
	ds_write_b128 v215, v[218:221] offset:9216
	s_waitcnt vmcnt(6)
	ds_write_b128 v215, v[222:225] offset:46080
	ds_read_b128 v[218:221], v208 offset:32
	ds_read_b128 v[222:225], v208 offset:4640
	s_waitcnt lgkmcnt(5)
	v_mfma_f32_32x32x16_bf16 v[80:95], v[234:237], v[160:163], v[80:95]
	v_mfma_f32_32x32x16_bf16 v[16:31], v[234:237], v[164:167], v[16:31]
	ds_read_b128 v[234:237], v192 offset:32
	s_waitcnt lgkmcnt(5)
	v_mfma_f32_32x32x16_bf16 v[64:79], v[238:241], v[160:163], v[64:79]
	v_mfma_f32_32x32x16_bf16 v[0:15], v[238:241], v[164:167], v[0:15]
	ds_read_b128 v[238:241], v192 offset:4640
	global_load_dwordx4 v[160:163], v[194:195], off offset:3712
	global_load_dwordx4 v[164:167], v[196:197], off offset:3712
	s_waitcnt lgkmcnt(1)
	v_mfma_f32_32x32x16_bf16 v[112:127], v[234:237], v[218:221], v[112:127]
	v_mfma_f32_32x32x16_bf16 v[48:63], v[234:237], v[222:225], v[48:63]
	s_waitcnt lgkmcnt(0)
	v_mfma_f32_32x32x16_bf16 v[96:111], v[238:241], v[218:221], v[96:111]
	v_mfma_f32_32x32x16_bf16 v[32:47], v[238:241], v[222:225], v[32:47]
	ds_read_b128 v[234:237], v192 offset:9248
	ds_read_b128 v[238:241], v192 offset:13856
	s_waitcnt vmcnt(7)
	ds_write_b128 v215, v[226:229] offset:18432
	s_waitcnt vmcnt(6)
	ds_write_b128 v215, v[230:233] offset:55296
	ds_read_b128 v[226:229], v208 offset:64
	ds_read_b128 v[230:233], v208 offset:4672
	s_waitcnt lgkmcnt(5)
	v_mfma_f32_32x32x16_bf16 v[80:95], v[234:237], v[218:221], v[80:95]
	v_mfma_f32_32x32x16_bf16 v[16:31], v[234:237], v[222:225], v[16:31]
	ds_read_b128 v[234:237], v192 offset:64
	s_waitcnt lgkmcnt(5)
	v_mfma_f32_32x32x16_bf16 v[64:79], v[238:241], v[218:221], v[64:79]
	v_mfma_f32_32x32x16_bf16 v[0:15], v[238:241], v[222:225], v[0:15]
	ds_read_b128 v[238:241], v192 offset:4672
	global_load_dwordx4 v[218:221], v[184:185], off offset:3712
	global_load_dwordx4 v[222:225], v[186:187], off offset:3712
	s_waitcnt lgkmcnt(1)
	v_mfma_f32_32x32x16_bf16 v[112:127], v[234:237], v[226:229], v[112:127]
	v_mfma_f32_32x32x16_bf16 v[48:63], v[234:237], v[230:233], v[48:63]
	s_waitcnt lgkmcnt(0)
	v_mfma_f32_32x32x16_bf16 v[96:111], v[238:241], v[226:229], v[96:111]
	v_mfma_f32_32x32x16_bf16 v[32:47], v[238:241], v[230:233], v[32:47]
	ds_read_b128 v[234:237], v192 offset:9280
	ds_read_b128 v[238:241], v192 offset:13888
	s_waitcnt vmcnt(7)
	ds_write_b128 v215, v[176:179] offset:27648
	s_waitcnt vmcnt(6)
	ds_write_b128 v215, v[180:183] offset:64512
	ds_read_b128 v[176:179], v208 offset:96
	ds_read_b128 v[180:183], v208 offset:4704
	s_waitcnt lgkmcnt(5)
	v_mfma_f32_32x32x16_bf16 v[80:95], v[234:237], v[226:229], v[80:95]
	v_mfma_f32_32x32x16_bf16 v[16:31], v[234:237], v[230:233], v[16:31]
	ds_read_b128 v[234:237], v192 offset:96
	s_waitcnt lgkmcnt(5)
	v_mfma_f32_32x32x16_bf16 v[64:79], v[238:241], v[226:229], v[64:79]
	v_mfma_f32_32x32x16_bf16 v[0:15], v[238:241], v[230:233], v[0:15]
	ds_read_b128 v[238:241], v192 offset:4704
	global_load_dwordx4 v[226:229], v[198:199], off offset:3712
	global_load_dwordx4 v[230:233], v[200:201], off offset:3712
	s_waitcnt lgkmcnt(1)
	v_mfma_f32_32x32x16_bf16 v[112:127], v[234:237], v[176:179], v[112:127]
	v_mfma_f32_32x32x16_bf16 v[48:63], v[234:237], v[180:183], v[48:63]
	s_waitcnt lgkmcnt(0)
	v_mfma_f32_32x32x16_bf16 v[96:111], v[238:241], v[176:179], v[96:111]
	v_mfma_f32_32x32x16_bf16 v[32:47], v[238:241], v[180:183], v[32:47]
	ds_read_b128 v[234:237], v192 offset:9312
	ds_read_b128 v[238:241], v192 offset:13920
	s_waitcnt lgkmcnt(1)
	v_mfma_f32_32x32x16_bf16 v[80:95], v[234:237], v[176:179], v[80:95]
	v_mfma_f32_32x32x16_bf16 v[16:31], v[234:237], v[180:183], v[16:31]
	s_waitcnt lgkmcnt(0)
	v_mfma_f32_32x32x16_bf16 v[64:79], v[238:241], v[176:179], v[64:79]
	v_mfma_f32_32x32x16_bf16 v[0:15], v[238:241], v[180:183], v[0:15]
	s_setprio 0
	s_barrier
; template <bool trans>
; DI void gemm_core(const GTile& tl, const GTile& nx, bool has_next  , bool chain  , bool pre, u32x4 (&ra)[4], u32x4 (&rb)[4], char* smem, f32x16 (&acc)[2][4]) {
;     ...
;   const int nk = K / 64;
;   if (!pre) { G_LOAD(0); G_STORE(0); G_LOAD(1); }
;   for (int kt = 0; kt < nk; ++kt) {
;     __syncthreads();
;     G_COMPUTE(kt & 1, kt);
;   }
	global_load_dwordx4 v[176:179], v[190:191], off offset:3840
	global_load_dwordx4 v[180:183], v[188:189], off offset:3840
	s_waitcnt vmcnt(9)
	ds_write_b128 v209, v[168:171]
	s_waitcnt vmcnt(8)
	ds_write_b128 v210, v[172:175]
	ds_read_b128 v[168:171], v205 offset:36864
	ds_read_b128 v[172:175], v205 offset:41472
	ds_read_b128 v[234:237], v204
	ds_read_b128 v[238:241], v204 offset:4608
	s_setprio 1
	s_waitcnt lgkmcnt(1)
	v_mfma_f32_32x32x16_bf16 v[112:127], v[234:237], v[168:171], v[112:127]
	v_mfma_f32_32x32x16_bf16 v[48:63], v[234:237], v[172:175], v[48:63]
	s_waitcnt lgkmcnt(0)
	v_mfma_f32_32x32x16_bf16 v[96:111], v[238:241], v[168:171], v[96:111]
	v_mfma_f32_32x32x16_bf16 v[32:47], v[238:241], v[172:175], v[32:47]
	ds_read_b128 v[234:237], v204 offset:9216
	ds_read_b128 v[238:241], v204 offset:13824
	s_waitcnt lgkmcnt(1)
	v_mfma_f32_32x32x16_bf16 v[80:95], v[234:237], v[168:171], v[80:95]
	v_mfma_f32_32x32x16_bf16 v[16:31], v[234:237], v[172:175], v[16:31]
	s_waitcnt lgkmcnt(0)
	v_mfma_f32_32x32x16_bf16 v[64:79], v[238:241], v[168:171], v[64:79]
	v_mfma_f32_32x32x16_bf16 v[0:15], v[238:241], v[172:175], v[0:15]
	s_setprio 0
	global_load_dwordx4 v[234:237], v[194:195], off offset:3840
	global_load_dwordx4 v[238:241], v[196:197], off offset:3840
	s_waitcnt vmcnt(9)
	ds_write_b128 v212, v[160:163]
	s_waitcnt vmcnt(8)
	ds_write_b128 v211, v[164:167]
	ds_read_b128 v[160:163], v205 offset:36896
	ds_read_b128 v[164:167], v205 offset:41504
	ds_read_b128 v[168:171], v204 offset:32
	ds_read_b128 v[172:175], v204 offset:4640
	s_setprio 1
	s_waitcnt lgkmcnt(1)
	v_mfma_f32_32x32x16_bf16 v[112:127], v[168:171], v[160:163], v[112:127]
	v_mfma_f32_32x32x16_bf16 v[48:63], v[168:171], v[164:167], v[48:63]
	s_waitcnt lgkmcnt(0)
	v_mfma_f32_32x32x16_bf16 v[96:111], v[172:175], v[160:163], v[96:111]
	v_mfma_f32_32x32x16_bf16 v[32:47], v[172:175], v[164:167], v[32:47]
	ds_read_b128 v[168:171], v204 offset:9248
	ds_read_b128 v[172:175], v204 offset:13856
	s_waitcnt lgkmcnt(1)
	v_mfma_f32_32x32x16_bf16 v[80:95], v[168:171], v[160:163], v[80:95]
	v_mfma_f32_32x32x16_bf16 v[16:31], v[168:171], v[164:167], v[16:31]
	s_waitcnt lgkmcnt(0)
	v_mfma_f32_32x32x16_bf16 v[64:79], v[172:175], v[160:163], v[64:79]
	v_mfma_f32_32x32x16_bf16 v[0:15], v[172:175], v[164:167], v[0:15]
	s_setprio 0
	global_load_dwordx4 v[242:245], v[184:185], off offset:3840
	global_load_dwordx4 v[246:249], v[186:187], off offset:3840
	s_waitcnt vmcnt(9)
	ds_write_b128 v214, v[218:221]
	s_waitcnt vmcnt(8)
	ds_write_b128 v213, v[222:225]
	ds_read_b128 v[160:163], v205 offset:36928
	ds_read_b128 v[164:167], v205 offset:41536
	ds_read_b128 v[168:171], v204 offset:64
	ds_read_b128 v[172:175], v204 offset:4672
	s_setprio 1
	s_waitcnt lgkmcnt(1)
	v_mfma_f32_32x32x16_bf16 v[112:127], v[168:171], v[160:163], v[112:127]
	v_mfma_f32_32x32x16_bf16 v[48:63], v[168:171], v[164:167], v[48:63]
	s_waitcnt lgkmcnt(0)
	v_mfma_f32_32x32x16_bf16 v[96:111], v[172:175], v[160:163], v[96:111]
	v_mfma_f32_32x32x16_bf16 v[32:47], v[172:175], v[164:167], v[32:47]
	ds_read_b128 v[168:171], v204 offset:9280
	ds_read_b128 v[172:175], v204 offset:13888
	s_waitcnt lgkmcnt(1)
	v_mfma_f32_32x32x16_bf16 v[80:95], v[168:171], v[160:163], v[80:95]
	v_mfma_f32_32x32x16_bf16 v[16:31], v[168:171], v[164:167], v[16:31]
	s_waitcnt lgkmcnt(0)
	v_mfma_f32_32x32x16_bf16 v[64:79], v[172:175], v[160:163], v[64:79]
	v_mfma_f32_32x32x16_bf16 v[0:15], v[172:175], v[164:167], v[0:15]
	s_setprio 0
	global_load_dwordx4 v[218:221], v[198:199], off offset:3840
	global_load_dwordx4 v[222:225], v[200:201], off offset:3840
	s_waitcnt vmcnt(9)
	ds_write_b128 v217, v[226:229]
	s_waitcnt vmcnt(8)
	ds_write_b128 v216, v[230:233]
	ds_read_b128 v[160:163], v205 offset:36960
	ds_read_b128 v[164:167], v205 offset:41568
	ds_read_b128 v[168:171], v204 offset:96
	ds_read_b128 v[172:175], v204 offset:4704
	s_setprio 1
	s_waitcnt lgkmcnt(1)
	v_mfma_f32_32x32x16_bf16 v[112:127], v[168:171], v[160:163], v[112:127]
	v_mfma_f32_32x32x16_bf16 v[48:63], v[168:171], v[164:167], v[48:63]
	s_waitcnt lgkmcnt(0)
	v_mfma_f32_32x32x16_bf16 v[96:111], v[172:175], v[160:163], v[96:111]
	v_mfma_f32_32x32x16_bf16 v[32:47], v[172:175], v[164:167], v[32:47]
	ds_read_b128 v[168:171], v204 offset:9312
	ds_read_b128 v[172:175], v204 offset:13920
	s_waitcnt lgkmcnt(1)
	v_mfma_f32_32x32x16_bf16 v[80:95], v[168:171], v[160:163], v[80:95]
	v_mfma_f32_32x32x16_bf16 v[16:31], v[168:171], v[164:167], v[16:31]
	s_waitcnt lgkmcnt(0)
	v_mfma_f32_32x32x16_bf16 v[64:79], v[172:175], v[160:163], v[64:79]
	v_mfma_f32_32x32x16_bf16 v[0:15], v[172:175], v[164:167], v[0:15]
	s_setprio 0
	s_barrier
; template <bool trans>
; DI void gemm_core(const GTile& tl, const GTile& nx, bool has_next  , bool chain  , bool pre, u32x4 (&ra)[4], u32x4 (&rb)[4], char* smem, f32x16 (&acc)[2][4]) {
;     ...
;   const int nk = K / 64;
;   if (!pre) { G_LOAD(0); G_STORE(0); G_LOAD(1); }
;   for (int kt = 0; kt < nk; ++kt) {
;     __syncthreads();
;     G_COMPUTE(kt & 1, kt);
;   }
	global_load_dwordx4 v[160:163], v[190:191], off offset:3968
	global_load_dwordx4 v[164:167], v[188:189], off offset:3968
	s_waitcnt vmcnt(9)
	ds_write_b128 v215, v[176:179]
	s_waitcnt vmcnt(8)
	ds_write_b128 v215, v[180:183] offset:36864
	ds_read_b128 v[168:171], v208
	ds_read_b128 v[172:175], v208 offset:4608
	ds_read_b128 v[176:179], v192
	ds_read_b128 v[180:183], v192 offset:4608
	s_setprio 1
	s_waitcnt lgkmcnt(1)
	v_mfma_f32_32x32x16_bf16 v[112:127], v[176:179], v[168:171], v[112:127]
	v_mfma_f32_32x32x16_bf16 v[48:63], v[176:179], v[172:175], v[48:63]
	s_waitcnt lgkmcnt(0)
	v_mfma_f32_32x32x16_bf16 v[96:111], v[180:183], v[168:171], v[96:111]
	v_mfma_f32_32x32x16_bf16 v[32:47], v[180:183], v[172:175], v[32:47]
	ds_read_b128 v[176:179], v192 offset:9216
	ds_read_b128 v[180:183], v192 offset:13824
	s_waitcnt lgkmcnt(1)
	v_mfma_f32_32x32x16_bf16 v[80:95], v[176:179], v[168:171], v[80:95]
	v_mfma_f32_32x32x16_bf16 v[16:31], v[176:179], v[172:175], v[16:31]
	s_waitcnt lgkmcnt(0)
	v_mfma_f32_32x32x16_bf16 v[64:79], v[180:183], v[168:171], v[64:79]
	v_mfma_f32_32x32x16_bf16 v[0:15], v[180:183], v[172:175], v[0:15]
	s_setprio 0
	global_load_dwordx4 v[168:171], v[194:195], off offset:3968
	global_load_dwordx4 v[172:175], v[196:197], off offset:3968
	s_waitcnt vmcnt(9)
	ds_write_b128 v215, v[234:237] offset:9216
	s_waitcnt vmcnt(8)
	ds_write_b128 v215, v[238:241] offset:46080
	ds_read_b128 v[176:179], v208 offset:32
	ds_read_b128 v[180:183], v208 offset:4640
	ds_read_b128 v[188:191], v192 offset:32
	ds_read_b128 v[194:197], v192 offset:4640
	s_setprio 1
	s_waitcnt lgkmcnt(1)
	v_mfma_f32_32x32x16_bf16 v[112:127], v[188:191], v[176:179], v[112:127]
	v_mfma_f32_32x32x16_bf16 v[48:63], v[188:191], v[180:183], v[48:63]
	s_waitcnt lgkmcnt(0)
	v_mfma_f32_32x32x16_bf16 v[96:111], v[194:197], v[176:179], v[96:111]
	v_mfma_f32_32x32x16_bf16 v[32:47], v[194:197], v[180:183], v[32:47]
	ds_read_b128 v[188:191], v192 offset:9248
	ds_read_b128 v[194:197], v192 offset:13856
	s_waitcnt lgkmcnt(1)
	v_mfma_f32_32x32x16_bf16 v[80:95], v[188:191], v[176:179], v[80:95]
	v_mfma_f32_32x32x16_bf16 v[16:31], v[188:191], v[180:183], v[16:31]
	s_waitcnt lgkmcnt(0)
	v_mfma_f32_32x32x16_bf16 v[64:79], v[194:197], v[176:179], v[64:79]
	v_mfma_f32_32x32x16_bf16 v[0:15], v[194:197], v[180:183], v[0:15]
	s_setprio 0
	global_load_dwordx4 v[176:179], v[184:185], off offset:3968
	global_load_dwordx4 v[180:183], v[186:187], off offset:3968
	s_waitcnt vmcnt(9)
	ds_write_b128 v215, v[242:245] offset:18432
	s_waitcnt vmcnt(8)
	ds_write_b128 v215, v[246:249] offset:55296
	ds_read_b128 v[184:187], v208 offset:64
	ds_read_b128 v[188:191], v208 offset:4672
	ds_read_b128 v[194:197], v192 offset:64
	ds_read_b128 v[226:229], v192 offset:4672
	s_setprio 1
	s_waitcnt lgkmcnt(1)
	v_mfma_f32_32x32x16_bf16 v[112:127], v[194:197], v[184:187], v[112:127]
	v_mfma_f32_32x32x16_bf16 v[48:63], v[194:197], v[188:191], v[48:63]
	s_waitcnt lgkmcnt(0)
	v_mfma_f32_32x32x16_bf16 v[96:111], v[226:229], v[184:187], v[96:111]
	v_mfma_f32_32x32x16_bf16 v[32:47], v[226:229], v[188:191], v[32:47]
	ds_read_b128 v[194:197], v192 offset:9280
	ds_read_b128 v[226:229], v192 offset:13888
	s_waitcnt lgkmcnt(1)
	v_mfma_f32_32x32x16_bf16 v[80:95], v[194:197], v[184:187], v[80:95]
	v_mfma_f32_32x32x16_bf16 v[16:31], v[194:197], v[188:191], v[16:31]
	s_waitcnt lgkmcnt(0)
	v_mfma_f32_32x32x16_bf16 v[64:79], v[226:229], v[184:187], v[64:79]
	v_mfma_f32_32x32x16_bf16 v[0:15], v[226:229], v[188:191], v[0:15]
	s_setprio 0
	global_load_dwordx4 v[184:187], v[198:199], off offset:3968
	global_load_dwordx4 v[188:191], v[200:201], off offset:3968
	s_waitcnt vmcnt(9)
	ds_write_b128 v215, v[218:221] offset:27648
	s_waitcnt vmcnt(8)
	ds_write_b128 v215, v[222:225] offset:64512
	ds_read_b128 v[194:197], v208 offset:96
	ds_read_b128 v[198:201], v208 offset:4704
	ds_read_b128 v[218:221], v192 offset:96
	ds_read_b128 v[222:225], v192 offset:4704
	s_setprio 1
	s_waitcnt lgkmcnt(1)
	v_mfma_f32_32x32x16_bf16 v[112:127], v[218:221], v[194:197], v[112:127]
	v_mfma_f32_32x32x16_bf16 v[48:63], v[218:221], v[198:201], v[48:63]
	s_waitcnt lgkmcnt(0)
	v_mfma_f32_32x32x16_bf16 v[96:111], v[222:225], v[194:197], v[96:111]
	v_mfma_f32_32x32x16_bf16 v[32:47], v[222:225], v[198:201], v[32:47]
	ds_read_b128 v[218:221], v192 offset:9312
	ds_read_b128 v[222:225], v192 offset:13920
	s_waitcnt lgkmcnt(1)
	v_mfma_f32_32x32x16_bf16 v[80:95], v[218:221], v[194:197], v[80:95]
	v_mfma_f32_32x32x16_bf16 v[16:31], v[218:221], v[198:201], v[16:31]
	s_waitcnt lgkmcnt(0)
	v_mfma_f32_32x32x16_bf16 v[64:79], v[222:225], v[194:197], v[64:79]
	v_mfma_f32_32x32x16_bf16 v[0:15], v[222:225], v[198:201], v[0:15]
	s_setprio 0
	s_barrier
; template <bool trans>
; DI void gemm_core(const GTile& tl, const GTile& nx, bool has_next  , bool chain  , bool pre, u32x4 (&ra)[4], u32x4 (&rb)[4], char* smem, f32x16 (&acc)[2][4]) {
;     ...
;   const int nk = K / 64;
;   if (!pre) { G_LOAD(0); G_STORE(0); G_LOAD(1); }
;   for (int kt = 0; kt < nk; ++kt) {
;     __syncthreads();
;     G_COMPUTE(kt & 1, kt);
;   }
	s_waitcnt vmcnt(7)
	ds_write_b128 v209, v[160:163]
	s_waitcnt vmcnt(6)
	ds_write_b128 v210, v[164:167]
	ds_read_b128 v[194:197], v205 offset:36864
	ds_read_b128 v[198:201], v205 offset:41472
	ds_read_b128 v[218:221], v204
	ds_read_b128 v[222:225], v204 offset:4608
	s_setprio 1
	s_waitcnt lgkmcnt(1)
	v_mfma_f32_32x32x16_bf16 v[112:127], v[218:221], v[194:197], v[112:127]
	v_mfma_f32_32x32x16_bf16 v[48:63], v[218:221], v[198:201], v[48:63]
	s_waitcnt lgkmcnt(0)
	v_mfma_f32_32x32x16_bf16 v[96:111], v[222:225], v[194:197], v[96:111]
	v_mfma_f32_32x32x16_bf16 v[32:47], v[222:225], v[198:201], v[32:47]
	ds_read_b128 v[218:221], v204 offset:9216
	ds_read_b128 v[222:225], v204 offset:13824
	s_waitcnt lgkmcnt(1)
	v_mfma_f32_32x32x16_bf16 v[80:95], v[218:221], v[194:197], v[80:95]
	v_mfma_f32_32x32x16_bf16 v[16:31], v[218:221], v[198:201], v[16:31]
	s_waitcnt lgkmcnt(0)
	v_mfma_f32_32x32x16_bf16 v[64:79], v[222:225], v[194:197], v[64:79]
	v_mfma_f32_32x32x16_bf16 v[0:15], v[222:225], v[198:201], v[0:15]
	s_setprio 0
	s_waitcnt vmcnt(5)
	ds_write_b128 v212, v[168:171]
	s_waitcnt vmcnt(4)
	ds_write_b128 v211, v[172:175]
	ds_read_b128 v[194:197], v205 offset:36896
	ds_read_b128 v[198:201], v205 offset:41504
	ds_read_b128 v[218:221], v204 offset:32
	ds_read_b128 v[222:225], v204 offset:4640
	s_setprio 1
	s_waitcnt lgkmcnt(1)
	v_mfma_f32_32x32x16_bf16 v[112:127], v[218:221], v[194:197], v[112:127]
	v_mfma_f32_32x32x16_bf16 v[48:63], v[218:221], v[198:201], v[48:63]
	s_waitcnt lgkmcnt(0)
	v_mfma_f32_32x32x16_bf16 v[96:111], v[222:225], v[194:197], v[96:111]
	v_mfma_f32_32x32x16_bf16 v[32:47], v[222:225], v[198:201], v[32:47]
	ds_read_b128 v[218:221], v204 offset:9248
	ds_read_b128 v[222:225], v204 offset:13856
	s_waitcnt lgkmcnt(1)
	v_mfma_f32_32x32x16_bf16 v[80:95], v[218:221], v[194:197], v[80:95]
	v_mfma_f32_32x32x16_bf16 v[16:31], v[218:221], v[198:201], v[16:31]
	s_waitcnt lgkmcnt(0)
	v_mfma_f32_32x32x16_bf16 v[64:79], v[222:225], v[194:197], v[64:79]
	v_mfma_f32_32x32x16_bf16 v[0:15], v[222:225], v[198:201], v[0:15]
	s_setprio 0
	s_waitcnt vmcnt(3)
	ds_write_b128 v214, v[176:179]
	s_waitcnt vmcnt(2)
	ds_write_b128 v213, v[180:183]
	ds_read_b128 v[194:197], v205 offset:36928
	ds_read_b128 v[198:201], v205 offset:41536
	ds_read_b128 v[210:213], v204 offset:64
	ds_read_b128 v[218:221], v204 offset:4672
	s_setprio 1
	s_waitcnt lgkmcnt(1)
	v_mfma_f32_32x32x16_bf16 v[112:127], v[210:213], v[194:197], v[112:127]
	v_mfma_f32_32x32x16_bf16 v[48:63], v[210:213], v[198:201], v[48:63]
	s_waitcnt lgkmcnt(0)
	v_mfma_f32_32x32x16_bf16 v[96:111], v[218:221], v[194:197], v[96:111]
	v_mfma_f32_32x32x16_bf16 v[32:47], v[218:221], v[198:201], v[32:47]
	ds_read_b128 v[210:213], v204 offset:9280
	ds_read_b128 v[218:221], v204 offset:13888
	s_waitcnt lgkmcnt(1)
	v_mfma_f32_32x32x16_bf16 v[80:95], v[210:213], v[194:197], v[80:95]
	v_mfma_f32_32x32x16_bf16 v[16:31], v[210:213], v[198:201], v[16:31]
	s_waitcnt lgkmcnt(0)
	v_mfma_f32_32x32x16_bf16 v[64:79], v[218:221], v[194:197], v[64:79]
	v_mfma_f32_32x32x16_bf16 v[0:15], v[218:221], v[198:201], v[0:15]
	s_setprio 0
	s_waitcnt vmcnt(1)
	ds_write_b128 v217, v[184:187]
	s_waitcnt vmcnt(0)
	ds_write_b128 v216, v[188:191]
	ds_read_b128 v[194:197], v205 offset:36960
	ds_read_b128 v[198:201], v205 offset:41568
	ds_read_b128 v[210:213], v204 offset:96
	ds_read_b128 v[214:217], v204 offset:4704
	s_setprio 1
	s_waitcnt lgkmcnt(1)
	v_mfma_f32_32x32x16_bf16 v[112:127], v[210:213], v[194:197], v[112:127]
	v_mfma_f32_32x32x16_bf16 v[48:63], v[210:213], v[198:201], v[48:63]
	s_waitcnt lgkmcnt(0)
	v_mfma_f32_32x32x16_bf16 v[96:111], v[214:217], v[194:197], v[96:111]
	v_mfma_f32_32x32x16_bf16 v[32:47], v[214:217], v[198:201], v[32:47]
	ds_read_b128 v[210:213], v204 offset:9312
	ds_read_b128 v[214:217], v204 offset:13920
	s_waitcnt lgkmcnt(1)
	v_mfma_f32_32x32x16_bf16 v[80:95], v[210:213], v[194:197], v[80:95]
	v_mfma_f32_32x32x16_bf16 v[16:31], v[210:213], v[198:201], v[16:31]
	s_waitcnt lgkmcnt(0)
	v_mfma_f32_32x32x16_bf16 v[64:79], v[214:217], v[194:197], v[64:79]
	v_mfma_f32_32x32x16_bf16 v[0:15], v[214:217], v[198:201], v[0:15]
	s_setprio 0
	s_barrier
; template <bool trans>
; DI void gemm_core(const GTile& tl, const GTile& nx, bool has_next  , bool chain  , bool pre, u32x4 (&ra)[4], u32x4 (&rb)[4], char* smem, f32x16 (&acc)[2][4]) {
;     ...
;   const int nk = K / 64;
;   if (!pre) { G_LOAD(0); G_STORE(0); G_LOAD(1); }
;   for (int kt = 0; kt < nk; ++kt) {
;     __syncthreads();
;     G_COMPUTE(kt & 1, kt);
;   }
;   if (!has_next) __syncthreads();
	ds_read_b128 v[194:197], v208
	ds_read_b128 v[198:201], v208 offset:4608
	ds_read_b128 v[210:213], v192
	ds_read_b128 v[214:217], v192 offset:4608
	s_setprio 1
	s_waitcnt lgkmcnt(1)
	v_mfma_f32_32x32x16_bf16 v[112:127], v[210:213], v[194:197], v[112:127]
	v_mfma_f32_32x32x16_bf16 v[48:63], v[210:213], v[198:201], v[48:63]
	s_waitcnt lgkmcnt(0)
	v_mfma_f32_32x32x16_bf16 v[96:111], v[214:217], v[194:197], v[96:111]
	v_mfma_f32_32x32x16_bf16 v[32:47], v[214:217], v[198:201], v[32:47]
	ds_read_b128 v[210:213], v192 offset:9216
	ds_read_b128 v[214:217], v192 offset:13824
	s_waitcnt lgkmcnt(1)
	v_mfma_f32_32x32x16_bf16 v[80:95], v[210:213], v[194:197], v[80:95]
	v_mfma_f32_32x32x16_bf16 v[16:31], v[210:213], v[198:201], v[16:31]
	s_waitcnt lgkmcnt(0)
	v_mfma_f32_32x32x16_bf16 v[64:79], v[214:217], v[194:197], v[64:79]
	v_mfma_f32_32x32x16_bf16 v[0:15], v[214:217], v[198:201], v[0:15]
	s_setprio 0
	ds_read_b128 v[194:197], v208 offset:32
	ds_read_b128 v[198:201], v208 offset:4640
	ds_read_b128 v[210:213], v192 offset:32
	ds_read_b128 v[214:217], v192 offset:4640
	s_setprio 1
	s_waitcnt lgkmcnt(1)
	v_mfma_f32_32x32x16_bf16 v[112:127], v[210:213], v[194:197], v[112:127]
	v_mfma_f32_32x32x16_bf16 v[48:63], v[210:213], v[198:201], v[48:63]
	s_waitcnt lgkmcnt(0)
	v_mfma_f32_32x32x16_bf16 v[96:111], v[214:217], v[194:197], v[96:111]
	v_mfma_f32_32x32x16_bf16 v[32:47], v[214:217], v[198:201], v[32:47]
	ds_read_b128 v[210:213], v192 offset:9248
	ds_read_b128 v[214:217], v192 offset:13856
	s_waitcnt lgkmcnt(1)
	v_mfma_f32_32x32x16_bf16 v[80:95], v[210:213], v[194:197], v[80:95]
	v_mfma_f32_32x32x16_bf16 v[16:31], v[210:213], v[198:201], v[16:31]
	s_waitcnt lgkmcnt(0)
	v_mfma_f32_32x32x16_bf16 v[64:79], v[214:217], v[194:197], v[64:79]
	v_mfma_f32_32x32x16_bf16 v[0:15], v[214:217], v[198:201], v[0:15]
	s_setprio 0
	ds_read_b128 v[194:197], v208 offset:64
	ds_read_b128 v[198:201], v208 offset:4672
	ds_read_b128 v[210:213], v192 offset:64
	ds_read_b128 v[214:217], v192 offset:4672
	s_setprio 1
	s_waitcnt lgkmcnt(1)
	v_mfma_f32_32x32x16_bf16 v[112:127], v[210:213], v[194:197], v[112:127]
	v_mfma_f32_32x32x16_bf16 v[48:63], v[210:213], v[198:201], v[48:63]
	s_waitcnt lgkmcnt(0)
	v_mfma_f32_32x32x16_bf16 v[96:111], v[214:217], v[194:197], v[96:111]
	v_mfma_f32_32x32x16_bf16 v[32:47], v[214:217], v[198:201], v[32:47]
	ds_read_b128 v[210:213], v192 offset:9280
	ds_read_b128 v[214:217], v192 offset:13888
	s_waitcnt lgkmcnt(1)
	v_mfma_f32_32x32x16_bf16 v[80:95], v[210:213], v[194:197], v[80:95]
	v_mfma_f32_32x32x16_bf16 v[16:31], v[210:213], v[198:201], v[16:31]
	s_waitcnt lgkmcnt(0)
	v_mfma_f32_32x32x16_bf16 v[64:79], v[214:217], v[194:197], v[64:79]
	v_mfma_f32_32x32x16_bf16 v[0:15], v[214:217], v[198:201], v[0:15]
	s_setprio 0
	ds_read_b128 v[194:197], v208 offset:96
	ds_read_b128 v[198:201], v208 offset:4704
	ds_read_b128 v[208:211], v192 offset:96
	ds_read_b128 v[212:215], v192 offset:4704
	s_setprio 1
	s_waitcnt lgkmcnt(1)
	v_mfma_f32_32x32x16_bf16 v[112:127], v[208:211], v[194:197], v[112:127]
	v_mfma_f32_32x32x16_bf16 v[48:63], v[208:211], v[198:201], v[48:63]
	s_waitcnt lgkmcnt(0)
	v_mfma_f32_32x32x16_bf16 v[96:111], v[212:215], v[194:197], v[96:111]
	v_mfma_f32_32x32x16_bf16 v[32:47], v[212:215], v[198:201], v[32:47]
	ds_read_b128 v[208:211], v192 offset:9312
	ds_read_b128 v[212:215], v192 offset:13920
	s_waitcnt lgkmcnt(1)
	v_mfma_f32_32x32x16_bf16 v[80:95], v[208:211], v[194:197], v[80:95]
	v_mfma_f32_32x32x16_bf16 v[16:31], v[208:211], v[198:201], v[16:31]
	s_waitcnt lgkmcnt(0)
	v_mfma_f32_32x32x16_bf16 v[64:79], v[212:215], v[194:197], v[64:79]
	v_mfma_f32_32x32x16_bf16 v[0:15], v[212:215], v[198:201], v[0:15]
	s_setprio 0
	s_andn2_b64 vcc, exec, s[48:49]
	s_cbranch_vccnz .LBB0_105
	s_barrier

; template <bool trans>
; DI void gemm_core(const GTile& tl, const GTile& nx, bool has_next  , bool chain  , bool pre, u32x4 (&ra)[4], u32x4 (&rb)[4], char* smem, f32x16 (&acc)[2][4]) {
;     ...
;   const int lrow = tid >> 3, kc = tid & 7;
;   const unsigned aoff = (unsigned)(lrow * lda + kc * 8) * 2u, boff = (unsigned)(lrow * ldb + kc * 8) * 2u;
;   const char* ag = (const char*)(A + (size_t)m0 * lda);
;   const char* bg = (const char*)(Bt + (size_t)n0 * ldb);
;   const unsigned aoffn = (unsigned)(lrow * nx.lda + kc * 8) * 2u, boffn = (unsigned)(lrow * nx.ldb + kc * 8) * 2u;
;   const char* agn = (const char*)(nx.A + (size_t)nx.m0 * nx.lda);
;   const char* bgn = (const char*)(nx.Bt + (size_t)nx.n0 * nx.ldb);
;     ...
;   const int nk = K / 64;
;   if (!pre) { G_LOAD(0); G_STORE(0); G_LOAD(1); }
;   for (int kt = 0; kt < nk; ++kt) {
;     __syncthreads();
;     G_COMPUTE(kt & 1, kt);
;   }
.LBB0_111:
	v_lshl_add_u64 v[136:137], s[0:1], 0, v[192:193]
	v_lshl_add_u64 v[138:139], s[2:3], 0, v[192:193]
	s_waitcnt lgkmcnt(0)
	s_barrier
	global_load_dwordx4 v[184:187], v[136:137], off offset:256
	global_load_dwordx4 v[188:191], v[138:139], off offset:256
	s_and_b32 s1, s36, 0x1f80000
	s_and_b32 s0, s38, 0xffffff00
	s_and_b32 s4, s33, 0xc0
	s_lshl_b32 s1, s1, 1
	s_add_u32 s2, s16, s1
	s_addc_u32 s3, s17, 0
	s_ashr_i32 s1, s0, 31
	s_lshl_b64 s[0:1], s[0:1], 12
	s_add_u32 s0, s22, s0
	s_addc_u32 s1, s23, s1
	s_lshr_b32 s5, s33, 1
	v_and_b32_e32 v11, 31, v8
	s_and_b32 s5, s5, 0xfffff80
	v_or_b32_e32 v12, s5, v11
	v_or_b32_e32 v11, s4, v11
	v_add3_u32 v148, 16, v10, v9
	v_lshrrev_b32_e32 v8, 1, v8
	v_mul_u32_u24_e32 v150, 0x90, v11
	v_lshl_add_u64 v[130:131], s[2:3], 0, v[192:193]
	v_lshl_add_u64 v[128:129], s[0:1], 0, v[192:193]
	v_and_b32_e32 v204, 16, v8
	v_add_u32_e32 v192, 0x12000, v148
	v_mul_lo_u32 v149, v12, s45
	v_add3_u32 v152, 16, v150, v204
	v_add_u32_e32 v159, 0x1b000, v148
	ds_write_b128 v192, v[0:3]
	s_waitcnt vmcnt(5)
	ds_write_b128 v159, v[4:7]
	v_add3_u32 v151, 16, v149, v204
	ds_read_b128 v[0:3], v152 offset:36864
	ds_read_b128 v[4:7], v152 offset:41472
	ds_read_b128 v[8:11], v151
	ds_read_b128 v[12:15], v151 offset:4608
	v_lshl_add_u64 v[140:141], v[136:137], 0, s[34:35]
	v_lshl_add_u64 v[142:143], v[138:139], 0, s[34:35]
	v_lshl_add_u64 v[132:133], v[136:137], 0, s[42:43]
	v_lshl_add_u64 v[134:135], v[138:139], 0, s[42:43]
	s_setprio 1
	s_waitcnt lgkmcnt(1)
	v_mfma_f32_32x32x16_bf16 v[112:127], v[0:3], v[8:11], 0
	v_mfma_f32_32x32x16_bf16 v[48:63], v[4:7], v[8:11], 0
	s_waitcnt lgkmcnt(0)
	v_mfma_f32_32x32x16_bf16 v[96:111], v[0:3], v[12:15], 0
	v_mfma_f32_32x32x16_bf16 v[32:47], v[4:7], v[12:15], 0
	ds_read_b128 v[8:11], v151 offset:9216
	ds_read_b128 v[12:15], v151 offset:13824
	s_waitcnt lgkmcnt(1)
	v_mfma_f32_32x32x16_bf16 v[80:95], v[0:3], v[8:11], 0
	v_mfma_f32_32x32x16_bf16 v[16:31], v[4:7], v[8:11], 0
	s_waitcnt lgkmcnt(0)
	v_mfma_f32_32x32x16_bf16 v[64:79], v[0:3], v[12:15], 0
	v_mfma_f32_32x32x16_bf16 v[0:15], v[4:7], v[12:15], 0
	s_setprio 0
	global_load_dwordx4 v[194:197], v[140:141], off offset:256
	global_load_dwordx4 v[198:201], v[142:143], off offset:256
	v_add_u32_e32 v158, 0x14400, v148
	v_add_u32_e32 v157, 0x1d400, v148
	ds_write_b128 v158, v[176:179]
	s_waitcnt vmcnt(6)
	ds_write_b128 v157, v[180:183]
	ds_read_b128 v[144:147], v152 offset:36896
	ds_read_b128 v[176:179], v152 offset:41504
	ds_read_b128 v[180:183], v151 offset:32
	ds_read_b128 v[208:211], v151 offset:4640
	s_setprio 1
	s_waitcnt lgkmcnt(1)
	v_mfma_f32_32x32x16_bf16 v[112:127], v[144:147], v[180:183], v[112:127]
	v_mfma_f32_32x32x16_bf16 v[48:63], v[176:179], v[180:183], v[48:63]
	s_waitcnt lgkmcnt(0)
	v_mfma_f32_32x32x16_bf16 v[96:111], v[144:147], v[208:211], v[96:111]
	v_mfma_f32_32x32x16_bf16 v[32:47], v[176:179], v[208:211], v[32:47]
	ds_read_b128 v[180:183], v151 offset:9248
	ds_read_b128 v[208:211], v151 offset:13856
	s_waitcnt lgkmcnt(1)
	v_mfma_f32_32x32x16_bf16 v[80:95], v[144:147], v[180:183], v[80:95]
	v_mfma_f32_32x32x16_bf16 v[16:31], v[176:179], v[180:183], v[16:31]
	s_waitcnt lgkmcnt(0)
	v_mfma_f32_32x32x16_bf16 v[64:79], v[144:147], v[208:211], v[64:79]
	v_mfma_f32_32x32x16_bf16 v[0:15], v[176:179], v[208:211], v[0:15]
	s_setprio 0
	global_load_dwordx4 v[176:179], v[132:133], off offset:256
	global_load_dwordx4 v[180:183], v[134:135], off offset:256
	v_add_u32_e32 v154, 0x16800, v148
	v_add_u32_e32 v153, 0x1f800, v148
	ds_write_b128 v154, v[168:171]
	s_waitcnt vmcnt(7)
	ds_write_b128 v153, v[172:175]
	ds_read_b128 v[144:147], v152 offset:36928
	ds_read_b128 v[168:171], v152 offset:41536
	ds_read_b128 v[172:175], v151 offset:64
	ds_read_b128 v[208:211], v151 offset:4672
	s_setprio 1
	s_waitcnt lgkmcnt(1)
	v_mfma_f32_32x32x16_bf16 v[112:127], v[144:147], v[172:175], v[112:127]
	v_mfma_f32_32x32x16_bf16 v[48:63], v[168:171], v[172:175], v[48:63]
	s_waitcnt lgkmcnt(0)
	v_mfma_f32_32x32x16_bf16 v[96:111], v[144:147], v[208:211], v[96:111]
	v_mfma_f32_32x32x16_bf16 v[32:47], v[168:171], v[208:211], v[32:47]
	ds_read_b128 v[172:175], v151 offset:9280
	ds_read_b128 v[208:211], v151 offset:13888
	s_waitcnt lgkmcnt(1)
	v_mfma_f32_32x32x16_bf16 v[80:95], v[144:147], v[172:175], v[80:95]
	v_mfma_f32_32x32x16_bf16 v[16:31], v[168:171], v[172:175], v[16:31]
	s_waitcnt lgkmcnt(0)
	v_mfma_f32_32x32x16_bf16 v[64:79], v[144:147], v[208:211], v[64:79]
	v_mfma_f32_32x32x16_bf16 v[0:15], v[168:171], v[208:211], v[0:15]
	s_setprio 0
	v_add_co_u32_e32 v144, vcc, s44, v136
	v_add_u32_e32 v156, 0x18c00, v148
	s_nop 0
	v_addc_co_u32_e32 v145, vcc, 0, v137, vcc
	v_add_co_u32_e32 v146, vcc, s44, v138
	v_add_u32_e32 v155, 0x21c00, v148
	s_nop 0
	v_addc_co_u32_e32 v147, vcc, 0, v139, vcc
	global_load_dwordx4 v[168:171], v[144:145], off offset:256
	global_load_dwordx4 v[172:175], v[146:147], off offset:256
	ds_write_b128 v156, v[160:163]
	s_waitcnt vmcnt(8)
	ds_write_b128 v155, v[164:167]
	ds_read_b128 v[160:163], v152 offset:36960
	ds_read_b128 v[164:167], v152 offset:41568
	ds_read_b128 v[208:211], v151 offset:96
	ds_read_b128 v[212:215], v151 offset:4704
	s_setprio 1
	s_waitcnt lgkmcnt(1)
	v_mfma_f32_32x32x16_bf16 v[112:127], v[160:163], v[208:211], v[112:127]
	v_mfma_f32_32x32x16_bf16 v[48:63], v[164:167], v[208:211], v[48:63]
	s_waitcnt lgkmcnt(0)
	v_mfma_f32_32x32x16_bf16 v[96:111], v[160:163], v[212:215], v[96:111]
	v_mfma_f32_32x32x16_bf16 v[32:47], v[164:167], v[212:215], v[32:47]
	ds_read_b128 v[208:211], v151 offset:9312
	ds_read_b128 v[212:215], v151 offset:13920
	s_waitcnt lgkmcnt(1)
	v_mfma_f32_32x32x16_bf16 v[80:95], v[160:163], v[208:211], v[80:95]
	v_mfma_f32_32x32x16_bf16 v[16:31], v[164:167], v[208:211], v[16:31]
	s_waitcnt lgkmcnt(0)
	v_mfma_f32_32x32x16_bf16 v[64:79], v[160:163], v[212:215], v[64:79]
	v_mfma_f32_32x32x16_bf16 v[0:15], v[164:167], v[212:215], v[0:15]
	s_setprio 0
	s_barrier
; template <bool trans>
; DI void gemm_core(const GTile& tl, const GTile& nx, bool has_next  , bool chain  , bool pre, u32x4 (&ra)[4], u32x4 (&rb)[4], char* smem, f32x16 (&acc)[2][4]) {
;     ...
;   const int nk = K / 64;
;   if (!pre) { G_LOAD(0); G_STORE(0); G_LOAD(1); }
;   for (int kt = 0; kt < nk; ++kt) {
;     __syncthreads();
;     G_COMPUTE(kt & 1, kt);
;   }
	global_load_dwordx4 v[160:163], v[136:137], off offset:384
	global_load_dwordx4 v[164:167], v[138:139], off offset:384
	s_add_i32 s0, 16, 0x12000
	v_add3_u32 v149, s0, v149, v204
	s_add_i32 s0, 16, 0x1b000
	v_add3_u32 v150, s0, v150, v204
	s_waitcnt vmcnt(9)
	ds_write_b128 v148, v[184:187]
	s_waitcnt vmcnt(8)
	ds_write_b128 v148, v[188:191] offset:36864
	ds_read_b128 v[184:187], v150
	ds_read_b128 v[188:191], v150 offset:4608
	ds_read_b128 v[208:211], v149
	ds_read_b128 v[212:215], v149 offset:4608
	s_setprio 1
	s_waitcnt lgkmcnt(1)
	v_mfma_f32_32x32x16_bf16 v[112:127], v[184:187], v[208:211], v[112:127]
	v_mfma_f32_32x32x16_bf16 v[48:63], v[188:191], v[208:211], v[48:63]
	s_waitcnt lgkmcnt(0)
	v_mfma_f32_32x32x16_bf16 v[96:111], v[184:187], v[212:215], v[96:111]
	v_mfma_f32_32x32x16_bf16 v[32:47], v[188:191], v[212:215], v[32:47]
	ds_read_b128 v[208:211], v149 offset:9216
	ds_read_b128 v[212:215], v149 offset:13824
	s_waitcnt lgkmcnt(1)
	v_mfma_f32_32x32x16_bf16 v[80:95], v[184:187], v[208:211], v[80:95]
	v_mfma_f32_32x32x16_bf16 v[16:31], v[188:191], v[208:211], v[16:31]
	s_waitcnt lgkmcnt(0)
	v_mfma_f32_32x32x16_bf16 v[64:79], v[184:187], v[212:215], v[64:79]
	v_mfma_f32_32x32x16_bf16 v[0:15], v[188:191], v[212:215], v[0:15]
	s_setprio 0
	global_load_dwordx4 v[184:187], v[140:141], off offset:384
	global_load_dwordx4 v[188:191], v[142:143], off offset:384
	s_waitcnt vmcnt(9)
	ds_write_b128 v148, v[194:197] offset:9216
	s_waitcnt vmcnt(8)
	ds_write_b128 v148, v[198:201] offset:46080
	ds_read_b128 v[194:197], v150 offset:32
	ds_read_b128 v[198:201], v150 offset:4640
	ds_read_b128 v[208:211], v149 offset:32
	ds_read_b128 v[212:215], v149 offset:4640
	s_setprio 1
	s_waitcnt lgkmcnt(1)
	v_mfma_f32_32x32x16_bf16 v[112:127], v[194:197], v[208:211], v[112:127]
	v_mfma_f32_32x32x16_bf16 v[48:63], v[198:201], v[208:211], v[48:63]
	s_waitcnt lgkmcnt(0)
	v_mfma_f32_32x32x16_bf16 v[96:111], v[194:197], v[212:215], v[96:111]
	v_mfma_f32_32x32x16_bf16 v[32:47], v[198:201], v[212:215], v[32:47]
	ds_read_b128 v[208:211], v149 offset:9248
	ds_read_b128 v[212:215], v149 offset:13856
	s_waitcnt lgkmcnt(1)
	v_mfma_f32_32x32x16_bf16 v[80:95], v[194:197], v[208:211], v[80:95]
	v_mfma_f32_32x32x16_bf16 v[16:31], v[198:201], v[208:211], v[16:31]
	s_waitcnt lgkmcnt(0)
	v_mfma_f32_32x32x16_bf16 v[64:79], v[194:197], v[212:215], v[64:79]
	v_mfma_f32_32x32x16_bf16 v[0:15], v[198:201], v[212:215], v[0:15]
	s_setprio 0
	global_load_dwordx4 v[194:197], v[132:133], off offset:384
	global_load_dwordx4 v[198:201], v[134:135], off offset:384
	s_waitcnt vmcnt(9)
	ds_write_b128 v148, v[176:179] offset:18432
	s_waitcnt vmcnt(8)
	ds_write_b128 v148, v[180:183] offset:55296
	ds_read_b128 v[176:179], v150 offset:64
	ds_read_b128 v[180:183], v150 offset:4672
	ds_read_b128 v[208:211], v149 offset:64
	ds_read_b128 v[212:215], v149 offset:4672
	s_setprio 1
	s_waitcnt lgkmcnt(1)
	v_mfma_f32_32x32x16_bf16 v[112:127], v[176:179], v[208:211], v[112:127]
	v_mfma_f32_32x32x16_bf16 v[48:63], v[180:183], v[208:211], v[48:63]
	s_waitcnt lgkmcnt(0)
	v_mfma_f32_32x32x16_bf16 v[96:111], v[176:179], v[212:215], v[96:111]
	v_mfma_f32_32x32x16_bf16 v[32:47], v[180:183], v[212:215], v[32:47]
	ds_read_b128 v[208:211], v149 offset:9280
	ds_read_b128 v[212:215], v149 offset:13888
	s_waitcnt lgkmcnt(1)
	v_mfma_f32_32x32x16_bf16 v[80:95], v[176:179], v[208:211], v[80:95]
	v_mfma_f32_32x32x16_bf16 v[16:31], v[180:183], v[208:211], v[16:31]
	s_waitcnt lgkmcnt(0)
	v_mfma_f32_32x32x16_bf16 v[64:79], v[176:179], v[212:215], v[64:79]
	v_mfma_f32_32x32x16_bf16 v[0:15], v[180:183], v[212:215], v[0:15]
	s_setprio 0
	global_load_dwordx4 v[176:179], v[144:145], off offset:384
	global_load_dwordx4 v[180:183], v[146:147], off offset:384
	s_waitcnt vmcnt(9)
	ds_write_b128 v148, v[168:171] offset:27648
	s_waitcnt vmcnt(8)
	ds_write_b128 v148, v[172:175] offset:64512
	ds_read_b128 v[168:171], v150 offset:96
	ds_read_b128 v[172:175], v150 offset:4704
	ds_read_b128 v[208:211], v149 offset:96
	ds_read_b128 v[212:215], v149 offset:4704
	s_setprio 1
	s_waitcnt lgkmcnt(1)
	v_mfma_f32_32x32x16_bf16 v[112:127], v[168:171], v[208:211], v[112:127]
	v_mfma_f32_32x32x16_bf16 v[48:63], v[172:175], v[208:211], v[48:63]
	s_waitcnt lgkmcnt(0)
	v_mfma_f32_32x32x16_bf16 v[96:111], v[168:171], v[212:215], v[96:111]
	v_mfma_f32_32x32x16_bf16 v[32:47], v[172:175], v[212:215], v[32:47]
	ds_read_b128 v[208:211], v149 offset:9312
	ds_read_b128 v[212:215], v149 offset:13920
	s_waitcnt lgkmcnt(1)
	v_mfma_f32_32x32x16_bf16 v[80:95], v[168:171], v[208:211], v[80:95]
	v_mfma_f32_32x32x16_bf16 v[16:31], v[172:175], v[208:211], v[16:31]
	s_waitcnt lgkmcnt(0)
	v_mfma_f32_32x32x16_bf16 v[64:79], v[168:171], v[212:215], v[64:79]
	v_mfma_f32_32x32x16_bf16 v[0:15], v[172:175], v[212:215], v[0:15]
	s_setprio 0
	s_barrier
; template <bool trans>
; DI void gemm_core(const GTile& tl, const GTile& nx, bool has_next  , bool chain  , bool pre, u32x4 (&ra)[4], u32x4 (&rb)[4], char* smem, f32x16 (&acc)[2][4]) {
;     ...
;   const int nk = K / 64;
;   if (!pre) { G_LOAD(0); G_STORE(0); G_LOAD(1); }
;   for (int kt = 0; kt < nk; ++kt) {
;     __syncthreads();
;     G_COMPUTE(kt & 1, kt);
;   }
	global_load_dwordx4 v[168:171], v[136:137], off offset:512
	global_load_dwordx4 v[172:175], v[138:139], off offset:512
	s_waitcnt vmcnt(9)
	ds_write_b128 v192, v[160:163]
	s_waitcnt vmcnt(8)
	ds_write_b128 v159, v[164:167]
	ds_read_b128 v[160:163], v152 offset:36864
	ds_read_b128 v[164:167], v152 offset:41472
	ds_read_b128 v[208:211], v151
	ds_read_b128 v[212:215], v151 offset:4608
	s_setprio 1
	s_waitcnt lgkmcnt(1)
	v_mfma_f32_32x32x16_bf16 v[112:127], v[160:163], v[208:211], v[112:127]
	v_mfma_f32_32x32x16_bf16 v[48:63], v[164:167], v[208:211], v[48:63]
	s_waitcnt lgkmcnt(0)
	v_mfma_f32_32x32x16_bf16 v[96:111], v[160:163], v[212:215], v[96:111]
	v_mfma_f32_32x32x16_bf16 v[32:47], v[164:167], v[212:215], v[32:47]
	ds_read_b128 v[208:211], v151 offset:9216
	ds_read_b128 v[212:215], v151 offset:13824
	s_waitcnt vmcnt(7)
	ds_write_b128 v158, v[184:187]
	s_waitcnt vmcnt(6)
	ds_write_b128 v157, v[188:191]
	ds_read_b128 v[184:187], v152 offset:36896
	ds_read_b128 v[188:191], v152 offset:41504
	s_waitcnt lgkmcnt(5)
	v_mfma_f32_32x32x16_bf16 v[80:95], v[160:163], v[208:211], v[80:95]
	v_mfma_f32_32x32x16_bf16 v[16:31], v[164:167], v[208:211], v[16:31]
	ds_read_b128 v[208:211], v151 offset:32
	s_waitcnt lgkmcnt(5)
	v_mfma_f32_32x32x16_bf16 v[64:79], v[160:163], v[212:215], v[64:79]
	v_mfma_f32_32x32x16_bf16 v[0:15], v[164:167], v[212:215], v[0:15]
	ds_read_b128 v[212:215], v151 offset:4640
	global_load_dwordx4 v[160:163], v[140:141], off offset:512
	global_load_dwordx4 v[164:167], v[142:143], off offset:512
	s_waitcnt lgkmcnt(1)
	v_mfma_f32_32x32x16_bf16 v[112:127], v[184:187], v[208:211], v[112:127]
	v_mfma_f32_32x32x16_bf16 v[48:63], v[188:191], v[208:211], v[48:63]
	s_waitcnt lgkmcnt(0)
	v_mfma_f32_32x32x16_bf16 v[96:111], v[184:187], v[212:215], v[96:111]
	v_mfma_f32_32x32x16_bf16 v[32:47], v[188:191], v[212:215], v[32:47]
	ds_read_b128 v[208:211], v151 offset:9248
	ds_read_b128 v[212:215], v151 offset:13856
	s_waitcnt vmcnt(7)
	ds_write_b128 v154, v[194:197]
	s_waitcnt vmcnt(6)
	ds_write_b128 v153, v[198:201]
	ds_read_b128 v[194:197], v152 offset:36928
	ds_read_b128 v[198:201], v152 offset:41536
	s_waitcnt lgkmcnt(5)
	v_mfma_f32_32x32x16_bf16 v[80:95], v[184:187], v[208:211], v[80:95]
	v_mfma_f32_32x32x16_bf16 v[16:31], v[188:191], v[208:211], v[16:31]
	ds_read_b128 v[208:211], v151 offset:64
	s_waitcnt lgkmcnt(5)
	v_mfma_f32_32x32x16_bf16 v[64:79], v[184:187], v[212:215], v[64:79]
	v_mfma_f32_32x32x16_bf16 v[0:15], v[188:191], v[212:215], v[0:15]
	ds_read_b128 v[212:215], v151 offset:4672
	global_load_dwordx4 v[184:187], v[132:133], off offset:512
	global_load_dwordx4 v[188:191], v[134:135], off offset:512
	s_waitcnt lgkmcnt(1)
	v_mfma_f32_32x32x16_bf16 v[112:127], v[194:197], v[208:211], v[112:127]
	v_mfma_f32_32x32x16_bf16 v[48:63], v[198:201], v[208:211], v[48:63]
	s_waitcnt lgkmcnt(0)
	v_mfma_f32_32x32x16_bf16 v[96:111], v[194:197], v[212:215], v[96:111]
	v_mfma_f32_32x32x16_bf16 v[32:47], v[198:201], v[212:215], v[32:47]
	ds_read_b128 v[208:211], v151 offset:9280
	ds_read_b128 v[212:215], v151 offset:13888
	s_waitcnt vmcnt(7)
	ds_write_b128 v156, v[176:179]
	s_waitcnt vmcnt(6)
	ds_write_b128 v155, v[180:183]
	ds_read_b128 v[176:179], v152 offset:36960
	ds_read_b128 v[180:183], v152 offset:41568
	s_waitcnt lgkmcnt(5)
	v_mfma_f32_32x32x16_bf16 v[80:95], v[194:197], v[208:211], v[80:95]
	v_mfma_f32_32x32x16_bf16 v[16:31], v[198:201], v[208:211], v[16:31]
	ds_read_b128 v[208:211], v151 offset:96
	s_waitcnt lgkmcnt(5)
	v_mfma_f32_32x32x16_bf16 v[64:79], v[194:197], v[212:215], v[64:79]
	v_mfma_f32_32x32x16_bf16 v[0:15], v[198:201], v[212:215], v[0:15]
	ds_read_b128 v[212:215], v151 offset:4704
	global_load_dwordx4 v[194:197], v[144:145], off offset:512
	global_load_dwordx4 v[198:201], v[146:147], off offset:512
	s_waitcnt lgkmcnt(1)
	v_mfma_f32_32x32x16_bf16 v[112:127], v[176:179], v[208:211], v[112:127]
	v_mfma_f32_32x32x16_bf16 v[48:63], v[180:183], v[208:211], v[48:63]
	s_waitcnt lgkmcnt(0)
	v_mfma_f32_32x32x16_bf16 v[96:111], v[176:179], v[212:215], v[96:111]
	v_mfma_f32_32x32x16_bf16 v[32:47], v[180:183], v[212:215], v[32:47]
	ds_read_b128 v[208:211], v151 offset:9312
	ds_read_b128 v[212:215], v151 offset:13920
	s_waitcnt lgkmcnt(1)
	v_mfma_f32_32x32x16_bf16 v[80:95], v[176:179], v[208:211], v[80:95]
	v_mfma_f32_32x32x16_bf16 v[16:31], v[180:183], v[208:211], v[16:31]
	s_waitcnt lgkmcnt(0)
	v_mfma_f32_32x32x16_bf16 v[64:79], v[176:179], v[212:215], v[64:79]
	v_mfma_f32_32x32x16_bf16 v[0:15], v[180:183], v[212:215], v[0:15]
	s_setprio 0
	s_barrier
; template <bool trans>
; DI void gemm_core(const GTile& tl, const GTile& nx, bool has_next  , bool chain  , bool pre, u32x4 (&ra)[4], u32x4 (&rb)[4], char* smem, f32x16 (&acc)[2][4]) {
;     ...
;   const int nk = K / 64;
;   if (!pre) { G_LOAD(0); G_STORE(0); G_LOAD(1); }
;   for (int kt = 0; kt < nk; ++kt) {
;     __syncthreads();
;     G_COMPUTE(kt & 1, kt);
;   }
	global_load_dwordx4 v[176:179], v[136:137], off offset:640
	global_load_dwordx4 v[180:183], v[138:139], off offset:640
	s_waitcnt vmcnt(9)
	ds_write_b128 v148, v[168:171]
	s_waitcnt vmcnt(8)
	ds_write_b128 v148, v[172:175] offset:36864
	ds_read_b128 v[168:171], v150
	ds_read_b128 v[172:175], v150 offset:4608
	ds_read_b128 v[208:211], v149
	ds_read_b128 v[212:215], v149 offset:4608
	s_setprio 1
	s_waitcnt lgkmcnt(1)
	v_mfma_f32_32x32x16_bf16 v[112:127], v[168:171], v[208:211], v[112:127]
	v_mfma_f32_32x32x16_bf16 v[48:63], v[172:175], v[208:211], v[48:63]
	s_waitcnt lgkmcnt(0)
	v_mfma_f32_32x32x16_bf16 v[96:111], v[168:171], v[212:215], v[96:111]
	v_mfma_f32_32x32x16_bf16 v[32:47], v[172:175], v[212:215], v[32:47]
	ds_read_b128 v[208:211], v149 offset:9216
	ds_read_b128 v[212:215], v149 offset:13824
	s_waitcnt vmcnt(7)
	ds_write_b128 v148, v[160:163] offset:9216
	s_waitcnt vmcnt(6)
	ds_write_b128 v148, v[164:167] offset:46080
	ds_read_b128 v[160:163], v150 offset:32
	ds_read_b128 v[164:167], v150 offset:4640
	s_waitcnt lgkmcnt(5)
	v_mfma_f32_32x32x16_bf16 v[80:95], v[168:171], v[208:211], v[80:95]
	v_mfma_f32_32x32x16_bf16 v[16:31], v[172:175], v[208:211], v[16:31]
	ds_read_b128 v[208:211], v149 offset:32
	s_waitcnt lgkmcnt(5)
	v_mfma_f32_32x32x16_bf16 v[64:79], v[168:171], v[212:215], v[64:79]
	v_mfma_f32_32x32x16_bf16 v[0:15], v[172:175], v[212:215], v[0:15]
	ds_read_b128 v[212:215], v149 offset:4640
	global_load_dwordx4 v[168:171], v[140:141], off offset:640
	global_load_dwordx4 v[172:175], v[142:143], off offset:640
	s_waitcnt lgkmcnt(1)
	v_mfma_f32_32x32x16_bf16 v[112:127], v[160:163], v[208:211], v[112:127]
	v_mfma_f32_32x32x16_bf16 v[48:63], v[164:167], v[208:211], v[48:63]
	s_waitcnt lgkmcnt(0)
	v_mfma_f32_32x32x16_bf16 v[96:111], v[160:163], v[212:215], v[96:111]
	v_mfma_f32_32x32x16_bf16 v[32:47], v[164:167], v[212:215], v[32:47]
	ds_read_b128 v[208:211], v149 offset:9248
	ds_read_b128 v[212:215], v149 offset:13856
	s_waitcnt vmcnt(7)
	ds_write_b128 v148, v[184:187] offset:18432
	s_waitcnt vmcnt(6)
	ds_write_b128 v148, v[188:191] offset:55296
	ds_read_b128 v[184:187], v150 offset:64
	ds_read_b128 v[188:191], v150 offset:4672
	s_waitcnt lgkmcnt(5)
	v_mfma_f32_32x32x16_bf16 v[80:95], v[160:163], v[208:211], v[80:95]
	v_mfma_f32_32x32x16_bf16 v[16:31], v[164:167], v[208:211], v[16:31]
	ds_read_b128 v[208:211], v149 offset:64
	s_waitcnt lgkmcnt(5)
	v_mfma_f32_32x32x16_bf16 v[64:79], v[160:163], v[212:215], v[64:79]
	v_mfma_f32_32x32x16_bf16 v[0:15], v[164:167], v[212:215], v[0:15]
	ds_read_b128 v[212:215], v149 offset:4672
	global_load_dwordx4 v[160:163], v[132:133], off offset:640
	global_load_dwordx4 v[164:167], v[134:135], off offset:640
	s_waitcnt lgkmcnt(1)
	v_mfma_f32_32x32x16_bf16 v[112:127], v[184:187], v[208:211], v[112:127]
	v_mfma_f32_32x32x16_bf16 v[48:63], v[188:191], v[208:211], v[48:63]
	s_waitcnt lgkmcnt(0)
	v_mfma_f32_32x32x16_bf16 v[96:111], v[184:187], v[212:215], v[96:111]
	v_mfma_f32_32x32x16_bf16 v[32:47], v[188:191], v[212:215], v[32:47]
	ds_read_b128 v[208:211], v149 offset:9280
	ds_read_b128 v[212:215], v149 offset:13888
	s_waitcnt vmcnt(7)
	ds_write_b128 v148, v[194:197] offset:27648
	s_waitcnt vmcnt(6)
	ds_write_b128 v148, v[198:201] offset:64512
	ds_read_b128 v[194:197], v150 offset:96
	ds_read_b128 v[198:201], v150 offset:4704
	s_waitcnt lgkmcnt(5)
	v_mfma_f32_32x32x16_bf16 v[80:95], v[184:187], v[208:211], v[80:95]
	v_mfma_f32_32x32x16_bf16 v[16:31], v[188:191], v[208:211], v[16:31]
	ds_read_b128 v[208:211], v149 offset:96
	s_waitcnt lgkmcnt(5)
	v_mfma_f32_32x32x16_bf16 v[64:79], v[184:187], v[212:215], v[64:79]
	v_mfma_f32_32x32x16_bf16 v[0:15], v[188:191], v[212:215], v[0:15]
	ds_read_b128 v[212:215], v149 offset:4704
	global_load_dwordx4 v[184:187], v[144:145], off offset:640
	global_load_dwordx4 v[188:191], v[146:147], off offset:640
	s_waitcnt lgkmcnt(1)
	v_mfma_f32_32x32x16_bf16 v[112:127], v[194:197], v[208:211], v[112:127]
	v_mfma_f32_32x32x16_bf16 v[48:63], v[198:201], v[208:211], v[48:63]
	s_waitcnt lgkmcnt(0)
	v_mfma_f32_32x32x16_bf16 v[96:111], v[194:197], v[212:215], v[96:111]
	v_mfma_f32_32x32x16_bf16 v[32:47], v[198:201], v[212:215], v[32:47]
	ds_read_b128 v[208:211], v149 offset:9312
	ds_read_b128 v[212:215], v149 offset:13920
	s_waitcnt lgkmcnt(1)
	v_mfma_f32_32x32x16_bf16 v[80:95], v[194:197], v[208:211], v[80:95]
	v_mfma_f32_32x32x16_bf16 v[16:31], v[198:201], v[208:211], v[16:31]
	s_waitcnt lgkmcnt(0)
	v_mfma_f32_32x32x16_bf16 v[64:79], v[194:197], v[212:215], v[64:79]
	v_mfma_f32_32x32x16_bf16 v[0:15], v[198:201], v[212:215], v[0:15]
	s_setprio 0
	s_barrier
; template <bool trans>
; DI void gemm_core(const GTile& tl, const GTile& nx, bool has_next  , bool chain  , bool pre, u32x4 (&ra)[4], u32x4 (&rb)[4], char* smem, f32x16 (&acc)[2][4]) {
;     ...
;   const int nk = K / 64;
;   if (!pre) { G_LOAD(0); G_STORE(0); G_LOAD(1); }
;   for (int kt = 0; kt < nk; ++kt) {
;     __syncthreads();
;     G_COMPUTE(kt & 1, kt);
;   }
	global_load_dwordx4 v[194:197], v[136:137], off offset:768
	global_load_dwordx4 v[198:201], v[138:139], off offset:768
	s_waitcnt vmcnt(9)
	ds_write_b128 v192, v[176:179]
	s_waitcnt vmcnt(8)
	ds_write_b128 v159, v[180:183]
	ds_read_b128 v[176:179], v152 offset:36864
	ds_read_b128 v[180:183], v152 offset:41472
	ds_read_b128 v[208:211], v151
	ds_read_b128 v[212:215], v151 offset:4608
	s_setprio 1
	s_waitcnt lgkmcnt(1)
	v_mfma_f32_32x32x16_bf16 v[112:127], v[176:179], v[208:211], v[112:127]
	v_mfma_f32_32x32x16_bf16 v[48:63], v[180:183], v[208:211], v[48:63]
	s_waitcnt lgkmcnt(0)
	v_mfma_f32_32x32x16_bf16 v[96:111], v[176:179], v[212:215], v[96:111]
	v_mfma_f32_32x32x16_bf16 v[32:47], v[180:183], v[212:215], v[32:47]
	ds_read_b128 v[208:211], v151 offset:9216
	ds_read_b128 v[212:215], v151 offset:13824
	s_waitcnt vmcnt(7)
	ds_write_b128 v158, v[168:171]
	s_waitcnt vmcnt(6)
	ds_write_b128 v157, v[172:175]
	ds_read_b128 v[168:171], v152 offset:36896
	ds_read_b128 v[172:175], v152 offset:41504
	s_waitcnt lgkmcnt(5)
	v_mfma_f32_32x32x16_bf16 v[80:95], v[176:179], v[208:211], v[80:95]
	v_mfma_f32_32x32x16_bf16 v[16:31], v[180:183], v[208:211], v[16:31]
	ds_read_b128 v[208:211], v151 offset:32
	s_waitcnt lgkmcnt(5)
	v_mfma_f32_32x32x16_bf16 v[64:79], v[176:179], v[212:215], v[64:79]
	v_mfma_f32_32x32x16_bf16 v[0:15], v[180:183], v[212:215], v[0:15]
	ds_read_b128 v[212:215], v151 offset:4640
	global_load_dwordx4 v[176:179], v[140:141], off offset:768
	global_load_dwordx4 v[180:183], v[142:143], off offset:768
	s_waitcnt lgkmcnt(1)
	v_mfma_f32_32x32x16_bf16 v[112:127], v[168:171], v[208:211], v[112:127]
	v_mfma_f32_32x32x16_bf16 v[48:63], v[172:175], v[208:211], v[48:63]
	s_waitcnt lgkmcnt(0)
	v_mfma_f32_32x32x16_bf16 v[96:111], v[168:171], v[212:215], v[96:111]
	v_mfma_f32_32x32x16_bf16 v[32:47], v[172:175], v[212:215], v[32:47]
	ds_read_b128 v[208:211], v151 offset:9248
	ds_read_b128 v[212:215], v151 offset:13856
	s_waitcnt vmcnt(7)
	ds_write_b128 v154, v[160:163]
	s_waitcnt vmcnt(6)
	ds_write_b128 v153, v[164:167]
	ds_read_b128 v[160:163], v152 offset:36928
	ds_read_b128 v[164:167], v152 offset:41536
	s_waitcnt lgkmcnt(5)
	v_mfma_f32_32x32x16_bf16 v[80:95], v[168:171], v[208:211], v[80:95]
	v_mfma_f32_32x32x16_bf16 v[16:31], v[172:175], v[208:211], v[16:31]
	ds_read_b128 v[208:211], v151 offset:64
	s_waitcnt lgkmcnt(5)
	v_mfma_f32_32x32x16_bf16 v[64:79], v[168:171], v[212:215], v[64:79]
	v_mfma_f32_32x32x16_bf16 v[0:15], v[172:175], v[212:215], v[0:15]
	ds_read_b128 v[212:215], v151 offset:4672
	global_load_dwordx4 v[168:171], v[132:133], off offset:768
	global_load_dwordx4 v[172:175], v[134:135], off offset:768
	s_waitcnt lgkmcnt(1)
	v_mfma_f32_32x32x16_bf16 v[112:127], v[160:163], v[208:211], v[112:127]
	v_mfma_f32_32x32x16_bf16 v[48:63], v[164:167], v[208:211], v[48:63]
	s_waitcnt lgkmcnt(0)
	v_mfma_f32_32x32x16_bf16 v[96:111], v[160:163], v[212:215], v[96:111]
	v_mfma_f32_32x32x16_bf16 v[32:47], v[164:167], v[212:215], v[32:47]
	ds_read_b128 v[208:211], v151 offset:9280
	ds_read_b128 v[212:215], v151 offset:13888
	s_waitcnt vmcnt(7)
	ds_write_b128 v156, v[184:187]
	s_waitcnt vmcnt(6)
	ds_write_b128 v155, v[188:191]
	ds_read_b128 v[184:187], v152 offset:36960
	ds_read_b128 v[188:191], v152 offset:41568
	s_waitcnt lgkmcnt(5)
	v_mfma_f32_32x32x16_bf16 v[80:95], v[160:163], v[208:211], v[80:95]
	v_mfma_f32_32x32x16_bf16 v[16:31], v[164:167], v[208:211], v[16:31]
	ds_read_b128 v[208:211], v151 offset:96
	s_waitcnt lgkmcnt(5)
	v_mfma_f32_32x32x16_bf16 v[64:79], v[160:163], v[212:215], v[64:79]
	v_mfma_f32_32x32x16_bf16 v[0:15], v[164:167], v[212:215], v[0:15]
	ds_read_b128 v[212:215], v151 offset:4704
	global_load_dwordx4 v[160:163], v[144:145], off offset:768
	global_load_dwordx4 v[164:167], v[146:147], off offset:768
	s_waitcnt lgkmcnt(1)
	v_mfma_f32_32x32x16_bf16 v[112:127], v[184:187], v[208:211], v[112:127]
	v_mfma_f32_32x32x16_bf16 v[48:63], v[188:191], v[208:211], v[48:63]
	s_waitcnt lgkmcnt(0)
	v_mfma_f32_32x32x16_bf16 v[96:111], v[184:187], v[212:215], v[96:111]
	v_mfma_f32_32x32x16_bf16 v[32:47], v[188:191], v[212:215], v[32:47]
	ds_read_b128 v[208:211], v151 offset:9312
	ds_read_b128 v[212:215], v151 offset:13920
	s_waitcnt lgkmcnt(1)
	v_mfma_f32_32x32x16_bf16 v[80:95], v[184:187], v[208:211], v[80:95]
	v_mfma_f32_32x32x16_bf16 v[16:31], v[188:191], v[208:211], v[16:31]
	s_waitcnt lgkmcnt(0)
	v_mfma_f32_32x32x16_bf16 v[64:79], v[184:187], v[212:215], v[64:79]
	v_mfma_f32_32x32x16_bf16 v[0:15], v[188:191], v[212:215], v[0:15]
	s_setprio 0
	s_barrier
; template <bool trans>
; DI void gemm_core(const GTile& tl, const GTile& nx, bool has_next  , bool chain  , bool pre, u32x4 (&ra)[4], u32x4 (&rb)[4], char* smem, f32x16 (&acc)[2][4]) {
;     ...
;   const int nk = K / 64;
;   if (!pre) { G_LOAD(0); G_STORE(0); G_LOAD(1); }
;   for (int kt = 0; kt < nk; ++kt) {
;     __syncthreads();
;     G_COMPUTE(kt & 1, kt);
;   }
	global_load_dwordx4 v[184:187], v[136:137], off offset:896
	global_load_dwordx4 v[188:191], v[138:139], off offset:896
	s_waitcnt vmcnt(9)
	ds_write_b128 v148, v[194:197]
	s_waitcnt vmcnt(8)
	ds_write_b128 v148, v[198:201] offset:36864
	ds_read_b128 v[194:197], v150
	ds_read_b128 v[198:201], v150 offset:4608
	ds_read_b128 v[208:211], v149
	ds_read_b128 v[212:215], v149 offset:4608
	s_setprio 1
	s_waitcnt lgkmcnt(1)
	v_mfma_f32_32x32x16_bf16 v[112:127], v[194:197], v[208:211], v[112:127]
	v_mfma_f32_32x32x16_bf16 v[48:63], v[198:201], v[208:211], v[48:63]
	s_waitcnt lgkmcnt(0)
	v_mfma_f32_32x32x16_bf16 v[96:111], v[194:197], v[212:215], v[96:111]
	v_mfma_f32_32x32x16_bf16 v[32:47], v[198:201], v[212:215], v[32:47]
	ds_read_b128 v[208:211], v149 offset:9216
	ds_read_b128 v[212:215], v149 offset:13824
	s_waitcnt vmcnt(7)
	ds_write_b128 v148, v[176:179] offset:9216
	s_waitcnt vmcnt(6)
	ds_write_b128 v148, v[180:183] offset:46080
	ds_read_b128 v[176:179], v150 offset:32
	ds_read_b128 v[180:183], v150 offset:4640
	s_waitcnt lgkmcnt(5)
	v_mfma_f32_32x32x16_bf16 v[80:95], v[194:197], v[208:211], v[80:95]
	v_mfma_f32_32x32x16_bf16 v[16:31], v[198:201], v[208:211], v[16:31]
	ds_read_b128 v[208:211], v149 offset:32
	s_waitcnt lgkmcnt(5)
	v_mfma_f32_32x32x16_bf16 v[64:79], v[194:197], v[212:215], v[64:79]
	v_mfma_f32_32x32x16_bf16 v[0:15], v[198:201], v[212:215], v[0:15]
	ds_read_b128 v[212:215], v149 offset:4640
	global_load_dwordx4 v[194:197], v[140:141], off offset:896
	global_load_dwordx4 v[198:201], v[142:143], off offset:896
	s_waitcnt lgkmcnt(1)
	v_mfma_f32_32x32x16_bf16 v[112:127], v[176:179], v[208:211], v[112:127]
	v_mfma_f32_32x32x16_bf16 v[48:63], v[180:183], v[208:211], v[48:63]
	s_waitcnt lgkmcnt(0)
	v_mfma_f32_32x32x16_bf16 v[96:111], v[176:179], v[212:215], v[96:111]
	v_mfma_f32_32x32x16_bf16 v[32:47], v[180:183], v[212:215], v[32:47]
	ds_read_b128 v[208:211], v149 offset:9248
	ds_read_b128 v[212:215], v149 offset:13856
	s_waitcnt vmcnt(7)
	ds_write_b128 v148, v[168:171] offset:18432
	s_waitcnt vmcnt(6)
	ds_write_b128 v148, v[172:175] offset:55296
	ds_read_b128 v[168:171], v150 offset:64
	ds_read_b128 v[172:175], v150 offset:4672
	s_waitcnt lgkmcnt(5)
	v_mfma_f32_32x32x16_bf16 v[80:95], v[176:179], v[208:211], v[80:95]
	v_mfma_f32_32x32x16_bf16 v[16:31], v[180:183], v[208:211], v[16:31]
	ds_read_b128 v[208:211], v149 offset:64
	s_waitcnt lgkmcnt(5)
	v_mfma_f32_32x32x16_bf16 v[64:79], v[176:179], v[212:215], v[64:79]
	v_mfma_f32_32x32x16_bf16 v[0:15], v[180:183], v[212:215], v[0:15]
	ds_read_b128 v[212:215], v149 offset:4672
	global_load_dwordx4 v[176:179], v[132:133], off offset:896
	global_load_dwordx4 v[180:183], v[134:135], off offset:896
	s_waitcnt lgkmcnt(1)
	v_mfma_f32_32x32x16_bf16 v[112:127], v[168:171], v[208:211], v[112:127]
	v_mfma_f32_32x32x16_bf16 v[48:63], v[172:175], v[208:211], v[48:63]
	s_waitcnt lgkmcnt(0)
	v_mfma_f32_32x32x16_bf16 v[96:111], v[168:171], v[212:215], v[96:111]
	v_mfma_f32_32x32x16_bf16 v[32:47], v[172:175], v[212:215], v[32:47]
	ds_read_b128 v[208:211], v149 offset:9280
	ds_read_b128 v[212:215], v149 offset:13888
	s_waitcnt vmcnt(7)
	ds_write_b128 v148, v[160:163] offset:27648
	s_waitcnt vmcnt(6)
	ds_write_b128 v148, v[164:167] offset:64512
	ds_read_b128 v[160:163], v150 offset:96
	ds_read_b128 v[164:167], v150 offset:4704
	s_waitcnt lgkmcnt(5)
	v_mfma_f32_32x32x16_bf16 v[80:95], v[168:171], v[208:211], v[80:95]
	v_mfma_f32_32x32x16_bf16 v[16:31], v[172:175], v[208:211], v[16:31]
	ds_read_b128 v[208:211], v149 offset:96
	s_waitcnt lgkmcnt(5)
	v_mfma_f32_32x32x16_bf16 v[64:79], v[168:171], v[212:215], v[64:79]
	v_mfma_f32_32x32x16_bf16 v[0:15], v[172:175], v[212:215], v[0:15]
	ds_read_b128 v[212:215], v149 offset:4704
	global_load_dwordx4 v[168:171], v[144:145], off offset:896
	global_load_dwordx4 v[172:175], v[146:147], off offset:896
	s_waitcnt lgkmcnt(1)
	v_mfma_f32_32x32x16_bf16 v[112:127], v[160:163], v[208:211], v[112:127]
	v_mfma_f32_32x32x16_bf16 v[48:63], v[164:167], v[208:211], v[48:63]
	s_waitcnt lgkmcnt(0)
	v_mfma_f32_32x32x16_bf16 v[96:111], v[160:163], v[212:215], v[96:111]
	v_mfma_f32_32x32x16_bf16 v[32:47], v[164:167], v[212:215], v[32:47]
	ds_read_b128 v[208:211], v149 offset:9312
	ds_read_b128 v[212:215], v149 offset:13920
	s_waitcnt lgkmcnt(1)
	v_mfma_f32_32x32x16_bf16 v[80:95], v[160:163], v[208:211], v[80:95]
	v_mfma_f32_32x32x16_bf16 v[16:31], v[164:167], v[208:211], v[16:31]
	s_waitcnt lgkmcnt(0)
	v_mfma_f32_32x32x16_bf16 v[64:79], v[160:163], v[212:215], v[64:79]
	v_mfma_f32_32x32x16_bf16 v[0:15], v[164:167], v[212:215], v[0:15]
	s_setprio 0
	s_barrier
; template <bool trans>
; DI void gemm_core(const GTile& tl, const GTile& nx, bool has_next  , bool chain  , bool pre, u32x4 (&ra)[4], u32x4 (&rb)[4], char* smem, f32x16 (&acc)[2][4]) {
;     ...
;   const int nk = K / 64;
;   if (!pre) { G_LOAD(0); G_STORE(0); G_LOAD(1); }
;   for (int kt = 0; kt < nk; ++kt) {
;     __syncthreads();
;     G_COMPUTE(kt & 1, kt);
;   }
	global_load_dwordx4 v[160:163], v[136:137], off offset:1024
	global_load_dwordx4 v[164:167], v[138:139], off offset:1024
	s_waitcnt vmcnt(9)
	ds_write_b128 v192, v[184:187]
	s_waitcnt vmcnt(8)
	ds_write_b128 v159, v[188:191]
	ds_read_b128 v[184:187], v152 offset:36864
	ds_read_b128 v[188:191], v152 offset:41472
	ds_read_b128 v[208:211], v151
	ds_read_b128 v[212:215], v151 offset:4608
	s_setprio 1
	s_waitcnt lgkmcnt(1)
	v_mfma_f32_32x32x16_bf16 v[112:127], v[184:187], v[208:211], v[112:127]
	v_mfma_f32_32x32x16_bf16 v[48:63], v[188:191], v[208:211], v[48:63]
	s_waitcnt lgkmcnt(0)
	v_mfma_f32_32x32x16_bf16 v[96:111], v[184:187], v[212:215], v[96:111]
	v_mfma_f32_32x32x16_bf16 v[32:47], v[188:191], v[212:215], v[32:47]
	ds_read_b128 v[208:211], v151 offset:9216
	ds_read_b128 v[212:215], v151 offset:13824
	s_waitcnt vmcnt(7)
	ds_write_b128 v158, v[194:197]
	s_waitcnt vmcnt(6)
	ds_write_b128 v157, v[198:201]
	ds_read_b128 v[194:197], v152 offset:36896
	ds_read_b128 v[198:201], v152 offset:41504
	s_waitcnt lgkmcnt(5)
	v_mfma_f32_32x32x16_bf16 v[80:95], v[184:187], v[208:211], v[80:95]
	v_mfma_f32_32x32x16_bf16 v[16:31], v[188:191], v[208:211], v[16:31]
	ds_read_b128 v[208:211], v151 offset:32
	s_waitcnt lgkmcnt(5)
	v_mfma_f32_32x32x16_bf16 v[64:79], v[184:187], v[212:215], v[64:79]
	v_mfma_f32_32x32x16_bf16 v[0:15], v[188:191], v[212:215], v[0:15]
	ds_read_b128 v[212:215], v151 offset:4640
	global_load_dwordx4 v[184:187], v[140:141], off offset:1024
	global_load_dwordx4 v[188:191], v[142:143], off offset:1024
	s_waitcnt lgkmcnt(1)
	v_mfma_f32_32x32x16_bf16 v[112:127], v[194:197], v[208:211], v[112:127]
	v_mfma_f32_32x32x16_bf16 v[48:63], v[198:201], v[208:211], v[48:63]
	s_waitcnt lgkmcnt(0)
	v_mfma_f32_32x32x16_bf16 v[96:111], v[194:197], v[212:215], v[96:111]
	v_mfma_f32_32x32x16_bf16 v[32:47], v[198:201], v[212:215], v[32:47]
	ds_read_b128 v[208:211], v151 offset:9248
	ds_read_b128 v[212:215], v151 offset:13856
	s_waitcnt vmcnt(7)
	ds_write_b128 v154, v[176:179]
	s_waitcnt vmcnt(6)
	ds_write_b128 v153, v[180:183]
	ds_read_b128 v[176:179], v152 offset:36928
	ds_read_b128 v[180:183], v152 offset:41536
	s_waitcnt lgkmcnt(5)
	v_mfma_f32_32x32x16_bf16 v[80:95], v[194:197], v[208:211], v[80:95]
	v_mfma_f32_32x32x16_bf16 v[16:31], v[198:201], v[208:211], v[16:31]
	ds_read_b128 v[208:211], v151 offset:64
	s_waitcnt lgkmcnt(5)
	v_mfma_f32_32x32x16_bf16 v[64:79], v[194:197], v[212:215], v[64:79]
	v_mfma_f32_32x32x16_bf16 v[0:15], v[198:201], v[212:215], v[0:15]
	ds_read_b128 v[212:215], v151 offset:4672
	global_load_dwordx4 v[194:197], v[132:133], off offset:1024
	global_load_dwordx4 v[198:201], v[134:135], off offset:1024
	s_waitcnt lgkmcnt(1)
	v_mfma_f32_32x32x16_bf16 v[112:127], v[176:179], v[208:211], v[112:127]
	v_mfma_f32_32x32x16_bf16 v[48:63], v[180:183], v[208:211], v[48:63]
	s_waitcnt lgkmcnt(0)
	v_mfma_f32_32x32x16_bf16 v[96:111], v[176:179], v[212:215], v[96:111]
	v_mfma_f32_32x32x16_bf16 v[32:47], v[180:183], v[212:215], v[32:47]
	ds_read_b128 v[208:211], v151 offset:9280
	ds_read_b128 v[212:215], v151 offset:13888
	s_waitcnt vmcnt(7)
	ds_write_b128 v156, v[168:171]
	s_waitcnt vmcnt(6)
	ds_write_b128 v155, v[172:175]
	ds_read_b128 v[168:171], v152 offset:36960
	ds_read_b128 v[172:175], v152 offset:41568
	s_waitcnt lgkmcnt(5)
	v_mfma_f32_32x32x16_bf16 v[80:95], v[176:179], v[208:211], v[80:95]
	v_mfma_f32_32x32x16_bf16 v[16:31], v[180:183], v[208:211], v[16:31]
	ds_read_b128 v[208:211], v151 offset:96
	s_waitcnt lgkmcnt(5)
	v_mfma_f32_32x32x16_bf16 v[64:79], v[176:179], v[212:215], v[64:79]
	v_mfma_f32_32x32x16_bf16 v[0:15], v[180:183], v[212:215], v[0:15]
	ds_read_b128 v[212:215], v151 offset:4704
	global_load_dwordx4 v[176:179], v[144:145], off offset:1024
	global_load_dwordx4 v[180:183], v[146:147], off offset:1024
	s_waitcnt lgkmcnt(1)
	v_mfma_f32_32x32x16_bf16 v[112:127], v[168:171], v[208:211], v[112:127]
	v_mfma_f32_32x32x16_bf16 v[48:63], v[172:175], v[208:211], v[48:63]
	s_waitcnt lgkmcnt(0)
	v_mfma_f32_32x32x16_bf16 v[96:111], v[168:171], v[212:215], v[96:111]
	v_mfma_f32_32x32x16_bf16 v[32:47], v[172:175], v[212:215], v[32:47]
	ds_read_b128 v[208:211], v151 offset:9312
	ds_read_b128 v[212:215], v151 offset:13920
	s_waitcnt lgkmcnt(1)
	v_mfma_f32_32x32x16_bf16 v[80:95], v[168:171], v[208:211], v[80:95]
	v_mfma_f32_32x32x16_bf16 v[16:31], v[172:175], v[208:211], v[16:31]
	s_waitcnt lgkmcnt(0)
	v_mfma_f32_32x32x16_bf16 v[64:79], v[168:171], v[212:215], v[64:79]
	v_mfma_f32_32x32x16_bf16 v[0:15], v[172:175], v[212:215], v[0:15]
	s_setprio 0
	s_barrier
; template <bool trans>
; DI void gemm_core(const GTile& tl, const GTile& nx, bool has_next  , bool chain  , bool pre, u32x4 (&ra)[4], u32x4 (&rb)[4], char* smem, f32x16 (&acc)[2][4]) {
;     ...
;   const int nk = K / 64;
;   if (!pre) { G_LOAD(0); G_STORE(0); G_LOAD(1); }
;   for (int kt = 0; kt < nk; ++kt) {
;     __syncthreads();
;     G_COMPUTE(kt & 1, kt);
;   }
	global_load_dwordx4 v[168:171], v[136:137], off offset:1152
	global_load_dwordx4 v[172:175], v[138:139], off offset:1152
	s_waitcnt vmcnt(9)
	ds_write_b128 v148, v[160:163]
	s_waitcnt vmcnt(8)
	ds_write_b128 v148, v[164:167] offset:36864
	ds_read_b128 v[160:163], v150
	ds_read_b128 v[164:167], v150 offset:4608
	ds_read_b128 v[208:211], v149
	ds_read_b128 v[212:215], v149 offset:4608
	s_setprio 1
	s_waitcnt lgkmcnt(1)
	v_mfma_f32_32x32x16_bf16 v[112:127], v[160:163], v[208:211], v[112:127]
	v_mfma_f32_32x32x16_bf16 v[48:63], v[164:167], v[208:211], v[48:63]
	s_waitcnt lgkmcnt(0)
	v_mfma_f32_32x32x16_bf16 v[96:111], v[160:163], v[212:215], v[96:111]
	v_mfma_f32_32x32x16_bf16 v[32:47], v[164:167], v[212:215], v[32:47]
	ds_read_b128 v[208:211], v149 offset:9216
	ds_read_b128 v[212:215], v149 offset:13824
	s_waitcnt vmcnt(7)
	ds_write_b128 v148, v[184:187] offset:9216
	s_waitcnt vmcnt(6)
	ds_write_b128 v148, v[188:191] offset:46080
	ds_read_b128 v[184:187], v150 offset:32
	ds_read_b128 v[188:191], v150 offset:4640
	s_waitcnt lgkmcnt(5)
	v_mfma_f32_32x32x16_bf16 v[80:95], v[160:163], v[208:211], v[80:95]
	v_mfma_f32_32x32x16_bf16 v[16:31], v[164:167], v[208:211], v[16:31]
	ds_read_b128 v[208:211], v149 offset:32
	s_waitcnt lgkmcnt(5)
	v_mfma_f32_32x32x16_bf16 v[64:79], v[160:163], v[212:215], v[64:79]
	v_mfma_f32_32x32x16_bf16 v[0:15], v[164:167], v[212:215], v[0:15]
	ds_read_b128 v[212:215], v149 offset:4640
	global_load_dwordx4 v[160:163], v[140:141], off offset:1152
	global_load_dwordx4 v[164:167], v[142:143], off offset:1152
	s_waitcnt lgkmcnt(1)
	v_mfma_f32_32x32x16_bf16 v[112:127], v[184:187], v[208:211], v[112:127]
	v_mfma_f32_32x32x16_bf16 v[48:63], v[188:191], v[208:211], v[48:63]
	s_waitcnt lgkmcnt(0)
	v_mfma_f32_32x32x16_bf16 v[96:111], v[184:187], v[212:215], v[96:111]
	v_mfma_f32_32x32x16_bf16 v[32:47], v[188:191], v[212:215], v[32:47]
	ds_read_b128 v[208:211], v149 offset:9248
	ds_read_b128 v[212:215], v149 offset:13856
	s_waitcnt vmcnt(7)
	ds_write_b128 v148, v[194:197] offset:18432
	s_waitcnt vmcnt(6)
	ds_write_b128 v148, v[198:201] offset:55296
	ds_read_b128 v[194:197], v150 offset:64
	ds_read_b128 v[198:201], v150 offset:4672
	s_waitcnt lgkmcnt(5)
	v_mfma_f32_32x32x16_bf16 v[80:95], v[184:187], v[208:211], v[80:95]
	v_mfma_f32_32x32x16_bf16 v[16:31], v[188:191], v[208:211], v[16:31]
	ds_read_b128 v[208:211], v149 offset:64
	s_waitcnt lgkmcnt(5)
	v_mfma_f32_32x32x16_bf16 v[64:79], v[184:187], v[212:215], v[64:79]
	v_mfma_f32_32x32x16_bf16 v[0:15], v[188:191], v[212:215], v[0:15]
	ds_read_b128 v[212:215], v149 offset:4672
	global_load_dwordx4 v[184:187], v[132:133], off offset:1152
	global_load_dwordx4 v[188:191], v[134:135], off offset:1152
	s_waitcnt lgkmcnt(1)
	v_mfma_f32_32x32x16_bf16 v[112:127], v[194:197], v[208:211], v[112:127]
	v_mfma_f32_32x32x16_bf16 v[48:63], v[198:201], v[208:211], v[48:63]
	s_waitcnt lgkmcnt(0)
	v_mfma_f32_32x32x16_bf16 v[96:111], v[194:197], v[212:215], v[96:111]
	v_mfma_f32_32x32x16_bf16 v[32:47], v[198:201], v[212:215], v[32:47]
	ds_read_b128 v[208:211], v149 offset:9280
	ds_read_b128 v[212:215], v149 offset:13888
	s_waitcnt vmcnt(7)
	ds_write_b128 v148, v[176:179] offset:27648
	s_waitcnt vmcnt(6)
	ds_write_b128 v148, v[180:183] offset:64512
	ds_read_b128 v[176:179], v150 offset:96
	ds_read_b128 v[180:183], v150 offset:4704
	s_waitcnt lgkmcnt(5)
	v_mfma_f32_32x32x16_bf16 v[80:95], v[194:197], v[208:211], v[80:95]
	v_mfma_f32_32x32x16_bf16 v[16:31], v[198:201], v[208:211], v[16:31]
	ds_read_b128 v[208:211], v149 offset:96
	s_waitcnt lgkmcnt(5)
	v_mfma_f32_32x32x16_bf16 v[64:79], v[194:197], v[212:215], v[64:79]
	v_mfma_f32_32x32x16_bf16 v[0:15], v[198:201], v[212:215], v[0:15]
	ds_read_b128 v[212:215], v149 offset:4704
	global_load_dwordx4 v[194:197], v[144:145], off offset:1152
	global_load_dwordx4 v[198:201], v[146:147], off offset:1152
	s_waitcnt lgkmcnt(1)
	v_mfma_f32_32x32x16_bf16 v[112:127], v[176:179], v[208:211], v[112:127]
	v_mfma_f32_32x32x16_bf16 v[48:63], v[180:183], v[208:211], v[48:63]
	s_waitcnt lgkmcnt(0)
	v_mfma_f32_32x32x16_bf16 v[96:111], v[176:179], v[212:215], v[96:111]
	v_mfma_f32_32x32x16_bf16 v[32:47], v[180:183], v[212:215], v[32:47]
	ds_read_b128 v[208:211], v149 offset:9312
	ds_read_b128 v[212:215], v149 offset:13920
	s_waitcnt lgkmcnt(1)
	v_mfma_f32_32x32x16_bf16 v[80:95], v[176:179], v[208:211], v[80:95]
	v_mfma_f32_32x32x16_bf16 v[16:31], v[180:183], v[208:211], v[16:31]
	s_waitcnt lgkmcnt(0)
	v_mfma_f32_32x32x16_bf16 v[64:79], v[176:179], v[212:215], v[64:79]
	v_mfma_f32_32x32x16_bf16 v[0:15], v[180:183], v[212:215], v[0:15]
	s_setprio 0
	s_barrier
; template <bool trans>
; DI void gemm_core(const GTile& tl, const GTile& nx, bool has_next  , bool chain  , bool pre, u32x4 (&ra)[4], u32x4 (&rb)[4], char* smem, f32x16 (&acc)[2][4]) {
;     ...
;   const int nk = K / 64;
;   if (!pre) { G_LOAD(0); G_STORE(0); G_LOAD(1); }
;   for (int kt = 0; kt < nk; ++kt) {
;     __syncthreads();
;     G_COMPUTE(kt & 1, kt);
;   }
	global_load_dwordx4 v[176:179], v[136:137], off offset:1280
	global_load_dwordx4 v[180:183], v[138:139], off offset:1280
	s_waitcnt vmcnt(9)
	ds_write_b128 v192, v[168:171]
	s_waitcnt vmcnt(8)
	ds_write_b128 v159, v[172:175]
	ds_read_b128 v[168:171], v152 offset:36864
	ds_read_b128 v[172:175], v152 offset:41472
	ds_read_b128 v[208:211], v151
	ds_read_b128 v[212:215], v151 offset:4608
	s_setprio 1
	s_waitcnt lgkmcnt(1)
	v_mfma_f32_32x32x16_bf16 v[112:127], v[168:171], v[208:211], v[112:127]
	v_mfma_f32_32x32x16_bf16 v[48:63], v[172:175], v[208:211], v[48:63]
	s_waitcnt lgkmcnt(0)
	v_mfma_f32_32x32x16_bf16 v[96:111], v[168:171], v[212:215], v[96:111]
	v_mfma_f32_32x32x16_bf16 v[32:47], v[172:175], v[212:215], v[32:47]
	ds_read_b128 v[208:211], v151 offset:9216
	ds_read_b128 v[212:215], v151 offset:13824
	s_waitcnt vmcnt(7)
	ds_write_b128 v158, v[160:163]
	s_waitcnt vmcnt(6)
	ds_write_b128 v157, v[164:167]
	ds_read_b128 v[160:163], v152 offset:36896
	ds_read_b128 v[164:167], v152 offset:41504
	s_waitcnt lgkmcnt(5)
	v_mfma_f32_32x32x16_bf16 v[80:95], v[168:171], v[208:211], v[80:95]
	v_mfma_f32_32x32x16_bf16 v[16:31], v[172:175], v[208:211], v[16:31]
	ds_read_b128 v[208:211], v151 offset:32
	s_waitcnt lgkmcnt(5)
	v_mfma_f32_32x32x16_bf16 v[64:79], v[168:171], v[212:215], v[64:79]
	v_mfma_f32_32x32x16_bf16 v[0:15], v[172:175], v[212:215], v[0:15]
	ds_read_b128 v[212:215], v151 offset:4640
	global_load_dwordx4 v[168:171], v[140:141], off offset:1280
	global_load_dwordx4 v[172:175], v[142:143], off offset:1280
	s_waitcnt lgkmcnt(1)
	v_mfma_f32_32x32x16_bf16 v[112:127], v[160:163], v[208:211], v[112:127]
	v_mfma_f32_32x32x16_bf16 v[48:63], v[164:167], v[208:211], v[48:63]
	s_waitcnt lgkmcnt(0)
	v_mfma_f32_32x32x16_bf16 v[96:111], v[160:163], v[212:215], v[96:111]
	v_mfma_f32_32x32x16_bf16 v[32:47], v[164:167], v[212:215], v[32:47]
	ds_read_b128 v[208:211], v151 offset:9248
	ds_read_b128 v[212:215], v151 offset:13856
	s_waitcnt vmcnt(7)
	ds_write_b128 v154, v[184:187]
	s_waitcnt vmcnt(6)
	ds_write_b128 v153, v[188:191]
	ds_read_b128 v[184:187], v152 offset:36928
	ds_read_b128 v[188:191], v152 offset:41536
	s_waitcnt lgkmcnt(5)
	v_mfma_f32_32x32x16_bf16 v[80:95], v[160:163], v[208:211], v[80:95]
	v_mfma_f32_32x32x16_bf16 v[16:31], v[164:167], v[208:211], v[16:31]
	ds_read_b128 v[208:211], v151 offset:64
	s_waitcnt lgkmcnt(5)
	v_mfma_f32_32x32x16_bf16 v[64:79], v[160:163], v[212:215], v[64:79]
	v_mfma_f32_32x32x16_bf16 v[0:15], v[164:167], v[212:215], v[0:15]
	ds_read_b128 v[212:215], v151 offset:4672
	global_load_dwordx4 v[160:163], v[132:133], off offset:1280
	global_load_dwordx4 v[164:167], v[134:135], off offset:1280
	s_waitcnt lgkmcnt(1)
	v_mfma_f32_32x32x16_bf16 v[112:127], v[184:187], v[208:211], v[112:127]
	v_mfma_f32_32x32x16_bf16 v[48:63], v[188:191], v[208:211], v[48:63]
	s_waitcnt lgkmcnt(0)
	v_mfma_f32_32x32x16_bf16 v[96:111], v[184:187], v[212:215], v[96:111]
	v_mfma_f32_32x32x16_bf16 v[32:47], v[188:191], v[212:215], v[32:47]
	ds_read_b128 v[208:211], v151 offset:9280
	ds_read_b128 v[212:215], v151 offset:13888
	s_waitcnt vmcnt(7)
	ds_write_b128 v156, v[194:197]
	s_waitcnt vmcnt(6)
	ds_write_b128 v155, v[198:201]
	ds_read_b128 v[194:197], v152 offset:36960
	ds_read_b128 v[198:201], v152 offset:41568
	s_waitcnt lgkmcnt(5)
	v_mfma_f32_32x32x16_bf16 v[80:95], v[184:187], v[208:211], v[80:95]
	v_mfma_f32_32x32x16_bf16 v[16:31], v[188:191], v[208:211], v[16:31]
	ds_read_b128 v[208:211], v151 offset:96
	s_waitcnt lgkmcnt(5)
	v_mfma_f32_32x32x16_bf16 v[64:79], v[184:187], v[212:215], v[64:79]
	v_mfma_f32_32x32x16_bf16 v[0:15], v[188:191], v[212:215], v[0:15]
	ds_read_b128 v[212:215], v151 offset:4704
	global_load_dwordx4 v[184:187], v[144:145], off offset:1280
	global_load_dwordx4 v[188:191], v[146:147], off offset:1280
	s_waitcnt lgkmcnt(1)
	v_mfma_f32_32x32x16_bf16 v[112:127], v[194:197], v[208:211], v[112:127]
	v_mfma_f32_32x32x16_bf16 v[48:63], v[198:201], v[208:211], v[48:63]
	s_waitcnt lgkmcnt(0)
	v_mfma_f32_32x32x16_bf16 v[96:111], v[194:197], v[212:215], v[96:111]
	v_mfma_f32_32x32x16_bf16 v[32:47], v[198:201], v[212:215], v[32:47]
	ds_read_b128 v[208:211], v151 offset:9312
	ds_read_b128 v[212:215], v151 offset:13920
	s_waitcnt lgkmcnt(1)
	v_mfma_f32_32x32x16_bf16 v[80:95], v[194:197], v[208:211], v[80:95]
	v_mfma_f32_32x32x16_bf16 v[16:31], v[198:201], v[208:211], v[16:31]
	s_waitcnt lgkmcnt(0)
	v_mfma_f32_32x32x16_bf16 v[64:79], v[194:197], v[212:215], v[64:79]
	v_mfma_f32_32x32x16_bf16 v[0:15], v[198:201], v[212:215], v[0:15]
	s_setprio 0
	s_barrier
	global_load_dwordx4 v[194:197], v[136:137], off offset:1408
	global_load_dwordx4 v[198:201], v[138:139], off offset:1408
	s_waitcnt vmcnt(9)
	ds_write_b128 v148, v[176:179]
	s_waitcnt vmcnt(8)
	ds_write_b128 v148, v[180:183] offset:36864
	ds_read_b128 v[176:179], v150
	ds_read_b128 v[180:183], v150 offset:4608
	ds_read_b128 v[208:211], v149
	ds_read_b128 v[212:215], v149 offset:4608
	s_setprio 1
	s_waitcnt lgkmcnt(1)
	v_mfma_f32_32x32x16_bf16 v[112:127], v[176:179], v[208:211], v[112:127]
	v_mfma_f32_32x32x16_bf16 v[48:63], v[180:183], v[208:211], v[48:63]
	s_waitcnt lgkmcnt(0)
	v_mfma_f32_32x32x16_bf16 v[96:111], v[176:179], v[212:215], v[96:111]
	v_mfma_f32_32x32x16_bf16 v[32:47], v[180:183], v[212:215], v[32:47]
	ds_read_b128 v[208:211], v149 offset:9216
	ds_read_b128 v[212:215], v149 offset:13824
	s_waitcnt vmcnt(7)
	ds_write_b128 v148, v[168:171] offset:9216
	s_waitcnt vmcnt(6)
	ds_write_b128 v148, v[172:175] offset:46080
	ds_read_b128 v[168:171], v150 offset:32
	ds_read_b128 v[172:175], v150 offset:4640
	s_waitcnt lgkmcnt(5)
	v_mfma_f32_32x32x16_bf16 v[80:95], v[176:179], v[208:211], v[80:95]
	v_mfma_f32_32x32x16_bf16 v[16:31], v[180:183], v[208:211], v[16:31]
	ds_read_b128 v[208:211], v149 offset:32
	s_waitcnt lgkmcnt(5)
	v_mfma_f32_32x32x16_bf16 v[64:79], v[176:179], v[212:215], v[64:79]
	v_mfma_f32_32x32x16_bf16 v[0:15], v[180:183], v[212:215], v[0:15]
	ds_read_b128 v[212:215], v149 offset:4640
	global_load_dwordx4 v[176:179], v[140:141], off offset:1408
	global_load_dwordx4 v[180:183], v[142:143], off offset:1408
	s_waitcnt lgkmcnt(1)
	v_mfma_f32_32x32x16_bf16 v[112:127], v[168:171], v[208:211], v[112:127]
	v_mfma_f32_32x32x16_bf16 v[48:63], v[172:175], v[208:211], v[48:63]
	s_waitcnt lgkmcnt(0)
	v_mfma_f32_32x32x16_bf16 v[96:111], v[168:171], v[212:215], v[96:111]
	v_mfma_f32_32x32x16_bf16 v[32:47], v[172:175], v[212:215], v[32:47]
	ds_read_b128 v[208:211], v149 offset:9248
	ds_read_b128 v[212:215], v149 offset:13856
	s_waitcnt vmcnt(7)
	ds_write_b128 v148, v[160:163] offset:18432
	s_waitcnt vmcnt(6)
	ds_write_b128 v148, v[164:167] offset:55296
	ds_read_b128 v[160:163], v150 offset:64
	ds_read_b128 v[164:167], v150 offset:4672
	s_waitcnt lgkmcnt(5)
	v_mfma_f32_32x32x16_bf16 v[80:95], v[168:171], v[208:211], v[80:95]
	v_mfma_f32_32x32x16_bf16 v[16:31], v[172:175], v[208:211], v[16:31]
	ds_read_b128 v[208:211], v149 offset:64
	s_waitcnt lgkmcnt(5)
	v_mfma_f32_32x32x16_bf16 v[64:79], v[168:171], v[212:215], v[64:79]
	v_mfma_f32_32x32x16_bf16 v[0:15], v[172:175], v[212:215], v[0:15]
	ds_read_b128 v[212:215], v149 offset:4672
	global_load_dwordx4 v[168:171], v[132:133], off offset:1408
	global_load_dwordx4 v[172:175], v[134:135], off offset:1408
	s_waitcnt lgkmcnt(1)
	v_mfma_f32_32x32x16_bf16 v[112:127], v[160:163], v[208:211], v[112:127]
	v_mfma_f32_32x32x16_bf16 v[48:63], v[164:167], v[208:211], v[48:63]
	s_waitcnt lgkmcnt(0)
	v_mfma_f32_32x32x16_bf16 v[96:111], v[160:163], v[212:215], v[96:111]
	v_mfma_f32_32x32x16_bf16 v[32:47], v[164:167], v[212:215], v[32:47]
	ds_read_b128 v[208:211], v149 offset:9280
	ds_read_b128 v[212:215], v149 offset:13888
	s_waitcnt vmcnt(7)
	ds_write_b128 v148, v[184:187] offset:27648
	s_waitcnt vmcnt(6)
	ds_write_b128 v148, v[188:191] offset:64512
	ds_read_b128 v[184:187], v150 offset:96
	ds_read_b128 v[188:191], v150 offset:4704
	s_waitcnt lgkmcnt(5)
	v_mfma_f32_32x32x16_bf16 v[80:95], v[160:163], v[208:211], v[80:95]
	v_mfma_f32_32x32x16_bf16 v[16:31], v[164:167], v[208:211], v[16:31]
	ds_read_b128 v[208:211], v149 offset:96
	s_waitcnt lgkmcnt(5)
	v_mfma_f32_32x32x16_bf16 v[64:79], v[160:163], v[212:215], v[64:79]
	v_mfma_f32_32x32x16_bf16 v[0:15], v[164:167], v[212:215], v[0:15]
	ds_read_b128 v[212:215], v149 offset:4704
	global_load_dwordx4 v[160:163], v[144:145], off offset:1408
	global_load_dwordx4 v[164:167], v[146:147], off offset:1408
	s_waitcnt lgkmcnt(1)
	v_mfma_f32_32x32x16_bf16 v[112:127], v[184:187], v[208:211], v[112:127]
	v_mfma_f32_32x32x16_bf16 v[48:63], v[188:191], v[208:211], v[48:63]
	s_waitcnt lgkmcnt(0)
	v_mfma_f32_32x32x16_bf16 v[96:111], v[184:187], v[212:215], v[96:111]
	v_mfma_f32_32x32x16_bf16 v[32:47], v[188:191], v[212:215], v[32:47]
	ds_read_b128 v[208:211], v149 offset:9312
	ds_read_b128 v[212:215], v149 offset:13920
	s_waitcnt lgkmcnt(1)
	v_mfma_f32_32x32x16_bf16 v[80:95], v[184:187], v[208:211], v[80:95]
	v_mfma_f32_32x32x16_bf16 v[16:31], v[188:191], v[208:211], v[16:31]
	s_waitcnt lgkmcnt(0)
	v_mfma_f32_32x32x16_bf16 v[64:79], v[184:187], v[212:215], v[64:79]
	v_mfma_f32_32x32x16_bf16 v[0:15], v[188:191], v[212:215], v[0:15]
	s_setprio 0
	s_barrier
	global_load_dwordx4 v[184:187], v[136:137], off offset:1536
	global_load_dwordx4 v[188:191], v[138:139], off offset:1536
	s_waitcnt vmcnt(9)
	ds_write_b128 v192, v[194:197]
	s_waitcnt vmcnt(8)
	ds_write_b128 v159, v[198:201]
	ds_read_b128 v[194:197], v152 offset:36864
	ds_read_b128 v[198:201], v152 offset:41472
	ds_read_b128 v[208:211], v151
	ds_read_b128 v[212:215], v151 offset:4608
	s_setprio 1
	s_waitcnt lgkmcnt(1)
	v_mfma_f32_32x32x16_bf16 v[112:127], v[194:197], v[208:211], v[112:127]
	v_mfma_f32_32x32x16_bf16 v[48:63], v[198:201], v[208:211], v[48:63]
	s_waitcnt lgkmcnt(0)
	v_mfma_f32_32x32x16_bf16 v[96:111], v[194:197], v[212:215], v[96:111]
	v_mfma_f32_32x32x16_bf16 v[32:47], v[198:201], v[212:215], v[32:47]
	ds_read_b128 v[208:211], v151 offset:9216
	ds_read_b128 v[212:215], v151 offset:13824
	s_waitcnt vmcnt(7)
	ds_write_b128 v158, v[176:179]
	s_waitcnt vmcnt(6)
	ds_write_b128 v157, v[180:183]
	ds_read_b128 v[176:179], v152 offset:36896
	ds_read_b128 v[180:183], v152 offset:41504
	s_waitcnt lgkmcnt(5)
	v_mfma_f32_32x32x16_bf16 v[80:95], v[194:197], v[208:211], v[80:95]
	v_mfma_f32_32x32x16_bf16 v[16:31], v[198:201], v[208:211], v[16:31]
	ds_read_b128 v[208:211], v151 offset:32
	s_waitcnt lgkmcnt(5)
	v_mfma_f32_32x32x16_bf16 v[64:79], v[194:197], v[212:215], v[64:79]
	v_mfma_f32_32x32x16_bf16 v[0:15], v[198:201], v[212:215], v[0:15]
	ds_read_b128 v[212:215], v151 offset:4640
	global_load_dwordx4 v[194:197], v[140:141], off offset:1536
	global_load_dwordx4 v[198:201], v[142:143], off offset:1536
	s_waitcnt lgkmcnt(1)
	v_mfma_f32_32x32x16_bf16 v[112:127], v[176:179], v[208:211], v[112:127]
	v_mfma_f32_32x32x16_bf16 v[48:63], v[180:183], v[208:211], v[48:63]
	s_waitcnt lgkmcnt(0)
	v_mfma_f32_32x32x16_bf16 v[96:111], v[176:179], v[212:215], v[96:111]
	v_mfma_f32_32x32x16_bf16 v[32:47], v[180:183], v[212:215], v[32:47]
	ds_read_b128 v[208:211], v151 offset:9248
	ds_read_b128 v[212:215], v151 offset:13856
	s_waitcnt vmcnt(7)
	ds_write_b128 v154, v[168:171]
	s_waitcnt vmcnt(6)
	ds_write_b128 v153, v[172:175]
	ds_read_b128 v[168:171], v152 offset:36928
	ds_read_b128 v[172:175], v152 offset:41536
	s_waitcnt lgkmcnt(5)
	v_mfma_f32_32x32x16_bf16 v[80:95], v[176:179], v[208:211], v[80:95]
	v_mfma_f32_32x32x16_bf16 v[16:31], v[180:183], v[208:211], v[16:31]
	ds_read_b128 v[208:211], v151 offset:64
	s_waitcnt lgkmcnt(5)
	v_mfma_f32_32x32x16_bf16 v[64:79], v[176:179], v[212:215], v[64:79]
	v_mfma_f32_32x32x16_bf16 v[0:15], v[180:183], v[212:215], v[0:15]
	ds_read_b128 v[212:215], v151 offset:4672
	global_load_dwordx4 v[176:179], v[132:133], off offset:1536
	global_load_dwordx4 v[180:183], v[134:135], off offset:1536
	s_waitcnt lgkmcnt(1)
	v_mfma_f32_32x32x16_bf16 v[112:127], v[168:171], v[208:211], v[112:127]
	v_mfma_f32_32x32x16_bf16 v[48:63], v[172:175], v[208:211], v[48:63]
	s_waitcnt lgkmcnt(0)
	v_mfma_f32_32x32x16_bf16 v[96:111], v[168:171], v[212:215], v[96:111]
	v_mfma_f32_32x32x16_bf16 v[32:47], v[172:175], v[212:215], v[32:47]
	ds_read_b128 v[208:211], v151 offset:9280
	ds_read_b128 v[212:215], v151 offset:13888
	s_waitcnt vmcnt(7)
	ds_write_b128 v156, v[160:163]
	s_waitcnt vmcnt(6)
	ds_write_b128 v155, v[164:167]
	ds_read_b128 v[160:163], v152 offset:36960
	ds_read_b128 v[164:167], v152 offset:41568
	s_waitcnt lgkmcnt(5)
	v_mfma_f32_32x32x16_bf16 v[80:95], v[168:171], v[208:211], v[80:95]
	v_mfma_f32_32x32x16_bf16 v[16:31], v[172:175], v[208:211], v[16:31]
	ds_read_b128 v[208:211], v151 offset:96
	s_waitcnt lgkmcnt(5)
	v_mfma_f32_32x32x16_bf16 v[64:79], v[168:171], v[212:215], v[64:79]
	v_mfma_f32_32x32x16_bf16 v[0:15], v[172:175], v[212:215], v[0:15]
	ds_read_b128 v[212:215], v151 offset:4704
	global_load_dwordx4 v[168:171], v[144:145], off offset:1536
	global_load_dwordx4 v[172:175], v[146:147], off offset:1536
	s_waitcnt lgkmcnt(1)
	v_mfma_f32_32x32x16_bf16 v[112:127], v[160:163], v[208:211], v[112:127]
	v_mfma_f32_32x32x16_bf16 v[48:63], v[164:167], v[208:211], v[48:63]
	s_waitcnt lgkmcnt(0)
	v_mfma_f32_32x32x16_bf16 v[96:111], v[160:163], v[212:215], v[96:111]
	v_mfma_f32_32x32x16_bf16 v[32:47], v[164:167], v[212:215], v[32:47]
	ds_read_b128 v[208:211], v151 offset:9312
	ds_read_b128 v[212:215], v151 offset:13920
	s_waitcnt lgkmcnt(1)
	v_mfma_f32_32x32x16_bf16 v[80:95], v[160:163], v[208:211], v[80:95]
	v_mfma_f32_32x32x16_bf16 v[16:31], v[164:167], v[208:211], v[16:31]
	s_waitcnt lgkmcnt(0)
	v_mfma_f32_32x32x16_bf16 v[64:79], v[160:163], v[212:215], v[64:79]
	v_mfma_f32_32x32x16_bf16 v[0:15], v[164:167], v[212:215], v[0:15]
	s_setprio 0
	s_barrier
	global_load_dwordx4 v[160:163], v[136:137], off offset:1664
	global_load_dwordx4 v[164:167], v[138:139], off offset:1664
	s_waitcnt vmcnt(9)
	ds_write_b128 v148, v[184:187]
	s_waitcnt vmcnt(8)
	ds_write_b128 v148, v[188:191] offset:36864
	ds_read_b128 v[184:187], v150
	ds_read_b128 v[188:191], v150 offset:4608
	ds_read_b128 v[208:211], v149
	ds_read_b128 v[212:215], v149 offset:4608
	s_setprio 1
	s_waitcnt lgkmcnt(1)
	v_mfma_f32_32x32x16_bf16 v[112:127], v[184:187], v[208:211], v[112:127]
	v_mfma_f32_32x32x16_bf16 v[48:63], v[188:191], v[208:211], v[48:63]
	s_waitcnt lgkmcnt(0)
	v_mfma_f32_32x32x16_bf16 v[96:111], v[184:187], v[212:215], v[96:111]
	v_mfma_f32_32x32x16_bf16 v[32:47], v[188:191], v[212:215], v[32:47]
	ds_read_b128 v[208:211], v149 offset:9216
	ds_read_b128 v[212:215], v149 offset:13824
	s_waitcnt vmcnt(7)
	ds_write_b128 v148, v[194:197] offset:9216
	s_waitcnt vmcnt(6)
	ds_write_b128 v148, v[198:201] offset:46080
	ds_read_b128 v[194:197], v150 offset:32
	ds_read_b128 v[198:201], v150 offset:4640
	s_waitcnt lgkmcnt(5)
	v_mfma_f32_32x32x16_bf16 v[80:95], v[184:187], v[208:211], v[80:95]
	v_mfma_f32_32x32x16_bf16 v[16:31], v[188:191], v[208:211], v[16:31]
	ds_read_b128 v[208:211], v149 offset:32
	s_waitcnt lgkmcnt(5)
	v_mfma_f32_32x32x16_bf16 v[64:79], v[184:187], v[212:215], v[64:79]
	v_mfma_f32_32x32x16_bf16 v[0:15], v[188:191], v[212:215], v[0:15]
	ds_read_b128 v[212:215], v149 offset:4640
	global_load_dwordx4 v[184:187], v[140:141], off offset:1664
	global_load_dwordx4 v[188:191], v[142:143], off offset:1664
	s_waitcnt lgkmcnt(1)
	v_mfma_f32_32x32x16_bf16 v[112:127], v[194:197], v[208:211], v[112:127]
	v_mfma_f32_32x32x16_bf16 v[48:63], v[198:201], v[208:211], v[48:63]
	s_waitcnt lgkmcnt(0)
	v_mfma_f32_32x32x16_bf16 v[96:111], v[194:197], v[212:215], v[96:111]
	v_mfma_f32_32x32x16_bf16 v[32:47], v[198:201], v[212:215], v[32:47]
	ds_read_b128 v[208:211], v149 offset:9248
	ds_read_b128 v[212:215], v149 offset:13856
	s_waitcnt vmcnt(7)
	ds_write_b128 v148, v[176:179] offset:18432
	s_waitcnt vmcnt(6)
	ds_write_b128 v148, v[180:183] offset:55296
	ds_read_b128 v[176:179], v150 offset:64
	ds_read_b128 v[180:183], v150 offset:4672
	s_waitcnt lgkmcnt(5)
	v_mfma_f32_32x32x16_bf16 v[80:95], v[194:197], v[208:211], v[80:95]
	v_mfma_f32_32x32x16_bf16 v[16:31], v[198:201], v[208:211], v[16:31]
	ds_read_b128 v[208:211], v149 offset:64
	s_waitcnt lgkmcnt(5)
	v_mfma_f32_32x32x16_bf16 v[64:79], v[194:197], v[212:215], v[64:79]
	v_mfma_f32_32x32x16_bf16 v[0:15], v[198:201], v[212:215], v[0:15]
	ds_read_b128 v[212:215], v149 offset:4672
	global_load_dwordx4 v[194:197], v[132:133], off offset:1664
	global_load_dwordx4 v[198:201], v[134:135], off offset:1664
	s_waitcnt lgkmcnt(1)
	v_mfma_f32_32x32x16_bf16 v[112:127], v[176:179], v[208:211], v[112:127]
	v_mfma_f32_32x32x16_bf16 v[48:63], v[180:183], v[208:211], v[48:63]
	s_waitcnt lgkmcnt(0)
	v_mfma_f32_32x32x16_bf16 v[96:111], v[176:179], v[212:215], v[96:111]
	v_mfma_f32_32x32x16_bf16 v[32:47], v[180:183], v[212:215], v[32:47]
	ds_read_b128 v[208:211], v149 offset:9280
	ds_read_b128 v[212:215], v149 offset:13888
	s_waitcnt vmcnt(7)
	ds_write_b128 v148, v[168:171] offset:27648
	s_waitcnt vmcnt(6)
	ds_write_b128 v148, v[172:175] offset:64512
	ds_read_b128 v[168:171], v150 offset:96
	ds_read_b128 v[172:175], v150 offset:4704
	s_waitcnt lgkmcnt(5)
	v_mfma_f32_32x32x16_bf16 v[80:95], v[176:179], v[208:211], v[80:95]
	v_mfma_f32_32x32x16_bf16 v[16:31], v[180:183], v[208:211], v[16:31]
	ds_read_b128 v[208:211], v149 offset:96
	s_waitcnt lgkmcnt(5)
	v_mfma_f32_32x32x16_bf16 v[64:79], v[176:179], v[212:215], v[64:79]
	v_mfma_f32_32x32x16_bf16 v[0:15], v[180:183], v[212:215], v[0:15]
	ds_read_b128 v[212:215], v149 offset:4704
	global_load_dwordx4 v[176:179], v[144:145], off offset:1664
	global_load_dwordx4 v[180:183], v[146:147], off offset:1664
	s_waitcnt lgkmcnt(1)
	v_mfma_f32_32x32x16_bf16 v[112:127], v[168:171], v[208:211], v[112:127]
	v_mfma_f32_32x32x16_bf16 v[48:63], v[172:175], v[208:211], v[48:63]
	s_waitcnt lgkmcnt(0)
	v_mfma_f32_32x32x16_bf16 v[96:111], v[168:171], v[212:215], v[96:111]
	v_mfma_f32_32x32x16_bf16 v[32:47], v[172:175], v[212:215], v[32:47]
	ds_read_b128 v[208:211], v149 offset:9312
	ds_read_b128 v[212:215], v149 offset:13920
	s_waitcnt lgkmcnt(1)
	v_mfma_f32_32x32x16_bf16 v[80:95], v[168:171], v[208:211], v[80:95]
	v_mfma_f32_32x32x16_bf16 v[16:31], v[172:175], v[208:211], v[16:31]
	s_waitcnt lgkmcnt(0)
	v_mfma_f32_32x32x16_bf16 v[64:79], v[168:171], v[212:215], v[64:79]
	v_mfma_f32_32x32x16_bf16 v[0:15], v[172:175], v[212:215], v[0:15]
	s_setprio 0
	s_barrier
	global_load_dwordx4 v[168:171], v[136:137], off offset:1792
	global_load_dwordx4 v[172:175], v[138:139], off offset:1792
	s_waitcnt vmcnt(9)
	ds_write_b128 v192, v[160:163]
	s_waitcnt vmcnt(8)
	ds_write_b128 v159, v[164:167]
	ds_read_b128 v[160:163], v152 offset:36864
	ds_read_b128 v[164:167], v152 offset:41472
	ds_read_b128 v[208:211], v151
	ds_read_b128 v[212:215], v151 offset:4608
	s_setprio 1
	s_waitcnt lgkmcnt(1)
	v_mfma_f32_32x32x16_bf16 v[112:127], v[160:163], v[208:211], v[112:127]
	v_mfma_f32_32x32x16_bf16 v[48:63], v[164:167], v[208:211], v[48:63]
	s_waitcnt lgkmcnt(0)
	v_mfma_f32_32x32x16_bf16 v[96:111], v[160:163], v[212:215], v[96:111]
	v_mfma_f32_32x32x16_bf16 v[32:47], v[164:167], v[212:215], v[32:47]
	ds_read_b128 v[208:211], v151 offset:9216
	ds_read_b128 v[212:215], v151 offset:13824
	s_waitcnt vmcnt(7)
	ds_write_b128 v158, v[184:187]
	s_waitcnt vmcnt(6)
	ds_write_b128 v157, v[188:191]
	ds_read_b128 v[184:187], v152 offset:36896
	ds_read_b128 v[188:191], v152 offset:41504
	s_waitcnt lgkmcnt(5)
	v_mfma_f32_32x32x16_bf16 v[80:95], v[160:163], v[208:211], v[80:95]
	v_mfma_f32_32x32x16_bf16 v[16:31], v[164:167], v[208:211], v[16:31]
	ds_read_b128 v[208:211], v151 offset:32
	s_waitcnt lgkmcnt(5)
	v_mfma_f32_32x32x16_bf16 v[64:79], v[160:163], v[212:215], v[64:79]
	v_mfma_f32_32x32x16_bf16 v[0:15], v[164:167], v[212:215], v[0:15]
	ds_read_b128 v[212:215], v151 offset:4640
	global_load_dwordx4 v[160:163], v[140:141], off offset:1792
	global_load_dwordx4 v[164:167], v[142:143], off offset:1792
	s_waitcnt lgkmcnt(1)
	v_mfma_f32_32x32x16_bf16 v[112:127], v[184:187], v[208:211], v[112:127]
	v_mfma_f32_32x32x16_bf16 v[48:63], v[188:191], v[208:211], v[48:63]
	s_waitcnt lgkmcnt(0)
	v_mfma_f32_32x32x16_bf16 v[96:111], v[184:187], v[212:215], v[96:111]
	v_mfma_f32_32x32x16_bf16 v[32:47], v[188:191], v[212:215], v[32:47]
	ds_read_b128 v[208:211], v151 offset:9248
	ds_read_b128 v[212:215], v151 offset:13856
	s_waitcnt vmcnt(7)
	ds_write_b128 v154, v[194:197]
	s_waitcnt vmcnt(6)
	ds_write_b128 v153, v[198:201]
	ds_read_b128 v[194:197], v152 offset:36928
	ds_read_b128 v[198:201], v152 offset:41536
	s_waitcnt lgkmcnt(5)
	v_mfma_f32_32x32x16_bf16 v[80:95], v[184:187], v[208:211], v[80:95]
	v_mfma_f32_32x32x16_bf16 v[16:31], v[188:191], v[208:211], v[16:31]
	ds_read_b128 v[208:211], v151 offset:64
	s_waitcnt lgkmcnt(5)
	v_mfma_f32_32x32x16_bf16 v[64:79], v[184:187], v[212:215], v[64:79]
	v_mfma_f32_32x32x16_bf16 v[0:15], v[188:191], v[212:215], v[0:15]
	ds_read_b128 v[212:215], v151 offset:4672
	global_load_dwordx4 v[184:187], v[132:133], off offset:1792
	global_load_dwordx4 v[188:191], v[134:135], off offset:1792
	s_waitcnt lgkmcnt(1)
	v_mfma_f32_32x32x16_bf16 v[112:127], v[194:197], v[208:211], v[112:127]
	v_mfma_f32_32x32x16_bf16 v[48:63], v[198:201], v[208:211], v[48:63]
	s_waitcnt lgkmcnt(0)
	v_mfma_f32_32x32x16_bf16 v[96:111], v[194:197], v[212:215], v[96:111]
	v_mfma_f32_32x32x16_bf16 v[32:47], v[198:201], v[212:215], v[32:47]
	ds_read_b128 v[208:211], v151 offset:9280
	ds_read_b128 v[212:215], v151 offset:13888
	s_waitcnt vmcnt(7)
	ds_write_b128 v156, v[176:179]
	s_waitcnt vmcnt(6)
	ds_write_b128 v155, v[180:183]
	ds_read_b128 v[176:179], v152 offset:36960
	ds_read_b128 v[180:183], v152 offset:41568
	s_waitcnt lgkmcnt(5)
	v_mfma_f32_32x32x16_bf16 v[80:95], v[194:197], v[208:211], v[80:95]
	v_mfma_f32_32x32x16_bf16 v[16:31], v[198:201], v[208:211], v[16:31]
	ds_read_b128 v[208:211], v151 offset:96
	s_waitcnt lgkmcnt(5)
	v_mfma_f32_32x32x16_bf16 v[64:79], v[194:197], v[212:215], v[64:79]
	v_mfma_f32_32x32x16_bf16 v[0:15], v[198:201], v[212:215], v[0:15]
	ds_read_b128 v[212:215], v151 offset:4704
	global_load_dwordx4 v[194:197], v[144:145], off offset:1792
	global_load_dwordx4 v[198:201], v[146:147], off offset:1792
	s_waitcnt lgkmcnt(1)
	v_mfma_f32_32x32x16_bf16 v[112:127], v[176:179], v[208:211], v[112:127]
	v_mfma_f32_32x32x16_bf16 v[48:63], v[180:183], v[208:211], v[48:63]
	s_waitcnt lgkmcnt(0)
	v_mfma_f32_32x32x16_bf16 v[96:111], v[176:179], v[212:215], v[96:111]
	v_mfma_f32_32x32x16_bf16 v[32:47], v[180:183], v[212:215], v[32:47]
	ds_read_b128 v[208:211], v151 offset:9312
	ds_read_b128 v[212:215], v151 offset:13920
	s_waitcnt lgkmcnt(1)
	v_mfma_f32_32x32x16_bf16 v[80:95], v[176:179], v[208:211], v[80:95]
	v_mfma_f32_32x32x16_bf16 v[16:31], v[180:183], v[208:211], v[16:31]
	s_waitcnt lgkmcnt(0)
	v_mfma_f32_32x32x16_bf16 v[64:79], v[176:179], v[212:215], v[64:79]
	v_mfma_f32_32x32x16_bf16 v[0:15], v[180:183], v[212:215], v[0:15]
	s_setprio 0
	s_barrier
	global_load_dwordx4 v[176:179], v[136:137], off offset:1920
	global_load_dwordx4 v[180:183], v[138:139], off offset:1920
	s_waitcnt vmcnt(9)
	ds_write_b128 v148, v[168:171]
	s_waitcnt vmcnt(8)
	ds_write_b128 v148, v[172:175] offset:36864
	ds_read_b128 v[168:171], v150
	ds_read_b128 v[172:175], v150 offset:4608
	ds_read_b128 v[208:211], v149
	ds_read_b128 v[212:215], v149 offset:4608
	s_setprio 1
	s_waitcnt lgkmcnt(1)
	v_mfma_f32_32x32x16_bf16 v[112:127], v[168:171], v[208:211], v[112:127]
	v_mfma_f32_32x32x16_bf16 v[48:63], v[172:175], v[208:211], v[48:63]
	s_waitcnt lgkmcnt(0)
	v_mfma_f32_32x32x16_bf16 v[96:111], v[168:171], v[212:215], v[96:111]
	v_mfma_f32_32x32x16_bf16 v[32:47], v[172:175], v[212:215], v[32:47]
	ds_read_b128 v[208:211], v149 offset:9216
	ds_read_b128 v[212:215], v149 offset:13824
	s_waitcnt vmcnt(7)
	ds_write_b128 v148, v[160:163] offset:9216
	s_waitcnt vmcnt(6)
	ds_write_b128 v148, v[164:167] offset:46080
	ds_read_b128 v[160:163], v150 offset:32
	ds_read_b128 v[164:167], v150 offset:4640
	s_waitcnt lgkmcnt(5)
	v_mfma_f32_32x32x16_bf16 v[80:95], v[168:171], v[208:211], v[80:95]
	v_mfma_f32_32x32x16_bf16 v[16:31], v[172:175], v[208:211], v[16:31]
	ds_read_b128 v[208:211], v149 offset:32
	s_waitcnt lgkmcnt(5)
	v_mfma_f32_32x32x16_bf16 v[64:79], v[168:171], v[212:215], v[64:79]
	v_mfma_f32_32x32x16_bf16 v[0:15], v[172:175], v[212:215], v[0:15]
	ds_read_b128 v[212:215], v149 offset:4640
	global_load_dwordx4 v[168:171], v[140:141], off offset:1920
	global_load_dwordx4 v[172:175], v[142:143], off offset:1920
	s_waitcnt lgkmcnt(1)
	v_mfma_f32_32x32x16_bf16 v[112:127], v[160:163], v[208:211], v[112:127]
	v_mfma_f32_32x32x16_bf16 v[48:63], v[164:167], v[208:211], v[48:63]
	s_waitcnt lgkmcnt(0)
	v_mfma_f32_32x32x16_bf16 v[96:111], v[160:163], v[212:215], v[96:111]
	v_mfma_f32_32x32x16_bf16 v[32:47], v[164:167], v[212:215], v[32:47]
	ds_read_b128 v[208:211], v149 offset:9248
	ds_read_b128 v[212:215], v149 offset:13856
	s_waitcnt vmcnt(7)
	ds_write_b128 v148, v[184:187] offset:18432
	s_waitcnt vmcnt(6)
	ds_write_b128 v148, v[188:191] offset:55296
	ds_read_b128 v[184:187], v150 offset:64
	ds_read_b128 v[188:191], v150 offset:4672
	s_waitcnt lgkmcnt(5)
	v_mfma_f32_32x32x16_bf16 v[80:95], v[160:163], v[208:211], v[80:95]
	v_mfma_f32_32x32x16_bf16 v[16:31], v[164:167], v[208:211], v[16:31]
	ds_read_b128 v[208:211], v149 offset:64
	s_waitcnt lgkmcnt(5)
	v_mfma_f32_32x32x16_bf16 v[64:79], v[160:163], v[212:215], v[64:79]
	v_mfma_f32_32x32x16_bf16 v[0:15], v[164:167], v[212:215], v[0:15]
	ds_read_b128 v[212:215], v149 offset:4672
	global_load_dwordx4 v[160:163], v[132:133], off offset:1920
	global_load_dwordx4 v[164:167], v[134:135], off offset:1920
	s_waitcnt lgkmcnt(1)
	v_mfma_f32_32x32x16_bf16 v[112:127], v[184:187], v[208:211], v[112:127]
	v_mfma_f32_32x32x16_bf16 v[48:63], v[188:191], v[208:211], v[48:63]
	s_waitcnt lgkmcnt(0)
	v_mfma_f32_32x32x16_bf16 v[96:111], v[184:187], v[212:215], v[96:111]
	v_mfma_f32_32x32x16_bf16 v[32:47], v[188:191], v[212:215], v[32:47]
	ds_read_b128 v[208:211], v149 offset:9280
	ds_read_b128 v[212:215], v149 offset:13888
	s_waitcnt vmcnt(7)
	ds_write_b128 v148, v[194:197] offset:27648
	s_waitcnt vmcnt(6)
	ds_write_b128 v148, v[198:201] offset:64512
	ds_read_b128 v[194:197], v150 offset:96
	ds_read_b128 v[198:201], v150 offset:4704
	s_waitcnt lgkmcnt(5)
	v_mfma_f32_32x32x16_bf16 v[80:95], v[184:187], v[208:211], v[80:95]
	v_mfma_f32_32x32x16_bf16 v[16:31], v[188:191], v[208:211], v[16:31]
	ds_read_b128 v[208:211], v149 offset:96
	s_waitcnt lgkmcnt(5)
	v_mfma_f32_32x32x16_bf16 v[64:79], v[184:187], v[212:215], v[64:79]
	v_mfma_f32_32x32x16_bf16 v[0:15], v[188:191], v[212:215], v[0:15]
	ds_read_b128 v[212:215], v149 offset:4704
	global_load_dwordx4 v[184:187], v[144:145], off offset:1920
	global_load_dwordx4 v[188:191], v[146:147], off offset:1920
	s_waitcnt lgkmcnt(1)
	v_mfma_f32_32x32x16_bf16 v[112:127], v[194:197], v[208:211], v[112:127]
	v_mfma_f32_32x32x16_bf16 v[48:63], v[198:201], v[208:211], v[48:63]
	s_waitcnt lgkmcnt(0)
	v_mfma_f32_32x32x16_bf16 v[96:111], v[194:197], v[212:215], v[96:111]
	v_mfma_f32_32x32x16_bf16 v[32:47], v[198:201], v[212:215], v[32:47]
	ds_read_b128 v[208:211], v149 offset:9312
	ds_read_b128 v[212:215], v149 offset:13920
	s_waitcnt lgkmcnt(1)
	v_mfma_f32_32x32x16_bf16 v[80:95], v[194:197], v[208:211], v[80:95]
	v_mfma_f32_32x32x16_bf16 v[16:31], v[198:201], v[208:211], v[16:31]
	s_waitcnt lgkmcnt(0)
	v_mfma_f32_32x32x16_bf16 v[64:79], v[194:197], v[212:215], v[64:79]
	v_mfma_f32_32x32x16_bf16 v[0:15], v[198:201], v[212:215], v[0:15]
	s_setprio 0
	s_barrier
	global_load_dwordx4 v[194:197], v[136:137], off offset:2048
	global_load_dwordx4 v[198:201], v[138:139], off offset:2048
	s_waitcnt vmcnt(9)
	ds_write_b128 v192, v[176:179]
	s_waitcnt vmcnt(8)
	ds_write_b128 v159, v[180:183]
	ds_read_b128 v[176:179], v152 offset:36864
	ds_read_b128 v[180:183], v152 offset:41472
	ds_read_b128 v[208:211], v151
	ds_read_b128 v[212:215], v151 offset:4608
	s_setprio 1
	s_waitcnt lgkmcnt(1)
	v_mfma_f32_32x32x16_bf16 v[112:127], v[176:179], v[208:211], v[112:127]
	v_mfma_f32_32x32x16_bf16 v[48:63], v[180:183], v[208:211], v[48:63]
	s_waitcnt lgkmcnt(0)
	v_mfma_f32_32x32x16_bf16 v[96:111], v[176:179], v[212:215], v[96:111]
	v_mfma_f32_32x32x16_bf16 v[32:47], v[180:183], v[212:215], v[32:47]
	ds_read_b128 v[208:211], v151 offset:9216
	ds_read_b128 v[212:215], v151 offset:13824
	s_waitcnt vmcnt(7)
	ds_write_b128 v158, v[168:171]
	s_waitcnt vmcnt(6)
	ds_write_b128 v157, v[172:175]
	ds_read_b128 v[168:171], v152 offset:36896
	ds_read_b128 v[172:175], v152 offset:41504
	s_waitcnt lgkmcnt(5)
	v_mfma_f32_32x32x16_bf16 v[80:95], v[176:179], v[208:211], v[80:95]
	v_mfma_f32_32x32x16_bf16 v[16:31], v[180:183], v[208:211], v[16:31]
	ds_read_b128 v[208:211], v151 offset:32
	s_waitcnt lgkmcnt(5)
	v_mfma_f32_32x32x16_bf16 v[64:79], v[176:179], v[212:215], v[64:79]
	v_mfma_f32_32x32x16_bf16 v[0:15], v[180:183], v[212:215], v[0:15]
	ds_read_b128 v[212:215], v151 offset:4640
	global_load_dwordx4 v[176:179], v[140:141], off offset:2048
	global_load_dwordx4 v[180:183], v[142:143], off offset:2048
	s_waitcnt lgkmcnt(1)
	v_mfma_f32_32x32x16_bf16 v[112:127], v[168:171], v[208:211], v[112:127]
	v_mfma_f32_32x32x16_bf16 v[48:63], v[172:175], v[208:211], v[48:63]
	s_waitcnt lgkmcnt(0)
	v_mfma_f32_32x32x16_bf16 v[96:111], v[168:171], v[212:215], v[96:111]
	v_mfma_f32_32x32x16_bf16 v[32:47], v[172:175], v[212:215], v[32:47]
	ds_read_b128 v[208:211], v151 offset:9248
	ds_read_b128 v[212:215], v151 offset:13856
	s_waitcnt vmcnt(7)
	ds_write_b128 v154, v[160:163]
	s_waitcnt vmcnt(6)
	ds_write_b128 v153, v[164:167]
	ds_read_b128 v[160:163], v152 offset:36928
	ds_read_b128 v[164:167], v152 offset:41536
	s_waitcnt lgkmcnt(5)
	v_mfma_f32_32x32x16_bf16 v[80:95], v[168:171], v[208:211], v[80:95]
	v_mfma_f32_32x32x16_bf16 v[16:31], v[172:175], v[208:211], v[16:31]
	ds_read_b128 v[208:211], v151 offset:64
	s_waitcnt lgkmcnt(5)
	v_mfma_f32_32x32x16_bf16 v[64:79], v[168:171], v[212:215], v[64:79]
	v_mfma_f32_32x32x16_bf16 v[0:15], v[172:175], v[212:215], v[0:15]
	ds_read_b128 v[212:215], v151 offset:4672
	global_load_dwordx4 v[168:171], v[132:133], off offset:2048
	global_load_dwordx4 v[172:175], v[134:135], off offset:2048
	s_waitcnt lgkmcnt(1)
	v_mfma_f32_32x32x16_bf16 v[112:127], v[160:163], v[208:211], v[112:127]
	v_mfma_f32_32x32x16_bf16 v[48:63], v[164:167], v[208:211], v[48:63]
	s_waitcnt lgkmcnt(0)
	v_mfma_f32_32x32x16_bf16 v[96:111], v[160:163], v[212:215], v[96:111]
	v_mfma_f32_32x32x16_bf16 v[32:47], v[164:167], v[212:215], v[32:47]
	ds_read_b128 v[208:211], v151 offset:9280
	ds_read_b128 v[212:215], v151 offset:13888
	s_waitcnt vmcnt(7)
	ds_write_b128 v156, v[184:187]
	s_waitcnt vmcnt(6)
	ds_write_b128 v155, v[188:191]
	ds_read_b128 v[184:187], v152 offset:36960
	ds_read_b128 v[188:191], v152 offset:41568
	s_waitcnt lgkmcnt(5)
	v_mfma_f32_32x32x16_bf16 v[80:95], v[160:163], v[208:211], v[80:95]
	v_mfma_f32_32x32x16_bf16 v[16:31], v[164:167], v[208:211], v[16:31]
	ds_read_b128 v[208:211], v151 offset:96
	s_waitcnt lgkmcnt(5)
	v_mfma_f32_32x32x16_bf16 v[64:79], v[160:163], v[212:215], v[64:79]
	v_mfma_f32_32x32x16_bf16 v[0:15], v[164:167], v[212:215], v[0:15]
	ds_read_b128 v[212:215], v151 offset:4704
	global_load_dwordx4 v[160:163], v[144:145], off offset:2048
	global_load_dwordx4 v[164:167], v[146:147], off offset:2048
	s_waitcnt lgkmcnt(1)
	v_mfma_f32_32x32x16_bf16 v[112:127], v[184:187], v[208:211], v[112:127]
	v_mfma_f32_32x32x16_bf16 v[48:63], v[188:191], v[208:211], v[48:63]
	s_waitcnt lgkmcnt(0)
	v_mfma_f32_32x32x16_bf16 v[96:111], v[184:187], v[212:215], v[96:111]
	v_mfma_f32_32x32x16_bf16 v[32:47], v[188:191], v[212:215], v[32:47]
	ds_read_b128 v[208:211], v151 offset:9312
	ds_read_b128 v[212:215], v151 offset:13920
	s_waitcnt lgkmcnt(1)
	v_mfma_f32_32x32x16_bf16 v[80:95], v[184:187], v[208:211], v[80:95]
	v_mfma_f32_32x32x16_bf16 v[16:31], v[188:191], v[208:211], v[16:31]
	s_waitcnt lgkmcnt(0)
	v_mfma_f32_32x32x16_bf16 v[64:79], v[184:187], v[212:215], v[64:79]
	v_mfma_f32_32x32x16_bf16 v[0:15], v[188:191], v[212:215], v[0:15]
	s_setprio 0
	s_barrier
	global_load_dwordx4 v[184:187], v[136:137], off offset:2176
	global_load_dwordx4 v[188:191], v[138:139], off offset:2176
	s_waitcnt vmcnt(9)
	ds_write_b128 v148, v[194:197]
	s_waitcnt vmcnt(8)
	ds_write_b128 v148, v[198:201] offset:36864
	ds_read_b128 v[194:197], v150
	ds_read_b128 v[198:201], v150 offset:4608
	ds_read_b128 v[208:211], v149
	ds_read_b128 v[212:215], v149 offset:4608
	s_setprio 1
	s_waitcnt lgkmcnt(1)
	v_mfma_f32_32x32x16_bf16 v[112:127], v[194:197], v[208:211], v[112:127]
	v_mfma_f32_32x32x16_bf16 v[48:63], v[198:201], v[208:211], v[48:63]
	s_waitcnt lgkmcnt(0)
	v_mfma_f32_32x32x16_bf16 v[96:111], v[194:197], v[212:215], v[96:111]
	v_mfma_f32_32x32x16_bf16 v[32:47], v[198:201], v[212:215], v[32:47]
	ds_read_b128 v[208:211], v149 offset:9216
	ds_read_b128 v[212:215], v149 offset:13824
	s_waitcnt vmcnt(7)
	ds_write_b128 v148, v[176:179] offset:9216
	s_waitcnt vmcnt(6)
	ds_write_b128 v148, v[180:183] offset:46080
	ds_read_b128 v[176:179], v150 offset:32
	ds_read_b128 v[180:183], v150 offset:4640
	s_waitcnt lgkmcnt(5)
	v_mfma_f32_32x32x16_bf16 v[80:95], v[194:197], v[208:211], v[80:95]
	v_mfma_f32_32x32x16_bf16 v[16:31], v[198:201], v[208:211], v[16:31]
	ds_read_b128 v[208:211], v149 offset:32
	s_waitcnt lgkmcnt(5)
	v_mfma_f32_32x32x16_bf16 v[64:79], v[194:197], v[212:215], v[64:79]
	v_mfma_f32_32x32x16_bf16 v[0:15], v[198:201], v[212:215], v[0:15]
	ds_read_b128 v[212:215], v149 offset:4640
	global_load_dwordx4 v[194:197], v[140:141], off offset:2176
	global_load_dwordx4 v[198:201], v[142:143], off offset:2176
	s_waitcnt lgkmcnt(1)
	v_mfma_f32_32x32x16_bf16 v[112:127], v[176:179], v[208:211], v[112:127]
	v_mfma_f32_32x32x16_bf16 v[48:63], v[180:183], v[208:211], v[48:63]
	s_waitcnt lgkmcnt(0)
	v_mfma_f32_32x32x16_bf16 v[96:111], v[176:179], v[212:215], v[96:111]
	v_mfma_f32_32x32x16_bf16 v[32:47], v[180:183], v[212:215], v[32:47]
	ds_read_b128 v[208:211], v149 offset:9248
	ds_read_b128 v[212:215], v149 offset:13856
	s_waitcnt vmcnt(7)
	ds_write_b128 v148, v[168:171] offset:18432
	s_waitcnt vmcnt(6)
	ds_write_b128 v148, v[172:175] offset:55296
	ds_read_b128 v[168:171], v150 offset:64
	ds_read_b128 v[172:175], v150 offset:4672
	s_waitcnt lgkmcnt(5)
	v_mfma_f32_32x32x16_bf16 v[80:95], v[176:179], v[208:211], v[80:95]
	v_mfma_f32_32x32x16_bf16 v[16:31], v[180:183], v[208:211], v[16:31]
	ds_read_b128 v[208:211], v149 offset:64
	s_waitcnt lgkmcnt(5)
	v_mfma_f32_32x32x16_bf16 v[64:79], v[176:179], v[212:215], v[64:79]
	v_mfma_f32_32x32x16_bf16 v[0:15], v[180:183], v[212:215], v[0:15]
	ds_read_b128 v[212:215], v149 offset:4672
	global_load_dwordx4 v[176:179], v[132:133], off offset:2176
	global_load_dwordx4 v[180:183], v[134:135], off offset:2176
	s_waitcnt lgkmcnt(1)
	v_mfma_f32_32x32x16_bf16 v[112:127], v[168:171], v[208:211], v[112:127]
	v_mfma_f32_32x32x16_bf16 v[48:63], v[172:175], v[208:211], v[48:63]
	s_waitcnt lgkmcnt(0)
	v_mfma_f32_32x32x16_bf16 v[96:111], v[168:171], v[212:215], v[96:111]
	v_mfma_f32_32x32x16_bf16 v[32:47], v[172:175], v[212:215], v[32:47]
	ds_read_b128 v[208:211], v149 offset:9280
	ds_read_b128 v[212:215], v149 offset:13888
	s_waitcnt vmcnt(7)
	ds_write_b128 v148, v[160:163] offset:27648
	s_waitcnt vmcnt(6)
	ds_write_b128 v148, v[164:167] offset:64512
	ds_read_b128 v[160:163], v150 offset:96
	ds_read_b128 v[164:167], v150 offset:4704
	s_waitcnt lgkmcnt(5)
	v_mfma_f32_32x32x16_bf16 v[80:95], v[168:171], v[208:211], v[80:95]
	v_mfma_f32_32x32x16_bf16 v[16:31], v[172:175], v[208:211], v[16:31]
	ds_read_b128 v[208:211], v149 offset:96
	s_waitcnt lgkmcnt(5)
	v_mfma_f32_32x32x16_bf16 v[64:79], v[168:171], v[212:215], v[64:79]
	v_mfma_f32_32x32x16_bf16 v[0:15], v[172:175], v[212:215], v[0:15]
	ds_read_b128 v[212:215], v149 offset:4704
	global_load_dwordx4 v[168:171], v[144:145], off offset:2176
	global_load_dwordx4 v[172:175], v[146:147], off offset:2176
	s_waitcnt lgkmcnt(1)
	v_mfma_f32_32x32x16_bf16 v[112:127], v[160:163], v[208:211], v[112:127]
	v_mfma_f32_32x32x16_bf16 v[48:63], v[164:167], v[208:211], v[48:63]
	s_waitcnt lgkmcnt(0)
	v_mfma_f32_32x32x16_bf16 v[96:111], v[160:163], v[212:215], v[96:111]
	v_mfma_f32_32x32x16_bf16 v[32:47], v[164:167], v[212:215], v[32:47]
	ds_read_b128 v[208:211], v149 offset:9312
	ds_read_b128 v[212:215], v149 offset:13920
	s_waitcnt lgkmcnt(1)
	v_mfma_f32_32x32x16_bf16 v[80:95], v[160:163], v[208:211], v[80:95]
	v_mfma_f32_32x32x16_bf16 v[16:31], v[164:167], v[208:211], v[16:31]
	s_waitcnt lgkmcnt(0)
	v_mfma_f32_32x32x16_bf16 v[64:79], v[160:163], v[212:215], v[64:79]
	v_mfma_f32_32x32x16_bf16 v[0:15], v[164:167], v[212:215], v[0:15]
	s_setprio 0
	s_barrier
	global_load_dwordx4 v[160:163], v[136:137], off offset:2304
	global_load_dwordx4 v[164:167], v[138:139], off offset:2304
	s_waitcnt vmcnt(9)
	ds_write_b128 v192, v[184:187]
	s_waitcnt vmcnt(8)
	ds_write_b128 v159, v[188:191]
	ds_read_b128 v[184:187], v152 offset:36864
	ds_read_b128 v[188:191], v152 offset:41472
	ds_read_b128 v[208:211], v151
	ds_read_b128 v[212:215], v151 offset:4608
	s_setprio 1
	s_waitcnt lgkmcnt(1)
	v_mfma_f32_32x32x16_bf16 v[112:127], v[184:187], v[208:211], v[112:127]
	v_mfma_f32_32x32x16_bf16 v[48:63], v[188:191], v[208:211], v[48:63]
	s_waitcnt lgkmcnt(0)
	v_mfma_f32_32x32x16_bf16 v[96:111], v[184:187], v[212:215], v[96:111]
	v_mfma_f32_32x32x16_bf16 v[32:47], v[188:191], v[212:215], v[32:47]
	ds_read_b128 v[208:211], v151 offset:9216
	ds_read_b128 v[212:215], v151 offset:13824
	s_waitcnt vmcnt(7)
	ds_write_b128 v158, v[194:197]
	s_waitcnt vmcnt(6)
	ds_write_b128 v157, v[198:201]
	ds_read_b128 v[194:197], v152 offset:36896
	ds_read_b128 v[198:201], v152 offset:41504
	s_waitcnt lgkmcnt(5)
	v_mfma_f32_32x32x16_bf16 v[80:95], v[184:187], v[208:211], v[80:95]
	v_mfma_f32_32x32x16_bf16 v[16:31], v[188:191], v[208:211], v[16:31]
	ds_read_b128 v[208:211], v151 offset:32
	s_waitcnt lgkmcnt(5)
	v_mfma_f32_32x32x16_bf16 v[64:79], v[184:187], v[212:215], v[64:79]
	v_mfma_f32_32x32x16_bf16 v[0:15], v[188:191], v[212:215], v[0:15]
	ds_read_b128 v[212:215], v151 offset:4640
	global_load_dwordx4 v[184:187], v[140:141], off offset:2304
	global_load_dwordx4 v[188:191], v[142:143], off offset:2304
	s_waitcnt lgkmcnt(1)
	v_mfma_f32_32x32x16_bf16 v[112:127], v[194:197], v[208:211], v[112:127]
	v_mfma_f32_32x32x16_bf16 v[48:63], v[198:201], v[208:211], v[48:63]
	s_waitcnt lgkmcnt(0)
	v_mfma_f32_32x32x16_bf16 v[96:111], v[194:197], v[212:215], v[96:111]
	v_mfma_f32_32x32x16_bf16 v[32:47], v[198:201], v[212:215], v[32:47]
	ds_read_b128 v[208:211], v151 offset:9248
	ds_read_b128 v[212:215], v151 offset:13856
	s_waitcnt vmcnt(7)
	ds_write_b128 v154, v[176:179]
	s_waitcnt vmcnt(6)
	ds_write_b128 v153, v[180:183]
	ds_read_b128 v[176:179], v152 offset:36928
	ds_read_b128 v[180:183], v152 offset:41536
	s_waitcnt lgkmcnt(5)
	v_mfma_f32_32x32x16_bf16 v[80:95], v[194:197], v[208:211], v[80:95]
	v_mfma_f32_32x32x16_bf16 v[16:31], v[198:201], v[208:211], v[16:31]
	ds_read_b128 v[208:211], v151 offset:64
	s_waitcnt lgkmcnt(5)
	v_mfma_f32_32x32x16_bf16 v[64:79], v[194:197], v[212:215], v[64:79]
	v_mfma_f32_32x32x16_bf16 v[0:15], v[198:201], v[212:215], v[0:15]
	ds_read_b128 v[212:215], v151 offset:4672
	global_load_dwordx4 v[194:197], v[132:133], off offset:2304
	global_load_dwordx4 v[198:201], v[134:135], off offset:2304
	s_waitcnt lgkmcnt(1)
	v_mfma_f32_32x32x16_bf16 v[112:127], v[176:179], v[208:211], v[112:127]
	v_mfma_f32_32x32x16_bf16 v[48:63], v[180:183], v[208:211], v[48:63]
	s_waitcnt lgkmcnt(0)
	v_mfma_f32_32x32x16_bf16 v[96:111], v[176:179], v[212:215], v[96:111]
	v_mfma_f32_32x32x16_bf16 v[32:47], v[180:183], v[212:215], v[32:47]
	ds_read_b128 v[208:211], v151 offset:9280
	ds_read_b128 v[212:215], v151 offset:13888
	s_waitcnt vmcnt(7)
	ds_write_b128 v156, v[168:171]
	s_waitcnt vmcnt(6)
	ds_write_b128 v155, v[172:175]
	ds_read_b128 v[168:171], v152 offset:36960
	ds_read_b128 v[172:175], v152 offset:41568
	s_waitcnt lgkmcnt(5)
	v_mfma_f32_32x32x16_bf16 v[80:95], v[176:179], v[208:211], v[80:95]
	v_mfma_f32_32x32x16_bf16 v[16:31], v[180:183], v[208:211], v[16:31]
	ds_read_b128 v[208:211], v151 offset:96
	s_waitcnt lgkmcnt(5)
	v_mfma_f32_32x32x16_bf16 v[64:79], v[176:179], v[212:215], v[64:79]
	v_mfma_f32_32x32x16_bf16 v[0:15], v[180:183], v[212:215], v[0:15]
	ds_read_b128 v[212:215], v151 offset:4704
	global_load_dwordx4 v[176:179], v[144:145], off offset:2304
	global_load_dwordx4 v[180:183], v[146:147], off offset:2304
	s_waitcnt lgkmcnt(1)
	v_mfma_f32_32x32x16_bf16 v[112:127], v[168:171], v[208:211], v[112:127]
	v_mfma_f32_32x32x16_bf16 v[48:63], v[172:175], v[208:211], v[48:63]
	s_waitcnt lgkmcnt(0)
	v_mfma_f32_32x32x16_bf16 v[96:111], v[168:171], v[212:215], v[96:111]
	v_mfma_f32_32x32x16_bf16 v[32:47], v[172:175], v[212:215], v[32:47]
	ds_read_b128 v[208:211], v151 offset:9312
	ds_read_b128 v[212:215], v151 offset:13920
	s_waitcnt lgkmcnt(1)
	v_mfma_f32_32x32x16_bf16 v[80:95], v[168:171], v[208:211], v[80:95]
	v_mfma_f32_32x32x16_bf16 v[16:31], v[172:175], v[208:211], v[16:31]
	s_waitcnt lgkmcnt(0)
	v_mfma_f32_32x32x16_bf16 v[64:79], v[168:171], v[212:215], v[64:79]
	v_mfma_f32_32x32x16_bf16 v[0:15], v[172:175], v[212:215], v[0:15]
	s_setprio 0
	s_barrier
	global_load_dwordx4 v[168:171], v[136:137], off offset:2432
	global_load_dwordx4 v[172:175], v[138:139], off offset:2432
	s_waitcnt vmcnt(9)
	ds_write_b128 v148, v[160:163]
	s_waitcnt vmcnt(8)
	ds_write_b128 v148, v[164:167] offset:36864
	ds_read_b128 v[160:163], v150
	ds_read_b128 v[164:167], v150 offset:4608
	ds_read_b128 v[208:211], v149
	ds_read_b128 v[212:215], v149 offset:4608
	s_setprio 1
	s_waitcnt lgkmcnt(1)
	v_mfma_f32_32x32x16_bf16 v[112:127], v[160:163], v[208:211], v[112:127]
	v_mfma_f32_32x32x16_bf16 v[48:63], v[164:167], v[208:211], v[48:63]
	s_waitcnt lgkmcnt(0)
	v_mfma_f32_32x32x16_bf16 v[96:111], v[160:163], v[212:215], v[96:111]
	v_mfma_f32_32x32x16_bf16 v[32:47], v[164:167], v[212:215], v[32:47]
	ds_read_b128 v[208:211], v149 offset:9216
	ds_read_b128 v[212:215], v149 offset:13824
	s_waitcnt vmcnt(7)
	ds_write_b128 v148, v[184:187] offset:9216
	s_waitcnt vmcnt(6)
	ds_write_b128 v148, v[188:191] offset:46080
	ds_read_b128 v[184:187], v150 offset:32
	ds_read_b128 v[188:191], v150 offset:4640
	s_waitcnt lgkmcnt(5)
	v_mfma_f32_32x32x16_bf16 v[80:95], v[160:163], v[208:211], v[80:95]
	v_mfma_f32_32x32x16_bf16 v[16:31], v[164:167], v[208:211], v[16:31]
	ds_read_b128 v[208:211], v149 offset:32
	s_waitcnt lgkmcnt(5)
	v_mfma_f32_32x32x16_bf16 v[64:79], v[160:163], v[212:215], v[64:79]
	v_mfma_f32_32x32x16_bf16 v[0:15], v[164:167], v[212:215], v[0:15]
	ds_read_b128 v[212:215], v149 offset:4640
	global_load_dwordx4 v[160:163], v[140:141], off offset:2432
	global_load_dwordx4 v[164:167], v[142:143], off offset:2432
	s_waitcnt lgkmcnt(1)
	v_mfma_f32_32x32x16_bf16 v[112:127], v[184:187], v[208:211], v[112:127]
	v_mfma_f32_32x32x16_bf16 v[48:63], v[188:191], v[208:211], v[48:63]
	s_waitcnt lgkmcnt(0)
	v_mfma_f32_32x32x16_bf16 v[96:111], v[184:187], v[212:215], v[96:111]
	v_mfma_f32_32x32x16_bf16 v[32:47], v[188:191], v[212:215], v[32:47]
	ds_read_b128 v[208:211], v149 offset:9248
	ds_read_b128 v[212:215], v149 offset:13856
	s_waitcnt vmcnt(7)
	ds_write_b128 v148, v[194:197] offset:18432
	s_waitcnt vmcnt(6)
	ds_write_b128 v148, v[198:201] offset:55296
	ds_read_b128 v[194:197], v150 offset:64
	ds_read_b128 v[198:201], v150 offset:4672
	s_waitcnt lgkmcnt(5)
	v_mfma_f32_32x32x16_bf16 v[80:95], v[184:187], v[208:211], v[80:95]
	v_mfma_f32_32x32x16_bf16 v[16:31], v[188:191], v[208:211], v[16:31]
	ds_read_b128 v[208:211], v149 offset:64
	s_waitcnt lgkmcnt(5)
	v_mfma_f32_32x32x16_bf16 v[64:79], v[184:187], v[212:215], v[64:79]
	v_mfma_f32_32x32x16_bf16 v[0:15], v[188:191], v[212:215], v[0:15]
	ds_read_b128 v[212:215], v149 offset:4672
	global_load_dwordx4 v[184:187], v[132:133], off offset:2432
	global_load_dwordx4 v[188:191], v[134:135], off offset:2432
	s_waitcnt lgkmcnt(1)
	v_mfma_f32_32x32x16_bf16 v[112:127], v[194:197], v[208:211], v[112:127]
	v_mfma_f32_32x32x16_bf16 v[48:63], v[198:201], v[208:211], v[48:63]
	s_waitcnt lgkmcnt(0)
	v_mfma_f32_32x32x16_bf16 v[96:111], v[194:197], v[212:215], v[96:111]
	v_mfma_f32_32x32x16_bf16 v[32:47], v[198:201], v[212:215], v[32:47]
	ds_read_b128 v[208:211], v149 offset:9280
	ds_read_b128 v[212:215], v149 offset:13888
	s_waitcnt vmcnt(7)
	ds_write_b128 v148, v[176:179] offset:27648
	s_waitcnt vmcnt(6)
	ds_write_b128 v148, v[180:183] offset:64512
	ds_read_b128 v[176:179], v150 offset:96
	ds_read_b128 v[180:183], v150 offset:4704
	s_waitcnt lgkmcnt(5)
	v_mfma_f32_32x32x16_bf16 v[80:95], v[194:197], v[208:211], v[80:95]
	v_mfma_f32_32x32x16_bf16 v[16:31], v[198:201], v[208:211], v[16:31]
	ds_read_b128 v[208:211], v149 offset:96
	s_waitcnt lgkmcnt(5)
	v_mfma_f32_32x32x16_bf16 v[64:79], v[194:197], v[212:215], v[64:79]
	v_mfma_f32_32x32x16_bf16 v[0:15], v[198:201], v[212:215], v[0:15]
	ds_read_b128 v[212:215], v149 offset:4704
	global_load_dwordx4 v[194:197], v[144:145], off offset:2432
	global_load_dwordx4 v[198:201], v[146:147], off offset:2432
	s_waitcnt lgkmcnt(1)
	v_mfma_f32_32x32x16_bf16 v[112:127], v[176:179], v[208:211], v[112:127]
	v_mfma_f32_32x32x16_bf16 v[48:63], v[180:183], v[208:211], v[48:63]
	s_waitcnt lgkmcnt(0)
	v_mfma_f32_32x32x16_bf16 v[96:111], v[176:179], v[212:215], v[96:111]
	v_mfma_f32_32x32x16_bf16 v[32:47], v[180:183], v[212:215], v[32:47]
	ds_read_b128 v[208:211], v149 offset:9312
	ds_read_b128 v[212:215], v149 offset:13920
	s_waitcnt lgkmcnt(1)
	v_mfma_f32_32x32x16_bf16 v[80:95], v[176:179], v[208:211], v[80:95]
	v_mfma_f32_32x32x16_bf16 v[16:31], v[180:183], v[208:211], v[16:31]
	s_waitcnt lgkmcnt(0)
	v_mfma_f32_32x32x16_bf16 v[64:79], v[176:179], v[212:215], v[64:79]
	v_mfma_f32_32x32x16_bf16 v[0:15], v[180:183], v[212:215], v[0:15]
	s_setprio 0
	s_barrier
	global_load_dwordx4 v[176:179], v[136:137], off offset:2560
	global_load_dwordx4 v[180:183], v[138:139], off offset:2560
	s_waitcnt vmcnt(9)
	ds_write_b128 v192, v[168:171]
	s_waitcnt vmcnt(8)
	ds_write_b128 v159, v[172:175]
	ds_read_b128 v[168:171], v152 offset:36864
	ds_read_b128 v[172:175], v152 offset:41472
	ds_read_b128 v[208:211], v151
	ds_read_b128 v[212:215], v151 offset:4608
	s_setprio 1
	s_waitcnt lgkmcnt(1)
	v_mfma_f32_32x32x16_bf16 v[112:127], v[168:171], v[208:211], v[112:127]
	v_mfma_f32_32x32x16_bf16 v[48:63], v[172:175], v[208:211], v[48:63]
	s_waitcnt lgkmcnt(0)
	v_mfma_f32_32x32x16_bf16 v[96:111], v[168:171], v[212:215], v[96:111]
	v_mfma_f32_32x32x16_bf16 v[32:47], v[172:175], v[212:215], v[32:47]
	ds_read_b128 v[208:211], v151 offset:9216
	ds_read_b128 v[212:215], v151 offset:13824
	s_waitcnt vmcnt(7)
	ds_write_b128 v158, v[160:163]
	s_waitcnt vmcnt(6)
	ds_write_b128 v157, v[164:167]
	ds_read_b128 v[160:163], v152 offset:36896
	ds_read_b128 v[164:167], v152 offset:41504
	s_waitcnt lgkmcnt(5)
	v_mfma_f32_32x32x16_bf16 v[80:95], v[168:171], v[208:211], v[80:95]
	v_mfma_f32_32x32x16_bf16 v[16:31], v[172:175], v[208:211], v[16:31]
	ds_read_b128 v[208:211], v151 offset:32
	s_waitcnt lgkmcnt(5)
	v_mfma_f32_32x32x16_bf16 v[64:79], v[168:171], v[212:215], v[64:79]
	v_mfma_f32_32x32x16_bf16 v[0:15], v[172:175], v[212:215], v[0:15]
	ds_read_b128 v[212:215], v151 offset:4640
	global_load_dwordx4 v[168:171], v[140:141], off offset:2560
	global_load_dwordx4 v[172:175], v[142:143], off offset:2560
	s_waitcnt lgkmcnt(1)
	v_mfma_f32_32x32x16_bf16 v[112:127], v[160:163], v[208:211], v[112:127]
	v_mfma_f32_32x32x16_bf16 v[48:63], v[164:167], v[208:211], v[48:63]
	s_waitcnt lgkmcnt(0)
	v_mfma_f32_32x32x16_bf16 v[96:111], v[160:163], v[212:215], v[96:111]
	v_mfma_f32_32x32x16_bf16 v[32:47], v[164:167], v[212:215], v[32:47]
	ds_read_b128 v[208:211], v151 offset:9248
	ds_read_b128 v[212:215], v151 offset:13856
	s_waitcnt vmcnt(7)
	ds_write_b128 v154, v[184:187]
	s_waitcnt vmcnt(6)
	ds_write_b128 v153, v[188:191]
	ds_read_b128 v[184:187], v152 offset:36928
	ds_read_b128 v[188:191], v152 offset:41536
	s_waitcnt lgkmcnt(5)
	v_mfma_f32_32x32x16_bf16 v[80:95], v[160:163], v[208:211], v[80:95]
	v_mfma_f32_32x32x16_bf16 v[16:31], v[164:167], v[208:211], v[16:31]
	ds_read_b128 v[208:211], v151 offset:64
	s_waitcnt lgkmcnt(5)
	v_mfma_f32_32x32x16_bf16 v[64:79], v[160:163], v[212:215], v[64:79]
	v_mfma_f32_32x32x16_bf16 v[0:15], v[164:167], v[212:215], v[0:15]
	ds_read_b128 v[212:215], v151 offset:4672
	global_load_dwordx4 v[160:163], v[132:133], off offset:2560
	global_load_dwordx4 v[164:167], v[134:135], off offset:2560
	s_waitcnt lgkmcnt(1)
	v_mfma_f32_32x32x16_bf16 v[112:127], v[184:187], v[208:211], v[112:127]
	v_mfma_f32_32x32x16_bf16 v[48:63], v[188:191], v[208:211], v[48:63]
	s_waitcnt lgkmcnt(0)
	v_mfma_f32_32x32x16_bf16 v[96:111], v[184:187], v[212:215], v[96:111]
	v_mfma_f32_32x32x16_bf16 v[32:47], v[188:191], v[212:215], v[32:47]
	ds_read_b128 v[208:211], v151 offset:9280
	ds_read_b128 v[212:215], v151 offset:13888
	s_waitcnt vmcnt(7)
	ds_write_b128 v156, v[194:197]
	s_waitcnt vmcnt(6)
	ds_write_b128 v155, v[198:201]
	ds_read_b128 v[194:197], v152 offset:36960
	ds_read_b128 v[198:201], v152 offset:41568
	s_waitcnt lgkmcnt(5)
	v_mfma_f32_32x32x16_bf16 v[80:95], v[184:187], v[208:211], v[80:95]
	v_mfma_f32_32x32x16_bf16 v[16:31], v[188:191], v[208:211], v[16:31]
	ds_read_b128 v[208:211], v151 offset:96
	s_waitcnt lgkmcnt(5)
	v_mfma_f32_32x32x16_bf16 v[64:79], v[184:187], v[212:215], v[64:79]
	v_mfma_f32_32x32x16_bf16 v[0:15], v[188:191], v[212:215], v[0:15]
	ds_read_b128 v[212:215], v151 offset:4704
	global_load_dwordx4 v[184:187], v[144:145], off offset:2560
	global_load_dwordx4 v[188:191], v[146:147], off offset:2560
	s_waitcnt lgkmcnt(1)
	v_mfma_f32_32x32x16_bf16 v[112:127], v[194:197], v[208:211], v[112:127]
	v_mfma_f32_32x32x16_bf16 v[48:63], v[198:201], v[208:211], v[48:63]
	s_waitcnt lgkmcnt(0)
	v_mfma_f32_32x32x16_bf16 v[96:111], v[194:197], v[212:215], v[96:111]
	v_mfma_f32_32x32x16_bf16 v[32:47], v[198:201], v[212:215], v[32:47]
	ds_read_b128 v[208:211], v151 offset:9312
	ds_read_b128 v[212:215], v151 offset:13920
	s_waitcnt lgkmcnt(1)
	v_mfma_f32_32x32x16_bf16 v[80:95], v[194:197], v[208:211], v[80:95]
	v_mfma_f32_32x32x16_bf16 v[16:31], v[198:201], v[208:211], v[16:31]
	s_waitcnt lgkmcnt(0)
	v_mfma_f32_32x32x16_bf16 v[64:79], v[194:197], v[212:215], v[64:79]
	v_mfma_f32_32x32x16_bf16 v[0:15], v[198:201], v[212:215], v[0:15]
	s_setprio 0
	s_barrier
	global_load_dwordx4 v[194:197], v[136:137], off offset:2688
	global_load_dwordx4 v[198:201], v[138:139], off offset:2688
	s_waitcnt vmcnt(9)
	ds_write_b128 v148, v[176:179]
	s_waitcnt vmcnt(8)
	ds_write_b128 v148, v[180:183] offset:36864
	ds_read_b128 v[176:179], v150
	ds_read_b128 v[180:183], v150 offset:4608
	ds_read_b128 v[208:211], v149
	ds_read_b128 v[212:215], v149 offset:4608
	s_setprio 1
	s_waitcnt lgkmcnt(1)
	v_mfma_f32_32x32x16_bf16 v[112:127], v[176:179], v[208:211], v[112:127]
	v_mfma_f32_32x32x16_bf16 v[48:63], v[180:183], v[208:211], v[48:63]
	s_waitcnt lgkmcnt(0)
	v_mfma_f32_32x32x16_bf16 v[96:111], v[176:179], v[212:215], v[96:111]
	v_mfma_f32_32x32x16_bf16 v[32:47], v[180:183], v[212:215], v[32:47]
	ds_read_b128 v[208:211], v149 offset:9216
	ds_read_b128 v[212:215], v149 offset:13824
	s_waitcnt vmcnt(7)
	ds_write_b128 v148, v[168:171] offset:9216
	s_waitcnt vmcnt(6)
	ds_write_b128 v148, v[172:175] offset:46080
	ds_read_b128 v[168:171], v150 offset:32
	ds_read_b128 v[172:175], v150 offset:4640
	s_waitcnt lgkmcnt(5)
	v_mfma_f32_32x32x16_bf16 v[80:95], v[176:179], v[208:211], v[80:95]
	v_mfma_f32_32x32x16_bf16 v[16:31], v[180:183], v[208:211], v[16:31]
	ds_read_b128 v[208:211], v149 offset:32
	s_waitcnt lgkmcnt(5)
	v_mfma_f32_32x32x16_bf16 v[64:79], v[176:179], v[212:215], v[64:79]
	v_mfma_f32_32x32x16_bf16 v[0:15], v[180:183], v[212:215], v[0:15]
	ds_read_b128 v[212:215], v149 offset:4640
	global_load_dwordx4 v[176:179], v[140:141], off offset:2688
	global_load_dwordx4 v[180:183], v[142:143], off offset:2688
	s_waitcnt lgkmcnt(1)
	v_mfma_f32_32x32x16_bf16 v[112:127], v[168:171], v[208:211], v[112:127]
	v_mfma_f32_32x32x16_bf16 v[48:63], v[172:175], v[208:211], v[48:63]
	s_waitcnt lgkmcnt(0)
	v_mfma_f32_32x32x16_bf16 v[96:111], v[168:171], v[212:215], v[96:111]
	v_mfma_f32_32x32x16_bf16 v[32:47], v[172:175], v[212:215], v[32:47]
	ds_read_b128 v[208:211], v149 offset:9248
	ds_read_b128 v[212:215], v149 offset:13856
	s_waitcnt vmcnt(7)
	ds_write_b128 v148, v[160:163] offset:18432
	s_waitcnt vmcnt(6)
	ds_write_b128 v148, v[164:167] offset:55296
	ds_read_b128 v[160:163], v150 offset:64
	ds_read_b128 v[164:167], v150 offset:4672
	s_waitcnt lgkmcnt(5)
	v_mfma_f32_32x32x16_bf16 v[80:95], v[168:171], v[208:211], v[80:95]
	v_mfma_f32_32x32x16_bf16 v[16:31], v[172:175], v[208:211], v[16:31]
	ds_read_b128 v[208:211], v149 offset:64
	s_waitcnt lgkmcnt(5)
	v_mfma_f32_32x32x16_bf16 v[64:79], v[168:171], v[212:215], v[64:79]
	v_mfma_f32_32x32x16_bf16 v[0:15], v[172:175], v[212:215], v[0:15]
	ds_read_b128 v[212:215], v149 offset:4672
	global_load_dwordx4 v[168:171], v[132:133], off offset:2688
	global_load_dwordx4 v[172:175], v[134:135], off offset:2688
	s_waitcnt lgkmcnt(1)
	v_mfma_f32_32x32x16_bf16 v[112:127], v[160:163], v[208:211], v[112:127]
	v_mfma_f32_32x32x16_bf16 v[48:63], v[164:167], v[208:211], v[48:63]
	s_waitcnt lgkmcnt(0)
	v_mfma_f32_32x32x16_bf16 v[96:111], v[160:163], v[212:215], v[96:111]
	v_mfma_f32_32x32x16_bf16 v[32:47], v[164:167], v[212:215], v[32:47]
	ds_read_b128 v[208:211], v149 offset:9280
	ds_read_b128 v[212:215], v149 offset:13888
	s_waitcnt vmcnt(7)
	ds_write_b128 v148, v[184:187] offset:27648
	s_waitcnt vmcnt(6)
	ds_write_b128 v148, v[188:191] offset:64512
	ds_read_b128 v[184:187], v150 offset:96
	ds_read_b128 v[188:191], v150 offset:4704
	s_waitcnt lgkmcnt(5)
	v_mfma_f32_32x32x16_bf16 v[80:95], v[160:163], v[208:211], v[80:95]
	v_mfma_f32_32x32x16_bf16 v[16:31], v[164:167], v[208:211], v[16:31]
	ds_read_b128 v[208:211], v149 offset:96
	s_waitcnt lgkmcnt(5)
	v_mfma_f32_32x32x16_bf16 v[64:79], v[160:163], v[212:215], v[64:79]
	v_mfma_f32_32x32x16_bf16 v[0:15], v[164:167], v[212:215], v[0:15]
	ds_read_b128 v[212:215], v149 offset:4704
	global_load_dwordx4 v[160:163], v[144:145], off offset:2688
	global_load_dwordx4 v[164:167], v[146:147], off offset:2688
	s_waitcnt lgkmcnt(1)
	v_mfma_f32_32x32x16_bf16 v[112:127], v[184:187], v[208:211], v[112:127]
	v_mfma_f32_32x32x16_bf16 v[48:63], v[188:191], v[208:211], v[48:63]
	s_waitcnt lgkmcnt(0)
	v_mfma_f32_32x32x16_bf16 v[96:111], v[184:187], v[212:215], v[96:111]
	v_mfma_f32_32x32x16_bf16 v[32:47], v[188:191], v[212:215], v[32:47]
	ds_read_b128 v[208:211], v149 offset:9312
	ds_read_b128 v[212:215], v149 offset:13920
	s_waitcnt lgkmcnt(1)
	v_mfma_f32_32x32x16_bf16 v[80:95], v[184:187], v[208:211], v[80:95]
	v_mfma_f32_32x32x16_bf16 v[16:31], v[188:191], v[208:211], v[16:31]
	s_waitcnt lgkmcnt(0)
	v_mfma_f32_32x32x16_bf16 v[64:79], v[184:187], v[212:215], v[64:79]
	v_mfma_f32_32x32x16_bf16 v[0:15], v[188:191], v[212:215], v[0:15]
	s_setprio 0
	s_barrier
	global_load_dwordx4 v[184:187], v[136:137], off offset:2816
	global_load_dwordx4 v[188:191], v[138:139], off offset:2816
	s_waitcnt vmcnt(9)
	ds_write_b128 v192, v[194:197]
	s_waitcnt vmcnt(8)
	ds_write_b128 v159, v[198:201]
	ds_read_b128 v[194:197], v152 offset:36864
	ds_read_b128 v[198:201], v152 offset:41472
	ds_read_b128 v[208:211], v151
	ds_read_b128 v[212:215], v151 offset:4608
	s_setprio 1
	s_waitcnt lgkmcnt(1)
	v_mfma_f32_32x32x16_bf16 v[112:127], v[194:197], v[208:211], v[112:127]
	v_mfma_f32_32x32x16_bf16 v[48:63], v[198:201], v[208:211], v[48:63]
	s_waitcnt lgkmcnt(0)
	v_mfma_f32_32x32x16_bf16 v[96:111], v[194:197], v[212:215], v[96:111]
	v_mfma_f32_32x32x16_bf16 v[32:47], v[198:201], v[212:215], v[32:47]
	ds_read_b128 v[208:211], v151 offset:9216
	ds_read_b128 v[212:215], v151 offset:13824
	s_waitcnt vmcnt(7)
	ds_write_b128 v158, v[176:179]
	s_waitcnt vmcnt(6)
	ds_write_b128 v157, v[180:183]
	ds_read_b128 v[176:179], v152 offset:36896
	ds_read_b128 v[180:183], v152 offset:41504
	s_waitcnt lgkmcnt(5)
	v_mfma_f32_32x32x16_bf16 v[80:95], v[194:197], v[208:211], v[80:95]
	v_mfma_f32_32x32x16_bf16 v[16:31], v[198:201], v[208:211], v[16:31]
	ds_read_b128 v[208:211], v151 offset:32
	s_waitcnt lgkmcnt(5)
	v_mfma_f32_32x32x16_bf16 v[64:79], v[194:197], v[212:215], v[64:79]
	v_mfma_f32_32x32x16_bf16 v[0:15], v[198:201], v[212:215], v[0:15]
	ds_read_b128 v[212:215], v151 offset:4640
	global_load_dwordx4 v[194:197], v[140:141], off offset:2816
	global_load_dwordx4 v[198:201], v[142:143], off offset:2816
	s_waitcnt lgkmcnt(1)
	v_mfma_f32_32x32x16_bf16 v[112:127], v[176:179], v[208:211], v[112:127]
	v_mfma_f32_32x32x16_bf16 v[48:63], v[180:183], v[208:211], v[48:63]
	s_waitcnt lgkmcnt(0)
	v_mfma_f32_32x32x16_bf16 v[96:111], v[176:179], v[212:215], v[96:111]
	v_mfma_f32_32x32x16_bf16 v[32:47], v[180:183], v[212:215], v[32:47]
	ds_read_b128 v[208:211], v151 offset:9248
	ds_read_b128 v[212:215], v151 offset:13856
	s_waitcnt vmcnt(7)
	ds_write_b128 v154, v[168:171]
	s_waitcnt vmcnt(6)
	ds_write_b128 v153, v[172:175]
	ds_read_b128 v[168:171], v152 offset:36928
	ds_read_b128 v[172:175], v152 offset:41536
	s_waitcnt lgkmcnt(5)
	v_mfma_f32_32x32x16_bf16 v[80:95], v[176:179], v[208:211], v[80:95]
	v_mfma_f32_32x32x16_bf16 v[16:31], v[180:183], v[208:211], v[16:31]
	ds_read_b128 v[208:211], v151 offset:64
	s_waitcnt lgkmcnt(5)
	v_mfma_f32_32x32x16_bf16 v[64:79], v[176:179], v[212:215], v[64:79]
	v_mfma_f32_32x32x16_bf16 v[0:15], v[180:183], v[212:215], v[0:15]
	ds_read_b128 v[212:215], v151 offset:4672
	global_load_dwordx4 v[176:179], v[132:133], off offset:2816
	global_load_dwordx4 v[180:183], v[134:135], off offset:2816
	s_waitcnt lgkmcnt(1)
	v_mfma_f32_32x32x16_bf16 v[112:127], v[168:171], v[208:211], v[112:127]
	v_mfma_f32_32x32x16_bf16 v[48:63], v[172:175], v[208:211], v[48:63]
	s_waitcnt lgkmcnt(0)
	v_mfma_f32_32x32x16_bf16 v[96:111], v[168:171], v[212:215], v[96:111]
	v_mfma_f32_32x32x16_bf16 v[32:47], v[172:175], v[212:215], v[32:47]
	ds_read_b128 v[208:211], v151 offset:9280
	ds_read_b128 v[212:215], v151 offset:13888
	s_waitcnt vmcnt(7)
	ds_write_b128 v156, v[160:163]
	s_waitcnt vmcnt(6)
	ds_write_b128 v155, v[164:167]
	ds_read_b128 v[160:163], v152 offset:36960
	ds_read_b128 v[164:167], v152 offset:41568
	s_waitcnt lgkmcnt(5)
	v_mfma_f32_32x32x16_bf16 v[80:95], v[168:171], v[208:211], v[80:95]
	v_mfma_f32_32x32x16_bf16 v[16:31], v[172:175], v[208:211], v[16:31]
	ds_read_b128 v[208:211], v151 offset:96
	s_waitcnt lgkmcnt(5)
	v_mfma_f32_32x32x16_bf16 v[64:79], v[168:171], v[212:215], v[64:79]
	v_mfma_f32_32x32x16_bf16 v[0:15], v[172:175], v[212:215], v[0:15]
	ds_read_b128 v[212:215], v151 offset:4704
	global_load_dwordx4 v[168:171], v[144:145], off offset:2816
	global_load_dwordx4 v[172:175], v[146:147], off offset:2816
	s_waitcnt lgkmcnt(1)
	v_mfma_f32_32x32x16_bf16 v[112:127], v[160:163], v[208:211], v[112:127]
	v_mfma_f32_32x32x16_bf16 v[48:63], v[164:167], v[208:211], v[48:63]
	s_waitcnt lgkmcnt(0)
	v_mfma_f32_32x32x16_bf16 v[96:111], v[160:163], v[212:215], v[96:111]
	v_mfma_f32_32x32x16_bf16 v[32:47], v[164:167], v[212:215], v[32:47]
	ds_read_b128 v[208:211], v151 offset:9312
	ds_read_b128 v[212:215], v151 offset:13920
	s_waitcnt lgkmcnt(1)
	v_mfma_f32_32x32x16_bf16 v[80:95], v[160:163], v[208:211], v[80:95]
	v_mfma_f32_32x32x16_bf16 v[16:31], v[164:167], v[208:211], v[16:31]
	s_waitcnt lgkmcnt(0)
	v_mfma_f32_32x32x16_bf16 v[64:79], v[160:163], v[212:215], v[64:79]
	v_mfma_f32_32x32x16_bf16 v[0:15], v[164:167], v[212:215], v[0:15]
	s_setprio 0
	s_barrier
	global_load_dwordx4 v[160:163], v[136:137], off offset:2944
	global_load_dwordx4 v[164:167], v[138:139], off offset:2944
	s_waitcnt vmcnt(9)
	ds_write_b128 v148, v[184:187]
	s_waitcnt vmcnt(8)
	ds_write_b128 v148, v[188:191] offset:36864
	ds_read_b128 v[184:187], v150
	ds_read_b128 v[188:191], v150 offset:4608
	ds_read_b128 v[208:211], v149
	ds_read_b128 v[212:215], v149 offset:4608
	s_setprio 1
	s_waitcnt lgkmcnt(1)
	v_mfma_f32_32x32x16_bf16 v[112:127], v[184:187], v[208:211], v[112:127]
	v_mfma_f32_32x32x16_bf16 v[48:63], v[188:191], v[208:211], v[48:63]
	s_waitcnt lgkmcnt(0)
	v_mfma_f32_32x32x16_bf16 v[96:111], v[184:187], v[212:215], v[96:111]
	v_mfma_f32_32x32x16_bf16 v[32:47], v[188:191], v[212:215], v[32:47]
	ds_read_b128 v[208:211], v149 offset:9216
	ds_read_b128 v[212:215], v149 offset:13824
	s_waitcnt vmcnt(7)
	ds_write_b128 v148, v[194:197] offset:9216
	s_waitcnt vmcnt(6)
	ds_write_b128 v148, v[198:201] offset:46080
	ds_read_b128 v[194:197], v150 offset:32
	ds_read_b128 v[198:201], v150 offset:4640
	s_waitcnt lgkmcnt(5)
	v_mfma_f32_32x32x16_bf16 v[80:95], v[184:187], v[208:211], v[80:95]
	v_mfma_f32_32x32x16_bf16 v[16:31], v[188:191], v[208:211], v[16:31]
	ds_read_b128 v[208:211], v149 offset:32
	s_waitcnt lgkmcnt(5)
	v_mfma_f32_32x32x16_bf16 v[64:79], v[184:187], v[212:215], v[64:79]
	v_mfma_f32_32x32x16_bf16 v[0:15], v[188:191], v[212:215], v[0:15]
	ds_read_b128 v[212:215], v149 offset:4640
	global_load_dwordx4 v[184:187], v[140:141], off offset:2944
	global_load_dwordx4 v[188:191], v[142:143], off offset:2944
	s_waitcnt lgkmcnt(1)
	v_mfma_f32_32x32x16_bf16 v[112:127], v[194:197], v[208:211], v[112:127]
	v_mfma_f32_32x32x16_bf16 v[48:63], v[198:201], v[208:211], v[48:63]
	s_waitcnt lgkmcnt(0)
	v_mfma_f32_32x32x16_bf16 v[96:111], v[194:197], v[212:215], v[96:111]
	v_mfma_f32_32x32x16_bf16 v[32:47], v[198:201], v[212:215], v[32:47]
	ds_read_b128 v[208:211], v149 offset:9248
	ds_read_b128 v[212:215], v149 offset:13856
	s_waitcnt vmcnt(7)
	ds_write_b128 v148, v[176:179] offset:18432
	s_waitcnt vmcnt(6)
	ds_write_b128 v148, v[180:183] offset:55296
	ds_read_b128 v[176:179], v150 offset:64
	ds_read_b128 v[180:183], v150 offset:4672
	s_waitcnt lgkmcnt(5)
	v_mfma_f32_32x32x16_bf16 v[80:95], v[194:197], v[208:211], v[80:95]
	v_mfma_f32_32x32x16_bf16 v[16:31], v[198:201], v[208:211], v[16:31]
	ds_read_b128 v[208:211], v149 offset:64
	s_waitcnt lgkmcnt(5)
	v_mfma_f32_32x32x16_bf16 v[64:79], v[194:197], v[212:215], v[64:79]
	v_mfma_f32_32x32x16_bf16 v[0:15], v[198:201], v[212:215], v[0:15]
	ds_read_b128 v[212:215], v149 offset:4672
	global_load_dwordx4 v[194:197], v[132:133], off offset:2944
	global_load_dwordx4 v[198:201], v[134:135], off offset:2944
	s_waitcnt lgkmcnt(1)
	v_mfma_f32_32x32x16_bf16 v[112:127], v[176:179], v[208:211], v[112:127]
	v_mfma_f32_32x32x16_bf16 v[48:63], v[180:183], v[208:211], v[48:63]
	s_waitcnt lgkmcnt(0)
	v_mfma_f32_32x32x16_bf16 v[96:111], v[176:179], v[212:215], v[96:111]
	v_mfma_f32_32x32x16_bf16 v[32:47], v[180:183], v[212:215], v[32:47]
	ds_read_b128 v[208:211], v149 offset:9280
	ds_read_b128 v[212:215], v149 offset:13888
	s_waitcnt vmcnt(7)
	ds_write_b128 v148, v[168:171] offset:27648
	s_waitcnt vmcnt(6)
	ds_write_b128 v148, v[172:175] offset:64512
	ds_read_b128 v[168:171], v150 offset:96
	ds_read_b128 v[172:175], v150 offset:4704
	s_waitcnt lgkmcnt(5)
	v_mfma_f32_32x32x16_bf16 v[80:95], v[176:179], v[208:211], v[80:95]
	v_mfma_f32_32x32x16_bf16 v[16:31], v[180:183], v[208:211], v[16:31]
	ds_read_b128 v[208:211], v149 offset:96
	s_waitcnt lgkmcnt(5)
	v_mfma_f32_32x32x16_bf16 v[64:79], v[176:179], v[212:215], v[64:79]
	v_mfma_f32_32x32x16_bf16 v[0:15], v[180:183], v[212:215], v[0:15]
	ds_read_b128 v[212:215], v149 offset:4704
	global_load_dwordx4 v[176:179], v[144:145], off offset:2944
	global_load_dwordx4 v[180:183], v[146:147], off offset:2944
	s_waitcnt lgkmcnt(1)
	v_mfma_f32_32x32x16_bf16 v[112:127], v[168:171], v[208:211], v[112:127]
	v_mfma_f32_32x32x16_bf16 v[48:63], v[172:175], v[208:211], v[48:63]
	s_waitcnt lgkmcnt(0)
	v_mfma_f32_32x32x16_bf16 v[96:111], v[168:171], v[212:215], v[96:111]
	v_mfma_f32_32x32x16_bf16 v[32:47], v[172:175], v[212:215], v[32:47]
	ds_read_b128 v[208:211], v149 offset:9312
	ds_read_b128 v[212:215], v149 offset:13920
	s_waitcnt lgkmcnt(1)
	v_mfma_f32_32x32x16_bf16 v[80:95], v[168:171], v[208:211], v[80:95]
	v_mfma_f32_32x32x16_bf16 v[16:31], v[172:175], v[208:211], v[16:31]
	s_waitcnt lgkmcnt(0)
	v_mfma_f32_32x32x16_bf16 v[64:79], v[168:171], v[212:215], v[64:79]
	v_mfma_f32_32x32x16_bf16 v[0:15], v[172:175], v[212:215], v[0:15]
	s_setprio 0
	s_barrier
	global_load_dwordx4 v[168:171], v[136:137], off offset:3072
	global_load_dwordx4 v[172:175], v[138:139], off offset:3072
	s_waitcnt vmcnt(9)
	ds_write_b128 v192, v[160:163]
	s_waitcnt vmcnt(8)
	ds_write_b128 v159, v[164:167]
	ds_read_b128 v[160:163], v152 offset:36864
	ds_read_b128 v[164:167], v152 offset:41472
	ds_read_b128 v[208:211], v151
	ds_read_b128 v[212:215], v151 offset:4608
	s_setprio 1
	s_waitcnt lgkmcnt(1)
	v_mfma_f32_32x32x16_bf16 v[112:127], v[160:163], v[208:211], v[112:127]
	v_mfma_f32_32x32x16_bf16 v[48:63], v[164:167], v[208:211], v[48:63]
	s_waitcnt lgkmcnt(0)
	v_mfma_f32_32x32x16_bf16 v[96:111], v[160:163], v[212:215], v[96:111]
	v_mfma_f32_32x32x16_bf16 v[32:47], v[164:167], v[212:215], v[32:47]
	ds_read_b128 v[208:211], v151 offset:9216
	ds_read_b128 v[212:215], v151 offset:13824
	s_waitcnt vmcnt(7)
	ds_write_b128 v158, v[184:187]
	s_waitcnt vmcnt(6)
	ds_write_b128 v157, v[188:191]
	ds_read_b128 v[184:187], v152 offset:36896
	ds_read_b128 v[188:191], v152 offset:41504
	s_waitcnt lgkmcnt(5)
	v_mfma_f32_32x32x16_bf16 v[80:95], v[160:163], v[208:211], v[80:95]
	v_mfma_f32_32x32x16_bf16 v[16:31], v[164:167], v[208:211], v[16:31]
	ds_read_b128 v[208:211], v151 offset:32
	s_waitcnt lgkmcnt(5)
	v_mfma_f32_32x32x16_bf16 v[64:79], v[160:163], v[212:215], v[64:79]
	v_mfma_f32_32x32x16_bf16 v[0:15], v[164:167], v[212:215], v[0:15]
	ds_read_b128 v[212:215], v151 offset:4640
	global_load_dwordx4 v[160:163], v[140:141], off offset:3072
	global_load_dwordx4 v[164:167], v[142:143], off offset:3072
	s_waitcnt lgkmcnt(1)
	v_mfma_f32_32x32x16_bf16 v[112:127], v[184:187], v[208:211], v[112:127]
	v_mfma_f32_32x32x16_bf16 v[48:63], v[188:191], v[208:211], v[48:63]
	s_waitcnt lgkmcnt(0)
	v_mfma_f32_32x32x16_bf16 v[96:111], v[184:187], v[212:215], v[96:111]
	v_mfma_f32_32x32x16_bf16 v[32:47], v[188:191], v[212:215], v[32:47]
	ds_read_b128 v[208:211], v151 offset:9248
	ds_read_b128 v[212:215], v151 offset:13856
	s_waitcnt vmcnt(7)
	ds_write_b128 v154, v[194:197]
	s_waitcnt vmcnt(6)
	ds_write_b128 v153, v[198:201]
	ds_read_b128 v[194:197], v152 offset:36928
	ds_read_b128 v[198:201], v152 offset:41536
	s_waitcnt lgkmcnt(5)
	v_mfma_f32_32x32x16_bf16 v[80:95], v[184:187], v[208:211], v[80:95]
	v_mfma_f32_32x32x16_bf16 v[16:31], v[188:191], v[208:211], v[16:31]
	ds_read_b128 v[208:211], v151 offset:64
	s_waitcnt lgkmcnt(5)
	v_mfma_f32_32x32x16_bf16 v[64:79], v[184:187], v[212:215], v[64:79]
	v_mfma_f32_32x32x16_bf16 v[0:15], v[188:191], v[212:215], v[0:15]
	ds_read_b128 v[212:215], v151 offset:4672
	global_load_dwordx4 v[184:187], v[132:133], off offset:3072
	global_load_dwordx4 v[188:191], v[134:135], off offset:3072
	s_waitcnt lgkmcnt(1)
	v_mfma_f32_32x32x16_bf16 v[112:127], v[194:197], v[208:211], v[112:127]
	v_mfma_f32_32x32x16_bf16 v[48:63], v[198:201], v[208:211], v[48:63]
	s_waitcnt lgkmcnt(0)
	v_mfma_f32_32x32x16_bf16 v[96:111], v[194:197], v[212:215], v[96:111]
	v_mfma_f32_32x32x16_bf16 v[32:47], v[198:201], v[212:215], v[32:47]
	ds_read_b128 v[208:211], v151 offset:9280
	ds_read_b128 v[212:215], v151 offset:13888
	s_waitcnt vmcnt(7)
	ds_write_b128 v156, v[176:179]
	s_waitcnt vmcnt(6)
	ds_write_b128 v155, v[180:183]
	ds_read_b128 v[176:179], v152 offset:36960
	ds_read_b128 v[180:183], v152 offset:41568
	s_waitcnt lgkmcnt(5)
	v_mfma_f32_32x32x16_bf16 v[80:95], v[194:197], v[208:211], v[80:95]
	v_mfma_f32_32x32x16_bf16 v[16:31], v[198:201], v[208:211], v[16:31]
	ds_read_b128 v[208:211], v151 offset:96
	s_waitcnt lgkmcnt(5)
	v_mfma_f32_32x32x16_bf16 v[64:79], v[194:197], v[212:215], v[64:79]
	v_mfma_f32_32x32x16_bf16 v[0:15], v[198:201], v[212:215], v[0:15]
	ds_read_b128 v[212:215], v151 offset:4704
	global_load_dwordx4 v[194:197], v[144:145], off offset:3072
	global_load_dwordx4 v[198:201], v[146:147], off offset:3072
	s_waitcnt lgkmcnt(1)
	v_mfma_f32_32x32x16_bf16 v[112:127], v[176:179], v[208:211], v[112:127]
	v_mfma_f32_32x32x16_bf16 v[48:63], v[180:183], v[208:211], v[48:63]
	s_waitcnt lgkmcnt(0)
	v_mfma_f32_32x32x16_bf16 v[96:111], v[176:179], v[212:215], v[96:111]
	v_mfma_f32_32x32x16_bf16 v[32:47], v[180:183], v[212:215], v[32:47]
	ds_read_b128 v[208:211], v151 offset:9312
	ds_read_b128 v[212:215], v151 offset:13920
	s_waitcnt lgkmcnt(1)
	v_mfma_f32_32x32x16_bf16 v[80:95], v[176:179], v[208:211], v[80:95]
	v_mfma_f32_32x32x16_bf16 v[16:31], v[180:183], v[208:211], v[16:31]
	s_waitcnt lgkmcnt(0)
	v_mfma_f32_32x32x16_bf16 v[64:79], v[176:179], v[212:215], v[64:79]
	v_mfma_f32_32x32x16_bf16 v[0:15], v[180:183], v[212:215], v[0:15]
	s_setprio 0
	s_barrier
	global_load_dwordx4 v[176:179], v[136:137], off offset:3200
	global_load_dwordx4 v[180:183], v[138:139], off offset:3200
	s_waitcnt vmcnt(9)
	ds_write_b128 v148, v[168:171]
	s_waitcnt vmcnt(8)
	ds_write_b128 v148, v[172:175] offset:36864
	ds_read_b128 v[168:171], v150
	ds_read_b128 v[172:175], v150 offset:4608
	ds_read_b128 v[208:211], v149
	ds_read_b128 v[212:215], v149 offset:4608
	s_setprio 1
	s_waitcnt lgkmcnt(1)
	v_mfma_f32_32x32x16_bf16 v[112:127], v[168:171], v[208:211], v[112:127]
	v_mfma_f32_32x32x16_bf16 v[48:63], v[172:175], v[208:211], v[48:63]
	s_waitcnt lgkmcnt(0)
	v_mfma_f32_32x32x16_bf16 v[96:111], v[168:171], v[212:215], v[96:111]
	v_mfma_f32_32x32x16_bf16 v[32:47], v[172:175], v[212:215], v[32:47]
	ds_read_b128 v[208:211], v149 offset:9216
	ds_read_b128 v[212:215], v149 offset:13824
	s_waitcnt vmcnt(7)
	ds_write_b128 v148, v[160:163] offset:9216
	s_waitcnt vmcnt(6)
	ds_write_b128 v148, v[164:167] offset:46080
	ds_read_b128 v[160:163], v150 offset:32
	ds_read_b128 v[164:167], v150 offset:4640
	s_waitcnt lgkmcnt(5)
	v_mfma_f32_32x32x16_bf16 v[80:95], v[168:171], v[208:211], v[80:95]
	v_mfma_f32_32x32x16_bf16 v[16:31], v[172:175], v[208:211], v[16:31]
	ds_read_b128 v[208:211], v149 offset:32
	s_waitcnt lgkmcnt(5)
	v_mfma_f32_32x32x16_bf16 v[64:79], v[168:171], v[212:215], v[64:79]
	v_mfma_f32_32x32x16_bf16 v[0:15], v[172:175], v[212:215], v[0:15]
	ds_read_b128 v[212:215], v149 offset:4640
	global_load_dwordx4 v[168:171], v[140:141], off offset:3200
	global_load_dwordx4 v[172:175], v[142:143], off offset:3200
	s_waitcnt lgkmcnt(1)
	v_mfma_f32_32x32x16_bf16 v[112:127], v[160:163], v[208:211], v[112:127]
	v_mfma_f32_32x32x16_bf16 v[48:63], v[164:167], v[208:211], v[48:63]
	s_waitcnt lgkmcnt(0)
	v_mfma_f32_32x32x16_bf16 v[96:111], v[160:163], v[212:215], v[96:111]
	v_mfma_f32_32x32x16_bf16 v[32:47], v[164:167], v[212:215], v[32:47]
	ds_read_b128 v[208:211], v149 offset:9248
	ds_read_b128 v[212:215], v149 offset:13856
	s_waitcnt vmcnt(7)
	ds_write_b128 v148, v[184:187] offset:18432
	s_waitcnt vmcnt(6)
	ds_write_b128 v148, v[188:191] offset:55296
	ds_read_b128 v[184:187], v150 offset:64
	ds_read_b128 v[188:191], v150 offset:4672
	s_waitcnt lgkmcnt(5)
	v_mfma_f32_32x32x16_bf16 v[80:95], v[160:163], v[208:211], v[80:95]
	v_mfma_f32_32x32x16_bf16 v[16:31], v[164:167], v[208:211], v[16:31]
	ds_read_b128 v[208:211], v149 offset:64
	s_waitcnt lgkmcnt(5)
	v_mfma_f32_32x32x16_bf16 v[64:79], v[160:163], v[212:215], v[64:79]
	v_mfma_f32_32x32x16_bf16 v[0:15], v[164:167], v[212:215], v[0:15]
	ds_read_b128 v[212:215], v149 offset:4672
	global_load_dwordx4 v[160:163], v[132:133], off offset:3200
	global_load_dwordx4 v[164:167], v[134:135], off offset:3200
	s_waitcnt lgkmcnt(1)
	v_mfma_f32_32x32x16_bf16 v[112:127], v[184:187], v[208:211], v[112:127]
	v_mfma_f32_32x32x16_bf16 v[48:63], v[188:191], v[208:211], v[48:63]
	s_waitcnt lgkmcnt(0)
	v_mfma_f32_32x32x16_bf16 v[96:111], v[184:187], v[212:215], v[96:111]
	v_mfma_f32_32x32x16_bf16 v[32:47], v[188:191], v[212:215], v[32:47]
	ds_read_b128 v[208:211], v149 offset:9280
	ds_read_b128 v[212:215], v149 offset:13888
	s_waitcnt vmcnt(7)
	ds_write_b128 v148, v[194:197] offset:27648
	s_waitcnt vmcnt(6)
	ds_write_b128 v148, v[198:201] offset:64512
	ds_read_b128 v[194:197], v150 offset:96
	ds_read_b128 v[198:201], v150 offset:4704
	s_waitcnt lgkmcnt(5)
	v_mfma_f32_32x32x16_bf16 v[80:95], v[184:187], v[208:211], v[80:95]
	v_mfma_f32_32x32x16_bf16 v[16:31], v[188:191], v[208:211], v[16:31]
	ds_read_b128 v[208:211], v149 offset:96
	s_waitcnt lgkmcnt(5)
	v_mfma_f32_32x32x16_bf16 v[64:79], v[184:187], v[212:215], v[64:79]
	v_mfma_f32_32x32x16_bf16 v[0:15], v[188:191], v[212:215], v[0:15]
	ds_read_b128 v[212:215], v149 offset:4704
	global_load_dwordx4 v[184:187], v[144:145], off offset:3200
	global_load_dwordx4 v[188:191], v[146:147], off offset:3200
	s_waitcnt lgkmcnt(1)
	v_mfma_f32_32x32x16_bf16 v[112:127], v[194:197], v[208:211], v[112:127]
	v_mfma_f32_32x32x16_bf16 v[48:63], v[198:201], v[208:211], v[48:63]
	s_waitcnt lgkmcnt(0)
	v_mfma_f32_32x32x16_bf16 v[96:111], v[194:197], v[212:215], v[96:111]
	v_mfma_f32_32x32x16_bf16 v[32:47], v[198:201], v[212:215], v[32:47]
	ds_read_b128 v[208:211], v149 offset:9312
	ds_read_b128 v[212:215], v149 offset:13920
	s_waitcnt lgkmcnt(1)
	v_mfma_f32_32x32x16_bf16 v[80:95], v[194:197], v[208:211], v[80:95]
	v_mfma_f32_32x32x16_bf16 v[16:31], v[198:201], v[208:211], v[16:31]
	s_waitcnt lgkmcnt(0)
	v_mfma_f32_32x32x16_bf16 v[64:79], v[194:197], v[212:215], v[64:79]
	v_mfma_f32_32x32x16_bf16 v[0:15], v[198:201], v[212:215], v[0:15]
	s_setprio 0
	s_barrier
	global_load_dwordx4 v[194:197], v[136:137], off offset:3328
	global_load_dwordx4 v[198:201], v[138:139], off offset:3328
	s_waitcnt vmcnt(9)
	ds_write_b128 v192, v[176:179]
	s_waitcnt vmcnt(8)
	ds_write_b128 v159, v[180:183]
	ds_read_b128 v[176:179], v152 offset:36864
	ds_read_b128 v[180:183], v152 offset:41472
	ds_read_b128 v[208:211], v151
	ds_read_b128 v[212:215], v151 offset:4608
	s_setprio 1
	s_waitcnt lgkmcnt(1)
	v_mfma_f32_32x32x16_bf16 v[112:127], v[176:179], v[208:211], v[112:127]
	v_mfma_f32_32x32x16_bf16 v[48:63], v[180:183], v[208:211], v[48:63]
	s_waitcnt lgkmcnt(0)
	v_mfma_f32_32x32x16_bf16 v[96:111], v[176:179], v[212:215], v[96:111]
	v_mfma_f32_32x32x16_bf16 v[32:47], v[180:183], v[212:215], v[32:47]
	ds_read_b128 v[208:211], v151 offset:9216
	ds_read_b128 v[212:215], v151 offset:13824
	s_waitcnt vmcnt(7)
	ds_write_b128 v158, v[168:171]
	s_waitcnt vmcnt(6)
	ds_write_b128 v157, v[172:175]
	ds_read_b128 v[168:171], v152 offset:36896
	ds_read_b128 v[172:175], v152 offset:41504
	s_waitcnt lgkmcnt(5)
	v_mfma_f32_32x32x16_bf16 v[80:95], v[176:179], v[208:211], v[80:95]
	v_mfma_f32_32x32x16_bf16 v[16:31], v[180:183], v[208:211], v[16:31]
	ds_read_b128 v[208:211], v151 offset:32
	s_waitcnt lgkmcnt(5)
	v_mfma_f32_32x32x16_bf16 v[64:79], v[176:179], v[212:215], v[64:79]
	v_mfma_f32_32x32x16_bf16 v[0:15], v[180:183], v[212:215], v[0:15]
	ds_read_b128 v[212:215], v151 offset:4640
	global_load_dwordx4 v[176:179], v[140:141], off offset:3328
	global_load_dwordx4 v[180:183], v[142:143], off offset:3328
	s_waitcnt lgkmcnt(1)
	v_mfma_f32_32x32x16_bf16 v[112:127], v[168:171], v[208:211], v[112:127]
	v_mfma_f32_32x32x16_bf16 v[48:63], v[172:175], v[208:211], v[48:63]
	s_waitcnt lgkmcnt(0)
	v_mfma_f32_32x32x16_bf16 v[96:111], v[168:171], v[212:215], v[96:111]
	v_mfma_f32_32x32x16_bf16 v[32:47], v[172:175], v[212:215], v[32:47]
	ds_read_b128 v[208:211], v151 offset:9248
	ds_read_b128 v[212:215], v151 offset:13856
	s_waitcnt vmcnt(7)
	ds_write_b128 v154, v[160:163]
	s_waitcnt vmcnt(6)
	ds_write_b128 v153, v[164:167]
	ds_read_b128 v[160:163], v152 offset:36928
	ds_read_b128 v[164:167], v152 offset:41536
	s_waitcnt lgkmcnt(5)
	v_mfma_f32_32x32x16_bf16 v[80:95], v[168:171], v[208:211], v[80:95]
	v_mfma_f32_32x32x16_bf16 v[16:31], v[172:175], v[208:211], v[16:31]
	ds_read_b128 v[208:211], v151 offset:64
	s_waitcnt lgkmcnt(5)
	v_mfma_f32_32x32x16_bf16 v[64:79], v[168:171], v[212:215], v[64:79]
	v_mfma_f32_32x32x16_bf16 v[0:15], v[172:175], v[212:215], v[0:15]
	ds_read_b128 v[212:215], v151 offset:4672
	global_load_dwordx4 v[168:171], v[132:133], off offset:3328
	global_load_dwordx4 v[172:175], v[134:135], off offset:3328
	s_waitcnt lgkmcnt(1)
	v_mfma_f32_32x32x16_bf16 v[112:127], v[160:163], v[208:211], v[112:127]
	v_mfma_f32_32x32x16_bf16 v[48:63], v[164:167], v[208:211], v[48:63]
	s_waitcnt lgkmcnt(0)
	v_mfma_f32_32x32x16_bf16 v[96:111], v[160:163], v[212:215], v[96:111]
	v_mfma_f32_32x32x16_bf16 v[32:47], v[164:167], v[212:215], v[32:47]
	ds_read_b128 v[208:211], v151 offset:9280
	ds_read_b128 v[212:215], v151 offset:13888
	s_waitcnt vmcnt(7)
	ds_write_b128 v156, v[184:187]
	s_waitcnt vmcnt(6)
	ds_write_b128 v155, v[188:191]
	ds_read_b128 v[184:187], v152 offset:36960
	ds_read_b128 v[188:191], v152 offset:41568
	s_waitcnt lgkmcnt(5)
	v_mfma_f32_32x32x16_bf16 v[80:95], v[160:163], v[208:211], v[80:95]
	v_mfma_f32_32x32x16_bf16 v[16:31], v[164:167], v[208:211], v[16:31]
	ds_read_b128 v[208:211], v151 offset:96
	s_waitcnt lgkmcnt(5)
	v_mfma_f32_32x32x16_bf16 v[64:79], v[160:163], v[212:215], v[64:79]
	v_mfma_f32_32x32x16_bf16 v[0:15], v[164:167], v[212:215], v[0:15]
	ds_read_b128 v[212:215], v151 offset:4704
	global_load_dwordx4 v[160:163], v[144:145], off offset:3328
	global_load_dwordx4 v[164:167], v[146:147], off offset:3328
	s_waitcnt lgkmcnt(1)
	v_mfma_f32_32x32x16_bf16 v[112:127], v[184:187], v[208:211], v[112:127]
	v_mfma_f32_32x32x16_bf16 v[48:63], v[188:191], v[208:211], v[48:63]
	s_waitcnt lgkmcnt(0)
	v_mfma_f32_32x32x16_bf16 v[96:111], v[184:187], v[212:215], v[96:111]
	v_mfma_f32_32x32x16_bf16 v[32:47], v[188:191], v[212:215], v[32:47]
	ds_read_b128 v[208:211], v151 offset:9312
	ds_read_b128 v[212:215], v151 offset:13920
	s_waitcnt lgkmcnt(1)
	v_mfma_f32_32x32x16_bf16 v[80:95], v[184:187], v[208:211], v[80:95]
	v_mfma_f32_32x32x16_bf16 v[16:31], v[188:191], v[208:211], v[16:31]
	s_waitcnt lgkmcnt(0)
	v_mfma_f32_32x32x16_bf16 v[64:79], v[184:187], v[212:215], v[64:79]
	v_mfma_f32_32x32x16_bf16 v[0:15], v[188:191], v[212:215], v[0:15]
	s_setprio 0
	s_barrier
	global_load_dwordx4 v[184:187], v[136:137], off offset:3456
	global_load_dwordx4 v[188:191], v[138:139], off offset:3456
	s_waitcnt vmcnt(9)
	ds_write_b128 v148, v[194:197]
	s_waitcnt vmcnt(8)
	ds_write_b128 v148, v[198:201] offset:36864
	ds_read_b128 v[194:197], v150
	ds_read_b128 v[198:201], v150 offset:4608
	ds_read_b128 v[208:211], v149
	ds_read_b128 v[212:215], v149 offset:4608
	s_setprio 1
	s_waitcnt lgkmcnt(1)
	v_mfma_f32_32x32x16_bf16 v[112:127], v[194:197], v[208:211], v[112:127]
	v_mfma_f32_32x32x16_bf16 v[48:63], v[198:201], v[208:211], v[48:63]
	s_waitcnt lgkmcnt(0)
	v_mfma_f32_32x32x16_bf16 v[96:111], v[194:197], v[212:215], v[96:111]
	v_mfma_f32_32x32x16_bf16 v[32:47], v[198:201], v[212:215], v[32:47]
	ds_read_b128 v[208:211], v149 offset:9216
	ds_read_b128 v[212:215], v149 offset:13824
	s_waitcnt vmcnt(7)
	ds_write_b128 v148, v[176:179] offset:9216
	s_waitcnt vmcnt(6)
	ds_write_b128 v148, v[180:183] offset:46080
	ds_read_b128 v[176:179], v150 offset:32
	ds_read_b128 v[180:183], v150 offset:4640
	s_waitcnt lgkmcnt(5)
	v_mfma_f32_32x32x16_bf16 v[80:95], v[194:197], v[208:211], v[80:95]
	v_mfma_f32_32x32x16_bf16 v[16:31], v[198:201], v[208:211], v[16:31]
	ds_read_b128 v[208:211], v149 offset:32
	s_waitcnt lgkmcnt(5)
	v_mfma_f32_32x32x16_bf16 v[64:79], v[194:197], v[212:215], v[64:79]
	v_mfma_f32_32x32x16_bf16 v[0:15], v[198:201], v[212:215], v[0:15]
	ds_read_b128 v[212:215], v149 offset:4640
	global_load_dwordx4 v[194:197], v[140:141], off offset:3456
	global_load_dwordx4 v[198:201], v[142:143], off offset:3456
	s_waitcnt lgkmcnt(1)
	v_mfma_f32_32x32x16_bf16 v[112:127], v[176:179], v[208:211], v[112:127]
	v_mfma_f32_32x32x16_bf16 v[48:63], v[180:183], v[208:211], v[48:63]
	s_waitcnt lgkmcnt(0)
	v_mfma_f32_32x32x16_bf16 v[96:111], v[176:179], v[212:215], v[96:111]
	v_mfma_f32_32x32x16_bf16 v[32:47], v[180:183], v[212:215], v[32:47]
	ds_read_b128 v[208:211], v149 offset:9248
	ds_read_b128 v[212:215], v149 offset:13856
	s_waitcnt vmcnt(7)
	ds_write_b128 v148, v[168:171] offset:18432
	s_waitcnt vmcnt(6)
	ds_write_b128 v148, v[172:175] offset:55296
	ds_read_b128 v[168:171], v150 offset:64
	ds_read_b128 v[172:175], v150 offset:4672
	s_waitcnt lgkmcnt(5)
	v_mfma_f32_32x32x16_bf16 v[80:95], v[176:179], v[208:211], v[80:95]
	v_mfma_f32_32x32x16_bf16 v[16:31], v[180:183], v[208:211], v[16:31]
	ds_read_b128 v[208:211], v149 offset:64
	s_waitcnt lgkmcnt(5)
	v_mfma_f32_32x32x16_bf16 v[64:79], v[176:179], v[212:215], v[64:79]
	v_mfma_f32_32x32x16_bf16 v[0:15], v[180:183], v[212:215], v[0:15]
	ds_read_b128 v[212:215], v149 offset:4672
	global_load_dwordx4 v[176:179], v[132:133], off offset:3456
	global_load_dwordx4 v[180:183], v[134:135], off offset:3456
	s_waitcnt lgkmcnt(1)
	v_mfma_f32_32x32x16_bf16 v[112:127], v[168:171], v[208:211], v[112:127]
	v_mfma_f32_32x32x16_bf16 v[48:63], v[172:175], v[208:211], v[48:63]
	s_waitcnt lgkmcnt(0)
	v_mfma_f32_32x32x16_bf16 v[96:111], v[168:171], v[212:215], v[96:111]
	v_mfma_f32_32x32x16_bf16 v[32:47], v[172:175], v[212:215], v[32:47]
	ds_read_b128 v[208:211], v149 offset:9280
	ds_read_b128 v[212:215], v149 offset:13888
	s_waitcnt vmcnt(7)
	ds_write_b128 v148, v[160:163] offset:27648
	s_waitcnt vmcnt(6)
	ds_write_b128 v148, v[164:167] offset:64512
	ds_read_b128 v[160:163], v150 offset:96
	ds_read_b128 v[164:167], v150 offset:4704
	s_waitcnt lgkmcnt(5)
	v_mfma_f32_32x32x16_bf16 v[80:95], v[168:171], v[208:211], v[80:95]
	v_mfma_f32_32x32x16_bf16 v[16:31], v[172:175], v[208:211], v[16:31]
	ds_read_b128 v[208:211], v149 offset:96
	s_waitcnt lgkmcnt(5)
	v_mfma_f32_32x32x16_bf16 v[64:79], v[168:171], v[212:215], v[64:79]
	v_mfma_f32_32x32x16_bf16 v[0:15], v[172:175], v[212:215], v[0:15]
	ds_read_b128 v[212:215], v149 offset:4704
	global_load_dwordx4 v[168:171], v[144:145], off offset:3456
	global_load_dwordx4 v[172:175], v[146:147], off offset:3456
	s_waitcnt lgkmcnt(1)
	v_mfma_f32_32x32x16_bf16 v[112:127], v[160:163], v[208:211], v[112:127]
	v_mfma_f32_32x32x16_bf16 v[48:63], v[164:167], v[208:211], v[48:63]
	s_waitcnt lgkmcnt(0)
	v_mfma_f32_32x32x16_bf16 v[96:111], v[160:163], v[212:215], v[96:111]
	v_mfma_f32_32x32x16_bf16 v[32:47], v[164:167], v[212:215], v[32:47]
	ds_read_b128 v[208:211], v149 offset:9312
	ds_read_b128 v[212:215], v149 offset:13920
	s_waitcnt lgkmcnt(1)
	v_mfma_f32_32x32x16_bf16 v[80:95], v[160:163], v[208:211], v[80:95]
	v_mfma_f32_32x32x16_bf16 v[16:31], v[164:167], v[208:211], v[16:31]
	s_waitcnt lgkmcnt(0)
	v_mfma_f32_32x32x16_bf16 v[64:79], v[160:163], v[212:215], v[64:79]
	v_mfma_f32_32x32x16_bf16 v[0:15], v[164:167], v[212:215], v[0:15]
	s_setprio 0
	s_barrier
	global_load_dwordx4 v[160:163], v[136:137], off offset:3584
	global_load_dwordx4 v[164:167], v[138:139], off offset:3584
	s_waitcnt vmcnt(9)
	ds_write_b128 v192, v[184:187]
	s_waitcnt vmcnt(8)
	ds_write_b128 v159, v[188:191]
	ds_read_b128 v[184:187], v152 offset:36864
	ds_read_b128 v[188:191], v152 offset:41472
	ds_read_b128 v[208:211], v151
	ds_read_b128 v[212:215], v151 offset:4608
	s_setprio 1
	s_waitcnt lgkmcnt(1)
	v_mfma_f32_32x32x16_bf16 v[112:127], v[184:187], v[208:211], v[112:127]
	v_mfma_f32_32x32x16_bf16 v[48:63], v[188:191], v[208:211], v[48:63]
	s_waitcnt lgkmcnt(0)
	v_mfma_f32_32x32x16_bf16 v[96:111], v[184:187], v[212:215], v[96:111]
	v_mfma_f32_32x32x16_bf16 v[32:47], v[188:191], v[212:215], v[32:47]
	ds_read_b128 v[208:211], v151 offset:9216
	ds_read_b128 v[212:215], v151 offset:13824
	s_waitcnt vmcnt(7)
	ds_write_b128 v158, v[194:197]
	s_waitcnt vmcnt(6)
	ds_write_b128 v157, v[198:201]
	ds_read_b128 v[194:197], v152 offset:36896
	ds_read_b128 v[198:201], v152 offset:41504
	s_waitcnt lgkmcnt(5)
	v_mfma_f32_32x32x16_bf16 v[80:95], v[184:187], v[208:211], v[80:95]
	v_mfma_f32_32x32x16_bf16 v[16:31], v[188:191], v[208:211], v[16:31]
	ds_read_b128 v[208:211], v151 offset:32
	s_waitcnt lgkmcnt(5)
	v_mfma_f32_32x32x16_bf16 v[64:79], v[184:187], v[212:215], v[64:79]
	v_mfma_f32_32x32x16_bf16 v[0:15], v[188:191], v[212:215], v[0:15]
	ds_read_b128 v[212:215], v151 offset:4640
	global_load_dwordx4 v[184:187], v[140:141], off offset:3584
	global_load_dwordx4 v[188:191], v[142:143], off offset:3584
	s_waitcnt lgkmcnt(1)
	v_mfma_f32_32x32x16_bf16 v[112:127], v[194:197], v[208:211], v[112:127]
	v_mfma_f32_32x32x16_bf16 v[48:63], v[198:201], v[208:211], v[48:63]
	s_waitcnt lgkmcnt(0)
	v_mfma_f32_32x32x16_bf16 v[96:111], v[194:197], v[212:215], v[96:111]
	v_mfma_f32_32x32x16_bf16 v[32:47], v[198:201], v[212:215], v[32:47]
	ds_read_b128 v[208:211], v151 offset:9248
	ds_read_b128 v[212:215], v151 offset:13856
	s_waitcnt vmcnt(7)
	ds_write_b128 v154, v[176:179]
	s_waitcnt vmcnt(6)
	ds_write_b128 v153, v[180:183]
	ds_read_b128 v[176:179], v152 offset:36928
	ds_read_b128 v[180:183], v152 offset:41536
	s_waitcnt lgkmcnt(5)
	v_mfma_f32_32x32x16_bf16 v[80:95], v[194:197], v[208:211], v[80:95]
	v_mfma_f32_32x32x16_bf16 v[16:31], v[198:201], v[208:211], v[16:31]
	ds_read_b128 v[208:211], v151 offset:64
	s_waitcnt lgkmcnt(5)
	v_mfma_f32_32x32x16_bf16 v[64:79], v[194:197], v[212:215], v[64:79]
	v_mfma_f32_32x32x16_bf16 v[0:15], v[198:201], v[212:215], v[0:15]
	ds_read_b128 v[212:215], v151 offset:4672
	global_load_dwordx4 v[194:197], v[132:133], off offset:3584
	global_load_dwordx4 v[198:201], v[134:135], off offset:3584
	s_waitcnt lgkmcnt(1)
	v_mfma_f32_32x32x16_bf16 v[112:127], v[176:179], v[208:211], v[112:127]
	v_mfma_f32_32x32x16_bf16 v[48:63], v[180:183], v[208:211], v[48:63]
	s_waitcnt lgkmcnt(0)
	v_mfma_f32_32x32x16_bf16 v[96:111], v[176:179], v[212:215], v[96:111]
	v_mfma_f32_32x32x16_bf16 v[32:47], v[180:183], v[212:215], v[32:47]
	ds_read_b128 v[208:211], v151 offset:9280
	ds_read_b128 v[212:215], v151 offset:13888
	s_waitcnt vmcnt(7)
	ds_write_b128 v156, v[168:171]
	s_waitcnt vmcnt(6)
	ds_write_b128 v155, v[172:175]
	ds_read_b128 v[168:171], v152 offset:36960
	ds_read_b128 v[172:175], v152 offset:41568
	s_waitcnt lgkmcnt(5)
	v_mfma_f32_32x32x16_bf16 v[80:95], v[176:179], v[208:211], v[80:95]
	v_mfma_f32_32x32x16_bf16 v[16:31], v[180:183], v[208:211], v[16:31]
	ds_read_b128 v[208:211], v151 offset:96
	s_waitcnt lgkmcnt(5)
	v_mfma_f32_32x32x16_bf16 v[64:79], v[176:179], v[212:215], v[64:79]
	v_mfma_f32_32x32x16_bf16 v[0:15], v[180:183], v[212:215], v[0:15]
	ds_read_b128 v[212:215], v151 offset:4704
	global_load_dwordx4 v[176:179], v[144:145], off offset:3584
	global_load_dwordx4 v[180:183], v[146:147], off offset:3584
	s_waitcnt lgkmcnt(1)
	v_mfma_f32_32x32x16_bf16 v[112:127], v[168:171], v[208:211], v[112:127]
	v_mfma_f32_32x32x16_bf16 v[48:63], v[172:175], v[208:211], v[48:63]
	s_waitcnt lgkmcnt(0)
	v_mfma_f32_32x32x16_bf16 v[96:111], v[168:171], v[212:215], v[96:111]
	v_mfma_f32_32x32x16_bf16 v[32:47], v[172:175], v[212:215], v[32:47]
	ds_read_b128 v[208:211], v151 offset:9312
	ds_read_b128 v[212:215], v151 offset:13920
	s_waitcnt lgkmcnt(1)
	v_mfma_f32_32x32x16_bf16 v[80:95], v[168:171], v[208:211], v[80:95]
	v_mfma_f32_32x32x16_bf16 v[16:31], v[172:175], v[208:211], v[16:31]
	s_waitcnt lgkmcnt(0)
	v_mfma_f32_32x32x16_bf16 v[64:79], v[168:171], v[212:215], v[64:79]
	v_mfma_f32_32x32x16_bf16 v[0:15], v[172:175], v[212:215], v[0:15]
	s_setprio 0
	s_barrier
	global_load_dwordx4 v[168:171], v[136:137], off offset:3712
	global_load_dwordx4 v[172:175], v[138:139], off offset:3712
	s_waitcnt vmcnt(9)
	ds_write_b128 v148, v[160:163]
	s_waitcnt vmcnt(8)
	ds_write_b128 v148, v[164:167] offset:36864
	ds_read_b128 v[160:163], v150
	ds_read_b128 v[164:167], v150 offset:4608
	ds_read_b128 v[208:211], v149
	ds_read_b128 v[212:215], v149 offset:4608
	s_setprio 1
	s_waitcnt lgkmcnt(1)
	v_mfma_f32_32x32x16_bf16 v[112:127], v[160:163], v[208:211], v[112:127]
	v_mfma_f32_32x32x16_bf16 v[48:63], v[164:167], v[208:211], v[48:63]
	s_waitcnt lgkmcnt(0)
	v_mfma_f32_32x32x16_bf16 v[96:111], v[160:163], v[212:215], v[96:111]
	v_mfma_f32_32x32x16_bf16 v[32:47], v[164:167], v[212:215], v[32:47]
	ds_read_b128 v[208:211], v149 offset:9216
	ds_read_b128 v[212:215], v149 offset:13824
	s_waitcnt vmcnt(7)
	ds_write_b128 v148, v[184:187] offset:9216
	s_waitcnt vmcnt(6)
	ds_write_b128 v148, v[188:191] offset:46080
	ds_read_b128 v[184:187], v150 offset:32
	ds_read_b128 v[188:191], v150 offset:4640
	s_waitcnt lgkmcnt(5)
	v_mfma_f32_32x32x16_bf16 v[80:95], v[160:163], v[208:211], v[80:95]
	v_mfma_f32_32x32x16_bf16 v[16:31], v[164:167], v[208:211], v[16:31]
	ds_read_b128 v[208:211], v149 offset:32
	s_waitcnt lgkmcnt(5)
	v_mfma_f32_32x32x16_bf16 v[64:79], v[160:163], v[212:215], v[64:79]
	v_mfma_f32_32x32x16_bf16 v[0:15], v[164:167], v[212:215], v[0:15]
	ds_read_b128 v[212:215], v149 offset:4640
	global_load_dwordx4 v[160:163], v[140:141], off offset:3712
	global_load_dwordx4 v[164:167], v[142:143], off offset:3712
	s_waitcnt lgkmcnt(1)
	v_mfma_f32_32x32x16_bf16 v[112:127], v[184:187], v[208:211], v[112:127]
	v_mfma_f32_32x32x16_bf16 v[48:63], v[188:191], v[208:211], v[48:63]
	s_waitcnt lgkmcnt(0)
	v_mfma_f32_32x32x16_bf16 v[96:111], v[184:187], v[212:215], v[96:111]
	v_mfma_f32_32x32x16_bf16 v[32:47], v[188:191], v[212:215], v[32:47]
	ds_read_b128 v[208:211], v149 offset:9248
	ds_read_b128 v[212:215], v149 offset:13856
	s_waitcnt vmcnt(7)
	ds_write_b128 v148, v[194:197] offset:18432
	s_waitcnt vmcnt(6)
	ds_write_b128 v148, v[198:201] offset:55296
	ds_read_b128 v[194:197], v150 offset:64
	ds_read_b128 v[198:201], v150 offset:4672
	s_waitcnt lgkmcnt(5)
	v_mfma_f32_32x32x16_bf16 v[80:95], v[184:187], v[208:211], v[80:95]
	v_mfma_f32_32x32x16_bf16 v[16:31], v[188:191], v[208:211], v[16:31]
	ds_read_b128 v[208:211], v149 offset:64
	s_waitcnt lgkmcnt(5)
	v_mfma_f32_32x32x16_bf16 v[64:79], v[184:187], v[212:215], v[64:79]
	v_mfma_f32_32x32x16_bf16 v[0:15], v[188:191], v[212:215], v[0:15]
	ds_read_b128 v[212:215], v149 offset:4672
	global_load_dwordx4 v[184:187], v[132:133], off offset:3712
	global_load_dwordx4 v[188:191], v[134:135], off offset:3712
	s_waitcnt lgkmcnt(1)
	v_mfma_f32_32x32x16_bf16 v[112:127], v[194:197], v[208:211], v[112:127]
	v_mfma_f32_32x32x16_bf16 v[48:63], v[198:201], v[208:211], v[48:63]
	s_waitcnt lgkmcnt(0)
	v_mfma_f32_32x32x16_bf16 v[96:111], v[194:197], v[212:215], v[96:111]
	v_mfma_f32_32x32x16_bf16 v[32:47], v[198:201], v[212:215], v[32:47]
	ds_read_b128 v[208:211], v149 offset:9280
	ds_read_b128 v[212:215], v149 offset:13888
	s_waitcnt vmcnt(7)
	ds_write_b128 v148, v[176:179] offset:27648
	s_waitcnt vmcnt(6)
	ds_write_b128 v148, v[180:183] offset:64512
	ds_read_b128 v[176:179], v150 offset:96
	ds_read_b128 v[180:183], v150 offset:4704
	s_waitcnt lgkmcnt(5)
	v_mfma_f32_32x32x16_bf16 v[80:95], v[194:197], v[208:211], v[80:95]
	v_mfma_f32_32x32x16_bf16 v[16:31], v[198:201], v[208:211], v[16:31]
	ds_read_b128 v[208:211], v149 offset:96
	s_waitcnt lgkmcnt(5)
	v_mfma_f32_32x32x16_bf16 v[64:79], v[194:197], v[212:215], v[64:79]
	v_mfma_f32_32x32x16_bf16 v[0:15], v[198:201], v[212:215], v[0:15]
	ds_read_b128 v[212:215], v149 offset:4704
	global_load_dwordx4 v[194:197], v[144:145], off offset:3712
	global_load_dwordx4 v[198:201], v[146:147], off offset:3712
	s_waitcnt lgkmcnt(1)
	v_mfma_f32_32x32x16_bf16 v[112:127], v[176:179], v[208:211], v[112:127]
	v_mfma_f32_32x32x16_bf16 v[48:63], v[180:183], v[208:211], v[48:63]
	s_waitcnt lgkmcnt(0)
	v_mfma_f32_32x32x16_bf16 v[96:111], v[176:179], v[212:215], v[96:111]
	v_mfma_f32_32x32x16_bf16 v[32:47], v[180:183], v[212:215], v[32:47]
	ds_read_b128 v[208:211], v149 offset:9312
	ds_read_b128 v[212:215], v149 offset:13920
	s_waitcnt lgkmcnt(1)
	v_mfma_f32_32x32x16_bf16 v[80:95], v[176:179], v[208:211], v[80:95]
	v_mfma_f32_32x32x16_bf16 v[16:31], v[180:183], v[208:211], v[16:31]
	s_waitcnt lgkmcnt(0)
	v_mfma_f32_32x32x16_bf16 v[64:79], v[176:179], v[212:215], v[64:79]
	v_mfma_f32_32x32x16_bf16 v[0:15], v[180:183], v[212:215], v[0:15]
	s_setprio 0
	s_barrier
	global_load_dwordx4 v[176:179], v[136:137], off offset:3840
	global_load_dwordx4 v[180:183], v[138:139], off offset:3840
	s_waitcnt vmcnt(9)
	ds_write_b128 v192, v[168:171]
	s_waitcnt vmcnt(8)
	ds_write_b128 v159, v[172:175]
	ds_read_b128 v[168:171], v152 offset:36864
	ds_read_b128 v[172:175], v152 offset:41472
	ds_read_b128 v[208:211], v151
	ds_read_b128 v[212:215], v151 offset:4608
	s_setprio 1
	s_waitcnt lgkmcnt(1)
	v_mfma_f32_32x32x16_bf16 v[112:127], v[168:171], v[208:211], v[112:127]
	v_mfma_f32_32x32x16_bf16 v[48:63], v[172:175], v[208:211], v[48:63]
	s_waitcnt lgkmcnt(0)
	v_mfma_f32_32x32x16_bf16 v[96:111], v[168:171], v[212:215], v[96:111]
	v_mfma_f32_32x32x16_bf16 v[32:47], v[172:175], v[212:215], v[32:47]
	ds_read_b128 v[208:211], v151 offset:9216
	ds_read_b128 v[212:215], v151 offset:13824
	s_waitcnt lgkmcnt(1)
	v_mfma_f32_32x32x16_bf16 v[80:95], v[168:171], v[208:211], v[80:95]
	v_mfma_f32_32x32x16_bf16 v[16:31], v[172:175], v[208:211], v[16:31]
	s_waitcnt lgkmcnt(0)
	v_mfma_f32_32x32x16_bf16 v[64:79], v[168:171], v[212:215], v[64:79]
	v_mfma_f32_32x32x16_bf16 v[0:15], v[172:175], v[212:215], v[0:15]
	s_setprio 0
	global_load_dwordx4 v[208:211], v[140:141], off offset:3840
	global_load_dwordx4 v[212:215], v[142:143], off offset:3840
	s_waitcnt vmcnt(9)
	ds_write_b128 v158, v[160:163]
	s_waitcnt vmcnt(8)
	ds_write_b128 v157, v[164:167]
	ds_read_b128 v[160:163], v152 offset:36896
	ds_read_b128 v[164:167], v152 offset:41504
	ds_read_b128 v[168:171], v151 offset:32
	ds_read_b128 v[172:175], v151 offset:4640
	s_setprio 1
	s_waitcnt lgkmcnt(1)
	v_mfma_f32_32x32x16_bf16 v[112:127], v[160:163], v[168:171], v[112:127]
	v_mfma_f32_32x32x16_bf16 v[48:63], v[164:167], v[168:171], v[48:63]
	s_waitcnt lgkmcnt(0)
	v_mfma_f32_32x32x16_bf16 v[96:111], v[160:163], v[172:175], v[96:111]
	v_mfma_f32_32x32x16_bf16 v[32:47], v[164:167], v[172:175], v[32:47]
	ds_read_b128 v[168:171], v151 offset:9248
	ds_read_b128 v[172:175], v151 offset:13856
	s_waitcnt lgkmcnt(1)
	v_mfma_f32_32x32x16_bf16 v[80:95], v[160:163], v[168:171], v[80:95]
	v_mfma_f32_32x32x16_bf16 v[16:31], v[164:167], v[168:171], v[16:31]
	s_waitcnt lgkmcnt(0)
	v_mfma_f32_32x32x16_bf16 v[64:79], v[160:163], v[172:175], v[64:79]
	v_mfma_f32_32x32x16_bf16 v[0:15], v[164:167], v[172:175], v[0:15]
	s_setprio 0
	global_load_dwordx4 v[216:219], v[132:133], off offset:3840
	global_load_dwordx4 v[220:223], v[134:135], off offset:3840
	s_waitcnt vmcnt(9)
	ds_write_b128 v154, v[184:187]
	s_waitcnt vmcnt(8)
	ds_write_b128 v153, v[188:191]
	ds_read_b128 v[160:163], v152 offset:36928
	ds_read_b128 v[164:167], v152 offset:41536
	ds_read_b128 v[168:171], v151 offset:64
	ds_read_b128 v[172:175], v151 offset:4672
	s_setprio 1
	s_waitcnt lgkmcnt(1)
	v_mfma_f32_32x32x16_bf16 v[112:127], v[160:163], v[168:171], v[112:127]
	v_mfma_f32_32x32x16_bf16 v[48:63], v[164:167], v[168:171], v[48:63]
	s_waitcnt lgkmcnt(0)
	v_mfma_f32_32x32x16_bf16 v[96:111], v[160:163], v[172:175], v[96:111]
	v_mfma_f32_32x32x16_bf16 v[32:47], v[164:167], v[172:175], v[32:47]
	ds_read_b128 v[168:171], v151 offset:9280
	ds_read_b128 v[172:175], v151 offset:13888
	s_waitcnt lgkmcnt(1)
	v_mfma_f32_32x32x16_bf16 v[80:95], v[160:163], v[168:171], v[80:95]
	v_mfma_f32_32x32x16_bf16 v[16:31], v[164:167], v[168:171], v[16:31]
	s_waitcnt lgkmcnt(0)
	v_mfma_f32_32x32x16_bf16 v[64:79], v[160:163], v[172:175], v[64:79]
	v_mfma_f32_32x32x16_bf16 v[0:15], v[164:167], v[172:175], v[0:15]
	s_setprio 0
	global_load_dwordx4 v[224:227], v[144:145], off offset:3840
	global_load_dwordx4 v[228:231], v[146:147], off offset:3840
	s_waitcnt vmcnt(9)
	ds_write_b128 v156, v[194:197]
	s_waitcnt vmcnt(8)
	ds_write_b128 v155, v[198:201]
	ds_read_b128 v[160:163], v152 offset:36960
	ds_read_b128 v[164:167], v152 offset:41568
	ds_read_b128 v[168:171], v151 offset:96
	ds_read_b128 v[172:175], v151 offset:4704
	s_setprio 1
	s_waitcnt lgkmcnt(1)
	v_mfma_f32_32x32x16_bf16 v[112:127], v[160:163], v[168:171], v[112:127]
	v_mfma_f32_32x32x16_bf16 v[48:63], v[164:167], v[168:171], v[48:63]
	s_waitcnt lgkmcnt(0)
	v_mfma_f32_32x32x16_bf16 v[96:111], v[160:163], v[172:175], v[96:111]
	v_mfma_f32_32x32x16_bf16 v[32:47], v[164:167], v[172:175], v[32:47]
	ds_read_b128 v[168:171], v151 offset:9312
	ds_read_b128 v[172:175], v151 offset:13920
	s_waitcnt lgkmcnt(1)
	v_mfma_f32_32x32x16_bf16 v[80:95], v[160:163], v[168:171], v[80:95]
	v_mfma_f32_32x32x16_bf16 v[16:31], v[164:167], v[168:171], v[16:31]
	s_waitcnt lgkmcnt(0)
	v_mfma_f32_32x32x16_bf16 v[64:79], v[160:163], v[172:175], v[64:79]
	v_mfma_f32_32x32x16_bf16 v[0:15], v[164:167], v[172:175], v[0:15]
	s_setprio 0
	s_barrier
; template <bool trans>
; DI void gemm_core(const GTile& tl, const GTile& nx, bool has_next  , bool chain  , bool pre, u32x4 (&ra)[4], u32x4 (&rb)[4], char* smem, f32x16 (&acc)[2][4]) {
;     ...
;   const int nk = K / 64;
;   if (!pre) { G_LOAD(0); G_STORE(0); G_LOAD(1); }
;   for (int kt = 0; kt < nk; ++kt) {
;     __syncthreads();
;     G_COMPUTE(kt & 1, kt);
;   }
;   if (!has_next) __syncthreads();
	global_load_dwordx4 v[160:163], v[136:137], off offset:3968
	global_load_dwordx4 v[164:167], v[138:139], off offset:3968
	s_waitcnt vmcnt(9)
	ds_write_b128 v148, v[176:179]
	s_waitcnt vmcnt(8)
	ds_write_b128 v148, v[180:183] offset:36864
	ds_read_b128 v[136:139], v150
	ds_read_b128 v[168:171], v150 offset:4608
	ds_read_b128 v[172:175], v149
	ds_read_b128 v[176:179], v149 offset:4608
	s_setprio 1
	s_waitcnt lgkmcnt(1)
	v_mfma_f32_32x32x16_bf16 v[112:127], v[136:139], v[172:175], v[112:127]
	v_mfma_f32_32x32x16_bf16 v[48:63], v[168:171], v[172:175], v[48:63]
	s_waitcnt lgkmcnt(0)
	v_mfma_f32_32x32x16_bf16 v[96:111], v[136:139], v[176:179], v[96:111]
	v_mfma_f32_32x32x16_bf16 v[32:47], v[168:171], v[176:179], v[32:47]
	ds_read_b128 v[172:175], v149 offset:9216
	ds_read_b128 v[176:179], v149 offset:13824
	s_waitcnt lgkmcnt(1)
	v_mfma_f32_32x32x16_bf16 v[80:95], v[136:139], v[172:175], v[80:95]
	v_mfma_f32_32x32x16_bf16 v[16:31], v[168:171], v[172:175], v[16:31]
	s_waitcnt lgkmcnt(0)
	v_mfma_f32_32x32x16_bf16 v[64:79], v[136:139], v[176:179], v[64:79]
	v_mfma_f32_32x32x16_bf16 v[0:15], v[168:171], v[176:179], v[0:15]
	s_setprio 0
	global_load_dwordx4 v[168:171], v[140:141], off offset:3968
	global_load_dwordx4 v[172:175], v[142:143], off offset:3968
	s_waitcnt vmcnt(9)
	ds_write_b128 v148, v[208:211] offset:9216
	s_waitcnt vmcnt(8)
	ds_write_b128 v148, v[212:215] offset:46080
	ds_read_b128 v[136:139], v150 offset:32
	ds_read_b128 v[140:143], v150 offset:4640
	ds_read_b128 v[176:179], v149 offset:32
	ds_read_b128 v[180:183], v149 offset:4640
	s_setprio 1
	s_waitcnt lgkmcnt(1)
	v_mfma_f32_32x32x16_bf16 v[112:127], v[136:139], v[176:179], v[112:127]
	v_mfma_f32_32x32x16_bf16 v[48:63], v[140:143], v[176:179], v[48:63]
	s_waitcnt lgkmcnt(0)
	v_mfma_f32_32x32x16_bf16 v[96:111], v[136:139], v[180:183], v[96:111]
	v_mfma_f32_32x32x16_bf16 v[32:47], v[140:143], v[180:183], v[32:47]
	ds_read_b128 v[176:179], v149 offset:9248
	ds_read_b128 v[180:183], v149 offset:13856
	s_waitcnt lgkmcnt(1)
	v_mfma_f32_32x32x16_bf16 v[80:95], v[136:139], v[176:179], v[80:95]
	v_mfma_f32_32x32x16_bf16 v[16:31], v[140:143], v[176:179], v[16:31]
	s_waitcnt lgkmcnt(0)
	v_mfma_f32_32x32x16_bf16 v[64:79], v[136:139], v[180:183], v[64:79]
	v_mfma_f32_32x32x16_bf16 v[0:15], v[140:143], v[180:183], v[0:15]
	s_setprio 0
	global_load_dwordx4 v[176:179], v[132:133], off offset:3968
	global_load_dwordx4 v[180:183], v[134:135], off offset:3968
	s_waitcnt vmcnt(9)
	ds_write_b128 v148, v[216:219] offset:18432
	s_waitcnt vmcnt(8)
	ds_write_b128 v148, v[220:223] offset:55296
	ds_read_b128 v[132:135], v150 offset:64
	ds_read_b128 v[136:139], v150 offset:4672
	ds_read_b128 v[140:143], v149 offset:64
	ds_read_b128 v[184:187], v149 offset:4672
	s_setprio 1
	s_waitcnt lgkmcnt(1)
	v_mfma_f32_32x32x16_bf16 v[112:127], v[132:135], v[140:143], v[112:127]
	v_mfma_f32_32x32x16_bf16 v[48:63], v[136:139], v[140:143], v[48:63]
	s_waitcnt lgkmcnt(0)
	v_mfma_f32_32x32x16_bf16 v[96:111], v[132:135], v[184:187], v[96:111]
	v_mfma_f32_32x32x16_bf16 v[32:47], v[136:139], v[184:187], v[32:47]
	ds_read_b128 v[140:143], v149 offset:9280
	ds_read_b128 v[184:187], v149 offset:13888
	s_waitcnt lgkmcnt(1)
	v_mfma_f32_32x32x16_bf16 v[80:95], v[132:135], v[140:143], v[80:95]
	v_mfma_f32_32x32x16_bf16 v[16:31], v[136:139], v[140:143], v[16:31]
	s_waitcnt lgkmcnt(0)
	v_mfma_f32_32x32x16_bf16 v[64:79], v[132:135], v[184:187], v[64:79]
	v_mfma_f32_32x32x16_bf16 v[0:15], v[136:139], v[184:187], v[0:15]
	s_setprio 0
	global_load_dwordx4 v[184:187], v[144:145], off offset:3968
	global_load_dwordx4 v[188:191], v[146:147], off offset:3968
	s_waitcnt vmcnt(9)
	ds_write_b128 v148, v[224:227] offset:27648
	s_waitcnt vmcnt(8)
	ds_write_b128 v148, v[228:231] offset:64512
	ds_read_b128 v[132:135], v150 offset:96
	ds_read_b128 v[136:139], v150 offset:4704
	ds_read_b128 v[140:143], v149 offset:96
	ds_read_b128 v[144:147], v149 offset:4704
	s_setprio 1
	s_waitcnt lgkmcnt(1)
	v_mfma_f32_32x32x16_bf16 v[112:127], v[132:135], v[140:143], v[112:127]
	v_mfma_f32_32x32x16_bf16 v[48:63], v[136:139], v[140:143], v[48:63]
	s_waitcnt lgkmcnt(0)
	v_mfma_f32_32x32x16_bf16 v[96:111], v[132:135], v[144:147], v[96:111]
	v_mfma_f32_32x32x16_bf16 v[32:47], v[136:139], v[144:147], v[32:47]
	ds_read_b128 v[140:143], v149 offset:9312
	ds_read_b128 v[144:147], v149 offset:13920
	s_waitcnt lgkmcnt(1)
	v_mfma_f32_32x32x16_bf16 v[80:95], v[132:135], v[140:143], v[80:95]
	v_mfma_f32_32x32x16_bf16 v[16:31], v[136:139], v[140:143], v[16:31]
	s_waitcnt lgkmcnt(0)
	v_mfma_f32_32x32x16_bf16 v[64:79], v[132:135], v[144:147], v[64:79]
	v_mfma_f32_32x32x16_bf16 v[0:15], v[136:139], v[144:147], v[0:15]
	s_setprio 0
	v_cndmask_b32_e64 v132, 0, 1, s[52:53]
	v_cmp_ne_u32_e64 s[4:5], 1, v132
	s_andn2_b64 vcc, exec, s[52:53]
	s_barrier
	s_waitcnt vmcnt(7)
	ds_write_b128 v192, v[160:163]
	s_waitcnt vmcnt(6)
	ds_write_b128 v159, v[164:167]
	s_cbranch_vccnz .LBB0_113
	global_load_dwordx4 v[160:163], v[130:131], off
	global_load_dwordx4 v[164:167], v[128:129], off

;   DI bf16_t* h() const { return (bf16_t*)(ws + OFF_H); }
; DI void phase_gemm_out(const Params& p, char* smem, const bf16_t* Wt, const float* R, float* O) {
;     ...
;   for (int t = blockIdx.x; t < 64 * 8; t += gridDim.x) {
;     const int mt = t & 63, nt = t >> 6, tn = t + gridDim.x;
;     const bool has_next = tn < 64 * 8;
;     const GTile tl{p.h(), D, Wt, D, D, mt * 256, nt * 256}, nx{p.h(), D, Wt, D, D, (tn & 63) * 256, (tn >> 6) * 256};
;     WAVE_GEOM;
;     f32x16 acc[2][4];
;     gemm_core<false>(tl, nx, has_next, has_next, pre, ra, rb, smem, acc);
.LBB0_749:
	v_lshl_add_u64 v[128:129], s[2:3], 0, v[184:185]
	v_lshl_add_u64 v[132:133], s[6:7], 0, v[184:185]
	s_waitcnt lgkmcnt(0)
	s_barrier
	global_load_dwordx4 v[198:201], v[128:129], off offset:256
	global_load_dwordx4 v[202:205], v[132:133], off offset:256
	s_add_i32 s38, s38, s96
	s_cmpk_lt_i32 s38, 0x200
	s_cselect_b64 s[14:15], -1, 0
	s_cmpk_gt_i32 s38, 0x1ff
	s_cselect_b64 s[12:13], -1, 0
	s_and_b32 s3, s28, 0x1f80000
	s_add_i32 s24, s25, s24
	s_and_b32 s2, s24, 0xffffff00
	s_and_b32 s40, s33, 0xc0
	s_lshl_b32 s3, s3, 1
	s_add_u32 s6, s18, s3
	s_addc_u32 s7, s19, 0
	s_ashr_i32 s3, s2, 31
	s_lshl_b64 s[2:3], s[2:3], 12
	s_add_u32 s2, s16, s2
	s_addc_u32 s3, s17, s3
	s_lshr_b32 s33, s33, 1
	v_and_b32_e32 v11, 31, v8
	s_and_b32 s33, s33, 0xfffff80
	v_or_b32_e32 v12, s33, v11
	v_or_b32_e32 v11, s40, v11
	v_add3_u32 v191, 16, v10, v9
	v_lshrrev_b32_e32 v8, 1, v8
	v_mul_u32_u24_e32 v131, 0x90, v11
	v_and_b32_e32 v134, 16, v8
	v_add_u32_e32 v195, 0x12000, v191
	v_mul_lo_u32 v130, v12, s35
	v_add3_u32 v192, 16, v131, v134
	v_add_u32_e32 v196, 0x1b000, v191
	ds_write_b128 v195, v[0:3]
	s_waitcnt vmcnt(5)
	ds_write_b128 v196, v[4:7]
	v_lshl_add_u64 v[188:189], s[6:7], 0, v[184:185]
	v_lshl_add_u64 v[186:187], s[2:3], 0, v[184:185]
	v_add3_u32 v184, 16, v130, v134
	ds_read_b128 v[0:3], v192 offset:36864
	ds_read_b128 v[4:7], v192 offset:41472
	ds_read_b128 v[8:11], v184
	ds_read_b128 v[12:15], v184 offset:4608
	v_lshl_add_u64 v[136:137], v[128:129], 0, s[0:1]
	v_lshl_add_u64 v[140:141], v[132:133], 0, s[0:1]
	v_lshl_add_u64 v[144:145], v[128:129], 0, s[8:9]
	v_lshl_add_u64 v[148:149], v[132:133], 0, s[8:9]
	s_setprio 1
	s_waitcnt lgkmcnt(1)
	v_mfma_f32_32x32x16_bf16 v[112:127], v[0:3], v[8:11], 0
	v_mfma_f32_32x32x16_bf16 v[48:63], v[4:7], v[8:11], 0
	s_waitcnt lgkmcnt(0)
	v_mfma_f32_32x32x16_bf16 v[96:111], v[0:3], v[12:15], 0
	v_mfma_f32_32x32x16_bf16 v[32:47], v[4:7], v[12:15], 0
	ds_read_b128 v[8:11], v184 offset:9216
	ds_read_b128 v[12:15], v184 offset:13824
	s_waitcnt lgkmcnt(1)
	v_mfma_f32_32x32x16_bf16 v[80:95], v[0:3], v[8:11], 0
	v_mfma_f32_32x32x16_bf16 v[16:31], v[4:7], v[8:11], 0
	s_waitcnt lgkmcnt(0)
	v_mfma_f32_32x32x16_bf16 v[64:79], v[0:3], v[12:15], 0
	v_mfma_f32_32x32x16_bf16 v[0:15], v[4:7], v[12:15], 0
	s_setprio 0
	global_load_dwordx4 v[208:211], v[136:137], off offset:256
	global_load_dwordx4 v[212:215], v[140:141], off offset:256
	v_add_u32_e32 v194, 0x14400, v191
	v_add_u32_e32 v193, 0x1d400, v191
	ds_write_b128 v194, v[176:179]
	s_waitcnt vmcnt(6)
	ds_write_b128 v193, v[180:183]
	ds_read_b128 v[150:153], v192 offset:36896
	ds_read_b128 v[154:157], v192 offset:41504
	ds_read_b128 v[176:179], v184 offset:32
	ds_read_b128 v[180:183], v184 offset:4640
	s_setprio 1
	s_waitcnt lgkmcnt(1)
	v_mfma_f32_32x32x16_bf16 v[112:127], v[150:153], v[176:179], v[112:127]
	v_mfma_f32_32x32x16_bf16 v[48:63], v[154:157], v[176:179], v[48:63]
	s_waitcnt lgkmcnt(0)
	v_mfma_f32_32x32x16_bf16 v[96:111], v[150:153], v[180:183], v[96:111]
	v_mfma_f32_32x32x16_bf16 v[32:47], v[154:157], v[180:183], v[32:47]
	ds_read_b128 v[176:179], v184 offset:9248
	ds_read_b128 v[180:183], v184 offset:13856
	s_waitcnt lgkmcnt(1)
	v_mfma_f32_32x32x16_bf16 v[80:95], v[150:153], v[176:179], v[80:95]
	v_mfma_f32_32x32x16_bf16 v[16:31], v[154:157], v[176:179], v[16:31]
	s_waitcnt lgkmcnt(0)
	v_mfma_f32_32x32x16_bf16 v[64:79], v[150:153], v[180:183], v[64:79]
	v_mfma_f32_32x32x16_bf16 v[0:15], v[154:157], v[180:183], v[0:15]
	s_setprio 0
	global_load_dwordx4 v[178:181], v[144:145], off offset:256
	global_load_dwordx4 v[216:219], v[148:149], off offset:256
	v_add_u32_e32 v177, 0x16800, v191
	v_add_u32_e32 v176, 0x1f800, v191
	ds_write_b128 v177, v[168:171]
	s_waitcnt vmcnt(7)
	ds_write_b128 v176, v[172:175]
	ds_read_b128 v[150:153], v192 offset:36928
	ds_read_b128 v[154:157], v192 offset:41536
	ds_read_b128 v[168:171], v184 offset:64
	ds_read_b128 v[172:175], v184 offset:4672
	s_setprio 1
	s_waitcnt lgkmcnt(1)
	v_mfma_f32_32x32x16_bf16 v[112:127], v[150:153], v[168:171], v[112:127]
	v_mfma_f32_32x32x16_bf16 v[48:63], v[154:157], v[168:171], v[48:63]
	s_waitcnt lgkmcnt(0)
	v_mfma_f32_32x32x16_bf16 v[96:111], v[150:153], v[172:175], v[96:111]
	v_mfma_f32_32x32x16_bf16 v[32:47], v[154:157], v[172:175], v[32:47]
	ds_read_b128 v[168:171], v184 offset:9280
	ds_read_b128 v[172:175], v184 offset:13888
	s_waitcnt lgkmcnt(1)
	v_mfma_f32_32x32x16_bf16 v[80:95], v[150:153], v[168:171], v[80:95]
	v_mfma_f32_32x32x16_bf16 v[16:31], v[154:157], v[168:171], v[16:31]
	s_waitcnt lgkmcnt(0)
	v_mfma_f32_32x32x16_bf16 v[64:79], v[150:153], v[172:175], v[64:79]
	v_mfma_f32_32x32x16_bf16 v[0:15], v[154:157], v[172:175], v[0:15]
	s_setprio 0
	v_add_co_u32_e32 v152, vcc, s34, v128
	v_add_u32_e32 v171, 0x18c00, v191
	s_nop 0
	v_addc_co_u32_e32 v153, vcc, 0, v129, vcc
	v_add_co_u32_e32 v156, vcc, s34, v132
	v_add_u32_e32 v170, 0x21c00, v191
	s_nop 0
	v_addc_co_u32_e32 v157, vcc, 0, v133, vcc
	global_load_dwordx4 v[172:175], v[152:153], off offset:256
	global_load_dwordx4 v[220:223], v[156:157], off offset:256
	ds_write_b128 v171, v[160:163]
	s_waitcnt vmcnt(8)
	ds_write_b128 v170, v[164:167]
	ds_read_b128 v[158:161], v192 offset:36960
	ds_read_b128 v[162:165], v192 offset:41568
	ds_read_b128 v[166:169], v184 offset:96
	ds_read_b128 v[224:227], v184 offset:4704
	s_setprio 1
	s_waitcnt lgkmcnt(1)
	v_mfma_f32_32x32x16_bf16 v[112:127], v[158:161], v[166:169], v[112:127]
	v_mfma_f32_32x32x16_bf16 v[48:63], v[162:165], v[166:169], v[48:63]
	s_waitcnt lgkmcnt(0)
	v_mfma_f32_32x32x16_bf16 v[96:111], v[158:161], v[224:227], v[96:111]
	v_mfma_f32_32x32x16_bf16 v[32:47], v[162:165], v[224:227], v[32:47]
	ds_read_b128 v[166:169], v184 offset:9312
	ds_read_b128 v[224:227], v184 offset:13920
	s_waitcnt lgkmcnt(1)
	v_mfma_f32_32x32x16_bf16 v[80:95], v[158:161], v[166:169], v[80:95]
	v_mfma_f32_32x32x16_bf16 v[16:31], v[162:165], v[166:169], v[16:31]
	s_waitcnt lgkmcnt(0)
	v_mfma_f32_32x32x16_bf16 v[64:79], v[158:161], v[224:227], v[64:79]
	v_mfma_f32_32x32x16_bf16 v[0:15], v[162:165], v[224:227], v[0:15]
	s_setprio 0
	s_barrier
	global_load_dwordx4 v[158:161], v[128:129], off offset:384
	global_load_dwordx4 v[162:165], v[132:133], off offset:384
	v_add3_u32 v169, s37, v131, v134
	s_waitcnt vmcnt(9)
	ds_write_b128 v191, v[198:201]
	s_waitcnt vmcnt(8)
	ds_write_b128 v191, v[202:205] offset:36864
	v_add3_u32 v168, s36, v130, v134
	ds_read_b128 v[198:201], v169
	ds_read_b128 v[202:205], v169 offset:4608
	ds_read_b128 v[224:227], v168
	ds_read_b128 v[228:231], v168 offset:4608
	s_setprio 1
	s_waitcnt lgkmcnt(1)
	v_mfma_f32_32x32x16_bf16 v[112:127], v[198:201], v[224:227], v[112:127]
	v_mfma_f32_32x32x16_bf16 v[48:63], v[202:205], v[224:227], v[48:63]
	s_waitcnt lgkmcnt(0)
	v_mfma_f32_32x32x16_bf16 v[96:111], v[198:201], v[228:231], v[96:111]
	v_mfma_f32_32x32x16_bf16 v[32:47], v[202:205], v[228:231], v[32:47]
	ds_read_b128 v[224:227], v168 offset:9216
	ds_read_b128 v[228:231], v168 offset:13824
	s_waitcnt lgkmcnt(1)
	v_mfma_f32_32x32x16_bf16 v[80:95], v[198:201], v[224:227], v[80:95]
	v_mfma_f32_32x32x16_bf16 v[16:31], v[202:205], v[224:227], v[16:31]
	s_waitcnt lgkmcnt(0)
	v_mfma_f32_32x32x16_bf16 v[64:79], v[198:201], v[228:231], v[64:79]
	v_mfma_f32_32x32x16_bf16 v[0:15], v[202:205], v[228:231], v[0:15]
	s_setprio 0
	global_load_dwordx4 v[198:201], v[136:137], off offset:384
	global_load_dwordx4 v[202:205], v[140:141], off offset:384
	s_waitcnt vmcnt(9)
	ds_write_b128 v191, v[208:211] offset:9216
	s_waitcnt vmcnt(8)
	ds_write_b128 v191, v[212:215] offset:46080
	ds_read_b128 v[208:211], v169 offset:32
	ds_read_b128 v[212:215], v169 offset:4640
	ds_read_b128 v[224:227], v168 offset:32
	ds_read_b128 v[228:231], v168 offset:4640
	s_setprio 1
	s_waitcnt lgkmcnt(1)
	v_mfma_f32_32x32x16_bf16 v[112:127], v[208:211], v[224:227], v[112:127]
	v_mfma_f32_32x32x16_bf16 v[48:63], v[212:215], v[224:227], v[48:63]
	s_waitcnt lgkmcnt(0)
	v_mfma_f32_32x32x16_bf16 v[96:111], v[208:211], v[228:231], v[96:111]
	v_mfma_f32_32x32x16_bf16 v[32:47], v[212:215], v[228:231], v[32:47]
	ds_read_b128 v[224:227], v168 offset:9248
	ds_read_b128 v[228:231], v168 offset:13856
	s_waitcnt lgkmcnt(1)
	v_mfma_f32_32x32x16_bf16 v[80:95], v[208:211], v[224:227], v[80:95]
	v_mfma_f32_32x32x16_bf16 v[16:31], v[212:215], v[224:227], v[16:31]
	s_waitcnt lgkmcnt(0)
	v_mfma_f32_32x32x16_bf16 v[64:79], v[208:211], v[228:231], v[64:79]
	v_mfma_f32_32x32x16_bf16 v[0:15], v[212:215], v[228:231], v[0:15]
	s_setprio 0
	global_load_dwordx4 v[208:211], v[144:145], off offset:384
	global_load_dwordx4 v[212:215], v[148:149], off offset:384
	s_waitcnt vmcnt(9)
	ds_write_b128 v191, v[178:181] offset:18432
	s_waitcnt vmcnt(8)
	ds_write_b128 v191, v[216:219] offset:55296
	ds_read_b128 v[178:181], v169 offset:64
	ds_read_b128 v[216:219], v169 offset:4672
	ds_read_b128 v[224:227], v168 offset:64
	ds_read_b128 v[228:231], v168 offset:4672
	s_setprio 1
	s_waitcnt lgkmcnt(1)
	v_mfma_f32_32x32x16_bf16 v[112:127], v[178:181], v[224:227], v[112:127]
	v_mfma_f32_32x32x16_bf16 v[48:63], v[216:219], v[224:227], v[48:63]
	s_waitcnt lgkmcnt(0)
	v_mfma_f32_32x32x16_bf16 v[96:111], v[178:181], v[228:231], v[96:111]
	v_mfma_f32_32x32x16_bf16 v[32:47], v[216:219], v[228:231], v[32:47]
	ds_read_b128 v[224:227], v168 offset:9280
	ds_read_b128 v[228:231], v168 offset:13888
	s_waitcnt lgkmcnt(1)
	v_mfma_f32_32x32x16_bf16 v[80:95], v[178:181], v[224:227], v[80:95]
	v_mfma_f32_32x32x16_bf16 v[16:31], v[216:219], v[224:227], v[16:31]
	s_waitcnt lgkmcnt(0)
	v_mfma_f32_32x32x16_bf16 v[64:79], v[178:181], v[228:231], v[64:79]
	v_mfma_f32_32x32x16_bf16 v[0:15], v[216:219], v[228:231], v[0:15]
	s_setprio 0
	global_load_dwordx4 v[178:181], v[152:153], off offset:384
	global_load_dwordx4 v[216:219], v[156:157], off offset:384
	s_waitcnt vmcnt(9)
	ds_write_b128 v191, v[172:175] offset:27648
	s_waitcnt vmcnt(8)
	ds_write_b128 v191, v[220:223] offset:64512
	ds_read_b128 v[172:175], v169 offset:96
	ds_read_b128 v[220:223], v169 offset:4704
	ds_read_b128 v[224:227], v168 offset:96
	ds_read_b128 v[228:231], v168 offset:4704
	s_setprio 1
	s_waitcnt lgkmcnt(1)
	v_mfma_f32_32x32x16_bf16 v[112:127], v[172:175], v[224:227], v[112:127]
	v_mfma_f32_32x32x16_bf16 v[48:63], v[220:223], v[224:227], v[48:63]
	s_waitcnt lgkmcnt(0)
	v_mfma_f32_32x32x16_bf16 v[96:111], v[172:175], v[228:231], v[96:111]
	v_mfma_f32_32x32x16_bf16 v[32:47], v[220:223], v[228:231], v[32:47]
	ds_read_b128 v[224:227], v168 offset:9312
	ds_read_b128 v[228:231], v168 offset:13920
	s_waitcnt lgkmcnt(1)
	v_mfma_f32_32x32x16_bf16 v[80:95], v[172:175], v[224:227], v[80:95]
	v_mfma_f32_32x32x16_bf16 v[16:31], v[220:223], v[224:227], v[16:31]
	s_waitcnt lgkmcnt(0)
	v_mfma_f32_32x32x16_bf16 v[64:79], v[172:175], v[228:231], v[64:79]
	v_mfma_f32_32x32x16_bf16 v[0:15], v[220:223], v[228:231], v[0:15]
	s_setprio 0
	s_barrier
	global_load_dwordx4 v[172:175], v[128:129], off offset:512
	global_load_dwordx4 v[220:223], v[132:133], off offset:512
	s_waitcnt vmcnt(9)
	ds_write_b128 v195, v[158:161]
	s_waitcnt vmcnt(8)
	ds_write_b128 v196, v[162:165]
	ds_read_b128 v[158:161], v192 offset:36864
	ds_read_b128 v[162:165], v192 offset:41472
	ds_read_b128 v[224:227], v184
	ds_read_b128 v[228:231], v184 offset:4608
	s_setprio 1
	s_waitcnt lgkmcnt(1)
	v_mfma_f32_32x32x16_bf16 v[112:127], v[158:161], v[224:227], v[112:127]
	v_mfma_f32_32x32x16_bf16 v[48:63], v[162:165], v[224:227], v[48:63]
	s_waitcnt lgkmcnt(0)
	v_mfma_f32_32x32x16_bf16 v[96:111], v[158:161], v[228:231], v[96:111]
	v_mfma_f32_32x32x16_bf16 v[32:47], v[162:165], v[228:231], v[32:47]
	ds_read_b128 v[224:227], v184 offset:9216
	ds_read_b128 v[228:231], v184 offset:13824
	s_waitcnt vmcnt(7)
	ds_write_b128 v194, v[198:201]
	s_waitcnt vmcnt(6)
	ds_write_b128 v193, v[202:205]
	ds_read_b128 v[198:201], v192 offset:36896
	ds_read_b128 v[202:205], v192 offset:41504
	s_waitcnt lgkmcnt(5)
	v_mfma_f32_32x32x16_bf16 v[80:95], v[158:161], v[224:227], v[80:95]
	v_mfma_f32_32x32x16_bf16 v[16:31], v[162:165], v[224:227], v[16:31]
	ds_read_b128 v[224:227], v184 offset:32
	s_waitcnt lgkmcnt(5)
	v_mfma_f32_32x32x16_bf16 v[64:79], v[158:161], v[228:231], v[64:79]
	v_mfma_f32_32x32x16_bf16 v[0:15], v[162:165], v[228:231], v[0:15]
	ds_read_b128 v[228:231], v184 offset:4640
	global_load_dwordx4 v[158:161], v[136:137], off offset:512
	global_load_dwordx4 v[162:165], v[140:141], off offset:512
	s_waitcnt lgkmcnt(1)
	v_mfma_f32_32x32x16_bf16 v[112:127], v[198:201], v[224:227], v[112:127]
	v_mfma_f32_32x32x16_bf16 v[48:63], v[202:205], v[224:227], v[48:63]
	s_waitcnt lgkmcnt(0)
	v_mfma_f32_32x32x16_bf16 v[96:111], v[198:201], v[228:231], v[96:111]
	v_mfma_f32_32x32x16_bf16 v[32:47], v[202:205], v[228:231], v[32:47]
	ds_read_b128 v[224:227], v184 offset:9248
	ds_read_b128 v[228:231], v184 offset:13856
	s_waitcnt vmcnt(7)
	ds_write_b128 v177, v[208:211]
	s_waitcnt vmcnt(6)
	ds_write_b128 v176, v[212:215]
	ds_read_b128 v[208:211], v192 offset:36928
	ds_read_b128 v[212:215], v192 offset:41536
	s_waitcnt lgkmcnt(5)
	v_mfma_f32_32x32x16_bf16 v[80:95], v[198:201], v[224:227], v[80:95]
	v_mfma_f32_32x32x16_bf16 v[16:31], v[202:205], v[224:227], v[16:31]
	ds_read_b128 v[224:227], v184 offset:64
	s_waitcnt lgkmcnt(5)
	v_mfma_f32_32x32x16_bf16 v[64:79], v[198:201], v[228:231], v[64:79]
	v_mfma_f32_32x32x16_bf16 v[0:15], v[202:205], v[228:231], v[0:15]
	ds_read_b128 v[228:231], v184 offset:4672
	global_load_dwordx4 v[198:201], v[144:145], off offset:512
	global_load_dwordx4 v[202:205], v[148:149], off offset:512
	s_waitcnt lgkmcnt(1)
	v_mfma_f32_32x32x16_bf16 v[112:127], v[208:211], v[224:227], v[112:127]
	v_mfma_f32_32x32x16_bf16 v[48:63], v[212:215], v[224:227], v[48:63]
	s_waitcnt lgkmcnt(0)
	v_mfma_f32_32x32x16_bf16 v[96:111], v[208:211], v[228:231], v[96:111]
	v_mfma_f32_32x32x16_bf16 v[32:47], v[212:215], v[228:231], v[32:47]
	ds_read_b128 v[224:227], v184 offset:9280
	ds_read_b128 v[228:231], v184 offset:13888
	s_waitcnt vmcnt(7)
	ds_write_b128 v171, v[178:181]
	s_waitcnt vmcnt(6)
	ds_write_b128 v170, v[216:219]
	ds_read_b128 v[178:181], v192 offset:36960
	ds_read_b128 v[216:219], v192 offset:41568
	s_waitcnt lgkmcnt(5)
	v_mfma_f32_32x32x16_bf16 v[80:95], v[208:211], v[224:227], v[80:95]
	v_mfma_f32_32x32x16_bf16 v[16:31], v[212:215], v[224:227], v[16:31]
	ds_read_b128 v[224:227], v184 offset:96
	s_waitcnt lgkmcnt(5)
	v_mfma_f32_32x32x16_bf16 v[64:79], v[208:211], v[228:231], v[64:79]
	v_mfma_f32_32x32x16_bf16 v[0:15], v[212:215], v[228:231], v[0:15]
	ds_read_b128 v[228:231], v184 offset:4704
	global_load_dwordx4 v[208:211], v[152:153], off offset:512
	global_load_dwordx4 v[212:215], v[156:157], off offset:512
	s_waitcnt lgkmcnt(1)
	v_mfma_f32_32x32x16_bf16 v[112:127], v[178:181], v[224:227], v[112:127]
	v_mfma_f32_32x32x16_bf16 v[48:63], v[216:219], v[224:227], v[48:63]
	s_waitcnt lgkmcnt(0)
	v_mfma_f32_32x32x16_bf16 v[96:111], v[178:181], v[228:231], v[96:111]
	v_mfma_f32_32x32x16_bf16 v[32:47], v[216:219], v[228:231], v[32:47]
	ds_read_b128 v[224:227], v184 offset:9312
	ds_read_b128 v[228:231], v184 offset:13920
	s_waitcnt lgkmcnt(1)
	v_mfma_f32_32x32x16_bf16 v[80:95], v[178:181], v[224:227], v[80:95]
	v_mfma_f32_32x32x16_bf16 v[16:31], v[216:219], v[224:227], v[16:31]
	s_waitcnt lgkmcnt(0)
	v_mfma_f32_32x32x16_bf16 v[64:79], v[178:181], v[228:231], v[64:79]
	v_mfma_f32_32x32x16_bf16 v[0:15], v[216:219], v[228:231], v[0:15]
	s_setprio 0
	s_barrier
	global_load_dwordx4 v[178:181], v[128:129], off offset:640
	global_load_dwordx4 v[216:219], v[132:133], off offset:640
	s_waitcnt vmcnt(9)
	ds_write_b128 v191, v[172:175]
	s_waitcnt vmcnt(8)
	ds_write_b128 v191, v[220:223] offset:36864
	ds_read_b128 v[172:175], v169
	ds_read_b128 v[220:223], v169 offset:4608
	ds_read_b128 v[224:227], v168
	ds_read_b128 v[228:231], v168 offset:4608
	s_setprio 1
	s_waitcnt lgkmcnt(1)
	v_mfma_f32_32x32x16_bf16 v[112:127], v[172:175], v[224:227], v[112:127]
	v_mfma_f32_32x32x16_bf16 v[48:63], v[220:223], v[224:227], v[48:63]
	s_waitcnt lgkmcnt(0)
	v_mfma_f32_32x32x16_bf16 v[96:111], v[172:175], v[228:231], v[96:111]
	v_mfma_f32_32x32x16_bf16 v[32:47], v[220:223], v[228:231], v[32:47]
	ds_read_b128 v[224:227], v168 offset:9216
	ds_read_b128 v[228:231], v168 offset:13824
	s_waitcnt vmcnt(7)
	ds_write_b128 v191, v[158:161] offset:9216
	s_waitcnt vmcnt(6)
	ds_write_b128 v191, v[162:165] offset:46080
	ds_read_b128 v[158:161], v169 offset:32
	ds_read_b128 v[162:165], v169 offset:4640
	s_waitcnt lgkmcnt(5)
	v_mfma_f32_32x32x16_bf16 v[80:95], v[172:175], v[224:227], v[80:95]
	v_mfma_f32_32x32x16_bf16 v[16:31], v[220:223], v[224:227], v[16:31]
	ds_read_b128 v[224:227], v168 offset:32
	s_waitcnt lgkmcnt(5)
	v_mfma_f32_32x32x16_bf16 v[64:79], v[172:175], v[228:231], v[64:79]
	v_mfma_f32_32x32x16_bf16 v[0:15], v[220:223], v[228:231], v[0:15]
	ds_read_b128 v[228:231], v168 offset:4640
	global_load_dwordx4 v[172:175], v[136:137], off offset:640
	global_load_dwordx4 v[220:223], v[140:141], off offset:640
	s_waitcnt lgkmcnt(1)
	v_mfma_f32_32x32x16_bf16 v[112:127], v[158:161], v[224:227], v[112:127]
	v_mfma_f32_32x32x16_bf16 v[48:63], v[162:165], v[224:227], v[48:63]
	s_waitcnt lgkmcnt(0)
	v_mfma_f32_32x32x16_bf16 v[96:111], v[158:161], v[228:231], v[96:111]
	v_mfma_f32_32x32x16_bf16 v[32:47], v[162:165], v[228:231], v[32:47]
	ds_read_b128 v[224:227], v168 offset:9248
	ds_read_b128 v[228:231], v168 offset:13856
	s_waitcnt vmcnt(7)
	ds_write_b128 v191, v[198:201] offset:18432
	s_waitcnt vmcnt(6)
	ds_write_b128 v191, v[202:205] offset:55296
	ds_read_b128 v[198:201], v169 offset:64
	ds_read_b128 v[202:205], v169 offset:4672
	s_waitcnt lgkmcnt(5)
	v_mfma_f32_32x32x16_bf16 v[80:95], v[158:161], v[224:227], v[80:95]
	v_mfma_f32_32x32x16_bf16 v[16:31], v[162:165], v[224:227], v[16:31]
	ds_read_b128 v[224:227], v168 offset:64
	s_waitcnt lgkmcnt(5)
	v_mfma_f32_32x32x16_bf16 v[64:79], v[158:161], v[228:231], v[64:79]
	v_mfma_f32_32x32x16_bf16 v[0:15], v[162:165], v[228:231], v[0:15]
	ds_read_b128 v[228:231], v168 offset:4672
	global_load_dwordx4 v[158:161], v[144:145], off offset:640
	global_load_dwordx4 v[162:165], v[148:149], off offset:640
	s_waitcnt lgkmcnt(1)
	v_mfma_f32_32x32x16_bf16 v[112:127], v[198:201], v[224:227], v[112:127]
	v_mfma_f32_32x32x16_bf16 v[48:63], v[202:205], v[224:227], v[48:63]
	s_waitcnt lgkmcnt(0)
	v_mfma_f32_32x32x16_bf16 v[96:111], v[198:201], v[228:231], v[96:111]
	v_mfma_f32_32x32x16_bf16 v[32:47], v[202:205], v[228:231], v[32:47]
	ds_read_b128 v[224:227], v168 offset:9280
	ds_read_b128 v[228:231], v168 offset:13888
	s_waitcnt vmcnt(7)
	ds_write_b128 v191, v[208:211] offset:27648
	s_waitcnt vmcnt(6)
	ds_write_b128 v191, v[212:215] offset:64512
	ds_read_b128 v[208:211], v169 offset:96
	ds_read_b128 v[212:215], v169 offset:4704
	s_waitcnt lgkmcnt(5)
	v_mfma_f32_32x32x16_bf16 v[80:95], v[198:201], v[224:227], v[80:95]
	v_mfma_f32_32x32x16_bf16 v[16:31], v[202:205], v[224:227], v[16:31]
	ds_read_b128 v[224:227], v168 offset:96
	s_waitcnt lgkmcnt(5)
	v_mfma_f32_32x32x16_bf16 v[64:79], v[198:201], v[228:231], v[64:79]
	v_mfma_f32_32x32x16_bf16 v[0:15], v[202:205], v[228:231], v[0:15]
	ds_read_b128 v[228:231], v168 offset:4704
	global_load_dwordx4 v[198:201], v[152:153], off offset:640
	global_load_dwordx4 v[202:205], v[156:157], off offset:640
	s_waitcnt lgkmcnt(1)
	v_mfma_f32_32x32x16_bf16 v[112:127], v[208:211], v[224:227], v[112:127]
	v_mfma_f32_32x32x16_bf16 v[48:63], v[212:215], v[224:227], v[48:63]
	s_waitcnt lgkmcnt(0)
	v_mfma_f32_32x32x16_bf16 v[96:111], v[208:211], v[228:231], v[96:111]
	v_mfma_f32_32x32x16_bf16 v[32:47], v[212:215], v[228:231], v[32:47]
	ds_read_b128 v[224:227], v168 offset:9312
	ds_read_b128 v[228:231], v168 offset:13920
	s_waitcnt lgkmcnt(1)
	v_mfma_f32_32x32x16_bf16 v[80:95], v[208:211], v[224:227], v[80:95]
	v_mfma_f32_32x32x16_bf16 v[16:31], v[212:215], v[224:227], v[16:31]
	s_waitcnt lgkmcnt(0)
	v_mfma_f32_32x32x16_bf16 v[64:79], v[208:211], v[228:231], v[64:79]
	v_mfma_f32_32x32x16_bf16 v[0:15], v[212:215], v[228:231], v[0:15]
	s_setprio 0
	s_barrier
	global_load_dwordx4 v[208:211], v[128:129], off offset:768
	global_load_dwordx4 v[212:215], v[132:133], off offset:768
	s_waitcnt vmcnt(9)
	ds_write_b128 v195, v[178:181]
	s_waitcnt vmcnt(8)
	ds_write_b128 v196, v[216:219]
	ds_read_b128 v[178:181], v192 offset:36864
	ds_read_b128 v[216:219], v192 offset:41472
	ds_read_b128 v[224:227], v184
	ds_read_b128 v[228:231], v184 offset:4608
	s_setprio 1
	s_waitcnt lgkmcnt(1)
	v_mfma_f32_32x32x16_bf16 v[112:127], v[178:181], v[224:227], v[112:127]
	v_mfma_f32_32x32x16_bf16 v[48:63], v[216:219], v[224:227], v[48:63]
	s_waitcnt lgkmcnt(0)
	v_mfma_f32_32x32x16_bf16 v[96:111], v[178:181], v[228:231], v[96:111]
	v_mfma_f32_32x32x16_bf16 v[32:47], v[216:219], v[228:231], v[32:47]
	ds_read_b128 v[224:227], v184 offset:9216
	ds_read_b128 v[228:231], v184 offset:13824
	s_waitcnt vmcnt(7)
	ds_write_b128 v194, v[172:175]
	s_waitcnt vmcnt(6)
	ds_write_b128 v193, v[220:223]
	ds_read_b128 v[172:175], v192 offset:36896
	ds_read_b128 v[220:223], v192 offset:41504
	s_waitcnt lgkmcnt(5)
	v_mfma_f32_32x32x16_bf16 v[80:95], v[178:181], v[224:227], v[80:95]
	v_mfma_f32_32x32x16_bf16 v[16:31], v[216:219], v[224:227], v[16:31]
	ds_read_b128 v[224:227], v184 offset:32
	s_waitcnt lgkmcnt(5)
	v_mfma_f32_32x32x16_bf16 v[64:79], v[178:181], v[228:231], v[64:79]
	v_mfma_f32_32x32x16_bf16 v[0:15], v[216:219], v[228:231], v[0:15]
	ds_read_b128 v[228:231], v184 offset:4640
	global_load_dwordx4 v[178:181], v[136:137], off offset:768
	global_load_dwordx4 v[216:219], v[140:141], off offset:768
	s_waitcnt lgkmcnt(1)
	v_mfma_f32_32x32x16_bf16 v[112:127], v[172:175], v[224:227], v[112:127]
	v_mfma_f32_32x32x16_bf16 v[48:63], v[220:223], v[224:227], v[48:63]
	s_waitcnt lgkmcnt(0)
	v_mfma_f32_32x32x16_bf16 v[96:111], v[172:175], v[228:231], v[96:111]
	v_mfma_f32_32x32x16_bf16 v[32:47], v[220:223], v[228:231], v[32:47]
	ds_read_b128 v[224:227], v184 offset:9248
	ds_read_b128 v[228:231], v184 offset:13856
	s_waitcnt vmcnt(7)
	ds_write_b128 v177, v[158:161]
	s_waitcnt vmcnt(6)
	ds_write_b128 v176, v[162:165]
	ds_read_b128 v[158:161], v192 offset:36928
	ds_read_b128 v[162:165], v192 offset:41536
	s_waitcnt lgkmcnt(5)
	v_mfma_f32_32x32x16_bf16 v[80:95], v[172:175], v[224:227], v[80:95]
	v_mfma_f32_32x32x16_bf16 v[16:31], v[220:223], v[224:227], v[16:31]
	ds_read_b128 v[224:227], v184 offset:64
	s_waitcnt lgkmcnt(5)
	v_mfma_f32_32x32x16_bf16 v[64:79], v[172:175], v[228:231], v[64:79]
	v_mfma_f32_32x32x16_bf16 v[0:15], v[220:223], v[228:231], v[0:15]
	ds_read_b128 v[228:231], v184 offset:4672
	global_load_dwordx4 v[172:175], v[144:145], off offset:768
	global_load_dwordx4 v[220:223], v[148:149], off offset:768
	s_waitcnt lgkmcnt(1)
	v_mfma_f32_32x32x16_bf16 v[112:127], v[158:161], v[224:227], v[112:127]
	v_mfma_f32_32x32x16_bf16 v[48:63], v[162:165], v[224:227], v[48:63]
	s_waitcnt lgkmcnt(0)
	v_mfma_f32_32x32x16_bf16 v[96:111], v[158:161], v[228:231], v[96:111]
	v_mfma_f32_32x32x16_bf16 v[32:47], v[162:165], v[228:231], v[32:47]
	ds_read_b128 v[224:227], v184 offset:9280
	ds_read_b128 v[228:231], v184 offset:13888
	s_waitcnt vmcnt(7)
	ds_write_b128 v171, v[198:201]
	s_waitcnt vmcnt(6)
	ds_write_b128 v170, v[202:205]
	ds_read_b128 v[198:201], v192 offset:36960
	ds_read_b128 v[202:205], v192 offset:41568
	s_waitcnt lgkmcnt(5)
	v_mfma_f32_32x32x16_bf16 v[80:95], v[158:161], v[224:227], v[80:95]
	v_mfma_f32_32x32x16_bf16 v[16:31], v[162:165], v[224:227], v[16:31]
	ds_read_b128 v[224:227], v184 offset:96
	s_waitcnt lgkmcnt(5)
	v_mfma_f32_32x32x16_bf16 v[64:79], v[158:161], v[228:231], v[64:79]
	v_mfma_f32_32x32x16_bf16 v[0:15], v[162:165], v[228:231], v[0:15]
	ds_read_b128 v[228:231], v184 offset:4704
	global_load_dwordx4 v[158:161], v[152:153], off offset:768
	global_load_dwordx4 v[162:165], v[156:157], off offset:768
	s_waitcnt lgkmcnt(1)
	v_mfma_f32_32x32x16_bf16 v[112:127], v[198:201], v[224:227], v[112:127]
	v_mfma_f32_32x32x16_bf16 v[48:63], v[202:205], v[224:227], v[48:63]
	s_waitcnt lgkmcnt(0)
	v_mfma_f32_32x32x16_bf16 v[96:111], v[198:201], v[228:231], v[96:111]
	v_mfma_f32_32x32x16_bf16 v[32:47], v[202:205], v[228:231], v[32:47]
	ds_read_b128 v[224:227], v184 offset:9312
	ds_read_b128 v[228:231], v184 offset:13920
	s_waitcnt lgkmcnt(1)
	v_mfma_f32_32x32x16_bf16 v[80:95], v[198:201], v[224:227], v[80:95]
	v_mfma_f32_32x32x16_bf16 v[16:31], v[202:205], v[224:227], v[16:31]
	s_waitcnt lgkmcnt(0)
	v_mfma_f32_32x32x16_bf16 v[64:79], v[198:201], v[228:231], v[64:79]
	v_mfma_f32_32x32x16_bf16 v[0:15], v[202:205], v[228:231], v[0:15]
	s_setprio 0
	s_barrier
; template <bool trans>
; DI void gemm_core(const GTile& tl, const GTile& nx, bool has_next  , bool chain  , bool pre, u32x4 (&ra)[4], u32x4 (&rb)[4], char* smem, f32x16 (&acc)[2][4]) {
;     ...
;   const int nk = K / 64;
;   if (!pre) { G_LOAD(0); G_STORE(0); G_LOAD(1); }
;   for (int kt = 0; kt < nk; ++kt) {
;     __syncthreads();
;     G_COMPUTE(kt & 1, kt);
	global_load_dwordx4 v[198:201], v[128:129], off offset:896
	global_load_dwordx4 v[202:205], v[132:133], off offset:896
	s_waitcnt vmcnt(9)
	ds_write_b128 v191, v[208:211]
	s_waitcnt vmcnt(8)
	ds_write_b128 v191, v[212:215] offset:36864
	ds_read_b128 v[208:211], v169
	ds_read_b128 v[212:215], v169 offset:4608
	ds_read_b128 v[224:227], v168
	ds_read_b128 v[228:231], v168 offset:4608
	s_setprio 1
	s_waitcnt lgkmcnt(1)
	v_mfma_f32_32x32x16_bf16 v[112:127], v[208:211], v[224:227], v[112:127]
	v_mfma_f32_32x32x16_bf16 v[48:63], v[212:215], v[224:227], v[48:63]
	s_waitcnt lgkmcnt(0)
	v_mfma_f32_32x32x16_bf16 v[96:111], v[208:211], v[228:231], v[96:111]
	v_mfma_f32_32x32x16_bf16 v[32:47], v[212:215], v[228:231], v[32:47]
	ds_read_b128 v[224:227], v168 offset:9216
	ds_read_b128 v[228:231], v168 offset:13824
	s_waitcnt vmcnt(7)
	ds_write_b128 v191, v[178:181] offset:9216
	s_waitcnt vmcnt(6)
	ds_write_b128 v191, v[216:219] offset:46080
	ds_read_b128 v[178:181], v169 offset:32
	ds_read_b128 v[216:219], v169 offset:4640
	s_waitcnt lgkmcnt(5)
	v_mfma_f32_32x32x16_bf16 v[80:95], v[208:211], v[224:227], v[80:95]
	v_mfma_f32_32x32x16_bf16 v[16:31], v[212:215], v[224:227], v[16:31]
	ds_read_b128 v[224:227], v168 offset:32
	s_waitcnt lgkmcnt(5)
	v_mfma_f32_32x32x16_bf16 v[64:79], v[208:211], v[228:231], v[64:79]
	v_mfma_f32_32x32x16_bf16 v[0:15], v[212:215], v[228:231], v[0:15]
	ds_read_b128 v[228:231], v168 offset:4640
	global_load_dwordx4 v[208:211], v[136:137], off offset:896
	global_load_dwordx4 v[212:215], v[140:141], off offset:896
	s_waitcnt lgkmcnt(1)
	v_mfma_f32_32x32x16_bf16 v[112:127], v[178:181], v[224:227], v[112:127]
	v_mfma_f32_32x32x16_bf16 v[48:63], v[216:219], v[224:227], v[48:63]
	s_waitcnt lgkmcnt(0)
	v_mfma_f32_32x32x16_bf16 v[96:111], v[178:181], v[228:231], v[96:111]
	v_mfma_f32_32x32x16_bf16 v[32:47], v[216:219], v[228:231], v[32:47]
	ds_read_b128 v[224:227], v168 offset:9248
	ds_read_b128 v[228:231], v168 offset:13856
	s_waitcnt vmcnt(7)
	ds_write_b128 v191, v[172:175] offset:18432
	s_waitcnt vmcnt(6)
	ds_write_b128 v191, v[220:223] offset:55296
	ds_read_b128 v[172:175], v169 offset:64
	ds_read_b128 v[220:223], v169 offset:4672
	s_waitcnt lgkmcnt(5)
	v_mfma_f32_32x32x16_bf16 v[80:95], v[178:181], v[224:227], v[80:95]
	v_mfma_f32_32x32x16_bf16 v[16:31], v[216:219], v[224:227], v[16:31]
	ds_read_b128 v[224:227], v168 offset:64
	s_waitcnt lgkmcnt(5)
	v_mfma_f32_32x32x16_bf16 v[64:79], v[178:181], v[228:231], v[64:79]
	v_mfma_f32_32x32x16_bf16 v[0:15], v[216:219], v[228:231], v[0:15]
	ds_read_b128 v[228:231], v168 offset:4672
	global_load_dwordx4 v[178:181], v[144:145], off offset:896
	global_load_dwordx4 v[216:219], v[148:149], off offset:896
	s_waitcnt lgkmcnt(1)
	v_mfma_f32_32x32x16_bf16 v[112:127], v[172:175], v[224:227], v[112:127]
	v_mfma_f32_32x32x16_bf16 v[48:63], v[220:223], v[224:227], v[48:63]
	s_waitcnt lgkmcnt(0)
	v_mfma_f32_32x32x16_bf16 v[96:111], v[172:175], v[228:231], v[96:111]
	v_mfma_f32_32x32x16_bf16 v[32:47], v[220:223], v[228:231], v[32:47]
	ds_read_b128 v[224:227], v168 offset:9280
	ds_read_b128 v[228:231], v168 offset:13888
	s_waitcnt vmcnt(7)
	ds_write_b128 v191, v[158:161] offset:27648
	s_waitcnt vmcnt(6)
	ds_write_b128 v191, v[162:165] offset:64512
	ds_read_b128 v[158:161], v169 offset:96
	ds_read_b128 v[162:165], v169 offset:4704
	s_waitcnt lgkmcnt(5)
	v_mfma_f32_32x32x16_bf16 v[80:95], v[172:175], v[224:227], v[80:95]
	v_mfma_f32_32x32x16_bf16 v[16:31], v[220:223], v[224:227], v[16:31]
	ds_read_b128 v[224:227], v168 offset:96
	s_waitcnt lgkmcnt(5)
	v_mfma_f32_32x32x16_bf16 v[64:79], v[172:175], v[228:231], v[64:79]
	v_mfma_f32_32x32x16_bf16 v[0:15], v[220:223], v[228:231], v[0:15]
	ds_read_b128 v[228:231], v168 offset:4704
	global_load_dwordx4 v[172:175], v[152:153], off offset:896
	global_load_dwordx4 v[220:223], v[156:157], off offset:896
	s_waitcnt lgkmcnt(1)
	v_mfma_f32_32x32x16_bf16 v[112:127], v[158:161], v[224:227], v[112:127]
	v_mfma_f32_32x32x16_bf16 v[48:63], v[162:165], v[224:227], v[48:63]
	s_waitcnt lgkmcnt(0)
	v_mfma_f32_32x32x16_bf16 v[96:111], v[158:161], v[228:231], v[96:111]
	v_mfma_f32_32x32x16_bf16 v[32:47], v[162:165], v[228:231], v[32:47]
	ds_read_b128 v[224:227], v168 offset:9312
	ds_read_b128 v[228:231], v168 offset:13920
	s_waitcnt lgkmcnt(1)
	v_mfma_f32_32x32x16_bf16 v[80:95], v[158:161], v[224:227], v[80:95]
	v_mfma_f32_32x32x16_bf16 v[16:31], v[162:165], v[224:227], v[16:31]
	s_waitcnt lgkmcnt(0)
	v_mfma_f32_32x32x16_bf16 v[64:79], v[158:161], v[228:231], v[64:79]
	v_mfma_f32_32x32x16_bf16 v[0:15], v[162:165], v[228:231], v[0:15]
	s_setprio 0
	s_barrier
; template <bool trans>
; DI void gemm_core(const GTile& tl, const GTile& nx, bool has_next  , bool chain  , bool pre, u32x4 (&ra)[4], u32x4 (&rb)[4], char* smem, f32x16 (&acc)[2][4]) {
;     ...
;   const int nk = K / 64;
;   if (!pre) { G_LOAD(0); G_STORE(0); G_LOAD(1); }
;   for (int kt = 0; kt < nk; ++kt) {
;     __syncthreads();
;     G_COMPUTE(kt & 1, kt);
	global_load_dwordx4 v[158:161], v[128:129], off offset:1024
	global_load_dwordx4 v[162:165], v[132:133], off offset:1024
	s_waitcnt vmcnt(9)
	ds_write_b128 v195, v[198:201]
	s_waitcnt vmcnt(8)
	ds_write_b128 v196, v[202:205]
	ds_read_b128 v[198:201], v192 offset:36864
	ds_read_b128 v[202:205], v192 offset:41472
	ds_read_b128 v[224:227], v184
	ds_read_b128 v[228:231], v184 offset:4608
	s_setprio 1
	s_waitcnt lgkmcnt(1)
	v_mfma_f32_32x32x16_bf16 v[112:127], v[198:201], v[224:227], v[112:127]
	v_mfma_f32_32x32x16_bf16 v[48:63], v[202:205], v[224:227], v[48:63]
	s_waitcnt lgkmcnt(0)
	v_mfma_f32_32x32x16_bf16 v[96:111], v[198:201], v[228:231], v[96:111]
	v_mfma_f32_32x32x16_bf16 v[32:47], v[202:205], v[228:231], v[32:47]
	ds_read_b128 v[224:227], v184 offset:9216
	ds_read_b128 v[228:231], v184 offset:13824
	s_waitcnt vmcnt(7)
	ds_write_b128 v194, v[208:211]
	s_waitcnt vmcnt(6)
	ds_write_b128 v193, v[212:215]
	ds_read_b128 v[208:211], v192 offset:36896
	ds_read_b128 v[212:215], v192 offset:41504
	s_waitcnt lgkmcnt(5)
	v_mfma_f32_32x32x16_bf16 v[80:95], v[198:201], v[224:227], v[80:95]
	v_mfma_f32_32x32x16_bf16 v[16:31], v[202:205], v[224:227], v[16:31]
	ds_read_b128 v[224:227], v184 offset:32
	s_waitcnt lgkmcnt(5)
	v_mfma_f32_32x32x16_bf16 v[64:79], v[198:201], v[228:231], v[64:79]
	v_mfma_f32_32x32x16_bf16 v[0:15], v[202:205], v[228:231], v[0:15]
	ds_read_b128 v[228:231], v184 offset:4640
	global_load_dwordx4 v[198:201], v[136:137], off offset:1024
	global_load_dwordx4 v[202:205], v[140:141], off offset:1024
	s_waitcnt lgkmcnt(1)
	v_mfma_f32_32x32x16_bf16 v[112:127], v[208:211], v[224:227], v[112:127]
	v_mfma_f32_32x32x16_bf16 v[48:63], v[212:215], v[224:227], v[48:63]
	s_waitcnt lgkmcnt(0)
	v_mfma_f32_32x32x16_bf16 v[96:111], v[208:211], v[228:231], v[96:111]
	v_mfma_f32_32x32x16_bf16 v[32:47], v[212:215], v[228:231], v[32:47]
	ds_read_b128 v[224:227], v184 offset:9248
	ds_read_b128 v[228:231], v184 offset:13856
	s_waitcnt vmcnt(7)
	ds_write_b128 v177, v[178:181]
	s_waitcnt vmcnt(6)
	ds_write_b128 v176, v[216:219]
	ds_read_b128 v[178:181], v192 offset:36928
	ds_read_b128 v[216:219], v192 offset:41536
	s_waitcnt lgkmcnt(5)
	v_mfma_f32_32x32x16_bf16 v[80:95], v[208:211], v[224:227], v[80:95]
	v_mfma_f32_32x32x16_bf16 v[16:31], v[212:215], v[224:227], v[16:31]
	ds_read_b128 v[224:227], v184 offset:64
	s_waitcnt lgkmcnt(5)
	v_mfma_f32_32x32x16_bf16 v[64:79], v[208:211], v[228:231], v[64:79]
	v_mfma_f32_32x32x16_bf16 v[0:15], v[212:215], v[228:231], v[0:15]
	ds_read_b128 v[228:231], v184 offset:4672
	global_load_dwordx4 v[208:211], v[144:145], off offset:1024
	global_load_dwordx4 v[212:215], v[148:149], off offset:1024
	s_waitcnt lgkmcnt(1)
	v_mfma_f32_32x32x16_bf16 v[112:127], v[178:181], v[224:227], v[112:127]
	v_mfma_f32_32x32x16_bf16 v[48:63], v[216:219], v[224:227], v[48:63]
	s_waitcnt lgkmcnt(0)
	v_mfma_f32_32x32x16_bf16 v[96:111], v[178:181], v[228:231], v[96:111]
	v_mfma_f32_32x32x16_bf16 v[32:47], v[216:219], v[228:231], v[32:47]
	ds_read_b128 v[224:227], v184 offset:9280
	ds_read_b128 v[228:231], v184 offset:13888
	s_waitcnt vmcnt(7)
	ds_write_b128 v171, v[172:175]
	s_waitcnt vmcnt(6)
	ds_write_b128 v170, v[220:223]
	ds_read_b128 v[172:175], v192 offset:36960
	ds_read_b128 v[220:223], v192 offset:41568
	s_waitcnt lgkmcnt(5)
	v_mfma_f32_32x32x16_bf16 v[80:95], v[178:181], v[224:227], v[80:95]
	v_mfma_f32_32x32x16_bf16 v[16:31], v[216:219], v[224:227], v[16:31]
	ds_read_b128 v[224:227], v184 offset:96
	s_waitcnt lgkmcnt(5)
	v_mfma_f32_32x32x16_bf16 v[64:79], v[178:181], v[228:231], v[64:79]
	v_mfma_f32_32x32x16_bf16 v[0:15], v[216:219], v[228:231], v[0:15]
	ds_read_b128 v[228:231], v184 offset:4704
	global_load_dwordx4 v[178:181], v[152:153], off offset:1024
	global_load_dwordx4 v[216:219], v[156:157], off offset:1024
	s_waitcnt lgkmcnt(1)
	v_mfma_f32_32x32x16_bf16 v[112:127], v[172:175], v[224:227], v[112:127]
	v_mfma_f32_32x32x16_bf16 v[48:63], v[220:223], v[224:227], v[48:63]
	s_waitcnt lgkmcnt(0)
	v_mfma_f32_32x32x16_bf16 v[96:111], v[172:175], v[228:231], v[96:111]
	v_mfma_f32_32x32x16_bf16 v[32:47], v[220:223], v[228:231], v[32:47]
	ds_read_b128 v[224:227], v184 offset:9312
	ds_read_b128 v[228:231], v184 offset:13920
	s_waitcnt lgkmcnt(1)
	v_mfma_f32_32x32x16_bf16 v[80:95], v[172:175], v[224:227], v[80:95]
	v_mfma_f32_32x32x16_bf16 v[16:31], v[220:223], v[224:227], v[16:31]
	s_waitcnt lgkmcnt(0)
	v_mfma_f32_32x32x16_bf16 v[64:79], v[172:175], v[228:231], v[64:79]
	v_mfma_f32_32x32x16_bf16 v[0:15], v[220:223], v[228:231], v[0:15]
	s_setprio 0
	s_barrier
; template <bool trans>
; DI void gemm_core(const GTile& tl, const GTile& nx, bool has_next  , bool chain  , bool pre, u32x4 (&ra)[4], u32x4 (&rb)[4], char* smem, f32x16 (&acc)[2][4]) {
;     ...
;   const int nk = K / 64;
;   if (!pre) { G_LOAD(0); G_STORE(0); G_LOAD(1); }
;   for (int kt = 0; kt < nk; ++kt) {
;     __syncthreads();
;     G_COMPUTE(kt & 1, kt);
	global_load_dwordx4 v[172:175], v[128:129], off offset:1152
	global_load_dwordx4 v[220:223], v[132:133], off offset:1152
	s_waitcnt vmcnt(9)
	ds_write_b128 v191, v[158:161]
	s_waitcnt vmcnt(8)
	ds_write_b128 v191, v[162:165] offset:36864
	ds_read_b128 v[158:161], v169
	ds_read_b128 v[162:165], v169 offset:4608
	ds_read_b128 v[224:227], v168
	ds_read_b128 v[228:231], v168 offset:4608
	s_setprio 1
	s_waitcnt lgkmcnt(1)
	v_mfma_f32_32x32x16_bf16 v[112:127], v[158:161], v[224:227], v[112:127]
	v_mfma_f32_32x32x16_bf16 v[48:63], v[162:165], v[224:227], v[48:63]
	s_waitcnt lgkmcnt(0)
	v_mfma_f32_32x32x16_bf16 v[96:111], v[158:161], v[228:231], v[96:111]
	v_mfma_f32_32x32x16_bf16 v[32:47], v[162:165], v[228:231], v[32:47]
	ds_read_b128 v[224:227], v168 offset:9216
	ds_read_b128 v[228:231], v168 offset:13824
	s_waitcnt vmcnt(7)
	ds_write_b128 v191, v[198:201] offset:9216
	s_waitcnt vmcnt(6)
	ds_write_b128 v191, v[202:205] offset:46080
	ds_read_b128 v[198:201], v169 offset:32
	ds_read_b128 v[202:205], v169 offset:4640
	s_waitcnt lgkmcnt(5)
	v_mfma_f32_32x32x16_bf16 v[80:95], v[158:161], v[224:227], v[80:95]
	v_mfma_f32_32x32x16_bf16 v[16:31], v[162:165], v[224:227], v[16:31]
	ds_read_b128 v[224:227], v168 offset:32
	s_waitcnt lgkmcnt(5)
	v_mfma_f32_32x32x16_bf16 v[64:79], v[158:161], v[228:231], v[64:79]
	v_mfma_f32_32x32x16_bf16 v[0:15], v[162:165], v[228:231], v[0:15]
	ds_read_b128 v[228:231], v168 offset:4640
	global_load_dwordx4 v[158:161], v[136:137], off offset:1152
	global_load_dwordx4 v[162:165], v[140:141], off offset:1152
	s_waitcnt lgkmcnt(1)
	v_mfma_f32_32x32x16_bf16 v[112:127], v[198:201], v[224:227], v[112:127]
	v_mfma_f32_32x32x16_bf16 v[48:63], v[202:205], v[224:227], v[48:63]
	s_waitcnt lgkmcnt(0)
	v_mfma_f32_32x32x16_bf16 v[96:111], v[198:201], v[228:231], v[96:111]
	v_mfma_f32_32x32x16_bf16 v[32:47], v[202:205], v[228:231], v[32:47]
	ds_read_b128 v[224:227], v168 offset:9248
	ds_read_b128 v[228:231], v168 offset:13856
	s_waitcnt vmcnt(7)
	ds_write_b128 v191, v[208:211] offset:18432
	s_waitcnt vmcnt(6)
	ds_write_b128 v191, v[212:215] offset:55296
	ds_read_b128 v[208:211], v169 offset:64
	ds_read_b128 v[212:215], v169 offset:4672
	s_waitcnt lgkmcnt(5)
	v_mfma_f32_32x32x16_bf16 v[80:95], v[198:201], v[224:227], v[80:95]
	v_mfma_f32_32x32x16_bf16 v[16:31], v[202:205], v[224:227], v[16:31]
	ds_read_b128 v[224:227], v168 offset:64
	s_waitcnt lgkmcnt(5)
	v_mfma_f32_32x32x16_bf16 v[64:79], v[198:201], v[228:231], v[64:79]
	v_mfma_f32_32x32x16_bf16 v[0:15], v[202:205], v[228:231], v[0:15]
	ds_read_b128 v[228:231], v168 offset:4672
	global_load_dwordx4 v[198:201], v[144:145], off offset:1152
	global_load_dwordx4 v[202:205], v[148:149], off offset:1152
	s_waitcnt lgkmcnt(1)
	v_mfma_f32_32x32x16_bf16 v[112:127], v[208:211], v[224:227], v[112:127]
	v_mfma_f32_32x32x16_bf16 v[48:63], v[212:215], v[224:227], v[48:63]
	s_waitcnt lgkmcnt(0)
	v_mfma_f32_32x32x16_bf16 v[96:111], v[208:211], v[228:231], v[96:111]
	v_mfma_f32_32x32x16_bf16 v[32:47], v[212:215], v[228:231], v[32:47]
	ds_read_b128 v[224:227], v168 offset:9280
	ds_read_b128 v[228:231], v168 offset:13888
	s_waitcnt vmcnt(7)
	ds_write_b128 v191, v[178:181] offset:27648
	s_waitcnt vmcnt(6)
	ds_write_b128 v191, v[216:219] offset:64512
	ds_read_b128 v[178:181], v169 offset:96
	ds_read_b128 v[216:219], v169 offset:4704
	s_waitcnt lgkmcnt(5)
	v_mfma_f32_32x32x16_bf16 v[80:95], v[208:211], v[224:227], v[80:95]
	v_mfma_f32_32x32x16_bf16 v[16:31], v[212:215], v[224:227], v[16:31]
	ds_read_b128 v[224:227], v168 offset:96
	s_waitcnt lgkmcnt(5)
	v_mfma_f32_32x32x16_bf16 v[64:79], v[208:211], v[228:231], v[64:79]
	v_mfma_f32_32x32x16_bf16 v[0:15], v[212:215], v[228:231], v[0:15]
	ds_read_b128 v[228:231], v168 offset:4704
	global_load_dwordx4 v[208:211], v[152:153], off offset:1152
	global_load_dwordx4 v[212:215], v[156:157], off offset:1152
	s_waitcnt lgkmcnt(1)
	v_mfma_f32_32x32x16_bf16 v[112:127], v[178:181], v[224:227], v[112:127]
	v_mfma_f32_32x32x16_bf16 v[48:63], v[216:219], v[224:227], v[48:63]
	s_waitcnt lgkmcnt(0)
	v_mfma_f32_32x32x16_bf16 v[96:111], v[178:181], v[228:231], v[96:111]
	v_mfma_f32_32x32x16_bf16 v[32:47], v[216:219], v[228:231], v[32:47]
	ds_read_b128 v[224:227], v168 offset:9312
	ds_read_b128 v[228:231], v168 offset:13920
	s_waitcnt lgkmcnt(1)
	v_mfma_f32_32x32x16_bf16 v[80:95], v[178:181], v[224:227], v[80:95]
	v_mfma_f32_32x32x16_bf16 v[16:31], v[216:219], v[224:227], v[16:31]
	s_waitcnt lgkmcnt(0)
	v_mfma_f32_32x32x16_bf16 v[64:79], v[178:181], v[228:231], v[64:79]
	v_mfma_f32_32x32x16_bf16 v[0:15], v[216:219], v[228:231], v[0:15]
	s_setprio 0
	s_barrier
; template <bool trans>
; DI void gemm_core(const GTile& tl, const GTile& nx, bool has_next  , bool chain  , bool pre, u32x4 (&ra)[4], u32x4 (&rb)[4], char* smem, f32x16 (&acc)[2][4]) {
;     ...
;   const int nk = K / 64;
;   if (!pre) { G_LOAD(0); G_STORE(0); G_LOAD(1); }
;   for (int kt = 0; kt < nk; ++kt) {
;     __syncthreads();
;     G_COMPUTE(kt & 1, kt);
	global_load_dwordx4 v[178:181], v[128:129], off offset:1280
	global_load_dwordx4 v[216:219], v[132:133], off offset:1280
	s_waitcnt vmcnt(9)
	ds_write_b128 v195, v[172:175]
	s_waitcnt vmcnt(8)
	ds_write_b128 v196, v[220:223]
	ds_read_b128 v[172:175], v192 offset:36864
	ds_read_b128 v[220:223], v192 offset:41472
	ds_read_b128 v[224:227], v184
	ds_read_b128 v[228:231], v184 offset:4608
	s_setprio 1
	s_waitcnt lgkmcnt(1)
	v_mfma_f32_32x32x16_bf16 v[112:127], v[172:175], v[224:227], v[112:127]
	v_mfma_f32_32x32x16_bf16 v[48:63], v[220:223], v[224:227], v[48:63]
	s_waitcnt lgkmcnt(0)
	v_mfma_f32_32x32x16_bf16 v[96:111], v[172:175], v[228:231], v[96:111]
	v_mfma_f32_32x32x16_bf16 v[32:47], v[220:223], v[228:231], v[32:47]
	ds_read_b128 v[224:227], v184 offset:9216
	ds_read_b128 v[228:231], v184 offset:13824
	s_waitcnt vmcnt(7)
	ds_write_b128 v194, v[158:161]
	s_waitcnt vmcnt(6)
	ds_write_b128 v193, v[162:165]
	ds_read_b128 v[158:161], v192 offset:36896
	ds_read_b128 v[162:165], v192 offset:41504
	s_waitcnt lgkmcnt(5)
	v_mfma_f32_32x32x16_bf16 v[80:95], v[172:175], v[224:227], v[80:95]
	v_mfma_f32_32x32x16_bf16 v[16:31], v[220:223], v[224:227], v[16:31]
	ds_read_b128 v[224:227], v184 offset:32
	s_waitcnt lgkmcnt(5)
	v_mfma_f32_32x32x16_bf16 v[64:79], v[172:175], v[228:231], v[64:79]
	v_mfma_f32_32x32x16_bf16 v[0:15], v[220:223], v[228:231], v[0:15]
	ds_read_b128 v[228:231], v184 offset:4640
	global_load_dwordx4 v[172:175], v[136:137], off offset:1280
	global_load_dwordx4 v[220:223], v[140:141], off offset:1280
	s_waitcnt lgkmcnt(1)
	v_mfma_f32_32x32x16_bf16 v[112:127], v[158:161], v[224:227], v[112:127]
	v_mfma_f32_32x32x16_bf16 v[48:63], v[162:165], v[224:227], v[48:63]
	s_waitcnt lgkmcnt(0)
	v_mfma_f32_32x32x16_bf16 v[96:111], v[158:161], v[228:231], v[96:111]
	v_mfma_f32_32x32x16_bf16 v[32:47], v[162:165], v[228:231], v[32:47]
	ds_read_b128 v[224:227], v184 offset:9248
	ds_read_b128 v[228:231], v184 offset:13856
	s_waitcnt vmcnt(7)
	ds_write_b128 v177, v[198:201]
	s_waitcnt vmcnt(6)
	ds_write_b128 v176, v[202:205]
	ds_read_b128 v[198:201], v192 offset:36928
	ds_read_b128 v[202:205], v192 offset:41536
	s_waitcnt lgkmcnt(5)
	v_mfma_f32_32x32x16_bf16 v[80:95], v[158:161], v[224:227], v[80:95]
	v_mfma_f32_32x32x16_bf16 v[16:31], v[162:165], v[224:227], v[16:31]
	ds_read_b128 v[224:227], v184 offset:64
	s_waitcnt lgkmcnt(5)
	v_mfma_f32_32x32x16_bf16 v[64:79], v[158:161], v[228:231], v[64:79]
	v_mfma_f32_32x32x16_bf16 v[0:15], v[162:165], v[228:231], v[0:15]
	ds_read_b128 v[228:231], v184 offset:4672
	global_load_dwordx4 v[158:161], v[144:145], off offset:1280
	global_load_dwordx4 v[162:165], v[148:149], off offset:1280
	s_waitcnt lgkmcnt(1)
	v_mfma_f32_32x32x16_bf16 v[112:127], v[198:201], v[224:227], v[112:127]
	v_mfma_f32_32x32x16_bf16 v[48:63], v[202:205], v[224:227], v[48:63]
	s_waitcnt lgkmcnt(0)
	v_mfma_f32_32x32x16_bf16 v[96:111], v[198:201], v[228:231], v[96:111]
	v_mfma_f32_32x32x16_bf16 v[32:47], v[202:205], v[228:231], v[32:47]
	ds_read_b128 v[224:227], v184 offset:9280
	ds_read_b128 v[228:231], v184 offset:13888
	s_waitcnt vmcnt(7)
	ds_write_b128 v171, v[208:211]
	s_waitcnt vmcnt(6)
	ds_write_b128 v170, v[212:215]
	ds_read_b128 v[208:211], v192 offset:36960
	ds_read_b128 v[212:215], v192 offset:41568
	s_waitcnt lgkmcnt(5)
	v_mfma_f32_32x32x16_bf16 v[80:95], v[198:201], v[224:227], v[80:95]
	v_mfma_f32_32x32x16_bf16 v[16:31], v[202:205], v[224:227], v[16:31]
	ds_read_b128 v[224:227], v184 offset:96
	s_waitcnt lgkmcnt(5)
	v_mfma_f32_32x32x16_bf16 v[64:79], v[198:201], v[228:231], v[64:79]
	v_mfma_f32_32x32x16_bf16 v[0:15], v[202:205], v[228:231], v[0:15]
	ds_read_b128 v[228:231], v184 offset:4704
	global_load_dwordx4 v[198:201], v[152:153], off offset:1280
	global_load_dwordx4 v[202:205], v[156:157], off offset:1280
	s_waitcnt lgkmcnt(1)
	v_mfma_f32_32x32x16_bf16 v[112:127], v[208:211], v[224:227], v[112:127]
	v_mfma_f32_32x32x16_bf16 v[48:63], v[212:215], v[224:227], v[48:63]
	s_waitcnt lgkmcnt(0)
	v_mfma_f32_32x32x16_bf16 v[96:111], v[208:211], v[228:231], v[96:111]
	v_mfma_f32_32x32x16_bf16 v[32:47], v[212:215], v[228:231], v[32:47]
	ds_read_b128 v[224:227], v184 offset:9312
	ds_read_b128 v[228:231], v184 offset:13920
	s_waitcnt lgkmcnt(1)
	v_mfma_f32_32x32x16_bf16 v[80:95], v[208:211], v[224:227], v[80:95]
	v_mfma_f32_32x32x16_bf16 v[16:31], v[212:215], v[224:227], v[16:31]
	s_waitcnt lgkmcnt(0)
	v_mfma_f32_32x32x16_bf16 v[64:79], v[208:211], v[228:231], v[64:79]
	v_mfma_f32_32x32x16_bf16 v[0:15], v[212:215], v[228:231], v[0:15]
	s_setprio 0
	s_barrier
; template <bool trans>
; DI void gemm_core(const GTile& tl, const GTile& nx, bool has_next  , bool chain  , bool pre, u32x4 (&ra)[4], u32x4 (&rb)[4], char* smem, f32x16 (&acc)[2][4]) {
;     ...
;   const int nk = K / 64;
;   if (!pre) { G_LOAD(0); G_STORE(0); G_LOAD(1); }
;   for (int kt = 0; kt < nk; ++kt) {
;     __syncthreads();
;     G_COMPUTE(kt & 1, kt);
	global_load_dwordx4 v[208:211], v[128:129], off offset:1408
	global_load_dwordx4 v[212:215], v[132:133], off offset:1408
	s_waitcnt vmcnt(9)
	ds_write_b128 v191, v[178:181]
	s_waitcnt vmcnt(8)
	ds_write_b128 v191, v[216:219] offset:36864
	ds_read_b128 v[178:181], v169
	ds_read_b128 v[216:219], v169 offset:4608
	ds_read_b128 v[224:227], v168
	ds_read_b128 v[228:231], v168 offset:4608
	s_setprio 1
	s_waitcnt lgkmcnt(1)
	v_mfma_f32_32x32x16_bf16 v[112:127], v[178:181], v[224:227], v[112:127]
	v_mfma_f32_32x32x16_bf16 v[48:63], v[216:219], v[224:227], v[48:63]
	s_waitcnt lgkmcnt(0)
	v_mfma_f32_32x32x16_bf16 v[96:111], v[178:181], v[228:231], v[96:111]
	v_mfma_f32_32x32x16_bf16 v[32:47], v[216:219], v[228:231], v[32:47]
	ds_read_b128 v[224:227], v168 offset:9216
	ds_read_b128 v[228:231], v168 offset:13824
	s_waitcnt vmcnt(7)
	ds_write_b128 v191, v[172:175] offset:9216
	s_waitcnt vmcnt(6)
	ds_write_b128 v191, v[220:223] offset:46080
	ds_read_b128 v[172:175], v169 offset:32
	ds_read_b128 v[220:223], v169 offset:4640
	s_waitcnt lgkmcnt(5)
	v_mfma_f32_32x32x16_bf16 v[80:95], v[178:181], v[224:227], v[80:95]
	v_mfma_f32_32x32x16_bf16 v[16:31], v[216:219], v[224:227], v[16:31]
	ds_read_b128 v[224:227], v168 offset:32
	s_waitcnt lgkmcnt(5)
	v_mfma_f32_32x32x16_bf16 v[64:79], v[178:181], v[228:231], v[64:79]
	v_mfma_f32_32x32x16_bf16 v[0:15], v[216:219], v[228:231], v[0:15]
	ds_read_b128 v[228:231], v168 offset:4640
	global_load_dwordx4 v[178:181], v[136:137], off offset:1408
	global_load_dwordx4 v[216:219], v[140:141], off offset:1408
	s_waitcnt lgkmcnt(1)
	v_mfma_f32_32x32x16_bf16 v[112:127], v[172:175], v[224:227], v[112:127]
	v_mfma_f32_32x32x16_bf16 v[48:63], v[220:223], v[224:227], v[48:63]
	s_waitcnt lgkmcnt(0)
	v_mfma_f32_32x32x16_bf16 v[96:111], v[172:175], v[228:231], v[96:111]
	v_mfma_f32_32x32x16_bf16 v[32:47], v[220:223], v[228:231], v[32:47]
	ds_read_b128 v[224:227], v168 offset:9248
	ds_read_b128 v[228:231], v168 offset:13856
	s_waitcnt vmcnt(7)
	ds_write_b128 v191, v[158:161] offset:18432
	s_waitcnt vmcnt(6)
	ds_write_b128 v191, v[162:165] offset:55296
	ds_read_b128 v[158:161], v169 offset:64
	ds_read_b128 v[162:165], v169 offset:4672
	s_waitcnt lgkmcnt(5)
	v_mfma_f32_32x32x16_bf16 v[80:95], v[172:175], v[224:227], v[80:95]
	v_mfma_f32_32x32x16_bf16 v[16:31], v[220:223], v[224:227], v[16:31]
	ds_read_b128 v[224:227], v168 offset:64
	s_waitcnt lgkmcnt(5)
	v_mfma_f32_32x32x16_bf16 v[64:79], v[172:175], v[228:231], v[64:79]
	v_mfma_f32_32x32x16_bf16 v[0:15], v[220:223], v[228:231], v[0:15]
	ds_read_b128 v[228:231], v168 offset:4672
	global_load_dwordx4 v[172:175], v[144:145], off offset:1408
	global_load_dwordx4 v[220:223], v[148:149], off offset:1408
	s_waitcnt lgkmcnt(1)
	v_mfma_f32_32x32x16_bf16 v[112:127], v[158:161], v[224:227], v[112:127]
	v_mfma_f32_32x32x16_bf16 v[48:63], v[162:165], v[224:227], v[48:63]
	s_waitcnt lgkmcnt(0)
	v_mfma_f32_32x32x16_bf16 v[96:111], v[158:161], v[228:231], v[96:111]
	v_mfma_f32_32x32x16_bf16 v[32:47], v[162:165], v[228:231], v[32:47]
	ds_read_b128 v[224:227], v168 offset:9280
	ds_read_b128 v[228:231], v168 offset:13888
	s_waitcnt vmcnt(7)
	ds_write_b128 v191, v[198:201] offset:27648
	s_waitcnt vmcnt(6)
	ds_write_b128 v191, v[202:205] offset:64512
	ds_read_b128 v[198:201], v169 offset:96
	ds_read_b128 v[202:205], v169 offset:4704
	s_waitcnt lgkmcnt(5)
	v_mfma_f32_32x32x16_bf16 v[80:95], v[158:161], v[224:227], v[80:95]
	v_mfma_f32_32x32x16_bf16 v[16:31], v[162:165], v[224:227], v[16:31]
	ds_read_b128 v[224:227], v168 offset:96
	s_waitcnt lgkmcnt(5)
	v_mfma_f32_32x32x16_bf16 v[64:79], v[158:161], v[228:231], v[64:79]
	v_mfma_f32_32x32x16_bf16 v[0:15], v[162:165], v[228:231], v[0:15]
	ds_read_b128 v[228:231], v168 offset:4704
	global_load_dwordx4 v[158:161], v[152:153], off offset:1408
	global_load_dwordx4 v[162:165], v[156:157], off offset:1408
	s_waitcnt lgkmcnt(1)
	v_mfma_f32_32x32x16_bf16 v[112:127], v[198:201], v[224:227], v[112:127]
	v_mfma_f32_32x32x16_bf16 v[48:63], v[202:205], v[224:227], v[48:63]
	s_waitcnt lgkmcnt(0)
	v_mfma_f32_32x32x16_bf16 v[96:111], v[198:201], v[228:231], v[96:111]
	v_mfma_f32_32x32x16_bf16 v[32:47], v[202:205], v[228:231], v[32:47]
	ds_read_b128 v[224:227], v168 offset:9312
	ds_read_b128 v[228:231], v168 offset:13920
	s_waitcnt lgkmcnt(1)
	v_mfma_f32_32x32x16_bf16 v[80:95], v[198:201], v[224:227], v[80:95]
	v_mfma_f32_32x32x16_bf16 v[16:31], v[202:205], v[224:227], v[16:31]
	s_waitcnt lgkmcnt(0)
	v_mfma_f32_32x32x16_bf16 v[64:79], v[198:201], v[228:231], v[64:79]
	v_mfma_f32_32x32x16_bf16 v[0:15], v[202:205], v[228:231], v[0:15]
	s_setprio 0
	s_barrier
; template <bool trans>
; DI void gemm_core(const GTile& tl, const GTile& nx, bool has_next  , bool chain  , bool pre, u32x4 (&ra)[4], u32x4 (&rb)[4], char* smem, f32x16 (&acc)[2][4]) {
;     ...
;   const int nk = K / 64;
;   if (!pre) { G_LOAD(0); G_STORE(0); G_LOAD(1); }
;   for (int kt = 0; kt < nk; ++kt) {
;     __syncthreads();
;     G_COMPUTE(kt & 1, kt);
	global_load_dwordx4 v[198:201], v[128:129], off offset:1536
	global_load_dwordx4 v[202:205], v[132:133], off offset:1536
	s_waitcnt vmcnt(9)
	ds_write_b128 v195, v[208:211]
	s_waitcnt vmcnt(8)
	ds_write_b128 v196, v[212:215]
	ds_read_b128 v[208:211], v192 offset:36864
	ds_read_b128 v[212:215], v192 offset:41472
	ds_read_b128 v[224:227], v184
	ds_read_b128 v[228:231], v184 offset:4608
	s_setprio 1
	s_waitcnt lgkmcnt(1)
	v_mfma_f32_32x32x16_bf16 v[112:127], v[208:211], v[224:227], v[112:127]
	v_mfma_f32_32x32x16_bf16 v[48:63], v[212:215], v[224:227], v[48:63]
	s_waitcnt lgkmcnt(0)
	v_mfma_f32_32x32x16_bf16 v[96:111], v[208:211], v[228:231], v[96:111]
	v_mfma_f32_32x32x16_bf16 v[32:47], v[212:215], v[228:231], v[32:47]
	ds_read_b128 v[224:227], v184 offset:9216
	ds_read_b128 v[228:231], v184 offset:13824
	s_waitcnt vmcnt(7)
	ds_write_b128 v194, v[178:181]
	s_waitcnt vmcnt(6)
	ds_write_b128 v193, v[216:219]
	ds_read_b128 v[178:181], v192 offset:36896
	ds_read_b128 v[216:219], v192 offset:41504
	s_waitcnt lgkmcnt(5)
	v_mfma_f32_32x32x16_bf16 v[80:95], v[208:211], v[224:227], v[80:95]
	v_mfma_f32_32x32x16_bf16 v[16:31], v[212:215], v[224:227], v[16:31]
	ds_read_b128 v[224:227], v184 offset:32
	s_waitcnt lgkmcnt(5)
	v_mfma_f32_32x32x16_bf16 v[64:79], v[208:211], v[228:231], v[64:79]
	v_mfma_f32_32x32x16_bf16 v[0:15], v[212:215], v[228:231], v[0:15]
	ds_read_b128 v[228:231], v184 offset:4640
	global_load_dwordx4 v[208:211], v[136:137], off offset:1536
	global_load_dwordx4 v[212:215], v[140:141], off offset:1536
	s_waitcnt lgkmcnt(1)
	v_mfma_f32_32x32x16_bf16 v[112:127], v[178:181], v[224:227], v[112:127]
	v_mfma_f32_32x32x16_bf16 v[48:63], v[216:219], v[224:227], v[48:63]
	s_waitcnt lgkmcnt(0)
	v_mfma_f32_32x32x16_bf16 v[96:111], v[178:181], v[228:231], v[96:111]
	v_mfma_f32_32x32x16_bf16 v[32:47], v[216:219], v[228:231], v[32:47]
	ds_read_b128 v[224:227], v184 offset:9248
	ds_read_b128 v[228:231], v184 offset:13856
	s_waitcnt vmcnt(7)
	ds_write_b128 v177, v[172:175]
	s_waitcnt vmcnt(6)
	ds_write_b128 v176, v[220:223]
	ds_read_b128 v[172:175], v192 offset:36928
	ds_read_b128 v[220:223], v192 offset:41536
	s_waitcnt lgkmcnt(5)
	v_mfma_f32_32x32x16_bf16 v[80:95], v[178:181], v[224:227], v[80:95]
	v_mfma_f32_32x32x16_bf16 v[16:31], v[216:219], v[224:227], v[16:31]
	ds_read_b128 v[224:227], v184 offset:64
	s_waitcnt lgkmcnt(5)
	v_mfma_f32_32x32x16_bf16 v[64:79], v[178:181], v[228:231], v[64:79]
	v_mfma_f32_32x32x16_bf16 v[0:15], v[216:219], v[228:231], v[0:15]
	ds_read_b128 v[228:231], v184 offset:4672
	global_load_dwordx4 v[178:181], v[144:145], off offset:1536
	global_load_dwordx4 v[216:219], v[148:149], off offset:1536
	s_waitcnt lgkmcnt(1)
	v_mfma_f32_32x32x16_bf16 v[112:127], v[172:175], v[224:227], v[112:127]
	v_mfma_f32_32x32x16_bf16 v[48:63], v[220:223], v[224:227], v[48:63]
	s_waitcnt lgkmcnt(0)
	v_mfma_f32_32x32x16_bf16 v[96:111], v[172:175], v[228:231], v[96:111]
	v_mfma_f32_32x32x16_bf16 v[32:47], v[220:223], v[228:231], v[32:47]
	ds_read_b128 v[224:227], v184 offset:9280
	ds_read_b128 v[228:231], v184 offset:13888
	s_waitcnt vmcnt(7)
	ds_write_b128 v171, v[158:161]
	s_waitcnt vmcnt(6)
	ds_write_b128 v170, v[162:165]
	ds_read_b128 v[158:161], v192 offset:36960
	ds_read_b128 v[162:165], v192 offset:41568
	s_waitcnt lgkmcnt(5)
	v_mfma_f32_32x32x16_bf16 v[80:95], v[172:175], v[224:227], v[80:95]
	v_mfma_f32_32x32x16_bf16 v[16:31], v[220:223], v[224:227], v[16:31]
	ds_read_b128 v[224:227], v184 offset:96
	s_waitcnt lgkmcnt(5)
	v_mfma_f32_32x32x16_bf16 v[64:79], v[172:175], v[228:231], v[64:79]
	v_mfma_f32_32x32x16_bf16 v[0:15], v[220:223], v[228:231], v[0:15]
	ds_read_b128 v[228:231], v184 offset:4704
	global_load_dwordx4 v[172:175], v[152:153], off offset:1536
	global_load_dwordx4 v[220:223], v[156:157], off offset:1536
	s_waitcnt lgkmcnt(1)
	v_mfma_f32_32x32x16_bf16 v[112:127], v[158:161], v[224:227], v[112:127]
	v_mfma_f32_32x32x16_bf16 v[48:63], v[162:165], v[224:227], v[48:63]
	s_waitcnt lgkmcnt(0)
	v_mfma_f32_32x32x16_bf16 v[96:111], v[158:161], v[228:231], v[96:111]
	v_mfma_f32_32x32x16_bf16 v[32:47], v[162:165], v[228:231], v[32:47]
	ds_read_b128 v[224:227], v184 offset:9312
	ds_read_b128 v[228:231], v184 offset:13920
	s_waitcnt lgkmcnt(1)
	v_mfma_f32_32x32x16_bf16 v[80:95], v[158:161], v[224:227], v[80:95]
	v_mfma_f32_32x32x16_bf16 v[16:31], v[162:165], v[224:227], v[16:31]
	s_waitcnt lgkmcnt(0)
	v_mfma_f32_32x32x16_bf16 v[64:79], v[158:161], v[228:231], v[64:79]
	v_mfma_f32_32x32x16_bf16 v[0:15], v[162:165], v[228:231], v[0:15]
	s_setprio 0
	s_barrier
; template <bool trans>
; DI void gemm_core(const GTile& tl, const GTile& nx, bool has_next  , bool chain  , bool pre, u32x4 (&ra)[4], u32x4 (&rb)[4], char* smem, f32x16 (&acc)[2][4]) {
;     ...
;   const int nk = K / 64;
;   if (!pre) { G_LOAD(0); G_STORE(0); G_LOAD(1); }
;   for (int kt = 0; kt < nk; ++kt) {
;     __syncthreads();
;     G_COMPUTE(kt & 1, kt);
	global_load_dwordx4 v[158:161], v[128:129], off offset:1664
	global_load_dwordx4 v[162:165], v[132:133], off offset:1664
	s_waitcnt vmcnt(9)
	ds_write_b128 v191, v[198:201]
	s_waitcnt vmcnt(8)
	ds_write_b128 v191, v[202:205] offset:36864
	ds_read_b128 v[198:201], v169
	ds_read_b128 v[202:205], v169 offset:4608
	ds_read_b128 v[224:227], v168
	ds_read_b128 v[228:231], v168 offset:4608
	s_setprio 1
	s_waitcnt lgkmcnt(1)
	v_mfma_f32_32x32x16_bf16 v[112:127], v[198:201], v[224:227], v[112:127]
	v_mfma_f32_32x32x16_bf16 v[48:63], v[202:205], v[224:227], v[48:63]
	s_waitcnt lgkmcnt(0)
	v_mfma_f32_32x32x16_bf16 v[96:111], v[198:201], v[228:231], v[96:111]
	v_mfma_f32_32x32x16_bf16 v[32:47], v[202:205], v[228:231], v[32:47]
	ds_read_b128 v[224:227], v168 offset:9216
	ds_read_b128 v[228:231], v168 offset:13824
	s_waitcnt vmcnt(7)
	ds_write_b128 v191, v[208:211] offset:9216
	s_waitcnt vmcnt(6)
	ds_write_b128 v191, v[212:215] offset:46080
	ds_read_b128 v[208:211], v169 offset:32
	ds_read_b128 v[212:215], v169 offset:4640
	s_waitcnt lgkmcnt(5)
	v_mfma_f32_32x32x16_bf16 v[80:95], v[198:201], v[224:227], v[80:95]
	v_mfma_f32_32x32x16_bf16 v[16:31], v[202:205], v[224:227], v[16:31]
	ds_read_b128 v[224:227], v168 offset:32
	s_waitcnt lgkmcnt(5)
	v_mfma_f32_32x32x16_bf16 v[64:79], v[198:201], v[228:231], v[64:79]
	v_mfma_f32_32x32x16_bf16 v[0:15], v[202:205], v[228:231], v[0:15]
	ds_read_b128 v[228:231], v168 offset:4640
	global_load_dwordx4 v[198:201], v[136:137], off offset:1664
	global_load_dwordx4 v[202:205], v[140:141], off offset:1664
	s_waitcnt lgkmcnt(1)
	v_mfma_f32_32x32x16_bf16 v[112:127], v[208:211], v[224:227], v[112:127]
	v_mfma_f32_32x32x16_bf16 v[48:63], v[212:215], v[224:227], v[48:63]
	s_waitcnt lgkmcnt(0)
	v_mfma_f32_32x32x16_bf16 v[96:111], v[208:211], v[228:231], v[96:111]
	v_mfma_f32_32x32x16_bf16 v[32:47], v[212:215], v[228:231], v[32:47]
	ds_read_b128 v[224:227], v168 offset:9248
	ds_read_b128 v[228:231], v168 offset:13856
	s_waitcnt vmcnt(7)
	ds_write_b128 v191, v[178:181] offset:18432
	s_waitcnt vmcnt(6)
	ds_write_b128 v191, v[216:219] offset:55296
	ds_read_b128 v[178:181], v169 offset:64
	ds_read_b128 v[216:219], v169 offset:4672
	s_waitcnt lgkmcnt(5)
	v_mfma_f32_32x32x16_bf16 v[80:95], v[208:211], v[224:227], v[80:95]
	v_mfma_f32_32x32x16_bf16 v[16:31], v[212:215], v[224:227], v[16:31]
	ds_read_b128 v[224:227], v168 offset:64
	s_waitcnt lgkmcnt(5)
	v_mfma_f32_32x32x16_bf16 v[64:79], v[208:211], v[228:231], v[64:79]
	v_mfma_f32_32x32x16_bf16 v[0:15], v[212:215], v[228:231], v[0:15]
	ds_read_b128 v[228:231], v168 offset:4672
	global_load_dwordx4 v[208:211], v[144:145], off offset:1664
	global_load_dwordx4 v[212:215], v[148:149], off offset:1664
	s_waitcnt lgkmcnt(1)
	v_mfma_f32_32x32x16_bf16 v[112:127], v[178:181], v[224:227], v[112:127]
	v_mfma_f32_32x32x16_bf16 v[48:63], v[216:219], v[224:227], v[48:63]
	s_waitcnt lgkmcnt(0)
	v_mfma_f32_32x32x16_bf16 v[96:111], v[178:181], v[228:231], v[96:111]
	v_mfma_f32_32x32x16_bf16 v[32:47], v[216:219], v[228:231], v[32:47]
	ds_read_b128 v[224:227], v168 offset:9280
	ds_read_b128 v[228:231], v168 offset:13888
	s_waitcnt vmcnt(7)
	ds_write_b128 v191, v[172:175] offset:27648
	s_waitcnt vmcnt(6)
	ds_write_b128 v191, v[220:223] offset:64512
	ds_read_b128 v[172:175], v169 offset:96
	ds_read_b128 v[220:223], v169 offset:4704
	s_waitcnt lgkmcnt(5)
	v_mfma_f32_32x32x16_bf16 v[80:95], v[178:181], v[224:227], v[80:95]
	v_mfma_f32_32x32x16_bf16 v[16:31], v[216:219], v[224:227], v[16:31]
	ds_read_b128 v[224:227], v168 offset:96
	s_waitcnt lgkmcnt(5)
	v_mfma_f32_32x32x16_bf16 v[64:79], v[178:181], v[228:231], v[64:79]
	v_mfma_f32_32x32x16_bf16 v[0:15], v[216:219], v[228:231], v[0:15]
	ds_read_b128 v[228:231], v168 offset:4704
	global_load_dwordx4 v[178:181], v[152:153], off offset:1664
	global_load_dwordx4 v[216:219], v[156:157], off offset:1664
	s_waitcnt lgkmcnt(1)
	v_mfma_f32_32x32x16_bf16 v[112:127], v[172:175], v[224:227], v[112:127]
	v_mfma_f32_32x32x16_bf16 v[48:63], v[220:223], v[224:227], v[48:63]
	s_waitcnt lgkmcnt(0)
	v_mfma_f32_32x32x16_bf16 v[96:111], v[172:175], v[228:231], v[96:111]
	v_mfma_f32_32x32x16_bf16 v[32:47], v[220:223], v[228:231], v[32:47]
	ds_read_b128 v[224:227], v168 offset:9312
	ds_read_b128 v[228:231], v168 offset:13920
	s_waitcnt lgkmcnt(1)
	v_mfma_f32_32x32x16_bf16 v[80:95], v[172:175], v[224:227], v[80:95]
	v_mfma_f32_32x32x16_bf16 v[16:31], v[220:223], v[224:227], v[16:31]
	s_waitcnt lgkmcnt(0)
	v_mfma_f32_32x32x16_bf16 v[64:79], v[172:175], v[228:231], v[64:79]
	v_mfma_f32_32x32x16_bf16 v[0:15], v[220:223], v[228:231], v[0:15]
	s_setprio 0
	s_barrier
; template <bool trans>
; DI void gemm_core(const GTile& tl, const GTile& nx, bool has_next  , bool chain  , bool pre, u32x4 (&ra)[4], u32x4 (&rb)[4], char* smem, f32x16 (&acc)[2][4]) {
;     ...
;   const int nk = K / 64;
;   if (!pre) { G_LOAD(0); G_STORE(0); G_LOAD(1); }
;   for (int kt = 0; kt < nk; ++kt) {
;     __syncthreads();
;     G_COMPUTE(kt & 1, kt);
	global_load_dwordx4 v[172:175], v[128:129], off offset:1792
	global_load_dwordx4 v[220:223], v[132:133], off offset:1792
	s_waitcnt vmcnt(9)
	ds_write_b128 v195, v[158:161]
	s_waitcnt vmcnt(8)
	ds_write_b128 v196, v[162:165]
	ds_read_b128 v[158:161], v192 offset:36864
	ds_read_b128 v[162:165], v192 offset:41472
	ds_read_b128 v[224:227], v184
	ds_read_b128 v[228:231], v184 offset:4608
	s_setprio 1
	s_waitcnt lgkmcnt(1)
	v_mfma_f32_32x32x16_bf16 v[112:127], v[158:161], v[224:227], v[112:127]
	v_mfma_f32_32x32x16_bf16 v[48:63], v[162:165], v[224:227], v[48:63]
	s_waitcnt lgkmcnt(0)
	v_mfma_f32_32x32x16_bf16 v[96:111], v[158:161], v[228:231], v[96:111]
	v_mfma_f32_32x32x16_bf16 v[32:47], v[162:165], v[228:231], v[32:47]
	ds_read_b128 v[224:227], v184 offset:9216
	ds_read_b128 v[228:231], v184 offset:13824
	s_waitcnt vmcnt(7)
	ds_write_b128 v194, v[198:201]
	s_waitcnt vmcnt(6)
	ds_write_b128 v193, v[202:205]
	ds_read_b128 v[198:201], v192 offset:36896
	ds_read_b128 v[202:205], v192 offset:41504
	s_waitcnt lgkmcnt(5)
	v_mfma_f32_32x32x16_bf16 v[80:95], v[158:161], v[224:227], v[80:95]
	v_mfma_f32_32x32x16_bf16 v[16:31], v[162:165], v[224:227], v[16:31]
	ds_read_b128 v[224:227], v184 offset:32
	s_waitcnt lgkmcnt(5)
	v_mfma_f32_32x32x16_bf16 v[64:79], v[158:161], v[228:231], v[64:79]
	v_mfma_f32_32x32x16_bf16 v[0:15], v[162:165], v[228:231], v[0:15]
	ds_read_b128 v[228:231], v184 offset:4640
	global_load_dwordx4 v[158:161], v[136:137], off offset:1792
	global_load_dwordx4 v[162:165], v[140:141], off offset:1792
	s_waitcnt lgkmcnt(1)
	v_mfma_f32_32x32x16_bf16 v[112:127], v[198:201], v[224:227], v[112:127]
	v_mfma_f32_32x32x16_bf16 v[48:63], v[202:205], v[224:227], v[48:63]
	s_waitcnt lgkmcnt(0)
	v_mfma_f32_32x32x16_bf16 v[96:111], v[198:201], v[228:231], v[96:111]
	v_mfma_f32_32x32x16_bf16 v[32:47], v[202:205], v[228:231], v[32:47]
	ds_read_b128 v[224:227], v184 offset:9248
	ds_read_b128 v[228:231], v184 offset:13856
	s_waitcnt vmcnt(7)
	ds_write_b128 v177, v[208:211]
	s_waitcnt vmcnt(6)
	ds_write_b128 v176, v[212:215]
	ds_read_b128 v[208:211], v192 offset:36928
	ds_read_b128 v[212:215], v192 offset:41536
	s_waitcnt lgkmcnt(5)
	v_mfma_f32_32x32x16_bf16 v[80:95], v[198:201], v[224:227], v[80:95]
	v_mfma_f32_32x32x16_bf16 v[16:31], v[202:205], v[224:227], v[16:31]
	ds_read_b128 v[224:227], v184 offset:64
	s_waitcnt lgkmcnt(5)
	v_mfma_f32_32x32x16_bf16 v[64:79], v[198:201], v[228:231], v[64:79]
	v_mfma_f32_32x32x16_bf16 v[0:15], v[202:205], v[228:231], v[0:15]
	ds_read_b128 v[228:231], v184 offset:4672
	global_load_dwordx4 v[198:201], v[144:145], off offset:1792
	global_load_dwordx4 v[202:205], v[148:149], off offset:1792
	s_waitcnt lgkmcnt(1)
	v_mfma_f32_32x32x16_bf16 v[112:127], v[208:211], v[224:227], v[112:127]
	v_mfma_f32_32x32x16_bf16 v[48:63], v[212:215], v[224:227], v[48:63]
	s_waitcnt lgkmcnt(0)
	v_mfma_f32_32x32x16_bf16 v[96:111], v[208:211], v[228:231], v[96:111]
	v_mfma_f32_32x32x16_bf16 v[32:47], v[212:215], v[228:231], v[32:47]
	ds_read_b128 v[224:227], v184 offset:9280
	ds_read_b128 v[228:231], v184 offset:13888
	s_waitcnt vmcnt(7)
	ds_write_b128 v171, v[178:181]
	s_waitcnt vmcnt(6)
	ds_write_b128 v170, v[216:219]
	ds_read_b128 v[178:181], v192 offset:36960
	ds_read_b128 v[216:219], v192 offset:41568
	s_waitcnt lgkmcnt(5)
	v_mfma_f32_32x32x16_bf16 v[80:95], v[208:211], v[224:227], v[80:95]
	v_mfma_f32_32x32x16_bf16 v[16:31], v[212:215], v[224:227], v[16:31]
	ds_read_b128 v[224:227], v184 offset:96
	s_waitcnt lgkmcnt(5)
	v_mfma_f32_32x32x16_bf16 v[64:79], v[208:211], v[228:231], v[64:79]
	v_mfma_f32_32x32x16_bf16 v[0:15], v[212:215], v[228:231], v[0:15]
	ds_read_b128 v[228:231], v184 offset:4704
	global_load_dwordx4 v[208:211], v[152:153], off offset:1792
	global_load_dwordx4 v[212:215], v[156:157], off offset:1792
	s_waitcnt lgkmcnt(1)
	v_mfma_f32_32x32x16_bf16 v[112:127], v[178:181], v[224:227], v[112:127]
	v_mfma_f32_32x32x16_bf16 v[48:63], v[216:219], v[224:227], v[48:63]
	s_waitcnt lgkmcnt(0)
	v_mfma_f32_32x32x16_bf16 v[96:111], v[178:181], v[228:231], v[96:111]
	v_mfma_f32_32x32x16_bf16 v[32:47], v[216:219], v[228:231], v[32:47]
	ds_read_b128 v[224:227], v184 offset:9312
	ds_read_b128 v[228:231], v184 offset:13920
	s_waitcnt lgkmcnt(1)
	v_mfma_f32_32x32x16_bf16 v[80:95], v[178:181], v[224:227], v[80:95]
	v_mfma_f32_32x32x16_bf16 v[16:31], v[216:219], v[224:227], v[16:31]
	s_waitcnt lgkmcnt(0)
	v_mfma_f32_32x32x16_bf16 v[64:79], v[178:181], v[228:231], v[64:79]
	v_mfma_f32_32x32x16_bf16 v[0:15], v[216:219], v[228:231], v[0:15]
	s_setprio 0
	s_barrier
; template <bool trans>
; DI void gemm_core(const GTile& tl, const GTile& nx, bool has_next  , bool chain  , bool pre, u32x4 (&ra)[4], u32x4 (&rb)[4], char* smem, f32x16 (&acc)[2][4]) {
;     ...
;   const int nk = K / 64;
;   if (!pre) { G_LOAD(0); G_STORE(0); G_LOAD(1); }
;   for (int kt = 0; kt < nk; ++kt) {
;     __syncthreads();
;     G_COMPUTE(kt & 1, kt);
	global_load_dwordx4 v[178:181], v[128:129], off offset:1920
	global_load_dwordx4 v[216:219], v[132:133], off offset:1920
	s_waitcnt vmcnt(9)
	ds_write_b128 v191, v[172:175]
	s_waitcnt vmcnt(8)
	ds_write_b128 v191, v[220:223] offset:36864
	ds_read_b128 v[172:175], v169
	ds_read_b128 v[220:223], v169 offset:4608
	ds_read_b128 v[224:227], v168
	ds_read_b128 v[228:231], v168 offset:4608
	s_setprio 1
	s_waitcnt lgkmcnt(1)
	v_mfma_f32_32x32x16_bf16 v[112:127], v[172:175], v[224:227], v[112:127]
	v_mfma_f32_32x32x16_bf16 v[48:63], v[220:223], v[224:227], v[48:63]
	s_waitcnt lgkmcnt(0)
	v_mfma_f32_32x32x16_bf16 v[96:111], v[172:175], v[228:231], v[96:111]
	v_mfma_f32_32x32x16_bf16 v[32:47], v[220:223], v[228:231], v[32:47]
	ds_read_b128 v[224:227], v168 offset:9216
	ds_read_b128 v[228:231], v168 offset:13824
	s_waitcnt vmcnt(7)
	ds_write_b128 v191, v[158:161] offset:9216
	s_waitcnt vmcnt(6)
	ds_write_b128 v191, v[162:165] offset:46080
	ds_read_b128 v[158:161], v169 offset:32
	ds_read_b128 v[162:165], v169 offset:4640
	s_waitcnt lgkmcnt(5)
	v_mfma_f32_32x32x16_bf16 v[80:95], v[172:175], v[224:227], v[80:95]
	v_mfma_f32_32x32x16_bf16 v[16:31], v[220:223], v[224:227], v[16:31]
	ds_read_b128 v[224:227], v168 offset:32
	s_waitcnt lgkmcnt(5)
	v_mfma_f32_32x32x16_bf16 v[64:79], v[172:175], v[228:231], v[64:79]
	v_mfma_f32_32x32x16_bf16 v[0:15], v[220:223], v[228:231], v[0:15]
	ds_read_b128 v[228:231], v168 offset:4640
	global_load_dwordx4 v[172:175], v[136:137], off offset:1920
	global_load_dwordx4 v[220:223], v[140:141], off offset:1920
	s_waitcnt lgkmcnt(1)
	v_mfma_f32_32x32x16_bf16 v[112:127], v[158:161], v[224:227], v[112:127]
	v_mfma_f32_32x32x16_bf16 v[48:63], v[162:165], v[224:227], v[48:63]
	s_waitcnt lgkmcnt(0)
	v_mfma_f32_32x32x16_bf16 v[96:111], v[158:161], v[228:231], v[96:111]
	v_mfma_f32_32x32x16_bf16 v[32:47], v[162:165], v[228:231], v[32:47]
	ds_read_b128 v[224:227], v168 offset:9248
	ds_read_b128 v[228:231], v168 offset:13856
	s_waitcnt vmcnt(7)
	ds_write_b128 v191, v[198:201] offset:18432
	s_waitcnt vmcnt(6)
	ds_write_b128 v191, v[202:205] offset:55296
	ds_read_b128 v[198:201], v169 offset:64
	ds_read_b128 v[202:205], v169 offset:4672
	s_waitcnt lgkmcnt(5)
	v_mfma_f32_32x32x16_bf16 v[80:95], v[158:161], v[224:227], v[80:95]
	v_mfma_f32_32x32x16_bf16 v[16:31], v[162:165], v[224:227], v[16:31]
	ds_read_b128 v[224:227], v168 offset:64
	s_waitcnt lgkmcnt(5)
	v_mfma_f32_32x32x16_bf16 v[64:79], v[158:161], v[228:231], v[64:79]
	v_mfma_f32_32x32x16_bf16 v[0:15], v[162:165], v[228:231], v[0:15]
	ds_read_b128 v[228:231], v168 offset:4672
	global_load_dwordx4 v[158:161], v[144:145], off offset:1920
	global_load_dwordx4 v[162:165], v[148:149], off offset:1920
	s_waitcnt lgkmcnt(1)
	v_mfma_f32_32x32x16_bf16 v[112:127], v[198:201], v[224:227], v[112:127]
	v_mfma_f32_32x32x16_bf16 v[48:63], v[202:205], v[224:227], v[48:63]
	s_waitcnt lgkmcnt(0)
	v_mfma_f32_32x32x16_bf16 v[96:111], v[198:201], v[228:231], v[96:111]
	v_mfma_f32_32x32x16_bf16 v[32:47], v[202:205], v[228:231], v[32:47]
	ds_read_b128 v[224:227], v168 offset:9280
	ds_read_b128 v[228:231], v168 offset:13888
	s_waitcnt vmcnt(7)
	ds_write_b128 v191, v[208:211] offset:27648
	s_waitcnt vmcnt(6)
	ds_write_b128 v191, v[212:215] offset:64512
	ds_read_b128 v[208:211], v169 offset:96
	ds_read_b128 v[212:215], v169 offset:4704
	s_waitcnt lgkmcnt(5)
	v_mfma_f32_32x32x16_bf16 v[80:95], v[198:201], v[224:227], v[80:95]
	v_mfma_f32_32x32x16_bf16 v[16:31], v[202:205], v[224:227], v[16:31]
	ds_read_b128 v[224:227], v168 offset:96
	s_waitcnt lgkmcnt(5)
	v_mfma_f32_32x32x16_bf16 v[64:79], v[198:201], v[228:231], v[64:79]
	v_mfma_f32_32x32x16_bf16 v[0:15], v[202:205], v[228:231], v[0:15]
	ds_read_b128 v[228:231], v168 offset:4704
	global_load_dwordx4 v[198:201], v[152:153], off offset:1920
	global_load_dwordx4 v[202:205], v[156:157], off offset:1920
	s_waitcnt lgkmcnt(1)
	v_mfma_f32_32x32x16_bf16 v[112:127], v[208:211], v[224:227], v[112:127]
	v_mfma_f32_32x32x16_bf16 v[48:63], v[212:215], v[224:227], v[48:63]
	s_waitcnt lgkmcnt(0)
	v_mfma_f32_32x32x16_bf16 v[96:111], v[208:211], v[228:231], v[96:111]
	v_mfma_f32_32x32x16_bf16 v[32:47], v[212:215], v[228:231], v[32:47]
	ds_read_b128 v[224:227], v168 offset:9312
	ds_read_b128 v[228:231], v168 offset:13920
	s_waitcnt lgkmcnt(1)
	v_mfma_f32_32x32x16_bf16 v[80:95], v[208:211], v[224:227], v[80:95]
	v_mfma_f32_32x32x16_bf16 v[16:31], v[212:215], v[224:227], v[16:31]
	s_waitcnt lgkmcnt(0)
	v_mfma_f32_32x32x16_bf16 v[64:79], v[208:211], v[228:231], v[64:79]
	v_mfma_f32_32x32x16_bf16 v[0:15], v[212:215], v[228:231], v[0:15]
	s_setprio 0
	s_barrier
; template <bool trans>
; DI void gemm_core(const GTile& tl, const GTile& nx, bool has_next  , bool chain  , bool pre, u32x4 (&ra)[4], u32x4 (&rb)[4], char* smem, f32x16 (&acc)[2][4]) {
;     ...
;   const int nk = K / 64;
;   if (!pre) { G_LOAD(0); G_STORE(0); G_LOAD(1); }
;   for (int kt = 0; kt < nk; ++kt) {
;     __syncthreads();
;     G_COMPUTE(kt & 1, kt);
	global_load_dwordx4 v[208:211], v[128:129], off offset:2048
	global_load_dwordx4 v[212:215], v[132:133], off offset:2048
	s_waitcnt vmcnt(9)
	ds_write_b128 v195, v[178:181]
	s_waitcnt vmcnt(8)
	ds_write_b128 v196, v[216:219]
	ds_read_b128 v[178:181], v192 offset:36864
	ds_read_b128 v[216:219], v192 offset:41472
	ds_read_b128 v[224:227], v184
	ds_read_b128 v[228:231], v184 offset:4608
	s_setprio 1
	s_waitcnt lgkmcnt(1)
	v_mfma_f32_32x32x16_bf16 v[112:127], v[178:181], v[224:227], v[112:127]
	v_mfma_f32_32x32x16_bf16 v[48:63], v[216:219], v[224:227], v[48:63]
	s_waitcnt lgkmcnt(0)
	v_mfma_f32_32x32x16_bf16 v[96:111], v[178:181], v[228:231], v[96:111]
	v_mfma_f32_32x32x16_bf16 v[32:47], v[216:219], v[228:231], v[32:47]
	ds_read_b128 v[224:227], v184 offset:9216
	ds_read_b128 v[228:231], v184 offset:13824
	s_waitcnt vmcnt(7)
	ds_write_b128 v194, v[172:175]
	s_waitcnt vmcnt(6)
	ds_write_b128 v193, v[220:223]
	ds_read_b128 v[172:175], v192 offset:36896
	ds_read_b128 v[220:223], v192 offset:41504
	s_waitcnt lgkmcnt(5)
	v_mfma_f32_32x32x16_bf16 v[80:95], v[178:181], v[224:227], v[80:95]
	v_mfma_f32_32x32x16_bf16 v[16:31], v[216:219], v[224:227], v[16:31]
	ds_read_b128 v[224:227], v184 offset:32
	s_waitcnt lgkmcnt(5)
	v_mfma_f32_32x32x16_bf16 v[64:79], v[178:181], v[228:231], v[64:79]
	v_mfma_f32_32x32x16_bf16 v[0:15], v[216:219], v[228:231], v[0:15]
	ds_read_b128 v[228:231], v184 offset:4640
	global_load_dwordx4 v[178:181], v[136:137], off offset:2048
	global_load_dwordx4 v[216:219], v[140:141], off offset:2048
	s_waitcnt lgkmcnt(1)
	v_mfma_f32_32x32x16_bf16 v[112:127], v[172:175], v[224:227], v[112:127]
	v_mfma_f32_32x32x16_bf16 v[48:63], v[220:223], v[224:227], v[48:63]
	s_waitcnt lgkmcnt(0)
	v_mfma_f32_32x32x16_bf16 v[96:111], v[172:175], v[228:231], v[96:111]
	v_mfma_f32_32x32x16_bf16 v[32:47], v[220:223], v[228:231], v[32:47]
	ds_read_b128 v[224:227], v184 offset:9248
	ds_read_b128 v[228:231], v184 offset:13856
	s_waitcnt vmcnt(7)
	ds_write_b128 v177, v[158:161]
	s_waitcnt vmcnt(6)
	ds_write_b128 v176, v[162:165]
	ds_read_b128 v[158:161], v192 offset:36928
	ds_read_b128 v[162:165], v192 offset:41536
	s_waitcnt lgkmcnt(5)
	v_mfma_f32_32x32x16_bf16 v[80:95], v[172:175], v[224:227], v[80:95]
	v_mfma_f32_32x32x16_bf16 v[16:31], v[220:223], v[224:227], v[16:31]
	ds_read_b128 v[224:227], v184 offset:64
	s_waitcnt lgkmcnt(5)
	v_mfma_f32_32x32x16_bf16 v[64:79], v[172:175], v[228:231], v[64:79]
	v_mfma_f32_32x32x16_bf16 v[0:15], v[220:223], v[228:231], v[0:15]
	ds_read_b128 v[228:231], v184 offset:4672
	global_load_dwordx4 v[172:175], v[144:145], off offset:2048
	global_load_dwordx4 v[220:223], v[148:149], off offset:2048
	s_waitcnt lgkmcnt(1)
	v_mfma_f32_32x32x16_bf16 v[112:127], v[158:161], v[224:227], v[112:127]
	v_mfma_f32_32x32x16_bf16 v[48:63], v[162:165], v[224:227], v[48:63]
	s_waitcnt lgkmcnt(0)
	v_mfma_f32_32x32x16_bf16 v[96:111], v[158:161], v[228:231], v[96:111]
	v_mfma_f32_32x32x16_bf16 v[32:47], v[162:165], v[228:231], v[32:47]
	ds_read_b128 v[224:227], v184 offset:9280
	ds_read_b128 v[228:231], v184 offset:13888
	s_waitcnt vmcnt(7)
	ds_write_b128 v171, v[198:201]
	s_waitcnt vmcnt(6)
	ds_write_b128 v170, v[202:205]
	ds_read_b128 v[198:201], v192 offset:36960
	ds_read_b128 v[202:205], v192 offset:41568
	s_waitcnt lgkmcnt(5)
	v_mfma_f32_32x32x16_bf16 v[80:95], v[158:161], v[224:227], v[80:95]
	v_mfma_f32_32x32x16_bf16 v[16:31], v[162:165], v[224:227], v[16:31]
	ds_read_b128 v[224:227], v184 offset:96
	s_waitcnt lgkmcnt(5)
	v_mfma_f32_32x32x16_bf16 v[64:79], v[158:161], v[228:231], v[64:79]
	v_mfma_f32_32x32x16_bf16 v[0:15], v[162:165], v[228:231], v[0:15]
	ds_read_b128 v[228:231], v184 offset:4704
	global_load_dwordx4 v[158:161], v[152:153], off offset:2048
	global_load_dwordx4 v[162:165], v[156:157], off offset:2048
	s_waitcnt lgkmcnt(1)
	v_mfma_f32_32x32x16_bf16 v[112:127], v[198:201], v[224:227], v[112:127]
	v_mfma_f32_32x32x16_bf16 v[48:63], v[202:205], v[224:227], v[48:63]
	s_waitcnt lgkmcnt(0)
	v_mfma_f32_32x32x16_bf16 v[96:111], v[198:201], v[228:231], v[96:111]
	v_mfma_f32_32x32x16_bf16 v[32:47], v[202:205], v[228:231], v[32:47]
	ds_read_b128 v[224:227], v184 offset:9312
	ds_read_b128 v[228:231], v184 offset:13920
	s_waitcnt lgkmcnt(1)
	v_mfma_f32_32x32x16_bf16 v[80:95], v[198:201], v[224:227], v[80:95]
	v_mfma_f32_32x32x16_bf16 v[16:31], v[202:205], v[224:227], v[16:31]
	s_waitcnt lgkmcnt(0)
	v_mfma_f32_32x32x16_bf16 v[64:79], v[198:201], v[228:231], v[64:79]
	v_mfma_f32_32x32x16_bf16 v[0:15], v[202:205], v[228:231], v[0:15]
	s_setprio 0
	s_barrier
; template <bool trans>
; DI void gemm_core(const GTile& tl, const GTile& nx, bool has_next  , bool chain  , bool pre, u32x4 (&ra)[4], u32x4 (&rb)[4], char* smem, f32x16 (&acc)[2][4]) {
;     ...
;   const int nk = K / 64;
;   if (!pre) { G_LOAD(0); G_STORE(0); G_LOAD(1); }
;   for (int kt = 0; kt < nk; ++kt) {
;     __syncthreads();
;     G_COMPUTE(kt & 1, kt);
	global_load_dwordx4 v[198:201], v[128:129], off offset:2176
	global_load_dwordx4 v[202:205], v[132:133], off offset:2176
	s_waitcnt vmcnt(9)
	ds_write_b128 v191, v[208:211]
	s_waitcnt vmcnt(8)
	ds_write_b128 v191, v[212:215] offset:36864
	ds_read_b128 v[208:211], v169
	ds_read_b128 v[212:215], v169 offset:4608
	ds_read_b128 v[224:227], v168
	ds_read_b128 v[228:231], v168 offset:4608
	s_setprio 1
	s_waitcnt lgkmcnt(1)
	v_mfma_f32_32x32x16_bf16 v[112:127], v[208:211], v[224:227], v[112:127]
	v_mfma_f32_32x32x16_bf16 v[48:63], v[212:215], v[224:227], v[48:63]
	s_waitcnt lgkmcnt(0)
	v_mfma_f32_32x32x16_bf16 v[96:111], v[208:211], v[228:231], v[96:111]
	v_mfma_f32_32x32x16_bf16 v[32:47], v[212:215], v[228:231], v[32:47]
	ds_read_b128 v[224:227], v168 offset:9216
	ds_read_b128 v[228:231], v168 offset:13824
	s_waitcnt vmcnt(7)
	ds_write_b128 v191, v[178:181] offset:9216
	s_waitcnt vmcnt(6)
	ds_write_b128 v191, v[216:219] offset:46080
	ds_read_b128 v[178:181], v169 offset:32
	ds_read_b128 v[216:219], v169 offset:4640
	s_waitcnt lgkmcnt(5)
	v_mfma_f32_32x32x16_bf16 v[80:95], v[208:211], v[224:227], v[80:95]
	v_mfma_f32_32x32x16_bf16 v[16:31], v[212:215], v[224:227], v[16:31]
	ds_read_b128 v[224:227], v168 offset:32
	s_waitcnt lgkmcnt(5)
	v_mfma_f32_32x32x16_bf16 v[64:79], v[208:211], v[228:231], v[64:79]
	v_mfma_f32_32x32x16_bf16 v[0:15], v[212:215], v[228:231], v[0:15]
	ds_read_b128 v[228:231], v168 offset:4640
	global_load_dwordx4 v[208:211], v[136:137], off offset:2176
	global_load_dwordx4 v[212:215], v[140:141], off offset:2176
	s_waitcnt lgkmcnt(1)
	v_mfma_f32_32x32x16_bf16 v[112:127], v[178:181], v[224:227], v[112:127]
	v_mfma_f32_32x32x16_bf16 v[48:63], v[216:219], v[224:227], v[48:63]
	s_waitcnt lgkmcnt(0)
	v_mfma_f32_32x32x16_bf16 v[96:111], v[178:181], v[228:231], v[96:111]
	v_mfma_f32_32x32x16_bf16 v[32:47], v[216:219], v[228:231], v[32:47]
	ds_read_b128 v[224:227], v168 offset:9248
	ds_read_b128 v[228:231], v168 offset:13856
	s_waitcnt vmcnt(7)
	ds_write_b128 v191, v[172:175] offset:18432
	s_waitcnt vmcnt(6)
	ds_write_b128 v191, v[220:223] offset:55296
	ds_read_b128 v[172:175], v169 offset:64
	ds_read_b128 v[220:223], v169 offset:4672
	s_waitcnt lgkmcnt(5)
	v_mfma_f32_32x32x16_bf16 v[80:95], v[178:181], v[224:227], v[80:95]
	v_mfma_f32_32x32x16_bf16 v[16:31], v[216:219], v[224:227], v[16:31]
	ds_read_b128 v[224:227], v168 offset:64
	s_waitcnt lgkmcnt(5)
	v_mfma_f32_32x32x16_bf16 v[64:79], v[178:181], v[228:231], v[64:79]
	v_mfma_f32_32x32x16_bf16 v[0:15], v[216:219], v[228:231], v[0:15]
	ds_read_b128 v[228:231], v168 offset:4672
	global_load_dwordx4 v[178:181], v[144:145], off offset:2176
	global_load_dwordx4 v[216:219], v[148:149], off offset:2176
	s_waitcnt lgkmcnt(1)
	v_mfma_f32_32x32x16_bf16 v[112:127], v[172:175], v[224:227], v[112:127]
	v_mfma_f32_32x32x16_bf16 v[48:63], v[220:223], v[224:227], v[48:63]
	s_waitcnt lgkmcnt(0)
	v_mfma_f32_32x32x16_bf16 v[96:111], v[172:175], v[228:231], v[96:111]
	v_mfma_f32_32x32x16_bf16 v[32:47], v[220:223], v[228:231], v[32:47]
	ds_read_b128 v[224:227], v168 offset:9280
	ds_read_b128 v[228:231], v168 offset:13888
	s_waitcnt vmcnt(7)
	ds_write_b128 v191, v[158:161] offset:27648
	s_waitcnt vmcnt(6)
	ds_write_b128 v191, v[162:165] offset:64512
	ds_read_b128 v[158:161], v169 offset:96
	ds_read_b128 v[162:165], v169 offset:4704
	s_waitcnt lgkmcnt(5)
	v_mfma_f32_32x32x16_bf16 v[80:95], v[172:175], v[224:227], v[80:95]
	v_mfma_f32_32x32x16_bf16 v[16:31], v[220:223], v[224:227], v[16:31]
	ds_read_b128 v[224:227], v168 offset:96
	s_waitcnt lgkmcnt(5)
	v_mfma_f32_32x32x16_bf16 v[64:79], v[172:175], v[228:231], v[64:79]
	v_mfma_f32_32x32x16_bf16 v[0:15], v[220:223], v[228:231], v[0:15]
	ds_read_b128 v[228:231], v168 offset:4704
	global_load_dwordx4 v[172:175], v[152:153], off offset:2176
	global_load_dwordx4 v[220:223], v[156:157], off offset:2176
	s_waitcnt lgkmcnt(1)
	v_mfma_f32_32x32x16_bf16 v[112:127], v[158:161], v[224:227], v[112:127]
	v_mfma_f32_32x32x16_bf16 v[48:63], v[162:165], v[224:227], v[48:63]
	s_waitcnt lgkmcnt(0)
	v_mfma_f32_32x32x16_bf16 v[96:111], v[158:161], v[228:231], v[96:111]
	v_mfma_f32_32x32x16_bf16 v[32:47], v[162:165], v[228:231], v[32:47]
	ds_read_b128 v[224:227], v168 offset:9312
	ds_read_b128 v[228:231], v168 offset:13920
	s_waitcnt lgkmcnt(1)
	v_mfma_f32_32x32x16_bf16 v[80:95], v[158:161], v[224:227], v[80:95]
	v_mfma_f32_32x32x16_bf16 v[16:31], v[162:165], v[224:227], v[16:31]
	s_waitcnt lgkmcnt(0)
	v_mfma_f32_32x32x16_bf16 v[64:79], v[158:161], v[228:231], v[64:79]
	v_mfma_f32_32x32x16_bf16 v[0:15], v[162:165], v[228:231], v[0:15]
	s_setprio 0
	s_barrier
; template <bool trans>
; DI void gemm_core(const GTile& tl, const GTile& nx, bool has_next  , bool chain  , bool pre, u32x4 (&ra)[4], u32x4 (&rb)[4], char* smem, f32x16 (&acc)[2][4]) {
;     ...
;   const int nk = K / 64;
;   if (!pre) { G_LOAD(0); G_STORE(0); G_LOAD(1); }
;   for (int kt = 0; kt < nk; ++kt) {
;     __syncthreads();
;     G_COMPUTE(kt & 1, kt);
	global_load_dwordx4 v[158:161], v[128:129], off offset:2304
	global_load_dwordx4 v[162:165], v[132:133], off offset:2304
	s_waitcnt vmcnt(9)
	ds_write_b128 v195, v[198:201]
	s_waitcnt vmcnt(8)
	ds_write_b128 v196, v[202:205]
	ds_read_b128 v[198:201], v192 offset:36864
	ds_read_b128 v[202:205], v192 offset:41472
	ds_read_b128 v[224:227], v184
	ds_read_b128 v[228:231], v184 offset:4608
	s_setprio 1
	s_waitcnt lgkmcnt(1)
	v_mfma_f32_32x32x16_bf16 v[112:127], v[198:201], v[224:227], v[112:127]
	v_mfma_f32_32x32x16_bf16 v[48:63], v[202:205], v[224:227], v[48:63]
	s_waitcnt lgkmcnt(0)
	v_mfma_f32_32x32x16_bf16 v[96:111], v[198:201], v[228:231], v[96:111]
	v_mfma_f32_32x32x16_bf16 v[32:47], v[202:205], v[228:231], v[32:47]
	ds_read_b128 v[224:227], v184 offset:9216
	ds_read_b128 v[228:231], v184 offset:13824
	s_waitcnt vmcnt(7)
	ds_write_b128 v194, v[208:211]
	s_waitcnt vmcnt(6)
	ds_write_b128 v193, v[212:215]
	ds_read_b128 v[208:211], v192 offset:36896
	ds_read_b128 v[212:215], v192 offset:41504
	s_waitcnt lgkmcnt(5)
	v_mfma_f32_32x32x16_bf16 v[80:95], v[198:201], v[224:227], v[80:95]
	v_mfma_f32_32x32x16_bf16 v[16:31], v[202:205], v[224:227], v[16:31]
	ds_read_b128 v[224:227], v184 offset:32
	s_waitcnt lgkmcnt(5)
	v_mfma_f32_32x32x16_bf16 v[64:79], v[198:201], v[228:231], v[64:79]
	v_mfma_f32_32x32x16_bf16 v[0:15], v[202:205], v[228:231], v[0:15]
	ds_read_b128 v[228:231], v184 offset:4640
	global_load_dwordx4 v[198:201], v[136:137], off offset:2304
	global_load_dwordx4 v[202:205], v[140:141], off offset:2304
	s_waitcnt lgkmcnt(1)
	v_mfma_f32_32x32x16_bf16 v[112:127], v[208:211], v[224:227], v[112:127]
	v_mfma_f32_32x32x16_bf16 v[48:63], v[212:215], v[224:227], v[48:63]
	s_waitcnt lgkmcnt(0)
	v_mfma_f32_32x32x16_bf16 v[96:111], v[208:211], v[228:231], v[96:111]
	v_mfma_f32_32x32x16_bf16 v[32:47], v[212:215], v[228:231], v[32:47]
	ds_read_b128 v[224:227], v184 offset:9248
	ds_read_b128 v[228:231], v184 offset:13856
	s_waitcnt vmcnt(7)
	ds_write_b128 v177, v[178:181]
	s_waitcnt vmcnt(6)
	ds_write_b128 v176, v[216:219]
	ds_read_b128 v[178:181], v192 offset:36928
	ds_read_b128 v[216:219], v192 offset:41536
	s_waitcnt lgkmcnt(5)
	v_mfma_f32_32x32x16_bf16 v[80:95], v[208:211], v[224:227], v[80:95]
	v_mfma_f32_32x32x16_bf16 v[16:31], v[212:215], v[224:227], v[16:31]
	ds_read_b128 v[224:227], v184 offset:64
	s_waitcnt lgkmcnt(5)
	v_mfma_f32_32x32x16_bf16 v[64:79], v[208:211], v[228:231], v[64:79]
	v_mfma_f32_32x32x16_bf16 v[0:15], v[212:215], v[228:231], v[0:15]
	ds_read_b128 v[228:231], v184 offset:4672
	global_load_dwordx4 v[208:211], v[144:145], off offset:2304
	global_load_dwordx4 v[212:215], v[148:149], off offset:2304
	s_waitcnt lgkmcnt(1)
	v_mfma_f32_32x32x16_bf16 v[112:127], v[178:181], v[224:227], v[112:127]
	v_mfma_f32_32x32x16_bf16 v[48:63], v[216:219], v[224:227], v[48:63]
	s_waitcnt lgkmcnt(0)
	v_mfma_f32_32x32x16_bf16 v[96:111], v[178:181], v[228:231], v[96:111]
	v_mfma_f32_32x32x16_bf16 v[32:47], v[216:219], v[228:231], v[32:47]
	ds_read_b128 v[224:227], v184 offset:9280
	ds_read_b128 v[228:231], v184 offset:13888
	s_waitcnt vmcnt(7)
	ds_write_b128 v171, v[172:175]
	s_waitcnt vmcnt(6)
	ds_write_b128 v170, v[220:223]
	ds_read_b128 v[172:175], v192 offset:36960
	ds_read_b128 v[220:223], v192 offset:41568
	s_waitcnt lgkmcnt(5)
	v_mfma_f32_32x32x16_bf16 v[80:95], v[178:181], v[224:227], v[80:95]
	v_mfma_f32_32x32x16_bf16 v[16:31], v[216:219], v[224:227], v[16:31]
	ds_read_b128 v[224:227], v184 offset:96
	s_waitcnt lgkmcnt(5)
	v_mfma_f32_32x32x16_bf16 v[64:79], v[178:181], v[228:231], v[64:79]
	v_mfma_f32_32x32x16_bf16 v[0:15], v[216:219], v[228:231], v[0:15]
	ds_read_b128 v[228:231], v184 offset:4704
	global_load_dwordx4 v[178:181], v[152:153], off offset:2304
	global_load_dwordx4 v[216:219], v[156:157], off offset:2304
	s_waitcnt lgkmcnt(1)
	v_mfma_f32_32x32x16_bf16 v[112:127], v[172:175], v[224:227], v[112:127]
	v_mfma_f32_32x32x16_bf16 v[48:63], v[220:223], v[224:227], v[48:63]
	s_waitcnt lgkmcnt(0)
	v_mfma_f32_32x32x16_bf16 v[96:111], v[172:175], v[228:231], v[96:111]
	v_mfma_f32_32x32x16_bf16 v[32:47], v[220:223], v[228:231], v[32:47]
	ds_read_b128 v[224:227], v184 offset:9312
	ds_read_b128 v[228:231], v184 offset:13920
	s_waitcnt lgkmcnt(1)
	v_mfma_f32_32x32x16_bf16 v[80:95], v[172:175], v[224:227], v[80:95]
	v_mfma_f32_32x32x16_bf16 v[16:31], v[220:223], v[224:227], v[16:31]
	s_waitcnt lgkmcnt(0)
	v_mfma_f32_32x32x16_bf16 v[64:79], v[172:175], v[228:231], v[64:79]
	v_mfma_f32_32x32x16_bf16 v[0:15], v[220:223], v[228:231], v[0:15]
	s_setprio 0
	s_barrier
; template <bool trans>
; DI void gemm_core(const GTile& tl, const GTile& nx, bool has_next  , bool chain  , bool pre, u32x4 (&ra)[4], u32x4 (&rb)[4], char* smem, f32x16 (&acc)[2][4]) {
;     ...
;   const int nk = K / 64;
;   if (!pre) { G_LOAD(0); G_STORE(0); G_LOAD(1); }
;   for (int kt = 0; kt < nk; ++kt) {
;     __syncthreads();
;     G_COMPUTE(kt & 1, kt);
	global_load_dwordx4 v[172:175], v[128:129], off offset:2432
	global_load_dwordx4 v[220:223], v[132:133], off offset:2432
	s_waitcnt vmcnt(9)
	ds_write_b128 v191, v[158:161]
	s_waitcnt vmcnt(8)
	ds_write_b128 v191, v[162:165] offset:36864
	ds_read_b128 v[158:161], v169
	ds_read_b128 v[162:165], v169 offset:4608
	ds_read_b128 v[224:227], v168
	ds_read_b128 v[228:231], v168 offset:4608
	s_setprio 1
	s_waitcnt lgkmcnt(1)
	v_mfma_f32_32x32x16_bf16 v[112:127], v[158:161], v[224:227], v[112:127]
	v_mfma_f32_32x32x16_bf16 v[48:63], v[162:165], v[224:227], v[48:63]
	s_waitcnt lgkmcnt(0)
	v_mfma_f32_32x32x16_bf16 v[96:111], v[158:161], v[228:231], v[96:111]
	v_mfma_f32_32x32x16_bf16 v[32:47], v[162:165], v[228:231], v[32:47]
	ds_read_b128 v[224:227], v168 offset:9216
	ds_read_b128 v[228:231], v168 offset:13824
	s_waitcnt vmcnt(7)
	ds_write_b128 v191, v[198:201] offset:9216
	s_waitcnt vmcnt(6)
	ds_write_b128 v191, v[202:205] offset:46080
	ds_read_b128 v[198:201], v169 offset:32
	ds_read_b128 v[202:205], v169 offset:4640
	s_waitcnt lgkmcnt(5)
	v_mfma_f32_32x32x16_bf16 v[80:95], v[158:161], v[224:227], v[80:95]
	v_mfma_f32_32x32x16_bf16 v[16:31], v[162:165], v[224:227], v[16:31]
	ds_read_b128 v[224:227], v168 offset:32
	s_waitcnt lgkmcnt(5)
	v_mfma_f32_32x32x16_bf16 v[64:79], v[158:161], v[228:231], v[64:79]
	v_mfma_f32_32x32x16_bf16 v[0:15], v[162:165], v[228:231], v[0:15]
	ds_read_b128 v[228:231], v168 offset:4640
	global_load_dwordx4 v[158:161], v[136:137], off offset:2432
	global_load_dwordx4 v[162:165], v[140:141], off offset:2432
	s_waitcnt lgkmcnt(1)
	v_mfma_f32_32x32x16_bf16 v[112:127], v[198:201], v[224:227], v[112:127]
	v_mfma_f32_32x32x16_bf16 v[48:63], v[202:205], v[224:227], v[48:63]
	s_waitcnt lgkmcnt(0)
	v_mfma_f32_32x32x16_bf16 v[96:111], v[198:201], v[228:231], v[96:111]
	v_mfma_f32_32x32x16_bf16 v[32:47], v[202:205], v[228:231], v[32:47]
	ds_read_b128 v[224:227], v168 offset:9248
	ds_read_b128 v[228:231], v168 offset:13856
	s_waitcnt vmcnt(7)
	ds_write_b128 v191, v[208:211] offset:18432
	s_waitcnt vmcnt(6)
	ds_write_b128 v191, v[212:215] offset:55296
	ds_read_b128 v[208:211], v169 offset:64
	ds_read_b128 v[212:215], v169 offset:4672
	s_waitcnt lgkmcnt(5)
	v_mfma_f32_32x32x16_bf16 v[80:95], v[198:201], v[224:227], v[80:95]
	v_mfma_f32_32x32x16_bf16 v[16:31], v[202:205], v[224:227], v[16:31]
	ds_read_b128 v[224:227], v168 offset:64
	s_waitcnt lgkmcnt(5)
	v_mfma_f32_32x32x16_bf16 v[64:79], v[198:201], v[228:231], v[64:79]
	v_mfma_f32_32x32x16_bf16 v[0:15], v[202:205], v[228:231], v[0:15]
	ds_read_b128 v[228:231], v168 offset:4672
	global_load_dwordx4 v[198:201], v[144:145], off offset:2432
	global_load_dwordx4 v[202:205], v[148:149], off offset:2432
	s_waitcnt lgkmcnt(1)
	v_mfma_f32_32x32x16_bf16 v[112:127], v[208:211], v[224:227], v[112:127]
	v_mfma_f32_32x32x16_bf16 v[48:63], v[212:215], v[224:227], v[48:63]
	s_waitcnt lgkmcnt(0)
	v_mfma_f32_32x32x16_bf16 v[96:111], v[208:211], v[228:231], v[96:111]
	v_mfma_f32_32x32x16_bf16 v[32:47], v[212:215], v[228:231], v[32:47]
	ds_read_b128 v[224:227], v168 offset:9280
	ds_read_b128 v[228:231], v168 offset:13888
	s_waitcnt vmcnt(7)
	ds_write_b128 v191, v[178:181] offset:27648
	s_waitcnt vmcnt(6)
	ds_write_b128 v191, v[216:219] offset:64512
	ds_read_b128 v[178:181], v169 offset:96
	ds_read_b128 v[216:219], v169 offset:4704
	s_waitcnt lgkmcnt(5)
	v_mfma_f32_32x32x16_bf16 v[80:95], v[208:211], v[224:227], v[80:95]
	v_mfma_f32_32x32x16_bf16 v[16:31], v[212:215], v[224:227], v[16:31]
	ds_read_b128 v[224:227], v168 offset:96
	s_waitcnt lgkmcnt(5)
	v_mfma_f32_32x32x16_bf16 v[64:79], v[208:211], v[228:231], v[64:79]
	v_mfma_f32_32x32x16_bf16 v[0:15], v[212:215], v[228:231], v[0:15]
	ds_read_b128 v[228:231], v168 offset:4704
	global_load_dwordx4 v[208:211], v[152:153], off offset:2432
	global_load_dwordx4 v[212:215], v[156:157], off offset:2432
	s_waitcnt lgkmcnt(1)
	v_mfma_f32_32x32x16_bf16 v[112:127], v[178:181], v[224:227], v[112:127]
	v_mfma_f32_32x32x16_bf16 v[48:63], v[216:219], v[224:227], v[48:63]
	s_waitcnt lgkmcnt(0)
	v_mfma_f32_32x32x16_bf16 v[96:111], v[178:181], v[228:231], v[96:111]
	v_mfma_f32_32x32x16_bf16 v[32:47], v[216:219], v[228:231], v[32:47]
	ds_read_b128 v[224:227], v168 offset:9312
	ds_read_b128 v[228:231], v168 offset:13920
	s_waitcnt lgkmcnt(1)
	v_mfma_f32_32x32x16_bf16 v[80:95], v[178:181], v[224:227], v[80:95]
	v_mfma_f32_32x32x16_bf16 v[16:31], v[216:219], v[224:227], v[16:31]
	s_waitcnt lgkmcnt(0)
	v_mfma_f32_32x32x16_bf16 v[64:79], v[178:181], v[228:231], v[64:79]
	v_mfma_f32_32x32x16_bf16 v[0:15], v[216:219], v[228:231], v[0:15]
	s_setprio 0
	s_barrier
; template <bool trans>
; DI void gemm_core(const GTile& tl, const GTile& nx, bool has_next  , bool chain  , bool pre, u32x4 (&ra)[4], u32x4 (&rb)[4], char* smem, f32x16 (&acc)[2][4]) {
;     ...
;   const int nk = K / 64;
;   if (!pre) { G_LOAD(0); G_STORE(0); G_LOAD(1); }
;   for (int kt = 0; kt < nk; ++kt) {
;     __syncthreads();
;     G_COMPUTE(kt & 1, kt);
	global_load_dwordx4 v[178:181], v[128:129], off offset:2560
	global_load_dwordx4 v[216:219], v[132:133], off offset:2560
	s_waitcnt vmcnt(9)
	ds_write_b128 v195, v[172:175]
	s_waitcnt vmcnt(8)
	ds_write_b128 v196, v[220:223]
	ds_read_b128 v[172:175], v192 offset:36864
	ds_read_b128 v[220:223], v192 offset:41472
	ds_read_b128 v[224:227], v184
	ds_read_b128 v[228:231], v184 offset:4608
	s_setprio 1
	s_waitcnt lgkmcnt(1)
	v_mfma_f32_32x32x16_bf16 v[112:127], v[172:175], v[224:227], v[112:127]
	v_mfma_f32_32x32x16_bf16 v[48:63], v[220:223], v[224:227], v[48:63]
	s_waitcnt lgkmcnt(0)
	v_mfma_f32_32x32x16_bf16 v[96:111], v[172:175], v[228:231], v[96:111]
	v_mfma_f32_32x32x16_bf16 v[32:47], v[220:223], v[228:231], v[32:47]
	ds_read_b128 v[224:227], v184 offset:9216
	ds_read_b128 v[228:231], v184 offset:13824
	s_waitcnt vmcnt(7)
	ds_write_b128 v194, v[158:161]
	s_waitcnt vmcnt(6)
	ds_write_b128 v193, v[162:165]
	ds_read_b128 v[158:161], v192 offset:36896
	ds_read_b128 v[162:165], v192 offset:41504
	s_waitcnt lgkmcnt(5)
	v_mfma_f32_32x32x16_bf16 v[80:95], v[172:175], v[224:227], v[80:95]
	v_mfma_f32_32x32x16_bf16 v[16:31], v[220:223], v[224:227], v[16:31]
	ds_read_b128 v[224:227], v184 offset:32
	s_waitcnt lgkmcnt(5)
	v_mfma_f32_32x32x16_bf16 v[64:79], v[172:175], v[228:231], v[64:79]
	v_mfma_f32_32x32x16_bf16 v[0:15], v[220:223], v[228:231], v[0:15]
	ds_read_b128 v[228:231], v184 offset:4640
	global_load_dwordx4 v[172:175], v[136:137], off offset:2560
	global_load_dwordx4 v[220:223], v[140:141], off offset:2560
	s_waitcnt lgkmcnt(1)
	v_mfma_f32_32x32x16_bf16 v[112:127], v[158:161], v[224:227], v[112:127]
	v_mfma_f32_32x32x16_bf16 v[48:63], v[162:165], v[224:227], v[48:63]
	s_waitcnt lgkmcnt(0)
	v_mfma_f32_32x32x16_bf16 v[96:111], v[158:161], v[228:231], v[96:111]
	v_mfma_f32_32x32x16_bf16 v[32:47], v[162:165], v[228:231], v[32:47]
	ds_read_b128 v[224:227], v184 offset:9248
	ds_read_b128 v[228:231], v184 offset:13856
	s_waitcnt vmcnt(7)
	ds_write_b128 v177, v[198:201]
	s_waitcnt vmcnt(6)
	ds_write_b128 v176, v[202:205]
	ds_read_b128 v[198:201], v192 offset:36928
	ds_read_b128 v[202:205], v192 offset:41536
	s_waitcnt lgkmcnt(5)
	v_mfma_f32_32x32x16_bf16 v[80:95], v[158:161], v[224:227], v[80:95]
	v_mfma_f32_32x32x16_bf16 v[16:31], v[162:165], v[224:227], v[16:31]
	ds_read_b128 v[224:227], v184 offset:64
	s_waitcnt lgkmcnt(5)
	v_mfma_f32_32x32x16_bf16 v[64:79], v[158:161], v[228:231], v[64:79]
	v_mfma_f32_32x32x16_bf16 v[0:15], v[162:165], v[228:231], v[0:15]
	ds_read_b128 v[228:231], v184 offset:4672
	global_load_dwordx4 v[158:161], v[144:145], off offset:2560
	global_load_dwordx4 v[162:165], v[148:149], off offset:2560
	s_waitcnt lgkmcnt(1)
	v_mfma_f32_32x32x16_bf16 v[112:127], v[198:201], v[224:227], v[112:127]
	v_mfma_f32_32x32x16_bf16 v[48:63], v[202:205], v[224:227], v[48:63]
	s_waitcnt lgkmcnt(0)
	v_mfma_f32_32x32x16_bf16 v[96:111], v[198:201], v[228:231], v[96:111]
	v_mfma_f32_32x32x16_bf16 v[32:47], v[202:205], v[228:231], v[32:47]
	ds_read_b128 v[224:227], v184 offset:9280
	ds_read_b128 v[228:231], v184 offset:13888
	s_waitcnt vmcnt(7)
	ds_write_b128 v171, v[208:211]
	s_waitcnt vmcnt(6)
	ds_write_b128 v170, v[212:215]
	ds_read_b128 v[208:211], v192 offset:36960
	ds_read_b128 v[212:215], v192 offset:41568
	s_waitcnt lgkmcnt(5)
	v_mfma_f32_32x32x16_bf16 v[80:95], v[198:201], v[224:227], v[80:95]
	v_mfma_f32_32x32x16_bf16 v[16:31], v[202:205], v[224:227], v[16:31]
	ds_read_b128 v[224:227], v184 offset:96
	s_waitcnt lgkmcnt(5)
	v_mfma_f32_32x32x16_bf16 v[64:79], v[198:201], v[228:231], v[64:79]
	v_mfma_f32_32x32x16_bf16 v[0:15], v[202:205], v[228:231], v[0:15]
	ds_read_b128 v[228:231], v184 offset:4704
	global_load_dwordx4 v[198:201], v[152:153], off offset:2560
	global_load_dwordx4 v[202:205], v[156:157], off offset:2560
	s_waitcnt lgkmcnt(1)
	v_mfma_f32_32x32x16_bf16 v[112:127], v[208:211], v[224:227], v[112:127]
	v_mfma_f32_32x32x16_bf16 v[48:63], v[212:215], v[224:227], v[48:63]
	s_waitcnt lgkmcnt(0)
	v_mfma_f32_32x32x16_bf16 v[96:111], v[208:211], v[228:231], v[96:111]
	v_mfma_f32_32x32x16_bf16 v[32:47], v[212:215], v[228:231], v[32:47]
	ds_read_b128 v[224:227], v184 offset:9312
	ds_read_b128 v[228:231], v184 offset:13920
	s_waitcnt lgkmcnt(1)
	v_mfma_f32_32x32x16_bf16 v[80:95], v[208:211], v[224:227], v[80:95]
	v_mfma_f32_32x32x16_bf16 v[16:31], v[212:215], v[224:227], v[16:31]
	s_waitcnt lgkmcnt(0)
	v_mfma_f32_32x32x16_bf16 v[64:79], v[208:211], v[228:231], v[64:79]
	v_mfma_f32_32x32x16_bf16 v[0:15], v[212:215], v[228:231], v[0:15]
	s_setprio 0
	s_barrier
; template <bool trans>
; DI void gemm_core(const GTile& tl, const GTile& nx, bool has_next  , bool chain  , bool pre, u32x4 (&ra)[4], u32x4 (&rb)[4], char* smem, f32x16 (&acc)[2][4]) {
;     ...
;   const int nk = K / 64;
;   if (!pre) { G_LOAD(0); G_STORE(0); G_LOAD(1); }
;   for (int kt = 0; kt < nk; ++kt) {
;     __syncthreads();
;     G_COMPUTE(kt & 1, kt);
	global_load_dwordx4 v[208:211], v[128:129], off offset:2688
	global_load_dwordx4 v[212:215], v[132:133], off offset:2688
	s_waitcnt vmcnt(9)
	ds_write_b128 v191, v[178:181]
	s_waitcnt vmcnt(8)
	ds_write_b128 v191, v[216:219] offset:36864
	ds_read_b128 v[178:181], v169
	ds_read_b128 v[216:219], v169 offset:4608
	ds_read_b128 v[224:227], v168
	ds_read_b128 v[228:231], v168 offset:4608
	s_setprio 1
	s_waitcnt lgkmcnt(1)
	v_mfma_f32_32x32x16_bf16 v[112:127], v[178:181], v[224:227], v[112:127]
	v_mfma_f32_32x32x16_bf16 v[48:63], v[216:219], v[224:227], v[48:63]
	s_waitcnt lgkmcnt(0)
	v_mfma_f32_32x32x16_bf16 v[96:111], v[178:181], v[228:231], v[96:111]
	v_mfma_f32_32x32x16_bf16 v[32:47], v[216:219], v[228:231], v[32:47]
	ds_read_b128 v[224:227], v168 offset:9216
	ds_read_b128 v[228:231], v168 offset:13824
	s_waitcnt vmcnt(7)
	ds_write_b128 v191, v[172:175] offset:9216
	s_waitcnt vmcnt(6)
	ds_write_b128 v191, v[220:223] offset:46080
	ds_read_b128 v[172:175], v169 offset:32
	ds_read_b128 v[220:223], v169 offset:4640
	s_waitcnt lgkmcnt(5)
	v_mfma_f32_32x32x16_bf16 v[80:95], v[178:181], v[224:227], v[80:95]
	v_mfma_f32_32x32x16_bf16 v[16:31], v[216:219], v[224:227], v[16:31]
	ds_read_b128 v[224:227], v168 offset:32
	s_waitcnt lgkmcnt(5)
	v_mfma_f32_32x32x16_bf16 v[64:79], v[178:181], v[228:231], v[64:79]
	v_mfma_f32_32x32x16_bf16 v[0:15], v[216:219], v[228:231], v[0:15]
	ds_read_b128 v[228:231], v168 offset:4640
	global_load_dwordx4 v[178:181], v[136:137], off offset:2688
	global_load_dwordx4 v[216:219], v[140:141], off offset:2688
	s_waitcnt lgkmcnt(1)
	v_mfma_f32_32x32x16_bf16 v[112:127], v[172:175], v[224:227], v[112:127]
	v_mfma_f32_32x32x16_bf16 v[48:63], v[220:223], v[224:227], v[48:63]
	s_waitcnt lgkmcnt(0)
	v_mfma_f32_32x32x16_bf16 v[96:111], v[172:175], v[228:231], v[96:111]
	v_mfma_f32_32x32x16_bf16 v[32:47], v[220:223], v[228:231], v[32:47]
	ds_read_b128 v[224:227], v168 offset:9248
	ds_read_b128 v[228:231], v168 offset:13856
	s_waitcnt vmcnt(7)
	ds_write_b128 v191, v[158:161] offset:18432
	s_waitcnt vmcnt(6)
	ds_write_b128 v191, v[162:165] offset:55296
	ds_read_b128 v[158:161], v169 offset:64
	ds_read_b128 v[162:165], v169 offset:4672
	s_waitcnt lgkmcnt(5)
	v_mfma_f32_32x32x16_bf16 v[80:95], v[172:175], v[224:227], v[80:95]
	v_mfma_f32_32x32x16_bf16 v[16:31], v[220:223], v[224:227], v[16:31]
	ds_read_b128 v[224:227], v168 offset:64
	s_waitcnt lgkmcnt(5)
	v_mfma_f32_32x32x16_bf16 v[64:79], v[172:175], v[228:231], v[64:79]
	v_mfma_f32_32x32x16_bf16 v[0:15], v[220:223], v[228:231], v[0:15]
	ds_read_b128 v[228:231], v168 offset:4672
	global_load_dwordx4 v[172:175], v[144:145], off offset:2688
	global_load_dwordx4 v[220:223], v[148:149], off offset:2688
	s_waitcnt lgkmcnt(1)
	v_mfma_f32_32x32x16_bf16 v[112:127], v[158:161], v[224:227], v[112:127]
	v_mfma_f32_32x32x16_bf16 v[48:63], v[162:165], v[224:227], v[48:63]
	s_waitcnt lgkmcnt(0)
	v_mfma_f32_32x32x16_bf16 v[96:111], v[158:161], v[228:231], v[96:111]
	v_mfma_f32_32x32x16_bf16 v[32:47], v[162:165], v[228:231], v[32:47]
	ds_read_b128 v[224:227], v168 offset:9280
	ds_read_b128 v[228:231], v168 offset:13888
	s_waitcnt vmcnt(7)
	ds_write_b128 v191, v[198:201] offset:27648
	s_waitcnt vmcnt(6)
	ds_write_b128 v191, v[202:205] offset:64512
	ds_read_b128 v[198:201], v169 offset:96
	ds_read_b128 v[202:205], v169 offset:4704
	s_waitcnt lgkmcnt(5)
	v_mfma_f32_32x32x16_bf16 v[80:95], v[158:161], v[224:227], v[80:95]
	v_mfma_f32_32x32x16_bf16 v[16:31], v[162:165], v[224:227], v[16:31]
	ds_read_b128 v[224:227], v168 offset:96
	s_waitcnt lgkmcnt(5)
	v_mfma_f32_32x32x16_bf16 v[64:79], v[158:161], v[228:231], v[64:79]
	v_mfma_f32_32x32x16_bf16 v[0:15], v[162:165], v[228:231], v[0:15]
	ds_read_b128 v[228:231], v168 offset:4704
	global_load_dwordx4 v[158:161], v[152:153], off offset:2688
	global_load_dwordx4 v[162:165], v[156:157], off offset:2688
	s_waitcnt lgkmcnt(1)
	v_mfma_f32_32x32x16_bf16 v[112:127], v[198:201], v[224:227], v[112:127]
	v_mfma_f32_32x32x16_bf16 v[48:63], v[202:205], v[224:227], v[48:63]
	s_waitcnt lgkmcnt(0)
	v_mfma_f32_32x32x16_bf16 v[96:111], v[198:201], v[228:231], v[96:111]
	v_mfma_f32_32x32x16_bf16 v[32:47], v[202:205], v[228:231], v[32:47]
	ds_read_b128 v[224:227], v168 offset:9312
	ds_read_b128 v[228:231], v168 offset:13920
	s_waitcnt lgkmcnt(1)
	v_mfma_f32_32x32x16_bf16 v[80:95], v[198:201], v[224:227], v[80:95]
	v_mfma_f32_32x32x16_bf16 v[16:31], v[202:205], v[224:227], v[16:31]
	s_waitcnt lgkmcnt(0)
	v_mfma_f32_32x32x16_bf16 v[64:79], v[198:201], v[228:231], v[64:79]
	v_mfma_f32_32x32x16_bf16 v[0:15], v[202:205], v[228:231], v[0:15]
	s_setprio 0
	s_barrier
; template <bool trans>
; DI void gemm_core(const GTile& tl, const GTile& nx, bool has_next  , bool chain  , bool pre, u32x4 (&ra)[4], u32x4 (&rb)[4], char* smem, f32x16 (&acc)[2][4]) {
;     ...
;   const int nk = K / 64;
;   if (!pre) { G_LOAD(0); G_STORE(0); G_LOAD(1); }
;   for (int kt = 0; kt < nk; ++kt) {
;     __syncthreads();
;     G_COMPUTE(kt & 1, kt);
	global_load_dwordx4 v[198:201], v[128:129], off offset:2816
	global_load_dwordx4 v[202:205], v[132:133], off offset:2816
	s_waitcnt vmcnt(9)
	ds_write_b128 v195, v[208:211]
	s_waitcnt vmcnt(8)
	ds_write_b128 v196, v[212:215]
	ds_read_b128 v[208:211], v192 offset:36864
	ds_read_b128 v[212:215], v192 offset:41472
	ds_read_b128 v[224:227], v184
	ds_read_b128 v[228:231], v184 offset:4608
	s_setprio 1
	s_waitcnt lgkmcnt(1)
	v_mfma_f32_32x32x16_bf16 v[112:127], v[208:211], v[224:227], v[112:127]
	v_mfma_f32_32x32x16_bf16 v[48:63], v[212:215], v[224:227], v[48:63]
	s_waitcnt lgkmcnt(0)
	v_mfma_f32_32x32x16_bf16 v[96:111], v[208:211], v[228:231], v[96:111]
	v_mfma_f32_32x32x16_bf16 v[32:47], v[212:215], v[228:231], v[32:47]
	ds_read_b128 v[224:227], v184 offset:9216
	ds_read_b128 v[228:231], v184 offset:13824
	s_waitcnt vmcnt(7)
	ds_write_b128 v194, v[178:181]
	s_waitcnt vmcnt(6)
	ds_write_b128 v193, v[216:219]
	ds_read_b128 v[178:181], v192 offset:36896
	ds_read_b128 v[216:219], v192 offset:41504
	s_waitcnt lgkmcnt(5)
	v_mfma_f32_32x32x16_bf16 v[80:95], v[208:211], v[224:227], v[80:95]
	v_mfma_f32_32x32x16_bf16 v[16:31], v[212:215], v[224:227], v[16:31]
	ds_read_b128 v[224:227], v184 offset:32
	s_waitcnt lgkmcnt(5)
	v_mfma_f32_32x32x16_bf16 v[64:79], v[208:211], v[228:231], v[64:79]
	v_mfma_f32_32x32x16_bf16 v[0:15], v[212:215], v[228:231], v[0:15]
	ds_read_b128 v[228:231], v184 offset:4640
	global_load_dwordx4 v[208:211], v[136:137], off offset:2816
	global_load_dwordx4 v[212:215], v[140:141], off offset:2816
	s_waitcnt lgkmcnt(1)
	v_mfma_f32_32x32x16_bf16 v[112:127], v[178:181], v[224:227], v[112:127]
	v_mfma_f32_32x32x16_bf16 v[48:63], v[216:219], v[224:227], v[48:63]
	s_waitcnt lgkmcnt(0)
	v_mfma_f32_32x32x16_bf16 v[96:111], v[178:181], v[228:231], v[96:111]
	v_mfma_f32_32x32x16_bf16 v[32:47], v[216:219], v[228:231], v[32:47]
	ds_read_b128 v[224:227], v184 offset:9248
	ds_read_b128 v[228:231], v184 offset:13856
	s_waitcnt vmcnt(7)
	ds_write_b128 v177, v[172:175]
	s_waitcnt vmcnt(6)
	ds_write_b128 v176, v[220:223]
	ds_read_b128 v[172:175], v192 offset:36928
	ds_read_b128 v[220:223], v192 offset:41536
	s_waitcnt lgkmcnt(5)
	v_mfma_f32_32x32x16_bf16 v[80:95], v[178:181], v[224:227], v[80:95]
	v_mfma_f32_32x32x16_bf16 v[16:31], v[216:219], v[224:227], v[16:31]
	ds_read_b128 v[224:227], v184 offset:64
	s_waitcnt lgkmcnt(5)
	v_mfma_f32_32x32x16_bf16 v[64:79], v[178:181], v[228:231], v[64:79]
	v_mfma_f32_32x32x16_bf16 v[0:15], v[216:219], v[228:231], v[0:15]
	ds_read_b128 v[228:231], v184 offset:4672
	global_load_dwordx4 v[178:181], v[144:145], off offset:2816
	global_load_dwordx4 v[216:219], v[148:149], off offset:2816
	s_waitcnt lgkmcnt(1)
	v_mfma_f32_32x32x16_bf16 v[112:127], v[172:175], v[224:227], v[112:127]
	v_mfma_f32_32x32x16_bf16 v[48:63], v[220:223], v[224:227], v[48:63]
	s_waitcnt lgkmcnt(0)
	v_mfma_f32_32x32x16_bf16 v[96:111], v[172:175], v[228:231], v[96:111]
	v_mfma_f32_32x32x16_bf16 v[32:47], v[220:223], v[228:231], v[32:47]
	ds_read_b128 v[224:227], v184 offset:9280
	ds_read_b128 v[228:231], v184 offset:13888
	s_waitcnt vmcnt(7)
	ds_write_b128 v171, v[158:161]
	s_waitcnt vmcnt(6)
	ds_write_b128 v170, v[162:165]
	ds_read_b128 v[158:161], v192 offset:36960
	ds_read_b128 v[162:165], v192 offset:41568
	s_waitcnt lgkmcnt(5)
	v_mfma_f32_32x32x16_bf16 v[80:95], v[172:175], v[224:227], v[80:95]
	v_mfma_f32_32x32x16_bf16 v[16:31], v[220:223], v[224:227], v[16:31]
	ds_read_b128 v[224:227], v184 offset:96
	s_waitcnt lgkmcnt(5)
	v_mfma_f32_32x32x16_bf16 v[64:79], v[172:175], v[228:231], v[64:79]
	v_mfma_f32_32x32x16_bf16 v[0:15], v[220:223], v[228:231], v[0:15]
	ds_read_b128 v[228:231], v184 offset:4704
	global_load_dwordx4 v[172:175], v[152:153], off offset:2816
	global_load_dwordx4 v[220:223], v[156:157], off offset:2816
	s_waitcnt lgkmcnt(1)
	v_mfma_f32_32x32x16_bf16 v[112:127], v[158:161], v[224:227], v[112:127]
	v_mfma_f32_32x32x16_bf16 v[48:63], v[162:165], v[224:227], v[48:63]
	s_waitcnt lgkmcnt(0)
	v_mfma_f32_32x32x16_bf16 v[96:111], v[158:161], v[228:231], v[96:111]
	v_mfma_f32_32x32x16_bf16 v[32:47], v[162:165], v[228:231], v[32:47]
	ds_read_b128 v[224:227], v184 offset:9312
	ds_read_b128 v[228:231], v184 offset:13920
	s_waitcnt lgkmcnt(1)
	v_mfma_f32_32x32x16_bf16 v[80:95], v[158:161], v[224:227], v[80:95]
	v_mfma_f32_32x32x16_bf16 v[16:31], v[162:165], v[224:227], v[16:31]
	s_waitcnt lgkmcnt(0)
	v_mfma_f32_32x32x16_bf16 v[64:79], v[158:161], v[228:231], v[64:79]
	v_mfma_f32_32x32x16_bf16 v[0:15], v[162:165], v[228:231], v[0:15]
	s_setprio 0
	s_barrier
; template <bool trans>
; DI void gemm_core(const GTile& tl, const GTile& nx, bool has_next  , bool chain  , bool pre, u32x4 (&ra)[4], u32x4 (&rb)[4], char* smem, f32x16 (&acc)[2][4]) {
;     ...
;   const int nk = K / 64;
;   if (!pre) { G_LOAD(0); G_STORE(0); G_LOAD(1); }
;   for (int kt = 0; kt < nk; ++kt) {
;     __syncthreads();
;     G_COMPUTE(kt & 1, kt);
	global_load_dwordx4 v[158:161], v[128:129], off offset:2944
	global_load_dwordx4 v[162:165], v[132:133], off offset:2944
	s_waitcnt vmcnt(9)
	ds_write_b128 v191, v[198:201]
	s_waitcnt vmcnt(8)
	ds_write_b128 v191, v[202:205] offset:36864
	ds_read_b128 v[198:201], v169
	ds_read_b128 v[202:205], v169 offset:4608
	ds_read_b128 v[224:227], v168
	ds_read_b128 v[228:231], v168 offset:4608
	s_setprio 1
	s_waitcnt lgkmcnt(1)
	v_mfma_f32_32x32x16_bf16 v[112:127], v[198:201], v[224:227], v[112:127]
	v_mfma_f32_32x32x16_bf16 v[48:63], v[202:205], v[224:227], v[48:63]
	s_waitcnt lgkmcnt(0)
	v_mfma_f32_32x32x16_bf16 v[96:111], v[198:201], v[228:231], v[96:111]
	v_mfma_f32_32x32x16_bf16 v[32:47], v[202:205], v[228:231], v[32:47]
	ds_read_b128 v[224:227], v168 offset:9216
	ds_read_b128 v[228:231], v168 offset:13824
	s_waitcnt vmcnt(7)
	ds_write_b128 v191, v[208:211] offset:9216
	s_waitcnt vmcnt(6)
	ds_write_b128 v191, v[212:215] offset:46080
	ds_read_b128 v[208:211], v169 offset:32
	ds_read_b128 v[212:215], v169 offset:4640
	s_waitcnt lgkmcnt(5)
	v_mfma_f32_32x32x16_bf16 v[80:95], v[198:201], v[224:227], v[80:95]
	v_mfma_f32_32x32x16_bf16 v[16:31], v[202:205], v[224:227], v[16:31]
	ds_read_b128 v[224:227], v168 offset:32
	s_waitcnt lgkmcnt(5)
	v_mfma_f32_32x32x16_bf16 v[64:79], v[198:201], v[228:231], v[64:79]
	v_mfma_f32_32x32x16_bf16 v[0:15], v[202:205], v[228:231], v[0:15]
	ds_read_b128 v[228:231], v168 offset:4640
	global_load_dwordx4 v[198:201], v[136:137], off offset:2944
	global_load_dwordx4 v[202:205], v[140:141], off offset:2944
	s_waitcnt lgkmcnt(1)
	v_mfma_f32_32x32x16_bf16 v[112:127], v[208:211], v[224:227], v[112:127]
	v_mfma_f32_32x32x16_bf16 v[48:63], v[212:215], v[224:227], v[48:63]
	s_waitcnt lgkmcnt(0)
	v_mfma_f32_32x32x16_bf16 v[96:111], v[208:211], v[228:231], v[96:111]
	v_mfma_f32_32x32x16_bf16 v[32:47], v[212:215], v[228:231], v[32:47]
	ds_read_b128 v[224:227], v168 offset:9248
	ds_read_b128 v[228:231], v168 offset:13856
	s_waitcnt vmcnt(7)
	ds_write_b128 v191, v[178:181] offset:18432
	s_waitcnt vmcnt(6)
	ds_write_b128 v191, v[216:219] offset:55296
	ds_read_b128 v[178:181], v169 offset:64
	ds_read_b128 v[216:219], v169 offset:4672
	s_waitcnt lgkmcnt(5)
	v_mfma_f32_32x32x16_bf16 v[80:95], v[208:211], v[224:227], v[80:95]
	v_mfma_f32_32x32x16_bf16 v[16:31], v[212:215], v[224:227], v[16:31]
	ds_read_b128 v[224:227], v168 offset:64
	s_waitcnt lgkmcnt(5)
	v_mfma_f32_32x32x16_bf16 v[64:79], v[208:211], v[228:231], v[64:79]
	v_mfma_f32_32x32x16_bf16 v[0:15], v[212:215], v[228:231], v[0:15]
	ds_read_b128 v[228:231], v168 offset:4672
	global_load_dwordx4 v[208:211], v[144:145], off offset:2944
	global_load_dwordx4 v[212:215], v[148:149], off offset:2944
	s_waitcnt lgkmcnt(1)
	v_mfma_f32_32x32x16_bf16 v[112:127], v[178:181], v[224:227], v[112:127]
	v_mfma_f32_32x32x16_bf16 v[48:63], v[216:219], v[224:227], v[48:63]
	s_waitcnt lgkmcnt(0)
	v_mfma_f32_32x32x16_bf16 v[96:111], v[178:181], v[228:231], v[96:111]
	v_mfma_f32_32x32x16_bf16 v[32:47], v[216:219], v[228:231], v[32:47]
	ds_read_b128 v[224:227], v168 offset:9280
	ds_read_b128 v[228:231], v168 offset:13888
	s_waitcnt vmcnt(7)
	ds_write_b128 v191, v[172:175] offset:27648
	s_waitcnt vmcnt(6)
	ds_write_b128 v191, v[220:223] offset:64512
	ds_read_b128 v[172:175], v169 offset:96
	ds_read_b128 v[220:223], v169 offset:4704
	s_waitcnt lgkmcnt(5)
	v_mfma_f32_32x32x16_bf16 v[80:95], v[178:181], v[224:227], v[80:95]
	v_mfma_f32_32x32x16_bf16 v[16:31], v[216:219], v[224:227], v[16:31]
	ds_read_b128 v[224:227], v168 offset:96
	s_waitcnt lgkmcnt(5)
	v_mfma_f32_32x32x16_bf16 v[64:79], v[178:181], v[228:231], v[64:79]
	v_mfma_f32_32x32x16_bf16 v[0:15], v[216:219], v[228:231], v[0:15]
	ds_read_b128 v[228:231], v168 offset:4704
	global_load_dwordx4 v[178:181], v[152:153], off offset:2944
	global_load_dwordx4 v[216:219], v[156:157], off offset:2944
	s_waitcnt lgkmcnt(1)
	v_mfma_f32_32x32x16_bf16 v[112:127], v[172:175], v[224:227], v[112:127]
	v_mfma_f32_32x32x16_bf16 v[48:63], v[220:223], v[224:227], v[48:63]
	s_waitcnt lgkmcnt(0)
	v_mfma_f32_32x32x16_bf16 v[96:111], v[172:175], v[228:231], v[96:111]
	v_mfma_f32_32x32x16_bf16 v[32:47], v[220:223], v[228:231], v[32:47]
	ds_read_b128 v[224:227], v168 offset:9312
	ds_read_b128 v[228:231], v168 offset:13920
	s_waitcnt lgkmcnt(1)
	v_mfma_f32_32x32x16_bf16 v[80:95], v[172:175], v[224:227], v[80:95]
	v_mfma_f32_32x32x16_bf16 v[16:31], v[220:223], v[224:227], v[16:31]
	s_waitcnt lgkmcnt(0)
	v_mfma_f32_32x32x16_bf16 v[64:79], v[172:175], v[228:231], v[64:79]
	v_mfma_f32_32x32x16_bf16 v[0:15], v[220:223], v[228:231], v[0:15]
	s_setprio 0
	s_barrier
; template <bool trans>
; DI void gemm_core(const GTile& tl, const GTile& nx, bool has_next  , bool chain  , bool pre, u32x4 (&ra)[4], u32x4 (&rb)[4], char* smem, f32x16 (&acc)[2][4]) {
;     ...
;   const int nk = K / 64;
;   if (!pre) { G_LOAD(0); G_STORE(0); G_LOAD(1); }
;   for (int kt = 0; kt < nk; ++kt) {
;     __syncthreads();
;     G_COMPUTE(kt & 1, kt);
	global_load_dwordx4 v[172:175], v[128:129], off offset:3072
	global_load_dwordx4 v[220:223], v[132:133], off offset:3072
	s_waitcnt vmcnt(9)
	ds_write_b128 v195, v[158:161]
	s_waitcnt vmcnt(8)
	ds_write_b128 v196, v[162:165]
	ds_read_b128 v[158:161], v192 offset:36864
	ds_read_b128 v[162:165], v192 offset:41472
	ds_read_b128 v[224:227], v184
	ds_read_b128 v[228:231], v184 offset:4608
	s_setprio 1
	s_waitcnt lgkmcnt(1)
	v_mfma_f32_32x32x16_bf16 v[112:127], v[158:161], v[224:227], v[112:127]
	v_mfma_f32_32x32x16_bf16 v[48:63], v[162:165], v[224:227], v[48:63]
	s_waitcnt lgkmcnt(0)
	v_mfma_f32_32x32x16_bf16 v[96:111], v[158:161], v[228:231], v[96:111]
	v_mfma_f32_32x32x16_bf16 v[32:47], v[162:165], v[228:231], v[32:47]
	ds_read_b128 v[224:227], v184 offset:9216
	ds_read_b128 v[228:231], v184 offset:13824
	s_waitcnt vmcnt(7)
	ds_write_b128 v194, v[198:201]
	s_waitcnt vmcnt(6)
	ds_write_b128 v193, v[202:205]
	ds_read_b128 v[198:201], v192 offset:36896
	ds_read_b128 v[202:205], v192 offset:41504
	s_waitcnt lgkmcnt(5)
	v_mfma_f32_32x32x16_bf16 v[80:95], v[158:161], v[224:227], v[80:95]
	v_mfma_f32_32x32x16_bf16 v[16:31], v[162:165], v[224:227], v[16:31]
	ds_read_b128 v[224:227], v184 offset:32
	s_waitcnt lgkmcnt(5)
	v_mfma_f32_32x32x16_bf16 v[64:79], v[158:161], v[228:231], v[64:79]
	v_mfma_f32_32x32x16_bf16 v[0:15], v[162:165], v[228:231], v[0:15]
	ds_read_b128 v[228:231], v184 offset:4640
	global_load_dwordx4 v[158:161], v[136:137], off offset:3072
	global_load_dwordx4 v[162:165], v[140:141], off offset:3072
	s_waitcnt lgkmcnt(1)
	v_mfma_f32_32x32x16_bf16 v[112:127], v[198:201], v[224:227], v[112:127]
	v_mfma_f32_32x32x16_bf16 v[48:63], v[202:205], v[224:227], v[48:63]
	s_waitcnt lgkmcnt(0)
	v_mfma_f32_32x32x16_bf16 v[96:111], v[198:201], v[228:231], v[96:111]
	v_mfma_f32_32x32x16_bf16 v[32:47], v[202:205], v[228:231], v[32:47]
	ds_read_b128 v[224:227], v184 offset:9248
	ds_read_b128 v[228:231], v184 offset:13856
	s_waitcnt vmcnt(7)
	ds_write_b128 v177, v[208:211]
	s_waitcnt vmcnt(6)
	ds_write_b128 v176, v[212:215]
	ds_read_b128 v[208:211], v192 offset:36928
	ds_read_b128 v[212:215], v192 offset:41536
	s_waitcnt lgkmcnt(5)
	v_mfma_f32_32x32x16_bf16 v[80:95], v[198:201], v[224:227], v[80:95]
	v_mfma_f32_32x32x16_bf16 v[16:31], v[202:205], v[224:227], v[16:31]
	ds_read_b128 v[224:227], v184 offset:64
	s_waitcnt lgkmcnt(5)
	v_mfma_f32_32x32x16_bf16 v[64:79], v[198:201], v[228:231], v[64:79]
	v_mfma_f32_32x32x16_bf16 v[0:15], v[202:205], v[228:231], v[0:15]
	ds_read_b128 v[228:231], v184 offset:4672
	global_load_dwordx4 v[198:201], v[144:145], off offset:3072
	global_load_dwordx4 v[202:205], v[148:149], off offset:3072
	s_waitcnt lgkmcnt(1)
	v_mfma_f32_32x32x16_bf16 v[112:127], v[208:211], v[224:227], v[112:127]
	v_mfma_f32_32x32x16_bf16 v[48:63], v[212:215], v[224:227], v[48:63]
	s_waitcnt lgkmcnt(0)
	v_mfma_f32_32x32x16_bf16 v[96:111], v[208:211], v[228:231], v[96:111]
	v_mfma_f32_32x32x16_bf16 v[32:47], v[212:215], v[228:231], v[32:47]
	ds_read_b128 v[224:227], v184 offset:9280
	ds_read_b128 v[228:231], v184 offset:13888
	s_waitcnt vmcnt(7)
	ds_write_b128 v171, v[178:181]
	s_waitcnt vmcnt(6)
	ds_write_b128 v170, v[216:219]
	ds_read_b128 v[178:181], v192 offset:36960
	ds_read_b128 v[216:219], v192 offset:41568
	s_waitcnt lgkmcnt(5)
	v_mfma_f32_32x32x16_bf16 v[80:95], v[208:211], v[224:227], v[80:95]
	v_mfma_f32_32x32x16_bf16 v[16:31], v[212:215], v[224:227], v[16:31]
	ds_read_b128 v[224:227], v184 offset:96
	s_waitcnt lgkmcnt(5)
	v_mfma_f32_32x32x16_bf16 v[64:79], v[208:211], v[228:231], v[64:79]
	v_mfma_f32_32x32x16_bf16 v[0:15], v[212:215], v[228:231], v[0:15]
	ds_read_b128 v[228:231], v184 offset:4704
	global_load_dwordx4 v[208:211], v[152:153], off offset:3072
	global_load_dwordx4 v[212:215], v[156:157], off offset:3072
	s_waitcnt lgkmcnt(1)
	v_mfma_f32_32x32x16_bf16 v[112:127], v[178:181], v[224:227], v[112:127]
	v_mfma_f32_32x32x16_bf16 v[48:63], v[216:219], v[224:227], v[48:63]
	s_waitcnt lgkmcnt(0)
	v_mfma_f32_32x32x16_bf16 v[96:111], v[178:181], v[228:231], v[96:111]
	v_mfma_f32_32x32x16_bf16 v[32:47], v[216:219], v[228:231], v[32:47]
	ds_read_b128 v[224:227], v184 offset:9312
	ds_read_b128 v[228:231], v184 offset:13920
	s_waitcnt lgkmcnt(1)
	v_mfma_f32_32x32x16_bf16 v[80:95], v[178:181], v[224:227], v[80:95]
	v_mfma_f32_32x32x16_bf16 v[16:31], v[216:219], v[224:227], v[16:31]
	s_waitcnt lgkmcnt(0)
	v_mfma_f32_32x32x16_bf16 v[64:79], v[178:181], v[228:231], v[64:79]
	v_mfma_f32_32x32x16_bf16 v[0:15], v[216:219], v[228:231], v[0:15]
	s_setprio 0
	s_barrier
; template <bool trans>
; DI void gemm_core(const GTile& tl, const GTile& nx, bool has_next  , bool chain  , bool pre, u32x4 (&ra)[4], u32x4 (&rb)[4], char* smem, f32x16 (&acc)[2][4]) {
;     ...
;   const int nk = K / 64;
;   if (!pre) { G_LOAD(0); G_STORE(0); G_LOAD(1); }
;   for (int kt = 0; kt < nk; ++kt) {
;     __syncthreads();
;     G_COMPUTE(kt & 1, kt);
	global_load_dwordx4 v[178:181], v[128:129], off offset:3200
	global_load_dwordx4 v[216:219], v[132:133], off offset:3200
	s_waitcnt vmcnt(9)
	ds_write_b128 v191, v[172:175]
	s_waitcnt vmcnt(8)
	ds_write_b128 v191, v[220:223] offset:36864
	ds_read_b128 v[172:175], v169
	ds_read_b128 v[220:223], v169 offset:4608
	ds_read_b128 v[224:227], v168
	ds_read_b128 v[228:231], v168 offset:4608
	s_setprio 1
	s_waitcnt lgkmcnt(1)
	v_mfma_f32_32x32x16_bf16 v[112:127], v[172:175], v[224:227], v[112:127]
	v_mfma_f32_32x32x16_bf16 v[48:63], v[220:223], v[224:227], v[48:63]
	s_waitcnt lgkmcnt(0)
	v_mfma_f32_32x32x16_bf16 v[96:111], v[172:175], v[228:231], v[96:111]
	v_mfma_f32_32x32x16_bf16 v[32:47], v[220:223], v[228:231], v[32:47]
	ds_read_b128 v[224:227], v168 offset:9216
	ds_read_b128 v[228:231], v168 offset:13824
	s_waitcnt vmcnt(7)
	ds_write_b128 v191, v[158:161] offset:9216
	s_waitcnt vmcnt(6)
	ds_write_b128 v191, v[162:165] offset:46080
	ds_read_b128 v[158:161], v169 offset:32
	ds_read_b128 v[162:165], v169 offset:4640
	s_waitcnt lgkmcnt(5)
	v_mfma_f32_32x32x16_bf16 v[80:95], v[172:175], v[224:227], v[80:95]
	v_mfma_f32_32x32x16_bf16 v[16:31], v[220:223], v[224:227], v[16:31]
	ds_read_b128 v[224:227], v168 offset:32
	s_waitcnt lgkmcnt(5)
	v_mfma_f32_32x32x16_bf16 v[64:79], v[172:175], v[228:231], v[64:79]
	v_mfma_f32_32x32x16_bf16 v[0:15], v[220:223], v[228:231], v[0:15]
	ds_read_b128 v[228:231], v168 offset:4640
	global_load_dwordx4 v[172:175], v[136:137], off offset:3200
	global_load_dwordx4 v[220:223], v[140:141], off offset:3200
	s_waitcnt lgkmcnt(1)
	v_mfma_f32_32x32x16_bf16 v[112:127], v[158:161], v[224:227], v[112:127]
	v_mfma_f32_32x32x16_bf16 v[48:63], v[162:165], v[224:227], v[48:63]
	s_waitcnt lgkmcnt(0)
	v_mfma_f32_32x32x16_bf16 v[96:111], v[158:161], v[228:231], v[96:111]
	v_mfma_f32_32x32x16_bf16 v[32:47], v[162:165], v[228:231], v[32:47]
	ds_read_b128 v[224:227], v168 offset:9248
	ds_read_b128 v[228:231], v168 offset:13856
	s_waitcnt vmcnt(7)
	ds_write_b128 v191, v[198:201] offset:18432
	s_waitcnt vmcnt(6)
	ds_write_b128 v191, v[202:205] offset:55296
	ds_read_b128 v[198:201], v169 offset:64
	ds_read_b128 v[202:205], v169 offset:4672
	s_waitcnt lgkmcnt(5)
	v_mfma_f32_32x32x16_bf16 v[80:95], v[158:161], v[224:227], v[80:95]
	v_mfma_f32_32x32x16_bf16 v[16:31], v[162:165], v[224:227], v[16:31]
	ds_read_b128 v[224:227], v168 offset:64
	s_waitcnt lgkmcnt(5)
	v_mfma_f32_32x32x16_bf16 v[64:79], v[158:161], v[228:231], v[64:79]
	v_mfma_f32_32x32x16_bf16 v[0:15], v[162:165], v[228:231], v[0:15]
	ds_read_b128 v[228:231], v168 offset:4672
	global_load_dwordx4 v[158:161], v[144:145], off offset:3200
	global_load_dwordx4 v[162:165], v[148:149], off offset:3200
	s_waitcnt lgkmcnt(1)
	v_mfma_f32_32x32x16_bf16 v[112:127], v[198:201], v[224:227], v[112:127]
	v_mfma_f32_32x32x16_bf16 v[48:63], v[202:205], v[224:227], v[48:63]
	s_waitcnt lgkmcnt(0)
	v_mfma_f32_32x32x16_bf16 v[96:111], v[198:201], v[228:231], v[96:111]
	v_mfma_f32_32x32x16_bf16 v[32:47], v[202:205], v[228:231], v[32:47]
	ds_read_b128 v[224:227], v168 offset:9280
	ds_read_b128 v[228:231], v168 offset:13888
	s_waitcnt vmcnt(7)
	ds_write_b128 v191, v[208:211] offset:27648
	s_waitcnt vmcnt(6)
	ds_write_b128 v191, v[212:215] offset:64512
	ds_read_b128 v[208:211], v169 offset:96
	ds_read_b128 v[212:215], v169 offset:4704
	s_waitcnt lgkmcnt(5)
	v_mfma_f32_32x32x16_bf16 v[80:95], v[198:201], v[224:227], v[80:95]
	v_mfma_f32_32x32x16_bf16 v[16:31], v[202:205], v[224:227], v[16:31]
	ds_read_b128 v[224:227], v168 offset:96
	s_waitcnt lgkmcnt(5)
	v_mfma_f32_32x32x16_bf16 v[64:79], v[198:201], v[228:231], v[64:79]
	v_mfma_f32_32x32x16_bf16 v[0:15], v[202:205], v[228:231], v[0:15]
	ds_read_b128 v[228:231], v168 offset:4704
	global_load_dwordx4 v[198:201], v[152:153], off offset:3200
	global_load_dwordx4 v[202:205], v[156:157], off offset:3200
	s_waitcnt lgkmcnt(1)
	v_mfma_f32_32x32x16_bf16 v[112:127], v[208:211], v[224:227], v[112:127]
	v_mfma_f32_32x32x16_bf16 v[48:63], v[212:215], v[224:227], v[48:63]
	s_waitcnt lgkmcnt(0)
	v_mfma_f32_32x32x16_bf16 v[96:111], v[208:211], v[228:231], v[96:111]
	v_mfma_f32_32x32x16_bf16 v[32:47], v[212:215], v[228:231], v[32:47]
	ds_read_b128 v[224:227], v168 offset:9312
	ds_read_b128 v[228:231], v168 offset:13920
	s_waitcnt lgkmcnt(1)
	v_mfma_f32_32x32x16_bf16 v[80:95], v[208:211], v[224:227], v[80:95]
	v_mfma_f32_32x32x16_bf16 v[16:31], v[212:215], v[224:227], v[16:31]
	s_waitcnt lgkmcnt(0)
	v_mfma_f32_32x32x16_bf16 v[64:79], v[208:211], v[228:231], v[64:79]
	v_mfma_f32_32x32x16_bf16 v[0:15], v[212:215], v[228:231], v[0:15]
	s_setprio 0
	s_barrier
; template <bool trans>
; DI void gemm_core(const GTile& tl, const GTile& nx, bool has_next  , bool chain  , bool pre, u32x4 (&ra)[4], u32x4 (&rb)[4], char* smem, f32x16 (&acc)[2][4]) {
;     ...
;   const int nk = K / 64;
;   if (!pre) { G_LOAD(0); G_STORE(0); G_LOAD(1); }
;   for (int kt = 0; kt < nk; ++kt) {
;     __syncthreads();
;     G_COMPUTE(kt & 1, kt);
	global_load_dwordx4 v[208:211], v[128:129], off offset:3328
	global_load_dwordx4 v[212:215], v[132:133], off offset:3328
	s_waitcnt vmcnt(9)
	ds_write_b128 v195, v[178:181]
	s_waitcnt vmcnt(8)
	ds_write_b128 v196, v[216:219]
	ds_read_b128 v[178:181], v192 offset:36864
	ds_read_b128 v[216:219], v192 offset:41472
	ds_read_b128 v[224:227], v184
	ds_read_b128 v[228:231], v184 offset:4608
	s_setprio 1
	s_waitcnt lgkmcnt(1)
	v_mfma_f32_32x32x16_bf16 v[112:127], v[178:181], v[224:227], v[112:127]
	v_mfma_f32_32x32x16_bf16 v[48:63], v[216:219], v[224:227], v[48:63]
	s_waitcnt lgkmcnt(0)
	v_mfma_f32_32x32x16_bf16 v[96:111], v[178:181], v[228:231], v[96:111]
	v_mfma_f32_32x32x16_bf16 v[32:47], v[216:219], v[228:231], v[32:47]
	ds_read_b128 v[224:227], v184 offset:9216
	ds_read_b128 v[228:231], v184 offset:13824
	s_waitcnt vmcnt(7)
	ds_write_b128 v194, v[172:175]
	s_waitcnt vmcnt(6)
	ds_write_b128 v193, v[220:223]
	ds_read_b128 v[172:175], v192 offset:36896
	ds_read_b128 v[220:223], v192 offset:41504
	s_waitcnt lgkmcnt(5)
	v_mfma_f32_32x32x16_bf16 v[80:95], v[178:181], v[224:227], v[80:95]
	v_mfma_f32_32x32x16_bf16 v[16:31], v[216:219], v[224:227], v[16:31]
	ds_read_b128 v[224:227], v184 offset:32
	s_waitcnt lgkmcnt(5)
	v_mfma_f32_32x32x16_bf16 v[64:79], v[178:181], v[228:231], v[64:79]
	v_mfma_f32_32x32x16_bf16 v[0:15], v[216:219], v[228:231], v[0:15]
	ds_read_b128 v[228:231], v184 offset:4640
	global_load_dwordx4 v[178:181], v[136:137], off offset:3328
	global_load_dwordx4 v[216:219], v[140:141], off offset:3328
	s_waitcnt lgkmcnt(1)
	v_mfma_f32_32x32x16_bf16 v[112:127], v[172:175], v[224:227], v[112:127]
	v_mfma_f32_32x32x16_bf16 v[48:63], v[220:223], v[224:227], v[48:63]
	s_waitcnt lgkmcnt(0)
	v_mfma_f32_32x32x16_bf16 v[96:111], v[172:175], v[228:231], v[96:111]
	v_mfma_f32_32x32x16_bf16 v[32:47], v[220:223], v[228:231], v[32:47]
	ds_read_b128 v[224:227], v184 offset:9248
	ds_read_b128 v[228:231], v184 offset:13856
	s_waitcnt vmcnt(7)
	ds_write_b128 v177, v[158:161]
	s_waitcnt vmcnt(6)
	ds_write_b128 v176, v[162:165]
	ds_read_b128 v[158:161], v192 offset:36928
	ds_read_b128 v[162:165], v192 offset:41536
	s_waitcnt lgkmcnt(5)
	v_mfma_f32_32x32x16_bf16 v[80:95], v[172:175], v[224:227], v[80:95]
	v_mfma_f32_32x32x16_bf16 v[16:31], v[220:223], v[224:227], v[16:31]
	ds_read_b128 v[224:227], v184 offset:64
	s_waitcnt lgkmcnt(5)
	v_mfma_f32_32x32x16_bf16 v[64:79], v[172:175], v[228:231], v[64:79]
	v_mfma_f32_32x32x16_bf16 v[0:15], v[220:223], v[228:231], v[0:15]
	ds_read_b128 v[228:231], v184 offset:4672
	global_load_dwordx4 v[172:175], v[144:145], off offset:3328
	global_load_dwordx4 v[220:223], v[148:149], off offset:3328
	s_waitcnt lgkmcnt(1)
	v_mfma_f32_32x32x16_bf16 v[112:127], v[158:161], v[224:227], v[112:127]
	v_mfma_f32_32x32x16_bf16 v[48:63], v[162:165], v[224:227], v[48:63]
	s_waitcnt lgkmcnt(0)
	v_mfma_f32_32x32x16_bf16 v[96:111], v[158:161], v[228:231], v[96:111]
	v_mfma_f32_32x32x16_bf16 v[32:47], v[162:165], v[228:231], v[32:47]
	ds_read_b128 v[224:227], v184 offset:9280
	ds_read_b128 v[228:231], v184 offset:13888
	s_waitcnt vmcnt(7)
	ds_write_b128 v171, v[198:201]
	s_waitcnt vmcnt(6)
	ds_write_b128 v170, v[202:205]
	ds_read_b128 v[198:201], v192 offset:36960
	ds_read_b128 v[202:205], v192 offset:41568
	s_waitcnt lgkmcnt(5)
	v_mfma_f32_32x32x16_bf16 v[80:95], v[158:161], v[224:227], v[80:95]
	v_mfma_f32_32x32x16_bf16 v[16:31], v[162:165], v[224:227], v[16:31]
	ds_read_b128 v[224:227], v184 offset:96
	s_waitcnt lgkmcnt(5)
	v_mfma_f32_32x32x16_bf16 v[64:79], v[158:161], v[228:231], v[64:79]
	v_mfma_f32_32x32x16_bf16 v[0:15], v[162:165], v[228:231], v[0:15]
	ds_read_b128 v[228:231], v184 offset:4704
	global_load_dwordx4 v[158:161], v[152:153], off offset:3328
	global_load_dwordx4 v[162:165], v[156:157], off offset:3328
	s_waitcnt lgkmcnt(1)
	v_mfma_f32_32x32x16_bf16 v[112:127], v[198:201], v[224:227], v[112:127]
	v_mfma_f32_32x32x16_bf16 v[48:63], v[202:205], v[224:227], v[48:63]
	s_waitcnt lgkmcnt(0)
	v_mfma_f32_32x32x16_bf16 v[96:111], v[198:201], v[228:231], v[96:111]
	v_mfma_f32_32x32x16_bf16 v[32:47], v[202:205], v[228:231], v[32:47]
	ds_read_b128 v[224:227], v184 offset:9312
	ds_read_b128 v[228:231], v184 offset:13920
	s_waitcnt lgkmcnt(1)
	v_mfma_f32_32x32x16_bf16 v[80:95], v[198:201], v[224:227], v[80:95]
	v_mfma_f32_32x32x16_bf16 v[16:31], v[202:205], v[224:227], v[16:31]
	s_waitcnt lgkmcnt(0)
	v_mfma_f32_32x32x16_bf16 v[64:79], v[198:201], v[228:231], v[64:79]
	v_mfma_f32_32x32x16_bf16 v[0:15], v[202:205], v[228:231], v[0:15]
	s_setprio 0
	s_barrier
; template <bool trans>
; DI void gemm_core(const GTile& tl, const GTile& nx, bool has_next  , bool chain  , bool pre, u32x4 (&ra)[4], u32x4 (&rb)[4], char* smem, f32x16 (&acc)[2][4]) {
;     ...
;   const int nk = K / 64;
;   if (!pre) { G_LOAD(0); G_STORE(0); G_LOAD(1); }
;   for (int kt = 0; kt < nk; ++kt) {
;     __syncthreads();
;     G_COMPUTE(kt & 1, kt);
	global_load_dwordx4 v[198:201], v[128:129], off offset:3456
	global_load_dwordx4 v[202:205], v[132:133], off offset:3456
	s_waitcnt vmcnt(9)
	ds_write_b128 v191, v[208:211]
	s_waitcnt vmcnt(8)
	ds_write_b128 v191, v[212:215] offset:36864
	ds_read_b128 v[208:211], v169
	ds_read_b128 v[212:215], v169 offset:4608
	ds_read_b128 v[224:227], v168
	ds_read_b128 v[228:231], v168 offset:4608
	s_setprio 1
	s_waitcnt lgkmcnt(1)
	v_mfma_f32_32x32x16_bf16 v[112:127], v[208:211], v[224:227], v[112:127]
	v_mfma_f32_32x32x16_bf16 v[48:63], v[212:215], v[224:227], v[48:63]
	s_waitcnt lgkmcnt(0)
	v_mfma_f32_32x32x16_bf16 v[96:111], v[208:211], v[228:231], v[96:111]
	v_mfma_f32_32x32x16_bf16 v[32:47], v[212:215], v[228:231], v[32:47]
	ds_read_b128 v[224:227], v168 offset:9216
	ds_read_b128 v[228:231], v168 offset:13824
	s_waitcnt vmcnt(7)
	ds_write_b128 v191, v[178:181] offset:9216
	s_waitcnt vmcnt(6)
	ds_write_b128 v191, v[216:219] offset:46080
	ds_read_b128 v[178:181], v169 offset:32
	ds_read_b128 v[216:219], v169 offset:4640
	s_waitcnt lgkmcnt(5)
	v_mfma_f32_32x32x16_bf16 v[80:95], v[208:211], v[224:227], v[80:95]
	v_mfma_f32_32x32x16_bf16 v[16:31], v[212:215], v[224:227], v[16:31]
	ds_read_b128 v[224:227], v168 offset:32
	s_waitcnt lgkmcnt(5)
	v_mfma_f32_32x32x16_bf16 v[64:79], v[208:211], v[228:231], v[64:79]
	v_mfma_f32_32x32x16_bf16 v[0:15], v[212:215], v[228:231], v[0:15]
	ds_read_b128 v[228:231], v168 offset:4640
	global_load_dwordx4 v[208:211], v[136:137], off offset:3456
	global_load_dwordx4 v[212:215], v[140:141], off offset:3456
	s_waitcnt lgkmcnt(1)
	v_mfma_f32_32x32x16_bf16 v[112:127], v[178:181], v[224:227], v[112:127]
	v_mfma_f32_32x32x16_bf16 v[48:63], v[216:219], v[224:227], v[48:63]
	s_waitcnt lgkmcnt(0)
	v_mfma_f32_32x32x16_bf16 v[96:111], v[178:181], v[228:231], v[96:111]
	v_mfma_f32_32x32x16_bf16 v[32:47], v[216:219], v[228:231], v[32:47]
	ds_read_b128 v[224:227], v168 offset:9248
	ds_read_b128 v[228:231], v168 offset:13856
	s_waitcnt vmcnt(7)
	ds_write_b128 v191, v[172:175] offset:18432
	s_waitcnt vmcnt(6)
	ds_write_b128 v191, v[220:223] offset:55296
	ds_read_b128 v[172:175], v169 offset:64
	ds_read_b128 v[220:223], v169 offset:4672
	s_waitcnt lgkmcnt(5)
	v_mfma_f32_32x32x16_bf16 v[80:95], v[178:181], v[224:227], v[80:95]
	v_mfma_f32_32x32x16_bf16 v[16:31], v[216:219], v[224:227], v[16:31]
	ds_read_b128 v[224:227], v168 offset:64
	s_waitcnt lgkmcnt(5)
	v_mfma_f32_32x32x16_bf16 v[64:79], v[178:181], v[228:231], v[64:79]
	v_mfma_f32_32x32x16_bf16 v[0:15], v[216:219], v[228:231], v[0:15]
	ds_read_b128 v[228:231], v168 offset:4672
	global_load_dwordx4 v[178:181], v[144:145], off offset:3456
	global_load_dwordx4 v[216:219], v[148:149], off offset:3456
	s_waitcnt lgkmcnt(1)
	v_mfma_f32_32x32x16_bf16 v[112:127], v[172:175], v[224:227], v[112:127]
	v_mfma_f32_32x32x16_bf16 v[48:63], v[220:223], v[224:227], v[48:63]
	s_waitcnt lgkmcnt(0)
	v_mfma_f32_32x32x16_bf16 v[96:111], v[172:175], v[228:231], v[96:111]
	v_mfma_f32_32x32x16_bf16 v[32:47], v[220:223], v[228:231], v[32:47]
	ds_read_b128 v[224:227], v168 offset:9280
	ds_read_b128 v[228:231], v168 offset:13888
	s_waitcnt vmcnt(7)
	ds_write_b128 v191, v[158:161] offset:27648
	s_waitcnt vmcnt(6)
	ds_write_b128 v191, v[162:165] offset:64512
	ds_read_b128 v[158:161], v169 offset:96
	ds_read_b128 v[162:165], v169 offset:4704
	s_waitcnt lgkmcnt(5)
	v_mfma_f32_32x32x16_bf16 v[80:95], v[172:175], v[224:227], v[80:95]
	v_mfma_f32_32x32x16_bf16 v[16:31], v[220:223], v[224:227], v[16:31]
	ds_read_b128 v[224:227], v168 offset:96
	s_waitcnt lgkmcnt(5)
	v_mfma_f32_32x32x16_bf16 v[64:79], v[172:175], v[228:231], v[64:79]
	v_mfma_f32_32x32x16_bf16 v[0:15], v[220:223], v[228:231], v[0:15]
	ds_read_b128 v[228:231], v168 offset:4704
	global_load_dwordx4 v[172:175], v[152:153], off offset:3456
	global_load_dwordx4 v[220:223], v[156:157], off offset:3456
	s_waitcnt lgkmcnt(1)
	v_mfma_f32_32x32x16_bf16 v[112:127], v[158:161], v[224:227], v[112:127]
	v_mfma_f32_32x32x16_bf16 v[48:63], v[162:165], v[224:227], v[48:63]
	s_waitcnt lgkmcnt(0)
	v_mfma_f32_32x32x16_bf16 v[96:111], v[158:161], v[228:231], v[96:111]
	v_mfma_f32_32x32x16_bf16 v[32:47], v[162:165], v[228:231], v[32:47]
	ds_read_b128 v[224:227], v168 offset:9312
	ds_read_b128 v[228:231], v168 offset:13920
	s_waitcnt lgkmcnt(1)
	v_mfma_f32_32x32x16_bf16 v[80:95], v[158:161], v[224:227], v[80:95]
	v_mfma_f32_32x32x16_bf16 v[16:31], v[162:165], v[224:227], v[16:31]
	s_waitcnt lgkmcnt(0)
	v_mfma_f32_32x32x16_bf16 v[64:79], v[158:161], v[228:231], v[64:79]
	v_mfma_f32_32x32x16_bf16 v[0:15], v[162:165], v[228:231], v[0:15]
	s_setprio 0
	s_barrier
; template <bool trans>
; DI void gemm_core(const GTile& tl, const GTile& nx, bool has_next  , bool chain  , bool pre, u32x4 (&ra)[4], u32x4 (&rb)[4], char* smem, f32x16 (&acc)[2][4]) {
;     ...
;   const int nk = K / 64;
;   if (!pre) { G_LOAD(0); G_STORE(0); G_LOAD(1); }
;   for (int kt = 0; kt < nk; ++kt) {
;     __syncthreads();
;     G_COMPUTE(kt & 1, kt);
	global_load_dwordx4 v[158:161], v[128:129], off offset:3584
	global_load_dwordx4 v[162:165], v[132:133], off offset:3584
	s_waitcnt vmcnt(9)
	ds_write_b128 v195, v[198:201]
	s_waitcnt vmcnt(8)
	ds_write_b128 v196, v[202:205]
	ds_read_b128 v[198:201], v192 offset:36864
	ds_read_b128 v[202:205], v192 offset:41472
	ds_read_b128 v[224:227], v184
	ds_read_b128 v[228:231], v184 offset:4608
	s_setprio 1
	s_waitcnt lgkmcnt(1)
	v_mfma_f32_32x32x16_bf16 v[112:127], v[198:201], v[224:227], v[112:127]
	v_mfma_f32_32x32x16_bf16 v[48:63], v[202:205], v[224:227], v[48:63]
	s_waitcnt lgkmcnt(0)
	v_mfma_f32_32x32x16_bf16 v[96:111], v[198:201], v[228:231], v[96:111]
	v_mfma_f32_32x32x16_bf16 v[32:47], v[202:205], v[228:231], v[32:47]
	ds_read_b128 v[224:227], v184 offset:9216
	ds_read_b128 v[228:231], v184 offset:13824
	s_waitcnt vmcnt(7)
	ds_write_b128 v194, v[208:211]
	s_waitcnt vmcnt(6)
	ds_write_b128 v193, v[212:215]
	ds_read_b128 v[208:211], v192 offset:36896
	ds_read_b128 v[212:215], v192 offset:41504
	s_waitcnt lgkmcnt(5)
	v_mfma_f32_32x32x16_bf16 v[80:95], v[198:201], v[224:227], v[80:95]
	v_mfma_f32_32x32x16_bf16 v[16:31], v[202:205], v[224:227], v[16:31]
	ds_read_b128 v[224:227], v184 offset:32
	s_waitcnt lgkmcnt(5)
	v_mfma_f32_32x32x16_bf16 v[64:79], v[198:201], v[228:231], v[64:79]
	v_mfma_f32_32x32x16_bf16 v[0:15], v[202:205], v[228:231], v[0:15]
	ds_read_b128 v[228:231], v184 offset:4640
	global_load_dwordx4 v[198:201], v[136:137], off offset:3584
	global_load_dwordx4 v[202:205], v[140:141], off offset:3584
	s_waitcnt lgkmcnt(1)
	v_mfma_f32_32x32x16_bf16 v[112:127], v[208:211], v[224:227], v[112:127]
	v_mfma_f32_32x32x16_bf16 v[48:63], v[212:215], v[224:227], v[48:63]
	s_waitcnt lgkmcnt(0)
	v_mfma_f32_32x32x16_bf16 v[96:111], v[208:211], v[228:231], v[96:111]
	v_mfma_f32_32x32x16_bf16 v[32:47], v[212:215], v[228:231], v[32:47]
	ds_read_b128 v[224:227], v184 offset:9248
	ds_read_b128 v[228:231], v184 offset:13856
	s_waitcnt vmcnt(7)
	ds_write_b128 v177, v[178:181]
	s_waitcnt vmcnt(6)
	ds_write_b128 v176, v[216:219]
	ds_read_b128 v[178:181], v192 offset:36928
	ds_read_b128 v[216:219], v192 offset:41536
	s_waitcnt lgkmcnt(5)
	v_mfma_f32_32x32x16_bf16 v[80:95], v[208:211], v[224:227], v[80:95]
	v_mfma_f32_32x32x16_bf16 v[16:31], v[212:215], v[224:227], v[16:31]
	ds_read_b128 v[224:227], v184 offset:64
	s_waitcnt lgkmcnt(5)
	v_mfma_f32_32x32x16_bf16 v[64:79], v[208:211], v[228:231], v[64:79]
	v_mfma_f32_32x32x16_bf16 v[0:15], v[212:215], v[228:231], v[0:15]
	ds_read_b128 v[228:231], v184 offset:4672
	global_load_dwordx4 v[208:211], v[144:145], off offset:3584
	global_load_dwordx4 v[212:215], v[148:149], off offset:3584
	s_waitcnt lgkmcnt(1)
	v_mfma_f32_32x32x16_bf16 v[112:127], v[178:181], v[224:227], v[112:127]
	v_mfma_f32_32x32x16_bf16 v[48:63], v[216:219], v[224:227], v[48:63]
	s_waitcnt lgkmcnt(0)
	v_mfma_f32_32x32x16_bf16 v[96:111], v[178:181], v[228:231], v[96:111]
	v_mfma_f32_32x32x16_bf16 v[32:47], v[216:219], v[228:231], v[32:47]
	ds_read_b128 v[224:227], v184 offset:9280
	ds_read_b128 v[228:231], v184 offset:13888
	s_waitcnt vmcnt(7)
	ds_write_b128 v171, v[172:175]
	s_waitcnt vmcnt(6)
	ds_write_b128 v170, v[220:223]
	ds_read_b128 v[172:175], v192 offset:36960
	ds_read_b128 v[220:223], v192 offset:41568
	s_waitcnt lgkmcnt(5)
	v_mfma_f32_32x32x16_bf16 v[80:95], v[178:181], v[224:227], v[80:95]
	v_mfma_f32_32x32x16_bf16 v[16:31], v[216:219], v[224:227], v[16:31]
	ds_read_b128 v[224:227], v184 offset:96
	s_waitcnt lgkmcnt(5)
	v_mfma_f32_32x32x16_bf16 v[64:79], v[178:181], v[228:231], v[64:79]
	v_mfma_f32_32x32x16_bf16 v[0:15], v[216:219], v[228:231], v[0:15]
	ds_read_b128 v[228:231], v184 offset:4704
	global_load_dwordx4 v[178:181], v[152:153], off offset:3584
	global_load_dwordx4 v[216:219], v[156:157], off offset:3584
	s_waitcnt lgkmcnt(1)
	v_mfma_f32_32x32x16_bf16 v[112:127], v[172:175], v[224:227], v[112:127]
	v_mfma_f32_32x32x16_bf16 v[48:63], v[220:223], v[224:227], v[48:63]
	s_waitcnt lgkmcnt(0)
	v_mfma_f32_32x32x16_bf16 v[96:111], v[172:175], v[228:231], v[96:111]
	v_mfma_f32_32x32x16_bf16 v[32:47], v[220:223], v[228:231], v[32:47]
	ds_read_b128 v[224:227], v184 offset:9312
	ds_read_b128 v[228:231], v184 offset:13920
	s_waitcnt lgkmcnt(1)
	v_mfma_f32_32x32x16_bf16 v[80:95], v[172:175], v[224:227], v[80:95]
	v_mfma_f32_32x32x16_bf16 v[16:31], v[220:223], v[224:227], v[16:31]
	s_waitcnt lgkmcnt(0)
	v_mfma_f32_32x32x16_bf16 v[64:79], v[172:175], v[228:231], v[64:79]
	v_mfma_f32_32x32x16_bf16 v[0:15], v[220:223], v[228:231], v[0:15]
	s_setprio 0
	s_barrier
; template <bool trans>
; DI void gemm_core(const GTile& tl, const GTile& nx, bool has_next  , bool chain  , bool pre, u32x4 (&ra)[4], u32x4 (&rb)[4], char* smem, f32x16 (&acc)[2][4]) {
;     ...
;   const int nk = K / 64;
;   if (!pre) { G_LOAD(0); G_STORE(0); G_LOAD(1); }
;   for (int kt = 0; kt < nk; ++kt) {
;     __syncthreads();
;     G_COMPUTE(kt & 1, kt);
	global_load_dwordx4 v[172:175], v[128:129], off offset:3712
	global_load_dwordx4 v[220:223], v[132:133], off offset:3712
	s_waitcnt vmcnt(9)
	ds_write_b128 v191, v[158:161]
	s_waitcnt vmcnt(8)
	ds_write_b128 v191, v[162:165] offset:36864
	ds_read_b128 v[158:161], v169
	ds_read_b128 v[162:165], v169 offset:4608
	ds_read_b128 v[224:227], v168
	ds_read_b128 v[228:231], v168 offset:4608
	s_setprio 1
	s_waitcnt lgkmcnt(1)
	v_mfma_f32_32x32x16_bf16 v[112:127], v[158:161], v[224:227], v[112:127]
	v_mfma_f32_32x32x16_bf16 v[48:63], v[162:165], v[224:227], v[48:63]
	s_waitcnt lgkmcnt(0)
	v_mfma_f32_32x32x16_bf16 v[96:111], v[158:161], v[228:231], v[96:111]
	v_mfma_f32_32x32x16_bf16 v[32:47], v[162:165], v[228:231], v[32:47]
	ds_read_b128 v[224:227], v168 offset:9216
	ds_read_b128 v[228:231], v168 offset:13824
	s_waitcnt vmcnt(7)
	ds_write_b128 v191, v[198:201] offset:9216
	s_waitcnt vmcnt(6)
	ds_write_b128 v191, v[202:205] offset:46080
	ds_read_b128 v[198:201], v169 offset:32
	ds_read_b128 v[202:205], v169 offset:4640
	s_waitcnt lgkmcnt(5)
	v_mfma_f32_32x32x16_bf16 v[80:95], v[158:161], v[224:227], v[80:95]
	v_mfma_f32_32x32x16_bf16 v[16:31], v[162:165], v[224:227], v[16:31]
	ds_read_b128 v[224:227], v168 offset:32
	s_waitcnt lgkmcnt(5)
	v_mfma_f32_32x32x16_bf16 v[64:79], v[158:161], v[228:231], v[64:79]
	v_mfma_f32_32x32x16_bf16 v[0:15], v[162:165], v[228:231], v[0:15]
	ds_read_b128 v[228:231], v168 offset:4640
	global_load_dwordx4 v[158:161], v[136:137], off offset:3712
	global_load_dwordx4 v[162:165], v[140:141], off offset:3712
	s_waitcnt lgkmcnt(1)
	v_mfma_f32_32x32x16_bf16 v[112:127], v[198:201], v[224:227], v[112:127]
	v_mfma_f32_32x32x16_bf16 v[48:63], v[202:205], v[224:227], v[48:63]
	s_waitcnt lgkmcnt(0)
	v_mfma_f32_32x32x16_bf16 v[96:111], v[198:201], v[228:231], v[96:111]
	v_mfma_f32_32x32x16_bf16 v[32:47], v[202:205], v[228:231], v[32:47]
	ds_read_b128 v[224:227], v168 offset:9248
	ds_read_b128 v[228:231], v168 offset:13856
	s_waitcnt vmcnt(7)
	ds_write_b128 v191, v[208:211] offset:18432
	s_waitcnt vmcnt(6)
	ds_write_b128 v191, v[212:215] offset:55296
	ds_read_b128 v[208:211], v169 offset:64
	ds_read_b128 v[212:215], v169 offset:4672
	s_waitcnt lgkmcnt(5)
	v_mfma_f32_32x32x16_bf16 v[80:95], v[198:201], v[224:227], v[80:95]
	v_mfma_f32_32x32x16_bf16 v[16:31], v[202:205], v[224:227], v[16:31]
	ds_read_b128 v[224:227], v168 offset:64
	s_waitcnt lgkmcnt(5)
	v_mfma_f32_32x32x16_bf16 v[64:79], v[198:201], v[228:231], v[64:79]
	v_mfma_f32_32x32x16_bf16 v[0:15], v[202:205], v[228:231], v[0:15]
	ds_read_b128 v[228:231], v168 offset:4672
	global_load_dwordx4 v[198:201], v[144:145], off offset:3712
	global_load_dwordx4 v[202:205], v[148:149], off offset:3712
	s_waitcnt lgkmcnt(1)
	v_mfma_f32_32x32x16_bf16 v[112:127], v[208:211], v[224:227], v[112:127]
	v_mfma_f32_32x32x16_bf16 v[48:63], v[212:215], v[224:227], v[48:63]
	s_waitcnt lgkmcnt(0)
	v_mfma_f32_32x32x16_bf16 v[96:111], v[208:211], v[228:231], v[96:111]
	v_mfma_f32_32x32x16_bf16 v[32:47], v[212:215], v[228:231], v[32:47]
	ds_read_b128 v[224:227], v168 offset:9280
	ds_read_b128 v[228:231], v168 offset:13888
	s_waitcnt vmcnt(7)
	ds_write_b128 v191, v[178:181] offset:27648
	s_waitcnt vmcnt(6)
	ds_write_b128 v191, v[216:219] offset:64512
	ds_read_b128 v[178:181], v169 offset:96
	ds_read_b128 v[216:219], v169 offset:4704
	s_waitcnt lgkmcnt(5)
	v_mfma_f32_32x32x16_bf16 v[80:95], v[208:211], v[224:227], v[80:95]
	v_mfma_f32_32x32x16_bf16 v[16:31], v[212:215], v[224:227], v[16:31]
	ds_read_b128 v[224:227], v168 offset:96
	s_waitcnt lgkmcnt(5)
	v_mfma_f32_32x32x16_bf16 v[64:79], v[208:211], v[228:231], v[64:79]
	v_mfma_f32_32x32x16_bf16 v[0:15], v[212:215], v[228:231], v[0:15]
	ds_read_b128 v[228:231], v168 offset:4704
	global_load_dwordx4 v[208:211], v[152:153], off offset:3712
	global_load_dwordx4 v[212:215], v[156:157], off offset:3712
	s_waitcnt lgkmcnt(1)
	v_mfma_f32_32x32x16_bf16 v[112:127], v[178:181], v[224:227], v[112:127]
	v_mfma_f32_32x32x16_bf16 v[48:63], v[216:219], v[224:227], v[48:63]
	s_waitcnt lgkmcnt(0)
	v_mfma_f32_32x32x16_bf16 v[96:111], v[178:181], v[228:231], v[96:111]
	v_mfma_f32_32x32x16_bf16 v[32:47], v[216:219], v[228:231], v[32:47]
	ds_read_b128 v[224:227], v168 offset:9312
	ds_read_b128 v[228:231], v168 offset:13920
	s_waitcnt lgkmcnt(1)
	v_mfma_f32_32x32x16_bf16 v[80:95], v[178:181], v[224:227], v[80:95]
	v_mfma_f32_32x32x16_bf16 v[16:31], v[216:219], v[224:227], v[16:31]
	s_waitcnt lgkmcnt(0)
	v_mfma_f32_32x32x16_bf16 v[64:79], v[178:181], v[228:231], v[64:79]
	v_mfma_f32_32x32x16_bf16 v[0:15], v[216:219], v[228:231], v[0:15]
	s_setprio 0
	s_barrier
; template <bool trans>
; DI void gemm_core(const GTile& tl, const GTile& nx, bool has_next  , bool chain  , bool pre, u32x4 (&ra)[4], u32x4 (&rb)[4], char* smem, f32x16 (&acc)[2][4]) {
;     ...
;   const int nk = K / 64;
;   if (!pre) { G_LOAD(0); G_STORE(0); G_LOAD(1); }
;   for (int kt = 0; kt < nk; ++kt) {
;     __syncthreads();
;     G_COMPUTE(kt & 1, kt);
	global_load_dwordx4 v[178:181], v[128:129], off offset:3840
	global_load_dwordx4 v[216:219], v[132:133], off offset:3840
	s_waitcnt vmcnt(9)
	ds_write_b128 v195, v[172:175]
	s_waitcnt vmcnt(8)
	ds_write_b128 v196, v[220:223]
	ds_read_b128 v[172:175], v192 offset:36864
	ds_read_b128 v[220:223], v192 offset:41472
	ds_read_b128 v[224:227], v184
	ds_read_b128 v[228:231], v184 offset:4608
	s_setprio 1
	s_waitcnt lgkmcnt(1)
	v_mfma_f32_32x32x16_bf16 v[112:127], v[172:175], v[224:227], v[112:127]
	v_mfma_f32_32x32x16_bf16 v[48:63], v[220:223], v[224:227], v[48:63]
	s_waitcnt lgkmcnt(0)
	v_mfma_f32_32x32x16_bf16 v[96:111], v[172:175], v[228:231], v[96:111]
	v_mfma_f32_32x32x16_bf16 v[32:47], v[220:223], v[228:231], v[32:47]
	ds_read_b128 v[224:227], v184 offset:9216
	ds_read_b128 v[228:231], v184 offset:13824
	s_waitcnt vmcnt(7)
	ds_write_b128 v194, v[158:161]
	s_waitcnt vmcnt(6)
	ds_write_b128 v193, v[162:165]
	ds_read_b128 v[158:161], v192 offset:36896
	ds_read_b128 v[162:165], v192 offset:41504
	s_waitcnt lgkmcnt(5)
	v_mfma_f32_32x32x16_bf16 v[80:95], v[172:175], v[224:227], v[80:95]
	v_mfma_f32_32x32x16_bf16 v[16:31], v[220:223], v[224:227], v[16:31]
	ds_read_b128 v[224:227], v184 offset:32
	s_waitcnt lgkmcnt(5)
	v_mfma_f32_32x32x16_bf16 v[64:79], v[172:175], v[228:231], v[64:79]
	v_mfma_f32_32x32x16_bf16 v[0:15], v[220:223], v[228:231], v[0:15]
	ds_read_b128 v[228:231], v184 offset:4640
	global_load_dwordx4 v[172:175], v[136:137], off offset:3840
	global_load_dwordx4 v[220:223], v[140:141], off offset:3840
	s_waitcnt lgkmcnt(1)
	v_mfma_f32_32x32x16_bf16 v[112:127], v[158:161], v[224:227], v[112:127]
	v_mfma_f32_32x32x16_bf16 v[48:63], v[162:165], v[224:227], v[48:63]
	s_waitcnt lgkmcnt(0)
	v_mfma_f32_32x32x16_bf16 v[96:111], v[158:161], v[228:231], v[96:111]
	v_mfma_f32_32x32x16_bf16 v[32:47], v[162:165], v[228:231], v[32:47]
	ds_read_b128 v[224:227], v184 offset:9248
	ds_read_b128 v[228:231], v184 offset:13856
	s_waitcnt vmcnt(7)
	ds_write_b128 v177, v[198:201]
	s_waitcnt vmcnt(6)
	ds_write_b128 v176, v[202:205]
	ds_read_b128 v[198:201], v192 offset:36928
	ds_read_b128 v[202:205], v192 offset:41536
	s_waitcnt lgkmcnt(5)
	v_mfma_f32_32x32x16_bf16 v[80:95], v[158:161], v[224:227], v[80:95]
	v_mfma_f32_32x32x16_bf16 v[16:31], v[162:165], v[224:227], v[16:31]
	ds_read_b128 v[224:227], v184 offset:64
	s_waitcnt lgkmcnt(5)
	v_mfma_f32_32x32x16_bf16 v[64:79], v[158:161], v[228:231], v[64:79]
	v_mfma_f32_32x32x16_bf16 v[0:15], v[162:165], v[228:231], v[0:15]
	ds_read_b128 v[228:231], v184 offset:4672
	global_load_dwordx4 v[158:161], v[144:145], off offset:3840
	global_load_dwordx4 v[162:165], v[148:149], off offset:3840
	s_waitcnt lgkmcnt(1)
	v_mfma_f32_32x32x16_bf16 v[112:127], v[198:201], v[224:227], v[112:127]
	v_mfma_f32_32x32x16_bf16 v[48:63], v[202:205], v[224:227], v[48:63]
	s_waitcnt lgkmcnt(0)
	v_mfma_f32_32x32x16_bf16 v[96:111], v[198:201], v[228:231], v[96:111]
	v_mfma_f32_32x32x16_bf16 v[32:47], v[202:205], v[228:231], v[32:47]
	ds_read_b128 v[224:227], v184 offset:9280
	ds_read_b128 v[228:231], v184 offset:13888
	s_waitcnt vmcnt(7)
	ds_write_b128 v171, v[208:211]
	s_waitcnt vmcnt(6)
	ds_write_b128 v170, v[212:215]
	ds_read_b128 v[208:211], v192 offset:36960
	ds_read_b128 v[212:215], v192 offset:41568
	s_waitcnt lgkmcnt(5)
	v_mfma_f32_32x32x16_bf16 v[80:95], v[198:201], v[224:227], v[80:95]
	v_mfma_f32_32x32x16_bf16 v[16:31], v[202:205], v[224:227], v[16:31]
	ds_read_b128 v[224:227], v184 offset:96
	s_waitcnt lgkmcnt(5)
	v_mfma_f32_32x32x16_bf16 v[64:79], v[198:201], v[228:231], v[64:79]
	v_mfma_f32_32x32x16_bf16 v[0:15], v[202:205], v[228:231], v[0:15]
	ds_read_b128 v[228:231], v184 offset:4704
	global_load_dwordx4 v[198:201], v[152:153], off offset:3840
	global_load_dwordx4 v[202:205], v[156:157], off offset:3840
	s_waitcnt lgkmcnt(1)
	v_mfma_f32_32x32x16_bf16 v[112:127], v[208:211], v[224:227], v[112:127]
	v_mfma_f32_32x32x16_bf16 v[48:63], v[212:215], v[224:227], v[48:63]
	s_waitcnt lgkmcnt(0)
	v_mfma_f32_32x32x16_bf16 v[96:111], v[208:211], v[228:231], v[96:111]
	v_mfma_f32_32x32x16_bf16 v[32:47], v[212:215], v[228:231], v[32:47]
	ds_read_b128 v[224:227], v184 offset:9312
	ds_read_b128 v[228:231], v184 offset:13920
	s_waitcnt lgkmcnt(1)
	v_mfma_f32_32x32x16_bf16 v[80:95], v[208:211], v[224:227], v[80:95]
	v_mfma_f32_32x32x16_bf16 v[16:31], v[212:215], v[224:227], v[16:31]
	s_waitcnt lgkmcnt(0)
	v_mfma_f32_32x32x16_bf16 v[64:79], v[208:211], v[228:231], v[64:79]
	v_mfma_f32_32x32x16_bf16 v[0:15], v[212:215], v[228:231], v[0:15]
	s_setprio 0
	s_barrier
; template <bool trans>
; DI void gemm_core(const GTile& tl, const GTile& nx, bool has_next  , bool chain  , bool pre, u32x4 (&ra)[4], u32x4 (&rb)[4], char* smem, f32x16 (&acc)[2][4]) {
;     ...
;   const int nk = K / 64;
;   if (!pre) { G_LOAD(0); G_STORE(0); G_LOAD(1); }
;   for (int kt = 0; kt < nk; ++kt) {
;     __syncthreads();
;     G_COMPUTE(kt & 1, kt);
;   }
	global_load_dwordx4 v[128:131], v[128:129], off offset:3968
	s_nop 0
	global_load_dwordx4 v[132:135], v[132:133], off offset:3968
	s_waitcnt vmcnt(9)
	ds_write_b128 v191, v[178:181]
	s_waitcnt vmcnt(8)
	ds_write_b128 v191, v[216:219] offset:36864
	ds_read_b128 v[178:181], v169
	ds_read_b128 v[208:211], v169 offset:4608
	ds_read_b128 v[212:215], v168
	ds_read_b128 v[216:219], v168 offset:4608
	s_setprio 1
	s_waitcnt lgkmcnt(1)
	v_mfma_f32_32x32x16_bf16 v[112:127], v[178:181], v[212:215], v[112:127]
	v_mfma_f32_32x32x16_bf16 v[48:63], v[208:211], v[212:215], v[48:63]
	s_waitcnt lgkmcnt(0)
	v_mfma_f32_32x32x16_bf16 v[96:111], v[178:181], v[216:219], v[96:111]
	v_mfma_f32_32x32x16_bf16 v[32:47], v[208:211], v[216:219], v[32:47]
	ds_read_b128 v[212:215], v168 offset:9216
	ds_read_b128 v[216:219], v168 offset:13824
	s_waitcnt lgkmcnt(1)
	v_mfma_f32_32x32x16_bf16 v[80:95], v[178:181], v[212:215], v[80:95]
	v_mfma_f32_32x32x16_bf16 v[16:31], v[208:211], v[212:215], v[16:31]
	s_waitcnt lgkmcnt(0)
	v_mfma_f32_32x32x16_bf16 v[64:79], v[178:181], v[216:219], v[64:79]
	v_mfma_f32_32x32x16_bf16 v[0:15], v[208:211], v[216:219], v[0:15]
	s_setprio 0
	global_load_dwordx4 v[136:139], v[136:137], off offset:3968
	s_nop 0
	global_load_dwordx4 v[140:143], v[140:141], off offset:3968
	s_waitcnt vmcnt(9)
	ds_write_b128 v191, v[172:175] offset:9216
	s_waitcnt vmcnt(8)
	ds_write_b128 v191, v[220:223] offset:46080
	ds_read_b128 v[172:175], v169 offset:32
	ds_read_b128 v[178:181], v169 offset:4640
	ds_read_b128 v[208:211], v168 offset:32
	ds_read_b128 v[212:215], v168 offset:4640
	s_setprio 1
	s_waitcnt lgkmcnt(1)
	v_mfma_f32_32x32x16_bf16 v[112:127], v[172:175], v[208:211], v[112:127]
	v_mfma_f32_32x32x16_bf16 v[48:63], v[178:181], v[208:211], v[48:63]
	s_waitcnt lgkmcnt(0)
	v_mfma_f32_32x32x16_bf16 v[96:111], v[172:175], v[212:215], v[96:111]
	v_mfma_f32_32x32x16_bf16 v[32:47], v[178:181], v[212:215], v[32:47]
	ds_read_b128 v[208:211], v168 offset:9248
	ds_read_b128 v[212:215], v168 offset:13856
	s_waitcnt lgkmcnt(1)
	v_mfma_f32_32x32x16_bf16 v[80:95], v[172:175], v[208:211], v[80:95]
	v_mfma_f32_32x32x16_bf16 v[16:31], v[178:181], v[208:211], v[16:31]
	s_waitcnt lgkmcnt(0)
	v_mfma_f32_32x32x16_bf16 v[64:79], v[172:175], v[212:215], v[64:79]
	v_mfma_f32_32x32x16_bf16 v[0:15], v[178:181], v[212:215], v[0:15]
	s_setprio 0
	global_load_dwordx4 v[144:147], v[144:145], off offset:3968
	s_nop 0
	global_load_dwordx4 v[148:151], v[148:149], off offset:3968
	s_waitcnt vmcnt(9)
	ds_write_b128 v191, v[158:161] offset:18432
	s_waitcnt vmcnt(8)
	ds_write_b128 v191, v[162:165] offset:55296
	ds_read_b128 v[158:161], v169 offset:64
	ds_read_b128 v[162:165], v169 offset:4672
	ds_read_b128 v[172:175], v168 offset:64
	ds_read_b128 v[178:181], v168 offset:4672
	s_setprio 1
	s_waitcnt lgkmcnt(1)
	v_mfma_f32_32x32x16_bf16 v[112:127], v[158:161], v[172:175], v[112:127]
	v_mfma_f32_32x32x16_bf16 v[48:63], v[162:165], v[172:175], v[48:63]
	s_waitcnt lgkmcnt(0)
	v_mfma_f32_32x32x16_bf16 v[96:111], v[158:161], v[178:181], v[96:111]
	v_mfma_f32_32x32x16_bf16 v[32:47], v[162:165], v[178:181], v[32:47]
	ds_read_b128 v[172:175], v168 offset:9280
	ds_read_b128 v[178:181], v168 offset:13888
	s_waitcnt lgkmcnt(1)
	v_mfma_f32_32x32x16_bf16 v[80:95], v[158:161], v[172:175], v[80:95]
	v_mfma_f32_32x32x16_bf16 v[16:31], v[162:165], v[172:175], v[16:31]
	s_waitcnt lgkmcnt(0)
	v_mfma_f32_32x32x16_bf16 v[64:79], v[158:161], v[178:181], v[64:79]
	v_mfma_f32_32x32x16_bf16 v[0:15], v[162:165], v[178:181], v[0:15]
	s_setprio 0
	global_load_dwordx4 v[152:155], v[152:153], off offset:3968
	s_nop 0
	global_load_dwordx4 v[156:159], v[156:157], off offset:3968
	s_waitcnt vmcnt(9)
	ds_write_b128 v191, v[198:201] offset:27648
	s_waitcnt vmcnt(8)
	ds_write_b128 v191, v[202:205] offset:64512
	ds_read_b128 v[160:163], v169 offset:96
	ds_read_b128 v[164:167], v169 offset:4704
	ds_read_b128 v[172:175], v168 offset:96
	ds_read_b128 v[178:181], v168 offset:4704
	s_setprio 1
	s_waitcnt lgkmcnt(1)
	v_mfma_f32_32x32x16_bf16 v[112:127], v[160:163], v[172:175], v[112:127]
	v_mfma_f32_32x32x16_bf16 v[48:63], v[164:167], v[172:175], v[48:63]
	s_waitcnt lgkmcnt(0)
	v_mfma_f32_32x32x16_bf16 v[96:111], v[160:163], v[178:181], v[96:111]
	v_mfma_f32_32x32x16_bf16 v[32:47], v[164:167], v[178:181], v[32:47]
	ds_read_b128 v[172:175], v168 offset:9312
	ds_read_b128 v[178:181], v168 offset:13920
	s_waitcnt lgkmcnt(1)
	v_mfma_f32_32x32x16_bf16 v[80:95], v[160:163], v[172:175], v[80:95]
	v_mfma_f32_32x32x16_bf16 v[16:31], v[164:167], v[172:175], v[16:31]
	s_waitcnt lgkmcnt(0)
	v_mfma_f32_32x32x16_bf16 v[64:79], v[160:163], v[178:181], v[64:79]
	v_mfma_f32_32x32x16_bf16 v[0:15], v[164:167], v[178:181], v[0:15]
	s_setprio 0
	s_and_b64 vcc, exec, s[12:13]
	s_barrier
	s_waitcnt vmcnt(7)
	ds_write_b128 v195, v[128:131]
	s_waitcnt vmcnt(6)
	ds_write_b128 v196, v[132:135]
	s_cbranch_vccnz .LBB0_751
	global_load_dwordx4 v[128:131], v[188:189], off
	global_load_dwordx4 v[132:135], v[186:187], off

; template <bool trans>
; DI void gemm_core(const GTile& tl, const GTile& nx, bool has_next  , bool chain  , bool pre, u32x4 (&ra)[4], u32x4 (&rb)[4], char* smem, f32x16 (&acc)[2][4]) {
;     ...
;   const int nk = K / 64;
;   if (!pre) { G_LOAD(0); G_STORE(0); G_LOAD(1); }
;   for (int kt = 0; kt < nk; ++kt) {
;     __syncthreads();
;     G_COMPUTE(kt & 1, kt);
;   }
.LBB0_882:
	v_lshl_add_u64 v[190:191], s[2:3], 0, v[192:193]
	v_lshl_add_u64 v[188:189], s[16:17], 0, v[192:193]
	s_waitcnt lgkmcnt(0)
	s_barrier
	global_load_dwordx4 v[218:221], v[190:191], off offset:256
	global_load_dwordx4 v[222:225], v[188:189], off offset:256
	s_lshr_b32 s3, s33, 1
	s_and_b32 s2, s33, 0xc0
	v_and_b32_e32 v10, 31, v8
	s_and_b32 s3, s3, 0xfffff80
	v_or_b32_e32 v12, s3, v10
	v_or_b32_e32 v10, s2, v10
	v_add3_u32 v215, 16, v11, v9
	v_lshrrev_b32_e32 v8, 1, v8
	v_mul_u32_u24_e32 v208, 0x90, v10
	v_and_b32_e32 v242, 16, v8
	v_add_u32_e32 v209, 0x12000, v215
	v_mul_lo_u32 v205, v12, s54
	v_add3_u32 v204, 16, v208, v242
	v_add_u32_e32 v210, 0x1b000, v215
	ds_write_b128 v209, v[0:3]
	s_waitcnt vmcnt(5)
	ds_write_b128 v210, v[4:7]
	v_add3_u32 v192, 16, v205, v242
	ds_read_b128 v[0:3], v204 offset:36864
	ds_read_b128 v[4:7], v204 offset:41472
	ds_read_b128 v[8:11], v192
	ds_read_b128 v[12:15], v192 offset:4608
	v_lshl_add_u64 v[184:185], v[190:191], 0, s[14:15]
	v_lshl_add_u64 v[186:187], v[188:189], 0, s[14:15]
	v_lshl_add_u64 v[194:195], v[190:191], 0, s[12:13]
	v_lshl_add_u64 v[196:197], v[188:189], 0, s[12:13]
	s_setprio 1
	s_waitcnt lgkmcnt(1)
	v_mfma_f32_32x32x16_bf16 v[112:127], v[8:11], v[0:3], 0
	v_mfma_f32_32x32x16_bf16 v[48:63], v[8:11], v[4:7], 0
	s_waitcnt lgkmcnt(0)
	v_mfma_f32_32x32x16_bf16 v[96:111], v[12:15], v[0:3], 0
	v_mfma_f32_32x32x16_bf16 v[32:47], v[12:15], v[4:7], 0
	ds_read_b128 v[8:11], v192 offset:9216
	ds_read_b128 v[12:15], v192 offset:13824
	s_waitcnt lgkmcnt(1)
	v_mfma_f32_32x32x16_bf16 v[80:95], v[8:11], v[0:3], 0
	v_mfma_f32_32x32x16_bf16 v[16:31], v[8:11], v[4:7], 0
	s_waitcnt lgkmcnt(0)
	v_mfma_f32_32x32x16_bf16 v[64:79], v[12:15], v[0:3], 0
	v_mfma_f32_32x32x16_bf16 v[0:15], v[12:15], v[4:7], 0
	s_setprio 0
	global_load_dwordx4 v[226:229], v[194:195], off offset:256
	global_load_dwordx4 v[230:233], v[196:197], off offset:256
	v_add_u32_e32 v212, 0x14400, v215
	v_add_u32_e32 v211, 0x1d400, v215
	ds_write_b128 v212, v[176:179]
	s_waitcnt vmcnt(6)
	ds_write_b128 v211, v[180:183]
	ds_read_b128 v[176:179], v204 offset:36896
	ds_read_b128 v[180:183], v204 offset:41504
	ds_read_b128 v[198:201], v192 offset:32
	ds_read_b128 v[234:237], v192 offset:4640
	s_setprio 1
	s_waitcnt lgkmcnt(1)
	v_mfma_f32_32x32x16_bf16 v[112:127], v[198:201], v[176:179], v[112:127]
	v_mfma_f32_32x32x16_bf16 v[48:63], v[198:201], v[180:183], v[48:63]
	s_waitcnt lgkmcnt(0)
	v_mfma_f32_32x32x16_bf16 v[96:111], v[234:237], v[176:179], v[96:111]
	v_mfma_f32_32x32x16_bf16 v[32:47], v[234:237], v[180:183], v[32:47]
	ds_read_b128 v[198:201], v192 offset:9248
	ds_read_b128 v[234:237], v192 offset:13856
	s_waitcnt lgkmcnt(1)
	v_mfma_f32_32x32x16_bf16 v[80:95], v[198:201], v[176:179], v[80:95]
	v_mfma_f32_32x32x16_bf16 v[16:31], v[198:201], v[180:183], v[16:31]
	s_waitcnt lgkmcnt(0)
	v_mfma_f32_32x32x16_bf16 v[64:79], v[234:237], v[176:179], v[64:79]
	v_mfma_f32_32x32x16_bf16 v[0:15], v[234:237], v[180:183], v[0:15]
	s_setprio 0
	global_load_dwordx4 v[176:179], v[184:185], off offset:256
	global_load_dwordx4 v[180:183], v[186:187], off offset:256
	v_add_u32_e32 v214, 0x16800, v215
	v_add_u32_e32 v213, 0x1f800, v215
	ds_write_b128 v214, v[168:171]
	s_waitcnt vmcnt(7)
	ds_write_b128 v213, v[172:175]
	ds_read_b128 v[168:171], v204 offset:36928
	ds_read_b128 v[172:175], v204 offset:41536
	ds_read_b128 v[198:201], v192 offset:64
	ds_read_b128 v[234:237], v192 offset:4672
	s_setprio 1
	s_waitcnt lgkmcnt(1)
	v_mfma_f32_32x32x16_bf16 v[112:127], v[198:201], v[168:171], v[112:127]
	v_mfma_f32_32x32x16_bf16 v[48:63], v[198:201], v[172:175], v[48:63]
	s_waitcnt lgkmcnt(0)
	v_mfma_f32_32x32x16_bf16 v[96:111], v[234:237], v[168:171], v[96:111]
	v_mfma_f32_32x32x16_bf16 v[32:47], v[234:237], v[172:175], v[32:47]
	ds_read_b128 v[198:201], v192 offset:9280
	ds_read_b128 v[234:237], v192 offset:13888
	s_waitcnt lgkmcnt(1)
	v_mfma_f32_32x32x16_bf16 v[80:95], v[198:201], v[168:171], v[80:95]
	v_mfma_f32_32x32x16_bf16 v[16:31], v[198:201], v[172:175], v[16:31]
	s_waitcnt lgkmcnt(0)
	v_mfma_f32_32x32x16_bf16 v[64:79], v[234:237], v[168:171], v[64:79]
	v_mfma_f32_32x32x16_bf16 v[0:15], v[234:237], v[172:175], v[0:15]
	s_setprio 0
	v_add_co_u32_e32 v198, vcc, s53, v190
	v_add_u32_e32 v217, 0x18c00, v215
	s_nop 0
	v_addc_co_u32_e32 v199, vcc, 0, v191, vcc
	v_add_co_u32_e32 v200, vcc, s53, v188
	v_add_u32_e32 v216, 0x21c00, v215
	s_nop 0
	v_addc_co_u32_e32 v201, vcc, 0, v189, vcc
	global_load_dwordx4 v[168:171], v[198:199], off offset:256
	global_load_dwordx4 v[172:175], v[200:201], off offset:256
	ds_write_b128 v217, v[160:163]
	s_waitcnt vmcnt(8)
	ds_write_b128 v216, v[164:167]
	ds_read_b128 v[160:163], v204 offset:36960
	ds_read_b128 v[164:167], v204 offset:41568
	ds_read_b128 v[234:237], v192 offset:96
	ds_read_b128 v[238:241], v192 offset:4704
	s_setprio 1
	s_waitcnt lgkmcnt(1)
	v_mfma_f32_32x32x16_bf16 v[112:127], v[234:237], v[160:163], v[112:127]
	v_mfma_f32_32x32x16_bf16 v[48:63], v[234:237], v[164:167], v[48:63]
	s_waitcnt lgkmcnt(0)
	v_mfma_f32_32x32x16_bf16 v[96:111], v[238:241], v[160:163], v[96:111]
	v_mfma_f32_32x32x16_bf16 v[32:47], v[238:241], v[164:167], v[32:47]
	ds_read_b128 v[234:237], v192 offset:9312
	ds_read_b128 v[238:241], v192 offset:13920
	s_waitcnt lgkmcnt(1)
	v_mfma_f32_32x32x16_bf16 v[80:95], v[234:237], v[160:163], v[80:95]
	v_mfma_f32_32x32x16_bf16 v[16:31], v[234:237], v[164:167], v[16:31]
	s_waitcnt lgkmcnt(0)
	v_mfma_f32_32x32x16_bf16 v[64:79], v[238:241], v[160:163], v[64:79]
	v_mfma_f32_32x32x16_bf16 v[0:15], v[238:241], v[164:167], v[0:15]
	s_setprio 0
	s_barrier
; template <bool trans>
; DI void gemm_core(const GTile& tl, const GTile& nx, bool has_next  , bool chain  , bool pre, u32x4 (&ra)[4], u32x4 (&rb)[4], char* smem, f32x16 (&acc)[2][4]) {
;     ...
;   const int nk = K / 64;
;   if (!pre) { G_LOAD(0); G_STORE(0); G_LOAD(1); }
;   for (int kt = 0; kt < nk; ++kt) {
;     __syncthreads();
;     G_COMPUTE(kt & 1, kt);
;   }
	global_load_dwordx4 v[160:163], v[190:191], off offset:384
	global_load_dwordx4 v[164:167], v[188:189], off offset:384
	s_add_i32 s2, 16, 0x12000
	v_add3_u32 v205, s2, v205, v242
	s_add_i32 s2, 16, 0x1b000
	v_add3_u32 v208, s2, v208, v242
	s_waitcnt vmcnt(9)
	ds_write_b128 v215, v[218:221]
	s_waitcnt vmcnt(8)
	ds_write_b128 v215, v[222:225] offset:36864
	ds_read_b128 v[218:221], v208
	ds_read_b128 v[222:225], v208 offset:4608
	ds_read_b128 v[234:237], v205
	ds_read_b128 v[238:241], v205 offset:4608
	s_setprio 1
	s_waitcnt lgkmcnt(1)
	v_mfma_f32_32x32x16_bf16 v[112:127], v[234:237], v[218:221], v[112:127]
	v_mfma_f32_32x32x16_bf16 v[48:63], v[234:237], v[222:225], v[48:63]
	s_waitcnt lgkmcnt(0)
	v_mfma_f32_32x32x16_bf16 v[96:111], v[238:241], v[218:221], v[96:111]
	v_mfma_f32_32x32x16_bf16 v[32:47], v[238:241], v[222:225], v[32:47]
	ds_read_b128 v[234:237], v205 offset:9216
	ds_read_b128 v[238:241], v205 offset:13824
	s_waitcnt lgkmcnt(1)
	v_mfma_f32_32x32x16_bf16 v[80:95], v[234:237], v[218:221], v[80:95]
	v_mfma_f32_32x32x16_bf16 v[16:31], v[234:237], v[222:225], v[16:31]
	s_waitcnt lgkmcnt(0)
	v_mfma_f32_32x32x16_bf16 v[64:79], v[238:241], v[218:221], v[64:79]
	v_mfma_f32_32x32x16_bf16 v[0:15], v[238:241], v[222:225], v[0:15]
	s_setprio 0
	global_load_dwordx4 v[218:221], v[194:195], off offset:384
	global_load_dwordx4 v[222:225], v[196:197], off offset:384
	s_waitcnt vmcnt(9)
	ds_write_b128 v215, v[226:229] offset:9216
	s_waitcnt vmcnt(8)
	ds_write_b128 v215, v[230:233] offset:46080
	ds_read_b128 v[226:229], v208 offset:32
	ds_read_b128 v[230:233], v208 offset:4640
	ds_read_b128 v[234:237], v205 offset:32
	ds_read_b128 v[238:241], v205 offset:4640
	s_setprio 1
	s_waitcnt lgkmcnt(1)
	v_mfma_f32_32x32x16_bf16 v[112:127], v[234:237], v[226:229], v[112:127]
	v_mfma_f32_32x32x16_bf16 v[48:63], v[234:237], v[230:233], v[48:63]
	s_waitcnt lgkmcnt(0)
	v_mfma_f32_32x32x16_bf16 v[96:111], v[238:241], v[226:229], v[96:111]
	v_mfma_f32_32x32x16_bf16 v[32:47], v[238:241], v[230:233], v[32:47]
	ds_read_b128 v[234:237], v205 offset:9248
	ds_read_b128 v[238:241], v205 offset:13856
	s_waitcnt lgkmcnt(1)
	v_mfma_f32_32x32x16_bf16 v[80:95], v[234:237], v[226:229], v[80:95]
	v_mfma_f32_32x32x16_bf16 v[16:31], v[234:237], v[230:233], v[16:31]
	s_waitcnt lgkmcnt(0)
	v_mfma_f32_32x32x16_bf16 v[64:79], v[238:241], v[226:229], v[64:79]
	v_mfma_f32_32x32x16_bf16 v[0:15], v[238:241], v[230:233], v[0:15]
	s_setprio 0
	global_load_dwordx4 v[226:229], v[184:185], off offset:384
	global_load_dwordx4 v[230:233], v[186:187], off offset:384
	s_waitcnt vmcnt(9)
	ds_write_b128 v215, v[176:179] offset:18432
	s_waitcnt vmcnt(8)
	ds_write_b128 v215, v[180:183] offset:55296
	ds_read_b128 v[176:179], v208 offset:64
	ds_read_b128 v[180:183], v208 offset:4672
	ds_read_b128 v[234:237], v205 offset:64
	ds_read_b128 v[238:241], v205 offset:4672
	s_setprio 1
	s_waitcnt lgkmcnt(1)
	v_mfma_f32_32x32x16_bf16 v[112:127], v[234:237], v[176:179], v[112:127]
	v_mfma_f32_32x32x16_bf16 v[48:63], v[234:237], v[180:183], v[48:63]
	s_waitcnt lgkmcnt(0)
	v_mfma_f32_32x32x16_bf16 v[96:111], v[238:241], v[176:179], v[96:111]
	v_mfma_f32_32x32x16_bf16 v[32:47], v[238:241], v[180:183], v[32:47]
	ds_read_b128 v[234:237], v205 offset:9280
	ds_read_b128 v[238:241], v205 offset:13888
	s_waitcnt lgkmcnt(1)
	v_mfma_f32_32x32x16_bf16 v[80:95], v[234:237], v[176:179], v[80:95]
	v_mfma_f32_32x32x16_bf16 v[16:31], v[234:237], v[180:183], v[16:31]
	s_waitcnt lgkmcnt(0)
	v_mfma_f32_32x32x16_bf16 v[64:79], v[238:241], v[176:179], v[64:79]
	v_mfma_f32_32x32x16_bf16 v[0:15], v[238:241], v[180:183], v[0:15]
	s_setprio 0
	global_load_dwordx4 v[176:179], v[198:199], off offset:384
	global_load_dwordx4 v[180:183], v[200:201], off offset:384
	s_waitcnt vmcnt(9)
	ds_write_b128 v215, v[168:171] offset:27648
	s_waitcnt vmcnt(8)
	ds_write_b128 v215, v[172:175] offset:64512
	ds_read_b128 v[168:171], v208 offset:96
	ds_read_b128 v[172:175], v208 offset:4704
	ds_read_b128 v[234:237], v205 offset:96
	ds_read_b128 v[238:241], v205 offset:4704
	s_setprio 1
	s_waitcnt lgkmcnt(1)
	v_mfma_f32_32x32x16_bf16 v[112:127], v[234:237], v[168:171], v[112:127]
	v_mfma_f32_32x32x16_bf16 v[48:63], v[234:237], v[172:175], v[48:63]
	s_waitcnt lgkmcnt(0)
	v_mfma_f32_32x32x16_bf16 v[96:111], v[238:241], v[168:171], v[96:111]
	v_mfma_f32_32x32x16_bf16 v[32:47], v[238:241], v[172:175], v[32:47]
	ds_read_b128 v[234:237], v205 offset:9312
	ds_read_b128 v[238:241], v205 offset:13920
	s_waitcnt lgkmcnt(1)
	v_mfma_f32_32x32x16_bf16 v[80:95], v[234:237], v[168:171], v[80:95]
	v_mfma_f32_32x32x16_bf16 v[16:31], v[234:237], v[172:175], v[16:31]
	s_waitcnt lgkmcnt(0)
	v_mfma_f32_32x32x16_bf16 v[64:79], v[238:241], v[168:171], v[64:79]
	v_mfma_f32_32x32x16_bf16 v[0:15], v[238:241], v[172:175], v[0:15]
	s_setprio 0
	s_barrier
; template <bool trans>
; DI void gemm_core(const GTile& tl, const GTile& nx, bool has_next  , bool chain  , bool pre, u32x4 (&ra)[4], u32x4 (&rb)[4], char* smem, f32x16 (&acc)[2][4]) {
;     ...
;   const int nk = K / 64;
;   if (!pre) { G_LOAD(0); G_STORE(0); G_LOAD(1); }
;   for (int kt = 0; kt < nk; ++kt) {
;     __syncthreads();
;     G_COMPUTE(kt & 1, kt);
;   }
	global_load_dwordx4 v[168:171], v[190:191], off offset:512
	global_load_dwordx4 v[172:175], v[188:189], off offset:512
	s_waitcnt vmcnt(9)
	ds_write_b128 v209, v[160:163]
	s_waitcnt vmcnt(8)
	ds_write_b128 v210, v[164:167]
	ds_read_b128 v[160:163], v204 offset:36864
	ds_read_b128 v[164:167], v204 offset:41472
	ds_read_b128 v[234:237], v192
	ds_read_b128 v[238:241], v192 offset:4608
	s_setprio 1
	s_waitcnt lgkmcnt(1)
	v_mfma_f32_32x32x16_bf16 v[112:127], v[234:237], v[160:163], v[112:127]
	v_mfma_f32_32x32x16_bf16 v[48:63], v[234:237], v[164:167], v[48:63]
	s_waitcnt lgkmcnt(0)
	v_mfma_f32_32x32x16_bf16 v[96:111], v[238:241], v[160:163], v[96:111]
	v_mfma_f32_32x32x16_bf16 v[32:47], v[238:241], v[164:167], v[32:47]
	ds_read_b128 v[234:237], v192 offset:9216
	ds_read_b128 v[238:241], v192 offset:13824
	s_waitcnt vmcnt(7)
	ds_write_b128 v212, v[218:221]
	s_waitcnt vmcnt(6)
	ds_write_b128 v211, v[222:225]
	ds_read_b128 v[218:221], v204 offset:36896
	ds_read_b128 v[222:225], v204 offset:41504
	s_waitcnt lgkmcnt(5)
	v_mfma_f32_32x32x16_bf16 v[80:95], v[234:237], v[160:163], v[80:95]
	v_mfma_f32_32x32x16_bf16 v[16:31], v[234:237], v[164:167], v[16:31]
	ds_read_b128 v[234:237], v192 offset:32
	s_waitcnt lgkmcnt(5)
	v_mfma_f32_32x32x16_bf16 v[64:79], v[238:241], v[160:163], v[64:79]
	v_mfma_f32_32x32x16_bf16 v[0:15], v[238:241], v[164:167], v[0:15]
	ds_read_b128 v[238:241], v192 offset:4640
	global_load_dwordx4 v[160:163], v[194:195], off offset:512
	global_load_dwordx4 v[164:167], v[196:197], off offset:512
	s_waitcnt lgkmcnt(1)
	v_mfma_f32_32x32x16_bf16 v[112:127], v[234:237], v[218:221], v[112:127]
	v_mfma_f32_32x32x16_bf16 v[48:63], v[234:237], v[222:225], v[48:63]
	s_waitcnt lgkmcnt(0)
	v_mfma_f32_32x32x16_bf16 v[96:111], v[238:241], v[218:221], v[96:111]
	v_mfma_f32_32x32x16_bf16 v[32:47], v[238:241], v[222:225], v[32:47]
	ds_read_b128 v[234:237], v192 offset:9248
	ds_read_b128 v[238:241], v192 offset:13856
	s_waitcnt vmcnt(7)
	ds_write_b128 v214, v[226:229]
	s_waitcnt vmcnt(6)
	ds_write_b128 v213, v[230:233]
	ds_read_b128 v[226:229], v204 offset:36928
	ds_read_b128 v[230:233], v204 offset:41536
	s_waitcnt lgkmcnt(5)
	v_mfma_f32_32x32x16_bf16 v[80:95], v[234:237], v[218:221], v[80:95]
	v_mfma_f32_32x32x16_bf16 v[16:31], v[234:237], v[222:225], v[16:31]
	ds_read_b128 v[234:237], v192 offset:64
	s_waitcnt lgkmcnt(5)
	v_mfma_f32_32x32x16_bf16 v[64:79], v[238:241], v[218:221], v[64:79]
	v_mfma_f32_32x32x16_bf16 v[0:15], v[238:241], v[222:225], v[0:15]
	ds_read_b128 v[238:241], v192 offset:4672
	global_load_dwordx4 v[218:221], v[184:185], off offset:512
	global_load_dwordx4 v[222:225], v[186:187], off offset:512
	s_waitcnt lgkmcnt(1)
	v_mfma_f32_32x32x16_bf16 v[112:127], v[234:237], v[226:229], v[112:127]
	v_mfma_f32_32x32x16_bf16 v[48:63], v[234:237], v[230:233], v[48:63]
	s_waitcnt lgkmcnt(0)
	v_mfma_f32_32x32x16_bf16 v[96:111], v[238:241], v[226:229], v[96:111]
	v_mfma_f32_32x32x16_bf16 v[32:47], v[238:241], v[230:233], v[32:47]
	ds_read_b128 v[234:237], v192 offset:9280
	ds_read_b128 v[238:241], v192 offset:13888
	s_waitcnt vmcnt(7)
	ds_write_b128 v217, v[176:179]
	s_waitcnt vmcnt(6)
	ds_write_b128 v216, v[180:183]
	ds_read_b128 v[176:179], v204 offset:36960
	ds_read_b128 v[180:183], v204 offset:41568
	s_waitcnt lgkmcnt(5)
	v_mfma_f32_32x32x16_bf16 v[80:95], v[234:237], v[226:229], v[80:95]
	v_mfma_f32_32x32x16_bf16 v[16:31], v[234:237], v[230:233], v[16:31]
	ds_read_b128 v[234:237], v192 offset:96
	s_waitcnt lgkmcnt(5)
	v_mfma_f32_32x32x16_bf16 v[64:79], v[238:241], v[226:229], v[64:79]
	v_mfma_f32_32x32x16_bf16 v[0:15], v[238:241], v[230:233], v[0:15]
	ds_read_b128 v[238:241], v192 offset:4704
	global_load_dwordx4 v[226:229], v[198:199], off offset:512
	global_load_dwordx4 v[230:233], v[200:201], off offset:512
	s_waitcnt lgkmcnt(1)
	v_mfma_f32_32x32x16_bf16 v[112:127], v[234:237], v[176:179], v[112:127]
	v_mfma_f32_32x32x16_bf16 v[48:63], v[234:237], v[180:183], v[48:63]
	s_waitcnt lgkmcnt(0)
	v_mfma_f32_32x32x16_bf16 v[96:111], v[238:241], v[176:179], v[96:111]
	v_mfma_f32_32x32x16_bf16 v[32:47], v[238:241], v[180:183], v[32:47]
	ds_read_b128 v[234:237], v192 offset:9312
	ds_read_b128 v[238:241], v192 offset:13920
	s_waitcnt lgkmcnt(1)
	v_mfma_f32_32x32x16_bf16 v[80:95], v[234:237], v[176:179], v[80:95]
	v_mfma_f32_32x32x16_bf16 v[16:31], v[234:237], v[180:183], v[16:31]
	s_waitcnt lgkmcnt(0)
	v_mfma_f32_32x32x16_bf16 v[64:79], v[238:241], v[176:179], v[64:79]
	v_mfma_f32_32x32x16_bf16 v[0:15], v[238:241], v[180:183], v[0:15]
	s_setprio 0
	s_barrier
; template <bool trans>
; DI void gemm_core(const GTile& tl, const GTile& nx, bool has_next  , bool chain  , bool pre, u32x4 (&ra)[4], u32x4 (&rb)[4], char* smem, f32x16 (&acc)[2][4]) {
;     ...
;   const int nk = K / 64;
;   if (!pre) { G_LOAD(0); G_STORE(0); G_LOAD(1); }
;   for (int kt = 0; kt < nk; ++kt) {
;     __syncthreads();
;     G_COMPUTE(kt & 1, kt);
;   }
	global_load_dwordx4 v[176:179], v[190:191], off offset:640
	global_load_dwordx4 v[180:183], v[188:189], off offset:640
	s_waitcnt vmcnt(9)
	ds_write_b128 v215, v[168:171]
	s_waitcnt vmcnt(8)
	ds_write_b128 v215, v[172:175] offset:36864
	ds_read_b128 v[168:171], v208
	ds_read_b128 v[172:175], v208 offset:4608
	ds_read_b128 v[234:237], v205
	ds_read_b128 v[238:241], v205 offset:4608
	s_setprio 1
	s_waitcnt lgkmcnt(1)
	v_mfma_f32_32x32x16_bf16 v[112:127], v[234:237], v[168:171], v[112:127]
	v_mfma_f32_32x32x16_bf16 v[48:63], v[234:237], v[172:175], v[48:63]
	s_waitcnt lgkmcnt(0)
	v_mfma_f32_32x32x16_bf16 v[96:111], v[238:241], v[168:171], v[96:111]
	v_mfma_f32_32x32x16_bf16 v[32:47], v[238:241], v[172:175], v[32:47]
	ds_read_b128 v[234:237], v205 offset:9216
	ds_read_b128 v[238:241], v205 offset:13824
	s_waitcnt vmcnt(7)
	ds_write_b128 v215, v[160:163] offset:9216
	s_waitcnt vmcnt(6)
	ds_write_b128 v215, v[164:167] offset:46080
	ds_read_b128 v[160:163], v208 offset:32
	ds_read_b128 v[164:167], v208 offset:4640
	s_waitcnt lgkmcnt(5)
	v_mfma_f32_32x32x16_bf16 v[80:95], v[234:237], v[168:171], v[80:95]
	v_mfma_f32_32x32x16_bf16 v[16:31], v[234:237], v[172:175], v[16:31]
	ds_read_b128 v[234:237], v205 offset:32
	s_waitcnt lgkmcnt(5)
	v_mfma_f32_32x32x16_bf16 v[64:79], v[238:241], v[168:171], v[64:79]
	v_mfma_f32_32x32x16_bf16 v[0:15], v[238:241], v[172:175], v[0:15]
	ds_read_b128 v[238:241], v205 offset:4640
	global_load_dwordx4 v[168:171], v[194:195], off offset:640
	global_load_dwordx4 v[172:175], v[196:197], off offset:640
	s_waitcnt lgkmcnt(1)
	v_mfma_f32_32x32x16_bf16 v[112:127], v[234:237], v[160:163], v[112:127]
	v_mfma_f32_32x32x16_bf16 v[48:63], v[234:237], v[164:167], v[48:63]
	s_waitcnt lgkmcnt(0)
	v_mfma_f32_32x32x16_bf16 v[96:111], v[238:241], v[160:163], v[96:111]
	v_mfma_f32_32x32x16_bf16 v[32:47], v[238:241], v[164:167], v[32:47]
	ds_read_b128 v[234:237], v205 offset:9248
	ds_read_b128 v[238:241], v205 offset:13856
	s_waitcnt vmcnt(7)
	ds_write_b128 v215, v[218:221] offset:18432
	s_waitcnt vmcnt(6)
	ds_write_b128 v215, v[222:225] offset:55296
	ds_read_b128 v[218:221], v208 offset:64
	ds_read_b128 v[222:225], v208 offset:4672
	s_waitcnt lgkmcnt(5)
	v_mfma_f32_32x32x16_bf16 v[80:95], v[234:237], v[160:163], v[80:95]
	v_mfma_f32_32x32x16_bf16 v[16:31], v[234:237], v[164:167], v[16:31]
	ds_read_b128 v[234:237], v205 offset:64
	s_waitcnt lgkmcnt(5)
	v_mfma_f32_32x32x16_bf16 v[64:79], v[238:241], v[160:163], v[64:79]
	v_mfma_f32_32x32x16_bf16 v[0:15], v[238:241], v[164:167], v[0:15]
	ds_read_b128 v[238:241], v205 offset:4672
	global_load_dwordx4 v[160:163], v[184:185], off offset:640
	global_load_dwordx4 v[164:167], v[186:187], off offset:640
	s_waitcnt lgkmcnt(1)
	v_mfma_f32_32x32x16_bf16 v[112:127], v[234:237], v[218:221], v[112:127]
	v_mfma_f32_32x32x16_bf16 v[48:63], v[234:237], v[222:225], v[48:63]
	s_waitcnt lgkmcnt(0)
	v_mfma_f32_32x32x16_bf16 v[96:111], v[238:241], v[218:221], v[96:111]
	v_mfma_f32_32x32x16_bf16 v[32:47], v[238:241], v[222:225], v[32:47]
	ds_read_b128 v[234:237], v205 offset:9280
	ds_read_b128 v[238:241], v205 offset:13888
	s_waitcnt vmcnt(7)
	ds_write_b128 v215, v[226:229] offset:27648
	s_waitcnt vmcnt(6)
	ds_write_b128 v215, v[230:233] offset:64512
	ds_read_b128 v[226:229], v208 offset:96
	ds_read_b128 v[230:233], v208 offset:4704
	s_waitcnt lgkmcnt(5)
	v_mfma_f32_32x32x16_bf16 v[80:95], v[234:237], v[218:221], v[80:95]
	v_mfma_f32_32x32x16_bf16 v[16:31], v[234:237], v[222:225], v[16:31]
	ds_read_b128 v[234:237], v205 offset:96
	s_waitcnt lgkmcnt(5)
	v_mfma_f32_32x32x16_bf16 v[64:79], v[238:241], v[218:221], v[64:79]
	v_mfma_f32_32x32x16_bf16 v[0:15], v[238:241], v[222:225], v[0:15]
	ds_read_b128 v[238:241], v205 offset:4704
	global_load_dwordx4 v[218:221], v[198:199], off offset:640
	global_load_dwordx4 v[222:225], v[200:201], off offset:640
	s_waitcnt lgkmcnt(1)
	v_mfma_f32_32x32x16_bf16 v[112:127], v[234:237], v[226:229], v[112:127]
	v_mfma_f32_32x32x16_bf16 v[48:63], v[234:237], v[230:233], v[48:63]
	s_waitcnt lgkmcnt(0)
	v_mfma_f32_32x32x16_bf16 v[96:111], v[238:241], v[226:229], v[96:111]
	v_mfma_f32_32x32x16_bf16 v[32:47], v[238:241], v[230:233], v[32:47]
	ds_read_b128 v[234:237], v205 offset:9312
	ds_read_b128 v[238:241], v205 offset:13920
	s_waitcnt lgkmcnt(1)
	v_mfma_f32_32x32x16_bf16 v[80:95], v[234:237], v[226:229], v[80:95]
	v_mfma_f32_32x32x16_bf16 v[16:31], v[234:237], v[230:233], v[16:31]
	s_waitcnt lgkmcnt(0)
	v_mfma_f32_32x32x16_bf16 v[64:79], v[238:241], v[226:229], v[64:79]
	v_mfma_f32_32x32x16_bf16 v[0:15], v[238:241], v[230:233], v[0:15]
	s_setprio 0
	s_barrier
; template <bool trans>
; DI void gemm_core(const GTile& tl, const GTile& nx, bool has_next  , bool chain  , bool pre, u32x4 (&ra)[4], u32x4 (&rb)[4], char* smem, f32x16 (&acc)[2][4]) {
;     ...
;   const int nk = K / 64;
;   if (!pre) { G_LOAD(0); G_STORE(0); G_LOAD(1); }
;   for (int kt = 0; kt < nk; ++kt) {
;     __syncthreads();
;     G_COMPUTE(kt & 1, kt);
;   }
	global_load_dwordx4 v[226:229], v[190:191], off offset:768
	global_load_dwordx4 v[230:233], v[188:189], off offset:768
	s_waitcnt vmcnt(9)
	ds_write_b128 v209, v[176:179]
	s_waitcnt vmcnt(8)
	ds_write_b128 v210, v[180:183]
	ds_read_b128 v[176:179], v204 offset:36864
	ds_read_b128 v[180:183], v204 offset:41472
	ds_read_b128 v[234:237], v192
	ds_read_b128 v[238:241], v192 offset:4608
	s_setprio 1
	s_waitcnt lgkmcnt(1)
	v_mfma_f32_32x32x16_bf16 v[112:127], v[234:237], v[176:179], v[112:127]
	v_mfma_f32_32x32x16_bf16 v[48:63], v[234:237], v[180:183], v[48:63]
	s_waitcnt lgkmcnt(0)
	v_mfma_f32_32x32x16_bf16 v[96:111], v[238:241], v[176:179], v[96:111]
	v_mfma_f32_32x32x16_bf16 v[32:47], v[238:241], v[180:183], v[32:47]
	ds_read_b128 v[234:237], v192 offset:9216
	ds_read_b128 v[238:241], v192 offset:13824
	s_waitcnt vmcnt(7)
	ds_write_b128 v212, v[168:171]
	s_waitcnt vmcnt(6)
	ds_write_b128 v211, v[172:175]
	ds_read_b128 v[168:171], v204 offset:36896
	ds_read_b128 v[172:175], v204 offset:41504
	s_waitcnt lgkmcnt(5)
	v_mfma_f32_32x32x16_bf16 v[80:95], v[234:237], v[176:179], v[80:95]
	v_mfma_f32_32x32x16_bf16 v[16:31], v[234:237], v[180:183], v[16:31]
	ds_read_b128 v[234:237], v192 offset:32
	s_waitcnt lgkmcnt(5)
	v_mfma_f32_32x32x16_bf16 v[64:79], v[238:241], v[176:179], v[64:79]
	v_mfma_f32_32x32x16_bf16 v[0:15], v[238:241], v[180:183], v[0:15]
	ds_read_b128 v[238:241], v192 offset:4640
	global_load_dwordx4 v[176:179], v[194:195], off offset:768
	global_load_dwordx4 v[180:183], v[196:197], off offset:768
	s_waitcnt lgkmcnt(1)
	v_mfma_f32_32x32x16_bf16 v[112:127], v[234:237], v[168:171], v[112:127]
	v_mfma_f32_32x32x16_bf16 v[48:63], v[234:237], v[172:175], v[48:63]
	s_waitcnt lgkmcnt(0)
	v_mfma_f32_32x32x16_bf16 v[96:111], v[238:241], v[168:171], v[96:111]
	v_mfma_f32_32x32x16_bf16 v[32:47], v[238:241], v[172:175], v[32:47]
	ds_read_b128 v[234:237], v192 offset:9248
	ds_read_b128 v[238:241], v192 offset:13856
	s_waitcnt vmcnt(7)
	ds_write_b128 v214, v[160:163]
	s_waitcnt vmcnt(6)
	ds_write_b128 v213, v[164:167]
	ds_read_b128 v[160:163], v204 offset:36928
	ds_read_b128 v[164:167], v204 offset:41536
	s_waitcnt lgkmcnt(5)
	v_mfma_f32_32x32x16_bf16 v[80:95], v[234:237], v[168:171], v[80:95]
	v_mfma_f32_32x32x16_bf16 v[16:31], v[234:237], v[172:175], v[16:31]
	ds_read_b128 v[234:237], v192 offset:64
	s_waitcnt lgkmcnt(5)
	v_mfma_f32_32x32x16_bf16 v[64:79], v[238:241], v[168:171], v[64:79]
	v_mfma_f32_32x32x16_bf16 v[0:15], v[238:241], v[172:175], v[0:15]
	ds_read_b128 v[238:241], v192 offset:4672
	global_load_dwordx4 v[168:171], v[184:185], off offset:768
	global_load_dwordx4 v[172:175], v[186:187], off offset:768
	s_waitcnt lgkmcnt(1)
	v_mfma_f32_32x32x16_bf16 v[112:127], v[234:237], v[160:163], v[112:127]
	v_mfma_f32_32x32x16_bf16 v[48:63], v[234:237], v[164:167], v[48:63]
	s_waitcnt lgkmcnt(0)
	v_mfma_f32_32x32x16_bf16 v[96:111], v[238:241], v[160:163], v[96:111]
	v_mfma_f32_32x32x16_bf16 v[32:47], v[238:241], v[164:167], v[32:47]
	ds_read_b128 v[234:237], v192 offset:9280
	ds_read_b128 v[238:241], v192 offset:13888
	s_waitcnt vmcnt(7)
	ds_write_b128 v217, v[218:221]
	s_waitcnt vmcnt(6)
	ds_write_b128 v216, v[222:225]
	ds_read_b128 v[218:221], v204 offset:36960
	ds_read_b128 v[222:225], v204 offset:41568
	s_waitcnt lgkmcnt(5)
	v_mfma_f32_32x32x16_bf16 v[80:95], v[234:237], v[160:163], v[80:95]
	v_mfma_f32_32x32x16_bf16 v[16:31], v[234:237], v[164:167], v[16:31]
	ds_read_b128 v[234:237], v192 offset:96
	s_waitcnt lgkmcnt(5)
	v_mfma_f32_32x32x16_bf16 v[64:79], v[238:241], v[160:163], v[64:79]
	v_mfma_f32_32x32x16_bf16 v[0:15], v[238:241], v[164:167], v[0:15]
	ds_read_b128 v[238:241], v192 offset:4704
	global_load_dwordx4 v[160:163], v[198:199], off offset:768
	global_load_dwordx4 v[164:167], v[200:201], off offset:768
	s_waitcnt lgkmcnt(1)
	v_mfma_f32_32x32x16_bf16 v[112:127], v[234:237], v[218:221], v[112:127]
	v_mfma_f32_32x32x16_bf16 v[48:63], v[234:237], v[222:225], v[48:63]
	s_waitcnt lgkmcnt(0)
	v_mfma_f32_32x32x16_bf16 v[96:111], v[238:241], v[218:221], v[96:111]
	v_mfma_f32_32x32x16_bf16 v[32:47], v[238:241], v[222:225], v[32:47]
	ds_read_b128 v[234:237], v192 offset:9312
	ds_read_b128 v[238:241], v192 offset:13920
	s_waitcnt lgkmcnt(1)
	v_mfma_f32_32x32x16_bf16 v[80:95], v[234:237], v[218:221], v[80:95]
	v_mfma_f32_32x32x16_bf16 v[16:31], v[234:237], v[222:225], v[16:31]
	s_waitcnt lgkmcnt(0)
	v_mfma_f32_32x32x16_bf16 v[64:79], v[238:241], v[218:221], v[64:79]
	v_mfma_f32_32x32x16_bf16 v[0:15], v[238:241], v[222:225], v[0:15]
	s_setprio 0
	s_barrier
; template <bool trans>
; DI void gemm_core(const GTile& tl, const GTile& nx, bool has_next  , bool chain  , bool pre, u32x4 (&ra)[4], u32x4 (&rb)[4], char* smem, f32x16 (&acc)[2][4]) {
;     ...
;   const int nk = K / 64;
;   if (!pre) { G_LOAD(0); G_STORE(0); G_LOAD(1); }
;   for (int kt = 0; kt < nk; ++kt) {
;     __syncthreads();
;     G_COMPUTE(kt & 1, kt);
;   }
	global_load_dwordx4 v[218:221], v[190:191], off offset:896
	global_load_dwordx4 v[222:225], v[188:189], off offset:896
	s_waitcnt vmcnt(9)
	ds_write_b128 v215, v[226:229]
	s_waitcnt vmcnt(8)
	ds_write_b128 v215, v[230:233] offset:36864
	ds_read_b128 v[226:229], v208
	ds_read_b128 v[230:233], v208 offset:4608
	ds_read_b128 v[234:237], v205
	ds_read_b128 v[238:241], v205 offset:4608
	s_setprio 1
	s_waitcnt lgkmcnt(1)
	v_mfma_f32_32x32x16_bf16 v[112:127], v[234:237], v[226:229], v[112:127]
	v_mfma_f32_32x32x16_bf16 v[48:63], v[234:237], v[230:233], v[48:63]
	s_waitcnt lgkmcnt(0)
	v_mfma_f32_32x32x16_bf16 v[96:111], v[238:241], v[226:229], v[96:111]
	v_mfma_f32_32x32x16_bf16 v[32:47], v[238:241], v[230:233], v[32:47]
	ds_read_b128 v[234:237], v205 offset:9216
	ds_read_b128 v[238:241], v205 offset:13824
	s_waitcnt vmcnt(7)
	ds_write_b128 v215, v[176:179] offset:9216
	s_waitcnt vmcnt(6)
	ds_write_b128 v215, v[180:183] offset:46080
	ds_read_b128 v[176:179], v208 offset:32
	ds_read_b128 v[180:183], v208 offset:4640
	s_waitcnt lgkmcnt(5)
	v_mfma_f32_32x32x16_bf16 v[80:95], v[234:237], v[226:229], v[80:95]
	v_mfma_f32_32x32x16_bf16 v[16:31], v[234:237], v[230:233], v[16:31]
	ds_read_b128 v[234:237], v205 offset:32
	s_waitcnt lgkmcnt(5)
	v_mfma_f32_32x32x16_bf16 v[64:79], v[238:241], v[226:229], v[64:79]
	v_mfma_f32_32x32x16_bf16 v[0:15], v[238:241], v[230:233], v[0:15]
	ds_read_b128 v[238:241], v205 offset:4640
	global_load_dwordx4 v[226:229], v[194:195], off offset:896
	global_load_dwordx4 v[230:233], v[196:197], off offset:896
	s_waitcnt lgkmcnt(1)
	v_mfma_f32_32x32x16_bf16 v[112:127], v[234:237], v[176:179], v[112:127]
	v_mfma_f32_32x32x16_bf16 v[48:63], v[234:237], v[180:183], v[48:63]
	s_waitcnt lgkmcnt(0)
	v_mfma_f32_32x32x16_bf16 v[96:111], v[238:241], v[176:179], v[96:111]
	v_mfma_f32_32x32x16_bf16 v[32:47], v[238:241], v[180:183], v[32:47]
	ds_read_b128 v[234:237], v205 offset:9248
	ds_read_b128 v[238:241], v205 offset:13856
	s_waitcnt vmcnt(7)
	ds_write_b128 v215, v[168:171] offset:18432
	s_waitcnt vmcnt(6)
	ds_write_b128 v215, v[172:175] offset:55296
	ds_read_b128 v[168:171], v208 offset:64
	ds_read_b128 v[172:175], v208 offset:4672
	s_waitcnt lgkmcnt(5)
	v_mfma_f32_32x32x16_bf16 v[80:95], v[234:237], v[176:179], v[80:95]
	v_mfma_f32_32x32x16_bf16 v[16:31], v[234:237], v[180:183], v[16:31]
	ds_read_b128 v[234:237], v205 offset:64
	s_waitcnt lgkmcnt(5)
	v_mfma_f32_32x32x16_bf16 v[64:79], v[238:241], v[176:179], v[64:79]
	v_mfma_f32_32x32x16_bf16 v[0:15], v[238:241], v[180:183], v[0:15]
	ds_read_b128 v[238:241], v205 offset:4672
	global_load_dwordx4 v[176:179], v[184:185], off offset:896
	global_load_dwordx4 v[180:183], v[186:187], off offset:896
	s_waitcnt lgkmcnt(1)
	v_mfma_f32_32x32x16_bf16 v[112:127], v[234:237], v[168:171], v[112:127]
	v_mfma_f32_32x32x16_bf16 v[48:63], v[234:237], v[172:175], v[48:63]
	s_waitcnt lgkmcnt(0)
	v_mfma_f32_32x32x16_bf16 v[96:111], v[238:241], v[168:171], v[96:111]
	v_mfma_f32_32x32x16_bf16 v[32:47], v[238:241], v[172:175], v[32:47]
	ds_read_b128 v[234:237], v205 offset:9280
	ds_read_b128 v[238:241], v205 offset:13888
	s_waitcnt vmcnt(7)
	ds_write_b128 v215, v[160:163] offset:27648
	s_waitcnt vmcnt(6)
	ds_write_b128 v215, v[164:167] offset:64512
	ds_read_b128 v[160:163], v208 offset:96
	ds_read_b128 v[164:167], v208 offset:4704
	s_waitcnt lgkmcnt(5)
	v_mfma_f32_32x32x16_bf16 v[80:95], v[234:237], v[168:171], v[80:95]
	v_mfma_f32_32x32x16_bf16 v[16:31], v[234:237], v[172:175], v[16:31]
	ds_read_b128 v[234:237], v205 offset:96
	s_waitcnt lgkmcnt(5)
	v_mfma_f32_32x32x16_bf16 v[64:79], v[238:241], v[168:171], v[64:79]
	v_mfma_f32_32x32x16_bf16 v[0:15], v[238:241], v[172:175], v[0:15]
	ds_read_b128 v[238:241], v205 offset:4704
	global_load_dwordx4 v[168:171], v[198:199], off offset:896
	global_load_dwordx4 v[172:175], v[200:201], off offset:896
	s_waitcnt lgkmcnt(1)
	v_mfma_f32_32x32x16_bf16 v[112:127], v[234:237], v[160:163], v[112:127]
	v_mfma_f32_32x32x16_bf16 v[48:63], v[234:237], v[164:167], v[48:63]
	s_waitcnt lgkmcnt(0)
	v_mfma_f32_32x32x16_bf16 v[96:111], v[238:241], v[160:163], v[96:111]
	v_mfma_f32_32x32x16_bf16 v[32:47], v[238:241], v[164:167], v[32:47]
	ds_read_b128 v[234:237], v205 offset:9312
	ds_read_b128 v[238:241], v205 offset:13920
	s_waitcnt lgkmcnt(1)
	v_mfma_f32_32x32x16_bf16 v[80:95], v[234:237], v[160:163], v[80:95]
	v_mfma_f32_32x32x16_bf16 v[16:31], v[234:237], v[164:167], v[16:31]
	s_waitcnt lgkmcnt(0)
	v_mfma_f32_32x32x16_bf16 v[64:79], v[238:241], v[160:163], v[64:79]
	v_mfma_f32_32x32x16_bf16 v[0:15], v[238:241], v[164:167], v[0:15]
	s_setprio 0
	s_barrier
; template <bool trans>
; DI void gemm_core(const GTile& tl, const GTile& nx, bool has_next  , bool chain  , bool pre, u32x4 (&ra)[4], u32x4 (&rb)[4], char* smem, f32x16 (&acc)[2][4]) {
;     ...
;   const int nk = K / 64;
;   if (!pre) { G_LOAD(0); G_STORE(0); G_LOAD(1); }
;   for (int kt = 0; kt < nk; ++kt) {
;     __syncthreads();
;     G_COMPUTE(kt & 1, kt);
;   }
	global_load_dwordx4 v[160:163], v[190:191], off offset:1024
	global_load_dwordx4 v[164:167], v[188:189], off offset:1024
	s_waitcnt vmcnt(9)
	ds_write_b128 v209, v[218:221]
	s_waitcnt vmcnt(8)
	ds_write_b128 v210, v[222:225]
	ds_read_b128 v[218:221], v204 offset:36864
	ds_read_b128 v[222:225], v204 offset:41472
	ds_read_b128 v[234:237], v192
	ds_read_b128 v[238:241], v192 offset:4608
	s_setprio 1
	s_waitcnt lgkmcnt(1)
	v_mfma_f32_32x32x16_bf16 v[112:127], v[234:237], v[218:221], v[112:127]
	v_mfma_f32_32x32x16_bf16 v[48:63], v[234:237], v[222:225], v[48:63]
	s_waitcnt lgkmcnt(0)
	v_mfma_f32_32x32x16_bf16 v[96:111], v[238:241], v[218:221], v[96:111]
	v_mfma_f32_32x32x16_bf16 v[32:47], v[238:241], v[222:225], v[32:47]
	ds_read_b128 v[234:237], v192 offset:9216
	ds_read_b128 v[238:241], v192 offset:13824
	s_waitcnt vmcnt(7)
	ds_write_b128 v212, v[226:229]
	s_waitcnt vmcnt(6)
	ds_write_b128 v211, v[230:233]
	ds_read_b128 v[226:229], v204 offset:36896
	ds_read_b128 v[230:233], v204 offset:41504
	s_waitcnt lgkmcnt(5)
	v_mfma_f32_32x32x16_bf16 v[80:95], v[234:237], v[218:221], v[80:95]
	v_mfma_f32_32x32x16_bf16 v[16:31], v[234:237], v[222:225], v[16:31]
	ds_read_b128 v[234:237], v192 offset:32
	s_waitcnt lgkmcnt(5)
	v_mfma_f32_32x32x16_bf16 v[64:79], v[238:241], v[218:221], v[64:79]
	v_mfma_f32_32x32x16_bf16 v[0:15], v[238:241], v[222:225], v[0:15]
	ds_read_b128 v[238:241], v192 offset:4640
	global_load_dwordx4 v[218:221], v[194:195], off offset:1024
	global_load_dwordx4 v[222:225], v[196:197], off offset:1024
	s_waitcnt lgkmcnt(1)
	v_mfma_f32_32x32x16_bf16 v[112:127], v[234:237], v[226:229], v[112:127]
	v_mfma_f32_32x32x16_bf16 v[48:63], v[234:237], v[230:233], v[48:63]
	s_waitcnt lgkmcnt(0)
	v_mfma_f32_32x32x16_bf16 v[96:111], v[238:241], v[226:229], v[96:111]
	v_mfma_f32_32x32x16_bf16 v[32:47], v[238:241], v[230:233], v[32:47]
	ds_read_b128 v[234:237], v192 offset:9248
	ds_read_b128 v[238:241], v192 offset:13856
	s_waitcnt vmcnt(7)
	ds_write_b128 v214, v[176:179]
	s_waitcnt vmcnt(6)
	ds_write_b128 v213, v[180:183]
	ds_read_b128 v[176:179], v204 offset:36928
	ds_read_b128 v[180:183], v204 offset:41536
	s_waitcnt lgkmcnt(5)
	v_mfma_f32_32x32x16_bf16 v[80:95], v[234:237], v[226:229], v[80:95]
	v_mfma_f32_32x32x16_bf16 v[16:31], v[234:237], v[230:233], v[16:31]
	ds_read_b128 v[234:237], v192 offset:64
	s_waitcnt lgkmcnt(5)
	v_mfma_f32_32x32x16_bf16 v[64:79], v[238:241], v[226:229], v[64:79]
	v_mfma_f32_32x32x16_bf16 v[0:15], v[238:241], v[230:233], v[0:15]
	ds_read_b128 v[238:241], v192 offset:4672
	global_load_dwordx4 v[226:229], v[184:185], off offset:1024
	global_load_dwordx4 v[230:233], v[186:187], off offset:1024
	s_waitcnt lgkmcnt(1)
	v_mfma_f32_32x32x16_bf16 v[112:127], v[234:237], v[176:179], v[112:127]
	v_mfma_f32_32x32x16_bf16 v[48:63], v[234:237], v[180:183], v[48:63]
	s_waitcnt lgkmcnt(0)
	v_mfma_f32_32x32x16_bf16 v[96:111], v[238:241], v[176:179], v[96:111]
	v_mfma_f32_32x32x16_bf16 v[32:47], v[238:241], v[180:183], v[32:47]
	ds_read_b128 v[234:237], v192 offset:9280
	ds_read_b128 v[238:241], v192 offset:13888
	s_waitcnt vmcnt(7)
	ds_write_b128 v217, v[168:171]
	s_waitcnt vmcnt(6)
	ds_write_b128 v216, v[172:175]
	ds_read_b128 v[168:171], v204 offset:36960
	ds_read_b128 v[172:175], v204 offset:41568
	s_waitcnt lgkmcnt(5)
	v_mfma_f32_32x32x16_bf16 v[80:95], v[234:237], v[176:179], v[80:95]
	v_mfma_f32_32x32x16_bf16 v[16:31], v[234:237], v[180:183], v[16:31]
	ds_read_b128 v[234:237], v192 offset:96
	s_waitcnt lgkmcnt(5)
	v_mfma_f32_32x32x16_bf16 v[64:79], v[238:241], v[176:179], v[64:79]
	v_mfma_f32_32x32x16_bf16 v[0:15], v[238:241], v[180:183], v[0:15]
	ds_read_b128 v[238:241], v192 offset:4704
	global_load_dwordx4 v[176:179], v[198:199], off offset:1024
	global_load_dwordx4 v[180:183], v[200:201], off offset:1024
	s_waitcnt lgkmcnt(1)
	v_mfma_f32_32x32x16_bf16 v[112:127], v[234:237], v[168:171], v[112:127]
	v_mfma_f32_32x32x16_bf16 v[48:63], v[234:237], v[172:175], v[48:63]
	s_waitcnt lgkmcnt(0)
	v_mfma_f32_32x32x16_bf16 v[96:111], v[238:241], v[168:171], v[96:111]
	v_mfma_f32_32x32x16_bf16 v[32:47], v[238:241], v[172:175], v[32:47]
	ds_read_b128 v[234:237], v192 offset:9312
	ds_read_b128 v[238:241], v192 offset:13920
	s_waitcnt lgkmcnt(1)
	v_mfma_f32_32x32x16_bf16 v[80:95], v[234:237], v[168:171], v[80:95]
	v_mfma_f32_32x32x16_bf16 v[16:31], v[234:237], v[172:175], v[16:31]
	s_waitcnt lgkmcnt(0)
	v_mfma_f32_32x32x16_bf16 v[64:79], v[238:241], v[168:171], v[64:79]
	v_mfma_f32_32x32x16_bf16 v[0:15], v[238:241], v[172:175], v[0:15]
	s_setprio 0
	s_barrier
; template <bool trans>
; DI void gemm_core(const GTile& tl, const GTile& nx, bool has_next  , bool chain  , bool pre, u32x4 (&ra)[4], u32x4 (&rb)[4], char* smem, f32x16 (&acc)[2][4]) {
;     ...
;   const int nk = K / 64;
;   if (!pre) { G_LOAD(0); G_STORE(0); G_LOAD(1); }
;   for (int kt = 0; kt < nk; ++kt) {
;     __syncthreads();
;     G_COMPUTE(kt & 1, kt);
;   }
	global_load_dwordx4 v[168:171], v[190:191], off offset:1152
	global_load_dwordx4 v[172:175], v[188:189], off offset:1152
	s_waitcnt vmcnt(9)
	ds_write_b128 v215, v[160:163]
	s_waitcnt vmcnt(8)
	ds_write_b128 v215, v[164:167] offset:36864
	ds_read_b128 v[160:163], v208
	ds_read_b128 v[164:167], v208 offset:4608
	ds_read_b128 v[234:237], v205
	ds_read_b128 v[238:241], v205 offset:4608
	s_setprio 1
	s_waitcnt lgkmcnt(1)
	v_mfma_f32_32x32x16_bf16 v[112:127], v[234:237], v[160:163], v[112:127]
	v_mfma_f32_32x32x16_bf16 v[48:63], v[234:237], v[164:167], v[48:63]
	s_waitcnt lgkmcnt(0)
	v_mfma_f32_32x32x16_bf16 v[96:111], v[238:241], v[160:163], v[96:111]
	v_mfma_f32_32x32x16_bf16 v[32:47], v[238:241], v[164:167], v[32:47]
	ds_read_b128 v[234:237], v205 offset:9216
	ds_read_b128 v[238:241], v205 offset:13824
	s_waitcnt vmcnt(7)
	ds_write_b128 v215, v[218:221] offset:9216
	s_waitcnt vmcnt(6)
	ds_write_b128 v215, v[222:225] offset:46080
	ds_read_b128 v[218:221], v208 offset:32
	ds_read_b128 v[222:225], v208 offset:4640
	s_waitcnt lgkmcnt(5)
	v_mfma_f32_32x32x16_bf16 v[80:95], v[234:237], v[160:163], v[80:95]
	v_mfma_f32_32x32x16_bf16 v[16:31], v[234:237], v[164:167], v[16:31]
	ds_read_b128 v[234:237], v205 offset:32
	s_waitcnt lgkmcnt(5)
	v_mfma_f32_32x32x16_bf16 v[64:79], v[238:241], v[160:163], v[64:79]
	v_mfma_f32_32x32x16_bf16 v[0:15], v[238:241], v[164:167], v[0:15]
	ds_read_b128 v[238:241], v205 offset:4640
	global_load_dwordx4 v[160:163], v[194:195], off offset:1152
	global_load_dwordx4 v[164:167], v[196:197], off offset:1152
	s_waitcnt lgkmcnt(1)
	v_mfma_f32_32x32x16_bf16 v[112:127], v[234:237], v[218:221], v[112:127]
	v_mfma_f32_32x32x16_bf16 v[48:63], v[234:237], v[222:225], v[48:63]
	s_waitcnt lgkmcnt(0)
	v_mfma_f32_32x32x16_bf16 v[96:111], v[238:241], v[218:221], v[96:111]
	v_mfma_f32_32x32x16_bf16 v[32:47], v[238:241], v[222:225], v[32:47]
	ds_read_b128 v[234:237], v205 offset:9248
	ds_read_b128 v[238:241], v205 offset:13856
	s_waitcnt vmcnt(7)
	ds_write_b128 v215, v[226:229] offset:18432
	s_waitcnt vmcnt(6)
	ds_write_b128 v215, v[230:233] offset:55296
	ds_read_b128 v[226:229], v208 offset:64
	ds_read_b128 v[230:233], v208 offset:4672
	s_waitcnt lgkmcnt(5)
	v_mfma_f32_32x32x16_bf16 v[80:95], v[234:237], v[218:221], v[80:95]
	v_mfma_f32_32x32x16_bf16 v[16:31], v[234:237], v[222:225], v[16:31]
	ds_read_b128 v[234:237], v205 offset:64
	s_waitcnt lgkmcnt(5)
	v_mfma_f32_32x32x16_bf16 v[64:79], v[238:241], v[218:221], v[64:79]
	v_mfma_f32_32x32x16_bf16 v[0:15], v[238:241], v[222:225], v[0:15]
	ds_read_b128 v[238:241], v205 offset:4672
	global_load_dwordx4 v[218:221], v[184:185], off offset:1152
	global_load_dwordx4 v[222:225], v[186:187], off offset:1152
	s_waitcnt lgkmcnt(1)
	v_mfma_f32_32x32x16_bf16 v[112:127], v[234:237], v[226:229], v[112:127]
	v_mfma_f32_32x32x16_bf16 v[48:63], v[234:237], v[230:233], v[48:63]
	s_waitcnt lgkmcnt(0)
	v_mfma_f32_32x32x16_bf16 v[96:111], v[238:241], v[226:229], v[96:111]
	v_mfma_f32_32x32x16_bf16 v[32:47], v[238:241], v[230:233], v[32:47]
	ds_read_b128 v[234:237], v205 offset:9280
	ds_read_b128 v[238:241], v205 offset:13888
	s_waitcnt vmcnt(7)
	ds_write_b128 v215, v[176:179] offset:27648
	s_waitcnt vmcnt(6)
	ds_write_b128 v215, v[180:183] offset:64512
	ds_read_b128 v[176:179], v208 offset:96
	ds_read_b128 v[180:183], v208 offset:4704
	s_waitcnt lgkmcnt(5)
	v_mfma_f32_32x32x16_bf16 v[80:95], v[234:237], v[226:229], v[80:95]
	v_mfma_f32_32x32x16_bf16 v[16:31], v[234:237], v[230:233], v[16:31]
	ds_read_b128 v[234:237], v205 offset:96
	s_waitcnt lgkmcnt(5)
	v_mfma_f32_32x32x16_bf16 v[64:79], v[238:241], v[226:229], v[64:79]
	v_mfma_f32_32x32x16_bf16 v[0:15], v[238:241], v[230:233], v[0:15]
	ds_read_b128 v[238:241], v205 offset:4704
	global_load_dwordx4 v[226:229], v[198:199], off offset:1152
	global_load_dwordx4 v[230:233], v[200:201], off offset:1152
	s_waitcnt lgkmcnt(1)
	v_mfma_f32_32x32x16_bf16 v[112:127], v[234:237], v[176:179], v[112:127]
	v_mfma_f32_32x32x16_bf16 v[48:63], v[234:237], v[180:183], v[48:63]
	s_waitcnt lgkmcnt(0)
	v_mfma_f32_32x32x16_bf16 v[96:111], v[238:241], v[176:179], v[96:111]
	v_mfma_f32_32x32x16_bf16 v[32:47], v[238:241], v[180:183], v[32:47]
	ds_read_b128 v[234:237], v205 offset:9312
	ds_read_b128 v[238:241], v205 offset:13920
	s_waitcnt lgkmcnt(1)
	v_mfma_f32_32x32x16_bf16 v[80:95], v[234:237], v[176:179], v[80:95]
	v_mfma_f32_32x32x16_bf16 v[16:31], v[234:237], v[180:183], v[16:31]
	s_waitcnt lgkmcnt(0)
	v_mfma_f32_32x32x16_bf16 v[64:79], v[238:241], v[176:179], v[64:79]
	v_mfma_f32_32x32x16_bf16 v[0:15], v[238:241], v[180:183], v[0:15]
	s_setprio 0
	s_barrier
; template <bool trans>
; DI void gemm_core(const GTile& tl, const GTile& nx, bool has_next  , bool chain  , bool pre, u32x4 (&ra)[4], u32x4 (&rb)[4], char* smem, f32x16 (&acc)[2][4]) {
;     ...
;   const int nk = K / 64;
;   if (!pre) { G_LOAD(0); G_STORE(0); G_LOAD(1); }
;   for (int kt = 0; kt < nk; ++kt) {
;     __syncthreads();
;     G_COMPUTE(kt & 1, kt);
;   }
	global_load_dwordx4 v[176:179], v[190:191], off offset:1280
	global_load_dwordx4 v[180:183], v[188:189], off offset:1280
	s_waitcnt vmcnt(9)
	ds_write_b128 v209, v[168:171]
	s_waitcnt vmcnt(8)
	ds_write_b128 v210, v[172:175]
	ds_read_b128 v[168:171], v204 offset:36864
	ds_read_b128 v[172:175], v204 offset:41472
	ds_read_b128 v[234:237], v192
	ds_read_b128 v[238:241], v192 offset:4608
	s_setprio 1
	s_waitcnt lgkmcnt(1)
	v_mfma_f32_32x32x16_bf16 v[112:127], v[234:237], v[168:171], v[112:127]
	v_mfma_f32_32x32x16_bf16 v[48:63], v[234:237], v[172:175], v[48:63]
	s_waitcnt lgkmcnt(0)
	v_mfma_f32_32x32x16_bf16 v[96:111], v[238:241], v[168:171], v[96:111]
	v_mfma_f32_32x32x16_bf16 v[32:47], v[238:241], v[172:175], v[32:47]
	ds_read_b128 v[234:237], v192 offset:9216
	ds_read_b128 v[238:241], v192 offset:13824
	s_waitcnt vmcnt(7)
	ds_write_b128 v212, v[160:163]
	s_waitcnt vmcnt(6)
	ds_write_b128 v211, v[164:167]
	ds_read_b128 v[160:163], v204 offset:36896
	ds_read_b128 v[164:167], v204 offset:41504
	s_waitcnt lgkmcnt(5)
	v_mfma_f32_32x32x16_bf16 v[80:95], v[234:237], v[168:171], v[80:95]
	v_mfma_f32_32x32x16_bf16 v[16:31], v[234:237], v[172:175], v[16:31]
	ds_read_b128 v[234:237], v192 offset:32
	s_waitcnt lgkmcnt(5)
	v_mfma_f32_32x32x16_bf16 v[64:79], v[238:241], v[168:171], v[64:79]
	v_mfma_f32_32x32x16_bf16 v[0:15], v[238:241], v[172:175], v[0:15]
	ds_read_b128 v[238:241], v192 offset:4640
	global_load_dwordx4 v[168:171], v[194:195], off offset:1280
	global_load_dwordx4 v[172:175], v[196:197], off offset:1280
	s_waitcnt lgkmcnt(1)
	v_mfma_f32_32x32x16_bf16 v[112:127], v[234:237], v[160:163], v[112:127]
	v_mfma_f32_32x32x16_bf16 v[48:63], v[234:237], v[164:167], v[48:63]
	s_waitcnt lgkmcnt(0)
	v_mfma_f32_32x32x16_bf16 v[96:111], v[238:241], v[160:163], v[96:111]
	v_mfma_f32_32x32x16_bf16 v[32:47], v[238:241], v[164:167], v[32:47]
	ds_read_b128 v[234:237], v192 offset:9248
	ds_read_b128 v[238:241], v192 offset:13856
	s_waitcnt vmcnt(7)
	ds_write_b128 v214, v[218:221]
	s_waitcnt vmcnt(6)
	ds_write_b128 v213, v[222:225]
	ds_read_b128 v[218:221], v204 offset:36928
	ds_read_b128 v[222:225], v204 offset:41536
	s_waitcnt lgkmcnt(5)
	v_mfma_f32_32x32x16_bf16 v[80:95], v[234:237], v[160:163], v[80:95]
	v_mfma_f32_32x32x16_bf16 v[16:31], v[234:237], v[164:167], v[16:31]
	ds_read_b128 v[234:237], v192 offset:64
	s_waitcnt lgkmcnt(5)
	v_mfma_f32_32x32x16_bf16 v[64:79], v[238:241], v[160:163], v[64:79]
	v_mfma_f32_32x32x16_bf16 v[0:15], v[238:241], v[164:167], v[0:15]
	ds_read_b128 v[238:241], v192 offset:4672
	global_load_dwordx4 v[160:163], v[184:185], off offset:1280
	global_load_dwordx4 v[164:167], v[186:187], off offset:1280
	s_waitcnt lgkmcnt(1)
	v_mfma_f32_32x32x16_bf16 v[112:127], v[234:237], v[218:221], v[112:127]
	v_mfma_f32_32x32x16_bf16 v[48:63], v[234:237], v[222:225], v[48:63]
	s_waitcnt lgkmcnt(0)
	v_mfma_f32_32x32x16_bf16 v[96:111], v[238:241], v[218:221], v[96:111]
	v_mfma_f32_32x32x16_bf16 v[32:47], v[238:241], v[222:225], v[32:47]
	ds_read_b128 v[234:237], v192 offset:9280
	ds_read_b128 v[238:241], v192 offset:13888
	s_waitcnt vmcnt(7)
	ds_write_b128 v217, v[226:229]
	s_waitcnt vmcnt(6)
	ds_write_b128 v216, v[230:233]
	ds_read_b128 v[226:229], v204 offset:36960
	ds_read_b128 v[230:233], v204 offset:41568
	s_waitcnt lgkmcnt(5)
	v_mfma_f32_32x32x16_bf16 v[80:95], v[234:237], v[218:221], v[80:95]
	v_mfma_f32_32x32x16_bf16 v[16:31], v[234:237], v[222:225], v[16:31]
	ds_read_b128 v[234:237], v192 offset:96
	s_waitcnt lgkmcnt(5)
	v_mfma_f32_32x32x16_bf16 v[64:79], v[238:241], v[218:221], v[64:79]
	v_mfma_f32_32x32x16_bf16 v[0:15], v[238:241], v[222:225], v[0:15]
	ds_read_b128 v[238:241], v192 offset:4704
	global_load_dwordx4 v[218:221], v[198:199], off offset:1280
	global_load_dwordx4 v[222:225], v[200:201], off offset:1280
	s_waitcnt lgkmcnt(1)
	v_mfma_f32_32x32x16_bf16 v[112:127], v[234:237], v[226:229], v[112:127]
	v_mfma_f32_32x32x16_bf16 v[48:63], v[234:237], v[230:233], v[48:63]
	s_waitcnt lgkmcnt(0)
	v_mfma_f32_32x32x16_bf16 v[96:111], v[238:241], v[226:229], v[96:111]
	v_mfma_f32_32x32x16_bf16 v[32:47], v[238:241], v[230:233], v[32:47]
	ds_read_b128 v[234:237], v192 offset:9312
	ds_read_b128 v[238:241], v192 offset:13920
	s_waitcnt lgkmcnt(1)
	v_mfma_f32_32x32x16_bf16 v[80:95], v[234:237], v[226:229], v[80:95]
	v_mfma_f32_32x32x16_bf16 v[16:31], v[234:237], v[230:233], v[16:31]
	s_waitcnt lgkmcnt(0)
	v_mfma_f32_32x32x16_bf16 v[64:79], v[238:241], v[226:229], v[64:79]
	v_mfma_f32_32x32x16_bf16 v[0:15], v[238:241], v[230:233], v[0:15]
	s_setprio 0
	s_barrier
; template <bool trans>
; DI void gemm_core(const GTile& tl, const GTile& nx, bool has_next  , bool chain  , bool pre, u32x4 (&ra)[4], u32x4 (&rb)[4], char* smem, f32x16 (&acc)[2][4]) {
;     ...
;   const int nk = K / 64;
;   if (!pre) { G_LOAD(0); G_STORE(0); G_LOAD(1); }
;   for (int kt = 0; kt < nk; ++kt) {
;     __syncthreads();
;     G_COMPUTE(kt & 1, kt);
;   }
	global_load_dwordx4 v[226:229], v[190:191], off offset:1408
	global_load_dwordx4 v[230:233], v[188:189], off offset:1408
	s_waitcnt vmcnt(9)
	ds_write_b128 v215, v[176:179]
	s_waitcnt vmcnt(8)
	ds_write_b128 v215, v[180:183] offset:36864
	ds_read_b128 v[176:179], v208
	ds_read_b128 v[180:183], v208 offset:4608
	ds_read_b128 v[234:237], v205
	ds_read_b128 v[238:241], v205 offset:4608
	s_setprio 1
	s_waitcnt lgkmcnt(1)
	v_mfma_f32_32x32x16_bf16 v[112:127], v[234:237], v[176:179], v[112:127]
	v_mfma_f32_32x32x16_bf16 v[48:63], v[234:237], v[180:183], v[48:63]
	s_waitcnt lgkmcnt(0)
	v_mfma_f32_32x32x16_bf16 v[96:111], v[238:241], v[176:179], v[96:111]
	v_mfma_f32_32x32x16_bf16 v[32:47], v[238:241], v[180:183], v[32:47]
	ds_read_b128 v[234:237], v205 offset:9216
	ds_read_b128 v[238:241], v205 offset:13824
	s_waitcnt vmcnt(7)
	ds_write_b128 v215, v[168:171] offset:9216
	s_waitcnt vmcnt(6)
	ds_write_b128 v215, v[172:175] offset:46080
	ds_read_b128 v[168:171], v208 offset:32
	ds_read_b128 v[172:175], v208 offset:4640
	s_waitcnt lgkmcnt(5)
	v_mfma_f32_32x32x16_bf16 v[80:95], v[234:237], v[176:179], v[80:95]
	v_mfma_f32_32x32x16_bf16 v[16:31], v[234:237], v[180:183], v[16:31]
	ds_read_b128 v[234:237], v205 offset:32
	s_waitcnt lgkmcnt(5)
	v_mfma_f32_32x32x16_bf16 v[64:79], v[238:241], v[176:179], v[64:79]
	v_mfma_f32_32x32x16_bf16 v[0:15], v[238:241], v[180:183], v[0:15]
	ds_read_b128 v[238:241], v205 offset:4640
	global_load_dwordx4 v[176:179], v[194:195], off offset:1408
	global_load_dwordx4 v[180:183], v[196:197], off offset:1408
	s_waitcnt lgkmcnt(1)
	v_mfma_f32_32x32x16_bf16 v[112:127], v[234:237], v[168:171], v[112:127]
	v_mfma_f32_32x32x16_bf16 v[48:63], v[234:237], v[172:175], v[48:63]
	s_waitcnt lgkmcnt(0)
	v_mfma_f32_32x32x16_bf16 v[96:111], v[238:241], v[168:171], v[96:111]
	v_mfma_f32_32x32x16_bf16 v[32:47], v[238:241], v[172:175], v[32:47]
	ds_read_b128 v[234:237], v205 offset:9248
	ds_read_b128 v[238:241], v205 offset:13856
	s_waitcnt vmcnt(7)
	ds_write_b128 v215, v[160:163] offset:18432
	s_waitcnt vmcnt(6)
	ds_write_b128 v215, v[164:167] offset:55296
	ds_read_b128 v[160:163], v208 offset:64
	ds_read_b128 v[164:167], v208 offset:4672
	s_waitcnt lgkmcnt(5)
	v_mfma_f32_32x32x16_bf16 v[80:95], v[234:237], v[168:171], v[80:95]
	v_mfma_f32_32x32x16_bf16 v[16:31], v[234:237], v[172:175], v[16:31]
	ds_read_b128 v[234:237], v205 offset:64
	s_waitcnt lgkmcnt(5)
	v_mfma_f32_32x32x16_bf16 v[64:79], v[238:241], v[168:171], v[64:79]
	v_mfma_f32_32x32x16_bf16 v[0:15], v[238:241], v[172:175], v[0:15]
	ds_read_b128 v[238:241], v205 offset:4672
	global_load_dwordx4 v[168:171], v[184:185], off offset:1408
	global_load_dwordx4 v[172:175], v[186:187], off offset:1408
	s_waitcnt lgkmcnt(1)
	v_mfma_f32_32x32x16_bf16 v[112:127], v[234:237], v[160:163], v[112:127]
	v_mfma_f32_32x32x16_bf16 v[48:63], v[234:237], v[164:167], v[48:63]
	s_waitcnt lgkmcnt(0)
	v_mfma_f32_32x32x16_bf16 v[96:111], v[238:241], v[160:163], v[96:111]
	v_mfma_f32_32x32x16_bf16 v[32:47], v[238:241], v[164:167], v[32:47]
	ds_read_b128 v[234:237], v205 offset:9280
	ds_read_b128 v[238:241], v205 offset:13888
	s_waitcnt vmcnt(7)
	ds_write_b128 v215, v[218:221] offset:27648
	s_waitcnt vmcnt(6)
	ds_write_b128 v215, v[222:225] offset:64512
	ds_read_b128 v[218:221], v208 offset:96
	ds_read_b128 v[222:225], v208 offset:4704
	s_waitcnt lgkmcnt(5)
	v_mfma_f32_32x32x16_bf16 v[80:95], v[234:237], v[160:163], v[80:95]
	v_mfma_f32_32x32x16_bf16 v[16:31], v[234:237], v[164:167], v[16:31]
	ds_read_b128 v[234:237], v205 offset:96
	s_waitcnt lgkmcnt(5)
	v_mfma_f32_32x32x16_bf16 v[64:79], v[238:241], v[160:163], v[64:79]
	v_mfma_f32_32x32x16_bf16 v[0:15], v[238:241], v[164:167], v[0:15]
	ds_read_b128 v[238:241], v205 offset:4704
	global_load_dwordx4 v[160:163], v[198:199], off offset:1408
	global_load_dwordx4 v[164:167], v[200:201], off offset:1408
	s_waitcnt lgkmcnt(1)
	v_mfma_f32_32x32x16_bf16 v[112:127], v[234:237], v[218:221], v[112:127]
	v_mfma_f32_32x32x16_bf16 v[48:63], v[234:237], v[222:225], v[48:63]
	s_waitcnt lgkmcnt(0)
	v_mfma_f32_32x32x16_bf16 v[96:111], v[238:241], v[218:221], v[96:111]
	v_mfma_f32_32x32x16_bf16 v[32:47], v[238:241], v[222:225], v[32:47]
	ds_read_b128 v[234:237], v205 offset:9312
	ds_read_b128 v[238:241], v205 offset:13920
	s_waitcnt lgkmcnt(1)
	v_mfma_f32_32x32x16_bf16 v[80:95], v[234:237], v[218:221], v[80:95]
	v_mfma_f32_32x32x16_bf16 v[16:31], v[234:237], v[222:225], v[16:31]
	s_waitcnt lgkmcnt(0)
	v_mfma_f32_32x32x16_bf16 v[64:79], v[238:241], v[218:221], v[64:79]
	v_mfma_f32_32x32x16_bf16 v[0:15], v[238:241], v[222:225], v[0:15]
	s_setprio 0
	s_barrier
; template <bool trans>
; DI void gemm_core(const GTile& tl, const GTile& nx, bool has_next  , bool chain  , bool pre, u32x4 (&ra)[4], u32x4 (&rb)[4], char* smem, f32x16 (&acc)[2][4]) {
;     ...
;   const int nk = K / 64;
;   if (!pre) { G_LOAD(0); G_STORE(0); G_LOAD(1); }
;   for (int kt = 0; kt < nk; ++kt) {
;     __syncthreads();
;     G_COMPUTE(kt & 1, kt);
;   }
	global_load_dwordx4 v[218:221], v[190:191], off offset:1536
	global_load_dwordx4 v[222:225], v[188:189], off offset:1536
	s_waitcnt vmcnt(9)
	ds_write_b128 v209, v[226:229]
	s_waitcnt vmcnt(8)
	ds_write_b128 v210, v[230:233]
	ds_read_b128 v[226:229], v204 offset:36864
	ds_read_b128 v[230:233], v204 offset:41472
	ds_read_b128 v[234:237], v192
	ds_read_b128 v[238:241], v192 offset:4608
	s_setprio 1
	s_waitcnt lgkmcnt(1)
	v_mfma_f32_32x32x16_bf16 v[112:127], v[234:237], v[226:229], v[112:127]
	v_mfma_f32_32x32x16_bf16 v[48:63], v[234:237], v[230:233], v[48:63]
	s_waitcnt lgkmcnt(0)
	v_mfma_f32_32x32x16_bf16 v[96:111], v[238:241], v[226:229], v[96:111]
	v_mfma_f32_32x32x16_bf16 v[32:47], v[238:241], v[230:233], v[32:47]
	ds_read_b128 v[234:237], v192 offset:9216
	ds_read_b128 v[238:241], v192 offset:13824
	s_waitcnt vmcnt(7)
	ds_write_b128 v212, v[176:179]
	s_waitcnt vmcnt(6)
	ds_write_b128 v211, v[180:183]
	ds_read_b128 v[176:179], v204 offset:36896
	ds_read_b128 v[180:183], v204 offset:41504
	s_waitcnt lgkmcnt(5)
	v_mfma_f32_32x32x16_bf16 v[80:95], v[234:237], v[226:229], v[80:95]
	v_mfma_f32_32x32x16_bf16 v[16:31], v[234:237], v[230:233], v[16:31]
	ds_read_b128 v[234:237], v192 offset:32
	s_waitcnt lgkmcnt(5)
	v_mfma_f32_32x32x16_bf16 v[64:79], v[238:241], v[226:229], v[64:79]
	v_mfma_f32_32x32x16_bf16 v[0:15], v[238:241], v[230:233], v[0:15]
	ds_read_b128 v[238:241], v192 offset:4640
	global_load_dwordx4 v[226:229], v[194:195], off offset:1536
	global_load_dwordx4 v[230:233], v[196:197], off offset:1536
	s_waitcnt lgkmcnt(1)
	v_mfma_f32_32x32x16_bf16 v[112:127], v[234:237], v[176:179], v[112:127]
	v_mfma_f32_32x32x16_bf16 v[48:63], v[234:237], v[180:183], v[48:63]
	s_waitcnt lgkmcnt(0)
	v_mfma_f32_32x32x16_bf16 v[96:111], v[238:241], v[176:179], v[96:111]
	v_mfma_f32_32x32x16_bf16 v[32:47], v[238:241], v[180:183], v[32:47]
	ds_read_b128 v[234:237], v192 offset:9248
	ds_read_b128 v[238:241], v192 offset:13856
	s_waitcnt vmcnt(7)
	ds_write_b128 v214, v[168:171]
	s_waitcnt vmcnt(6)
	ds_write_b128 v213, v[172:175]
	ds_read_b128 v[168:171], v204 offset:36928
	ds_read_b128 v[172:175], v204 offset:41536
	s_waitcnt lgkmcnt(5)
	v_mfma_f32_32x32x16_bf16 v[80:95], v[234:237], v[176:179], v[80:95]
	v_mfma_f32_32x32x16_bf16 v[16:31], v[234:237], v[180:183], v[16:31]
	ds_read_b128 v[234:237], v192 offset:64
	s_waitcnt lgkmcnt(5)
	v_mfma_f32_32x32x16_bf16 v[64:79], v[238:241], v[176:179], v[64:79]
	v_mfma_f32_32x32x16_bf16 v[0:15], v[238:241], v[180:183], v[0:15]
	ds_read_b128 v[238:241], v192 offset:4672
	global_load_dwordx4 v[176:179], v[184:185], off offset:1536
	global_load_dwordx4 v[180:183], v[186:187], off offset:1536
	s_waitcnt lgkmcnt(1)
	v_mfma_f32_32x32x16_bf16 v[112:127], v[234:237], v[168:171], v[112:127]
	v_mfma_f32_32x32x16_bf16 v[48:63], v[234:237], v[172:175], v[48:63]
	s_waitcnt lgkmcnt(0)
	v_mfma_f32_32x32x16_bf16 v[96:111], v[238:241], v[168:171], v[96:111]
	v_mfma_f32_32x32x16_bf16 v[32:47], v[238:241], v[172:175], v[32:47]
	ds_read_b128 v[234:237], v192 offset:9280
	ds_read_b128 v[238:241], v192 offset:13888
	s_waitcnt vmcnt(7)
	ds_write_b128 v217, v[160:163]
	s_waitcnt vmcnt(6)
	ds_write_b128 v216, v[164:167]
	ds_read_b128 v[160:163], v204 offset:36960
	ds_read_b128 v[164:167], v204 offset:41568
	s_waitcnt lgkmcnt(5)
	v_mfma_f32_32x32x16_bf16 v[80:95], v[234:237], v[168:171], v[80:95]
	v_mfma_f32_32x32x16_bf16 v[16:31], v[234:237], v[172:175], v[16:31]
	ds_read_b128 v[234:237], v192 offset:96
	s_waitcnt lgkmcnt(5)
	v_mfma_f32_32x32x16_bf16 v[64:79], v[238:241], v[168:171], v[64:79]
	v_mfma_f32_32x32x16_bf16 v[0:15], v[238:241], v[172:175], v[0:15]
	ds_read_b128 v[238:241], v192 offset:4704
	global_load_dwordx4 v[168:171], v[198:199], off offset:1536
	global_load_dwordx4 v[172:175], v[200:201], off offset:1536
	s_waitcnt lgkmcnt(1)
	v_mfma_f32_32x32x16_bf16 v[112:127], v[234:237], v[160:163], v[112:127]
	v_mfma_f32_32x32x16_bf16 v[48:63], v[234:237], v[164:167], v[48:63]
	s_waitcnt lgkmcnt(0)
	v_mfma_f32_32x32x16_bf16 v[96:111], v[238:241], v[160:163], v[96:111]
	v_mfma_f32_32x32x16_bf16 v[32:47], v[238:241], v[164:167], v[32:47]
	ds_read_b128 v[234:237], v192 offset:9312
	ds_read_b128 v[238:241], v192 offset:13920
	s_waitcnt lgkmcnt(1)
	v_mfma_f32_32x32x16_bf16 v[80:95], v[234:237], v[160:163], v[80:95]
	v_mfma_f32_32x32x16_bf16 v[16:31], v[234:237], v[164:167], v[16:31]
	s_waitcnt lgkmcnt(0)
	v_mfma_f32_32x32x16_bf16 v[64:79], v[238:241], v[160:163], v[64:79]
	v_mfma_f32_32x32x16_bf16 v[0:15], v[238:241], v[164:167], v[0:15]
	s_setprio 0
	s_barrier
; template <bool trans>
; DI void gemm_core(const GTile& tl, const GTile& nx, bool has_next  , bool chain  , bool pre, u32x4 (&ra)[4], u32x4 (&rb)[4], char* smem, f32x16 (&acc)[2][4]) {
;     ...
;   const int nk = K / 64;
;   if (!pre) { G_LOAD(0); G_STORE(0); G_LOAD(1); }
;   for (int kt = 0; kt < nk; ++kt) {
;     __syncthreads();
;     G_COMPUTE(kt & 1, kt);
;   }
	global_load_dwordx4 v[160:163], v[190:191], off offset:1664
	global_load_dwordx4 v[164:167], v[188:189], off offset:1664
	s_waitcnt vmcnt(9)
	ds_write_b128 v215, v[218:221]
	s_waitcnt vmcnt(8)
	ds_write_b128 v215, v[222:225] offset:36864
	ds_read_b128 v[218:221], v208
	ds_read_b128 v[222:225], v208 offset:4608
	ds_read_b128 v[234:237], v205
	ds_read_b128 v[238:241], v205 offset:4608
	s_setprio 1
	s_waitcnt lgkmcnt(1)
	v_mfma_f32_32x32x16_bf16 v[112:127], v[234:237], v[218:221], v[112:127]
	v_mfma_f32_32x32x16_bf16 v[48:63], v[234:237], v[222:225], v[48:63]
	s_waitcnt lgkmcnt(0)
	v_mfma_f32_32x32x16_bf16 v[96:111], v[238:241], v[218:221], v[96:111]
	v_mfma_f32_32x32x16_bf16 v[32:47], v[238:241], v[222:225], v[32:47]
	ds_read_b128 v[234:237], v205 offset:9216
	ds_read_b128 v[238:241], v205 offset:13824
	s_waitcnt vmcnt(7)
	ds_write_b128 v215, v[226:229] offset:9216
	s_waitcnt vmcnt(6)
	ds_write_b128 v215, v[230:233] offset:46080
	ds_read_b128 v[226:229], v208 offset:32
	ds_read_b128 v[230:233], v208 offset:4640
	s_waitcnt lgkmcnt(5)
	v_mfma_f32_32x32x16_bf16 v[80:95], v[234:237], v[218:221], v[80:95]
	v_mfma_f32_32x32x16_bf16 v[16:31], v[234:237], v[222:225], v[16:31]
	ds_read_b128 v[234:237], v205 offset:32
	s_waitcnt lgkmcnt(5)
	v_mfma_f32_32x32x16_bf16 v[64:79], v[238:241], v[218:221], v[64:79]
	v_mfma_f32_32x32x16_bf16 v[0:15], v[238:241], v[222:225], v[0:15]
	ds_read_b128 v[238:241], v205 offset:4640
	global_load_dwordx4 v[218:221], v[194:195], off offset:1664
	global_load_dwordx4 v[222:225], v[196:197], off offset:1664
	s_waitcnt lgkmcnt(1)
	v_mfma_f32_32x32x16_bf16 v[112:127], v[234:237], v[226:229], v[112:127]
	v_mfma_f32_32x32x16_bf16 v[48:63], v[234:237], v[230:233], v[48:63]
	s_waitcnt lgkmcnt(0)
	v_mfma_f32_32x32x16_bf16 v[96:111], v[238:241], v[226:229], v[96:111]
	v_mfma_f32_32x32x16_bf16 v[32:47], v[238:241], v[230:233], v[32:47]
	ds_read_b128 v[234:237], v205 offset:9248
	ds_read_b128 v[238:241], v205 offset:13856
	s_waitcnt vmcnt(7)
	ds_write_b128 v215, v[176:179] offset:18432
	s_waitcnt vmcnt(6)
	ds_write_b128 v215, v[180:183] offset:55296
	ds_read_b128 v[176:179], v208 offset:64
	ds_read_b128 v[180:183], v208 offset:4672
	s_waitcnt lgkmcnt(5)
	v_mfma_f32_32x32x16_bf16 v[80:95], v[234:237], v[226:229], v[80:95]
	v_mfma_f32_32x32x16_bf16 v[16:31], v[234:237], v[230:233], v[16:31]
	ds_read_b128 v[234:237], v205 offset:64
	s_waitcnt lgkmcnt(5)
	v_mfma_f32_32x32x16_bf16 v[64:79], v[238:241], v[226:229], v[64:79]
	v_mfma_f32_32x32x16_bf16 v[0:15], v[238:241], v[230:233], v[0:15]
	ds_read_b128 v[238:241], v205 offset:4672
	global_load_dwordx4 v[226:229], v[184:185], off offset:1664
	global_load_dwordx4 v[230:233], v[186:187], off offset:1664
	s_waitcnt lgkmcnt(1)
	v_mfma_f32_32x32x16_bf16 v[112:127], v[234:237], v[176:179], v[112:127]
	v_mfma_f32_32x32x16_bf16 v[48:63], v[234:237], v[180:183], v[48:63]
	s_waitcnt lgkmcnt(0)
	v_mfma_f32_32x32x16_bf16 v[96:111], v[238:241], v[176:179], v[96:111]
	v_mfma_f32_32x32x16_bf16 v[32:47], v[238:241], v[180:183], v[32:47]
	ds_read_b128 v[234:237], v205 offset:9280
	ds_read_b128 v[238:241], v205 offset:13888
	s_waitcnt vmcnt(7)
	ds_write_b128 v215, v[168:171] offset:27648
	s_waitcnt vmcnt(6)
	ds_write_b128 v215, v[172:175] offset:64512
	ds_read_b128 v[168:171], v208 offset:96
	ds_read_b128 v[172:175], v208 offset:4704
	s_waitcnt lgkmcnt(5)
	v_mfma_f32_32x32x16_bf16 v[80:95], v[234:237], v[176:179], v[80:95]
	v_mfma_f32_32x32x16_bf16 v[16:31], v[234:237], v[180:183], v[16:31]
	ds_read_b128 v[234:237], v205 offset:96
	s_waitcnt lgkmcnt(5)
	v_mfma_f32_32x32x16_bf16 v[64:79], v[238:241], v[176:179], v[64:79]
	v_mfma_f32_32x32x16_bf16 v[0:15], v[238:241], v[180:183], v[0:15]
	ds_read_b128 v[238:241], v205 offset:4704
	global_load_dwordx4 v[176:179], v[198:199], off offset:1664
	global_load_dwordx4 v[180:183], v[200:201], off offset:1664
	s_waitcnt lgkmcnt(1)
	v_mfma_f32_32x32x16_bf16 v[112:127], v[234:237], v[168:171], v[112:127]
	v_mfma_f32_32x32x16_bf16 v[48:63], v[234:237], v[172:175], v[48:63]
	s_waitcnt lgkmcnt(0)
	v_mfma_f32_32x32x16_bf16 v[96:111], v[238:241], v[168:171], v[96:111]
	v_mfma_f32_32x32x16_bf16 v[32:47], v[238:241], v[172:175], v[32:47]
	ds_read_b128 v[234:237], v205 offset:9312
	ds_read_b128 v[238:241], v205 offset:13920
	s_waitcnt lgkmcnt(1)
	v_mfma_f32_32x32x16_bf16 v[80:95], v[234:237], v[168:171], v[80:95]
	v_mfma_f32_32x32x16_bf16 v[16:31], v[234:237], v[172:175], v[16:31]
	s_waitcnt lgkmcnt(0)
	v_mfma_f32_32x32x16_bf16 v[64:79], v[238:241], v[168:171], v[64:79]
	v_mfma_f32_32x32x16_bf16 v[0:15], v[238:241], v[172:175], v[0:15]
	s_setprio 0
	s_barrier
; template <bool trans>
; DI void gemm_core(const GTile& tl, const GTile& nx, bool has_next  , bool chain  , bool pre, u32x4 (&ra)[4], u32x4 (&rb)[4], char* smem, f32x16 (&acc)[2][4]) {
;     ...
;   const int nk = K / 64;
;   if (!pre) { G_LOAD(0); G_STORE(0); G_LOAD(1); }
;   for (int kt = 0; kt < nk; ++kt) {
;     __syncthreads();
;     G_COMPUTE(kt & 1, kt);
;   }
	global_load_dwordx4 v[168:171], v[190:191], off offset:1792
	global_load_dwordx4 v[172:175], v[188:189], off offset:1792
	s_waitcnt vmcnt(9)
	ds_write_b128 v209, v[160:163]
	s_waitcnt vmcnt(8)
	ds_write_b128 v210, v[164:167]
	ds_read_b128 v[160:163], v204 offset:36864
	ds_read_b128 v[164:167], v204 offset:41472
	ds_read_b128 v[234:237], v192
	ds_read_b128 v[238:241], v192 offset:4608
	s_setprio 1
	s_waitcnt lgkmcnt(1)
	v_mfma_f32_32x32x16_bf16 v[112:127], v[234:237], v[160:163], v[112:127]
	v_mfma_f32_32x32x16_bf16 v[48:63], v[234:237], v[164:167], v[48:63]
	s_waitcnt lgkmcnt(0)
	v_mfma_f32_32x32x16_bf16 v[96:111], v[238:241], v[160:163], v[96:111]
	v_mfma_f32_32x32x16_bf16 v[32:47], v[238:241], v[164:167], v[32:47]
	ds_read_b128 v[234:237], v192 offset:9216
	ds_read_b128 v[238:241], v192 offset:13824
	s_waitcnt vmcnt(7)
	ds_write_b128 v212, v[218:221]
	s_waitcnt vmcnt(6)
	ds_write_b128 v211, v[222:225]
	ds_read_b128 v[218:221], v204 offset:36896
	ds_read_b128 v[222:225], v204 offset:41504
	s_waitcnt lgkmcnt(5)
	v_mfma_f32_32x32x16_bf16 v[80:95], v[234:237], v[160:163], v[80:95]
	v_mfma_f32_32x32x16_bf16 v[16:31], v[234:237], v[164:167], v[16:31]
	ds_read_b128 v[234:237], v192 offset:32
	s_waitcnt lgkmcnt(5)
	v_mfma_f32_32x32x16_bf16 v[64:79], v[238:241], v[160:163], v[64:79]
	v_mfma_f32_32x32x16_bf16 v[0:15], v[238:241], v[164:167], v[0:15]
	ds_read_b128 v[238:241], v192 offset:4640
	global_load_dwordx4 v[160:163], v[194:195], off offset:1792
	global_load_dwordx4 v[164:167], v[196:197], off offset:1792
	s_waitcnt lgkmcnt(1)
	v_mfma_f32_32x32x16_bf16 v[112:127], v[234:237], v[218:221], v[112:127]
	v_mfma_f32_32x32x16_bf16 v[48:63], v[234:237], v[222:225], v[48:63]
	s_waitcnt lgkmcnt(0)
	v_mfma_f32_32x32x16_bf16 v[96:111], v[238:241], v[218:221], v[96:111]
	v_mfma_f32_32x32x16_bf16 v[32:47], v[238:241], v[222:225], v[32:47]
	ds_read_b128 v[234:237], v192 offset:9248
	ds_read_b128 v[238:241], v192 offset:13856
	s_waitcnt vmcnt(7)
	ds_write_b128 v214, v[226:229]
	s_waitcnt vmcnt(6)
	ds_write_b128 v213, v[230:233]
	ds_read_b128 v[226:229], v204 offset:36928
	ds_read_b128 v[230:233], v204 offset:41536
	s_waitcnt lgkmcnt(5)
	v_mfma_f32_32x32x16_bf16 v[80:95], v[234:237], v[218:221], v[80:95]
	v_mfma_f32_32x32x16_bf16 v[16:31], v[234:237], v[222:225], v[16:31]
	ds_read_b128 v[234:237], v192 offset:64
	s_waitcnt lgkmcnt(5)
	v_mfma_f32_32x32x16_bf16 v[64:79], v[238:241], v[218:221], v[64:79]
	v_mfma_f32_32x32x16_bf16 v[0:15], v[238:241], v[222:225], v[0:15]
	ds_read_b128 v[238:241], v192 offset:4672
	global_load_dwordx4 v[218:221], v[184:185], off offset:1792
	global_load_dwordx4 v[222:225], v[186:187], off offset:1792
	s_waitcnt lgkmcnt(1)
	v_mfma_f32_32x32x16_bf16 v[112:127], v[234:237], v[226:229], v[112:127]
	v_mfma_f32_32x32x16_bf16 v[48:63], v[234:237], v[230:233], v[48:63]
	s_waitcnt lgkmcnt(0)
	v_mfma_f32_32x32x16_bf16 v[96:111], v[238:241], v[226:229], v[96:111]
	v_mfma_f32_32x32x16_bf16 v[32:47], v[238:241], v[230:233], v[32:47]
	ds_read_b128 v[234:237], v192 offset:9280
	ds_read_b128 v[238:241], v192 offset:13888
	s_waitcnt vmcnt(7)
	ds_write_b128 v217, v[176:179]
	s_waitcnt vmcnt(6)
	ds_write_b128 v216, v[180:183]
	ds_read_b128 v[176:179], v204 offset:36960
	ds_read_b128 v[180:183], v204 offset:41568
	s_waitcnt lgkmcnt(5)
	v_mfma_f32_32x32x16_bf16 v[80:95], v[234:237], v[226:229], v[80:95]
	v_mfma_f32_32x32x16_bf16 v[16:31], v[234:237], v[230:233], v[16:31]
	ds_read_b128 v[234:237], v192 offset:96
	s_waitcnt lgkmcnt(5)
	v_mfma_f32_32x32x16_bf16 v[64:79], v[238:241], v[226:229], v[64:79]
	v_mfma_f32_32x32x16_bf16 v[0:15], v[238:241], v[230:233], v[0:15]
	ds_read_b128 v[238:241], v192 offset:4704
	global_load_dwordx4 v[226:229], v[198:199], off offset:1792
	global_load_dwordx4 v[230:233], v[200:201], off offset:1792
	s_waitcnt lgkmcnt(1)
	v_mfma_f32_32x32x16_bf16 v[112:127], v[234:237], v[176:179], v[112:127]
	v_mfma_f32_32x32x16_bf16 v[48:63], v[234:237], v[180:183], v[48:63]
	s_waitcnt lgkmcnt(0)
	v_mfma_f32_32x32x16_bf16 v[96:111], v[238:241], v[176:179], v[96:111]
	v_mfma_f32_32x32x16_bf16 v[32:47], v[238:241], v[180:183], v[32:47]
	ds_read_b128 v[234:237], v192 offset:9312
	ds_read_b128 v[238:241], v192 offset:13920
	s_waitcnt lgkmcnt(1)
	v_mfma_f32_32x32x16_bf16 v[80:95], v[234:237], v[176:179], v[80:95]
	v_mfma_f32_32x32x16_bf16 v[16:31], v[234:237], v[180:183], v[16:31]
	s_waitcnt lgkmcnt(0)
	v_mfma_f32_32x32x16_bf16 v[64:79], v[238:241], v[176:179], v[64:79]
	v_mfma_f32_32x32x16_bf16 v[0:15], v[238:241], v[180:183], v[0:15]
	s_setprio 0
	s_barrier
; template <bool trans>
; DI void gemm_core(const GTile& tl, const GTile& nx, bool has_next  , bool chain  , bool pre, u32x4 (&ra)[4], u32x4 (&rb)[4], char* smem, f32x16 (&acc)[2][4]) {
;     ...
;   const int nk = K / 64;
;   if (!pre) { G_LOAD(0); G_STORE(0); G_LOAD(1); }
;   for (int kt = 0; kt < nk; ++kt) {
;     __syncthreads();
;     G_COMPUTE(kt & 1, kt);
;   }
	global_load_dwordx4 v[176:179], v[190:191], off offset:1920
	global_load_dwordx4 v[180:183], v[188:189], off offset:1920
	s_waitcnt vmcnt(9)
	ds_write_b128 v215, v[168:171]
	s_waitcnt vmcnt(8)
	ds_write_b128 v215, v[172:175] offset:36864
	ds_read_b128 v[168:171], v208
	ds_read_b128 v[172:175], v208 offset:4608
	ds_read_b128 v[234:237], v205
	ds_read_b128 v[238:241], v205 offset:4608
	s_setprio 1
	s_waitcnt lgkmcnt(1)
	v_mfma_f32_32x32x16_bf16 v[112:127], v[234:237], v[168:171], v[112:127]
	v_mfma_f32_32x32x16_bf16 v[48:63], v[234:237], v[172:175], v[48:63]
	s_waitcnt lgkmcnt(0)
	v_mfma_f32_32x32x16_bf16 v[96:111], v[238:241], v[168:171], v[96:111]
	v_mfma_f32_32x32x16_bf16 v[32:47], v[238:241], v[172:175], v[32:47]
	ds_read_b128 v[234:237], v205 offset:9216
	ds_read_b128 v[238:241], v205 offset:13824
	s_waitcnt vmcnt(7)
	ds_write_b128 v215, v[160:163] offset:9216
	s_waitcnt vmcnt(6)
	ds_write_b128 v215, v[164:167] offset:46080
	ds_read_b128 v[160:163], v208 offset:32
	ds_read_b128 v[164:167], v208 offset:4640
	s_waitcnt lgkmcnt(5)
	v_mfma_f32_32x32x16_bf16 v[80:95], v[234:237], v[168:171], v[80:95]
	v_mfma_f32_32x32x16_bf16 v[16:31], v[234:237], v[172:175], v[16:31]
	ds_read_b128 v[234:237], v205 offset:32
	s_waitcnt lgkmcnt(5)
	v_mfma_f32_32x32x16_bf16 v[64:79], v[238:241], v[168:171], v[64:79]
	v_mfma_f32_32x32x16_bf16 v[0:15], v[238:241], v[172:175], v[0:15]
	ds_read_b128 v[238:241], v205 offset:4640
	global_load_dwordx4 v[168:171], v[194:195], off offset:1920
	global_load_dwordx4 v[172:175], v[196:197], off offset:1920
	s_waitcnt lgkmcnt(1)
	v_mfma_f32_32x32x16_bf16 v[112:127], v[234:237], v[160:163], v[112:127]
	v_mfma_f32_32x32x16_bf16 v[48:63], v[234:237], v[164:167], v[48:63]
	s_waitcnt lgkmcnt(0)
	v_mfma_f32_32x32x16_bf16 v[96:111], v[238:241], v[160:163], v[96:111]
	v_mfma_f32_32x32x16_bf16 v[32:47], v[238:241], v[164:167], v[32:47]
	ds_read_b128 v[234:237], v205 offset:9248
	ds_read_b128 v[238:241], v205 offset:13856
	s_waitcnt vmcnt(7)
	ds_write_b128 v215, v[218:221] offset:18432
	s_waitcnt vmcnt(6)
	ds_write_b128 v215, v[222:225] offset:55296
	ds_read_b128 v[218:221], v208 offset:64
	ds_read_b128 v[222:225], v208 offset:4672
	s_waitcnt lgkmcnt(5)
	v_mfma_f32_32x32x16_bf16 v[80:95], v[234:237], v[160:163], v[80:95]
	v_mfma_f32_32x32x16_bf16 v[16:31], v[234:237], v[164:167], v[16:31]
	ds_read_b128 v[234:237], v205 offset:64
	s_waitcnt lgkmcnt(5)
	v_mfma_f32_32x32x16_bf16 v[64:79], v[238:241], v[160:163], v[64:79]
	v_mfma_f32_32x32x16_bf16 v[0:15], v[238:241], v[164:167], v[0:15]
	ds_read_b128 v[238:241], v205 offset:4672
	global_load_dwordx4 v[160:163], v[184:185], off offset:1920
	global_load_dwordx4 v[164:167], v[186:187], off offset:1920
	s_waitcnt lgkmcnt(1)
	v_mfma_f32_32x32x16_bf16 v[112:127], v[234:237], v[218:221], v[112:127]
	v_mfma_f32_32x32x16_bf16 v[48:63], v[234:237], v[222:225], v[48:63]
	s_waitcnt lgkmcnt(0)
	v_mfma_f32_32x32x16_bf16 v[96:111], v[238:241], v[218:221], v[96:111]
	v_mfma_f32_32x32x16_bf16 v[32:47], v[238:241], v[222:225], v[32:47]
	ds_read_b128 v[234:237], v205 offset:9280
	ds_read_b128 v[238:241], v205 offset:13888
	s_waitcnt vmcnt(7)
	ds_write_b128 v215, v[226:229] offset:27648
	s_waitcnt vmcnt(6)
	ds_write_b128 v215, v[230:233] offset:64512
	ds_read_b128 v[226:229], v208 offset:96
	ds_read_b128 v[230:233], v208 offset:4704
	s_waitcnt lgkmcnt(5)
	v_mfma_f32_32x32x16_bf16 v[80:95], v[234:237], v[218:221], v[80:95]
	v_mfma_f32_32x32x16_bf16 v[16:31], v[234:237], v[222:225], v[16:31]
	ds_read_b128 v[234:237], v205 offset:96
	s_waitcnt lgkmcnt(5)
	v_mfma_f32_32x32x16_bf16 v[64:79], v[238:241], v[218:221], v[64:79]
	v_mfma_f32_32x32x16_bf16 v[0:15], v[238:241], v[222:225], v[0:15]
	ds_read_b128 v[238:241], v205 offset:4704
	global_load_dwordx4 v[218:221], v[198:199], off offset:1920
	global_load_dwordx4 v[222:225], v[200:201], off offset:1920
	s_waitcnt lgkmcnt(1)
	v_mfma_f32_32x32x16_bf16 v[112:127], v[234:237], v[226:229], v[112:127]
	v_mfma_f32_32x32x16_bf16 v[48:63], v[234:237], v[230:233], v[48:63]
	s_waitcnt lgkmcnt(0)
	v_mfma_f32_32x32x16_bf16 v[96:111], v[238:241], v[226:229], v[96:111]
	v_mfma_f32_32x32x16_bf16 v[32:47], v[238:241], v[230:233], v[32:47]
	ds_read_b128 v[234:237], v205 offset:9312
	ds_read_b128 v[238:241], v205 offset:13920
	s_waitcnt lgkmcnt(1)
	v_mfma_f32_32x32x16_bf16 v[80:95], v[234:237], v[226:229], v[80:95]
	v_mfma_f32_32x32x16_bf16 v[16:31], v[234:237], v[230:233], v[16:31]
	s_waitcnt lgkmcnt(0)
	v_mfma_f32_32x32x16_bf16 v[64:79], v[238:241], v[226:229], v[64:79]
	v_mfma_f32_32x32x16_bf16 v[0:15], v[238:241], v[230:233], v[0:15]
	s_setprio 0
	s_barrier
; template <bool trans>
; DI void gemm_core(const GTile& tl, const GTile& nx, bool has_next  , bool chain  , bool pre, u32x4 (&ra)[4], u32x4 (&rb)[4], char* smem, f32x16 (&acc)[2][4]) {
;     ...
;   const int nk = K / 64;
;   if (!pre) { G_LOAD(0); G_STORE(0); G_LOAD(1); }
;   for (int kt = 0; kt < nk; ++kt) {
;     __syncthreads();
;     G_COMPUTE(kt & 1, kt);
;   }
	global_load_dwordx4 v[226:229], v[190:191], off offset:2048
	global_load_dwordx4 v[230:233], v[188:189], off offset:2048
	s_waitcnt vmcnt(9)
	ds_write_b128 v209, v[176:179]
	s_waitcnt vmcnt(8)
	ds_write_b128 v210, v[180:183]
	ds_read_b128 v[176:179], v204 offset:36864
	ds_read_b128 v[180:183], v204 offset:41472
	ds_read_b128 v[234:237], v192
	ds_read_b128 v[238:241], v192 offset:4608
	s_setprio 1
	s_waitcnt lgkmcnt(1)
	v_mfma_f32_32x32x16_bf16 v[112:127], v[234:237], v[176:179], v[112:127]
	v_mfma_f32_32x32x16_bf16 v[48:63], v[234:237], v[180:183], v[48:63]
	s_waitcnt lgkmcnt(0)
	v_mfma_f32_32x32x16_bf16 v[96:111], v[238:241], v[176:179], v[96:111]
	v_mfma_f32_32x32x16_bf16 v[32:47], v[238:241], v[180:183], v[32:47]
	ds_read_b128 v[234:237], v192 offset:9216
	ds_read_b128 v[238:241], v192 offset:13824
	s_waitcnt vmcnt(7)
	ds_write_b128 v212, v[168:171]
	s_waitcnt vmcnt(6)
	ds_write_b128 v211, v[172:175]
	ds_read_b128 v[168:171], v204 offset:36896
	ds_read_b128 v[172:175], v204 offset:41504
	s_waitcnt lgkmcnt(5)
	v_mfma_f32_32x32x16_bf16 v[80:95], v[234:237], v[176:179], v[80:95]
	v_mfma_f32_32x32x16_bf16 v[16:31], v[234:237], v[180:183], v[16:31]
	ds_read_b128 v[234:237], v192 offset:32
	s_waitcnt lgkmcnt(5)
	v_mfma_f32_32x32x16_bf16 v[64:79], v[238:241], v[176:179], v[64:79]
	v_mfma_f32_32x32x16_bf16 v[0:15], v[238:241], v[180:183], v[0:15]
	ds_read_b128 v[238:241], v192 offset:4640
	global_load_dwordx4 v[176:179], v[194:195], off offset:2048
	global_load_dwordx4 v[180:183], v[196:197], off offset:2048
	s_waitcnt lgkmcnt(1)
	v_mfma_f32_32x32x16_bf16 v[112:127], v[234:237], v[168:171], v[112:127]
	v_mfma_f32_32x32x16_bf16 v[48:63], v[234:237], v[172:175], v[48:63]
	s_waitcnt lgkmcnt(0)
	v_mfma_f32_32x32x16_bf16 v[96:111], v[238:241], v[168:171], v[96:111]
	v_mfma_f32_32x32x16_bf16 v[32:47], v[238:241], v[172:175], v[32:47]
	ds_read_b128 v[234:237], v192 offset:9248
	ds_read_b128 v[238:241], v192 offset:13856
	s_waitcnt vmcnt(7)
	ds_write_b128 v214, v[160:163]
	s_waitcnt vmcnt(6)
	ds_write_b128 v213, v[164:167]
	ds_read_b128 v[160:163], v204 offset:36928
	ds_read_b128 v[164:167], v204 offset:41536
	s_waitcnt lgkmcnt(5)
	v_mfma_f32_32x32x16_bf16 v[80:95], v[234:237], v[168:171], v[80:95]
	v_mfma_f32_32x32x16_bf16 v[16:31], v[234:237], v[172:175], v[16:31]
	ds_read_b128 v[234:237], v192 offset:64
	s_waitcnt lgkmcnt(5)
	v_mfma_f32_32x32x16_bf16 v[64:79], v[238:241], v[168:171], v[64:79]
	v_mfma_f32_32x32x16_bf16 v[0:15], v[238:241], v[172:175], v[0:15]
	ds_read_b128 v[238:241], v192 offset:4672
	global_load_dwordx4 v[168:171], v[184:185], off offset:2048
	global_load_dwordx4 v[172:175], v[186:187], off offset:2048
	s_waitcnt lgkmcnt(1)
	v_mfma_f32_32x32x16_bf16 v[112:127], v[234:237], v[160:163], v[112:127]
	v_mfma_f32_32x32x16_bf16 v[48:63], v[234:237], v[164:167], v[48:63]
	s_waitcnt lgkmcnt(0)
	v_mfma_f32_32x32x16_bf16 v[96:111], v[238:241], v[160:163], v[96:111]
	v_mfma_f32_32x32x16_bf16 v[32:47], v[238:241], v[164:167], v[32:47]
	ds_read_b128 v[234:237], v192 offset:9280
	ds_read_b128 v[238:241], v192 offset:13888
	s_waitcnt vmcnt(7)
	ds_write_b128 v217, v[218:221]
	s_waitcnt vmcnt(6)
	ds_write_b128 v216, v[222:225]
	ds_read_b128 v[218:221], v204 offset:36960
	ds_read_b128 v[222:225], v204 offset:41568
	s_waitcnt lgkmcnt(5)
	v_mfma_f32_32x32x16_bf16 v[80:95], v[234:237], v[160:163], v[80:95]
	v_mfma_f32_32x32x16_bf16 v[16:31], v[234:237], v[164:167], v[16:31]
	ds_read_b128 v[234:237], v192 offset:96
	s_waitcnt lgkmcnt(5)
	v_mfma_f32_32x32x16_bf16 v[64:79], v[238:241], v[160:163], v[64:79]
	v_mfma_f32_32x32x16_bf16 v[0:15], v[238:241], v[164:167], v[0:15]
	ds_read_b128 v[238:241], v192 offset:4704
	global_load_dwordx4 v[160:163], v[198:199], off offset:2048
	global_load_dwordx4 v[164:167], v[200:201], off offset:2048
	s_waitcnt lgkmcnt(1)
	v_mfma_f32_32x32x16_bf16 v[112:127], v[234:237], v[218:221], v[112:127]
	v_mfma_f32_32x32x16_bf16 v[48:63], v[234:237], v[222:225], v[48:63]
	s_waitcnt lgkmcnt(0)
	v_mfma_f32_32x32x16_bf16 v[96:111], v[238:241], v[218:221], v[96:111]
	v_mfma_f32_32x32x16_bf16 v[32:47], v[238:241], v[222:225], v[32:47]
	ds_read_b128 v[234:237], v192 offset:9312
	ds_read_b128 v[238:241], v192 offset:13920
	s_waitcnt lgkmcnt(1)
	v_mfma_f32_32x32x16_bf16 v[80:95], v[234:237], v[218:221], v[80:95]
	v_mfma_f32_32x32x16_bf16 v[16:31], v[234:237], v[222:225], v[16:31]
	s_waitcnt lgkmcnt(0)
	v_mfma_f32_32x32x16_bf16 v[64:79], v[238:241], v[218:221], v[64:79]
	v_mfma_f32_32x32x16_bf16 v[0:15], v[238:241], v[222:225], v[0:15]
	s_setprio 0
	s_barrier
; template <bool trans>
; DI void gemm_core(const GTile& tl, const GTile& nx, bool has_next  , bool chain  , bool pre, u32x4 (&ra)[4], u32x4 (&rb)[4], char* smem, f32x16 (&acc)[2][4]) {
;     ...
;   const int nk = K / 64;
;   if (!pre) { G_LOAD(0); G_STORE(0); G_LOAD(1); }
;   for (int kt = 0; kt < nk; ++kt) {
;     __syncthreads();
;     G_COMPUTE(kt & 1, kt);
;   }
	global_load_dwordx4 v[218:221], v[190:191], off offset:2176
	global_load_dwordx4 v[222:225], v[188:189], off offset:2176
	s_waitcnt vmcnt(9)
	ds_write_b128 v215, v[226:229]
	s_waitcnt vmcnt(8)
	ds_write_b128 v215, v[230:233] offset:36864
	ds_read_b128 v[226:229], v208
	ds_read_b128 v[230:233], v208 offset:4608
	ds_read_b128 v[234:237], v205
	ds_read_b128 v[238:241], v205 offset:4608
	s_setprio 1
	s_waitcnt lgkmcnt(1)
	v_mfma_f32_32x32x16_bf16 v[112:127], v[234:237], v[226:229], v[112:127]
	v_mfma_f32_32x32x16_bf16 v[48:63], v[234:237], v[230:233], v[48:63]
	s_waitcnt lgkmcnt(0)
	v_mfma_f32_32x32x16_bf16 v[96:111], v[238:241], v[226:229], v[96:111]
	v_mfma_f32_32x32x16_bf16 v[32:47], v[238:241], v[230:233], v[32:47]
	ds_read_b128 v[234:237], v205 offset:9216
	ds_read_b128 v[238:241], v205 offset:13824
	s_waitcnt vmcnt(7)
	ds_write_b128 v215, v[176:179] offset:9216
	s_waitcnt vmcnt(6)
	ds_write_b128 v215, v[180:183] offset:46080
	ds_read_b128 v[176:179], v208 offset:32
	ds_read_b128 v[180:183], v208 offset:4640
	s_waitcnt lgkmcnt(5)
	v_mfma_f32_32x32x16_bf16 v[80:95], v[234:237], v[226:229], v[80:95]
	v_mfma_f32_32x32x16_bf16 v[16:31], v[234:237], v[230:233], v[16:31]
	ds_read_b128 v[234:237], v205 offset:32
	s_waitcnt lgkmcnt(5)
	v_mfma_f32_32x32x16_bf16 v[64:79], v[238:241], v[226:229], v[64:79]
	v_mfma_f32_32x32x16_bf16 v[0:15], v[238:241], v[230:233], v[0:15]
	ds_read_b128 v[238:241], v205 offset:4640
	global_load_dwordx4 v[226:229], v[194:195], off offset:2176
	global_load_dwordx4 v[230:233], v[196:197], off offset:2176
	s_waitcnt lgkmcnt(1)
	v_mfma_f32_32x32x16_bf16 v[112:127], v[234:237], v[176:179], v[112:127]
	v_mfma_f32_32x32x16_bf16 v[48:63], v[234:237], v[180:183], v[48:63]
	s_waitcnt lgkmcnt(0)
	v_mfma_f32_32x32x16_bf16 v[96:111], v[238:241], v[176:179], v[96:111]
	v_mfma_f32_32x32x16_bf16 v[32:47], v[238:241], v[180:183], v[32:47]
	ds_read_b128 v[234:237], v205 offset:9248
	ds_read_b128 v[238:241], v205 offset:13856
	s_waitcnt vmcnt(7)
	ds_write_b128 v215, v[168:171] offset:18432
	s_waitcnt vmcnt(6)
	ds_write_b128 v215, v[172:175] offset:55296
	ds_read_b128 v[168:171], v208 offset:64
	ds_read_b128 v[172:175], v208 offset:4672
	s_waitcnt lgkmcnt(5)
	v_mfma_f32_32x32x16_bf16 v[80:95], v[234:237], v[176:179], v[80:95]
	v_mfma_f32_32x32x16_bf16 v[16:31], v[234:237], v[180:183], v[16:31]
	ds_read_b128 v[234:237], v205 offset:64
	s_waitcnt lgkmcnt(5)
	v_mfma_f32_32x32x16_bf16 v[64:79], v[238:241], v[176:179], v[64:79]
	v_mfma_f32_32x32x16_bf16 v[0:15], v[238:241], v[180:183], v[0:15]
	ds_read_b128 v[238:241], v205 offset:4672
	global_load_dwordx4 v[176:179], v[184:185], off offset:2176
	global_load_dwordx4 v[180:183], v[186:187], off offset:2176
	s_waitcnt lgkmcnt(1)
	v_mfma_f32_32x32x16_bf16 v[112:127], v[234:237], v[168:171], v[112:127]
	v_mfma_f32_32x32x16_bf16 v[48:63], v[234:237], v[172:175], v[48:63]
	s_waitcnt lgkmcnt(0)
	v_mfma_f32_32x32x16_bf16 v[96:111], v[238:241], v[168:171], v[96:111]
	v_mfma_f32_32x32x16_bf16 v[32:47], v[238:241], v[172:175], v[32:47]
	ds_read_b128 v[234:237], v205 offset:9280
	ds_read_b128 v[238:241], v205 offset:13888
	s_waitcnt vmcnt(7)
	ds_write_b128 v215, v[160:163] offset:27648
	s_waitcnt vmcnt(6)
	ds_write_b128 v215, v[164:167] offset:64512
	ds_read_b128 v[160:163], v208 offset:96
	ds_read_b128 v[164:167], v208 offset:4704
	s_waitcnt lgkmcnt(5)
	v_mfma_f32_32x32x16_bf16 v[80:95], v[234:237], v[168:171], v[80:95]
	v_mfma_f32_32x32x16_bf16 v[16:31], v[234:237], v[172:175], v[16:31]
	ds_read_b128 v[234:237], v205 offset:96
	s_waitcnt lgkmcnt(5)
	v_mfma_f32_32x32x16_bf16 v[64:79], v[238:241], v[168:171], v[64:79]
	v_mfma_f32_32x32x16_bf16 v[0:15], v[238:241], v[172:175], v[0:15]
	ds_read_b128 v[238:241], v205 offset:4704
	global_load_dwordx4 v[168:171], v[198:199], off offset:2176
	global_load_dwordx4 v[172:175], v[200:201], off offset:2176
	s_waitcnt lgkmcnt(1)
	v_mfma_f32_32x32x16_bf16 v[112:127], v[234:237], v[160:163], v[112:127]
	v_mfma_f32_32x32x16_bf16 v[48:63], v[234:237], v[164:167], v[48:63]
	s_waitcnt lgkmcnt(0)
	v_mfma_f32_32x32x16_bf16 v[96:111], v[238:241], v[160:163], v[96:111]
	v_mfma_f32_32x32x16_bf16 v[32:47], v[238:241], v[164:167], v[32:47]
	ds_read_b128 v[234:237], v205 offset:9312
	ds_read_b128 v[238:241], v205 offset:13920
	s_waitcnt lgkmcnt(1)
	v_mfma_f32_32x32x16_bf16 v[80:95], v[234:237], v[160:163], v[80:95]
	v_mfma_f32_32x32x16_bf16 v[16:31], v[234:237], v[164:167], v[16:31]
	s_waitcnt lgkmcnt(0)
	v_mfma_f32_32x32x16_bf16 v[64:79], v[238:241], v[160:163], v[64:79]
	v_mfma_f32_32x32x16_bf16 v[0:15], v[238:241], v[164:167], v[0:15]
	s_setprio 0
	s_barrier
; template <bool trans>
; DI void gemm_core(const GTile& tl, const GTile& nx, bool has_next  , bool chain  , bool pre, u32x4 (&ra)[4], u32x4 (&rb)[4], char* smem, f32x16 (&acc)[2][4]) {
;     ...
;   const int nk = K / 64;
;   if (!pre) { G_LOAD(0); G_STORE(0); G_LOAD(1); }
;   for (int kt = 0; kt < nk; ++kt) {
;     __syncthreads();
;     G_COMPUTE(kt & 1, kt);
;   }
	global_load_dwordx4 v[160:163], v[190:191], off offset:2304
	global_load_dwordx4 v[164:167], v[188:189], off offset:2304
	s_waitcnt vmcnt(9)
	ds_write_b128 v209, v[218:221]
	s_waitcnt vmcnt(8)
	ds_write_b128 v210, v[222:225]
	ds_read_b128 v[218:221], v204 offset:36864
	ds_read_b128 v[222:225], v204 offset:41472
	ds_read_b128 v[234:237], v192
	ds_read_b128 v[238:241], v192 offset:4608
	s_setprio 1
	s_waitcnt lgkmcnt(1)
	v_mfma_f32_32x32x16_bf16 v[112:127], v[234:237], v[218:221], v[112:127]
	v_mfma_f32_32x32x16_bf16 v[48:63], v[234:237], v[222:225], v[48:63]
	s_waitcnt lgkmcnt(0)
	v_mfma_f32_32x32x16_bf16 v[96:111], v[238:241], v[218:221], v[96:111]
	v_mfma_f32_32x32x16_bf16 v[32:47], v[238:241], v[222:225], v[32:47]
	ds_read_b128 v[234:237], v192 offset:9216
	ds_read_b128 v[238:241], v192 offset:13824
	s_waitcnt vmcnt(7)
	ds_write_b128 v212, v[226:229]
	s_waitcnt vmcnt(6)
	ds_write_b128 v211, v[230:233]
	ds_read_b128 v[226:229], v204 offset:36896
	ds_read_b128 v[230:233], v204 offset:41504
	s_waitcnt lgkmcnt(5)
	v_mfma_f32_32x32x16_bf16 v[80:95], v[234:237], v[218:221], v[80:95]
	v_mfma_f32_32x32x16_bf16 v[16:31], v[234:237], v[222:225], v[16:31]
	ds_read_b128 v[234:237], v192 offset:32
	s_waitcnt lgkmcnt(5)
	v_mfma_f32_32x32x16_bf16 v[64:79], v[238:241], v[218:221], v[64:79]
	v_mfma_f32_32x32x16_bf16 v[0:15], v[238:241], v[222:225], v[0:15]
	ds_read_b128 v[238:241], v192 offset:4640
	global_load_dwordx4 v[218:221], v[194:195], off offset:2304
	global_load_dwordx4 v[222:225], v[196:197], off offset:2304
	s_waitcnt lgkmcnt(1)
	v_mfma_f32_32x32x16_bf16 v[112:127], v[234:237], v[226:229], v[112:127]
	v_mfma_f32_32x32x16_bf16 v[48:63], v[234:237], v[230:233], v[48:63]
	s_waitcnt lgkmcnt(0)
	v_mfma_f32_32x32x16_bf16 v[96:111], v[238:241], v[226:229], v[96:111]
	v_mfma_f32_32x32x16_bf16 v[32:47], v[238:241], v[230:233], v[32:47]
	ds_read_b128 v[234:237], v192 offset:9248
	ds_read_b128 v[238:241], v192 offset:13856
	s_waitcnt vmcnt(7)
	ds_write_b128 v214, v[176:179]
	s_waitcnt vmcnt(6)
	ds_write_b128 v213, v[180:183]
	ds_read_b128 v[176:179], v204 offset:36928
	ds_read_b128 v[180:183], v204 offset:41536
	s_waitcnt lgkmcnt(5)
	v_mfma_f32_32x32x16_bf16 v[80:95], v[234:237], v[226:229], v[80:95]
	v_mfma_f32_32x32x16_bf16 v[16:31], v[234:237], v[230:233], v[16:31]
	ds_read_b128 v[234:237], v192 offset:64
	s_waitcnt lgkmcnt(5)
	v_mfma_f32_32x32x16_bf16 v[64:79], v[238:241], v[226:229], v[64:79]
	v_mfma_f32_32x32x16_bf16 v[0:15], v[238:241], v[230:233], v[0:15]
	ds_read_b128 v[238:241], v192 offset:4672
	global_load_dwordx4 v[226:229], v[184:185], off offset:2304
	global_load_dwordx4 v[230:233], v[186:187], off offset:2304
	s_waitcnt lgkmcnt(1)
	v_mfma_f32_32x32x16_bf16 v[112:127], v[234:237], v[176:179], v[112:127]
	v_mfma_f32_32x32x16_bf16 v[48:63], v[234:237], v[180:183], v[48:63]
	s_waitcnt lgkmcnt(0)
	v_mfma_f32_32x32x16_bf16 v[96:111], v[238:241], v[176:179], v[96:111]
	v_mfma_f32_32x32x16_bf16 v[32:47], v[238:241], v[180:183], v[32:47]
	ds_read_b128 v[234:237], v192 offset:9280
	ds_read_b128 v[238:241], v192 offset:13888
	s_waitcnt vmcnt(7)
	ds_write_b128 v217, v[168:171]
	s_waitcnt vmcnt(6)
	ds_write_b128 v216, v[172:175]
	ds_read_b128 v[168:171], v204 offset:36960
	ds_read_b128 v[172:175], v204 offset:41568
	s_waitcnt lgkmcnt(5)
	v_mfma_f32_32x32x16_bf16 v[80:95], v[234:237], v[176:179], v[80:95]
	v_mfma_f32_32x32x16_bf16 v[16:31], v[234:237], v[180:183], v[16:31]
	ds_read_b128 v[234:237], v192 offset:96
	s_waitcnt lgkmcnt(5)
	v_mfma_f32_32x32x16_bf16 v[64:79], v[238:241], v[176:179], v[64:79]
	v_mfma_f32_32x32x16_bf16 v[0:15], v[238:241], v[180:183], v[0:15]
	ds_read_b128 v[238:241], v192 offset:4704
	global_load_dwordx4 v[176:179], v[198:199], off offset:2304
	global_load_dwordx4 v[180:183], v[200:201], off offset:2304
	s_waitcnt lgkmcnt(1)
	v_mfma_f32_32x32x16_bf16 v[112:127], v[234:237], v[168:171], v[112:127]
	v_mfma_f32_32x32x16_bf16 v[48:63], v[234:237], v[172:175], v[48:63]
	s_waitcnt lgkmcnt(0)
	v_mfma_f32_32x32x16_bf16 v[96:111], v[238:241], v[168:171], v[96:111]
	v_mfma_f32_32x32x16_bf16 v[32:47], v[238:241], v[172:175], v[32:47]
	ds_read_b128 v[234:237], v192 offset:9312
	ds_read_b128 v[238:241], v192 offset:13920
	s_waitcnt lgkmcnt(1)
	v_mfma_f32_32x32x16_bf16 v[80:95], v[234:237], v[168:171], v[80:95]
	v_mfma_f32_32x32x16_bf16 v[16:31], v[234:237], v[172:175], v[16:31]
	s_waitcnt lgkmcnt(0)
	v_mfma_f32_32x32x16_bf16 v[64:79], v[238:241], v[168:171], v[64:79]
	v_mfma_f32_32x32x16_bf16 v[0:15], v[238:241], v[172:175], v[0:15]
	s_setprio 0
	s_barrier
; template <bool trans>
; DI void gemm_core(const GTile& tl, const GTile& nx, bool has_next  , bool chain  , bool pre, u32x4 (&ra)[4], u32x4 (&rb)[4], char* smem, f32x16 (&acc)[2][4]) {
;     ...
;   const int nk = K / 64;
;   if (!pre) { G_LOAD(0); G_STORE(0); G_LOAD(1); }
;   for (int kt = 0; kt < nk; ++kt) {
;     __syncthreads();
;     G_COMPUTE(kt & 1, kt);
;   }
	global_load_dwordx4 v[168:171], v[190:191], off offset:2432
	global_load_dwordx4 v[172:175], v[188:189], off offset:2432
	s_waitcnt vmcnt(9)
	ds_write_b128 v215, v[160:163]
	s_waitcnt vmcnt(8)
	ds_write_b128 v215, v[164:167] offset:36864
	ds_read_b128 v[160:163], v208
	ds_read_b128 v[164:167], v208 offset:4608
	ds_read_b128 v[234:237], v205
	ds_read_b128 v[238:241], v205 offset:4608
	s_setprio 1
	s_waitcnt lgkmcnt(1)
	v_mfma_f32_32x32x16_bf16 v[112:127], v[234:237], v[160:163], v[112:127]
	v_mfma_f32_32x32x16_bf16 v[48:63], v[234:237], v[164:167], v[48:63]
	s_waitcnt lgkmcnt(0)
	v_mfma_f32_32x32x16_bf16 v[96:111], v[238:241], v[160:163], v[96:111]
	v_mfma_f32_32x32x16_bf16 v[32:47], v[238:241], v[164:167], v[32:47]
	ds_read_b128 v[234:237], v205 offset:9216
	ds_read_b128 v[238:241], v205 offset:13824
	s_waitcnt vmcnt(7)
	ds_write_b128 v215, v[218:221] offset:9216
	s_waitcnt vmcnt(6)
	ds_write_b128 v215, v[222:225] offset:46080
	ds_read_b128 v[218:221], v208 offset:32
	ds_read_b128 v[222:225], v208 offset:4640
	s_waitcnt lgkmcnt(5)
	v_mfma_f32_32x32x16_bf16 v[80:95], v[234:237], v[160:163], v[80:95]
	v_mfma_f32_32x32x16_bf16 v[16:31], v[234:237], v[164:167], v[16:31]
	ds_read_b128 v[234:237], v205 offset:32
	s_waitcnt lgkmcnt(5)
	v_mfma_f32_32x32x16_bf16 v[64:79], v[238:241], v[160:163], v[64:79]
	v_mfma_f32_32x32x16_bf16 v[0:15], v[238:241], v[164:167], v[0:15]
	ds_read_b128 v[238:241], v205 offset:4640
	global_load_dwordx4 v[160:163], v[194:195], off offset:2432
	global_load_dwordx4 v[164:167], v[196:197], off offset:2432
	s_waitcnt lgkmcnt(1)
	v_mfma_f32_32x32x16_bf16 v[112:127], v[234:237], v[218:221], v[112:127]
	v_mfma_f32_32x32x16_bf16 v[48:63], v[234:237], v[222:225], v[48:63]
	s_waitcnt lgkmcnt(0)
	v_mfma_f32_32x32x16_bf16 v[96:111], v[238:241], v[218:221], v[96:111]
	v_mfma_f32_32x32x16_bf16 v[32:47], v[238:241], v[222:225], v[32:47]
	ds_read_b128 v[234:237], v205 offset:9248
	ds_read_b128 v[238:241], v205 offset:13856
	s_waitcnt vmcnt(7)
	ds_write_b128 v215, v[226:229] offset:18432
	s_waitcnt vmcnt(6)
	ds_write_b128 v215, v[230:233] offset:55296
	ds_read_b128 v[226:229], v208 offset:64
	ds_read_b128 v[230:233], v208 offset:4672
	s_waitcnt lgkmcnt(5)
	v_mfma_f32_32x32x16_bf16 v[80:95], v[234:237], v[218:221], v[80:95]
	v_mfma_f32_32x32x16_bf16 v[16:31], v[234:237], v[222:225], v[16:31]
	ds_read_b128 v[234:237], v205 offset:64
	s_waitcnt lgkmcnt(5)
	v_mfma_f32_32x32x16_bf16 v[64:79], v[238:241], v[218:221], v[64:79]
	v_mfma_f32_32x32x16_bf16 v[0:15], v[238:241], v[222:225], v[0:15]
	ds_read_b128 v[238:241], v205 offset:4672
	global_load_dwordx4 v[218:221], v[184:185], off offset:2432
	global_load_dwordx4 v[222:225], v[186:187], off offset:2432
	s_waitcnt lgkmcnt(1)
	v_mfma_f32_32x32x16_bf16 v[112:127], v[234:237], v[226:229], v[112:127]
	v_mfma_f32_32x32x16_bf16 v[48:63], v[234:237], v[230:233], v[48:63]
	s_waitcnt lgkmcnt(0)
	v_mfma_f32_32x32x16_bf16 v[96:111], v[238:241], v[226:229], v[96:111]
	v_mfma_f32_32x32x16_bf16 v[32:47], v[238:241], v[230:233], v[32:47]
	ds_read_b128 v[234:237], v205 offset:9280
	ds_read_b128 v[238:241], v205 offset:13888
	s_waitcnt vmcnt(7)
	ds_write_b128 v215, v[176:179] offset:27648
	s_waitcnt vmcnt(6)
	ds_write_b128 v215, v[180:183] offset:64512
	ds_read_b128 v[176:179], v208 offset:96
	ds_read_b128 v[180:183], v208 offset:4704
	s_waitcnt lgkmcnt(5)
	v_mfma_f32_32x32x16_bf16 v[80:95], v[234:237], v[226:229], v[80:95]
	v_mfma_f32_32x32x16_bf16 v[16:31], v[234:237], v[230:233], v[16:31]
	ds_read_b128 v[234:237], v205 offset:96
	s_waitcnt lgkmcnt(5)
	v_mfma_f32_32x32x16_bf16 v[64:79], v[238:241], v[226:229], v[64:79]
	v_mfma_f32_32x32x16_bf16 v[0:15], v[238:241], v[230:233], v[0:15]
	ds_read_b128 v[238:241], v205 offset:4704
	global_load_dwordx4 v[226:229], v[198:199], off offset:2432
	global_load_dwordx4 v[230:233], v[200:201], off offset:2432
	s_waitcnt lgkmcnt(1)
	v_mfma_f32_32x32x16_bf16 v[112:127], v[234:237], v[176:179], v[112:127]
	v_mfma_f32_32x32x16_bf16 v[48:63], v[234:237], v[180:183], v[48:63]
	s_waitcnt lgkmcnt(0)
	v_mfma_f32_32x32x16_bf16 v[96:111], v[238:241], v[176:179], v[96:111]
	v_mfma_f32_32x32x16_bf16 v[32:47], v[238:241], v[180:183], v[32:47]
	ds_read_b128 v[234:237], v205 offset:9312
	ds_read_b128 v[238:241], v205 offset:13920
	s_waitcnt lgkmcnt(1)
	v_mfma_f32_32x32x16_bf16 v[80:95], v[234:237], v[176:179], v[80:95]
	v_mfma_f32_32x32x16_bf16 v[16:31], v[234:237], v[180:183], v[16:31]
	s_waitcnt lgkmcnt(0)
	v_mfma_f32_32x32x16_bf16 v[64:79], v[238:241], v[176:179], v[64:79]
	v_mfma_f32_32x32x16_bf16 v[0:15], v[238:241], v[180:183], v[0:15]
	s_setprio 0
	s_barrier
; template <bool trans>
; DI void gemm_core(const GTile& tl, const GTile& nx, bool has_next  , bool chain  , bool pre, u32x4 (&ra)[4], u32x4 (&rb)[4], char* smem, f32x16 (&acc)[2][4]) {
;     ...
;   const int nk = K / 64;
;   if (!pre) { G_LOAD(0); G_STORE(0); G_LOAD(1); }
;   for (int kt = 0; kt < nk; ++kt) {
;     __syncthreads();
;     G_COMPUTE(kt & 1, kt);
;   }
	global_load_dwordx4 v[176:179], v[190:191], off offset:2560
	global_load_dwordx4 v[180:183], v[188:189], off offset:2560
	s_waitcnt vmcnt(9)
	ds_write_b128 v209, v[168:171]
	s_waitcnt vmcnt(8)
	ds_write_b128 v210, v[172:175]
	ds_read_b128 v[168:171], v204 offset:36864
	ds_read_b128 v[172:175], v204 offset:41472
	ds_read_b128 v[234:237], v192
	ds_read_b128 v[238:241], v192 offset:4608
	s_setprio 1
	s_waitcnt lgkmcnt(1)
	v_mfma_f32_32x32x16_bf16 v[112:127], v[234:237], v[168:171], v[112:127]
	v_mfma_f32_32x32x16_bf16 v[48:63], v[234:237], v[172:175], v[48:63]
	s_waitcnt lgkmcnt(0)
	v_mfma_f32_32x32x16_bf16 v[96:111], v[238:241], v[168:171], v[96:111]
	v_mfma_f32_32x32x16_bf16 v[32:47], v[238:241], v[172:175], v[32:47]
	ds_read_b128 v[234:237], v192 offset:9216
	ds_read_b128 v[238:241], v192 offset:13824
	s_waitcnt vmcnt(7)
	ds_write_b128 v212, v[160:163]
	s_waitcnt vmcnt(6)
	ds_write_b128 v211, v[164:167]
	ds_read_b128 v[160:163], v204 offset:36896
	ds_read_b128 v[164:167], v204 offset:41504
	s_waitcnt lgkmcnt(5)
	v_mfma_f32_32x32x16_bf16 v[80:95], v[234:237], v[168:171], v[80:95]
	v_mfma_f32_32x32x16_bf16 v[16:31], v[234:237], v[172:175], v[16:31]
	ds_read_b128 v[234:237], v192 offset:32
	s_waitcnt lgkmcnt(5)
	v_mfma_f32_32x32x16_bf16 v[64:79], v[238:241], v[168:171], v[64:79]
	v_mfma_f32_32x32x16_bf16 v[0:15], v[238:241], v[172:175], v[0:15]
	ds_read_b128 v[238:241], v192 offset:4640
	global_load_dwordx4 v[168:171], v[194:195], off offset:2560
	global_load_dwordx4 v[172:175], v[196:197], off offset:2560
	s_waitcnt lgkmcnt(1)
	v_mfma_f32_32x32x16_bf16 v[112:127], v[234:237], v[160:163], v[112:127]
	v_mfma_f32_32x32x16_bf16 v[48:63], v[234:237], v[164:167], v[48:63]
	s_waitcnt lgkmcnt(0)
	v_mfma_f32_32x32x16_bf16 v[96:111], v[238:241], v[160:163], v[96:111]
	v_mfma_f32_32x32x16_bf16 v[32:47], v[238:241], v[164:167], v[32:47]
	ds_read_b128 v[234:237], v192 offset:9248
	ds_read_b128 v[238:241], v192 offset:13856
	s_waitcnt vmcnt(7)
	ds_write_b128 v214, v[218:221]
	s_waitcnt vmcnt(6)
	ds_write_b128 v213, v[222:225]
	ds_read_b128 v[218:221], v204 offset:36928
	ds_read_b128 v[222:225], v204 offset:41536
	s_waitcnt lgkmcnt(5)
	v_mfma_f32_32x32x16_bf16 v[80:95], v[234:237], v[160:163], v[80:95]
	v_mfma_f32_32x32x16_bf16 v[16:31], v[234:237], v[164:167], v[16:31]
	ds_read_b128 v[234:237], v192 offset:64
	s_waitcnt lgkmcnt(5)
	v_mfma_f32_32x32x16_bf16 v[64:79], v[238:241], v[160:163], v[64:79]
	v_mfma_f32_32x32x16_bf16 v[0:15], v[238:241], v[164:167], v[0:15]
	ds_read_b128 v[238:241], v192 offset:4672
	global_load_dwordx4 v[160:163], v[184:185], off offset:2560
	global_load_dwordx4 v[164:167], v[186:187], off offset:2560
	s_waitcnt lgkmcnt(1)
	v_mfma_f32_32x32x16_bf16 v[112:127], v[234:237], v[218:221], v[112:127]
	v_mfma_f32_32x32x16_bf16 v[48:63], v[234:237], v[222:225], v[48:63]
	s_waitcnt lgkmcnt(0)
	v_mfma_f32_32x32x16_bf16 v[96:111], v[238:241], v[218:221], v[96:111]
	v_mfma_f32_32x32x16_bf16 v[32:47], v[238:241], v[222:225], v[32:47]
	ds_read_b128 v[234:237], v192 offset:9280
	ds_read_b128 v[238:241], v192 offset:13888
	s_waitcnt vmcnt(7)
	ds_write_b128 v217, v[226:229]
	s_waitcnt vmcnt(6)
	ds_write_b128 v216, v[230:233]
	ds_read_b128 v[226:229], v204 offset:36960
	ds_read_b128 v[230:233], v204 offset:41568
	s_waitcnt lgkmcnt(5)
	v_mfma_f32_32x32x16_bf16 v[80:95], v[234:237], v[218:221], v[80:95]
	v_mfma_f32_32x32x16_bf16 v[16:31], v[234:237], v[222:225], v[16:31]
	ds_read_b128 v[234:237], v192 offset:96
	s_waitcnt lgkmcnt(5)
	v_mfma_f32_32x32x16_bf16 v[64:79], v[238:241], v[218:221], v[64:79]
	v_mfma_f32_32x32x16_bf16 v[0:15], v[238:241], v[222:225], v[0:15]
	ds_read_b128 v[238:241], v192 offset:4704
	global_load_dwordx4 v[218:221], v[198:199], off offset:2560
	global_load_dwordx4 v[222:225], v[200:201], off offset:2560
	s_waitcnt lgkmcnt(1)
	v_mfma_f32_32x32x16_bf16 v[112:127], v[234:237], v[226:229], v[112:127]
	v_mfma_f32_32x32x16_bf16 v[48:63], v[234:237], v[230:233], v[48:63]
	s_waitcnt lgkmcnt(0)
	v_mfma_f32_32x32x16_bf16 v[96:111], v[238:241], v[226:229], v[96:111]
	v_mfma_f32_32x32x16_bf16 v[32:47], v[238:241], v[230:233], v[32:47]
	ds_read_b128 v[234:237], v192 offset:9312
	ds_read_b128 v[238:241], v192 offset:13920
	s_waitcnt lgkmcnt(1)
	v_mfma_f32_32x32x16_bf16 v[80:95], v[234:237], v[226:229], v[80:95]
	v_mfma_f32_32x32x16_bf16 v[16:31], v[234:237], v[230:233], v[16:31]
	s_waitcnt lgkmcnt(0)
	v_mfma_f32_32x32x16_bf16 v[64:79], v[238:241], v[226:229], v[64:79]
	v_mfma_f32_32x32x16_bf16 v[0:15], v[238:241], v[230:233], v[0:15]
	s_setprio 0
	s_barrier
; template <bool trans>
; DI void gemm_core(const GTile& tl, const GTile& nx, bool has_next  , bool chain  , bool pre, u32x4 (&ra)[4], u32x4 (&rb)[4], char* smem, f32x16 (&acc)[2][4]) {
;     ...
;   const int nk = K / 64;
;   if (!pre) { G_LOAD(0); G_STORE(0); G_LOAD(1); }
;   for (int kt = 0; kt < nk; ++kt) {
;     __syncthreads();
;     G_COMPUTE(kt & 1, kt);
;   }
	global_load_dwordx4 v[226:229], v[190:191], off offset:2688
	global_load_dwordx4 v[230:233], v[188:189], off offset:2688
	s_waitcnt vmcnt(9)
	ds_write_b128 v215, v[176:179]
	s_waitcnt vmcnt(8)
	ds_write_b128 v215, v[180:183] offset:36864
	ds_read_b128 v[176:179], v208
	ds_read_b128 v[180:183], v208 offset:4608
	ds_read_b128 v[234:237], v205
	ds_read_b128 v[238:241], v205 offset:4608
	s_setprio 1
	s_waitcnt lgkmcnt(1)
	v_mfma_f32_32x32x16_bf16 v[112:127], v[234:237], v[176:179], v[112:127]
	v_mfma_f32_32x32x16_bf16 v[48:63], v[234:237], v[180:183], v[48:63]
	s_waitcnt lgkmcnt(0)
	v_mfma_f32_32x32x16_bf16 v[96:111], v[238:241], v[176:179], v[96:111]
	v_mfma_f32_32x32x16_bf16 v[32:47], v[238:241], v[180:183], v[32:47]
	ds_read_b128 v[234:237], v205 offset:9216
	ds_read_b128 v[238:241], v205 offset:13824
	s_waitcnt vmcnt(7)
	ds_write_b128 v215, v[168:171] offset:9216
	s_waitcnt vmcnt(6)
	ds_write_b128 v215, v[172:175] offset:46080
	ds_read_b128 v[168:171], v208 offset:32
	ds_read_b128 v[172:175], v208 offset:4640
	s_waitcnt lgkmcnt(5)
	v_mfma_f32_32x32x16_bf16 v[80:95], v[234:237], v[176:179], v[80:95]
	v_mfma_f32_32x32x16_bf16 v[16:31], v[234:237], v[180:183], v[16:31]
	ds_read_b128 v[234:237], v205 offset:32
	s_waitcnt lgkmcnt(5)
	v_mfma_f32_32x32x16_bf16 v[64:79], v[238:241], v[176:179], v[64:79]
	v_mfma_f32_32x32x16_bf16 v[0:15], v[238:241], v[180:183], v[0:15]
	ds_read_b128 v[238:241], v205 offset:4640
	global_load_dwordx4 v[176:179], v[194:195], off offset:2688
	global_load_dwordx4 v[180:183], v[196:197], off offset:2688
	s_waitcnt lgkmcnt(1)
	v_mfma_f32_32x32x16_bf16 v[112:127], v[234:237], v[168:171], v[112:127]
	v_mfma_f32_32x32x16_bf16 v[48:63], v[234:237], v[172:175], v[48:63]
	s_waitcnt lgkmcnt(0)
	v_mfma_f32_32x32x16_bf16 v[96:111], v[238:241], v[168:171], v[96:111]
	v_mfma_f32_32x32x16_bf16 v[32:47], v[238:241], v[172:175], v[32:47]
	ds_read_b128 v[234:237], v205 offset:9248
	ds_read_b128 v[238:241], v205 offset:13856
	s_waitcnt vmcnt(7)
	ds_write_b128 v215, v[160:163] offset:18432
	s_waitcnt vmcnt(6)
	ds_write_b128 v215, v[164:167] offset:55296
	ds_read_b128 v[160:163], v208 offset:64
	ds_read_b128 v[164:167], v208 offset:4672
	s_waitcnt lgkmcnt(5)
	v_mfma_f32_32x32x16_bf16 v[80:95], v[234:237], v[168:171], v[80:95]
	v_mfma_f32_32x32x16_bf16 v[16:31], v[234:237], v[172:175], v[16:31]
	ds_read_b128 v[234:237], v205 offset:64
	s_waitcnt lgkmcnt(5)
	v_mfma_f32_32x32x16_bf16 v[64:79], v[238:241], v[168:171], v[64:79]
	v_mfma_f32_32x32x16_bf16 v[0:15], v[238:241], v[172:175], v[0:15]
	ds_read_b128 v[238:241], v205 offset:4672
	global_load_dwordx4 v[168:171], v[184:185], off offset:2688
	global_load_dwordx4 v[172:175], v[186:187], off offset:2688
	s_waitcnt lgkmcnt(1)
	v_mfma_f32_32x32x16_bf16 v[112:127], v[234:237], v[160:163], v[112:127]
	v_mfma_f32_32x32x16_bf16 v[48:63], v[234:237], v[164:167], v[48:63]
	s_waitcnt lgkmcnt(0)
	v_mfma_f32_32x32x16_bf16 v[96:111], v[238:241], v[160:163], v[96:111]
	v_mfma_f32_32x32x16_bf16 v[32:47], v[238:241], v[164:167], v[32:47]
	ds_read_b128 v[234:237], v205 offset:9280
	ds_read_b128 v[238:241], v205 offset:13888
	s_waitcnt vmcnt(7)
	ds_write_b128 v215, v[218:221] offset:27648
	s_waitcnt vmcnt(6)
	ds_write_b128 v215, v[222:225] offset:64512
	ds_read_b128 v[218:221], v208 offset:96
	ds_read_b128 v[222:225], v208 offset:4704
	s_waitcnt lgkmcnt(5)
	v_mfma_f32_32x32x16_bf16 v[80:95], v[234:237], v[160:163], v[80:95]
	v_mfma_f32_32x32x16_bf16 v[16:31], v[234:237], v[164:167], v[16:31]
	ds_read_b128 v[234:237], v205 offset:96
	s_waitcnt lgkmcnt(5)
	v_mfma_f32_32x32x16_bf16 v[64:79], v[238:241], v[160:163], v[64:79]
	v_mfma_f32_32x32x16_bf16 v[0:15], v[238:241], v[164:167], v[0:15]
	ds_read_b128 v[238:241], v205 offset:4704
	global_load_dwordx4 v[160:163], v[198:199], off offset:2688
	global_load_dwordx4 v[164:167], v[200:201], off offset:2688
	s_waitcnt lgkmcnt(1)
	v_mfma_f32_32x32x16_bf16 v[112:127], v[234:237], v[218:221], v[112:127]
	v_mfma_f32_32x32x16_bf16 v[48:63], v[234:237], v[222:225], v[48:63]
	s_waitcnt lgkmcnt(0)
	v_mfma_f32_32x32x16_bf16 v[96:111], v[238:241], v[218:221], v[96:111]
	v_mfma_f32_32x32x16_bf16 v[32:47], v[238:241], v[222:225], v[32:47]
	ds_read_b128 v[234:237], v205 offset:9312
	ds_read_b128 v[238:241], v205 offset:13920
	s_waitcnt lgkmcnt(1)
	v_mfma_f32_32x32x16_bf16 v[80:95], v[234:237], v[218:221], v[80:95]
	v_mfma_f32_32x32x16_bf16 v[16:31], v[234:237], v[222:225], v[16:31]
	s_waitcnt lgkmcnt(0)
	v_mfma_f32_32x32x16_bf16 v[64:79], v[238:241], v[218:221], v[64:79]
	v_mfma_f32_32x32x16_bf16 v[0:15], v[238:241], v[222:225], v[0:15]
	s_setprio 0
	s_barrier
; template <bool trans>
; DI void gemm_core(const GTile& tl, const GTile& nx, bool has_next  , bool chain  , bool pre, u32x4 (&ra)[4], u32x4 (&rb)[4], char* smem, f32x16 (&acc)[2][4]) {
;     ...
;   const int nk = K / 64;
;   if (!pre) { G_LOAD(0); G_STORE(0); G_LOAD(1); }
;   for (int kt = 0; kt < nk; ++kt) {
;     __syncthreads();
;     G_COMPUTE(kt & 1, kt);
;   }
	global_load_dwordx4 v[218:221], v[190:191], off offset:2816
	global_load_dwordx4 v[222:225], v[188:189], off offset:2816
	s_waitcnt vmcnt(9)
	ds_write_b128 v209, v[226:229]
	s_waitcnt vmcnt(8)
	ds_write_b128 v210, v[230:233]
	ds_read_b128 v[226:229], v204 offset:36864
	ds_read_b128 v[230:233], v204 offset:41472
	ds_read_b128 v[234:237], v192
	ds_read_b128 v[238:241], v192 offset:4608
	s_setprio 1
	s_waitcnt lgkmcnt(1)
	v_mfma_f32_32x32x16_bf16 v[112:127], v[234:237], v[226:229], v[112:127]
	v_mfma_f32_32x32x16_bf16 v[48:63], v[234:237], v[230:233], v[48:63]
	s_waitcnt lgkmcnt(0)
	v_mfma_f32_32x32x16_bf16 v[96:111], v[238:241], v[226:229], v[96:111]
	v_mfma_f32_32x32x16_bf16 v[32:47], v[238:241], v[230:233], v[32:47]
	ds_read_b128 v[234:237], v192 offset:9216
	ds_read_b128 v[238:241], v192 offset:13824
	s_waitcnt vmcnt(7)
	ds_write_b128 v212, v[176:179]
	s_waitcnt vmcnt(6)
	ds_write_b128 v211, v[180:183]
	ds_read_b128 v[176:179], v204 offset:36896
	ds_read_b128 v[180:183], v204 offset:41504
	s_waitcnt lgkmcnt(5)
	v_mfma_f32_32x32x16_bf16 v[80:95], v[234:237], v[226:229], v[80:95]
	v_mfma_f32_32x32x16_bf16 v[16:31], v[234:237], v[230:233], v[16:31]
	ds_read_b128 v[234:237], v192 offset:32
	s_waitcnt lgkmcnt(5)
	v_mfma_f32_32x32x16_bf16 v[64:79], v[238:241], v[226:229], v[64:79]
	v_mfma_f32_32x32x16_bf16 v[0:15], v[238:241], v[230:233], v[0:15]
	ds_read_b128 v[238:241], v192 offset:4640
	global_load_dwordx4 v[226:229], v[194:195], off offset:2816
	global_load_dwordx4 v[230:233], v[196:197], off offset:2816
	s_waitcnt lgkmcnt(1)
	v_mfma_f32_32x32x16_bf16 v[112:127], v[234:237], v[176:179], v[112:127]
	v_mfma_f32_32x32x16_bf16 v[48:63], v[234:237], v[180:183], v[48:63]
	s_waitcnt lgkmcnt(0)
	v_mfma_f32_32x32x16_bf16 v[96:111], v[238:241], v[176:179], v[96:111]
	v_mfma_f32_32x32x16_bf16 v[32:47], v[238:241], v[180:183], v[32:47]
	ds_read_b128 v[234:237], v192 offset:9248
	ds_read_b128 v[238:241], v192 offset:13856
	s_waitcnt vmcnt(7)
	ds_write_b128 v214, v[168:171]
	s_waitcnt vmcnt(6)
	ds_write_b128 v213, v[172:175]
	ds_read_b128 v[168:171], v204 offset:36928
	ds_read_b128 v[172:175], v204 offset:41536
	s_waitcnt lgkmcnt(5)
	v_mfma_f32_32x32x16_bf16 v[80:95], v[234:237], v[176:179], v[80:95]
	v_mfma_f32_32x32x16_bf16 v[16:31], v[234:237], v[180:183], v[16:31]
	ds_read_b128 v[234:237], v192 offset:64
	s_waitcnt lgkmcnt(5)
	v_mfma_f32_32x32x16_bf16 v[64:79], v[238:241], v[176:179], v[64:79]
	v_mfma_f32_32x32x16_bf16 v[0:15], v[238:241], v[180:183], v[0:15]
	ds_read_b128 v[238:241], v192 offset:4672
	global_load_dwordx4 v[176:179], v[184:185], off offset:2816
	global_load_dwordx4 v[180:183], v[186:187], off offset:2816
	s_waitcnt lgkmcnt(1)
	v_mfma_f32_32x32x16_bf16 v[112:127], v[234:237], v[168:171], v[112:127]
	v_mfma_f32_32x32x16_bf16 v[48:63], v[234:237], v[172:175], v[48:63]
	s_waitcnt lgkmcnt(0)
	v_mfma_f32_32x32x16_bf16 v[96:111], v[238:241], v[168:171], v[96:111]
	v_mfma_f32_32x32x16_bf16 v[32:47], v[238:241], v[172:175], v[32:47]
	ds_read_b128 v[234:237], v192 offset:9280
	ds_read_b128 v[238:241], v192 offset:13888
	s_waitcnt vmcnt(7)
	ds_write_b128 v217, v[160:163]
	s_waitcnt vmcnt(6)
	ds_write_b128 v216, v[164:167]
	ds_read_b128 v[160:163], v204 offset:36960
	ds_read_b128 v[164:167], v204 offset:41568
	s_waitcnt lgkmcnt(5)
	v_mfma_f32_32x32x16_bf16 v[80:95], v[234:237], v[168:171], v[80:95]
	v_mfma_f32_32x32x16_bf16 v[16:31], v[234:237], v[172:175], v[16:31]
	ds_read_b128 v[234:237], v192 offset:96
	s_waitcnt lgkmcnt(5)
	v_mfma_f32_32x32x16_bf16 v[64:79], v[238:241], v[168:171], v[64:79]
	v_mfma_f32_32x32x16_bf16 v[0:15], v[238:241], v[172:175], v[0:15]
	ds_read_b128 v[238:241], v192 offset:4704
	global_load_dwordx4 v[168:171], v[198:199], off offset:2816
	global_load_dwordx4 v[172:175], v[200:201], off offset:2816
	s_waitcnt lgkmcnt(1)
	v_mfma_f32_32x32x16_bf16 v[112:127], v[234:237], v[160:163], v[112:127]
	v_mfma_f32_32x32x16_bf16 v[48:63], v[234:237], v[164:167], v[48:63]
	s_waitcnt lgkmcnt(0)
	v_mfma_f32_32x32x16_bf16 v[96:111], v[238:241], v[160:163], v[96:111]
	v_mfma_f32_32x32x16_bf16 v[32:47], v[238:241], v[164:167], v[32:47]
	ds_read_b128 v[234:237], v192 offset:9312
	ds_read_b128 v[238:241], v192 offset:13920
	s_waitcnt lgkmcnt(1)
	v_mfma_f32_32x32x16_bf16 v[80:95], v[234:237], v[160:163], v[80:95]
	v_mfma_f32_32x32x16_bf16 v[16:31], v[234:237], v[164:167], v[16:31]
	s_waitcnt lgkmcnt(0)
	v_mfma_f32_32x32x16_bf16 v[64:79], v[238:241], v[160:163], v[64:79]
	v_mfma_f32_32x32x16_bf16 v[0:15], v[238:241], v[164:167], v[0:15]
	s_setprio 0
	s_barrier
; template <bool trans>
; DI void gemm_core(const GTile& tl, const GTile& nx, bool has_next  , bool chain  , bool pre, u32x4 (&ra)[4], u32x4 (&rb)[4], char* smem, f32x16 (&acc)[2][4]) {
;     ...
;   const int nk = K / 64;
;   if (!pre) { G_LOAD(0); G_STORE(0); G_LOAD(1); }
;   for (int kt = 0; kt < nk; ++kt) {
;     __syncthreads();
;     G_COMPUTE(kt & 1, kt);
;   }
	global_load_dwordx4 v[160:163], v[190:191], off offset:2944
	global_load_dwordx4 v[164:167], v[188:189], off offset:2944
	s_waitcnt vmcnt(9)
	ds_write_b128 v215, v[218:221]
	s_waitcnt vmcnt(8)
	ds_write_b128 v215, v[222:225] offset:36864
	ds_read_b128 v[218:221], v208
	ds_read_b128 v[222:225], v208 offset:4608
	ds_read_b128 v[234:237], v205
	ds_read_b128 v[238:241], v205 offset:4608
	s_setprio 1
	s_waitcnt lgkmcnt(1)
	v_mfma_f32_32x32x16_bf16 v[112:127], v[234:237], v[218:221], v[112:127]
	v_mfma_f32_32x32x16_bf16 v[48:63], v[234:237], v[222:225], v[48:63]
	s_waitcnt lgkmcnt(0)
	v_mfma_f32_32x32x16_bf16 v[96:111], v[238:241], v[218:221], v[96:111]
	v_mfma_f32_32x32x16_bf16 v[32:47], v[238:241], v[222:225], v[32:47]
	ds_read_b128 v[234:237], v205 offset:9216
	ds_read_b128 v[238:241], v205 offset:13824
	s_waitcnt vmcnt(7)
	ds_write_b128 v215, v[226:229] offset:9216
	s_waitcnt vmcnt(6)
	ds_write_b128 v215, v[230:233] offset:46080
	ds_read_b128 v[226:229], v208 offset:32
	ds_read_b128 v[230:233], v208 offset:4640
	s_waitcnt lgkmcnt(5)
	v_mfma_f32_32x32x16_bf16 v[80:95], v[234:237], v[218:221], v[80:95]
	v_mfma_f32_32x32x16_bf16 v[16:31], v[234:237], v[222:225], v[16:31]
	ds_read_b128 v[234:237], v205 offset:32
	s_waitcnt lgkmcnt(5)
	v_mfma_f32_32x32x16_bf16 v[64:79], v[238:241], v[218:221], v[64:79]
	v_mfma_f32_32x32x16_bf16 v[0:15], v[238:241], v[222:225], v[0:15]
	ds_read_b128 v[238:241], v205 offset:4640
	global_load_dwordx4 v[218:221], v[194:195], off offset:2944
	global_load_dwordx4 v[222:225], v[196:197], off offset:2944
	s_waitcnt lgkmcnt(1)
	v_mfma_f32_32x32x16_bf16 v[112:127], v[234:237], v[226:229], v[112:127]
	v_mfma_f32_32x32x16_bf16 v[48:63], v[234:237], v[230:233], v[48:63]
	s_waitcnt lgkmcnt(0)
	v_mfma_f32_32x32x16_bf16 v[96:111], v[238:241], v[226:229], v[96:111]
	v_mfma_f32_32x32x16_bf16 v[32:47], v[238:241], v[230:233], v[32:47]
	ds_read_b128 v[234:237], v205 offset:9248
	ds_read_b128 v[238:241], v205 offset:13856
	s_waitcnt vmcnt(7)
	ds_write_b128 v215, v[176:179] offset:18432
	s_waitcnt vmcnt(6)
	ds_write_b128 v215, v[180:183] offset:55296
	ds_read_b128 v[176:179], v208 offset:64
	ds_read_b128 v[180:183], v208 offset:4672
	s_waitcnt lgkmcnt(5)
	v_mfma_f32_32x32x16_bf16 v[80:95], v[234:237], v[226:229], v[80:95]
	v_mfma_f32_32x32x16_bf16 v[16:31], v[234:237], v[230:233], v[16:31]
	ds_read_b128 v[234:237], v205 offset:64
	s_waitcnt lgkmcnt(5)
	v_mfma_f32_32x32x16_bf16 v[64:79], v[238:241], v[226:229], v[64:79]
	v_mfma_f32_32x32x16_bf16 v[0:15], v[238:241], v[230:233], v[0:15]
	ds_read_b128 v[238:241], v205 offset:4672
	global_load_dwordx4 v[226:229], v[184:185], off offset:2944
	global_load_dwordx4 v[230:233], v[186:187], off offset:2944
	s_waitcnt lgkmcnt(1)
	v_mfma_f32_32x32x16_bf16 v[112:127], v[234:237], v[176:179], v[112:127]
	v_mfma_f32_32x32x16_bf16 v[48:63], v[234:237], v[180:183], v[48:63]
	s_waitcnt lgkmcnt(0)
	v_mfma_f32_32x32x16_bf16 v[96:111], v[238:241], v[176:179], v[96:111]
	v_mfma_f32_32x32x16_bf16 v[32:47], v[238:241], v[180:183], v[32:47]
	ds_read_b128 v[234:237], v205 offset:9280
	ds_read_b128 v[238:241], v205 offset:13888
	s_waitcnt vmcnt(7)
	ds_write_b128 v215, v[168:171] offset:27648
	s_waitcnt vmcnt(6)
	ds_write_b128 v215, v[172:175] offset:64512
	ds_read_b128 v[168:171], v208 offset:96
	ds_read_b128 v[172:175], v208 offset:4704
	s_waitcnt lgkmcnt(5)
	v_mfma_f32_32x32x16_bf16 v[80:95], v[234:237], v[176:179], v[80:95]
	v_mfma_f32_32x32x16_bf16 v[16:31], v[234:237], v[180:183], v[16:31]
	ds_read_b128 v[234:237], v205 offset:96
	s_waitcnt lgkmcnt(5)
	v_mfma_f32_32x32x16_bf16 v[64:79], v[238:241], v[176:179], v[64:79]
	v_mfma_f32_32x32x16_bf16 v[0:15], v[238:241], v[180:183], v[0:15]
	ds_read_b128 v[238:241], v205 offset:4704
	global_load_dwordx4 v[176:179], v[198:199], off offset:2944
	global_load_dwordx4 v[180:183], v[200:201], off offset:2944
	s_waitcnt lgkmcnt(1)
	v_mfma_f32_32x32x16_bf16 v[112:127], v[234:237], v[168:171], v[112:127]
	v_mfma_f32_32x32x16_bf16 v[48:63], v[234:237], v[172:175], v[48:63]
	s_waitcnt lgkmcnt(0)
	v_mfma_f32_32x32x16_bf16 v[96:111], v[238:241], v[168:171], v[96:111]
	v_mfma_f32_32x32x16_bf16 v[32:47], v[238:241], v[172:175], v[32:47]
	ds_read_b128 v[234:237], v205 offset:9312
	ds_read_b128 v[238:241], v205 offset:13920
	s_waitcnt lgkmcnt(1)
	v_mfma_f32_32x32x16_bf16 v[80:95], v[234:237], v[168:171], v[80:95]
	v_mfma_f32_32x32x16_bf16 v[16:31], v[234:237], v[172:175], v[16:31]
	s_waitcnt lgkmcnt(0)
	v_mfma_f32_32x32x16_bf16 v[64:79], v[238:241], v[168:171], v[64:79]
	v_mfma_f32_32x32x16_bf16 v[0:15], v[238:241], v[172:175], v[0:15]
	s_setprio 0
	s_barrier
; template <bool trans>
; DI void gemm_core(const GTile& tl, const GTile& nx, bool has_next  , bool chain  , bool pre, u32x4 (&ra)[4], u32x4 (&rb)[4], char* smem, f32x16 (&acc)[2][4]) {
;     ...
;   const int nk = K / 64;
;   if (!pre) { G_LOAD(0); G_STORE(0); G_LOAD(1); }
;   for (int kt = 0; kt < nk; ++kt) {
;     __syncthreads();
;     G_COMPUTE(kt & 1, kt);
;   }
	global_load_dwordx4 v[168:171], v[190:191], off offset:3072
	global_load_dwordx4 v[172:175], v[188:189], off offset:3072
	s_waitcnt vmcnt(9)
	ds_write_b128 v209, v[160:163]
	s_waitcnt vmcnt(8)
	ds_write_b128 v210, v[164:167]
	ds_read_b128 v[160:163], v204 offset:36864
	ds_read_b128 v[164:167], v204 offset:41472
	ds_read_b128 v[234:237], v192
	ds_read_b128 v[238:241], v192 offset:4608
	s_setprio 1
	s_waitcnt lgkmcnt(1)
	v_mfma_f32_32x32x16_bf16 v[112:127], v[234:237], v[160:163], v[112:127]
	v_mfma_f32_32x32x16_bf16 v[48:63], v[234:237], v[164:167], v[48:63]
	s_waitcnt lgkmcnt(0)
	v_mfma_f32_32x32x16_bf16 v[96:111], v[238:241], v[160:163], v[96:111]
	v_mfma_f32_32x32x16_bf16 v[32:47], v[238:241], v[164:167], v[32:47]
	ds_read_b128 v[234:237], v192 offset:9216
	ds_read_b128 v[238:241], v192 offset:13824
	s_waitcnt vmcnt(7)
	ds_write_b128 v212, v[218:221]
	s_waitcnt vmcnt(6)
	ds_write_b128 v211, v[222:225]
	ds_read_b128 v[218:221], v204 offset:36896
	ds_read_b128 v[222:225], v204 offset:41504
	s_waitcnt lgkmcnt(5)
	v_mfma_f32_32x32x16_bf16 v[80:95], v[234:237], v[160:163], v[80:95]
	v_mfma_f32_32x32x16_bf16 v[16:31], v[234:237], v[164:167], v[16:31]
	ds_read_b128 v[234:237], v192 offset:32
	s_waitcnt lgkmcnt(5)
	v_mfma_f32_32x32x16_bf16 v[64:79], v[238:241], v[160:163], v[64:79]
	v_mfma_f32_32x32x16_bf16 v[0:15], v[238:241], v[164:167], v[0:15]
	ds_read_b128 v[238:241], v192 offset:4640
	global_load_dwordx4 v[160:163], v[194:195], off offset:3072
	global_load_dwordx4 v[164:167], v[196:197], off offset:3072
	s_waitcnt lgkmcnt(1)
	v_mfma_f32_32x32x16_bf16 v[112:127], v[234:237], v[218:221], v[112:127]
	v_mfma_f32_32x32x16_bf16 v[48:63], v[234:237], v[222:225], v[48:63]
	s_waitcnt lgkmcnt(0)
	v_mfma_f32_32x32x16_bf16 v[96:111], v[238:241], v[218:221], v[96:111]
	v_mfma_f32_32x32x16_bf16 v[32:47], v[238:241], v[222:225], v[32:47]
	ds_read_b128 v[234:237], v192 offset:9248
	ds_read_b128 v[238:241], v192 offset:13856
	s_waitcnt vmcnt(7)
	ds_write_b128 v214, v[226:229]
	s_waitcnt vmcnt(6)
	ds_write_b128 v213, v[230:233]
	ds_read_b128 v[226:229], v204 offset:36928
	ds_read_b128 v[230:233], v204 offset:41536
	s_waitcnt lgkmcnt(5)
	v_mfma_f32_32x32x16_bf16 v[80:95], v[234:237], v[218:221], v[80:95]
	v_mfma_f32_32x32x16_bf16 v[16:31], v[234:237], v[222:225], v[16:31]
	ds_read_b128 v[234:237], v192 offset:64
	s_waitcnt lgkmcnt(5)
	v_mfma_f32_32x32x16_bf16 v[64:79], v[238:241], v[218:221], v[64:79]
	v_mfma_f32_32x32x16_bf16 v[0:15], v[238:241], v[222:225], v[0:15]
	ds_read_b128 v[238:241], v192 offset:4672
	global_load_dwordx4 v[218:221], v[184:185], off offset:3072
	global_load_dwordx4 v[222:225], v[186:187], off offset:3072
	s_waitcnt lgkmcnt(1)
	v_mfma_f32_32x32x16_bf16 v[112:127], v[234:237], v[226:229], v[112:127]
	v_mfma_f32_32x32x16_bf16 v[48:63], v[234:237], v[230:233], v[48:63]
	s_waitcnt lgkmcnt(0)
	v_mfma_f32_32x32x16_bf16 v[96:111], v[238:241], v[226:229], v[96:111]
	v_mfma_f32_32x32x16_bf16 v[32:47], v[238:241], v[230:233], v[32:47]
	ds_read_b128 v[234:237], v192 offset:9280
	ds_read_b128 v[238:241], v192 offset:13888
	s_waitcnt vmcnt(7)
	ds_write_b128 v217, v[176:179]
	s_waitcnt vmcnt(6)
	ds_write_b128 v216, v[180:183]
	ds_read_b128 v[176:179], v204 offset:36960
	ds_read_b128 v[180:183], v204 offset:41568
	s_waitcnt lgkmcnt(5)
	v_mfma_f32_32x32x16_bf16 v[80:95], v[234:237], v[226:229], v[80:95]
	v_mfma_f32_32x32x16_bf16 v[16:31], v[234:237], v[230:233], v[16:31]
	ds_read_b128 v[234:237], v192 offset:96
	s_waitcnt lgkmcnt(5)
	v_mfma_f32_32x32x16_bf16 v[64:79], v[238:241], v[226:229], v[64:79]
	v_mfma_f32_32x32x16_bf16 v[0:15], v[238:241], v[230:233], v[0:15]
	ds_read_b128 v[238:241], v192 offset:4704
	global_load_dwordx4 v[226:229], v[198:199], off offset:3072
	global_load_dwordx4 v[230:233], v[200:201], off offset:3072
	s_waitcnt lgkmcnt(1)
	v_mfma_f32_32x32x16_bf16 v[112:127], v[234:237], v[176:179], v[112:127]
	v_mfma_f32_32x32x16_bf16 v[48:63], v[234:237], v[180:183], v[48:63]
	s_waitcnt lgkmcnt(0)
	v_mfma_f32_32x32x16_bf16 v[96:111], v[238:241], v[176:179], v[96:111]
	v_mfma_f32_32x32x16_bf16 v[32:47], v[238:241], v[180:183], v[32:47]
	ds_read_b128 v[234:237], v192 offset:9312
	ds_read_b128 v[238:241], v192 offset:13920
	s_waitcnt lgkmcnt(1)
	v_mfma_f32_32x32x16_bf16 v[80:95], v[234:237], v[176:179], v[80:95]
	v_mfma_f32_32x32x16_bf16 v[16:31], v[234:237], v[180:183], v[16:31]
	s_waitcnt lgkmcnt(0)
	v_mfma_f32_32x32x16_bf16 v[64:79], v[238:241], v[176:179], v[64:79]
	v_mfma_f32_32x32x16_bf16 v[0:15], v[238:241], v[180:183], v[0:15]
	s_setprio 0
	s_barrier
; template <bool trans>
; DI void gemm_core(const GTile& tl, const GTile& nx, bool has_next  , bool chain  , bool pre, u32x4 (&ra)[4], u32x4 (&rb)[4], char* smem, f32x16 (&acc)[2][4]) {
;     ...
;   const int nk = K / 64;
;   if (!pre) { G_LOAD(0); G_STORE(0); G_LOAD(1); }
;   for (int kt = 0; kt < nk; ++kt) {
;     __syncthreads();
;     G_COMPUTE(kt & 1, kt);
;   }
	global_load_dwordx4 v[176:179], v[190:191], off offset:3200
	global_load_dwordx4 v[180:183], v[188:189], off offset:3200
	s_waitcnt vmcnt(9)
	ds_write_b128 v215, v[168:171]
	s_waitcnt vmcnt(8)
	ds_write_b128 v215, v[172:175] offset:36864
	ds_read_b128 v[168:171], v208
	ds_read_b128 v[172:175], v208 offset:4608
	ds_read_b128 v[234:237], v205
	ds_read_b128 v[238:241], v205 offset:4608
	s_setprio 1
	s_waitcnt lgkmcnt(1)
	v_mfma_f32_32x32x16_bf16 v[112:127], v[234:237], v[168:171], v[112:127]
	v_mfma_f32_32x32x16_bf16 v[48:63], v[234:237], v[172:175], v[48:63]
	s_waitcnt lgkmcnt(0)
	v_mfma_f32_32x32x16_bf16 v[96:111], v[238:241], v[168:171], v[96:111]
	v_mfma_f32_32x32x16_bf16 v[32:47], v[238:241], v[172:175], v[32:47]
	ds_read_b128 v[234:237], v205 offset:9216
	ds_read_b128 v[238:241], v205 offset:13824
	s_waitcnt vmcnt(7)
	ds_write_b128 v215, v[160:163] offset:9216
	s_waitcnt vmcnt(6)
	ds_write_b128 v215, v[164:167] offset:46080
	ds_read_b128 v[160:163], v208 offset:32
	ds_read_b128 v[164:167], v208 offset:4640
	s_waitcnt lgkmcnt(5)
	v_mfma_f32_32x32x16_bf16 v[80:95], v[234:237], v[168:171], v[80:95]
	v_mfma_f32_32x32x16_bf16 v[16:31], v[234:237], v[172:175], v[16:31]
	ds_read_b128 v[234:237], v205 offset:32
	s_waitcnt lgkmcnt(5)
	v_mfma_f32_32x32x16_bf16 v[64:79], v[238:241], v[168:171], v[64:79]
	v_mfma_f32_32x32x16_bf16 v[0:15], v[238:241], v[172:175], v[0:15]
	ds_read_b128 v[238:241], v205 offset:4640
	global_load_dwordx4 v[168:171], v[194:195], off offset:3200
	global_load_dwordx4 v[172:175], v[196:197], off offset:3200
	s_waitcnt lgkmcnt(1)
	v_mfma_f32_32x32x16_bf16 v[112:127], v[234:237], v[160:163], v[112:127]
	v_mfma_f32_32x32x16_bf16 v[48:63], v[234:237], v[164:167], v[48:63]
	s_waitcnt lgkmcnt(0)
	v_mfma_f32_32x32x16_bf16 v[96:111], v[238:241], v[160:163], v[96:111]
	v_mfma_f32_32x32x16_bf16 v[32:47], v[238:241], v[164:167], v[32:47]
	ds_read_b128 v[234:237], v205 offset:9248
	ds_read_b128 v[238:241], v205 offset:13856
	s_waitcnt vmcnt(7)
	ds_write_b128 v215, v[218:221] offset:18432
	s_waitcnt vmcnt(6)
	ds_write_b128 v215, v[222:225] offset:55296
	ds_read_b128 v[218:221], v208 offset:64
	ds_read_b128 v[222:225], v208 offset:4672
	s_waitcnt lgkmcnt(5)
	v_mfma_f32_32x32x16_bf16 v[80:95], v[234:237], v[160:163], v[80:95]
	v_mfma_f32_32x32x16_bf16 v[16:31], v[234:237], v[164:167], v[16:31]
	ds_read_b128 v[234:237], v205 offset:64
	s_waitcnt lgkmcnt(5)
	v_mfma_f32_32x32x16_bf16 v[64:79], v[238:241], v[160:163], v[64:79]
	v_mfma_f32_32x32x16_bf16 v[0:15], v[238:241], v[164:167], v[0:15]
	ds_read_b128 v[238:241], v205 offset:4672
	global_load_dwordx4 v[160:163], v[184:185], off offset:3200
	global_load_dwordx4 v[164:167], v[186:187], off offset:3200
	s_waitcnt lgkmcnt(1)
	v_mfma_f32_32x32x16_bf16 v[112:127], v[234:237], v[218:221], v[112:127]
	v_mfma_f32_32x32x16_bf16 v[48:63], v[234:237], v[222:225], v[48:63]
	s_waitcnt lgkmcnt(0)
	v_mfma_f32_32x32x16_bf16 v[96:111], v[238:241], v[218:221], v[96:111]
	v_mfma_f32_32x32x16_bf16 v[32:47], v[238:241], v[222:225], v[32:47]
	ds_read_b128 v[234:237], v205 offset:9280
	ds_read_b128 v[238:241], v205 offset:13888
	s_waitcnt vmcnt(7)
	ds_write_b128 v215, v[226:229] offset:27648
	s_waitcnt vmcnt(6)
	ds_write_b128 v215, v[230:233] offset:64512
	ds_read_b128 v[226:229], v208 offset:96
	ds_read_b128 v[230:233], v208 offset:4704
	s_waitcnt lgkmcnt(5)
	v_mfma_f32_32x32x16_bf16 v[80:95], v[234:237], v[218:221], v[80:95]
	v_mfma_f32_32x32x16_bf16 v[16:31], v[234:237], v[222:225], v[16:31]
	ds_read_b128 v[234:237], v205 offset:96
	s_waitcnt lgkmcnt(5)
	v_mfma_f32_32x32x16_bf16 v[64:79], v[238:241], v[218:221], v[64:79]
	v_mfma_f32_32x32x16_bf16 v[0:15], v[238:241], v[222:225], v[0:15]
	ds_read_b128 v[238:241], v205 offset:4704
	global_load_dwordx4 v[218:221], v[198:199], off offset:3200
	global_load_dwordx4 v[222:225], v[200:201], off offset:3200
	s_waitcnt lgkmcnt(1)
	v_mfma_f32_32x32x16_bf16 v[112:127], v[234:237], v[226:229], v[112:127]
	v_mfma_f32_32x32x16_bf16 v[48:63], v[234:237], v[230:233], v[48:63]
	s_waitcnt lgkmcnt(0)
	v_mfma_f32_32x32x16_bf16 v[96:111], v[238:241], v[226:229], v[96:111]
	v_mfma_f32_32x32x16_bf16 v[32:47], v[238:241], v[230:233], v[32:47]
	ds_read_b128 v[234:237], v205 offset:9312
	ds_read_b128 v[238:241], v205 offset:13920
	s_waitcnt lgkmcnt(1)
	v_mfma_f32_32x32x16_bf16 v[80:95], v[234:237], v[226:229], v[80:95]
	v_mfma_f32_32x32x16_bf16 v[16:31], v[234:237], v[230:233], v[16:31]
	s_waitcnt lgkmcnt(0)
	v_mfma_f32_32x32x16_bf16 v[64:79], v[238:241], v[226:229], v[64:79]
	v_mfma_f32_32x32x16_bf16 v[0:15], v[238:241], v[230:233], v[0:15]
	s_setprio 0
	s_barrier
; template <bool trans>
; DI void gemm_core(const GTile& tl, const GTile& nx, bool has_next  , bool chain  , bool pre, u32x4 (&ra)[4], u32x4 (&rb)[4], char* smem, f32x16 (&acc)[2][4]) {
;     ...
;   const int nk = K / 64;
;   if (!pre) { G_LOAD(0); G_STORE(0); G_LOAD(1); }
;   for (int kt = 0; kt < nk; ++kt) {
;     __syncthreads();
;     G_COMPUTE(kt & 1, kt);
;   }
	global_load_dwordx4 v[226:229], v[190:191], off offset:3328
	global_load_dwordx4 v[230:233], v[188:189], off offset:3328
	s_waitcnt vmcnt(9)
	ds_write_b128 v209, v[176:179]
	s_waitcnt vmcnt(8)
	ds_write_b128 v210, v[180:183]
	ds_read_b128 v[176:179], v204 offset:36864
	ds_read_b128 v[180:183], v204 offset:41472
	ds_read_b128 v[234:237], v192
	ds_read_b128 v[238:241], v192 offset:4608
	s_setprio 1
	s_waitcnt lgkmcnt(1)
	v_mfma_f32_32x32x16_bf16 v[112:127], v[234:237], v[176:179], v[112:127]
	v_mfma_f32_32x32x16_bf16 v[48:63], v[234:237], v[180:183], v[48:63]
	s_waitcnt lgkmcnt(0)
	v_mfma_f32_32x32x16_bf16 v[96:111], v[238:241], v[176:179], v[96:111]
	v_mfma_f32_32x32x16_bf16 v[32:47], v[238:241], v[180:183], v[32:47]
	ds_read_b128 v[234:237], v192 offset:9216
	ds_read_b128 v[238:241], v192 offset:13824
	s_waitcnt vmcnt(7)
	ds_write_b128 v212, v[168:171]
	s_waitcnt vmcnt(6)
	ds_write_b128 v211, v[172:175]
	ds_read_b128 v[168:171], v204 offset:36896
	ds_read_b128 v[172:175], v204 offset:41504
	s_waitcnt lgkmcnt(5)
	v_mfma_f32_32x32x16_bf16 v[80:95], v[234:237], v[176:179], v[80:95]
	v_mfma_f32_32x32x16_bf16 v[16:31], v[234:237], v[180:183], v[16:31]
	ds_read_b128 v[234:237], v192 offset:32
	s_waitcnt lgkmcnt(5)
	v_mfma_f32_32x32x16_bf16 v[64:79], v[238:241], v[176:179], v[64:79]
	v_mfma_f32_32x32x16_bf16 v[0:15], v[238:241], v[180:183], v[0:15]
	ds_read_b128 v[238:241], v192 offset:4640
	global_load_dwordx4 v[176:179], v[194:195], off offset:3328
	global_load_dwordx4 v[180:183], v[196:197], off offset:3328
	s_waitcnt lgkmcnt(1)
	v_mfma_f32_32x32x16_bf16 v[112:127], v[234:237], v[168:171], v[112:127]
	v_mfma_f32_32x32x16_bf16 v[48:63], v[234:237], v[172:175], v[48:63]
	s_waitcnt lgkmcnt(0)
	v_mfma_f32_32x32x16_bf16 v[96:111], v[238:241], v[168:171], v[96:111]
	v_mfma_f32_32x32x16_bf16 v[32:47], v[238:241], v[172:175], v[32:47]
	ds_read_b128 v[234:237], v192 offset:9248
	ds_read_b128 v[238:241], v192 offset:13856
	s_waitcnt vmcnt(7)
	ds_write_b128 v214, v[160:163]
	s_waitcnt vmcnt(6)
	ds_write_b128 v213, v[164:167]
	ds_read_b128 v[160:163], v204 offset:36928
	ds_read_b128 v[164:167], v204 offset:41536
	s_waitcnt lgkmcnt(5)
	v_mfma_f32_32x32x16_bf16 v[80:95], v[234:237], v[168:171], v[80:95]
	v_mfma_f32_32x32x16_bf16 v[16:31], v[234:237], v[172:175], v[16:31]
	ds_read_b128 v[234:237], v192 offset:64
	s_waitcnt lgkmcnt(5)
	v_mfma_f32_32x32x16_bf16 v[64:79], v[238:241], v[168:171], v[64:79]
	v_mfma_f32_32x32x16_bf16 v[0:15], v[238:241], v[172:175], v[0:15]
	ds_read_b128 v[238:241], v192 offset:4672
	global_load_dwordx4 v[168:171], v[184:185], off offset:3328
	global_load_dwordx4 v[172:175], v[186:187], off offset:3328
	s_waitcnt lgkmcnt(1)
	v_mfma_f32_32x32x16_bf16 v[112:127], v[234:237], v[160:163], v[112:127]
	v_mfma_f32_32x32x16_bf16 v[48:63], v[234:237], v[164:167], v[48:63]
	s_waitcnt lgkmcnt(0)
	v_mfma_f32_32x32x16_bf16 v[96:111], v[238:241], v[160:163], v[96:111]
	v_mfma_f32_32x32x16_bf16 v[32:47], v[238:241], v[164:167], v[32:47]
	ds_read_b128 v[234:237], v192 offset:9280
	ds_read_b128 v[238:241], v192 offset:13888
	s_waitcnt vmcnt(7)
	ds_write_b128 v217, v[218:221]
	s_waitcnt vmcnt(6)
	ds_write_b128 v216, v[222:225]
	ds_read_b128 v[218:221], v204 offset:36960
	ds_read_b128 v[222:225], v204 offset:41568
	s_waitcnt lgkmcnt(5)
	v_mfma_f32_32x32x16_bf16 v[80:95], v[234:237], v[160:163], v[80:95]
	v_mfma_f32_32x32x16_bf16 v[16:31], v[234:237], v[164:167], v[16:31]
	ds_read_b128 v[234:237], v192 offset:96
	s_waitcnt lgkmcnt(5)
	v_mfma_f32_32x32x16_bf16 v[64:79], v[238:241], v[160:163], v[64:79]
	v_mfma_f32_32x32x16_bf16 v[0:15], v[238:241], v[164:167], v[0:15]
	ds_read_b128 v[238:241], v192 offset:4704
	global_load_dwordx4 v[160:163], v[198:199], off offset:3328
	global_load_dwordx4 v[164:167], v[200:201], off offset:3328
	s_waitcnt lgkmcnt(1)
	v_mfma_f32_32x32x16_bf16 v[112:127], v[234:237], v[218:221], v[112:127]
	v_mfma_f32_32x32x16_bf16 v[48:63], v[234:237], v[222:225], v[48:63]
	s_waitcnt lgkmcnt(0)
	v_mfma_f32_32x32x16_bf16 v[96:111], v[238:241], v[218:221], v[96:111]
	v_mfma_f32_32x32x16_bf16 v[32:47], v[238:241], v[222:225], v[32:47]
	ds_read_b128 v[234:237], v192 offset:9312
	ds_read_b128 v[238:241], v192 offset:13920
	s_waitcnt lgkmcnt(1)
	v_mfma_f32_32x32x16_bf16 v[80:95], v[234:237], v[218:221], v[80:95]
	v_mfma_f32_32x32x16_bf16 v[16:31], v[234:237], v[222:225], v[16:31]
	s_waitcnt lgkmcnt(0)
	v_mfma_f32_32x32x16_bf16 v[64:79], v[238:241], v[218:221], v[64:79]
	v_mfma_f32_32x32x16_bf16 v[0:15], v[238:241], v[222:225], v[0:15]
	s_setprio 0
	s_barrier
; template <bool trans>
; DI void gemm_core(const GTile& tl, const GTile& nx, bool has_next  , bool chain  , bool pre, u32x4 (&ra)[4], u32x4 (&rb)[4], char* smem, f32x16 (&acc)[2][4]) {
;     ...
;   const int nk = K / 64;
;   if (!pre) { G_LOAD(0); G_STORE(0); G_LOAD(1); }
;   for (int kt = 0; kt < nk; ++kt) {
;     __syncthreads();
;     G_COMPUTE(kt & 1, kt);
;   }
	global_load_dwordx4 v[218:221], v[190:191], off offset:3456
	global_load_dwordx4 v[222:225], v[188:189], off offset:3456
	s_waitcnt vmcnt(9)
	ds_write_b128 v215, v[226:229]
	s_waitcnt vmcnt(8)
	ds_write_b128 v215, v[230:233] offset:36864
	ds_read_b128 v[226:229], v208
	ds_read_b128 v[230:233], v208 offset:4608
	ds_read_b128 v[234:237], v205
	ds_read_b128 v[238:241], v205 offset:4608
	s_setprio 1
	s_waitcnt lgkmcnt(1)
	v_mfma_f32_32x32x16_bf16 v[112:127], v[234:237], v[226:229], v[112:127]
	v_mfma_f32_32x32x16_bf16 v[48:63], v[234:237], v[230:233], v[48:63]
	s_waitcnt lgkmcnt(0)
	v_mfma_f32_32x32x16_bf16 v[96:111], v[238:241], v[226:229], v[96:111]
	v_mfma_f32_32x32x16_bf16 v[32:47], v[238:241], v[230:233], v[32:47]
	ds_read_b128 v[234:237], v205 offset:9216
	ds_read_b128 v[238:241], v205 offset:13824
	s_waitcnt vmcnt(7)
	ds_write_b128 v215, v[176:179] offset:9216
	s_waitcnt vmcnt(6)
	ds_write_b128 v215, v[180:183] offset:46080
	ds_read_b128 v[176:179], v208 offset:32
	ds_read_b128 v[180:183], v208 offset:4640
	s_waitcnt lgkmcnt(5)
	v_mfma_f32_32x32x16_bf16 v[80:95], v[234:237], v[226:229], v[80:95]
	v_mfma_f32_32x32x16_bf16 v[16:31], v[234:237], v[230:233], v[16:31]
	ds_read_b128 v[234:237], v205 offset:32
	s_waitcnt lgkmcnt(5)
	v_mfma_f32_32x32x16_bf16 v[64:79], v[238:241], v[226:229], v[64:79]
	v_mfma_f32_32x32x16_bf16 v[0:15], v[238:241], v[230:233], v[0:15]
	ds_read_b128 v[238:241], v205 offset:4640
	global_load_dwordx4 v[226:229], v[194:195], off offset:3456
	global_load_dwordx4 v[230:233], v[196:197], off offset:3456
	s_waitcnt lgkmcnt(1)
	v_mfma_f32_32x32x16_bf16 v[112:127], v[234:237], v[176:179], v[112:127]
	v_mfma_f32_32x32x16_bf16 v[48:63], v[234:237], v[180:183], v[48:63]
	s_waitcnt lgkmcnt(0)
	v_mfma_f32_32x32x16_bf16 v[96:111], v[238:241], v[176:179], v[96:111]
	v_mfma_f32_32x32x16_bf16 v[32:47], v[238:241], v[180:183], v[32:47]
	ds_read_b128 v[234:237], v205 offset:9248
	ds_read_b128 v[238:241], v205 offset:13856
	s_waitcnt vmcnt(7)
	ds_write_b128 v215, v[168:171] offset:18432
	s_waitcnt vmcnt(6)
	ds_write_b128 v215, v[172:175] offset:55296
	ds_read_b128 v[168:171], v208 offset:64
	ds_read_b128 v[172:175], v208 offset:4672
	s_waitcnt lgkmcnt(5)
	v_mfma_f32_32x32x16_bf16 v[80:95], v[234:237], v[176:179], v[80:95]
	v_mfma_f32_32x32x16_bf16 v[16:31], v[234:237], v[180:183], v[16:31]
	ds_read_b128 v[234:237], v205 offset:64
	s_waitcnt lgkmcnt(5)
	v_mfma_f32_32x32x16_bf16 v[64:79], v[238:241], v[176:179], v[64:79]
	v_mfma_f32_32x32x16_bf16 v[0:15], v[238:241], v[180:183], v[0:15]
	ds_read_b128 v[238:241], v205 offset:4672
	global_load_dwordx4 v[176:179], v[184:185], off offset:3456
	global_load_dwordx4 v[180:183], v[186:187], off offset:3456
	s_waitcnt lgkmcnt(1)
	v_mfma_f32_32x32x16_bf16 v[112:127], v[234:237], v[168:171], v[112:127]
	v_mfma_f32_32x32x16_bf16 v[48:63], v[234:237], v[172:175], v[48:63]
	s_waitcnt lgkmcnt(0)
	v_mfma_f32_32x32x16_bf16 v[96:111], v[238:241], v[168:171], v[96:111]
	v_mfma_f32_32x32x16_bf16 v[32:47], v[238:241], v[172:175], v[32:47]
	ds_read_b128 v[234:237], v205 offset:9280
	ds_read_b128 v[238:241], v205 offset:13888
	s_waitcnt vmcnt(7)
	ds_write_b128 v215, v[160:163] offset:27648
	s_waitcnt vmcnt(6)
	ds_write_b128 v215, v[164:167] offset:64512
	ds_read_b128 v[160:163], v208 offset:96
	ds_read_b128 v[164:167], v208 offset:4704
	s_waitcnt lgkmcnt(5)
	v_mfma_f32_32x32x16_bf16 v[80:95], v[234:237], v[168:171], v[80:95]
	v_mfma_f32_32x32x16_bf16 v[16:31], v[234:237], v[172:175], v[16:31]
	ds_read_b128 v[234:237], v205 offset:96
	s_waitcnt lgkmcnt(5)
	v_mfma_f32_32x32x16_bf16 v[64:79], v[238:241], v[168:171], v[64:79]
	v_mfma_f32_32x32x16_bf16 v[0:15], v[238:241], v[172:175], v[0:15]
	ds_read_b128 v[238:241], v205 offset:4704
	global_load_dwordx4 v[168:171], v[198:199], off offset:3456
	global_load_dwordx4 v[172:175], v[200:201], off offset:3456
	s_waitcnt lgkmcnt(1)
	v_mfma_f32_32x32x16_bf16 v[112:127], v[234:237], v[160:163], v[112:127]
	v_mfma_f32_32x32x16_bf16 v[48:63], v[234:237], v[164:167], v[48:63]
	s_waitcnt lgkmcnt(0)
	v_mfma_f32_32x32x16_bf16 v[96:111], v[238:241], v[160:163], v[96:111]
	v_mfma_f32_32x32x16_bf16 v[32:47], v[238:241], v[164:167], v[32:47]
	ds_read_b128 v[234:237], v205 offset:9312
	ds_read_b128 v[238:241], v205 offset:13920
	s_waitcnt lgkmcnt(1)
	v_mfma_f32_32x32x16_bf16 v[80:95], v[234:237], v[160:163], v[80:95]
	v_mfma_f32_32x32x16_bf16 v[16:31], v[234:237], v[164:167], v[16:31]
	s_waitcnt lgkmcnt(0)
	v_mfma_f32_32x32x16_bf16 v[64:79], v[238:241], v[160:163], v[64:79]
	v_mfma_f32_32x32x16_bf16 v[0:15], v[238:241], v[164:167], v[0:15]
	s_setprio 0
	s_barrier
; template <bool trans>
; DI void gemm_core(const GTile& tl, const GTile& nx, bool has_next  , bool chain  , bool pre, u32x4 (&ra)[4], u32x4 (&rb)[4], char* smem, f32x16 (&acc)[2][4]) {
;     ...
;   const int nk = K / 64;
;   if (!pre) { G_LOAD(0); G_STORE(0); G_LOAD(1); }
;   for (int kt = 0; kt < nk; ++kt) {
;     __syncthreads();
;     G_COMPUTE(kt & 1, kt);
;   }
	global_load_dwordx4 v[160:163], v[190:191], off offset:3584
	global_load_dwordx4 v[164:167], v[188:189], off offset:3584
	s_waitcnt vmcnt(9)
	ds_write_b128 v209, v[218:221]
	s_waitcnt vmcnt(8)
	ds_write_b128 v210, v[222:225]
	ds_read_b128 v[218:221], v204 offset:36864
	ds_read_b128 v[222:225], v204 offset:41472
	ds_read_b128 v[234:237], v192
	ds_read_b128 v[238:241], v192 offset:4608
	s_setprio 1
	s_waitcnt lgkmcnt(1)
	v_mfma_f32_32x32x16_bf16 v[112:127], v[234:237], v[218:221], v[112:127]
	v_mfma_f32_32x32x16_bf16 v[48:63], v[234:237], v[222:225], v[48:63]
	s_waitcnt lgkmcnt(0)
	v_mfma_f32_32x32x16_bf16 v[96:111], v[238:241], v[218:221], v[96:111]
	v_mfma_f32_32x32x16_bf16 v[32:47], v[238:241], v[222:225], v[32:47]
	ds_read_b128 v[234:237], v192 offset:9216
	ds_read_b128 v[238:241], v192 offset:13824
	s_waitcnt vmcnt(7)
	ds_write_b128 v212, v[226:229]
	s_waitcnt vmcnt(6)
	ds_write_b128 v211, v[230:233]
	ds_read_b128 v[226:229], v204 offset:36896
	ds_read_b128 v[230:233], v204 offset:41504
	s_waitcnt lgkmcnt(5)
	v_mfma_f32_32x32x16_bf16 v[80:95], v[234:237], v[218:221], v[80:95]
	v_mfma_f32_32x32x16_bf16 v[16:31], v[234:237], v[222:225], v[16:31]
	ds_read_b128 v[234:237], v192 offset:32
	s_waitcnt lgkmcnt(5)
	v_mfma_f32_32x32x16_bf16 v[64:79], v[238:241], v[218:221], v[64:79]
	v_mfma_f32_32x32x16_bf16 v[0:15], v[238:241], v[222:225], v[0:15]
	ds_read_b128 v[238:241], v192 offset:4640
	global_load_dwordx4 v[218:221], v[194:195], off offset:3584
	global_load_dwordx4 v[222:225], v[196:197], off offset:3584
	s_waitcnt lgkmcnt(1)
	v_mfma_f32_32x32x16_bf16 v[112:127], v[234:237], v[226:229], v[112:127]
	v_mfma_f32_32x32x16_bf16 v[48:63], v[234:237], v[230:233], v[48:63]
	s_waitcnt lgkmcnt(0)
	v_mfma_f32_32x32x16_bf16 v[96:111], v[238:241], v[226:229], v[96:111]
	v_mfma_f32_32x32x16_bf16 v[32:47], v[238:241], v[230:233], v[32:47]
	ds_read_b128 v[234:237], v192 offset:9248
	ds_read_b128 v[238:241], v192 offset:13856
	s_waitcnt vmcnt(7)
	ds_write_b128 v214, v[176:179]
	s_waitcnt vmcnt(6)
	ds_write_b128 v213, v[180:183]
	ds_read_b128 v[176:179], v204 offset:36928
	ds_read_b128 v[180:183], v204 offset:41536
	s_waitcnt lgkmcnt(5)
	v_mfma_f32_32x32x16_bf16 v[80:95], v[234:237], v[226:229], v[80:95]
	v_mfma_f32_32x32x16_bf16 v[16:31], v[234:237], v[230:233], v[16:31]
	ds_read_b128 v[234:237], v192 offset:64
	s_waitcnt lgkmcnt(5)
	v_mfma_f32_32x32x16_bf16 v[64:79], v[238:241], v[226:229], v[64:79]
	v_mfma_f32_32x32x16_bf16 v[0:15], v[238:241], v[230:233], v[0:15]
	ds_read_b128 v[238:241], v192 offset:4672
	global_load_dwordx4 v[226:229], v[184:185], off offset:3584
	global_load_dwordx4 v[230:233], v[186:187], off offset:3584
	s_waitcnt lgkmcnt(1)
	v_mfma_f32_32x32x16_bf16 v[112:127], v[234:237], v[176:179], v[112:127]
	v_mfma_f32_32x32x16_bf16 v[48:63], v[234:237], v[180:183], v[48:63]
	s_waitcnt lgkmcnt(0)
	v_mfma_f32_32x32x16_bf16 v[96:111], v[238:241], v[176:179], v[96:111]
	v_mfma_f32_32x32x16_bf16 v[32:47], v[238:241], v[180:183], v[32:47]
	ds_read_b128 v[234:237], v192 offset:9280
	ds_read_b128 v[238:241], v192 offset:13888
	s_waitcnt vmcnt(7)
	ds_write_b128 v217, v[168:171]
	s_waitcnt vmcnt(6)
	ds_write_b128 v216, v[172:175]
	ds_read_b128 v[168:171], v204 offset:36960
	ds_read_b128 v[172:175], v204 offset:41568
	s_waitcnt lgkmcnt(5)
	v_mfma_f32_32x32x16_bf16 v[80:95], v[234:237], v[176:179], v[80:95]
	v_mfma_f32_32x32x16_bf16 v[16:31], v[234:237], v[180:183], v[16:31]
	ds_read_b128 v[234:237], v192 offset:96
	s_waitcnt lgkmcnt(5)
	v_mfma_f32_32x32x16_bf16 v[64:79], v[238:241], v[176:179], v[64:79]
	v_mfma_f32_32x32x16_bf16 v[0:15], v[238:241], v[180:183], v[0:15]
	ds_read_b128 v[238:241], v192 offset:4704
	global_load_dwordx4 v[176:179], v[198:199], off offset:3584
	global_load_dwordx4 v[180:183], v[200:201], off offset:3584
	s_waitcnt lgkmcnt(1)
	v_mfma_f32_32x32x16_bf16 v[112:127], v[234:237], v[168:171], v[112:127]
	v_mfma_f32_32x32x16_bf16 v[48:63], v[234:237], v[172:175], v[48:63]
	s_waitcnt lgkmcnt(0)
	v_mfma_f32_32x32x16_bf16 v[96:111], v[238:241], v[168:171], v[96:111]
	v_mfma_f32_32x32x16_bf16 v[32:47], v[238:241], v[172:175], v[32:47]
	ds_read_b128 v[234:237], v192 offset:9312
	ds_read_b128 v[238:241], v192 offset:13920
	s_waitcnt lgkmcnt(1)
	v_mfma_f32_32x32x16_bf16 v[80:95], v[234:237], v[168:171], v[80:95]
	v_mfma_f32_32x32x16_bf16 v[16:31], v[234:237], v[172:175], v[16:31]
	s_waitcnt lgkmcnt(0)
	v_mfma_f32_32x32x16_bf16 v[64:79], v[238:241], v[168:171], v[64:79]
	v_mfma_f32_32x32x16_bf16 v[0:15], v[238:241], v[172:175], v[0:15]
	s_setprio 0
	s_barrier
	global_load_dwordx4 v[168:171], v[190:191], off offset:3712
	global_load_dwordx4 v[172:175], v[188:189], off offset:3712
	s_waitcnt vmcnt(9)
	ds_write_b128 v215, v[160:163]
	s_waitcnt vmcnt(8)
	ds_write_b128 v215, v[164:167] offset:36864
	ds_read_b128 v[160:163], v208
	ds_read_b128 v[164:167], v208 offset:4608
	ds_read_b128 v[234:237], v205
	ds_read_b128 v[238:241], v205 offset:4608
	s_setprio 1
	s_waitcnt lgkmcnt(1)
	v_mfma_f32_32x32x16_bf16 v[112:127], v[234:237], v[160:163], v[112:127]
	v_mfma_f32_32x32x16_bf16 v[48:63], v[234:237], v[164:167], v[48:63]
	s_waitcnt lgkmcnt(0)
	v_mfma_f32_32x32x16_bf16 v[96:111], v[238:241], v[160:163], v[96:111]
	v_mfma_f32_32x32x16_bf16 v[32:47], v[238:241], v[164:167], v[32:47]
	ds_read_b128 v[234:237], v205 offset:9216
	ds_read_b128 v[238:241], v205 offset:13824
	s_waitcnt vmcnt(7)
	ds_write_b128 v215, v[218:221] offset:9216
	s_waitcnt vmcnt(6)
	ds_write_b128 v215, v[222:225] offset:46080
	ds_read_b128 v[218:221], v208 offset:32
	ds_read_b128 v[222:225], v208 offset:4640
	s_waitcnt lgkmcnt(5)
	v_mfma_f32_32x32x16_bf16 v[80:95], v[234:237], v[160:163], v[80:95]
	v_mfma_f32_32x32x16_bf16 v[16:31], v[234:237], v[164:167], v[16:31]
	ds_read_b128 v[234:237], v205 offset:32
	s_waitcnt lgkmcnt(5)
	v_mfma_f32_32x32x16_bf16 v[64:79], v[238:241], v[160:163], v[64:79]
	v_mfma_f32_32x32x16_bf16 v[0:15], v[238:241], v[164:167], v[0:15]
	ds_read_b128 v[238:241], v205 offset:4640
	global_load_dwordx4 v[160:163], v[194:195], off offset:3712
	global_load_dwordx4 v[164:167], v[196:197], off offset:3712
	s_waitcnt lgkmcnt(1)
	v_mfma_f32_32x32x16_bf16 v[112:127], v[234:237], v[218:221], v[112:127]
	v_mfma_f32_32x32x16_bf16 v[48:63], v[234:237], v[222:225], v[48:63]
	s_waitcnt lgkmcnt(0)
	v_mfma_f32_32x32x16_bf16 v[96:111], v[238:241], v[218:221], v[96:111]
	v_mfma_f32_32x32x16_bf16 v[32:47], v[238:241], v[222:225], v[32:47]
	ds_read_b128 v[234:237], v205 offset:9248
	ds_read_b128 v[238:241], v205 offset:13856
	s_waitcnt vmcnt(7)
	ds_write_b128 v215, v[226:229] offset:18432
	s_waitcnt vmcnt(6)
	ds_write_b128 v215, v[230:233] offset:55296
	ds_read_b128 v[226:229], v208 offset:64
	ds_read_b128 v[230:233], v208 offset:4672
	s_waitcnt lgkmcnt(5)
	v_mfma_f32_32x32x16_bf16 v[80:95], v[234:237], v[218:221], v[80:95]
	v_mfma_f32_32x32x16_bf16 v[16:31], v[234:237], v[222:225], v[16:31]
	ds_read_b128 v[234:237], v205 offset:64
	s_waitcnt lgkmcnt(5)
	v_mfma_f32_32x32x16_bf16 v[64:79], v[238:241], v[218:221], v[64:79]
	v_mfma_f32_32x32x16_bf16 v[0:15], v[238:241], v[222:225], v[0:15]
	ds_read_b128 v[238:241], v205 offset:4672
	global_load_dwordx4 v[218:221], v[184:185], off offset:3712
	global_load_dwordx4 v[222:225], v[186:187], off offset:3712
	s_waitcnt lgkmcnt(1)
	v_mfma_f32_32x32x16_bf16 v[112:127], v[234:237], v[226:229], v[112:127]
	v_mfma_f32_32x32x16_bf16 v[48:63], v[234:237], v[230:233], v[48:63]
	s_waitcnt lgkmcnt(0)
	v_mfma_f32_32x32x16_bf16 v[96:111], v[238:241], v[226:229], v[96:111]
	v_mfma_f32_32x32x16_bf16 v[32:47], v[238:241], v[230:233], v[32:47]
	ds_read_b128 v[234:237], v205 offset:9280
	ds_read_b128 v[238:241], v205 offset:13888
	s_waitcnt vmcnt(7)
	ds_write_b128 v215, v[176:179] offset:27648
	s_waitcnt vmcnt(6)
	ds_write_b128 v215, v[180:183] offset:64512
	ds_read_b128 v[176:179], v208 offset:96
	ds_read_b128 v[180:183], v208 offset:4704
	s_waitcnt lgkmcnt(5)
	v_mfma_f32_32x32x16_bf16 v[80:95], v[234:237], v[226:229], v[80:95]
	v_mfma_f32_32x32x16_bf16 v[16:31], v[234:237], v[230:233], v[16:31]
	ds_read_b128 v[234:237], v205 offset:96
	s_waitcnt lgkmcnt(5)
	v_mfma_f32_32x32x16_bf16 v[64:79], v[238:241], v[226:229], v[64:79]
	v_mfma_f32_32x32x16_bf16 v[0:15], v[238:241], v[230:233], v[0:15]
	ds_read_b128 v[238:241], v205 offset:4704
	global_load_dwordx4 v[226:229], v[198:199], off offset:3712
	global_load_dwordx4 v[230:233], v[200:201], off offset:3712
	s_waitcnt lgkmcnt(1)
	v_mfma_f32_32x32x16_bf16 v[112:127], v[234:237], v[176:179], v[112:127]
	v_mfma_f32_32x32x16_bf16 v[48:63], v[234:237], v[180:183], v[48:63]
	s_waitcnt lgkmcnt(0)
	v_mfma_f32_32x32x16_bf16 v[96:111], v[238:241], v[176:179], v[96:111]
	v_mfma_f32_32x32x16_bf16 v[32:47], v[238:241], v[180:183], v[32:47]
	ds_read_b128 v[234:237], v205 offset:9312
	ds_read_b128 v[238:241], v205 offset:13920
	s_waitcnt lgkmcnt(1)
	v_mfma_f32_32x32x16_bf16 v[80:95], v[234:237], v[176:179], v[80:95]
	v_mfma_f32_32x32x16_bf16 v[16:31], v[234:237], v[180:183], v[16:31]
	s_waitcnt lgkmcnt(0)
	v_mfma_f32_32x32x16_bf16 v[64:79], v[238:241], v[176:179], v[64:79]
	v_mfma_f32_32x32x16_bf16 v[0:15], v[238:241], v[180:183], v[0:15]
	s_setprio 0
	s_barrier
	global_load_dwordx4 v[176:179], v[190:191], off offset:3840
	global_load_dwordx4 v[180:183], v[188:189], off offset:3840
	s_waitcnt vmcnt(9)
	ds_write_b128 v209, v[168:171]
	s_waitcnt vmcnt(8)
	ds_write_b128 v210, v[172:175]
	ds_read_b128 v[168:171], v204 offset:36864
	ds_read_b128 v[172:175], v204 offset:41472
	ds_read_b128 v[234:237], v192
	ds_read_b128 v[238:241], v192 offset:4608
	s_setprio 1
	s_waitcnt lgkmcnt(1)
	v_mfma_f32_32x32x16_bf16 v[112:127], v[234:237], v[168:171], v[112:127]
	v_mfma_f32_32x32x16_bf16 v[48:63], v[234:237], v[172:175], v[48:63]
	s_waitcnt lgkmcnt(0)
	v_mfma_f32_32x32x16_bf16 v[96:111], v[238:241], v[168:171], v[96:111]
	v_mfma_f32_32x32x16_bf16 v[32:47], v[238:241], v[172:175], v[32:47]
	ds_read_b128 v[234:237], v192 offset:9216
	ds_read_b128 v[238:241], v192 offset:13824
	s_waitcnt lgkmcnt(1)
	v_mfma_f32_32x32x16_bf16 v[80:95], v[234:237], v[168:171], v[80:95]
	v_mfma_f32_32x32x16_bf16 v[16:31], v[234:237], v[172:175], v[16:31]
	s_waitcnt lgkmcnt(0)
	v_mfma_f32_32x32x16_bf16 v[64:79], v[238:241], v[168:171], v[64:79]
	v_mfma_f32_32x32x16_bf16 v[0:15], v[238:241], v[172:175], v[0:15]
	s_setprio 0
	global_load_dwordx4 v[234:237], v[194:195], off offset:3840
	global_load_dwordx4 v[238:241], v[196:197], off offset:3840
	s_waitcnt vmcnt(9)
	ds_write_b128 v212, v[160:163]
	s_waitcnt vmcnt(8)
	ds_write_b128 v211, v[164:167]
	ds_read_b128 v[160:163], v204 offset:36896
	ds_read_b128 v[164:167], v204 offset:41504
	ds_read_b128 v[168:171], v192 offset:32
	ds_read_b128 v[172:175], v192 offset:4640
	s_setprio 1
	s_waitcnt lgkmcnt(1)
	v_mfma_f32_32x32x16_bf16 v[112:127], v[168:171], v[160:163], v[112:127]
	v_mfma_f32_32x32x16_bf16 v[48:63], v[168:171], v[164:167], v[48:63]
	s_waitcnt lgkmcnt(0)
	v_mfma_f32_32x32x16_bf16 v[96:111], v[172:175], v[160:163], v[96:111]
	v_mfma_f32_32x32x16_bf16 v[32:47], v[172:175], v[164:167], v[32:47]
	ds_read_b128 v[168:171], v192 offset:9248
	ds_read_b128 v[172:175], v192 offset:13856
	s_waitcnt lgkmcnt(1)
	v_mfma_f32_32x32x16_bf16 v[80:95], v[168:171], v[160:163], v[80:95]
	v_mfma_f32_32x32x16_bf16 v[16:31], v[168:171], v[164:167], v[16:31]
	s_waitcnt lgkmcnt(0)
	v_mfma_f32_32x32x16_bf16 v[64:79], v[172:175], v[160:163], v[64:79]
	v_mfma_f32_32x32x16_bf16 v[0:15], v[172:175], v[164:167], v[0:15]
	s_setprio 0
	global_load_dwordx4 v[242:245], v[184:185], off offset:3840
	global_load_dwordx4 v[246:249], v[186:187], off offset:3840
	s_waitcnt vmcnt(9)
	ds_write_b128 v214, v[218:221]
	s_waitcnt vmcnt(8)
	ds_write_b128 v213, v[222:225]
	ds_read_b128 v[160:163], v204 offset:36928
	ds_read_b128 v[164:167], v204 offset:41536
	ds_read_b128 v[168:171], v192 offset:64
	ds_read_b128 v[172:175], v192 offset:4672
	s_setprio 1
	s_waitcnt lgkmcnt(1)
	v_mfma_f32_32x32x16_bf16 v[112:127], v[168:171], v[160:163], v[112:127]
	v_mfma_f32_32x32x16_bf16 v[48:63], v[168:171], v[164:167], v[48:63]
	s_waitcnt lgkmcnt(0)
	v_mfma_f32_32x32x16_bf16 v[96:111], v[172:175], v[160:163], v[96:111]
	v_mfma_f32_32x32x16_bf16 v[32:47], v[172:175], v[164:167], v[32:47]
	ds_read_b128 v[168:171], v192 offset:9280
	ds_read_b128 v[172:175], v192 offset:13888
	s_waitcnt lgkmcnt(1)
	v_mfma_f32_32x32x16_bf16 v[80:95], v[168:171], v[160:163], v[80:95]
	v_mfma_f32_32x32x16_bf16 v[16:31], v[168:171], v[164:167], v[16:31]
	s_waitcnt lgkmcnt(0)
	v_mfma_f32_32x32x16_bf16 v[64:79], v[172:175], v[160:163], v[64:79]
	v_mfma_f32_32x32x16_bf16 v[0:15], v[172:175], v[164:167], v[0:15]
	s_setprio 0
	global_load_dwordx4 v[218:221], v[198:199], off offset:3840
	global_load_dwordx4 v[222:225], v[200:201], off offset:3840
	s_waitcnt vmcnt(9)
	ds_write_b128 v217, v[226:229]
	s_waitcnt vmcnt(8)
	ds_write_b128 v216, v[230:233]
	ds_read_b128 v[160:163], v204 offset:36960
	ds_read_b128 v[164:167], v204 offset:41568
	ds_read_b128 v[168:171], v192 offset:96
	ds_read_b128 v[172:175], v192 offset:4704
	s_setprio 1
	s_waitcnt lgkmcnt(1)
	v_mfma_f32_32x32x16_bf16 v[112:127], v[168:171], v[160:163], v[112:127]
	v_mfma_f32_32x32x16_bf16 v[48:63], v[168:171], v[164:167], v[48:63]
	s_waitcnt lgkmcnt(0)
	v_mfma_f32_32x32x16_bf16 v[96:111], v[172:175], v[160:163], v[96:111]
	v_mfma_f32_32x32x16_bf16 v[32:47], v[172:175], v[164:167], v[32:47]
	ds_read_b128 v[168:171], v192 offset:9312
	ds_read_b128 v[172:175], v192 offset:13920
	s_waitcnt lgkmcnt(1)
	v_mfma_f32_32x32x16_bf16 v[80:95], v[168:171], v[160:163], v[80:95]
	v_mfma_f32_32x32x16_bf16 v[16:31], v[168:171], v[164:167], v[16:31]
	s_waitcnt lgkmcnt(0)
	v_mfma_f32_32x32x16_bf16 v[64:79], v[172:175], v[160:163], v[64:79]
	v_mfma_f32_32x32x16_bf16 v[0:15], v[172:175], v[164:167], v[0:15]
	s_setprio 0
	s_barrier
	global_load_dwordx4 v[160:163], v[190:191], off offset:3968
	global_load_dwordx4 v[164:167], v[188:189], off offset:3968
	s_waitcnt vmcnt(9)
	ds_write_b128 v215, v[176:179]
	s_waitcnt vmcnt(8)
	ds_write_b128 v215, v[180:183] offset:36864
	ds_read_b128 v[168:171], v208
	ds_read_b128 v[172:175], v208 offset:4608
	ds_read_b128 v[176:179], v205
	ds_read_b128 v[180:183], v205 offset:4608
	s_setprio 1
	s_waitcnt lgkmcnt(1)
	v_mfma_f32_32x32x16_bf16 v[112:127], v[176:179], v[168:171], v[112:127]
	v_mfma_f32_32x32x16_bf16 v[48:63], v[176:179], v[172:175], v[48:63]
	s_waitcnt lgkmcnt(0)
	v_mfma_f32_32x32x16_bf16 v[96:111], v[180:183], v[168:171], v[96:111]
	v_mfma_f32_32x32x16_bf16 v[32:47], v[180:183], v[172:175], v[32:47]
	ds_read_b128 v[176:179], v205 offset:9216
	ds_read_b128 v[180:183], v205 offset:13824
	s_waitcnt lgkmcnt(1)
	v_mfma_f32_32x32x16_bf16 v[80:95], v[176:179], v[168:171], v[80:95]
	v_mfma_f32_32x32x16_bf16 v[16:31], v[176:179], v[172:175], v[16:31]
	s_waitcnt lgkmcnt(0)
	v_mfma_f32_32x32x16_bf16 v[64:79], v[180:183], v[168:171], v[64:79]
	v_mfma_f32_32x32x16_bf16 v[0:15], v[180:183], v[172:175], v[0:15]
	s_setprio 0
	global_load_dwordx4 v[168:171], v[194:195], off offset:3968
	global_load_dwordx4 v[172:175], v[196:197], off offset:3968
	s_waitcnt vmcnt(9)
	ds_write_b128 v215, v[234:237] offset:9216
	s_waitcnt vmcnt(8)
	ds_write_b128 v215, v[238:241] offset:46080
	ds_read_b128 v[176:179], v208 offset:32
	ds_read_b128 v[180:183], v208 offset:4640
	ds_read_b128 v[188:191], v205 offset:32
	ds_read_b128 v[194:197], v205 offset:4640
	s_setprio 1
	s_waitcnt lgkmcnt(1)
	v_mfma_f32_32x32x16_bf16 v[112:127], v[188:191], v[176:179], v[112:127]
	v_mfma_f32_32x32x16_bf16 v[48:63], v[188:191], v[180:183], v[48:63]
	s_waitcnt lgkmcnt(0)
	v_mfma_f32_32x32x16_bf16 v[96:111], v[194:197], v[176:179], v[96:111]
	v_mfma_f32_32x32x16_bf16 v[32:47], v[194:197], v[180:183], v[32:47]
	ds_read_b128 v[188:191], v205 offset:9248
	ds_read_b128 v[194:197], v205 offset:13856
	s_waitcnt lgkmcnt(1)
	v_mfma_f32_32x32x16_bf16 v[80:95], v[188:191], v[176:179], v[80:95]
	v_mfma_f32_32x32x16_bf16 v[16:31], v[188:191], v[180:183], v[16:31]
	s_waitcnt lgkmcnt(0)
	v_mfma_f32_32x32x16_bf16 v[64:79], v[194:197], v[176:179], v[64:79]
	v_mfma_f32_32x32x16_bf16 v[0:15], v[194:197], v[180:183], v[0:15]
	s_setprio 0
	global_load_dwordx4 v[176:179], v[184:185], off offset:3968
	global_load_dwordx4 v[180:183], v[186:187], off offset:3968
	s_waitcnt vmcnt(9)
	ds_write_b128 v215, v[242:245] offset:18432
	s_waitcnt vmcnt(8)
	ds_write_b128 v215, v[246:249] offset:55296
	ds_read_b128 v[184:187], v208 offset:64
	ds_read_b128 v[188:191], v208 offset:4672
	ds_read_b128 v[194:197], v205 offset:64
	ds_read_b128 v[226:229], v205 offset:4672
	s_setprio 1
	s_waitcnt lgkmcnt(1)
	v_mfma_f32_32x32x16_bf16 v[112:127], v[194:197], v[184:187], v[112:127]
	v_mfma_f32_32x32x16_bf16 v[48:63], v[194:197], v[188:191], v[48:63]
	s_waitcnt lgkmcnt(0)
	v_mfma_f32_32x32x16_bf16 v[96:111], v[226:229], v[184:187], v[96:111]
	v_mfma_f32_32x32x16_bf16 v[32:47], v[226:229], v[188:191], v[32:47]
	ds_read_b128 v[194:197], v205 offset:9280
	ds_read_b128 v[226:229], v205 offset:13888
	s_waitcnt lgkmcnt(1)
	v_mfma_f32_32x32x16_bf16 v[80:95], v[194:197], v[184:187], v[80:95]
	v_mfma_f32_32x32x16_bf16 v[16:31], v[194:197], v[188:191], v[16:31]
	s_waitcnt lgkmcnt(0)
	v_mfma_f32_32x32x16_bf16 v[64:79], v[226:229], v[184:187], v[64:79]
	v_mfma_f32_32x32x16_bf16 v[0:15], v[226:229], v[188:191], v[0:15]
	s_setprio 0
	global_load_dwordx4 v[184:187], v[198:199], off offset:3968
	global_load_dwordx4 v[188:191], v[200:201], off offset:3968
	s_waitcnt vmcnt(9)
	ds_write_b128 v215, v[218:221] offset:27648
	s_waitcnt vmcnt(8)
	ds_write_b128 v215, v[222:225] offset:64512
	ds_read_b128 v[194:197], v208 offset:96
	ds_read_b128 v[198:201], v208 offset:4704
	ds_read_b128 v[218:221], v205 offset:96
	ds_read_b128 v[222:225], v205 offset:4704
	s_setprio 1
	s_waitcnt lgkmcnt(1)
	v_mfma_f32_32x32x16_bf16 v[112:127], v[218:221], v[194:197], v[112:127]
	v_mfma_f32_32x32x16_bf16 v[48:63], v[218:221], v[198:201], v[48:63]
	s_waitcnt lgkmcnt(0)
	v_mfma_f32_32x32x16_bf16 v[96:111], v[222:225], v[194:197], v[96:111]
	v_mfma_f32_32x32x16_bf16 v[32:47], v[222:225], v[198:201], v[32:47]
	ds_read_b128 v[218:221], v205 offset:9312
	ds_read_b128 v[222:225], v205 offset:13920
	s_waitcnt lgkmcnt(1)
	v_mfma_f32_32x32x16_bf16 v[80:95], v[218:221], v[194:197], v[80:95]
	v_mfma_f32_32x32x16_bf16 v[16:31], v[218:221], v[198:201], v[16:31]
	s_waitcnt lgkmcnt(0)
	v_mfma_f32_32x32x16_bf16 v[64:79], v[222:225], v[194:197], v[64:79]
	v_mfma_f32_32x32x16_bf16 v[0:15], v[222:225], v[198:201], v[0:15]
	s_setprio 0
	s_barrier
	s_waitcnt vmcnt(7)
	ds_write_b128 v209, v[160:163]
	s_waitcnt vmcnt(6)
	ds_write_b128 v210, v[164:167]
	ds_read_b128 v[194:197], v204 offset:36864
	ds_read_b128 v[198:201], v204 offset:41472
	ds_read_b128 v[218:221], v192
	ds_read_b128 v[222:225], v192 offset:4608
	s_setprio 1
	s_waitcnt lgkmcnt(1)
	v_mfma_f32_32x32x16_bf16 v[112:127], v[218:221], v[194:197], v[112:127]
	v_mfma_f32_32x32x16_bf16 v[48:63], v[218:221], v[198:201], v[48:63]
	s_waitcnt lgkmcnt(0)
	v_mfma_f32_32x32x16_bf16 v[96:111], v[222:225], v[194:197], v[96:111]
	v_mfma_f32_32x32x16_bf16 v[32:47], v[222:225], v[198:201], v[32:47]
	ds_read_b128 v[218:221], v192 offset:9216
	ds_read_b128 v[222:225], v192 offset:13824
	s_waitcnt lgkmcnt(1)
	v_mfma_f32_32x32x16_bf16 v[80:95], v[218:221], v[194:197], v[80:95]
	v_mfma_f32_32x32x16_bf16 v[16:31], v[218:221], v[198:201], v[16:31]
	s_waitcnt lgkmcnt(0)
	v_mfma_f32_32x32x16_bf16 v[64:79], v[222:225], v[194:197], v[64:79]
	v_mfma_f32_32x32x16_bf16 v[0:15], v[222:225], v[198:201], v[0:15]
	s_setprio 0
	s_waitcnt vmcnt(5)
	ds_write_b128 v212, v[168:171]
	s_waitcnt vmcnt(4)
	ds_write_b128 v211, v[172:175]
	ds_read_b128 v[194:197], v204 offset:36896
	ds_read_b128 v[198:201], v204 offset:41504
	ds_read_b128 v[218:221], v192 offset:32
	ds_read_b128 v[222:225], v192 offset:4640
	s_setprio 1
	s_waitcnt lgkmcnt(1)
	v_mfma_f32_32x32x16_bf16 v[112:127], v[218:221], v[194:197], v[112:127]
	v_mfma_f32_32x32x16_bf16 v[48:63], v[218:221], v[198:201], v[48:63]
	s_waitcnt lgkmcnt(0)
	v_mfma_f32_32x32x16_bf16 v[96:111], v[222:225], v[194:197], v[96:111]
	v_mfma_f32_32x32x16_bf16 v[32:47], v[222:225], v[198:201], v[32:47]
	ds_read_b128 v[218:221], v192 offset:9248
	ds_read_b128 v[222:225], v192 offset:13856
	s_waitcnt lgkmcnt(1)
	v_mfma_f32_32x32x16_bf16 v[80:95], v[218:221], v[194:197], v[80:95]
	v_mfma_f32_32x32x16_bf16 v[16:31], v[218:221], v[198:201], v[16:31]
	s_waitcnt lgkmcnt(0)
	v_mfma_f32_32x32x16_bf16 v[64:79], v[222:225], v[194:197], v[64:79]
	v_mfma_f32_32x32x16_bf16 v[0:15], v[222:225], v[198:201], v[0:15]
	s_setprio 0
	s_waitcnt vmcnt(3)
	ds_write_b128 v214, v[176:179]
	s_waitcnt vmcnt(2)
	ds_write_b128 v213, v[180:183]
	ds_read_b128 v[194:197], v204 offset:36928
	ds_read_b128 v[198:201], v204 offset:41536
	ds_read_b128 v[210:213], v192 offset:64
	ds_read_b128 v[218:221], v192 offset:4672
	s_setprio 1
	s_waitcnt lgkmcnt(1)
	v_mfma_f32_32x32x16_bf16 v[112:127], v[210:213], v[194:197], v[112:127]
	v_mfma_f32_32x32x16_bf16 v[48:63], v[210:213], v[198:201], v[48:63]
	s_waitcnt lgkmcnt(0)
	v_mfma_f32_32x32x16_bf16 v[96:111], v[218:221], v[194:197], v[96:111]
	v_mfma_f32_32x32x16_bf16 v[32:47], v[218:221], v[198:201], v[32:47]
	ds_read_b128 v[210:213], v192 offset:9280
	ds_read_b128 v[218:221], v192 offset:13888
	s_waitcnt lgkmcnt(1)
	v_mfma_f32_32x32x16_bf16 v[80:95], v[210:213], v[194:197], v[80:95]
	v_mfma_f32_32x32x16_bf16 v[16:31], v[210:213], v[198:201], v[16:31]
	s_waitcnt lgkmcnt(0)
	v_mfma_f32_32x32x16_bf16 v[64:79], v[218:221], v[194:197], v[64:79]
	v_mfma_f32_32x32x16_bf16 v[0:15], v[218:221], v[198:201], v[0:15]
	s_setprio 0
	s_waitcnt vmcnt(1)
	ds_write_b128 v217, v[184:187]
	s_waitcnt vmcnt(0)
	ds_write_b128 v216, v[188:191]
	ds_read_b128 v[194:197], v204 offset:36960
	ds_read_b128 v[198:201], v204 offset:41568
	ds_read_b128 v[210:213], v192 offset:96
	ds_read_b128 v[214:217], v192 offset:4704
	s_setprio 1
	s_waitcnt lgkmcnt(1)
	v_mfma_f32_32x32x16_bf16 v[112:127], v[210:213], v[194:197], v[112:127]
	v_mfma_f32_32x32x16_bf16 v[48:63], v[210:213], v[198:201], v[48:63]
	s_waitcnt lgkmcnt(0)
	v_mfma_f32_32x32x16_bf16 v[96:111], v[214:217], v[194:197], v[96:111]
	v_mfma_f32_32x32x16_bf16 v[32:47], v[214:217], v[198:201], v[32:47]
	ds_read_b128 v[210:213], v192 offset:9312
	ds_read_b128 v[214:217], v192 offset:13920
	s_waitcnt lgkmcnt(1)
	v_mfma_f32_32x32x16_bf16 v[80:95], v[210:213], v[194:197], v[80:95]
	v_mfma_f32_32x32x16_bf16 v[16:31], v[210:213], v[198:201], v[16:31]
	s_waitcnt lgkmcnt(0)
	v_mfma_f32_32x32x16_bf16 v[64:79], v[214:217], v[194:197], v[64:79]
	v_mfma_f32_32x32x16_bf16 v[0:15], v[214:217], v[198:201], v[0:15]
	s_setprio 0
	s_barrier
; template <bool trans>
; DI void gemm_core(const GTile& tl, const GTile& nx, bool has_next  , bool chain  , bool pre, u32x4 (&ra)[4], u32x4 (&rb)[4], char* smem, f32x16 (&acc)[2][4]) {
;     ...
;   const int nk = K / 64;
;   if (!pre) { G_LOAD(0); G_STORE(0); G_LOAD(1); }
;   for (int kt = 0; kt < nk; ++kt) {
;     __syncthreads();
;     G_COMPUTE(kt & 1, kt);
;   }
;   if (!has_next) __syncthreads();
	ds_read_b128 v[194:197], v208
	ds_read_b128 v[198:201], v208 offset:4608
	ds_read_b128 v[210:213], v205
	ds_read_b128 v[214:217], v205 offset:4608
	s_setprio 1
	s_waitcnt lgkmcnt(1)
	v_mfma_f32_32x32x16_bf16 v[112:127], v[210:213], v[194:197], v[112:127]
	v_mfma_f32_32x32x16_bf16 v[48:63], v[210:213], v[198:201], v[48:63]
	s_waitcnt lgkmcnt(0)
	v_mfma_f32_32x32x16_bf16 v[96:111], v[214:217], v[194:197], v[96:111]
	v_mfma_f32_32x32x16_bf16 v[32:47], v[214:217], v[198:201], v[32:47]
	ds_read_b128 v[210:213], v205 offset:9216
	ds_read_b128 v[214:217], v205 offset:13824
	s_waitcnt lgkmcnt(1)
	v_mfma_f32_32x32x16_bf16 v[80:95], v[210:213], v[194:197], v[80:95]
	v_mfma_f32_32x32x16_bf16 v[16:31], v[210:213], v[198:201], v[16:31]
	s_waitcnt lgkmcnt(0)
	v_mfma_f32_32x32x16_bf16 v[64:79], v[214:217], v[194:197], v[64:79]
	v_mfma_f32_32x32x16_bf16 v[0:15], v[214:217], v[198:201], v[0:15]
	s_setprio 0
	ds_read_b128 v[194:197], v208 offset:32
	ds_read_b128 v[198:201], v208 offset:4640
	ds_read_b128 v[210:213], v205 offset:32
	ds_read_b128 v[214:217], v205 offset:4640
	s_setprio 1
	s_waitcnt lgkmcnt(1)
	v_mfma_f32_32x32x16_bf16 v[112:127], v[210:213], v[194:197], v[112:127]
	v_mfma_f32_32x32x16_bf16 v[48:63], v[210:213], v[198:201], v[48:63]
	s_waitcnt lgkmcnt(0)
	v_mfma_f32_32x32x16_bf16 v[96:111], v[214:217], v[194:197], v[96:111]
	v_mfma_f32_32x32x16_bf16 v[32:47], v[214:217], v[198:201], v[32:47]
	ds_read_b128 v[210:213], v205 offset:9248
	ds_read_b128 v[214:217], v205 offset:13856
	s_waitcnt lgkmcnt(1)
	v_mfma_f32_32x32x16_bf16 v[80:95], v[210:213], v[194:197], v[80:95]
	v_mfma_f32_32x32x16_bf16 v[16:31], v[210:213], v[198:201], v[16:31]
	s_waitcnt lgkmcnt(0)
	v_mfma_f32_32x32x16_bf16 v[64:79], v[214:217], v[194:197], v[64:79]
	v_mfma_f32_32x32x16_bf16 v[0:15], v[214:217], v[198:201], v[0:15]
	s_setprio 0
	ds_read_b128 v[194:197], v208 offset:64
	ds_read_b128 v[198:201], v208 offset:4672
	ds_read_b128 v[210:213], v205 offset:64
	ds_read_b128 v[214:217], v205 offset:4672
	s_setprio 1
	s_waitcnt lgkmcnt(1)
	v_mfma_f32_32x32x16_bf16 v[112:127], v[210:213], v[194:197], v[112:127]
	v_mfma_f32_32x32x16_bf16 v[48:63], v[210:213], v[198:201], v[48:63]
	s_waitcnt lgkmcnt(0)
	v_mfma_f32_32x32x16_bf16 v[96:111], v[214:217], v[194:197], v[96:111]
	v_mfma_f32_32x32x16_bf16 v[32:47], v[214:217], v[198:201], v[32:47]
	ds_read_b128 v[210:213], v205 offset:9280
	ds_read_b128 v[214:217], v205 offset:13888
	s_waitcnt lgkmcnt(1)
	v_mfma_f32_32x32x16_bf16 v[80:95], v[210:213], v[194:197], v[80:95]
	v_mfma_f32_32x32x16_bf16 v[16:31], v[210:213], v[198:201], v[16:31]
	s_waitcnt lgkmcnt(0)
	v_mfma_f32_32x32x16_bf16 v[64:79], v[214:217], v[194:197], v[64:79]
	v_mfma_f32_32x32x16_bf16 v[0:15], v[214:217], v[198:201], v[0:15]
	s_setprio 0
	ds_read_b128 v[194:197], v208 offset:96
	ds_read_b128 v[198:201], v208 offset:4704
	ds_read_b128 v[208:211], v205 offset:96
	ds_read_b128 v[212:215], v205 offset:4704
	s_setprio 1
	s_waitcnt lgkmcnt(1)
	v_mfma_f32_32x32x16_bf16 v[112:127], v[208:211], v[194:197], v[112:127]
	v_mfma_f32_32x32x16_bf16 v[48:63], v[208:211], v[198:201], v[48:63]
	s_waitcnt lgkmcnt(0)
	v_mfma_f32_32x32x16_bf16 v[96:111], v[212:215], v[194:197], v[96:111]
	v_mfma_f32_32x32x16_bf16 v[32:47], v[212:215], v[198:201], v[32:47]
	ds_read_b128 v[208:211], v205 offset:9312
	ds_read_b128 v[212:215], v205 offset:13920
	s_waitcnt lgkmcnt(1)
	v_mfma_f32_32x32x16_bf16 v[80:95], v[208:211], v[194:197], v[80:95]
	v_mfma_f32_32x32x16_bf16 v[16:31], v[208:211], v[198:201], v[16:31]
	s_waitcnt lgkmcnt(0)
	v_mfma_f32_32x32x16_bf16 v[64:79], v[212:215], v[194:197], v[64:79]
	v_mfma_f32_32x32x16_bf16 v[0:15], v[212:215], v[198:201], v[0:15]
	s_setprio 0
	s_andn2_b64 vcc, exec, s[30:31]
	s_cbranch_vccnz .LBB0_884
	s_barrier

;   DI bf16_t* wt_in1() const { return (bf16_t*)(ws + OFF_WT_IN1); }
;   DI bf16_t* h() const { return (bf16_t*)(ws + OFF_H); }
; template <bool trans>
; DI void gemm_core(const GTile& tl, const GTile& nx, bool has_next  , bool chain  , bool pre, u32x4 (&ra)[4], u32x4 (&rb)[4], char* smem, f32x16 (&acc)[2][4]) {
;     ...
;   const int nk = K / 64;
;   if (!pre) { G_LOAD(0); G_STORE(0); G_LOAD(1); }
;   for (int kt = 0; kt < nk; ++kt) {
;     __syncthreads();
;     G_COMPUTE(kt & 1, kt);
; DI int in1_nt(int t) { return (t >> 6) < 23 ? (t >> 6) : 25; }
; DI void phase_gemm_in1(const Params& p, char* smem) {
;   u32x4 ra[4], rb[4]; bool pre = false;
;   for (int t = blockIdx.x; t < 64 * 24; t += gridDim.x) {
;     const int mt = t & 63, nt = in1_nt(t), tn = t + gridDim.x;
;     const bool has_next = tn < 64 * 24;
;     const GTile tl{p.h(), D, p.wt_in1(), D, D, mt * 256, nt * 256}, nx{p.h(), D, p.wt_in1(), D, D, (tn & 63) * 256, in1_nt(tn) * 256};
.LBB0_890:
	v_lshl_add_u64 v[136:137], s[2:3], 0, v[192:193]
	v_lshl_add_u64 v[138:139], s[16:17], 0, v[192:193]
	s_waitcnt lgkmcnt(0)
	s_barrier
	global_load_dwordx4 v[184:187], v[136:137], off offset:256
	global_load_dwordx4 v[188:191], v[138:139], off offset:256
	s_ashr_i32 s2, s56, 6
	s_lshl_b32 s3, s2, 8
	s_cmp_lt_i32 s2, 23
	s_cselect_b32 s2, s3, 0x1900
	s_and_b32 s3, s49, 0x1f80000
	s_and_b32 s16, s18, 0xc0
	s_lshl_b32 s3, s3, 1
	s_add_u32 s6, s24, s3
	s_addc_u32 s7, s25, 0
	s_ashr_i32 s3, s2, 31
	s_lshl_b64 s[2:3], s[2:3], 12
	s_add_u32 s2, s27, s2
	s_addc_u32 s3, s40, s3
	s_lshr_b32 s17, s18, 1
	v_and_b32_e32 v11, 31, v8
	s_and_b32 s17, s17, 0xfffff80
	v_or_b32_e32 v12, s17, v11
	v_or_b32_e32 v11, s16, v11
	v_add3_u32 v148, 16, v10, v9
	v_lshrrev_b32_e32 v8, 1, v8
	v_mul_u32_u24_e32 v150, 0x90, v11
	v_lshl_add_u64 v[130:131], s[6:7], 0, v[192:193]
	v_lshl_add_u64 v[128:129], s[2:3], 0, v[192:193]
	v_and_b32_e32 v204, 16, v8
	v_add_u32_e32 v192, 0x12000, v148
	v_mul_lo_u32 v149, v12, s54
	v_add3_u32 v152, 16, v150, v204
	v_add_u32_e32 v159, 0x1b000, v148
	ds_write_b128 v192, v[0:3]
	s_waitcnt vmcnt(5)
	ds_write_b128 v159, v[4:7]
	v_add3_u32 v151, 16, v149, v204
	ds_read_b128 v[0:3], v152 offset:36864
	ds_read_b128 v[16:19], v152 offset:41472
	ds_read_b128 v[4:7], v151
	ds_read_b128 v[8:11], v151 offset:4608
	v_lshl_add_u64 v[140:141], v[136:137], 0, s[12:13]
	v_lshl_add_u64 v[142:143], v[138:139], 0, s[12:13]
	v_lshl_add_u64 v[132:133], v[136:137], 0, s[14:15]
	v_lshl_add_u64 v[134:135], v[138:139], 0, s[14:15]
	s_setprio 1
	s_waitcnt lgkmcnt(1)
	v_mfma_f32_32x32x16_bf16 v[96:111], v[0:3], v[4:7], 0
	v_mfma_f32_32x32x16_bf16 v[112:127], v[16:19], v[4:7], 0
	ds_read_b128 v[4:7], v151 offset:9216
	ds_read_b128 v[20:23], v151 offset:13824
	s_waitcnt lgkmcnt(2)
	v_mfma_f32_32x32x16_bf16 v[64:79], v[0:3], v[8:11], 0
	v_mfma_f32_32x32x16_bf16 v[80:95], v[16:19], v[8:11], 0
	s_waitcnt lgkmcnt(1)
	v_mfma_f32_32x32x16_bf16 v[32:47], v[0:3], v[4:7], 0
	v_mfma_f32_32x32x16_bf16 v[48:63], v[16:19], v[4:7], 0
	s_waitcnt lgkmcnt(0)
	v_mfma_f32_32x32x16_bf16 v[0:15], v[0:3], v[20:23], 0
	v_mfma_f32_32x32x16_bf16 v[16:31], v[16:19], v[20:23], 0
	s_setprio 0
	global_load_dwordx4 v[194:197], v[140:141], off offset:256
	global_load_dwordx4 v[198:201], v[142:143], off offset:256
	v_add_u32_e32 v158, 0x14400, v148
	v_add_u32_e32 v157, 0x1d400, v148
	ds_write_b128 v158, v[176:179]
	s_waitcnt vmcnt(6)
	ds_write_b128 v157, v[180:183]
	ds_read_b128 v[144:147], v152 offset:36896
	ds_read_b128 v[176:179], v152 offset:41504
	ds_read_b128 v[180:183], v151 offset:32
	ds_read_b128 v[208:211], v151 offset:4640
	s_setprio 1
	s_waitcnt lgkmcnt(1)
	v_mfma_f32_32x32x16_bf16 v[96:111], v[144:147], v[180:183], v[96:111]
	v_mfma_f32_32x32x16_bf16 v[112:127], v[176:179], v[180:183], v[112:127]
	s_waitcnt lgkmcnt(0)
	v_mfma_f32_32x32x16_bf16 v[64:79], v[144:147], v[208:211], v[64:79]
	v_mfma_f32_32x32x16_bf16 v[80:95], v[176:179], v[208:211], v[80:95]
	ds_read_b128 v[180:183], v151 offset:9248
	ds_read_b128 v[208:211], v151 offset:13856
	s_waitcnt lgkmcnt(1)
	v_mfma_f32_32x32x16_bf16 v[32:47], v[144:147], v[180:183], v[32:47]
	v_mfma_f32_32x32x16_bf16 v[48:63], v[176:179], v[180:183], v[48:63]
	s_waitcnt lgkmcnt(0)
	v_mfma_f32_32x32x16_bf16 v[0:15], v[144:147], v[208:211], v[0:15]
	v_mfma_f32_32x32x16_bf16 v[16:31], v[176:179], v[208:211], v[16:31]
	s_setprio 0
	global_load_dwordx4 v[176:179], v[132:133], off offset:256
	global_load_dwordx4 v[180:183], v[134:135], off offset:256
	v_add_u32_e32 v154, 0x16800, v148
	v_add_u32_e32 v153, 0x1f800, v148
	ds_write_b128 v154, v[168:171]
	s_waitcnt vmcnt(7)
	ds_write_b128 v153, v[172:175]
	ds_read_b128 v[144:147], v152 offset:36928
	ds_read_b128 v[168:171], v152 offset:41536
	ds_read_b128 v[172:175], v151 offset:64
	ds_read_b128 v[208:211], v151 offset:4672
	s_setprio 1
	s_waitcnt lgkmcnt(1)
	v_mfma_f32_32x32x16_bf16 v[96:111], v[144:147], v[172:175], v[96:111]
	v_mfma_f32_32x32x16_bf16 v[112:127], v[168:171], v[172:175], v[112:127]
	s_waitcnt lgkmcnt(0)
	v_mfma_f32_32x32x16_bf16 v[64:79], v[144:147], v[208:211], v[64:79]
	v_mfma_f32_32x32x16_bf16 v[80:95], v[168:171], v[208:211], v[80:95]
	ds_read_b128 v[172:175], v151 offset:9280
	ds_read_b128 v[208:211], v151 offset:13888
	s_waitcnt lgkmcnt(1)
	v_mfma_f32_32x32x16_bf16 v[32:47], v[144:147], v[172:175], v[32:47]
	v_mfma_f32_32x32x16_bf16 v[48:63], v[168:171], v[172:175], v[48:63]
	s_waitcnt lgkmcnt(0)
	v_mfma_f32_32x32x16_bf16 v[0:15], v[144:147], v[208:211], v[0:15]
	v_mfma_f32_32x32x16_bf16 v[16:31], v[168:171], v[208:211], v[16:31]
	s_setprio 0
	v_add_co_u32_e32 v144, vcc, s53, v136
	v_add_u32_e32 v156, 0x18c00, v148
	s_nop 0
	v_addc_co_u32_e32 v145, vcc, 0, v137, vcc
	v_add_co_u32_e32 v146, vcc, s53, v138
	v_add_u32_e32 v155, 0x21c00, v148
	s_nop 0
	v_addc_co_u32_e32 v147, vcc, 0, v139, vcc
	global_load_dwordx4 v[168:171], v[144:145], off offset:256
	global_load_dwordx4 v[172:175], v[146:147], off offset:256
	ds_write_b128 v156, v[160:163]
	s_waitcnt vmcnt(8)
	ds_write_b128 v155, v[164:167]
	ds_read_b128 v[160:163], v152 offset:36960
	ds_read_b128 v[164:167], v152 offset:41568
	ds_read_b128 v[208:211], v151 offset:96
	ds_read_b128 v[212:215], v151 offset:4704
	s_setprio 1
	s_waitcnt lgkmcnt(1)
	v_mfma_f32_32x32x16_bf16 v[96:111], v[160:163], v[208:211], v[96:111]
	v_mfma_f32_32x32x16_bf16 v[112:127], v[164:167], v[208:211], v[112:127]
	s_waitcnt lgkmcnt(0)
	v_mfma_f32_32x32x16_bf16 v[64:79], v[160:163], v[212:215], v[64:79]
	v_mfma_f32_32x32x16_bf16 v[80:95], v[164:167], v[212:215], v[80:95]
	ds_read_b128 v[208:211], v151 offset:9312
	ds_read_b128 v[212:215], v151 offset:13920
	s_waitcnt lgkmcnt(1)
	v_mfma_f32_32x32x16_bf16 v[32:47], v[160:163], v[208:211], v[32:47]
	v_mfma_f32_32x32x16_bf16 v[48:63], v[164:167], v[208:211], v[48:63]
	s_waitcnt lgkmcnt(0)
	v_mfma_f32_32x32x16_bf16 v[0:15], v[160:163], v[212:215], v[0:15]
	v_mfma_f32_32x32x16_bf16 v[16:31], v[164:167], v[212:215], v[16:31]
	s_setprio 0
	s_barrier
	global_load_dwordx4 v[160:163], v[136:137], off offset:384
	global_load_dwordx4 v[164:167], v[138:139], off offset:384
	s_add_i32 s2, 16, 0x12000
	v_add3_u32 v149, s2, v149, v204
	s_add_i32 s2, 16, 0x1b000
	v_add3_u32 v150, s2, v150, v204
	s_waitcnt vmcnt(9)
	ds_write_b128 v148, v[184:187]
	s_waitcnt vmcnt(8)
	ds_write_b128 v148, v[188:191] offset:36864
	ds_read_b128 v[184:187], v150
	ds_read_b128 v[188:191], v150 offset:4608
	ds_read_b128 v[208:211], v149
	ds_read_b128 v[212:215], v149 offset:4608
	s_setprio 1
	s_waitcnt lgkmcnt(1)
	v_mfma_f32_32x32x16_bf16 v[96:111], v[184:187], v[208:211], v[96:111]
	v_mfma_f32_32x32x16_bf16 v[112:127], v[188:191], v[208:211], v[112:127]
	s_waitcnt lgkmcnt(0)
	v_mfma_f32_32x32x16_bf16 v[64:79], v[184:187], v[212:215], v[64:79]
	v_mfma_f32_32x32x16_bf16 v[80:95], v[188:191], v[212:215], v[80:95]
	ds_read_b128 v[208:211], v149 offset:9216
	ds_read_b128 v[212:215], v149 offset:13824
	s_waitcnt lgkmcnt(1)
	v_mfma_f32_32x32x16_bf16 v[32:47], v[184:187], v[208:211], v[32:47]
	v_mfma_f32_32x32x16_bf16 v[48:63], v[188:191], v[208:211], v[48:63]
	s_waitcnt lgkmcnt(0)
	v_mfma_f32_32x32x16_bf16 v[0:15], v[184:187], v[212:215], v[0:15]
	v_mfma_f32_32x32x16_bf16 v[16:31], v[188:191], v[212:215], v[16:31]
	s_setprio 0
	global_load_dwordx4 v[184:187], v[140:141], off offset:384
	global_load_dwordx4 v[188:191], v[142:143], off offset:384
	s_waitcnt vmcnt(9)
	ds_write_b128 v148, v[194:197] offset:9216
	s_waitcnt vmcnt(8)
	ds_write_b128 v148, v[198:201] offset:46080
	ds_read_b128 v[194:197], v150 offset:32
	ds_read_b128 v[198:201], v150 offset:4640
	ds_read_b128 v[208:211], v149 offset:32
	ds_read_b128 v[212:215], v149 offset:4640
	s_setprio 1
	s_waitcnt lgkmcnt(1)
	v_mfma_f32_32x32x16_bf16 v[96:111], v[194:197], v[208:211], v[96:111]
	v_mfma_f32_32x32x16_bf16 v[112:127], v[198:201], v[208:211], v[112:127]
	s_waitcnt lgkmcnt(0)
	v_mfma_f32_32x32x16_bf16 v[64:79], v[194:197], v[212:215], v[64:79]
	v_mfma_f32_32x32x16_bf16 v[80:95], v[198:201], v[212:215], v[80:95]
	ds_read_b128 v[208:211], v149 offset:9248
	ds_read_b128 v[212:215], v149 offset:13856
	s_waitcnt lgkmcnt(1)
	v_mfma_f32_32x32x16_bf16 v[32:47], v[194:197], v[208:211], v[32:47]
	v_mfma_f32_32x32x16_bf16 v[48:63], v[198:201], v[208:211], v[48:63]
	s_waitcnt lgkmcnt(0)
	v_mfma_f32_32x32x16_bf16 v[0:15], v[194:197], v[212:215], v[0:15]
	v_mfma_f32_32x32x16_bf16 v[16:31], v[198:201], v[212:215], v[16:31]
	s_setprio 0
	global_load_dwordx4 v[194:197], v[132:133], off offset:384
	global_load_dwordx4 v[198:201], v[134:135], off offset:384
	s_waitcnt vmcnt(9)
	ds_write_b128 v148, v[176:179] offset:18432
	s_waitcnt vmcnt(8)
	ds_write_b128 v148, v[180:183] offset:55296
	ds_read_b128 v[176:179], v150 offset:64
	ds_read_b128 v[180:183], v150 offset:4672
	ds_read_b128 v[208:211], v149 offset:64
	ds_read_b128 v[212:215], v149 offset:4672
	s_setprio 1
	s_waitcnt lgkmcnt(1)
	v_mfma_f32_32x32x16_bf16 v[96:111], v[176:179], v[208:211], v[96:111]
	v_mfma_f32_32x32x16_bf16 v[112:127], v[180:183], v[208:211], v[112:127]
	s_waitcnt lgkmcnt(0)
	v_mfma_f32_32x32x16_bf16 v[64:79], v[176:179], v[212:215], v[64:79]
	v_mfma_f32_32x32x16_bf16 v[80:95], v[180:183], v[212:215], v[80:95]
	ds_read_b128 v[208:211], v149 offset:9280
	ds_read_b128 v[212:215], v149 offset:13888
	s_waitcnt lgkmcnt(1)
	v_mfma_f32_32x32x16_bf16 v[32:47], v[176:179], v[208:211], v[32:47]
	v_mfma_f32_32x32x16_bf16 v[48:63], v[180:183], v[208:211], v[48:63]
	s_waitcnt lgkmcnt(0)
	v_mfma_f32_32x32x16_bf16 v[0:15], v[176:179], v[212:215], v[0:15]
	v_mfma_f32_32x32x16_bf16 v[16:31], v[180:183], v[212:215], v[16:31]
	s_setprio 0
	global_load_dwordx4 v[176:179], v[144:145], off offset:384
	global_load_dwordx4 v[180:183], v[146:147], off offset:384
	s_waitcnt vmcnt(9)
	ds_write_b128 v148, v[168:171] offset:27648
	s_waitcnt vmcnt(8)
	ds_write_b128 v148, v[172:175] offset:64512
	ds_read_b128 v[168:171], v150 offset:96
	ds_read_b128 v[172:175], v150 offset:4704
	ds_read_b128 v[208:211], v149 offset:96
	ds_read_b128 v[212:215], v149 offset:4704
	s_setprio 1
	s_waitcnt lgkmcnt(1)
	v_mfma_f32_32x32x16_bf16 v[96:111], v[168:171], v[208:211], v[96:111]
	v_mfma_f32_32x32x16_bf16 v[112:127], v[172:175], v[208:211], v[112:127]
	s_waitcnt lgkmcnt(0)
	v_mfma_f32_32x32x16_bf16 v[64:79], v[168:171], v[212:215], v[64:79]
	v_mfma_f32_32x32x16_bf16 v[80:95], v[172:175], v[212:215], v[80:95]
	ds_read_b128 v[208:211], v149 offset:9312
	ds_read_b128 v[212:215], v149 offset:13920
	s_waitcnt lgkmcnt(1)
	v_mfma_f32_32x32x16_bf16 v[32:47], v[168:171], v[208:211], v[32:47]
	v_mfma_f32_32x32x16_bf16 v[48:63], v[172:175], v[208:211], v[48:63]
	s_waitcnt lgkmcnt(0)
	v_mfma_f32_32x32x16_bf16 v[0:15], v[168:171], v[212:215], v[0:15]
	v_mfma_f32_32x32x16_bf16 v[16:31], v[172:175], v[212:215], v[16:31]
	s_setprio 0
	s_barrier
	global_load_dwordx4 v[168:171], v[136:137], off offset:512
	global_load_dwordx4 v[172:175], v[138:139], off offset:512
	s_waitcnt vmcnt(9)
	ds_write_b128 v192, v[160:163]
	s_waitcnt vmcnt(8)
	ds_write_b128 v159, v[164:167]
	ds_read_b128 v[160:163], v152 offset:36864
	ds_read_b128 v[164:167], v152 offset:41472
	ds_read_b128 v[208:211], v151
	ds_read_b128 v[212:215], v151 offset:4608
	s_setprio 1
	s_waitcnt lgkmcnt(1)
	v_mfma_f32_32x32x16_bf16 v[96:111], v[160:163], v[208:211], v[96:111]
	v_mfma_f32_32x32x16_bf16 v[112:127], v[164:167], v[208:211], v[112:127]
	s_waitcnt lgkmcnt(0)
	v_mfma_f32_32x32x16_bf16 v[64:79], v[160:163], v[212:215], v[64:79]
	v_mfma_f32_32x32x16_bf16 v[80:95], v[164:167], v[212:215], v[80:95]
	ds_read_b128 v[208:211], v151 offset:9216
	ds_read_b128 v[212:215], v151 offset:13824
	s_waitcnt vmcnt(7)
	ds_write_b128 v158, v[184:187]
	s_waitcnt vmcnt(6)
	ds_write_b128 v157, v[188:191]
	ds_read_b128 v[184:187], v152 offset:36896
	ds_read_b128 v[188:191], v152 offset:41504
	s_waitcnt lgkmcnt(5)
	v_mfma_f32_32x32x16_bf16 v[32:47], v[160:163], v[208:211], v[32:47]
	v_mfma_f32_32x32x16_bf16 v[48:63], v[164:167], v[208:211], v[48:63]
	ds_read_b128 v[208:211], v151 offset:32
	s_waitcnt lgkmcnt(5)
	v_mfma_f32_32x32x16_bf16 v[0:15], v[160:163], v[212:215], v[0:15]
	v_mfma_f32_32x32x16_bf16 v[16:31], v[164:167], v[212:215], v[16:31]
	ds_read_b128 v[212:215], v151 offset:4640
	global_load_dwordx4 v[160:163], v[140:141], off offset:512
	global_load_dwordx4 v[164:167], v[142:143], off offset:512
	s_waitcnt lgkmcnt(1)
	v_mfma_f32_32x32x16_bf16 v[96:111], v[184:187], v[208:211], v[96:111]
	v_mfma_f32_32x32x16_bf16 v[112:127], v[188:191], v[208:211], v[112:127]
	s_waitcnt lgkmcnt(0)
	v_mfma_f32_32x32x16_bf16 v[64:79], v[184:187], v[212:215], v[64:79]
	v_mfma_f32_32x32x16_bf16 v[80:95], v[188:191], v[212:215], v[80:95]
	ds_read_b128 v[208:211], v151 offset:9248
	ds_read_b128 v[212:215], v151 offset:13856
	s_waitcnt vmcnt(7)
	ds_write_b128 v154, v[194:197]
	s_waitcnt vmcnt(6)
	ds_write_b128 v153, v[198:201]
	ds_read_b128 v[194:197], v152 offset:36928
	ds_read_b128 v[198:201], v152 offset:41536
	s_waitcnt lgkmcnt(5)
	v_mfma_f32_32x32x16_bf16 v[32:47], v[184:187], v[208:211], v[32:47]
	v_mfma_f32_32x32x16_bf16 v[48:63], v[188:191], v[208:211], v[48:63]
	ds_read_b128 v[208:211], v151 offset:64
	s_waitcnt lgkmcnt(5)
	v_mfma_f32_32x32x16_bf16 v[0:15], v[184:187], v[212:215], v[0:15]
	v_mfma_f32_32x32x16_bf16 v[16:31], v[188:191], v[212:215], v[16:31]
	ds_read_b128 v[212:215], v151 offset:4672
	global_load_dwordx4 v[184:187], v[132:133], off offset:512
	global_load_dwordx4 v[188:191], v[134:135], off offset:512
	s_waitcnt lgkmcnt(1)
	v_mfma_f32_32x32x16_bf16 v[96:111], v[194:197], v[208:211], v[96:111]
	v_mfma_f32_32x32x16_bf16 v[112:127], v[198:201], v[208:211], v[112:127]
	s_waitcnt lgkmcnt(0)
	v_mfma_f32_32x32x16_bf16 v[64:79], v[194:197], v[212:215], v[64:79]
	v_mfma_f32_32x32x16_bf16 v[80:95], v[198:201], v[212:215], v[80:95]
	ds_read_b128 v[208:211], v151 offset:9280
	ds_read_b128 v[212:215], v151 offset:13888
	s_waitcnt vmcnt(7)
	ds_write_b128 v156, v[176:179]
	s_waitcnt vmcnt(6)
	ds_write_b128 v155, v[180:183]
	ds_read_b128 v[176:179], v152 offset:36960
	ds_read_b128 v[180:183], v152 offset:41568
	s_waitcnt lgkmcnt(5)
	v_mfma_f32_32x32x16_bf16 v[32:47], v[194:197], v[208:211], v[32:47]
	v_mfma_f32_32x32x16_bf16 v[48:63], v[198:201], v[208:211], v[48:63]
	ds_read_b128 v[208:211], v151 offset:96
	s_waitcnt lgkmcnt(5)
	v_mfma_f32_32x32x16_bf16 v[0:15], v[194:197], v[212:215], v[0:15]
	v_mfma_f32_32x32x16_bf16 v[16:31], v[198:201], v[212:215], v[16:31]
	ds_read_b128 v[212:215], v151 offset:4704
	global_load_dwordx4 v[194:197], v[144:145], off offset:512
	global_load_dwordx4 v[198:201], v[146:147], off offset:512
	s_waitcnt lgkmcnt(1)
	v_mfma_f32_32x32x16_bf16 v[96:111], v[176:179], v[208:211], v[96:111]
	v_mfma_f32_32x32x16_bf16 v[112:127], v[180:183], v[208:211], v[112:127]
	s_waitcnt lgkmcnt(0)
	v_mfma_f32_32x32x16_bf16 v[64:79], v[176:179], v[212:215], v[64:79]
	v_mfma_f32_32x32x16_bf16 v[80:95], v[180:183], v[212:215], v[80:95]
	ds_read_b128 v[208:211], v151 offset:9312
	ds_read_b128 v[212:215], v151 offset:13920
	s_waitcnt lgkmcnt(1)
	v_mfma_f32_32x32x16_bf16 v[32:47], v[176:179], v[208:211], v[32:47]
	v_mfma_f32_32x32x16_bf16 v[48:63], v[180:183], v[208:211], v[48:63]
	s_waitcnt lgkmcnt(0)
	v_mfma_f32_32x32x16_bf16 v[0:15], v[176:179], v[212:215], v[0:15]
	v_mfma_f32_32x32x16_bf16 v[16:31], v[180:183], v[212:215], v[16:31]
	s_setprio 0
	s_barrier
	global_load_dwordx4 v[176:179], v[136:137], off offset:640
	global_load_dwordx4 v[180:183], v[138:139], off offset:640
	s_waitcnt vmcnt(9)
	ds_write_b128 v148, v[168:171]
	s_waitcnt vmcnt(8)
	ds_write_b128 v148, v[172:175] offset:36864
	ds_read_b128 v[168:171], v150
	ds_read_b128 v[172:175], v150 offset:4608
	ds_read_b128 v[208:211], v149
	ds_read_b128 v[212:215], v149 offset:4608
	s_setprio 1
	s_waitcnt lgkmcnt(1)
	v_mfma_f32_32x32x16_bf16 v[96:111], v[168:171], v[208:211], v[96:111]
	v_mfma_f32_32x32x16_bf16 v[112:127], v[172:175], v[208:211], v[112:127]
	s_waitcnt lgkmcnt(0)
	v_mfma_f32_32x32x16_bf16 v[64:79], v[168:171], v[212:215], v[64:79]
	v_mfma_f32_32x32x16_bf16 v[80:95], v[172:175], v[212:215], v[80:95]
	ds_read_b128 v[208:211], v149 offset:9216
	ds_read_b128 v[212:215], v149 offset:13824
	s_waitcnt vmcnt(7)
	ds_write_b128 v148, v[160:163] offset:9216
	s_waitcnt vmcnt(6)
	ds_write_b128 v148, v[164:167] offset:46080
	ds_read_b128 v[160:163], v150 offset:32
	ds_read_b128 v[164:167], v150 offset:4640
	s_waitcnt lgkmcnt(5)
	v_mfma_f32_32x32x16_bf16 v[32:47], v[168:171], v[208:211], v[32:47]
	v_mfma_f32_32x32x16_bf16 v[48:63], v[172:175], v[208:211], v[48:63]
	ds_read_b128 v[208:211], v149 offset:32
	s_waitcnt lgkmcnt(5)
	v_mfma_f32_32x32x16_bf16 v[0:15], v[168:171], v[212:215], v[0:15]
	v_mfma_f32_32x32x16_bf16 v[16:31], v[172:175], v[212:215], v[16:31]
	ds_read_b128 v[212:215], v149 offset:4640
	global_load_dwordx4 v[168:171], v[140:141], off offset:640
	global_load_dwordx4 v[172:175], v[142:143], off offset:640
	s_waitcnt lgkmcnt(1)
	v_mfma_f32_32x32x16_bf16 v[96:111], v[160:163], v[208:211], v[96:111]
	v_mfma_f32_32x32x16_bf16 v[112:127], v[164:167], v[208:211], v[112:127]
	s_waitcnt lgkmcnt(0)
	v_mfma_f32_32x32x16_bf16 v[64:79], v[160:163], v[212:215], v[64:79]
	v_mfma_f32_32x32x16_bf16 v[80:95], v[164:167], v[212:215], v[80:95]
	ds_read_b128 v[208:211], v149 offset:9248
	ds_read_b128 v[212:215], v149 offset:13856
	s_waitcnt vmcnt(7)
	ds_write_b128 v148, v[184:187] offset:18432
	s_waitcnt vmcnt(6)
	ds_write_b128 v148, v[188:191] offset:55296
	ds_read_b128 v[184:187], v150 offset:64
	ds_read_b128 v[188:191], v150 offset:4672
	s_waitcnt lgkmcnt(5)
	v_mfma_f32_32x32x16_bf16 v[32:47], v[160:163], v[208:211], v[32:47]
	v_mfma_f32_32x32x16_bf16 v[48:63], v[164:167], v[208:211], v[48:63]
	ds_read_b128 v[208:211], v149 offset:64
	s_waitcnt lgkmcnt(5)
	v_mfma_f32_32x32x16_bf16 v[0:15], v[160:163], v[212:215], v[0:15]
	v_mfma_f32_32x32x16_bf16 v[16:31], v[164:167], v[212:215], v[16:31]
	ds_read_b128 v[212:215], v149 offset:4672
	global_load_dwordx4 v[160:163], v[132:133], off offset:640
	global_load_dwordx4 v[164:167], v[134:135], off offset:640
	s_waitcnt lgkmcnt(1)
	v_mfma_f32_32x32x16_bf16 v[96:111], v[184:187], v[208:211], v[96:111]
	v_mfma_f32_32x32x16_bf16 v[112:127], v[188:191], v[208:211], v[112:127]
	s_waitcnt lgkmcnt(0)
	v_mfma_f32_32x32x16_bf16 v[64:79], v[184:187], v[212:215], v[64:79]
	v_mfma_f32_32x32x16_bf16 v[80:95], v[188:191], v[212:215], v[80:95]
	ds_read_b128 v[208:211], v149 offset:9280
	ds_read_b128 v[212:215], v149 offset:13888
	s_waitcnt vmcnt(7)
	ds_write_b128 v148, v[194:197] offset:27648
	s_waitcnt vmcnt(6)
	ds_write_b128 v148, v[198:201] offset:64512
	ds_read_b128 v[194:197], v150 offset:96
	ds_read_b128 v[198:201], v150 offset:4704
	s_waitcnt lgkmcnt(5)
	v_mfma_f32_32x32x16_bf16 v[32:47], v[184:187], v[208:211], v[32:47]
	v_mfma_f32_32x32x16_bf16 v[48:63], v[188:191], v[208:211], v[48:63]
	ds_read_b128 v[208:211], v149 offset:96
	s_waitcnt lgkmcnt(5)
	v_mfma_f32_32x32x16_bf16 v[0:15], v[184:187], v[212:215], v[0:15]
	v_mfma_f32_32x32x16_bf16 v[16:31], v[188:191], v[212:215], v[16:31]
	ds_read_b128 v[212:215], v149 offset:4704
	global_load_dwordx4 v[184:187], v[144:145], off offset:640
	global_load_dwordx4 v[188:191], v[146:147], off offset:640
	s_waitcnt lgkmcnt(1)
	v_mfma_f32_32x32x16_bf16 v[96:111], v[194:197], v[208:211], v[96:111]
	v_mfma_f32_32x32x16_bf16 v[112:127], v[198:201], v[208:211], v[112:127]
	s_waitcnt lgkmcnt(0)
	v_mfma_f32_32x32x16_bf16 v[64:79], v[194:197], v[212:215], v[64:79]
	v_mfma_f32_32x32x16_bf16 v[80:95], v[198:201], v[212:215], v[80:95]
	ds_read_b128 v[208:211], v149 offset:9312
	ds_read_b128 v[212:215], v149 offset:13920
	s_waitcnt lgkmcnt(1)
	v_mfma_f32_32x32x16_bf16 v[32:47], v[194:197], v[208:211], v[32:47]
	v_mfma_f32_32x32x16_bf16 v[48:63], v[198:201], v[208:211], v[48:63]
	s_waitcnt lgkmcnt(0)
	v_mfma_f32_32x32x16_bf16 v[0:15], v[194:197], v[212:215], v[0:15]
	v_mfma_f32_32x32x16_bf16 v[16:31], v[198:201], v[212:215], v[16:31]
	s_setprio 0
	s_barrier
	global_load_dwordx4 v[194:197], v[136:137], off offset:768
	global_load_dwordx4 v[198:201], v[138:139], off offset:768
	s_waitcnt vmcnt(9)
	ds_write_b128 v192, v[176:179]
	s_waitcnt vmcnt(8)
	ds_write_b128 v159, v[180:183]
	ds_read_b128 v[176:179], v152 offset:36864
	ds_read_b128 v[180:183], v152 offset:41472
	ds_read_b128 v[208:211], v151
	ds_read_b128 v[212:215], v151 offset:4608
	s_setprio 1
	s_waitcnt lgkmcnt(1)
	v_mfma_f32_32x32x16_bf16 v[96:111], v[176:179], v[208:211], v[96:111]
	v_mfma_f32_32x32x16_bf16 v[112:127], v[180:183], v[208:211], v[112:127]
	s_waitcnt lgkmcnt(0)
	v_mfma_f32_32x32x16_bf16 v[64:79], v[176:179], v[212:215], v[64:79]
	v_mfma_f32_32x32x16_bf16 v[80:95], v[180:183], v[212:215], v[80:95]
	ds_read_b128 v[208:211], v151 offset:9216
	ds_read_b128 v[212:215], v151 offset:13824
	s_waitcnt vmcnt(7)
	ds_write_b128 v158, v[168:171]
	s_waitcnt vmcnt(6)
	ds_write_b128 v157, v[172:175]
	ds_read_b128 v[168:171], v152 offset:36896
	ds_read_b128 v[172:175], v152 offset:41504
	s_waitcnt lgkmcnt(5)
	v_mfma_f32_32x32x16_bf16 v[32:47], v[176:179], v[208:211], v[32:47]
	v_mfma_f32_32x32x16_bf16 v[48:63], v[180:183], v[208:211], v[48:63]
	ds_read_b128 v[208:211], v151 offset:32
	s_waitcnt lgkmcnt(5)
	v_mfma_f32_32x32x16_bf16 v[0:15], v[176:179], v[212:215], v[0:15]
	v_mfma_f32_32x32x16_bf16 v[16:31], v[180:183], v[212:215], v[16:31]
	ds_read_b128 v[212:215], v151 offset:4640
	global_load_dwordx4 v[176:179], v[140:141], off offset:768
	global_load_dwordx4 v[180:183], v[142:143], off offset:768
	s_waitcnt lgkmcnt(1)
	v_mfma_f32_32x32x16_bf16 v[96:111], v[168:171], v[208:211], v[96:111]
	v_mfma_f32_32x32x16_bf16 v[112:127], v[172:175], v[208:211], v[112:127]
	s_waitcnt lgkmcnt(0)
	v_mfma_f32_32x32x16_bf16 v[64:79], v[168:171], v[212:215], v[64:79]
	v_mfma_f32_32x32x16_bf16 v[80:95], v[172:175], v[212:215], v[80:95]
	ds_read_b128 v[208:211], v151 offset:9248
	ds_read_b128 v[212:215], v151 offset:13856
	s_waitcnt vmcnt(7)
	ds_write_b128 v154, v[160:163]
	s_waitcnt vmcnt(6)
	ds_write_b128 v153, v[164:167]
	ds_read_b128 v[160:163], v152 offset:36928
	ds_read_b128 v[164:167], v152 offset:41536
	s_waitcnt lgkmcnt(5)
	v_mfma_f32_32x32x16_bf16 v[32:47], v[168:171], v[208:211], v[32:47]
	v_mfma_f32_32x32x16_bf16 v[48:63], v[172:175], v[208:211], v[48:63]
	ds_read_b128 v[208:211], v151 offset:64
	s_waitcnt lgkmcnt(5)
	v_mfma_f32_32x32x16_bf16 v[0:15], v[168:171], v[212:215], v[0:15]
	v_mfma_f32_32x32x16_bf16 v[16:31], v[172:175], v[212:215], v[16:31]
	ds_read_b128 v[212:215], v151 offset:4672
	global_load_dwordx4 v[168:171], v[132:133], off offset:768
	global_load_dwordx4 v[172:175], v[134:135], off offset:768
	s_waitcnt lgkmcnt(1)
	v_mfma_f32_32x32x16_bf16 v[96:111], v[160:163], v[208:211], v[96:111]
	v_mfma_f32_32x32x16_bf16 v[112:127], v[164:167], v[208:211], v[112:127]
	s_waitcnt lgkmcnt(0)
	v_mfma_f32_32x32x16_bf16 v[64:79], v[160:163], v[212:215], v[64:79]
	v_mfma_f32_32x32x16_bf16 v[80:95], v[164:167], v[212:215], v[80:95]
	ds_read_b128 v[208:211], v151 offset:9280
	ds_read_b128 v[212:215], v151 offset:13888
	s_waitcnt vmcnt(7)
	ds_write_b128 v156, v[184:187]
	s_waitcnt vmcnt(6)
	ds_write_b128 v155, v[188:191]
	ds_read_b128 v[184:187], v152 offset:36960
	ds_read_b128 v[188:191], v152 offset:41568
	s_waitcnt lgkmcnt(5)
	v_mfma_f32_32x32x16_bf16 v[32:47], v[160:163], v[208:211], v[32:47]
	v_mfma_f32_32x32x16_bf16 v[48:63], v[164:167], v[208:211], v[48:63]
	ds_read_b128 v[208:211], v151 offset:96
	s_waitcnt lgkmcnt(5)
	v_mfma_f32_32x32x16_bf16 v[0:15], v[160:163], v[212:215], v[0:15]
	v_mfma_f32_32x32x16_bf16 v[16:31], v[164:167], v[212:215], v[16:31]
	ds_read_b128 v[212:215], v151 offset:4704
	global_load_dwordx4 v[160:163], v[144:145], off offset:768
	global_load_dwordx4 v[164:167], v[146:147], off offset:768
	s_waitcnt lgkmcnt(1)
	v_mfma_f32_32x32x16_bf16 v[96:111], v[184:187], v[208:211], v[96:111]
	v_mfma_f32_32x32x16_bf16 v[112:127], v[188:191], v[208:211], v[112:127]
	s_waitcnt lgkmcnt(0)
	v_mfma_f32_32x32x16_bf16 v[64:79], v[184:187], v[212:215], v[64:79]
	v_mfma_f32_32x32x16_bf16 v[80:95], v[188:191], v[212:215], v[80:95]
	ds_read_b128 v[208:211], v151 offset:9312
	ds_read_b128 v[212:215], v151 offset:13920
	s_waitcnt lgkmcnt(1)
	v_mfma_f32_32x32x16_bf16 v[32:47], v[184:187], v[208:211], v[32:47]
	v_mfma_f32_32x32x16_bf16 v[48:63], v[188:191], v[208:211], v[48:63]
	s_waitcnt lgkmcnt(0)
	v_mfma_f32_32x32x16_bf16 v[0:15], v[184:187], v[212:215], v[0:15]
	v_mfma_f32_32x32x16_bf16 v[16:31], v[188:191], v[212:215], v[16:31]
	s_setprio 0
	s_barrier
	global_load_dwordx4 v[184:187], v[136:137], off offset:896
	global_load_dwordx4 v[188:191], v[138:139], off offset:896
	s_waitcnt vmcnt(9)
	ds_write_b128 v148, v[194:197]
	s_waitcnt vmcnt(8)
	ds_write_b128 v148, v[198:201] offset:36864
	ds_read_b128 v[194:197], v150
	ds_read_b128 v[198:201], v150 offset:4608
	ds_read_b128 v[208:211], v149
	ds_read_b128 v[212:215], v149 offset:4608
	s_setprio 1
	s_waitcnt lgkmcnt(1)
	v_mfma_f32_32x32x16_bf16 v[96:111], v[194:197], v[208:211], v[96:111]
	v_mfma_f32_32x32x16_bf16 v[112:127], v[198:201], v[208:211], v[112:127]
	s_waitcnt lgkmcnt(0)
	v_mfma_f32_32x32x16_bf16 v[64:79], v[194:197], v[212:215], v[64:79]
	v_mfma_f32_32x32x16_bf16 v[80:95], v[198:201], v[212:215], v[80:95]
	ds_read_b128 v[208:211], v149 offset:9216
	ds_read_b128 v[212:215], v149 offset:13824
	s_waitcnt vmcnt(7)
	ds_write_b128 v148, v[176:179] offset:9216
	s_waitcnt vmcnt(6)
	ds_write_b128 v148, v[180:183] offset:46080
	ds_read_b128 v[176:179], v150 offset:32
	ds_read_b128 v[180:183], v150 offset:4640
	s_waitcnt lgkmcnt(5)
	v_mfma_f32_32x32x16_bf16 v[32:47], v[194:197], v[208:211], v[32:47]
	v_mfma_f32_32x32x16_bf16 v[48:63], v[198:201], v[208:211], v[48:63]
	ds_read_b128 v[208:211], v149 offset:32
	s_waitcnt lgkmcnt(5)
	v_mfma_f32_32x32x16_bf16 v[0:15], v[194:197], v[212:215], v[0:15]
	v_mfma_f32_32x32x16_bf16 v[16:31], v[198:201], v[212:215], v[16:31]
	ds_read_b128 v[212:215], v149 offset:4640
	global_load_dwordx4 v[194:197], v[140:141], off offset:896
	global_load_dwordx4 v[198:201], v[142:143], off offset:896
	s_waitcnt lgkmcnt(1)
	v_mfma_f32_32x32x16_bf16 v[96:111], v[176:179], v[208:211], v[96:111]
	v_mfma_f32_32x32x16_bf16 v[112:127], v[180:183], v[208:211], v[112:127]
	s_waitcnt lgkmcnt(0)
	v_mfma_f32_32x32x16_bf16 v[64:79], v[176:179], v[212:215], v[64:79]
	v_mfma_f32_32x32x16_bf16 v[80:95], v[180:183], v[212:215], v[80:95]
	ds_read_b128 v[208:211], v149 offset:9248
	ds_read_b128 v[212:215], v149 offset:13856
	s_waitcnt vmcnt(7)
	ds_write_b128 v148, v[168:171] offset:18432
	s_waitcnt vmcnt(6)
	ds_write_b128 v148, v[172:175] offset:55296
	ds_read_b128 v[168:171], v150 offset:64
	ds_read_b128 v[172:175], v150 offset:4672
	s_waitcnt lgkmcnt(5)
	v_mfma_f32_32x32x16_bf16 v[32:47], v[176:179], v[208:211], v[32:47]
	v_mfma_f32_32x32x16_bf16 v[48:63], v[180:183], v[208:211], v[48:63]
	ds_read_b128 v[208:211], v149 offset:64
	s_waitcnt lgkmcnt(5)
	v_mfma_f32_32x32x16_bf16 v[0:15], v[176:179], v[212:215], v[0:15]
	v_mfma_f32_32x32x16_bf16 v[16:31], v[180:183], v[212:215], v[16:31]
	ds_read_b128 v[212:215], v149 offset:4672
	global_load_dwordx4 v[176:179], v[132:133], off offset:896
	global_load_dwordx4 v[180:183], v[134:135], off offset:896
	s_waitcnt lgkmcnt(1)
	v_mfma_f32_32x32x16_bf16 v[96:111], v[168:171], v[208:211], v[96:111]
	v_mfma_f32_32x32x16_bf16 v[112:127], v[172:175], v[208:211], v[112:127]
	s_waitcnt lgkmcnt(0)
	v_mfma_f32_32x32x16_bf16 v[64:79], v[168:171], v[212:215], v[64:79]
	v_mfma_f32_32x32x16_bf16 v[80:95], v[172:175], v[212:215], v[80:95]
	ds_read_b128 v[208:211], v149 offset:9280
	ds_read_b128 v[212:215], v149 offset:13888
	s_waitcnt vmcnt(7)
	ds_write_b128 v148, v[160:163] offset:27648
	s_waitcnt vmcnt(6)
	ds_write_b128 v148, v[164:167] offset:64512
	ds_read_b128 v[160:163], v150 offset:96
	ds_read_b128 v[164:167], v150 offset:4704
	s_waitcnt lgkmcnt(5)
	v_mfma_f32_32x32x16_bf16 v[32:47], v[168:171], v[208:211], v[32:47]
	v_mfma_f32_32x32x16_bf16 v[48:63], v[172:175], v[208:211], v[48:63]
	ds_read_b128 v[208:211], v149 offset:96
	s_waitcnt lgkmcnt(5)
	v_mfma_f32_32x32x16_bf16 v[0:15], v[168:171], v[212:215], v[0:15]
	v_mfma_f32_32x32x16_bf16 v[16:31], v[172:175], v[212:215], v[16:31]
	ds_read_b128 v[212:215], v149 offset:4704
	global_load_dwordx4 v[168:171], v[144:145], off offset:896
	global_load_dwordx4 v[172:175], v[146:147], off offset:896
	s_waitcnt lgkmcnt(1)
	v_mfma_f32_32x32x16_bf16 v[96:111], v[160:163], v[208:211], v[96:111]
	v_mfma_f32_32x32x16_bf16 v[112:127], v[164:167], v[208:211], v[112:127]
	s_waitcnt lgkmcnt(0)
	v_mfma_f32_32x32x16_bf16 v[64:79], v[160:163], v[212:215], v[64:79]
	v_mfma_f32_32x32x16_bf16 v[80:95], v[164:167], v[212:215], v[80:95]
	ds_read_b128 v[208:211], v149 offset:9312
	ds_read_b128 v[212:215], v149 offset:13920
	s_waitcnt lgkmcnt(1)
	v_mfma_f32_32x32x16_bf16 v[32:47], v[160:163], v[208:211], v[32:47]
	v_mfma_f32_32x32x16_bf16 v[48:63], v[164:167], v[208:211], v[48:63]
	s_waitcnt lgkmcnt(0)
	v_mfma_f32_32x32x16_bf16 v[0:15], v[160:163], v[212:215], v[0:15]
	v_mfma_f32_32x32x16_bf16 v[16:31], v[164:167], v[212:215], v[16:31]
	s_setprio 0
	s_barrier
	global_load_dwordx4 v[160:163], v[136:137], off offset:1024
	global_load_dwordx4 v[164:167], v[138:139], off offset:1024
	s_waitcnt vmcnt(9)
	ds_write_b128 v192, v[184:187]
	s_waitcnt vmcnt(8)
	ds_write_b128 v159, v[188:191]
	ds_read_b128 v[184:187], v152 offset:36864
	ds_read_b128 v[188:191], v152 offset:41472
	ds_read_b128 v[208:211], v151
	ds_read_b128 v[212:215], v151 offset:4608
	s_setprio 1
	s_waitcnt lgkmcnt(1)
	v_mfma_f32_32x32x16_bf16 v[96:111], v[184:187], v[208:211], v[96:111]
	v_mfma_f32_32x32x16_bf16 v[112:127], v[188:191], v[208:211], v[112:127]
	s_waitcnt lgkmcnt(0)
	v_mfma_f32_32x32x16_bf16 v[64:79], v[184:187], v[212:215], v[64:79]
	v_mfma_f32_32x32x16_bf16 v[80:95], v[188:191], v[212:215], v[80:95]
	ds_read_b128 v[208:211], v151 offset:9216
	ds_read_b128 v[212:215], v151 offset:13824
	s_waitcnt vmcnt(7)
	ds_write_b128 v158, v[194:197]
	s_waitcnt vmcnt(6)
	ds_write_b128 v157, v[198:201]
	ds_read_b128 v[194:197], v152 offset:36896
	ds_read_b128 v[198:201], v152 offset:41504
	s_waitcnt lgkmcnt(5)
	v_mfma_f32_32x32x16_bf16 v[32:47], v[184:187], v[208:211], v[32:47]
	v_mfma_f32_32x32x16_bf16 v[48:63], v[188:191], v[208:211], v[48:63]
	ds_read_b128 v[208:211], v151 offset:32
	s_waitcnt lgkmcnt(5)
	v_mfma_f32_32x32x16_bf16 v[0:15], v[184:187], v[212:215], v[0:15]
	v_mfma_f32_32x32x16_bf16 v[16:31], v[188:191], v[212:215], v[16:31]
	ds_read_b128 v[212:215], v151 offset:4640
	global_load_dwordx4 v[184:187], v[140:141], off offset:1024
	global_load_dwordx4 v[188:191], v[142:143], off offset:1024
	s_waitcnt lgkmcnt(1)
	v_mfma_f32_32x32x16_bf16 v[96:111], v[194:197], v[208:211], v[96:111]
	v_mfma_f32_32x32x16_bf16 v[112:127], v[198:201], v[208:211], v[112:127]
	s_waitcnt lgkmcnt(0)
	v_mfma_f32_32x32x16_bf16 v[64:79], v[194:197], v[212:215], v[64:79]
	v_mfma_f32_32x32x16_bf16 v[80:95], v[198:201], v[212:215], v[80:95]
	ds_read_b128 v[208:211], v151 offset:9248
	ds_read_b128 v[212:215], v151 offset:13856
	s_waitcnt vmcnt(7)
	ds_write_b128 v154, v[176:179]
	s_waitcnt vmcnt(6)
	ds_write_b128 v153, v[180:183]
	ds_read_b128 v[176:179], v152 offset:36928
	ds_read_b128 v[180:183], v152 offset:41536
	s_waitcnt lgkmcnt(5)
	v_mfma_f32_32x32x16_bf16 v[32:47], v[194:197], v[208:211], v[32:47]
	v_mfma_f32_32x32x16_bf16 v[48:63], v[198:201], v[208:211], v[48:63]
	ds_read_b128 v[208:211], v151 offset:64
	s_waitcnt lgkmcnt(5)
	v_mfma_f32_32x32x16_bf16 v[0:15], v[194:197], v[212:215], v[0:15]
	v_mfma_f32_32x32x16_bf16 v[16:31], v[198:201], v[212:215], v[16:31]
	ds_read_b128 v[212:215], v151 offset:4672
	global_load_dwordx4 v[194:197], v[132:133], off offset:1024
	global_load_dwordx4 v[198:201], v[134:135], off offset:1024
	s_waitcnt lgkmcnt(1)
	v_mfma_f32_32x32x16_bf16 v[96:111], v[176:179], v[208:211], v[96:111]
	v_mfma_f32_32x32x16_bf16 v[112:127], v[180:183], v[208:211], v[112:127]
	s_waitcnt lgkmcnt(0)
	v_mfma_f32_32x32x16_bf16 v[64:79], v[176:179], v[212:215], v[64:79]
	v_mfma_f32_32x32x16_bf16 v[80:95], v[180:183], v[212:215], v[80:95]
	ds_read_b128 v[208:211], v151 offset:9280
	ds_read_b128 v[212:215], v151 offset:13888
	s_waitcnt vmcnt(7)
	ds_write_b128 v156, v[168:171]
	s_waitcnt vmcnt(6)
	ds_write_b128 v155, v[172:175]
	ds_read_b128 v[168:171], v152 offset:36960
	ds_read_b128 v[172:175], v152 offset:41568
	s_waitcnt lgkmcnt(5)
	v_mfma_f32_32x32x16_bf16 v[32:47], v[176:179], v[208:211], v[32:47]
	v_mfma_f32_32x32x16_bf16 v[48:63], v[180:183], v[208:211], v[48:63]
	ds_read_b128 v[208:211], v151 offset:96
	s_waitcnt lgkmcnt(5)
	v_mfma_f32_32x32x16_bf16 v[0:15], v[176:179], v[212:215], v[0:15]
	v_mfma_f32_32x32x16_bf16 v[16:31], v[180:183], v[212:215], v[16:31]
	ds_read_b128 v[212:215], v151 offset:4704
	global_load_dwordx4 v[176:179], v[144:145], off offset:1024
	global_load_dwordx4 v[180:183], v[146:147], off offset:1024
	s_waitcnt lgkmcnt(1)
	v_mfma_f32_32x32x16_bf16 v[96:111], v[168:171], v[208:211], v[96:111]
	v_mfma_f32_32x32x16_bf16 v[112:127], v[172:175], v[208:211], v[112:127]
	s_waitcnt lgkmcnt(0)
	v_mfma_f32_32x32x16_bf16 v[64:79], v[168:171], v[212:215], v[64:79]
	v_mfma_f32_32x32x16_bf16 v[80:95], v[172:175], v[212:215], v[80:95]
	ds_read_b128 v[208:211], v151 offset:9312
	ds_read_b128 v[212:215], v151 offset:13920
	s_waitcnt lgkmcnt(1)
	v_mfma_f32_32x32x16_bf16 v[32:47], v[168:171], v[208:211], v[32:47]
	v_mfma_f32_32x32x16_bf16 v[48:63], v[172:175], v[208:211], v[48:63]
	s_waitcnt lgkmcnt(0)
	v_mfma_f32_32x32x16_bf16 v[0:15], v[168:171], v[212:215], v[0:15]
	v_mfma_f32_32x32x16_bf16 v[16:31], v[172:175], v[212:215], v[16:31]
	s_setprio 0
	s_barrier
	global_load_dwordx4 v[168:171], v[136:137], off offset:1152
	global_load_dwordx4 v[172:175], v[138:139], off offset:1152
	s_waitcnt vmcnt(9)
	ds_write_b128 v148, v[160:163]
	s_waitcnt vmcnt(8)
	ds_write_b128 v148, v[164:167] offset:36864
	ds_read_b128 v[160:163], v150
	ds_read_b128 v[164:167], v150 offset:4608
	ds_read_b128 v[208:211], v149
	ds_read_b128 v[212:215], v149 offset:4608
	s_setprio 1
	s_waitcnt lgkmcnt(1)
	v_mfma_f32_32x32x16_bf16 v[96:111], v[160:163], v[208:211], v[96:111]
	v_mfma_f32_32x32x16_bf16 v[112:127], v[164:167], v[208:211], v[112:127]
	s_waitcnt lgkmcnt(0)
	v_mfma_f32_32x32x16_bf16 v[64:79], v[160:163], v[212:215], v[64:79]
	v_mfma_f32_32x32x16_bf16 v[80:95], v[164:167], v[212:215], v[80:95]
	ds_read_b128 v[208:211], v149 offset:9216
	ds_read_b128 v[212:215], v149 offset:13824
	s_waitcnt vmcnt(7)
	ds_write_b128 v148, v[184:187] offset:9216
	s_waitcnt vmcnt(6)
	ds_write_b128 v148, v[188:191] offset:46080
	ds_read_b128 v[184:187], v150 offset:32
	ds_read_b128 v[188:191], v150 offset:4640
	s_waitcnt lgkmcnt(5)
	v_mfma_f32_32x32x16_bf16 v[32:47], v[160:163], v[208:211], v[32:47]
	v_mfma_f32_32x32x16_bf16 v[48:63], v[164:167], v[208:211], v[48:63]
	ds_read_b128 v[208:211], v149 offset:32
	s_waitcnt lgkmcnt(5)
	v_mfma_f32_32x32x16_bf16 v[0:15], v[160:163], v[212:215], v[0:15]
	v_mfma_f32_32x32x16_bf16 v[16:31], v[164:167], v[212:215], v[16:31]
	ds_read_b128 v[212:215], v149 offset:4640
	global_load_dwordx4 v[160:163], v[140:141], off offset:1152
	global_load_dwordx4 v[164:167], v[142:143], off offset:1152
	s_waitcnt lgkmcnt(1)
	v_mfma_f32_32x32x16_bf16 v[96:111], v[184:187], v[208:211], v[96:111]
	v_mfma_f32_32x32x16_bf16 v[112:127], v[188:191], v[208:211], v[112:127]
	s_waitcnt lgkmcnt(0)
	v_mfma_f32_32x32x16_bf16 v[64:79], v[184:187], v[212:215], v[64:79]
	v_mfma_f32_32x32x16_bf16 v[80:95], v[188:191], v[212:215], v[80:95]
	ds_read_b128 v[208:211], v149 offset:9248
	ds_read_b128 v[212:215], v149 offset:13856
	s_waitcnt vmcnt(7)
	ds_write_b128 v148, v[194:197] offset:18432
	s_waitcnt vmcnt(6)
	ds_write_b128 v148, v[198:201] offset:55296
	ds_read_b128 v[194:197], v150 offset:64
	ds_read_b128 v[198:201], v150 offset:4672
	s_waitcnt lgkmcnt(5)
	v_mfma_f32_32x32x16_bf16 v[32:47], v[184:187], v[208:211], v[32:47]
	v_mfma_f32_32x32x16_bf16 v[48:63], v[188:191], v[208:211], v[48:63]
	ds_read_b128 v[208:211], v149 offset:64
	s_waitcnt lgkmcnt(5)
	v_mfma_f32_32x32x16_bf16 v[0:15], v[184:187], v[212:215], v[0:15]
	v_mfma_f32_32x32x16_bf16 v[16:31], v[188:191], v[212:215], v[16:31]
	ds_read_b128 v[212:215], v149 offset:4672
	global_load_dwordx4 v[184:187], v[132:133], off offset:1152
	global_load_dwordx4 v[188:191], v[134:135], off offset:1152
	s_waitcnt lgkmcnt(1)
	v_mfma_f32_32x32x16_bf16 v[96:111], v[194:197], v[208:211], v[96:111]
	v_mfma_f32_32x32x16_bf16 v[112:127], v[198:201], v[208:211], v[112:127]
	s_waitcnt lgkmcnt(0)
	v_mfma_f32_32x32x16_bf16 v[64:79], v[194:197], v[212:215], v[64:79]
	v_mfma_f32_32x32x16_bf16 v[80:95], v[198:201], v[212:215], v[80:95]
	ds_read_b128 v[208:211], v149 offset:9280
	ds_read_b128 v[212:215], v149 offset:13888
	s_waitcnt vmcnt(7)
	ds_write_b128 v148, v[176:179] offset:27648
	s_waitcnt vmcnt(6)
	ds_write_b128 v148, v[180:183] offset:64512
	ds_read_b128 v[176:179], v150 offset:96
	ds_read_b128 v[180:183], v150 offset:4704
	s_waitcnt lgkmcnt(5)
	v_mfma_f32_32x32x16_bf16 v[32:47], v[194:197], v[208:211], v[32:47]
	v_mfma_f32_32x32x16_bf16 v[48:63], v[198:201], v[208:211], v[48:63]
	ds_read_b128 v[208:211], v149 offset:96
	s_waitcnt lgkmcnt(5)
	v_mfma_f32_32x32x16_bf16 v[0:15], v[194:197], v[212:215], v[0:15]
	v_mfma_f32_32x32x16_bf16 v[16:31], v[198:201], v[212:215], v[16:31]
	ds_read_b128 v[212:215], v149 offset:4704
	global_load_dwordx4 v[194:197], v[144:145], off offset:1152
	global_load_dwordx4 v[198:201], v[146:147], off offset:1152
	s_waitcnt lgkmcnt(1)
	v_mfma_f32_32x32x16_bf16 v[96:111], v[176:179], v[208:211], v[96:111]
	v_mfma_f32_32x32x16_bf16 v[112:127], v[180:183], v[208:211], v[112:127]
	s_waitcnt lgkmcnt(0)
	v_mfma_f32_32x32x16_bf16 v[64:79], v[176:179], v[212:215], v[64:79]
	v_mfma_f32_32x32x16_bf16 v[80:95], v[180:183], v[212:215], v[80:95]
	ds_read_b128 v[208:211], v149 offset:9312
	ds_read_b128 v[212:215], v149 offset:13920
	s_waitcnt lgkmcnt(1)
	v_mfma_f32_32x32x16_bf16 v[32:47], v[176:179], v[208:211], v[32:47]
	v_mfma_f32_32x32x16_bf16 v[48:63], v[180:183], v[208:211], v[48:63]
	s_waitcnt lgkmcnt(0)
	v_mfma_f32_32x32x16_bf16 v[0:15], v[176:179], v[212:215], v[0:15]
	v_mfma_f32_32x32x16_bf16 v[16:31], v[180:183], v[212:215], v[16:31]
	s_setprio 0
	s_barrier
	global_load_dwordx4 v[176:179], v[136:137], off offset:1280
	global_load_dwordx4 v[180:183], v[138:139], off offset:1280
	s_waitcnt vmcnt(9)
	ds_write_b128 v192, v[168:171]
	s_waitcnt vmcnt(8)
	ds_write_b128 v159, v[172:175]
	ds_read_b128 v[168:171], v152 offset:36864
	ds_read_b128 v[172:175], v152 offset:41472
	ds_read_b128 v[208:211], v151
	ds_read_b128 v[212:215], v151 offset:4608
	s_setprio 1
	s_waitcnt lgkmcnt(1)
	v_mfma_f32_32x32x16_bf16 v[96:111], v[168:171], v[208:211], v[96:111]
	v_mfma_f32_32x32x16_bf16 v[112:127], v[172:175], v[208:211], v[112:127]
	s_waitcnt lgkmcnt(0)
	v_mfma_f32_32x32x16_bf16 v[64:79], v[168:171], v[212:215], v[64:79]
	v_mfma_f32_32x32x16_bf16 v[80:95], v[172:175], v[212:215], v[80:95]
	ds_read_b128 v[208:211], v151 offset:9216
	ds_read_b128 v[212:215], v151 offset:13824
	s_waitcnt vmcnt(7)
	ds_write_b128 v158, v[160:163]
	s_waitcnt vmcnt(6)
	ds_write_b128 v157, v[164:167]
	ds_read_b128 v[160:163], v152 offset:36896
	ds_read_b128 v[164:167], v152 offset:41504
	s_waitcnt lgkmcnt(5)
	v_mfma_f32_32x32x16_bf16 v[32:47], v[168:171], v[208:211], v[32:47]
	v_mfma_f32_32x32x16_bf16 v[48:63], v[172:175], v[208:211], v[48:63]
	ds_read_b128 v[208:211], v151 offset:32
	s_waitcnt lgkmcnt(5)
	v_mfma_f32_32x32x16_bf16 v[0:15], v[168:171], v[212:215], v[0:15]
	v_mfma_f32_32x32x16_bf16 v[16:31], v[172:175], v[212:215], v[16:31]
	ds_read_b128 v[212:215], v151 offset:4640
	global_load_dwordx4 v[168:171], v[140:141], off offset:1280
	global_load_dwordx4 v[172:175], v[142:143], off offset:1280
	s_waitcnt lgkmcnt(1)
	v_mfma_f32_32x32x16_bf16 v[96:111], v[160:163], v[208:211], v[96:111]
	v_mfma_f32_32x32x16_bf16 v[112:127], v[164:167], v[208:211], v[112:127]
	s_waitcnt lgkmcnt(0)
	v_mfma_f32_32x32x16_bf16 v[64:79], v[160:163], v[212:215], v[64:79]
	v_mfma_f32_32x32x16_bf16 v[80:95], v[164:167], v[212:215], v[80:95]
	ds_read_b128 v[208:211], v151 offset:9248
	ds_read_b128 v[212:215], v151 offset:13856
	s_waitcnt vmcnt(7)
	ds_write_b128 v154, v[184:187]
	s_waitcnt vmcnt(6)
	ds_write_b128 v153, v[188:191]
	ds_read_b128 v[184:187], v152 offset:36928
	ds_read_b128 v[188:191], v152 offset:41536
	s_waitcnt lgkmcnt(5)
	v_mfma_f32_32x32x16_bf16 v[32:47], v[160:163], v[208:211], v[32:47]
	v_mfma_f32_32x32x16_bf16 v[48:63], v[164:167], v[208:211], v[48:63]
	ds_read_b128 v[208:211], v151 offset:64
	s_waitcnt lgkmcnt(5)
	v_mfma_f32_32x32x16_bf16 v[0:15], v[160:163], v[212:215], v[0:15]
	v_mfma_f32_32x32x16_bf16 v[16:31], v[164:167], v[212:215], v[16:31]
	ds_read_b128 v[212:215], v151 offset:4672
	global_load_dwordx4 v[160:163], v[132:133], off offset:1280
	global_load_dwordx4 v[164:167], v[134:135], off offset:1280
	s_waitcnt lgkmcnt(1)
	v_mfma_f32_32x32x16_bf16 v[96:111], v[184:187], v[208:211], v[96:111]
	v_mfma_f32_32x32x16_bf16 v[112:127], v[188:191], v[208:211], v[112:127]
	s_waitcnt lgkmcnt(0)
	v_mfma_f32_32x32x16_bf16 v[64:79], v[184:187], v[212:215], v[64:79]
	v_mfma_f32_32x32x16_bf16 v[80:95], v[188:191], v[212:215], v[80:95]
	ds_read_b128 v[208:211], v151 offset:9280
	ds_read_b128 v[212:215], v151 offset:13888
	s_waitcnt vmcnt(7)
	ds_write_b128 v156, v[194:197]
	s_waitcnt vmcnt(6)
	ds_write_b128 v155, v[198:201]
	ds_read_b128 v[194:197], v152 offset:36960
	ds_read_b128 v[198:201], v152 offset:41568
	s_waitcnt lgkmcnt(5)
	v_mfma_f32_32x32x16_bf16 v[32:47], v[184:187], v[208:211], v[32:47]
	v_mfma_f32_32x32x16_bf16 v[48:63], v[188:191], v[208:211], v[48:63]
	ds_read_b128 v[208:211], v151 offset:96
	s_waitcnt lgkmcnt(5)
	v_mfma_f32_32x32x16_bf16 v[0:15], v[184:187], v[212:215], v[0:15]
	v_mfma_f32_32x32x16_bf16 v[16:31], v[188:191], v[212:215], v[16:31]
	ds_read_b128 v[212:215], v151 offset:4704
	global_load_dwordx4 v[184:187], v[144:145], off offset:1280
	global_load_dwordx4 v[188:191], v[146:147], off offset:1280
	s_waitcnt lgkmcnt(1)
	v_mfma_f32_32x32x16_bf16 v[96:111], v[194:197], v[208:211], v[96:111]
	v_mfma_f32_32x32x16_bf16 v[112:127], v[198:201], v[208:211], v[112:127]
	s_waitcnt lgkmcnt(0)
	v_mfma_f32_32x32x16_bf16 v[64:79], v[194:197], v[212:215], v[64:79]
	v_mfma_f32_32x32x16_bf16 v[80:95], v[198:201], v[212:215], v[80:95]
	ds_read_b128 v[208:211], v151 offset:9312
	ds_read_b128 v[212:215], v151 offset:13920
	s_waitcnt lgkmcnt(1)
	v_mfma_f32_32x32x16_bf16 v[32:47], v[194:197], v[208:211], v[32:47]
	v_mfma_f32_32x32x16_bf16 v[48:63], v[198:201], v[208:211], v[48:63]
	s_waitcnt lgkmcnt(0)
	v_mfma_f32_32x32x16_bf16 v[0:15], v[194:197], v[212:215], v[0:15]
	v_mfma_f32_32x32x16_bf16 v[16:31], v[198:201], v[212:215], v[16:31]
	s_setprio 0
	s_barrier
	global_load_dwordx4 v[194:197], v[136:137], off offset:1408
	global_load_dwordx4 v[198:201], v[138:139], off offset:1408
	s_waitcnt vmcnt(9)
	ds_write_b128 v148, v[176:179]
	s_waitcnt vmcnt(8)
	ds_write_b128 v148, v[180:183] offset:36864
	ds_read_b128 v[176:179], v150
	ds_read_b128 v[180:183], v150 offset:4608
	ds_read_b128 v[208:211], v149
	ds_read_b128 v[212:215], v149 offset:4608
	s_setprio 1
	s_waitcnt lgkmcnt(1)
	v_mfma_f32_32x32x16_bf16 v[96:111], v[176:179], v[208:211], v[96:111]
	v_mfma_f32_32x32x16_bf16 v[112:127], v[180:183], v[208:211], v[112:127]
	s_waitcnt lgkmcnt(0)
	v_mfma_f32_32x32x16_bf16 v[64:79], v[176:179], v[212:215], v[64:79]
	v_mfma_f32_32x32x16_bf16 v[80:95], v[180:183], v[212:215], v[80:95]
	ds_read_b128 v[208:211], v149 offset:9216
	ds_read_b128 v[212:215], v149 offset:13824
	s_waitcnt vmcnt(7)
	ds_write_b128 v148, v[168:171] offset:9216
	s_waitcnt vmcnt(6)
	ds_write_b128 v148, v[172:175] offset:46080
	ds_read_b128 v[168:171], v150 offset:32
	ds_read_b128 v[172:175], v150 offset:4640
	s_waitcnt lgkmcnt(5)
	v_mfma_f32_32x32x16_bf16 v[32:47], v[176:179], v[208:211], v[32:47]
	v_mfma_f32_32x32x16_bf16 v[48:63], v[180:183], v[208:211], v[48:63]
	ds_read_b128 v[208:211], v149 offset:32
	s_waitcnt lgkmcnt(5)
	v_mfma_f32_32x32x16_bf16 v[0:15], v[176:179], v[212:215], v[0:15]
	v_mfma_f32_32x32x16_bf16 v[16:31], v[180:183], v[212:215], v[16:31]
	ds_read_b128 v[212:215], v149 offset:4640
	global_load_dwordx4 v[176:179], v[140:141], off offset:1408
	global_load_dwordx4 v[180:183], v[142:143], off offset:1408
	s_waitcnt lgkmcnt(1)
	v_mfma_f32_32x32x16_bf16 v[96:111], v[168:171], v[208:211], v[96:111]
	v_mfma_f32_32x32x16_bf16 v[112:127], v[172:175], v[208:211], v[112:127]
	s_waitcnt lgkmcnt(0)
	v_mfma_f32_32x32x16_bf16 v[64:79], v[168:171], v[212:215], v[64:79]
	v_mfma_f32_32x32x16_bf16 v[80:95], v[172:175], v[212:215], v[80:95]
	ds_read_b128 v[208:211], v149 offset:9248
	ds_read_b128 v[212:215], v149 offset:13856
	s_waitcnt vmcnt(7)
	ds_write_b128 v148, v[160:163] offset:18432
	s_waitcnt vmcnt(6)
	ds_write_b128 v148, v[164:167] offset:55296
	ds_read_b128 v[160:163], v150 offset:64
	ds_read_b128 v[164:167], v150 offset:4672
	s_waitcnt lgkmcnt(5)
	v_mfma_f32_32x32x16_bf16 v[32:47], v[168:171], v[208:211], v[32:47]
	v_mfma_f32_32x32x16_bf16 v[48:63], v[172:175], v[208:211], v[48:63]
	ds_read_b128 v[208:211], v149 offset:64
	s_waitcnt lgkmcnt(5)
	v_mfma_f32_32x32x16_bf16 v[0:15], v[168:171], v[212:215], v[0:15]
	v_mfma_f32_32x32x16_bf16 v[16:31], v[172:175], v[212:215], v[16:31]
	ds_read_b128 v[212:215], v149 offset:4672
	global_load_dwordx4 v[168:171], v[132:133], off offset:1408
	global_load_dwordx4 v[172:175], v[134:135], off offset:1408
	s_waitcnt lgkmcnt(1)
	v_mfma_f32_32x32x16_bf16 v[96:111], v[160:163], v[208:211], v[96:111]
	v_mfma_f32_32x32x16_bf16 v[112:127], v[164:167], v[208:211], v[112:127]
	s_waitcnt lgkmcnt(0)
	v_mfma_f32_32x32x16_bf16 v[64:79], v[160:163], v[212:215], v[64:79]
	v_mfma_f32_32x32x16_bf16 v[80:95], v[164:167], v[212:215], v[80:95]
	ds_read_b128 v[208:211], v149 offset:9280
	ds_read_b128 v[212:215], v149 offset:13888
	s_waitcnt vmcnt(7)
	ds_write_b128 v148, v[184:187] offset:27648
	s_waitcnt vmcnt(6)
	ds_write_b128 v148, v[188:191] offset:64512
	ds_read_b128 v[184:187], v150 offset:96
	ds_read_b128 v[188:191], v150 offset:4704
	s_waitcnt lgkmcnt(5)
	v_mfma_f32_32x32x16_bf16 v[32:47], v[160:163], v[208:211], v[32:47]
	v_mfma_f32_32x32x16_bf16 v[48:63], v[164:167], v[208:211], v[48:63]
	ds_read_b128 v[208:211], v149 offset:96
	s_waitcnt lgkmcnt(5)
	v_mfma_f32_32x32x16_bf16 v[0:15], v[160:163], v[212:215], v[0:15]
	v_mfma_f32_32x32x16_bf16 v[16:31], v[164:167], v[212:215], v[16:31]
	ds_read_b128 v[212:215], v149 offset:4704
	global_load_dwordx4 v[160:163], v[144:145], off offset:1408
	global_load_dwordx4 v[164:167], v[146:147], off offset:1408
	s_waitcnt lgkmcnt(1)
	v_mfma_f32_32x32x16_bf16 v[96:111], v[184:187], v[208:211], v[96:111]
	v_mfma_f32_32x32x16_bf16 v[112:127], v[188:191], v[208:211], v[112:127]
	s_waitcnt lgkmcnt(0)
	v_mfma_f32_32x32x16_bf16 v[64:79], v[184:187], v[212:215], v[64:79]
	v_mfma_f32_32x32x16_bf16 v[80:95], v[188:191], v[212:215], v[80:95]
	ds_read_b128 v[208:211], v149 offset:9312
	ds_read_b128 v[212:215], v149 offset:13920
	s_waitcnt lgkmcnt(1)
	v_mfma_f32_32x32x16_bf16 v[32:47], v[184:187], v[208:211], v[32:47]
	v_mfma_f32_32x32x16_bf16 v[48:63], v[188:191], v[208:211], v[48:63]
	s_waitcnt lgkmcnt(0)
	v_mfma_f32_32x32x16_bf16 v[0:15], v[184:187], v[212:215], v[0:15]
	v_mfma_f32_32x32x16_bf16 v[16:31], v[188:191], v[212:215], v[16:31]
	s_setprio 0
	s_barrier
	global_load_dwordx4 v[184:187], v[136:137], off offset:1536
	global_load_dwordx4 v[188:191], v[138:139], off offset:1536
	s_waitcnt vmcnt(9)
	ds_write_b128 v192, v[194:197]
	s_waitcnt vmcnt(8)
	ds_write_b128 v159, v[198:201]
	ds_read_b128 v[194:197], v152 offset:36864
	ds_read_b128 v[198:201], v152 offset:41472
	ds_read_b128 v[208:211], v151
	ds_read_b128 v[212:215], v151 offset:4608
	s_setprio 1
	s_waitcnt lgkmcnt(1)
	v_mfma_f32_32x32x16_bf16 v[96:111], v[194:197], v[208:211], v[96:111]
	v_mfma_f32_32x32x16_bf16 v[112:127], v[198:201], v[208:211], v[112:127]
	s_waitcnt lgkmcnt(0)
	v_mfma_f32_32x32x16_bf16 v[64:79], v[194:197], v[212:215], v[64:79]
	v_mfma_f32_32x32x16_bf16 v[80:95], v[198:201], v[212:215], v[80:95]
	ds_read_b128 v[208:211], v151 offset:9216
	ds_read_b128 v[212:215], v151 offset:13824
	s_waitcnt vmcnt(7)
	ds_write_b128 v158, v[176:179]
	s_waitcnt vmcnt(6)
	ds_write_b128 v157, v[180:183]
	ds_read_b128 v[176:179], v152 offset:36896
	ds_read_b128 v[180:183], v152 offset:41504
	s_waitcnt lgkmcnt(5)
	v_mfma_f32_32x32x16_bf16 v[32:47], v[194:197], v[208:211], v[32:47]
	v_mfma_f32_32x32x16_bf16 v[48:63], v[198:201], v[208:211], v[48:63]
	ds_read_b128 v[208:211], v151 offset:32
	s_waitcnt lgkmcnt(5)
	v_mfma_f32_32x32x16_bf16 v[0:15], v[194:197], v[212:215], v[0:15]
	v_mfma_f32_32x32x16_bf16 v[16:31], v[198:201], v[212:215], v[16:31]
	ds_read_b128 v[212:215], v151 offset:4640
	global_load_dwordx4 v[194:197], v[140:141], off offset:1536
	global_load_dwordx4 v[198:201], v[142:143], off offset:1536
	s_waitcnt lgkmcnt(1)
	v_mfma_f32_32x32x16_bf16 v[96:111], v[176:179], v[208:211], v[96:111]
	v_mfma_f32_32x32x16_bf16 v[112:127], v[180:183], v[208:211], v[112:127]
	s_waitcnt lgkmcnt(0)
	v_mfma_f32_32x32x16_bf16 v[64:79], v[176:179], v[212:215], v[64:79]
	v_mfma_f32_32x32x16_bf16 v[80:95], v[180:183], v[212:215], v[80:95]
	ds_read_b128 v[208:211], v151 offset:9248
	ds_read_b128 v[212:215], v151 offset:13856
	s_waitcnt vmcnt(7)
	ds_write_b128 v154, v[168:171]
	s_waitcnt vmcnt(6)
	ds_write_b128 v153, v[172:175]
	ds_read_b128 v[168:171], v152 offset:36928
	ds_read_b128 v[172:175], v152 offset:41536
	s_waitcnt lgkmcnt(5)
	v_mfma_f32_32x32x16_bf16 v[32:47], v[176:179], v[208:211], v[32:47]
	v_mfma_f32_32x32x16_bf16 v[48:63], v[180:183], v[208:211], v[48:63]
	ds_read_b128 v[208:211], v151 offset:64
	s_waitcnt lgkmcnt(5)
	v_mfma_f32_32x32x16_bf16 v[0:15], v[176:179], v[212:215], v[0:15]
	v_mfma_f32_32x32x16_bf16 v[16:31], v[180:183], v[212:215], v[16:31]
	ds_read_b128 v[212:215], v151 offset:4672
	global_load_dwordx4 v[176:179], v[132:133], off offset:1536
	global_load_dwordx4 v[180:183], v[134:135], off offset:1536
	s_waitcnt lgkmcnt(1)
	v_mfma_f32_32x32x16_bf16 v[96:111], v[168:171], v[208:211], v[96:111]
	v_mfma_f32_32x32x16_bf16 v[112:127], v[172:175], v[208:211], v[112:127]
	s_waitcnt lgkmcnt(0)
	v_mfma_f32_32x32x16_bf16 v[64:79], v[168:171], v[212:215], v[64:79]
	v_mfma_f32_32x32x16_bf16 v[80:95], v[172:175], v[212:215], v[80:95]
	ds_read_b128 v[208:211], v151 offset:9280
	ds_read_b128 v[212:215], v151 offset:13888
	s_waitcnt vmcnt(7)
	ds_write_b128 v156, v[160:163]
	s_waitcnt vmcnt(6)
	ds_write_b128 v155, v[164:167]
	ds_read_b128 v[160:163], v152 offset:36960
	ds_read_b128 v[164:167], v152 offset:41568
	s_waitcnt lgkmcnt(5)
	v_mfma_f32_32x32x16_bf16 v[32:47], v[168:171], v[208:211], v[32:47]
	v_mfma_f32_32x32x16_bf16 v[48:63], v[172:175], v[208:211], v[48:63]
	ds_read_b128 v[208:211], v151 offset:96
	s_waitcnt lgkmcnt(5)
	v_mfma_f32_32x32x16_bf16 v[0:15], v[168:171], v[212:215], v[0:15]
	v_mfma_f32_32x32x16_bf16 v[16:31], v[172:175], v[212:215], v[16:31]
	ds_read_b128 v[212:215], v151 offset:4704
	global_load_dwordx4 v[168:171], v[144:145], off offset:1536
	global_load_dwordx4 v[172:175], v[146:147], off offset:1536
	s_waitcnt lgkmcnt(1)
	v_mfma_f32_32x32x16_bf16 v[96:111], v[160:163], v[208:211], v[96:111]
	v_mfma_f32_32x32x16_bf16 v[112:127], v[164:167], v[208:211], v[112:127]
	s_waitcnt lgkmcnt(0)
	v_mfma_f32_32x32x16_bf16 v[64:79], v[160:163], v[212:215], v[64:79]
	v_mfma_f32_32x32x16_bf16 v[80:95], v[164:167], v[212:215], v[80:95]
	ds_read_b128 v[208:211], v151 offset:9312
	ds_read_b128 v[212:215], v151 offset:13920
	s_waitcnt lgkmcnt(1)
	v_mfma_f32_32x32x16_bf16 v[32:47], v[160:163], v[208:211], v[32:47]
	v_mfma_f32_32x32x16_bf16 v[48:63], v[164:167], v[208:211], v[48:63]
	s_waitcnt lgkmcnt(0)
	v_mfma_f32_32x32x16_bf16 v[0:15], v[160:163], v[212:215], v[0:15]
	v_mfma_f32_32x32x16_bf16 v[16:31], v[164:167], v[212:215], v[16:31]
	s_setprio 0
	s_barrier
	global_load_dwordx4 v[160:163], v[136:137], off offset:1664
	global_load_dwordx4 v[164:167], v[138:139], off offset:1664
	s_waitcnt vmcnt(9)
	ds_write_b128 v148, v[184:187]
	s_waitcnt vmcnt(8)
	ds_write_b128 v148, v[188:191] offset:36864
	ds_read_b128 v[184:187], v150
	ds_read_b128 v[188:191], v150 offset:4608
	ds_read_b128 v[208:211], v149
	ds_read_b128 v[212:215], v149 offset:4608
	s_setprio 1
	s_waitcnt lgkmcnt(1)
	v_mfma_f32_32x32x16_bf16 v[96:111], v[184:187], v[208:211], v[96:111]
	v_mfma_f32_32x32x16_bf16 v[112:127], v[188:191], v[208:211], v[112:127]
	s_waitcnt lgkmcnt(0)
	v_mfma_f32_32x32x16_bf16 v[64:79], v[184:187], v[212:215], v[64:79]
	v_mfma_f32_32x32x16_bf16 v[80:95], v[188:191], v[212:215], v[80:95]
	ds_read_b128 v[208:211], v149 offset:9216
	ds_read_b128 v[212:215], v149 offset:13824
	s_waitcnt vmcnt(7)
	ds_write_b128 v148, v[194:197] offset:9216
	s_waitcnt vmcnt(6)
	ds_write_b128 v148, v[198:201] offset:46080
	ds_read_b128 v[194:197], v150 offset:32
	ds_read_b128 v[198:201], v150 offset:4640
	s_waitcnt lgkmcnt(5)
	v_mfma_f32_32x32x16_bf16 v[32:47], v[184:187], v[208:211], v[32:47]
	v_mfma_f32_32x32x16_bf16 v[48:63], v[188:191], v[208:211], v[48:63]
	ds_read_b128 v[208:211], v149 offset:32
	s_waitcnt lgkmcnt(5)
	v_mfma_f32_32x32x16_bf16 v[0:15], v[184:187], v[212:215], v[0:15]
	v_mfma_f32_32x32x16_bf16 v[16:31], v[188:191], v[212:215], v[16:31]
	ds_read_b128 v[212:215], v149 offset:4640
	global_load_dwordx4 v[184:187], v[140:141], off offset:1664
	global_load_dwordx4 v[188:191], v[142:143], off offset:1664
	s_waitcnt lgkmcnt(1)
	v_mfma_f32_32x32x16_bf16 v[96:111], v[194:197], v[208:211], v[96:111]
	v_mfma_f32_32x32x16_bf16 v[112:127], v[198:201], v[208:211], v[112:127]
	s_waitcnt lgkmcnt(0)
	v_mfma_f32_32x32x16_bf16 v[64:79], v[194:197], v[212:215], v[64:79]
	v_mfma_f32_32x32x16_bf16 v[80:95], v[198:201], v[212:215], v[80:95]
	ds_read_b128 v[208:211], v149 offset:9248
	ds_read_b128 v[212:215], v149 offset:13856
	s_waitcnt vmcnt(7)
	ds_write_b128 v148, v[176:179] offset:18432
	s_waitcnt vmcnt(6)
	ds_write_b128 v148, v[180:183] offset:55296
	ds_read_b128 v[176:179], v150 offset:64
	ds_read_b128 v[180:183], v150 offset:4672
	s_waitcnt lgkmcnt(5)
	v_mfma_f32_32x32x16_bf16 v[32:47], v[194:197], v[208:211], v[32:47]
	v_mfma_f32_32x32x16_bf16 v[48:63], v[198:201], v[208:211], v[48:63]
	ds_read_b128 v[208:211], v149 offset:64
	s_waitcnt lgkmcnt(5)
	v_mfma_f32_32x32x16_bf16 v[0:15], v[194:197], v[212:215], v[0:15]
	v_mfma_f32_32x32x16_bf16 v[16:31], v[198:201], v[212:215], v[16:31]
	ds_read_b128 v[212:215], v149 offset:4672
	global_load_dwordx4 v[194:197], v[132:133], off offset:1664
	global_load_dwordx4 v[198:201], v[134:135], off offset:1664
	s_waitcnt lgkmcnt(1)
	v_mfma_f32_32x32x16_bf16 v[96:111], v[176:179], v[208:211], v[96:111]
	v_mfma_f32_32x32x16_bf16 v[112:127], v[180:183], v[208:211], v[112:127]
	s_waitcnt lgkmcnt(0)
	v_mfma_f32_32x32x16_bf16 v[64:79], v[176:179], v[212:215], v[64:79]
	v_mfma_f32_32x32x16_bf16 v[80:95], v[180:183], v[212:215], v[80:95]
	ds_read_b128 v[208:211], v149 offset:9280
	ds_read_b128 v[212:215], v149 offset:13888
	s_waitcnt vmcnt(7)
	ds_write_b128 v148, v[168:171] offset:27648
	s_waitcnt vmcnt(6)
	ds_write_b128 v148, v[172:175] offset:64512
	ds_read_b128 v[168:171], v150 offset:96
	ds_read_b128 v[172:175], v150 offset:4704
	s_waitcnt lgkmcnt(5)
	v_mfma_f32_32x32x16_bf16 v[32:47], v[176:179], v[208:211], v[32:47]
	v_mfma_f32_32x32x16_bf16 v[48:63], v[180:183], v[208:211], v[48:63]
	ds_read_b128 v[208:211], v149 offset:96
	s_waitcnt lgkmcnt(5)
	v_mfma_f32_32x32x16_bf16 v[0:15], v[176:179], v[212:215], v[0:15]
	v_mfma_f32_32x32x16_bf16 v[16:31], v[180:183], v[212:215], v[16:31]
	ds_read_b128 v[212:215], v149 offset:4704
	global_load_dwordx4 v[176:179], v[144:145], off offset:1664
	global_load_dwordx4 v[180:183], v[146:147], off offset:1664
	s_waitcnt lgkmcnt(1)
	v_mfma_f32_32x32x16_bf16 v[96:111], v[168:171], v[208:211], v[96:111]
	v_mfma_f32_32x32x16_bf16 v[112:127], v[172:175], v[208:211], v[112:127]
	s_waitcnt lgkmcnt(0)
	v_mfma_f32_32x32x16_bf16 v[64:79], v[168:171], v[212:215], v[64:79]
	v_mfma_f32_32x32x16_bf16 v[80:95], v[172:175], v[212:215], v[80:95]
	ds_read_b128 v[208:211], v149 offset:9312
	ds_read_b128 v[212:215], v149 offset:13920
	s_waitcnt lgkmcnt(1)
	v_mfma_f32_32x32x16_bf16 v[32:47], v[168:171], v[208:211], v[32:47]
	v_mfma_f32_32x32x16_bf16 v[48:63], v[172:175], v[208:211], v[48:63]
	s_waitcnt lgkmcnt(0)
	v_mfma_f32_32x32x16_bf16 v[0:15], v[168:171], v[212:215], v[0:15]
	v_mfma_f32_32x32x16_bf16 v[16:31], v[172:175], v[212:215], v[16:31]
	s_setprio 0
	s_barrier
	global_load_dwordx4 v[168:171], v[136:137], off offset:1792
	global_load_dwordx4 v[172:175], v[138:139], off offset:1792
	s_waitcnt vmcnt(9)
	ds_write_b128 v192, v[160:163]
	s_waitcnt vmcnt(8)
	ds_write_b128 v159, v[164:167]
	ds_read_b128 v[160:163], v152 offset:36864
	ds_read_b128 v[164:167], v152 offset:41472
	ds_read_b128 v[208:211], v151
	ds_read_b128 v[212:215], v151 offset:4608
	s_setprio 1
	s_waitcnt lgkmcnt(1)
	v_mfma_f32_32x32x16_bf16 v[96:111], v[160:163], v[208:211], v[96:111]
	v_mfma_f32_32x32x16_bf16 v[112:127], v[164:167], v[208:211], v[112:127]
	s_waitcnt lgkmcnt(0)
	v_mfma_f32_32x32x16_bf16 v[64:79], v[160:163], v[212:215], v[64:79]
	v_mfma_f32_32x32x16_bf16 v[80:95], v[164:167], v[212:215], v[80:95]
	ds_read_b128 v[208:211], v151 offset:9216
	ds_read_b128 v[212:215], v151 offset:13824
	s_waitcnt vmcnt(7)
	ds_write_b128 v158, v[184:187]
	s_waitcnt vmcnt(6)
	ds_write_b128 v157, v[188:191]
	ds_read_b128 v[184:187], v152 offset:36896
	ds_read_b128 v[188:191], v152 offset:41504
	s_waitcnt lgkmcnt(5)
	v_mfma_f32_32x32x16_bf16 v[32:47], v[160:163], v[208:211], v[32:47]
	v_mfma_f32_32x32x16_bf16 v[48:63], v[164:167], v[208:211], v[48:63]
	ds_read_b128 v[208:211], v151 offset:32
	s_waitcnt lgkmcnt(5)
	v_mfma_f32_32x32x16_bf16 v[0:15], v[160:163], v[212:215], v[0:15]
	v_mfma_f32_32x32x16_bf16 v[16:31], v[164:167], v[212:215], v[16:31]
	ds_read_b128 v[212:215], v151 offset:4640
	global_load_dwordx4 v[160:163], v[140:141], off offset:1792
	global_load_dwordx4 v[164:167], v[142:143], off offset:1792
	s_waitcnt lgkmcnt(1)
	v_mfma_f32_32x32x16_bf16 v[96:111], v[184:187], v[208:211], v[96:111]
	v_mfma_f32_32x32x16_bf16 v[112:127], v[188:191], v[208:211], v[112:127]
	s_waitcnt lgkmcnt(0)
	v_mfma_f32_32x32x16_bf16 v[64:79], v[184:187], v[212:215], v[64:79]
	v_mfma_f32_32x32x16_bf16 v[80:95], v[188:191], v[212:215], v[80:95]
	ds_read_b128 v[208:211], v151 offset:9248
	ds_read_b128 v[212:215], v151 offset:13856
	s_waitcnt vmcnt(7)
	ds_write_b128 v154, v[194:197]
	s_waitcnt vmcnt(6)
	ds_write_b128 v153, v[198:201]
	ds_read_b128 v[194:197], v152 offset:36928
	ds_read_b128 v[198:201], v152 offset:41536
	s_waitcnt lgkmcnt(5)
	v_mfma_f32_32x32x16_bf16 v[32:47], v[184:187], v[208:211], v[32:47]
	v_mfma_f32_32x32x16_bf16 v[48:63], v[188:191], v[208:211], v[48:63]
	ds_read_b128 v[208:211], v151 offset:64
	s_waitcnt lgkmcnt(5)
	v_mfma_f32_32x32x16_bf16 v[0:15], v[184:187], v[212:215], v[0:15]
	v_mfma_f32_32x32x16_bf16 v[16:31], v[188:191], v[212:215], v[16:31]
	ds_read_b128 v[212:215], v151 offset:4672
	global_load_dwordx4 v[184:187], v[132:133], off offset:1792
	global_load_dwordx4 v[188:191], v[134:135], off offset:1792
	s_waitcnt lgkmcnt(1)
	v_mfma_f32_32x32x16_bf16 v[96:111], v[194:197], v[208:211], v[96:111]
	v_mfma_f32_32x32x16_bf16 v[112:127], v[198:201], v[208:211], v[112:127]
	s_waitcnt lgkmcnt(0)
	v_mfma_f32_32x32x16_bf16 v[64:79], v[194:197], v[212:215], v[64:79]
	v_mfma_f32_32x32x16_bf16 v[80:95], v[198:201], v[212:215], v[80:95]
	ds_read_b128 v[208:211], v151 offset:9280
	ds_read_b128 v[212:215], v151 offset:13888
	s_waitcnt vmcnt(7)
	ds_write_b128 v156, v[176:179]
	s_waitcnt vmcnt(6)
	ds_write_b128 v155, v[180:183]
	ds_read_b128 v[176:179], v152 offset:36960
	ds_read_b128 v[180:183], v152 offset:41568
	s_waitcnt lgkmcnt(5)
	v_mfma_f32_32x32x16_bf16 v[32:47], v[194:197], v[208:211], v[32:47]
	v_mfma_f32_32x32x16_bf16 v[48:63], v[198:201], v[208:211], v[48:63]
	ds_read_b128 v[208:211], v151 offset:96
	s_waitcnt lgkmcnt(5)
	v_mfma_f32_32x32x16_bf16 v[0:15], v[194:197], v[212:215], v[0:15]
	v_mfma_f32_32x32x16_bf16 v[16:31], v[198:201], v[212:215], v[16:31]
	ds_read_b128 v[212:215], v151 offset:4704
	global_load_dwordx4 v[194:197], v[144:145], off offset:1792
	global_load_dwordx4 v[198:201], v[146:147], off offset:1792
	s_waitcnt lgkmcnt(1)
	v_mfma_f32_32x32x16_bf16 v[96:111], v[176:179], v[208:211], v[96:111]
	v_mfma_f32_32x32x16_bf16 v[112:127], v[180:183], v[208:211], v[112:127]
	s_waitcnt lgkmcnt(0)
	v_mfma_f32_32x32x16_bf16 v[64:79], v[176:179], v[212:215], v[64:79]
	v_mfma_f32_32x32x16_bf16 v[80:95], v[180:183], v[212:215], v[80:95]
	ds_read_b128 v[208:211], v151 offset:9312
	ds_read_b128 v[212:215], v151 offset:13920
	s_waitcnt lgkmcnt(1)
	v_mfma_f32_32x32x16_bf16 v[32:47], v[176:179], v[208:211], v[32:47]
	v_mfma_f32_32x32x16_bf16 v[48:63], v[180:183], v[208:211], v[48:63]
	s_waitcnt lgkmcnt(0)
	v_mfma_f32_32x32x16_bf16 v[0:15], v[176:179], v[212:215], v[0:15]
	v_mfma_f32_32x32x16_bf16 v[16:31], v[180:183], v[212:215], v[16:31]
	s_setprio 0
	s_barrier
	global_load_dwordx4 v[176:179], v[136:137], off offset:1920
	global_load_dwordx4 v[180:183], v[138:139], off offset:1920
	s_waitcnt vmcnt(9)
	ds_write_b128 v148, v[168:171]
	s_waitcnt vmcnt(8)
	ds_write_b128 v148, v[172:175] offset:36864
	ds_read_b128 v[168:171], v150
	ds_read_b128 v[172:175], v150 offset:4608
	ds_read_b128 v[208:211], v149
	ds_read_b128 v[212:215], v149 offset:4608
	s_setprio 1
	s_waitcnt lgkmcnt(1)
	v_mfma_f32_32x32x16_bf16 v[96:111], v[168:171], v[208:211], v[96:111]
	v_mfma_f32_32x32x16_bf16 v[112:127], v[172:175], v[208:211], v[112:127]
	s_waitcnt lgkmcnt(0)
	v_mfma_f32_32x32x16_bf16 v[64:79], v[168:171], v[212:215], v[64:79]
	v_mfma_f32_32x32x16_bf16 v[80:95], v[172:175], v[212:215], v[80:95]
	ds_read_b128 v[208:211], v149 offset:9216
	ds_read_b128 v[212:215], v149 offset:13824
	s_waitcnt vmcnt(7)
	ds_write_b128 v148, v[160:163] offset:9216
	s_waitcnt vmcnt(6)
	ds_write_b128 v148, v[164:167] offset:46080
	ds_read_b128 v[160:163], v150 offset:32
	ds_read_b128 v[164:167], v150 offset:4640
	s_waitcnt lgkmcnt(5)
	v_mfma_f32_32x32x16_bf16 v[32:47], v[168:171], v[208:211], v[32:47]
	v_mfma_f32_32x32x16_bf16 v[48:63], v[172:175], v[208:211], v[48:63]
	ds_read_b128 v[208:211], v149 offset:32
	s_waitcnt lgkmcnt(5)
	v_mfma_f32_32x32x16_bf16 v[0:15], v[168:171], v[212:215], v[0:15]
	v_mfma_f32_32x32x16_bf16 v[16:31], v[172:175], v[212:215], v[16:31]
	ds_read_b128 v[212:215], v149 offset:4640
	global_load_dwordx4 v[168:171], v[140:141], off offset:1920
	global_load_dwordx4 v[172:175], v[142:143], off offset:1920
	s_waitcnt lgkmcnt(1)
	v_mfma_f32_32x32x16_bf16 v[96:111], v[160:163], v[208:211], v[96:111]
	v_mfma_f32_32x32x16_bf16 v[112:127], v[164:167], v[208:211], v[112:127]
	s_waitcnt lgkmcnt(0)
	v_mfma_f32_32x32x16_bf16 v[64:79], v[160:163], v[212:215], v[64:79]
	v_mfma_f32_32x32x16_bf16 v[80:95], v[164:167], v[212:215], v[80:95]
	ds_read_b128 v[208:211], v149 offset:9248
	ds_read_b128 v[212:215], v149 offset:13856
	s_waitcnt vmcnt(7)
	ds_write_b128 v148, v[184:187] offset:18432
	s_waitcnt vmcnt(6)
	ds_write_b128 v148, v[188:191] offset:55296
	ds_read_b128 v[184:187], v150 offset:64
	ds_read_b128 v[188:191], v150 offset:4672
	s_waitcnt lgkmcnt(5)
	v_mfma_f32_32x32x16_bf16 v[32:47], v[160:163], v[208:211], v[32:47]
	v_mfma_f32_32x32x16_bf16 v[48:63], v[164:167], v[208:211], v[48:63]
	ds_read_b128 v[208:211], v149 offset:64
	s_waitcnt lgkmcnt(5)
	v_mfma_f32_32x32x16_bf16 v[0:15], v[160:163], v[212:215], v[0:15]
	v_mfma_f32_32x32x16_bf16 v[16:31], v[164:167], v[212:215], v[16:31]
	ds_read_b128 v[212:215], v149 offset:4672
	global_load_dwordx4 v[160:163], v[132:133], off offset:1920
	global_load_dwordx4 v[164:167], v[134:135], off offset:1920
	s_waitcnt lgkmcnt(1)
	v_mfma_f32_32x32x16_bf16 v[96:111], v[184:187], v[208:211], v[96:111]
	v_mfma_f32_32x32x16_bf16 v[112:127], v[188:191], v[208:211], v[112:127]
	s_waitcnt lgkmcnt(0)
	v_mfma_f32_32x32x16_bf16 v[64:79], v[184:187], v[212:215], v[64:79]
	v_mfma_f32_32x32x16_bf16 v[80:95], v[188:191], v[212:215], v[80:95]
	ds_read_b128 v[208:211], v149 offset:9280
	ds_read_b128 v[212:215], v149 offset:13888
	s_waitcnt vmcnt(7)
	ds_write_b128 v148, v[194:197] offset:27648
	s_waitcnt vmcnt(6)
	ds_write_b128 v148, v[198:201] offset:64512
	ds_read_b128 v[194:197], v150 offset:96
	ds_read_b128 v[198:201], v150 offset:4704
	s_waitcnt lgkmcnt(5)
	v_mfma_f32_32x32x16_bf16 v[32:47], v[184:187], v[208:211], v[32:47]
	v_mfma_f32_32x32x16_bf16 v[48:63], v[188:191], v[208:211], v[48:63]
	ds_read_b128 v[208:211], v149 offset:96
	s_waitcnt lgkmcnt(5)
	v_mfma_f32_32x32x16_bf16 v[0:15], v[184:187], v[212:215], v[0:15]
	v_mfma_f32_32x32x16_bf16 v[16:31], v[188:191], v[212:215], v[16:31]
	ds_read_b128 v[212:215], v149 offset:4704
	global_load_dwordx4 v[184:187], v[144:145], off offset:1920
	global_load_dwordx4 v[188:191], v[146:147], off offset:1920
	s_waitcnt lgkmcnt(1)
	v_mfma_f32_32x32x16_bf16 v[96:111], v[194:197], v[208:211], v[96:111]
	v_mfma_f32_32x32x16_bf16 v[112:127], v[198:201], v[208:211], v[112:127]
	s_waitcnt lgkmcnt(0)
	v_mfma_f32_32x32x16_bf16 v[64:79], v[194:197], v[212:215], v[64:79]
	v_mfma_f32_32x32x16_bf16 v[80:95], v[198:201], v[212:215], v[80:95]
	ds_read_b128 v[208:211], v149 offset:9312
	ds_read_b128 v[212:215], v149 offset:13920
	s_waitcnt lgkmcnt(1)
	v_mfma_f32_32x32x16_bf16 v[32:47], v[194:197], v[208:211], v[32:47]
	v_mfma_f32_32x32x16_bf16 v[48:63], v[198:201], v[208:211], v[48:63]
	s_waitcnt lgkmcnt(0)
	v_mfma_f32_32x32x16_bf16 v[0:15], v[194:197], v[212:215], v[0:15]
	v_mfma_f32_32x32x16_bf16 v[16:31], v[198:201], v[212:215], v[16:31]
	s_setprio 0
	s_barrier
	global_load_dwordx4 v[194:197], v[136:137], off offset:2048
	global_load_dwordx4 v[198:201], v[138:139], off offset:2048
	s_waitcnt vmcnt(9)
	ds_write_b128 v192, v[176:179]
	s_waitcnt vmcnt(8)
	ds_write_b128 v159, v[180:183]
	ds_read_b128 v[176:179], v152 offset:36864
	ds_read_b128 v[180:183], v152 offset:41472
	ds_read_b128 v[208:211], v151
	ds_read_b128 v[212:215], v151 offset:4608
	s_setprio 1
	s_waitcnt lgkmcnt(1)
	v_mfma_f32_32x32x16_bf16 v[96:111], v[176:179], v[208:211], v[96:111]
	v_mfma_f32_32x32x16_bf16 v[112:127], v[180:183], v[208:211], v[112:127]
	s_waitcnt lgkmcnt(0)
	v_mfma_f32_32x32x16_bf16 v[64:79], v[176:179], v[212:215], v[64:79]
	v_mfma_f32_32x32x16_bf16 v[80:95], v[180:183], v[212:215], v[80:95]
	ds_read_b128 v[208:211], v151 offset:9216
	ds_read_b128 v[212:215], v151 offset:13824
	s_waitcnt vmcnt(7)
	ds_write_b128 v158, v[168:171]
	s_waitcnt vmcnt(6)
	ds_write_b128 v157, v[172:175]
	ds_read_b128 v[168:171], v152 offset:36896
	ds_read_b128 v[172:175], v152 offset:41504
	s_waitcnt lgkmcnt(5)
	v_mfma_f32_32x32x16_bf16 v[32:47], v[176:179], v[208:211], v[32:47]
	v_mfma_f32_32x32x16_bf16 v[48:63], v[180:183], v[208:211], v[48:63]
	ds_read_b128 v[208:211], v151 offset:32
	s_waitcnt lgkmcnt(5)
	v_mfma_f32_32x32x16_bf16 v[0:15], v[176:179], v[212:215], v[0:15]
	v_mfma_f32_32x32x16_bf16 v[16:31], v[180:183], v[212:215], v[16:31]
	ds_read_b128 v[212:215], v151 offset:4640
	global_load_dwordx4 v[176:179], v[140:141], off offset:2048
	global_load_dwordx4 v[180:183], v[142:143], off offset:2048
	s_waitcnt lgkmcnt(1)
	v_mfma_f32_32x32x16_bf16 v[96:111], v[168:171], v[208:211], v[96:111]
	v_mfma_f32_32x32x16_bf16 v[112:127], v[172:175], v[208:211], v[112:127]
	s_waitcnt lgkmcnt(0)
	v_mfma_f32_32x32x16_bf16 v[64:79], v[168:171], v[212:215], v[64:79]
	v_mfma_f32_32x32x16_bf16 v[80:95], v[172:175], v[212:215], v[80:95]
	ds_read_b128 v[208:211], v151 offset:9248
	ds_read_b128 v[212:215], v151 offset:13856
	s_waitcnt vmcnt(7)
	ds_write_b128 v154, v[160:163]
	s_waitcnt vmcnt(6)
	ds_write_b128 v153, v[164:167]
	ds_read_b128 v[160:163], v152 offset:36928
	ds_read_b128 v[164:167], v152 offset:41536
	s_waitcnt lgkmcnt(5)
	v_mfma_f32_32x32x16_bf16 v[32:47], v[168:171], v[208:211], v[32:47]
	v_mfma_f32_32x32x16_bf16 v[48:63], v[172:175], v[208:211], v[48:63]
	ds_read_b128 v[208:211], v151 offset:64
	s_waitcnt lgkmcnt(5)
	v_mfma_f32_32x32x16_bf16 v[0:15], v[168:171], v[212:215], v[0:15]
	v_mfma_f32_32x32x16_bf16 v[16:31], v[172:175], v[212:215], v[16:31]
	ds_read_b128 v[212:215], v151 offset:4672
	global_load_dwordx4 v[168:171], v[132:133], off offset:2048
	global_load_dwordx4 v[172:175], v[134:135], off offset:2048
	s_waitcnt lgkmcnt(1)
	v_mfma_f32_32x32x16_bf16 v[96:111], v[160:163], v[208:211], v[96:111]
	v_mfma_f32_32x32x16_bf16 v[112:127], v[164:167], v[208:211], v[112:127]
	s_waitcnt lgkmcnt(0)
	v_mfma_f32_32x32x16_bf16 v[64:79], v[160:163], v[212:215], v[64:79]
	v_mfma_f32_32x32x16_bf16 v[80:95], v[164:167], v[212:215], v[80:95]
	ds_read_b128 v[208:211], v151 offset:9280
	ds_read_b128 v[212:215], v151 offset:13888
	s_waitcnt vmcnt(7)
	ds_write_b128 v156, v[184:187]
	s_waitcnt vmcnt(6)
	ds_write_b128 v155, v[188:191]
	ds_read_b128 v[184:187], v152 offset:36960
	ds_read_b128 v[188:191], v152 offset:41568
	s_waitcnt lgkmcnt(5)
	v_mfma_f32_32x32x16_bf16 v[32:47], v[160:163], v[208:211], v[32:47]
	v_mfma_f32_32x32x16_bf16 v[48:63], v[164:167], v[208:211], v[48:63]
	ds_read_b128 v[208:211], v151 offset:96
	s_waitcnt lgkmcnt(5)
	v_mfma_f32_32x32x16_bf16 v[0:15], v[160:163], v[212:215], v[0:15]
	v_mfma_f32_32x32x16_bf16 v[16:31], v[164:167], v[212:215], v[16:31]
	ds_read_b128 v[212:215], v151 offset:4704
	global_load_dwordx4 v[160:163], v[144:145], off offset:2048
	global_load_dwordx4 v[164:167], v[146:147], off offset:2048
	s_waitcnt lgkmcnt(1)
	v_mfma_f32_32x32x16_bf16 v[96:111], v[184:187], v[208:211], v[96:111]
	v_mfma_f32_32x32x16_bf16 v[112:127], v[188:191], v[208:211], v[112:127]
	s_waitcnt lgkmcnt(0)
	v_mfma_f32_32x32x16_bf16 v[64:79], v[184:187], v[212:215], v[64:79]
	v_mfma_f32_32x32x16_bf16 v[80:95], v[188:191], v[212:215], v[80:95]
	ds_read_b128 v[208:211], v151 offset:9312
	ds_read_b128 v[212:215], v151 offset:13920
	s_waitcnt lgkmcnt(1)
	v_mfma_f32_32x32x16_bf16 v[32:47], v[184:187], v[208:211], v[32:47]
	v_mfma_f32_32x32x16_bf16 v[48:63], v[188:191], v[208:211], v[48:63]
	s_waitcnt lgkmcnt(0)
	v_mfma_f32_32x32x16_bf16 v[0:15], v[184:187], v[212:215], v[0:15]
	v_mfma_f32_32x32x16_bf16 v[16:31], v[188:191], v[212:215], v[16:31]
	s_setprio 0
	s_barrier
	global_load_dwordx4 v[184:187], v[136:137], off offset:2176
	global_load_dwordx4 v[188:191], v[138:139], off offset:2176
	s_waitcnt vmcnt(9)
	ds_write_b128 v148, v[194:197]
	s_waitcnt vmcnt(8)
	ds_write_b128 v148, v[198:201] offset:36864
	ds_read_b128 v[194:197], v150
	ds_read_b128 v[198:201], v150 offset:4608
	ds_read_b128 v[208:211], v149
	ds_read_b128 v[212:215], v149 offset:4608
	s_setprio 1
	s_waitcnt lgkmcnt(1)
	v_mfma_f32_32x32x16_bf16 v[96:111], v[194:197], v[208:211], v[96:111]
	v_mfma_f32_32x32x16_bf16 v[112:127], v[198:201], v[208:211], v[112:127]
	s_waitcnt lgkmcnt(0)
	v_mfma_f32_32x32x16_bf16 v[64:79], v[194:197], v[212:215], v[64:79]
	v_mfma_f32_32x32x16_bf16 v[80:95], v[198:201], v[212:215], v[80:95]
	ds_read_b128 v[208:211], v149 offset:9216
	ds_read_b128 v[212:215], v149 offset:13824
	s_waitcnt vmcnt(7)
	ds_write_b128 v148, v[176:179] offset:9216
	s_waitcnt vmcnt(6)
	ds_write_b128 v148, v[180:183] offset:46080
	ds_read_b128 v[176:179], v150 offset:32
	ds_read_b128 v[180:183], v150 offset:4640
	s_waitcnt lgkmcnt(5)
	v_mfma_f32_32x32x16_bf16 v[32:47], v[194:197], v[208:211], v[32:47]
	v_mfma_f32_32x32x16_bf16 v[48:63], v[198:201], v[208:211], v[48:63]
	ds_read_b128 v[208:211], v149 offset:32
	s_waitcnt lgkmcnt(5)
	v_mfma_f32_32x32x16_bf16 v[0:15], v[194:197], v[212:215], v[0:15]
	v_mfma_f32_32x32x16_bf16 v[16:31], v[198:201], v[212:215], v[16:31]
	ds_read_b128 v[212:215], v149 offset:4640
	global_load_dwordx4 v[194:197], v[140:141], off offset:2176
	global_load_dwordx4 v[198:201], v[142:143], off offset:2176
	s_waitcnt lgkmcnt(1)
	v_mfma_f32_32x32x16_bf16 v[96:111], v[176:179], v[208:211], v[96:111]
	v_mfma_f32_32x32x16_bf16 v[112:127], v[180:183], v[208:211], v[112:127]
	s_waitcnt lgkmcnt(0)
	v_mfma_f32_32x32x16_bf16 v[64:79], v[176:179], v[212:215], v[64:79]
	v_mfma_f32_32x32x16_bf16 v[80:95], v[180:183], v[212:215], v[80:95]
	ds_read_b128 v[208:211], v149 offset:9248
	ds_read_b128 v[212:215], v149 offset:13856
	s_waitcnt vmcnt(7)
	ds_write_b128 v148, v[168:171] offset:18432
	s_waitcnt vmcnt(6)
	ds_write_b128 v148, v[172:175] offset:55296
	ds_read_b128 v[168:171], v150 offset:64
	ds_read_b128 v[172:175], v150 offset:4672
	s_waitcnt lgkmcnt(5)
	v_mfma_f32_32x32x16_bf16 v[32:47], v[176:179], v[208:211], v[32:47]
	v_mfma_f32_32x32x16_bf16 v[48:63], v[180:183], v[208:211], v[48:63]
	ds_read_b128 v[208:211], v149 offset:64
	s_waitcnt lgkmcnt(5)
	v_mfma_f32_32x32x16_bf16 v[0:15], v[176:179], v[212:215], v[0:15]
	v_mfma_f32_32x32x16_bf16 v[16:31], v[180:183], v[212:215], v[16:31]
	ds_read_b128 v[212:215], v149 offset:4672
	global_load_dwordx4 v[176:179], v[132:133], off offset:2176
	global_load_dwordx4 v[180:183], v[134:135], off offset:2176
	s_waitcnt lgkmcnt(1)
	v_mfma_f32_32x32x16_bf16 v[96:111], v[168:171], v[208:211], v[96:111]
	v_mfma_f32_32x32x16_bf16 v[112:127], v[172:175], v[208:211], v[112:127]
	s_waitcnt lgkmcnt(0)
	v_mfma_f32_32x32x16_bf16 v[64:79], v[168:171], v[212:215], v[64:79]
	v_mfma_f32_32x32x16_bf16 v[80:95], v[172:175], v[212:215], v[80:95]
	ds_read_b128 v[208:211], v149 offset:9280
	ds_read_b128 v[212:215], v149 offset:13888
	s_waitcnt vmcnt(7)
	ds_write_b128 v148, v[160:163] offset:27648
	s_waitcnt vmcnt(6)
	ds_write_b128 v148, v[164:167] offset:64512
	ds_read_b128 v[160:163], v150 offset:96
	ds_read_b128 v[164:167], v150 offset:4704
	s_waitcnt lgkmcnt(5)
	v_mfma_f32_32x32x16_bf16 v[32:47], v[168:171], v[208:211], v[32:47]
	v_mfma_f32_32x32x16_bf16 v[48:63], v[172:175], v[208:211], v[48:63]
	ds_read_b128 v[208:211], v149 offset:96
	s_waitcnt lgkmcnt(5)
	v_mfma_f32_32x32x16_bf16 v[0:15], v[168:171], v[212:215], v[0:15]
	v_mfma_f32_32x32x16_bf16 v[16:31], v[172:175], v[212:215], v[16:31]
	ds_read_b128 v[212:215], v149 offset:4704
	global_load_dwordx4 v[168:171], v[144:145], off offset:2176
	global_load_dwordx4 v[172:175], v[146:147], off offset:2176
	s_waitcnt lgkmcnt(1)
	v_mfma_f32_32x32x16_bf16 v[96:111], v[160:163], v[208:211], v[96:111]
	v_mfma_f32_32x32x16_bf16 v[112:127], v[164:167], v[208:211], v[112:127]
	s_waitcnt lgkmcnt(0)
	v_mfma_f32_32x32x16_bf16 v[64:79], v[160:163], v[212:215], v[64:79]
	v_mfma_f32_32x32x16_bf16 v[80:95], v[164:167], v[212:215], v[80:95]
	ds_read_b128 v[208:211], v149 offset:9312
	ds_read_b128 v[212:215], v149 offset:13920
	s_waitcnt lgkmcnt(1)
	v_mfma_f32_32x32x16_bf16 v[32:47], v[160:163], v[208:211], v[32:47]
	v_mfma_f32_32x32x16_bf16 v[48:63], v[164:167], v[208:211], v[48:63]
	s_waitcnt lgkmcnt(0)
	v_mfma_f32_32x32x16_bf16 v[0:15], v[160:163], v[212:215], v[0:15]
	v_mfma_f32_32x32x16_bf16 v[16:31], v[164:167], v[212:215], v[16:31]
	s_setprio 0
	s_barrier
	global_load_dwordx4 v[160:163], v[136:137], off offset:2304
	global_load_dwordx4 v[164:167], v[138:139], off offset:2304
	s_waitcnt vmcnt(9)
	ds_write_b128 v192, v[184:187]
	s_waitcnt vmcnt(8)
	ds_write_b128 v159, v[188:191]
	ds_read_b128 v[184:187], v152 offset:36864
	ds_read_b128 v[188:191], v152 offset:41472
	ds_read_b128 v[208:211], v151
	ds_read_b128 v[212:215], v151 offset:4608
	s_setprio 1
	s_waitcnt lgkmcnt(1)
	v_mfma_f32_32x32x16_bf16 v[96:111], v[184:187], v[208:211], v[96:111]
	v_mfma_f32_32x32x16_bf16 v[112:127], v[188:191], v[208:211], v[112:127]
	s_waitcnt lgkmcnt(0)
	v_mfma_f32_32x32x16_bf16 v[64:79], v[184:187], v[212:215], v[64:79]
	v_mfma_f32_32x32x16_bf16 v[80:95], v[188:191], v[212:215], v[80:95]
	ds_read_b128 v[208:211], v151 offset:9216
	ds_read_b128 v[212:215], v151 offset:13824
	s_waitcnt vmcnt(7)
	ds_write_b128 v158, v[194:197]
	s_waitcnt vmcnt(6)
	ds_write_b128 v157, v[198:201]
	ds_read_b128 v[194:197], v152 offset:36896
	ds_read_b128 v[198:201], v152 offset:41504
	s_waitcnt lgkmcnt(5)
	v_mfma_f32_32x32x16_bf16 v[32:47], v[184:187], v[208:211], v[32:47]
	v_mfma_f32_32x32x16_bf16 v[48:63], v[188:191], v[208:211], v[48:63]
	ds_read_b128 v[208:211], v151 offset:32
	s_waitcnt lgkmcnt(5)
	v_mfma_f32_32x32x16_bf16 v[0:15], v[184:187], v[212:215], v[0:15]
	v_mfma_f32_32x32x16_bf16 v[16:31], v[188:191], v[212:215], v[16:31]
	ds_read_b128 v[212:215], v151 offset:4640
	global_load_dwordx4 v[184:187], v[140:141], off offset:2304
	global_load_dwordx4 v[188:191], v[142:143], off offset:2304
	s_waitcnt lgkmcnt(1)
	v_mfma_f32_32x32x16_bf16 v[96:111], v[194:197], v[208:211], v[96:111]
	v_mfma_f32_32x32x16_bf16 v[112:127], v[198:201], v[208:211], v[112:127]
	s_waitcnt lgkmcnt(0)
	v_mfma_f32_32x32x16_bf16 v[64:79], v[194:197], v[212:215], v[64:79]
	v_mfma_f32_32x32x16_bf16 v[80:95], v[198:201], v[212:215], v[80:95]
	ds_read_b128 v[208:211], v151 offset:9248
	ds_read_b128 v[212:215], v151 offset:13856
	s_waitcnt vmcnt(7)
	ds_write_b128 v154, v[176:179]
	s_waitcnt vmcnt(6)
	ds_write_b128 v153, v[180:183]
	ds_read_b128 v[176:179], v152 offset:36928
	ds_read_b128 v[180:183], v152 offset:41536
	s_waitcnt lgkmcnt(5)
	v_mfma_f32_32x32x16_bf16 v[32:47], v[194:197], v[208:211], v[32:47]
	v_mfma_f32_32x32x16_bf16 v[48:63], v[198:201], v[208:211], v[48:63]
	ds_read_b128 v[208:211], v151 offset:64
	s_waitcnt lgkmcnt(5)
	v_mfma_f32_32x32x16_bf16 v[0:15], v[194:197], v[212:215], v[0:15]
	v_mfma_f32_32x32x16_bf16 v[16:31], v[198:201], v[212:215], v[16:31]
	ds_read_b128 v[212:215], v151 offset:4672
	global_load_dwordx4 v[194:197], v[132:133], off offset:2304
	global_load_dwordx4 v[198:201], v[134:135], off offset:2304
	s_waitcnt lgkmcnt(1)
	v_mfma_f32_32x32x16_bf16 v[96:111], v[176:179], v[208:211], v[96:111]
	v_mfma_f32_32x32x16_bf16 v[112:127], v[180:183], v[208:211], v[112:127]
	s_waitcnt lgkmcnt(0)
	v_mfma_f32_32x32x16_bf16 v[64:79], v[176:179], v[212:215], v[64:79]
	v_mfma_f32_32x32x16_bf16 v[80:95], v[180:183], v[212:215], v[80:95]
	ds_read_b128 v[208:211], v151 offset:9280
	ds_read_b128 v[212:215], v151 offset:13888
	s_waitcnt vmcnt(7)
	ds_write_b128 v156, v[168:171]
	s_waitcnt vmcnt(6)
	ds_write_b128 v155, v[172:175]
	ds_read_b128 v[168:171], v152 offset:36960
	ds_read_b128 v[172:175], v152 offset:41568
	s_waitcnt lgkmcnt(5)
	v_mfma_f32_32x32x16_bf16 v[32:47], v[176:179], v[208:211], v[32:47]
	v_mfma_f32_32x32x16_bf16 v[48:63], v[180:183], v[208:211], v[48:63]
	ds_read_b128 v[208:211], v151 offset:96
	s_waitcnt lgkmcnt(5)
	v_mfma_f32_32x32x16_bf16 v[0:15], v[176:179], v[212:215], v[0:15]
	v_mfma_f32_32x32x16_bf16 v[16:31], v[180:183], v[212:215], v[16:31]
	ds_read_b128 v[212:215], v151 offset:4704
	global_load_dwordx4 v[176:179], v[144:145], off offset:2304
	global_load_dwordx4 v[180:183], v[146:147], off offset:2304
	s_waitcnt lgkmcnt(1)
	v_mfma_f32_32x32x16_bf16 v[96:111], v[168:171], v[208:211], v[96:111]
	v_mfma_f32_32x32x16_bf16 v[112:127], v[172:175], v[208:211], v[112:127]
	s_waitcnt lgkmcnt(0)
	v_mfma_f32_32x32x16_bf16 v[64:79], v[168:171], v[212:215], v[64:79]
	v_mfma_f32_32x32x16_bf16 v[80:95], v[172:175], v[212:215], v[80:95]
	ds_read_b128 v[208:211], v151 offset:9312
	ds_read_b128 v[212:215], v151 offset:13920
	s_waitcnt lgkmcnt(1)
	v_mfma_f32_32x32x16_bf16 v[32:47], v[168:171], v[208:211], v[32:47]
	v_mfma_f32_32x32x16_bf16 v[48:63], v[172:175], v[208:211], v[48:63]
	s_waitcnt lgkmcnt(0)
	v_mfma_f32_32x32x16_bf16 v[0:15], v[168:171], v[212:215], v[0:15]
	v_mfma_f32_32x32x16_bf16 v[16:31], v[172:175], v[212:215], v[16:31]
	s_setprio 0
	s_barrier
	global_load_dwordx4 v[168:171], v[136:137], off offset:2432
	global_load_dwordx4 v[172:175], v[138:139], off offset:2432
	s_waitcnt vmcnt(9)
	ds_write_b128 v148, v[160:163]
	s_waitcnt vmcnt(8)
	ds_write_b128 v148, v[164:167] offset:36864
	ds_read_b128 v[160:163], v150
	ds_read_b128 v[164:167], v150 offset:4608
	ds_read_b128 v[208:211], v149
	ds_read_b128 v[212:215], v149 offset:4608
	s_setprio 1
	s_waitcnt lgkmcnt(1)
	v_mfma_f32_32x32x16_bf16 v[96:111], v[160:163], v[208:211], v[96:111]
	v_mfma_f32_32x32x16_bf16 v[112:127], v[164:167], v[208:211], v[112:127]
	s_waitcnt lgkmcnt(0)
	v_mfma_f32_32x32x16_bf16 v[64:79], v[160:163], v[212:215], v[64:79]
	v_mfma_f32_32x32x16_bf16 v[80:95], v[164:167], v[212:215], v[80:95]
	ds_read_b128 v[208:211], v149 offset:9216
	ds_read_b128 v[212:215], v149 offset:13824
	s_waitcnt vmcnt(7)
	ds_write_b128 v148, v[184:187] offset:9216
	s_waitcnt vmcnt(6)
	ds_write_b128 v148, v[188:191] offset:46080
	ds_read_b128 v[184:187], v150 offset:32
	ds_read_b128 v[188:191], v150 offset:4640
	s_waitcnt lgkmcnt(5)
	v_mfma_f32_32x32x16_bf16 v[32:47], v[160:163], v[208:211], v[32:47]
	v_mfma_f32_32x32x16_bf16 v[48:63], v[164:167], v[208:211], v[48:63]
	ds_read_b128 v[208:211], v149 offset:32
	s_waitcnt lgkmcnt(5)
	v_mfma_f32_32x32x16_bf16 v[0:15], v[160:163], v[212:215], v[0:15]
	v_mfma_f32_32x32x16_bf16 v[16:31], v[164:167], v[212:215], v[16:31]
	ds_read_b128 v[212:215], v149 offset:4640
	global_load_dwordx4 v[160:163], v[140:141], off offset:2432
	global_load_dwordx4 v[164:167], v[142:143], off offset:2432
	s_waitcnt lgkmcnt(1)
	v_mfma_f32_32x32x16_bf16 v[96:111], v[184:187], v[208:211], v[96:111]
	v_mfma_f32_32x32x16_bf16 v[112:127], v[188:191], v[208:211], v[112:127]
	s_waitcnt lgkmcnt(0)
	v_mfma_f32_32x32x16_bf16 v[64:79], v[184:187], v[212:215], v[64:79]
	v_mfma_f32_32x32x16_bf16 v[80:95], v[188:191], v[212:215], v[80:95]
	ds_read_b128 v[208:211], v149 offset:9248
	ds_read_b128 v[212:215], v149 offset:13856
	s_waitcnt vmcnt(7)
	ds_write_b128 v148, v[194:197] offset:18432
	s_waitcnt vmcnt(6)
	ds_write_b128 v148, v[198:201] offset:55296
	ds_read_b128 v[194:197], v150 offset:64
	ds_read_b128 v[198:201], v150 offset:4672
	s_waitcnt lgkmcnt(5)
	v_mfma_f32_32x32x16_bf16 v[32:47], v[184:187], v[208:211], v[32:47]
	v_mfma_f32_32x32x16_bf16 v[48:63], v[188:191], v[208:211], v[48:63]
	ds_read_b128 v[208:211], v149 offset:64
	s_waitcnt lgkmcnt(5)
	v_mfma_f32_32x32x16_bf16 v[0:15], v[184:187], v[212:215], v[0:15]
	v_mfma_f32_32x32x16_bf16 v[16:31], v[188:191], v[212:215], v[16:31]
	ds_read_b128 v[212:215], v149 offset:4672
	global_load_dwordx4 v[184:187], v[132:133], off offset:2432
	global_load_dwordx4 v[188:191], v[134:135], off offset:2432
	s_waitcnt lgkmcnt(1)
	v_mfma_f32_32x32x16_bf16 v[96:111], v[194:197], v[208:211], v[96:111]
	v_mfma_f32_32x32x16_bf16 v[112:127], v[198:201], v[208:211], v[112:127]
	s_waitcnt lgkmcnt(0)
	v_mfma_f32_32x32x16_bf16 v[64:79], v[194:197], v[212:215], v[64:79]
	v_mfma_f32_32x32x16_bf16 v[80:95], v[198:201], v[212:215], v[80:95]
	ds_read_b128 v[208:211], v149 offset:9280
	ds_read_b128 v[212:215], v149 offset:13888
	s_waitcnt vmcnt(7)
	ds_write_b128 v148, v[176:179] offset:27648
	s_waitcnt vmcnt(6)
	ds_write_b128 v148, v[180:183] offset:64512
	ds_read_b128 v[176:179], v150 offset:96
	ds_read_b128 v[180:183], v150 offset:4704
	s_waitcnt lgkmcnt(5)
	v_mfma_f32_32x32x16_bf16 v[32:47], v[194:197], v[208:211], v[32:47]
	v_mfma_f32_32x32x16_bf16 v[48:63], v[198:201], v[208:211], v[48:63]
	ds_read_b128 v[208:211], v149 offset:96
	s_waitcnt lgkmcnt(5)
	v_mfma_f32_32x32x16_bf16 v[0:15], v[194:197], v[212:215], v[0:15]
	v_mfma_f32_32x32x16_bf16 v[16:31], v[198:201], v[212:215], v[16:31]
	ds_read_b128 v[212:215], v149 offset:4704
	global_load_dwordx4 v[194:197], v[144:145], off offset:2432
	global_load_dwordx4 v[198:201], v[146:147], off offset:2432
	s_waitcnt lgkmcnt(1)
	v_mfma_f32_32x32x16_bf16 v[96:111], v[176:179], v[208:211], v[96:111]
	v_mfma_f32_32x32x16_bf16 v[112:127], v[180:183], v[208:211], v[112:127]
	s_waitcnt lgkmcnt(0)
	v_mfma_f32_32x32x16_bf16 v[64:79], v[176:179], v[212:215], v[64:79]
	v_mfma_f32_32x32x16_bf16 v[80:95], v[180:183], v[212:215], v[80:95]
	ds_read_b128 v[208:211], v149 offset:9312
	ds_read_b128 v[212:215], v149 offset:13920
	s_waitcnt lgkmcnt(1)
	v_mfma_f32_32x32x16_bf16 v[32:47], v[176:179], v[208:211], v[32:47]
	v_mfma_f32_32x32x16_bf16 v[48:63], v[180:183], v[208:211], v[48:63]
	s_waitcnt lgkmcnt(0)
	v_mfma_f32_32x32x16_bf16 v[0:15], v[176:179], v[212:215], v[0:15]
	v_mfma_f32_32x32x16_bf16 v[16:31], v[180:183], v[212:215], v[16:31]
	s_setprio 0
	s_barrier
	global_load_dwordx4 v[176:179], v[136:137], off offset:2560
	global_load_dwordx4 v[180:183], v[138:139], off offset:2560
	s_waitcnt vmcnt(9)
	ds_write_b128 v192, v[168:171]
	s_waitcnt vmcnt(8)
	ds_write_b128 v159, v[172:175]
	ds_read_b128 v[168:171], v152 offset:36864
	ds_read_b128 v[172:175], v152 offset:41472
	ds_read_b128 v[208:211], v151
	ds_read_b128 v[212:215], v151 offset:4608
	s_setprio 1
	s_waitcnt lgkmcnt(1)
	v_mfma_f32_32x32x16_bf16 v[96:111], v[168:171], v[208:211], v[96:111]
	v_mfma_f32_32x32x16_bf16 v[112:127], v[172:175], v[208:211], v[112:127]
	s_waitcnt lgkmcnt(0)
	v_mfma_f32_32x32x16_bf16 v[64:79], v[168:171], v[212:215], v[64:79]
	v_mfma_f32_32x32x16_bf16 v[80:95], v[172:175], v[212:215], v[80:95]
	ds_read_b128 v[208:211], v151 offset:9216
	ds_read_b128 v[212:215], v151 offset:13824
	s_waitcnt vmcnt(7)
	ds_write_b128 v158, v[160:163]
	s_waitcnt vmcnt(6)
	ds_write_b128 v157, v[164:167]
	ds_read_b128 v[160:163], v152 offset:36896
	ds_read_b128 v[164:167], v152 offset:41504
	s_waitcnt lgkmcnt(5)
	v_mfma_f32_32x32x16_bf16 v[32:47], v[168:171], v[208:211], v[32:47]
	v_mfma_f32_32x32x16_bf16 v[48:63], v[172:175], v[208:211], v[48:63]
	ds_read_b128 v[208:211], v151 offset:32
	s_waitcnt lgkmcnt(5)
	v_mfma_f32_32x32x16_bf16 v[0:15], v[168:171], v[212:215], v[0:15]
	v_mfma_f32_32x32x16_bf16 v[16:31], v[172:175], v[212:215], v[16:31]
	ds_read_b128 v[212:215], v151 offset:4640
	global_load_dwordx4 v[168:171], v[140:141], off offset:2560
	global_load_dwordx4 v[172:175], v[142:143], off offset:2560
	s_waitcnt lgkmcnt(1)
	v_mfma_f32_32x32x16_bf16 v[96:111], v[160:163], v[208:211], v[96:111]
	v_mfma_f32_32x32x16_bf16 v[112:127], v[164:167], v[208:211], v[112:127]
	s_waitcnt lgkmcnt(0)
	v_mfma_f32_32x32x16_bf16 v[64:79], v[160:163], v[212:215], v[64:79]
	v_mfma_f32_32x32x16_bf16 v[80:95], v[164:167], v[212:215], v[80:95]
	ds_read_b128 v[208:211], v151 offset:9248
	ds_read_b128 v[212:215], v151 offset:13856
	s_waitcnt vmcnt(7)
	ds_write_b128 v154, v[184:187]
	s_waitcnt vmcnt(6)
	ds_write_b128 v153, v[188:191]
	ds_read_b128 v[184:187], v152 offset:36928
	ds_read_b128 v[188:191], v152 offset:41536
	s_waitcnt lgkmcnt(5)
	v_mfma_f32_32x32x16_bf16 v[32:47], v[160:163], v[208:211], v[32:47]
	v_mfma_f32_32x32x16_bf16 v[48:63], v[164:167], v[208:211], v[48:63]
	ds_read_b128 v[208:211], v151 offset:64
	s_waitcnt lgkmcnt(5)
	v_mfma_f32_32x32x16_bf16 v[0:15], v[160:163], v[212:215], v[0:15]
	v_mfma_f32_32x32x16_bf16 v[16:31], v[164:167], v[212:215], v[16:31]
	ds_read_b128 v[212:215], v151 offset:4672
	global_load_dwordx4 v[160:163], v[132:133], off offset:2560
	global_load_dwordx4 v[164:167], v[134:135], off offset:2560
	s_waitcnt lgkmcnt(1)
	v_mfma_f32_32x32x16_bf16 v[96:111], v[184:187], v[208:211], v[96:111]
	v_mfma_f32_32x32x16_bf16 v[112:127], v[188:191], v[208:211], v[112:127]
	s_waitcnt lgkmcnt(0)
	v_mfma_f32_32x32x16_bf16 v[64:79], v[184:187], v[212:215], v[64:79]
	v_mfma_f32_32x32x16_bf16 v[80:95], v[188:191], v[212:215], v[80:95]
	ds_read_b128 v[208:211], v151 offset:9280
	ds_read_b128 v[212:215], v151 offset:13888
	s_waitcnt vmcnt(7)
	ds_write_b128 v156, v[194:197]
	s_waitcnt vmcnt(6)
	ds_write_b128 v155, v[198:201]
	ds_read_b128 v[194:197], v152 offset:36960
	ds_read_b128 v[198:201], v152 offset:41568
	s_waitcnt lgkmcnt(5)
	v_mfma_f32_32x32x16_bf16 v[32:47], v[184:187], v[208:211], v[32:47]
	v_mfma_f32_32x32x16_bf16 v[48:63], v[188:191], v[208:211], v[48:63]
	ds_read_b128 v[208:211], v151 offset:96
	s_waitcnt lgkmcnt(5)
	v_mfma_f32_32x32x16_bf16 v[0:15], v[184:187], v[212:215], v[0:15]
	v_mfma_f32_32x32x16_bf16 v[16:31], v[188:191], v[212:215], v[16:31]
	ds_read_b128 v[212:215], v151 offset:4704
	global_load_dwordx4 v[184:187], v[144:145], off offset:2560
	global_load_dwordx4 v[188:191], v[146:147], off offset:2560
	s_waitcnt lgkmcnt(1)
	v_mfma_f32_32x32x16_bf16 v[96:111], v[194:197], v[208:211], v[96:111]
	v_mfma_f32_32x32x16_bf16 v[112:127], v[198:201], v[208:211], v[112:127]
	s_waitcnt lgkmcnt(0)
	v_mfma_f32_32x32x16_bf16 v[64:79], v[194:197], v[212:215], v[64:79]
	v_mfma_f32_32x32x16_bf16 v[80:95], v[198:201], v[212:215], v[80:95]
	ds_read_b128 v[208:211], v151 offset:9312
	ds_read_b128 v[212:215], v151 offset:13920
	s_waitcnt lgkmcnt(1)
	v_mfma_f32_32x32x16_bf16 v[32:47], v[194:197], v[208:211], v[32:47]
	v_mfma_f32_32x32x16_bf16 v[48:63], v[198:201], v[208:211], v[48:63]
	s_waitcnt lgkmcnt(0)
	v_mfma_f32_32x32x16_bf16 v[0:15], v[194:197], v[212:215], v[0:15]
	v_mfma_f32_32x32x16_bf16 v[16:31], v[198:201], v[212:215], v[16:31]
	s_setprio 0
	s_barrier
	global_load_dwordx4 v[194:197], v[136:137], off offset:2688
	global_load_dwordx4 v[198:201], v[138:139], off offset:2688
	s_waitcnt vmcnt(9)
	ds_write_b128 v148, v[176:179]
	s_waitcnt vmcnt(8)
	ds_write_b128 v148, v[180:183] offset:36864
	ds_read_b128 v[176:179], v150
	ds_read_b128 v[180:183], v150 offset:4608
	ds_read_b128 v[208:211], v149
	ds_read_b128 v[212:215], v149 offset:4608
	s_setprio 1
	s_waitcnt lgkmcnt(1)
	v_mfma_f32_32x32x16_bf16 v[96:111], v[176:179], v[208:211], v[96:111]
	v_mfma_f32_32x32x16_bf16 v[112:127], v[180:183], v[208:211], v[112:127]
	s_waitcnt lgkmcnt(0)
	v_mfma_f32_32x32x16_bf16 v[64:79], v[176:179], v[212:215], v[64:79]
	v_mfma_f32_32x32x16_bf16 v[80:95], v[180:183], v[212:215], v[80:95]
	ds_read_b128 v[208:211], v149 offset:9216
	ds_read_b128 v[212:215], v149 offset:13824
	s_waitcnt vmcnt(7)
	ds_write_b128 v148, v[168:171] offset:9216
	s_waitcnt vmcnt(6)
	ds_write_b128 v148, v[172:175] offset:46080
	ds_read_b128 v[168:171], v150 offset:32
	ds_read_b128 v[172:175], v150 offset:4640
	s_waitcnt lgkmcnt(5)
	v_mfma_f32_32x32x16_bf16 v[32:47], v[176:179], v[208:211], v[32:47]
	v_mfma_f32_32x32x16_bf16 v[48:63], v[180:183], v[208:211], v[48:63]
	ds_read_b128 v[208:211], v149 offset:32
	s_waitcnt lgkmcnt(5)
	v_mfma_f32_32x32x16_bf16 v[0:15], v[176:179], v[212:215], v[0:15]
	v_mfma_f32_32x32x16_bf16 v[16:31], v[180:183], v[212:215], v[16:31]
	ds_read_b128 v[212:215], v149 offset:4640
	global_load_dwordx4 v[176:179], v[140:141], off offset:2688
	global_load_dwordx4 v[180:183], v[142:143], off offset:2688
	s_waitcnt lgkmcnt(1)
	v_mfma_f32_32x32x16_bf16 v[96:111], v[168:171], v[208:211], v[96:111]
	v_mfma_f32_32x32x16_bf16 v[112:127], v[172:175], v[208:211], v[112:127]
	s_waitcnt lgkmcnt(0)
	v_mfma_f32_32x32x16_bf16 v[64:79], v[168:171], v[212:215], v[64:79]
	v_mfma_f32_32x32x16_bf16 v[80:95], v[172:175], v[212:215], v[80:95]
	ds_read_b128 v[208:211], v149 offset:9248
	ds_read_b128 v[212:215], v149 offset:13856
	s_waitcnt vmcnt(7)
	ds_write_b128 v148, v[160:163] offset:18432
	s_waitcnt vmcnt(6)
	ds_write_b128 v148, v[164:167] offset:55296
	ds_read_b128 v[160:163], v150 offset:64
	ds_read_b128 v[164:167], v150 offset:4672
	s_waitcnt lgkmcnt(5)
	v_mfma_f32_32x32x16_bf16 v[32:47], v[168:171], v[208:211], v[32:47]
	v_mfma_f32_32x32x16_bf16 v[48:63], v[172:175], v[208:211], v[48:63]
	ds_read_b128 v[208:211], v149 offset:64
	s_waitcnt lgkmcnt(5)
	v_mfma_f32_32x32x16_bf16 v[0:15], v[168:171], v[212:215], v[0:15]
	v_mfma_f32_32x32x16_bf16 v[16:31], v[172:175], v[212:215], v[16:31]
	ds_read_b128 v[212:215], v149 offset:4672
	global_load_dwordx4 v[168:171], v[132:133], off offset:2688
	global_load_dwordx4 v[172:175], v[134:135], off offset:2688
	s_waitcnt lgkmcnt(1)
	v_mfma_f32_32x32x16_bf16 v[96:111], v[160:163], v[208:211], v[96:111]
	v_mfma_f32_32x32x16_bf16 v[112:127], v[164:167], v[208:211], v[112:127]
	s_waitcnt lgkmcnt(0)
	v_mfma_f32_32x32x16_bf16 v[64:79], v[160:163], v[212:215], v[64:79]
	v_mfma_f32_32x32x16_bf16 v[80:95], v[164:167], v[212:215], v[80:95]
	ds_read_b128 v[208:211], v149 offset:9280
	ds_read_b128 v[212:215], v149 offset:13888
	s_waitcnt vmcnt(7)
	ds_write_b128 v148, v[184:187] offset:27648
	s_waitcnt vmcnt(6)
	ds_write_b128 v148, v[188:191] offset:64512
	ds_read_b128 v[184:187], v150 offset:96
	ds_read_b128 v[188:191], v150 offset:4704
	s_waitcnt lgkmcnt(5)
	v_mfma_f32_32x32x16_bf16 v[32:47], v[160:163], v[208:211], v[32:47]
	v_mfma_f32_32x32x16_bf16 v[48:63], v[164:167], v[208:211], v[48:63]
	ds_read_b128 v[208:211], v149 offset:96
	s_waitcnt lgkmcnt(5)
	v_mfma_f32_32x32x16_bf16 v[0:15], v[160:163], v[212:215], v[0:15]
	v_mfma_f32_32x32x16_bf16 v[16:31], v[164:167], v[212:215], v[16:31]
	ds_read_b128 v[212:215], v149 offset:4704
	global_load_dwordx4 v[160:163], v[144:145], off offset:2688
	global_load_dwordx4 v[164:167], v[146:147], off offset:2688
	s_waitcnt lgkmcnt(1)
	v_mfma_f32_32x32x16_bf16 v[96:111], v[184:187], v[208:211], v[96:111]
	v_mfma_f32_32x32x16_bf16 v[112:127], v[188:191], v[208:211], v[112:127]
	s_waitcnt lgkmcnt(0)
	v_mfma_f32_32x32x16_bf16 v[64:79], v[184:187], v[212:215], v[64:79]
	v_mfma_f32_32x32x16_bf16 v[80:95], v[188:191], v[212:215], v[80:95]
	ds_read_b128 v[208:211], v149 offset:9312
	ds_read_b128 v[212:215], v149 offset:13920
	s_waitcnt lgkmcnt(1)
	v_mfma_f32_32x32x16_bf16 v[32:47], v[184:187], v[208:211], v[32:47]
	v_mfma_f32_32x32x16_bf16 v[48:63], v[188:191], v[208:211], v[48:63]
	s_waitcnt lgkmcnt(0)
	v_mfma_f32_32x32x16_bf16 v[0:15], v[184:187], v[212:215], v[0:15]
	v_mfma_f32_32x32x16_bf16 v[16:31], v[188:191], v[212:215], v[16:31]
	s_setprio 0
	s_barrier
	global_load_dwordx4 v[184:187], v[136:137], off offset:2816
	global_load_dwordx4 v[188:191], v[138:139], off offset:2816
	s_waitcnt vmcnt(9)
	ds_write_b128 v192, v[194:197]
	s_waitcnt vmcnt(8)
	ds_write_b128 v159, v[198:201]
	ds_read_b128 v[194:197], v152 offset:36864
	ds_read_b128 v[198:201], v152 offset:41472
	ds_read_b128 v[208:211], v151
	ds_read_b128 v[212:215], v151 offset:4608
	s_setprio 1
	s_waitcnt lgkmcnt(1)
	v_mfma_f32_32x32x16_bf16 v[96:111], v[194:197], v[208:211], v[96:111]
	v_mfma_f32_32x32x16_bf16 v[112:127], v[198:201], v[208:211], v[112:127]
	s_waitcnt lgkmcnt(0)
	v_mfma_f32_32x32x16_bf16 v[64:79], v[194:197], v[212:215], v[64:79]
	v_mfma_f32_32x32x16_bf16 v[80:95], v[198:201], v[212:215], v[80:95]
	ds_read_b128 v[208:211], v151 offset:9216
	ds_read_b128 v[212:215], v151 offset:13824
	s_waitcnt vmcnt(7)
	ds_write_b128 v158, v[176:179]
	s_waitcnt vmcnt(6)
	ds_write_b128 v157, v[180:183]
	ds_read_b128 v[176:179], v152 offset:36896
	ds_read_b128 v[180:183], v152 offset:41504
	s_waitcnt lgkmcnt(5)
	v_mfma_f32_32x32x16_bf16 v[32:47], v[194:197], v[208:211], v[32:47]
	v_mfma_f32_32x32x16_bf16 v[48:63], v[198:201], v[208:211], v[48:63]
	ds_read_b128 v[208:211], v151 offset:32
	s_waitcnt lgkmcnt(5)
	v_mfma_f32_32x32x16_bf16 v[0:15], v[194:197], v[212:215], v[0:15]
	v_mfma_f32_32x32x16_bf16 v[16:31], v[198:201], v[212:215], v[16:31]
	ds_read_b128 v[212:215], v151 offset:4640
	global_load_dwordx4 v[194:197], v[140:141], off offset:2816
	global_load_dwordx4 v[198:201], v[142:143], off offset:2816
	s_waitcnt lgkmcnt(1)
	v_mfma_f32_32x32x16_bf16 v[96:111], v[176:179], v[208:211], v[96:111]
	v_mfma_f32_32x32x16_bf16 v[112:127], v[180:183], v[208:211], v[112:127]
	s_waitcnt lgkmcnt(0)
	v_mfma_f32_32x32x16_bf16 v[64:79], v[176:179], v[212:215], v[64:79]
	v_mfma_f32_32x32x16_bf16 v[80:95], v[180:183], v[212:215], v[80:95]
	ds_read_b128 v[208:211], v151 offset:9248
	ds_read_b128 v[212:215], v151 offset:13856
	s_waitcnt vmcnt(7)
	ds_write_b128 v154, v[168:171]
	s_waitcnt vmcnt(6)
	ds_write_b128 v153, v[172:175]
	ds_read_b128 v[168:171], v152 offset:36928
	ds_read_b128 v[172:175], v152 offset:41536
	s_waitcnt lgkmcnt(5)
	v_mfma_f32_32x32x16_bf16 v[32:47], v[176:179], v[208:211], v[32:47]
	v_mfma_f32_32x32x16_bf16 v[48:63], v[180:183], v[208:211], v[48:63]
	ds_read_b128 v[208:211], v151 offset:64
	s_waitcnt lgkmcnt(5)
	v_mfma_f32_32x32x16_bf16 v[0:15], v[176:179], v[212:215], v[0:15]
	v_mfma_f32_32x32x16_bf16 v[16:31], v[180:183], v[212:215], v[16:31]
	ds_read_b128 v[212:215], v151 offset:4672
	global_load_dwordx4 v[176:179], v[132:133], off offset:2816
	global_load_dwordx4 v[180:183], v[134:135], off offset:2816
	s_waitcnt lgkmcnt(1)
	v_mfma_f32_32x32x16_bf16 v[96:111], v[168:171], v[208:211], v[96:111]
	v_mfma_f32_32x32x16_bf16 v[112:127], v[172:175], v[208:211], v[112:127]
	s_waitcnt lgkmcnt(0)
	v_mfma_f32_32x32x16_bf16 v[64:79], v[168:171], v[212:215], v[64:79]
	v_mfma_f32_32x32x16_bf16 v[80:95], v[172:175], v[212:215], v[80:95]
	ds_read_b128 v[208:211], v151 offset:9280
	ds_read_b128 v[212:215], v151 offset:13888
	s_waitcnt vmcnt(7)
	ds_write_b128 v156, v[160:163]
	s_waitcnt vmcnt(6)
	ds_write_b128 v155, v[164:167]
	ds_read_b128 v[160:163], v152 offset:36960
	ds_read_b128 v[164:167], v152 offset:41568
	s_waitcnt lgkmcnt(5)
	v_mfma_f32_32x32x16_bf16 v[32:47], v[168:171], v[208:211], v[32:47]
	v_mfma_f32_32x32x16_bf16 v[48:63], v[172:175], v[208:211], v[48:63]
	ds_read_b128 v[208:211], v151 offset:96
	s_waitcnt lgkmcnt(5)
	v_mfma_f32_32x32x16_bf16 v[0:15], v[168:171], v[212:215], v[0:15]
	v_mfma_f32_32x32x16_bf16 v[16:31], v[172:175], v[212:215], v[16:31]
	ds_read_b128 v[212:215], v151 offset:4704
	global_load_dwordx4 v[168:171], v[144:145], off offset:2816
	global_load_dwordx4 v[172:175], v[146:147], off offset:2816
	s_waitcnt lgkmcnt(1)
	v_mfma_f32_32x32x16_bf16 v[96:111], v[160:163], v[208:211], v[96:111]
	v_mfma_f32_32x32x16_bf16 v[112:127], v[164:167], v[208:211], v[112:127]
	s_waitcnt lgkmcnt(0)
	v_mfma_f32_32x32x16_bf16 v[64:79], v[160:163], v[212:215], v[64:79]
	v_mfma_f32_32x32x16_bf16 v[80:95], v[164:167], v[212:215], v[80:95]
	ds_read_b128 v[208:211], v151 offset:9312
	ds_read_b128 v[212:215], v151 offset:13920
	s_waitcnt lgkmcnt(1)
	v_mfma_f32_32x32x16_bf16 v[32:47], v[160:163], v[208:211], v[32:47]
	v_mfma_f32_32x32x16_bf16 v[48:63], v[164:167], v[208:211], v[48:63]
	s_waitcnt lgkmcnt(0)
	v_mfma_f32_32x32x16_bf16 v[0:15], v[160:163], v[212:215], v[0:15]
	v_mfma_f32_32x32x16_bf16 v[16:31], v[164:167], v[212:215], v[16:31]
	s_setprio 0
	s_barrier
; template <bool trans>
; DI void gemm_core(const GTile& tl, const GTile& nx, bool has_next  , bool chain  , bool pre, u32x4 (&ra)[4], u32x4 (&rb)[4], char* smem, f32x16 (&acc)[2][4]) {
;     ...
;   const int nk = K / 64;
;   if (!pre) { G_LOAD(0); G_STORE(0); G_LOAD(1); }
;   for (int kt = 0; kt < nk; ++kt) {
;     __syncthreads();
;     G_COMPUTE(kt & 1, kt);
;   }
	global_load_dwordx4 v[160:163], v[136:137], off offset:2944
	global_load_dwordx4 v[164:167], v[138:139], off offset:2944
	s_waitcnt vmcnt(9)
	ds_write_b128 v148, v[184:187]
	s_waitcnt vmcnt(8)
	ds_write_b128 v148, v[188:191] offset:36864
	ds_read_b128 v[184:187], v150
	ds_read_b128 v[188:191], v150 offset:4608
	ds_read_b128 v[208:211], v149
	ds_read_b128 v[212:215], v149 offset:4608
	s_setprio 1
	s_waitcnt lgkmcnt(1)
	v_mfma_f32_32x32x16_bf16 v[96:111], v[184:187], v[208:211], v[96:111]
	v_mfma_f32_32x32x16_bf16 v[112:127], v[188:191], v[208:211], v[112:127]
	s_waitcnt lgkmcnt(0)
	v_mfma_f32_32x32x16_bf16 v[64:79], v[184:187], v[212:215], v[64:79]
	v_mfma_f32_32x32x16_bf16 v[80:95], v[188:191], v[212:215], v[80:95]
	ds_read_b128 v[208:211], v149 offset:9216
	ds_read_b128 v[212:215], v149 offset:13824
	s_waitcnt vmcnt(7)
	ds_write_b128 v148, v[194:197] offset:9216
	s_waitcnt vmcnt(6)
	ds_write_b128 v148, v[198:201] offset:46080
	ds_read_b128 v[194:197], v150 offset:32
	ds_read_b128 v[198:201], v150 offset:4640
	s_waitcnt lgkmcnt(5)
	v_mfma_f32_32x32x16_bf16 v[32:47], v[184:187], v[208:211], v[32:47]
	v_mfma_f32_32x32x16_bf16 v[48:63], v[188:191], v[208:211], v[48:63]
	ds_read_b128 v[208:211], v149 offset:32
	s_waitcnt lgkmcnt(5)
	v_mfma_f32_32x32x16_bf16 v[0:15], v[184:187], v[212:215], v[0:15]
	v_mfma_f32_32x32x16_bf16 v[16:31], v[188:191], v[212:215], v[16:31]
	ds_read_b128 v[212:215], v149 offset:4640
	global_load_dwordx4 v[184:187], v[140:141], off offset:2944
	global_load_dwordx4 v[188:191], v[142:143], off offset:2944
	s_waitcnt lgkmcnt(1)
	v_mfma_f32_32x32x16_bf16 v[96:111], v[194:197], v[208:211], v[96:111]
	v_mfma_f32_32x32x16_bf16 v[112:127], v[198:201], v[208:211], v[112:127]
	s_waitcnt lgkmcnt(0)
	v_mfma_f32_32x32x16_bf16 v[64:79], v[194:197], v[212:215], v[64:79]
	v_mfma_f32_32x32x16_bf16 v[80:95], v[198:201], v[212:215], v[80:95]
	ds_read_b128 v[208:211], v149 offset:9248
	ds_read_b128 v[212:215], v149 offset:13856
	s_waitcnt vmcnt(7)
	ds_write_b128 v148, v[176:179] offset:18432
	s_waitcnt vmcnt(6)
	ds_write_b128 v148, v[180:183] offset:55296
	ds_read_b128 v[176:179], v150 offset:64
	ds_read_b128 v[180:183], v150 offset:4672
	s_waitcnt lgkmcnt(5)
	v_mfma_f32_32x32x16_bf16 v[32:47], v[194:197], v[208:211], v[32:47]
	v_mfma_f32_32x32x16_bf16 v[48:63], v[198:201], v[208:211], v[48:63]
	ds_read_b128 v[208:211], v149 offset:64
	s_waitcnt lgkmcnt(5)
	v_mfma_f32_32x32x16_bf16 v[0:15], v[194:197], v[212:215], v[0:15]
	v_mfma_f32_32x32x16_bf16 v[16:31], v[198:201], v[212:215], v[16:31]
	ds_read_b128 v[212:215], v149 offset:4672
	global_load_dwordx4 v[194:197], v[132:133], off offset:2944
	global_load_dwordx4 v[198:201], v[134:135], off offset:2944
	s_waitcnt lgkmcnt(1)
	v_mfma_f32_32x32x16_bf16 v[96:111], v[176:179], v[208:211], v[96:111]
	v_mfma_f32_32x32x16_bf16 v[112:127], v[180:183], v[208:211], v[112:127]
	s_waitcnt lgkmcnt(0)
	v_mfma_f32_32x32x16_bf16 v[64:79], v[176:179], v[212:215], v[64:79]
	v_mfma_f32_32x32x16_bf16 v[80:95], v[180:183], v[212:215], v[80:95]
	ds_read_b128 v[208:211], v149 offset:9280
	ds_read_b128 v[212:215], v149 offset:13888
	s_waitcnt vmcnt(7)
	ds_write_b128 v148, v[168:171] offset:27648
	s_waitcnt vmcnt(6)
	ds_write_b128 v148, v[172:175] offset:64512
	ds_read_b128 v[168:171], v150 offset:96
	ds_read_b128 v[172:175], v150 offset:4704
	s_waitcnt lgkmcnt(5)
	v_mfma_f32_32x32x16_bf16 v[32:47], v[176:179], v[208:211], v[32:47]
	v_mfma_f32_32x32x16_bf16 v[48:63], v[180:183], v[208:211], v[48:63]
	ds_read_b128 v[208:211], v149 offset:96
	s_waitcnt lgkmcnt(5)
	v_mfma_f32_32x32x16_bf16 v[0:15], v[176:179], v[212:215], v[0:15]
	v_mfma_f32_32x32x16_bf16 v[16:31], v[180:183], v[212:215], v[16:31]
	ds_read_b128 v[212:215], v149 offset:4704
	global_load_dwordx4 v[176:179], v[144:145], off offset:2944
	global_load_dwordx4 v[180:183], v[146:147], off offset:2944
	s_waitcnt lgkmcnt(1)
	v_mfma_f32_32x32x16_bf16 v[96:111], v[168:171], v[208:211], v[96:111]
	v_mfma_f32_32x32x16_bf16 v[112:127], v[172:175], v[208:211], v[112:127]
	s_waitcnt lgkmcnt(0)
	v_mfma_f32_32x32x16_bf16 v[64:79], v[168:171], v[212:215], v[64:79]
	v_mfma_f32_32x32x16_bf16 v[80:95], v[172:175], v[212:215], v[80:95]
	ds_read_b128 v[208:211], v149 offset:9312
	ds_read_b128 v[212:215], v149 offset:13920
	s_waitcnt lgkmcnt(1)
	v_mfma_f32_32x32x16_bf16 v[32:47], v[168:171], v[208:211], v[32:47]
	v_mfma_f32_32x32x16_bf16 v[48:63], v[172:175], v[208:211], v[48:63]
	s_waitcnt lgkmcnt(0)
	v_mfma_f32_32x32x16_bf16 v[0:15], v[168:171], v[212:215], v[0:15]
	v_mfma_f32_32x32x16_bf16 v[16:31], v[172:175], v[212:215], v[16:31]
	s_setprio 0
	s_barrier
; template <bool trans>
; DI void gemm_core(const GTile& tl, const GTile& nx, bool has_next  , bool chain  , bool pre, u32x4 (&ra)[4], u32x4 (&rb)[4], char* smem, f32x16 (&acc)[2][4]) {
;     ...
;   const int nk = K / 64;
;   if (!pre) { G_LOAD(0); G_STORE(0); G_LOAD(1); }
;   for (int kt = 0; kt < nk; ++kt) {
;     __syncthreads();
;     G_COMPUTE(kt & 1, kt);
;   }
	global_load_dwordx4 v[168:171], v[136:137], off offset:3072
	global_load_dwordx4 v[172:175], v[138:139], off offset:3072
	s_waitcnt vmcnt(9)
	ds_write_b128 v192, v[160:163]
	s_waitcnt vmcnt(8)
	ds_write_b128 v159, v[164:167]
	ds_read_b128 v[160:163], v152 offset:36864
	ds_read_b128 v[164:167], v152 offset:41472
	ds_read_b128 v[208:211], v151
	ds_read_b128 v[212:215], v151 offset:4608
	s_setprio 1
	s_waitcnt lgkmcnt(1)
	v_mfma_f32_32x32x16_bf16 v[96:111], v[160:163], v[208:211], v[96:111]
	v_mfma_f32_32x32x16_bf16 v[112:127], v[164:167], v[208:211], v[112:127]
	s_waitcnt lgkmcnt(0)
	v_mfma_f32_32x32x16_bf16 v[64:79], v[160:163], v[212:215], v[64:79]
	v_mfma_f32_32x32x16_bf16 v[80:95], v[164:167], v[212:215], v[80:95]
	ds_read_b128 v[208:211], v151 offset:9216
	ds_read_b128 v[212:215], v151 offset:13824
	s_waitcnt vmcnt(7)
	ds_write_b128 v158, v[184:187]
	s_waitcnt vmcnt(6)
	ds_write_b128 v157, v[188:191]
	ds_read_b128 v[184:187], v152 offset:36896
	ds_read_b128 v[188:191], v152 offset:41504
	s_waitcnt lgkmcnt(5)
	v_mfma_f32_32x32x16_bf16 v[32:47], v[160:163], v[208:211], v[32:47]
	v_mfma_f32_32x32x16_bf16 v[48:63], v[164:167], v[208:211], v[48:63]
	ds_read_b128 v[208:211], v151 offset:32
	s_waitcnt lgkmcnt(5)
	v_mfma_f32_32x32x16_bf16 v[0:15], v[160:163], v[212:215], v[0:15]
	v_mfma_f32_32x32x16_bf16 v[16:31], v[164:167], v[212:215], v[16:31]
	ds_read_b128 v[212:215], v151 offset:4640
	global_load_dwordx4 v[160:163], v[140:141], off offset:3072
	global_load_dwordx4 v[164:167], v[142:143], off offset:3072
	s_waitcnt lgkmcnt(1)
	v_mfma_f32_32x32x16_bf16 v[96:111], v[184:187], v[208:211], v[96:111]
	v_mfma_f32_32x32x16_bf16 v[112:127], v[188:191], v[208:211], v[112:127]
	s_waitcnt lgkmcnt(0)
	v_mfma_f32_32x32x16_bf16 v[64:79], v[184:187], v[212:215], v[64:79]
	v_mfma_f32_32x32x16_bf16 v[80:95], v[188:191], v[212:215], v[80:95]
	ds_read_b128 v[208:211], v151 offset:9248
	ds_read_b128 v[212:215], v151 offset:13856
	s_waitcnt vmcnt(7)
	ds_write_b128 v154, v[194:197]
	s_waitcnt vmcnt(6)
	ds_write_b128 v153, v[198:201]
	ds_read_b128 v[194:197], v152 offset:36928
	ds_read_b128 v[198:201], v152 offset:41536
	s_waitcnt lgkmcnt(5)
	v_mfma_f32_32x32x16_bf16 v[32:47], v[184:187], v[208:211], v[32:47]
	v_mfma_f32_32x32x16_bf16 v[48:63], v[188:191], v[208:211], v[48:63]
	ds_read_b128 v[208:211], v151 offset:64
	s_waitcnt lgkmcnt(5)
	v_mfma_f32_32x32x16_bf16 v[0:15], v[184:187], v[212:215], v[0:15]
	v_mfma_f32_32x32x16_bf16 v[16:31], v[188:191], v[212:215], v[16:31]
	ds_read_b128 v[212:215], v151 offset:4672
	global_load_dwordx4 v[184:187], v[132:133], off offset:3072
	global_load_dwordx4 v[188:191], v[134:135], off offset:3072
	s_waitcnt lgkmcnt(1)
	v_mfma_f32_32x32x16_bf16 v[96:111], v[194:197], v[208:211], v[96:111]
	v_mfma_f32_32x32x16_bf16 v[112:127], v[198:201], v[208:211], v[112:127]
	s_waitcnt lgkmcnt(0)
	v_mfma_f32_32x32x16_bf16 v[64:79], v[194:197], v[212:215], v[64:79]
	v_mfma_f32_32x32x16_bf16 v[80:95], v[198:201], v[212:215], v[80:95]
	ds_read_b128 v[208:211], v151 offset:9280
	ds_read_b128 v[212:215], v151 offset:13888
	s_waitcnt vmcnt(7)
	ds_write_b128 v156, v[176:179]
	s_waitcnt vmcnt(6)
	ds_write_b128 v155, v[180:183]
	ds_read_b128 v[176:179], v152 offset:36960
	ds_read_b128 v[180:183], v152 offset:41568
	s_waitcnt lgkmcnt(5)
	v_mfma_f32_32x32x16_bf16 v[32:47], v[194:197], v[208:211], v[32:47]
	v_mfma_f32_32x32x16_bf16 v[48:63], v[198:201], v[208:211], v[48:63]
	ds_read_b128 v[208:211], v151 offset:96
	s_waitcnt lgkmcnt(5)
	v_mfma_f32_32x32x16_bf16 v[0:15], v[194:197], v[212:215], v[0:15]
	v_mfma_f32_32x32x16_bf16 v[16:31], v[198:201], v[212:215], v[16:31]
	ds_read_b128 v[212:215], v151 offset:4704
	global_load_dwordx4 v[194:197], v[144:145], off offset:3072
	global_load_dwordx4 v[198:201], v[146:147], off offset:3072
	s_waitcnt lgkmcnt(1)
	v_mfma_f32_32x32x16_bf16 v[96:111], v[176:179], v[208:211], v[96:111]
	v_mfma_f32_32x32x16_bf16 v[112:127], v[180:183], v[208:211], v[112:127]
	s_waitcnt lgkmcnt(0)
	v_mfma_f32_32x32x16_bf16 v[64:79], v[176:179], v[212:215], v[64:79]
	v_mfma_f32_32x32x16_bf16 v[80:95], v[180:183], v[212:215], v[80:95]
	ds_read_b128 v[208:211], v151 offset:9312
	ds_read_b128 v[212:215], v151 offset:13920
	s_waitcnt lgkmcnt(1)
	v_mfma_f32_32x32x16_bf16 v[32:47], v[176:179], v[208:211], v[32:47]
	v_mfma_f32_32x32x16_bf16 v[48:63], v[180:183], v[208:211], v[48:63]
	s_waitcnt lgkmcnt(0)
	v_mfma_f32_32x32x16_bf16 v[0:15], v[176:179], v[212:215], v[0:15]
	v_mfma_f32_32x32x16_bf16 v[16:31], v[180:183], v[212:215], v[16:31]
	s_setprio 0
	s_barrier
; template <bool trans>
; DI void gemm_core(const GTile& tl, const GTile& nx, bool has_next  , bool chain  , bool pre, u32x4 (&ra)[4], u32x4 (&rb)[4], char* smem, f32x16 (&acc)[2][4]) {
;     ...
;   const int nk = K / 64;
;   if (!pre) { G_LOAD(0); G_STORE(0); G_LOAD(1); }
;   for (int kt = 0; kt < nk; ++kt) {
;     __syncthreads();
;     G_COMPUTE(kt & 1, kt);
;   }
	global_load_dwordx4 v[176:179], v[136:137], off offset:3200
	global_load_dwordx4 v[180:183], v[138:139], off offset:3200
	s_waitcnt vmcnt(9)
	ds_write_b128 v148, v[168:171]
	s_waitcnt vmcnt(8)
	ds_write_b128 v148, v[172:175] offset:36864
	ds_read_b128 v[168:171], v150
	ds_read_b128 v[172:175], v150 offset:4608
	ds_read_b128 v[208:211], v149
	ds_read_b128 v[212:215], v149 offset:4608
	s_setprio 1
	s_waitcnt lgkmcnt(1)
	v_mfma_f32_32x32x16_bf16 v[96:111], v[168:171], v[208:211], v[96:111]
	v_mfma_f32_32x32x16_bf16 v[112:127], v[172:175], v[208:211], v[112:127]
	s_waitcnt lgkmcnt(0)
	v_mfma_f32_32x32x16_bf16 v[64:79], v[168:171], v[212:215], v[64:79]
	v_mfma_f32_32x32x16_bf16 v[80:95], v[172:175], v[212:215], v[80:95]
	ds_read_b128 v[208:211], v149 offset:9216
	ds_read_b128 v[212:215], v149 offset:13824
	s_waitcnt vmcnt(7)
	ds_write_b128 v148, v[160:163] offset:9216
	s_waitcnt vmcnt(6)
	ds_write_b128 v148, v[164:167] offset:46080
	ds_read_b128 v[160:163], v150 offset:32
	ds_read_b128 v[164:167], v150 offset:4640
	s_waitcnt lgkmcnt(5)
	v_mfma_f32_32x32x16_bf16 v[32:47], v[168:171], v[208:211], v[32:47]
	v_mfma_f32_32x32x16_bf16 v[48:63], v[172:175], v[208:211], v[48:63]
	ds_read_b128 v[208:211], v149 offset:32
	s_waitcnt lgkmcnt(5)
	v_mfma_f32_32x32x16_bf16 v[0:15], v[168:171], v[212:215], v[0:15]
	v_mfma_f32_32x32x16_bf16 v[16:31], v[172:175], v[212:215], v[16:31]
	ds_read_b128 v[212:215], v149 offset:4640
	global_load_dwordx4 v[168:171], v[140:141], off offset:3200
	global_load_dwordx4 v[172:175], v[142:143], off offset:3200
	s_waitcnt lgkmcnt(1)
	v_mfma_f32_32x32x16_bf16 v[96:111], v[160:163], v[208:211], v[96:111]
	v_mfma_f32_32x32x16_bf16 v[112:127], v[164:167], v[208:211], v[112:127]
	s_waitcnt lgkmcnt(0)
	v_mfma_f32_32x32x16_bf16 v[64:79], v[160:163], v[212:215], v[64:79]
	v_mfma_f32_32x32x16_bf16 v[80:95], v[164:167], v[212:215], v[80:95]
	ds_read_b128 v[208:211], v149 offset:9248
	ds_read_b128 v[212:215], v149 offset:13856
	s_waitcnt vmcnt(7)
	ds_write_b128 v148, v[184:187] offset:18432
	s_waitcnt vmcnt(6)
	ds_write_b128 v148, v[188:191] offset:55296
	ds_read_b128 v[184:187], v150 offset:64
	ds_read_b128 v[188:191], v150 offset:4672
	s_waitcnt lgkmcnt(5)
	v_mfma_f32_32x32x16_bf16 v[32:47], v[160:163], v[208:211], v[32:47]
	v_mfma_f32_32x32x16_bf16 v[48:63], v[164:167], v[208:211], v[48:63]
	ds_read_b128 v[208:211], v149 offset:64
	s_waitcnt lgkmcnt(5)
	v_mfma_f32_32x32x16_bf16 v[0:15], v[160:163], v[212:215], v[0:15]
	v_mfma_f32_32x32x16_bf16 v[16:31], v[164:167], v[212:215], v[16:31]
	ds_read_b128 v[212:215], v149 offset:4672
	global_load_dwordx4 v[160:163], v[132:133], off offset:3200
	global_load_dwordx4 v[164:167], v[134:135], off offset:3200
	s_waitcnt lgkmcnt(1)
	v_mfma_f32_32x32x16_bf16 v[96:111], v[184:187], v[208:211], v[96:111]
	v_mfma_f32_32x32x16_bf16 v[112:127], v[188:191], v[208:211], v[112:127]
	s_waitcnt lgkmcnt(0)
	v_mfma_f32_32x32x16_bf16 v[64:79], v[184:187], v[212:215], v[64:79]
	v_mfma_f32_32x32x16_bf16 v[80:95], v[188:191], v[212:215], v[80:95]
	ds_read_b128 v[208:211], v149 offset:9280
	ds_read_b128 v[212:215], v149 offset:13888
	s_waitcnt vmcnt(7)
	ds_write_b128 v148, v[194:197] offset:27648
	s_waitcnt vmcnt(6)
	ds_write_b128 v148, v[198:201] offset:64512
	ds_read_b128 v[194:197], v150 offset:96
	ds_read_b128 v[198:201], v150 offset:4704
	s_waitcnt lgkmcnt(5)
	v_mfma_f32_32x32x16_bf16 v[32:47], v[184:187], v[208:211], v[32:47]
	v_mfma_f32_32x32x16_bf16 v[48:63], v[188:191], v[208:211], v[48:63]
	ds_read_b128 v[208:211], v149 offset:96
	s_waitcnt lgkmcnt(5)
	v_mfma_f32_32x32x16_bf16 v[0:15], v[184:187], v[212:215], v[0:15]
	v_mfma_f32_32x32x16_bf16 v[16:31], v[188:191], v[212:215], v[16:31]
	ds_read_b128 v[212:215], v149 offset:4704
	global_load_dwordx4 v[184:187], v[144:145], off offset:3200
	global_load_dwordx4 v[188:191], v[146:147], off offset:3200
	s_waitcnt lgkmcnt(1)
	v_mfma_f32_32x32x16_bf16 v[96:111], v[194:197], v[208:211], v[96:111]
	v_mfma_f32_32x32x16_bf16 v[112:127], v[198:201], v[208:211], v[112:127]
	s_waitcnt lgkmcnt(0)
	v_mfma_f32_32x32x16_bf16 v[64:79], v[194:197], v[212:215], v[64:79]
	v_mfma_f32_32x32x16_bf16 v[80:95], v[198:201], v[212:215], v[80:95]
	ds_read_b128 v[208:211], v149 offset:9312
	ds_read_b128 v[212:215], v149 offset:13920
	s_waitcnt lgkmcnt(1)
	v_mfma_f32_32x32x16_bf16 v[32:47], v[194:197], v[208:211], v[32:47]
	v_mfma_f32_32x32x16_bf16 v[48:63], v[198:201], v[208:211], v[48:63]
	s_waitcnt lgkmcnt(0)
	v_mfma_f32_32x32x16_bf16 v[0:15], v[194:197], v[212:215], v[0:15]
	v_mfma_f32_32x32x16_bf16 v[16:31], v[198:201], v[212:215], v[16:31]
	s_setprio 0
	s_barrier
; template <bool trans>
; DI void gemm_core(const GTile& tl, const GTile& nx, bool has_next  , bool chain  , bool pre, u32x4 (&ra)[4], u32x4 (&rb)[4], char* smem, f32x16 (&acc)[2][4]) {
;     ...
;   const int nk = K / 64;
;   if (!pre) { G_LOAD(0); G_STORE(0); G_LOAD(1); }
;   for (int kt = 0; kt < nk; ++kt) {
;     __syncthreads();
;     G_COMPUTE(kt & 1, kt);
;   }
	global_load_dwordx4 v[194:197], v[136:137], off offset:3328
	global_load_dwordx4 v[198:201], v[138:139], off offset:3328
	s_waitcnt vmcnt(9)
	ds_write_b128 v192, v[176:179]
	s_waitcnt vmcnt(8)
	ds_write_b128 v159, v[180:183]
	ds_read_b128 v[176:179], v152 offset:36864
	ds_read_b128 v[180:183], v152 offset:41472
	ds_read_b128 v[208:211], v151
	ds_read_b128 v[212:215], v151 offset:4608
	s_setprio 1
	s_waitcnt lgkmcnt(1)
	v_mfma_f32_32x32x16_bf16 v[96:111], v[176:179], v[208:211], v[96:111]
	v_mfma_f32_32x32x16_bf16 v[112:127], v[180:183], v[208:211], v[112:127]
	s_waitcnt lgkmcnt(0)
	v_mfma_f32_32x32x16_bf16 v[64:79], v[176:179], v[212:215], v[64:79]
	v_mfma_f32_32x32x16_bf16 v[80:95], v[180:183], v[212:215], v[80:95]
	ds_read_b128 v[208:211], v151 offset:9216
	ds_read_b128 v[212:215], v151 offset:13824
	s_waitcnt vmcnt(7)
	ds_write_b128 v158, v[168:171]
	s_waitcnt vmcnt(6)
	ds_write_b128 v157, v[172:175]
	ds_read_b128 v[168:171], v152 offset:36896
	ds_read_b128 v[172:175], v152 offset:41504
	s_waitcnt lgkmcnt(5)
	v_mfma_f32_32x32x16_bf16 v[32:47], v[176:179], v[208:211], v[32:47]
	v_mfma_f32_32x32x16_bf16 v[48:63], v[180:183], v[208:211], v[48:63]
	ds_read_b128 v[208:211], v151 offset:32
	s_waitcnt lgkmcnt(5)
	v_mfma_f32_32x32x16_bf16 v[0:15], v[176:179], v[212:215], v[0:15]
	v_mfma_f32_32x32x16_bf16 v[16:31], v[180:183], v[212:215], v[16:31]
	ds_read_b128 v[212:215], v151 offset:4640
	global_load_dwordx4 v[176:179], v[140:141], off offset:3328
	global_load_dwordx4 v[180:183], v[142:143], off offset:3328
	s_waitcnt lgkmcnt(1)
	v_mfma_f32_32x32x16_bf16 v[96:111], v[168:171], v[208:211], v[96:111]
	v_mfma_f32_32x32x16_bf16 v[112:127], v[172:175], v[208:211], v[112:127]
	s_waitcnt lgkmcnt(0)
	v_mfma_f32_32x32x16_bf16 v[64:79], v[168:171], v[212:215], v[64:79]
	v_mfma_f32_32x32x16_bf16 v[80:95], v[172:175], v[212:215], v[80:95]
	ds_read_b128 v[208:211], v151 offset:9248
	ds_read_b128 v[212:215], v151 offset:13856
	s_waitcnt vmcnt(7)
	ds_write_b128 v154, v[160:163]
	s_waitcnt vmcnt(6)
	ds_write_b128 v153, v[164:167]
	ds_read_b128 v[160:163], v152 offset:36928
	ds_read_b128 v[164:167], v152 offset:41536
	s_waitcnt lgkmcnt(5)
	v_mfma_f32_32x32x16_bf16 v[32:47], v[168:171], v[208:211], v[32:47]
	v_mfma_f32_32x32x16_bf16 v[48:63], v[172:175], v[208:211], v[48:63]
	ds_read_b128 v[208:211], v151 offset:64
	s_waitcnt lgkmcnt(5)
	v_mfma_f32_32x32x16_bf16 v[0:15], v[168:171], v[212:215], v[0:15]
	v_mfma_f32_32x32x16_bf16 v[16:31], v[172:175], v[212:215], v[16:31]
	ds_read_b128 v[212:215], v151 offset:4672
	global_load_dwordx4 v[168:171], v[132:133], off offset:3328
	global_load_dwordx4 v[172:175], v[134:135], off offset:3328
	s_waitcnt lgkmcnt(1)
	v_mfma_f32_32x32x16_bf16 v[96:111], v[160:163], v[208:211], v[96:111]
	v_mfma_f32_32x32x16_bf16 v[112:127], v[164:167], v[208:211], v[112:127]
	s_waitcnt lgkmcnt(0)
	v_mfma_f32_32x32x16_bf16 v[64:79], v[160:163], v[212:215], v[64:79]
	v_mfma_f32_32x32x16_bf16 v[80:95], v[164:167], v[212:215], v[80:95]
	ds_read_b128 v[208:211], v151 offset:9280
	ds_read_b128 v[212:215], v151 offset:13888
	s_waitcnt vmcnt(7)
	ds_write_b128 v156, v[184:187]
	s_waitcnt vmcnt(6)
	ds_write_b128 v155, v[188:191]
	ds_read_b128 v[184:187], v152 offset:36960
	ds_read_b128 v[188:191], v152 offset:41568
	s_waitcnt lgkmcnt(5)
	v_mfma_f32_32x32x16_bf16 v[32:47], v[160:163], v[208:211], v[32:47]
	v_mfma_f32_32x32x16_bf16 v[48:63], v[164:167], v[208:211], v[48:63]
	ds_read_b128 v[208:211], v151 offset:96
	s_waitcnt lgkmcnt(5)
	v_mfma_f32_32x32x16_bf16 v[0:15], v[160:163], v[212:215], v[0:15]
	v_mfma_f32_32x32x16_bf16 v[16:31], v[164:167], v[212:215], v[16:31]
	ds_read_b128 v[212:215], v151 offset:4704
	global_load_dwordx4 v[160:163], v[144:145], off offset:3328
	global_load_dwordx4 v[164:167], v[146:147], off offset:3328
	s_waitcnt lgkmcnt(1)
	v_mfma_f32_32x32x16_bf16 v[96:111], v[184:187], v[208:211], v[96:111]
	v_mfma_f32_32x32x16_bf16 v[112:127], v[188:191], v[208:211], v[112:127]
	s_waitcnt lgkmcnt(0)
	v_mfma_f32_32x32x16_bf16 v[64:79], v[184:187], v[212:215], v[64:79]
	v_mfma_f32_32x32x16_bf16 v[80:95], v[188:191], v[212:215], v[80:95]
	ds_read_b128 v[208:211], v151 offset:9312
	ds_read_b128 v[212:215], v151 offset:13920
	s_waitcnt lgkmcnt(1)
	v_mfma_f32_32x32x16_bf16 v[32:47], v[184:187], v[208:211], v[32:47]
	v_mfma_f32_32x32x16_bf16 v[48:63], v[188:191], v[208:211], v[48:63]
	s_waitcnt lgkmcnt(0)
	v_mfma_f32_32x32x16_bf16 v[0:15], v[184:187], v[212:215], v[0:15]
	v_mfma_f32_32x32x16_bf16 v[16:31], v[188:191], v[212:215], v[16:31]
	s_setprio 0
	s_barrier
; template <bool trans>
; DI void gemm_core(const GTile& tl, const GTile& nx, bool has_next  , bool chain  , bool pre, u32x4 (&ra)[4], u32x4 (&rb)[4], char* smem, f32x16 (&acc)[2][4]) {
;     ...
;   const int nk = K / 64;
;   if (!pre) { G_LOAD(0); G_STORE(0); G_LOAD(1); }
;   for (int kt = 0; kt < nk; ++kt) {
;     __syncthreads();
;     G_COMPUTE(kt & 1, kt);
;   }
	global_load_dwordx4 v[184:187], v[136:137], off offset:3456
	global_load_dwordx4 v[188:191], v[138:139], off offset:3456
	s_waitcnt vmcnt(9)
	ds_write_b128 v148, v[194:197]
	s_waitcnt vmcnt(8)
	ds_write_b128 v148, v[198:201] offset:36864
	ds_read_b128 v[194:197], v150
	ds_read_b128 v[198:201], v150 offset:4608
	ds_read_b128 v[208:211], v149
	ds_read_b128 v[212:215], v149 offset:4608
	s_setprio 1
	s_waitcnt lgkmcnt(1)
	v_mfma_f32_32x32x16_bf16 v[96:111], v[194:197], v[208:211], v[96:111]
	v_mfma_f32_32x32x16_bf16 v[112:127], v[198:201], v[208:211], v[112:127]
	s_waitcnt lgkmcnt(0)
	v_mfma_f32_32x32x16_bf16 v[64:79], v[194:197], v[212:215], v[64:79]
	v_mfma_f32_32x32x16_bf16 v[80:95], v[198:201], v[212:215], v[80:95]
	ds_read_b128 v[208:211], v149 offset:9216
	ds_read_b128 v[212:215], v149 offset:13824
	s_waitcnt vmcnt(7)
	ds_write_b128 v148, v[176:179] offset:9216
	s_waitcnt vmcnt(6)
	ds_write_b128 v148, v[180:183] offset:46080
	ds_read_b128 v[176:179], v150 offset:32
	ds_read_b128 v[180:183], v150 offset:4640
	s_waitcnt lgkmcnt(5)
	v_mfma_f32_32x32x16_bf16 v[32:47], v[194:197], v[208:211], v[32:47]
	v_mfma_f32_32x32x16_bf16 v[48:63], v[198:201], v[208:211], v[48:63]
	ds_read_b128 v[208:211], v149 offset:32
	s_waitcnt lgkmcnt(5)
	v_mfma_f32_32x32x16_bf16 v[0:15], v[194:197], v[212:215], v[0:15]
	v_mfma_f32_32x32x16_bf16 v[16:31], v[198:201], v[212:215], v[16:31]
	ds_read_b128 v[212:215], v149 offset:4640
	global_load_dwordx4 v[194:197], v[140:141], off offset:3456
	global_load_dwordx4 v[198:201], v[142:143], off offset:3456
	s_waitcnt lgkmcnt(1)
	v_mfma_f32_32x32x16_bf16 v[96:111], v[176:179], v[208:211], v[96:111]
	v_mfma_f32_32x32x16_bf16 v[112:127], v[180:183], v[208:211], v[112:127]
	s_waitcnt lgkmcnt(0)
	v_mfma_f32_32x32x16_bf16 v[64:79], v[176:179], v[212:215], v[64:79]
	v_mfma_f32_32x32x16_bf16 v[80:95], v[180:183], v[212:215], v[80:95]
	ds_read_b128 v[208:211], v149 offset:9248
	ds_read_b128 v[212:215], v149 offset:13856
	s_waitcnt vmcnt(7)
	ds_write_b128 v148, v[168:171] offset:18432
	s_waitcnt vmcnt(6)
	ds_write_b128 v148, v[172:175] offset:55296
	ds_read_b128 v[168:171], v150 offset:64
	ds_read_b128 v[172:175], v150 offset:4672
	s_waitcnt lgkmcnt(5)
	v_mfma_f32_32x32x16_bf16 v[32:47], v[176:179], v[208:211], v[32:47]
	v_mfma_f32_32x32x16_bf16 v[48:63], v[180:183], v[208:211], v[48:63]
	ds_read_b128 v[208:211], v149 offset:64
	s_waitcnt lgkmcnt(5)
	v_mfma_f32_32x32x16_bf16 v[0:15], v[176:179], v[212:215], v[0:15]
	v_mfma_f32_32x32x16_bf16 v[16:31], v[180:183], v[212:215], v[16:31]
	ds_read_b128 v[212:215], v149 offset:4672
	global_load_dwordx4 v[176:179], v[132:133], off offset:3456
	global_load_dwordx4 v[180:183], v[134:135], off offset:3456
	s_waitcnt lgkmcnt(1)
	v_mfma_f32_32x32x16_bf16 v[96:111], v[168:171], v[208:211], v[96:111]
	v_mfma_f32_32x32x16_bf16 v[112:127], v[172:175], v[208:211], v[112:127]
	s_waitcnt lgkmcnt(0)
	v_mfma_f32_32x32x16_bf16 v[64:79], v[168:171], v[212:215], v[64:79]
	v_mfma_f32_32x32x16_bf16 v[80:95], v[172:175], v[212:215], v[80:95]
	ds_read_b128 v[208:211], v149 offset:9280
	ds_read_b128 v[212:215], v149 offset:13888
	s_waitcnt vmcnt(7)
	ds_write_b128 v148, v[160:163] offset:27648
	s_waitcnt vmcnt(6)
	ds_write_b128 v148, v[164:167] offset:64512
	ds_read_b128 v[160:163], v150 offset:96
	ds_read_b128 v[164:167], v150 offset:4704
	s_waitcnt lgkmcnt(5)
	v_mfma_f32_32x32x16_bf16 v[32:47], v[168:171], v[208:211], v[32:47]
	v_mfma_f32_32x32x16_bf16 v[48:63], v[172:175], v[208:211], v[48:63]
	ds_read_b128 v[208:211], v149 offset:96
	s_waitcnt lgkmcnt(5)
	v_mfma_f32_32x32x16_bf16 v[0:15], v[168:171], v[212:215], v[0:15]
	v_mfma_f32_32x32x16_bf16 v[16:31], v[172:175], v[212:215], v[16:31]
	ds_read_b128 v[212:215], v149 offset:4704
	global_load_dwordx4 v[168:171], v[144:145], off offset:3456
	global_load_dwordx4 v[172:175], v[146:147], off offset:3456
	s_waitcnt lgkmcnt(1)
	v_mfma_f32_32x32x16_bf16 v[96:111], v[160:163], v[208:211], v[96:111]
	v_mfma_f32_32x32x16_bf16 v[112:127], v[164:167], v[208:211], v[112:127]
	s_waitcnt lgkmcnt(0)
	v_mfma_f32_32x32x16_bf16 v[64:79], v[160:163], v[212:215], v[64:79]
	v_mfma_f32_32x32x16_bf16 v[80:95], v[164:167], v[212:215], v[80:95]
	ds_read_b128 v[208:211], v149 offset:9312
	ds_read_b128 v[212:215], v149 offset:13920
	s_waitcnt lgkmcnt(1)
	v_mfma_f32_32x32x16_bf16 v[32:47], v[160:163], v[208:211], v[32:47]
	v_mfma_f32_32x32x16_bf16 v[48:63], v[164:167], v[208:211], v[48:63]
	s_waitcnt lgkmcnt(0)
	v_mfma_f32_32x32x16_bf16 v[0:15], v[160:163], v[212:215], v[0:15]
	v_mfma_f32_32x32x16_bf16 v[16:31], v[164:167], v[212:215], v[16:31]
	s_setprio 0
	s_barrier
; template <bool trans>
; DI void gemm_core(const GTile& tl, const GTile& nx, bool has_next  , bool chain  , bool pre, u32x4 (&ra)[4], u32x4 (&rb)[4], char* smem, f32x16 (&acc)[2][4]) {
;     ...
;   const int nk = K / 64;
;   if (!pre) { G_LOAD(0); G_STORE(0); G_LOAD(1); }
;   for (int kt = 0; kt < nk; ++kt) {
;     __syncthreads();
;     G_COMPUTE(kt & 1, kt);
;   }
	global_load_dwordx4 v[160:163], v[136:137], off offset:3584
	global_load_dwordx4 v[164:167], v[138:139], off offset:3584
	s_waitcnt vmcnt(9)
	ds_write_b128 v192, v[184:187]
	s_waitcnt vmcnt(8)
	ds_write_b128 v159, v[188:191]
	ds_read_b128 v[184:187], v152 offset:36864
	ds_read_b128 v[188:191], v152 offset:41472
	ds_read_b128 v[208:211], v151
	ds_read_b128 v[212:215], v151 offset:4608
	s_setprio 1
	s_waitcnt lgkmcnt(1)
	v_mfma_f32_32x32x16_bf16 v[96:111], v[184:187], v[208:211], v[96:111]
	v_mfma_f32_32x32x16_bf16 v[112:127], v[188:191], v[208:211], v[112:127]
	s_waitcnt lgkmcnt(0)
	v_mfma_f32_32x32x16_bf16 v[64:79], v[184:187], v[212:215], v[64:79]
	v_mfma_f32_32x32x16_bf16 v[80:95], v[188:191], v[212:215], v[80:95]
	ds_read_b128 v[208:211], v151 offset:9216
	ds_read_b128 v[212:215], v151 offset:13824
	s_waitcnt vmcnt(7)
	ds_write_b128 v158, v[194:197]
	s_waitcnt vmcnt(6)
	ds_write_b128 v157, v[198:201]
	ds_read_b128 v[194:197], v152 offset:36896
	ds_read_b128 v[198:201], v152 offset:41504
	s_waitcnt lgkmcnt(5)
	v_mfma_f32_32x32x16_bf16 v[32:47], v[184:187], v[208:211], v[32:47]
	v_mfma_f32_32x32x16_bf16 v[48:63], v[188:191], v[208:211], v[48:63]
	ds_read_b128 v[208:211], v151 offset:32
	s_waitcnt lgkmcnt(5)
	v_mfma_f32_32x32x16_bf16 v[0:15], v[184:187], v[212:215], v[0:15]
	v_mfma_f32_32x32x16_bf16 v[16:31], v[188:191], v[212:215], v[16:31]
	ds_read_b128 v[212:215], v151 offset:4640
	global_load_dwordx4 v[184:187], v[140:141], off offset:3584
	global_load_dwordx4 v[188:191], v[142:143], off offset:3584
	s_waitcnt lgkmcnt(1)
	v_mfma_f32_32x32x16_bf16 v[96:111], v[194:197], v[208:211], v[96:111]
	v_mfma_f32_32x32x16_bf16 v[112:127], v[198:201], v[208:211], v[112:127]
	s_waitcnt lgkmcnt(0)
	v_mfma_f32_32x32x16_bf16 v[64:79], v[194:197], v[212:215], v[64:79]
	v_mfma_f32_32x32x16_bf16 v[80:95], v[198:201], v[212:215], v[80:95]
	ds_read_b128 v[208:211], v151 offset:9248
	ds_read_b128 v[212:215], v151 offset:13856
	s_waitcnt vmcnt(7)
	ds_write_b128 v154, v[176:179]
	s_waitcnt vmcnt(6)
	ds_write_b128 v153, v[180:183]
	ds_read_b128 v[176:179], v152 offset:36928
	ds_read_b128 v[180:183], v152 offset:41536
	s_waitcnt lgkmcnt(5)
	v_mfma_f32_32x32x16_bf16 v[32:47], v[194:197], v[208:211], v[32:47]
	v_mfma_f32_32x32x16_bf16 v[48:63], v[198:201], v[208:211], v[48:63]
	ds_read_b128 v[208:211], v151 offset:64
	s_waitcnt lgkmcnt(5)
	v_mfma_f32_32x32x16_bf16 v[0:15], v[194:197], v[212:215], v[0:15]
	v_mfma_f32_32x32x16_bf16 v[16:31], v[198:201], v[212:215], v[16:31]
	ds_read_b128 v[212:215], v151 offset:4672
	global_load_dwordx4 v[194:197], v[132:133], off offset:3584
	global_load_dwordx4 v[198:201], v[134:135], off offset:3584
	s_waitcnt lgkmcnt(1)
	v_mfma_f32_32x32x16_bf16 v[96:111], v[176:179], v[208:211], v[96:111]
	v_mfma_f32_32x32x16_bf16 v[112:127], v[180:183], v[208:211], v[112:127]
	s_waitcnt lgkmcnt(0)
	v_mfma_f32_32x32x16_bf16 v[64:79], v[176:179], v[212:215], v[64:79]
	v_mfma_f32_32x32x16_bf16 v[80:95], v[180:183], v[212:215], v[80:95]
	ds_read_b128 v[208:211], v151 offset:9280
	ds_read_b128 v[212:215], v151 offset:13888
	s_waitcnt vmcnt(7)
	ds_write_b128 v156, v[168:171]
	s_waitcnt vmcnt(6)
	ds_write_b128 v155, v[172:175]
	ds_read_b128 v[168:171], v152 offset:36960
	ds_read_b128 v[172:175], v152 offset:41568
	s_waitcnt lgkmcnt(5)
	v_mfma_f32_32x32x16_bf16 v[32:47], v[176:179], v[208:211], v[32:47]
	v_mfma_f32_32x32x16_bf16 v[48:63], v[180:183], v[208:211], v[48:63]
	ds_read_b128 v[208:211], v151 offset:96
	s_waitcnt lgkmcnt(5)
	v_mfma_f32_32x32x16_bf16 v[0:15], v[176:179], v[212:215], v[0:15]
	v_mfma_f32_32x32x16_bf16 v[16:31], v[180:183], v[212:215], v[16:31]
	ds_read_b128 v[212:215], v151 offset:4704
	global_load_dwordx4 v[176:179], v[144:145], off offset:3584
	global_load_dwordx4 v[180:183], v[146:147], off offset:3584
	s_waitcnt lgkmcnt(1)
	v_mfma_f32_32x32x16_bf16 v[96:111], v[168:171], v[208:211], v[96:111]
	v_mfma_f32_32x32x16_bf16 v[112:127], v[172:175], v[208:211], v[112:127]
	s_waitcnt lgkmcnt(0)
	v_mfma_f32_32x32x16_bf16 v[64:79], v[168:171], v[212:215], v[64:79]
	v_mfma_f32_32x32x16_bf16 v[80:95], v[172:175], v[212:215], v[80:95]
	ds_read_b128 v[208:211], v151 offset:9312
	ds_read_b128 v[212:215], v151 offset:13920
	s_waitcnt lgkmcnt(1)
	v_mfma_f32_32x32x16_bf16 v[32:47], v[168:171], v[208:211], v[32:47]
	v_mfma_f32_32x32x16_bf16 v[48:63], v[172:175], v[208:211], v[48:63]
	s_waitcnt lgkmcnt(0)
	v_mfma_f32_32x32x16_bf16 v[0:15], v[168:171], v[212:215], v[0:15]
	v_mfma_f32_32x32x16_bf16 v[16:31], v[172:175], v[212:215], v[16:31]
	s_setprio 0
	s_barrier
; template <bool trans>
; DI void gemm_core(const GTile& tl, const GTile& nx, bool has_next  , bool chain  , bool pre, u32x4 (&ra)[4], u32x4 (&rb)[4], char* smem, f32x16 (&acc)[2][4]) {
;     ...
;   const int nk = K / 64;
;   if (!pre) { G_LOAD(0); G_STORE(0); G_LOAD(1); }
;   for (int kt = 0; kt < nk; ++kt) {
;     __syncthreads();
;     G_COMPUTE(kt & 1, kt);
;   }
	global_load_dwordx4 v[168:171], v[136:137], off offset:3712
	global_load_dwordx4 v[172:175], v[138:139], off offset:3712
	s_waitcnt vmcnt(9)
	ds_write_b128 v148, v[160:163]
	s_waitcnt vmcnt(8)
	ds_write_b128 v148, v[164:167] offset:36864
	ds_read_b128 v[160:163], v150
	ds_read_b128 v[164:167], v150 offset:4608
	ds_read_b128 v[208:211], v149
	ds_read_b128 v[212:215], v149 offset:4608
	s_setprio 1
	s_waitcnt lgkmcnt(1)
	v_mfma_f32_32x32x16_bf16 v[96:111], v[160:163], v[208:211], v[96:111]
	v_mfma_f32_32x32x16_bf16 v[112:127], v[164:167], v[208:211], v[112:127]
	s_waitcnt lgkmcnt(0)
	v_mfma_f32_32x32x16_bf16 v[64:79], v[160:163], v[212:215], v[64:79]
	v_mfma_f32_32x32x16_bf16 v[80:95], v[164:167], v[212:215], v[80:95]
	ds_read_b128 v[208:211], v149 offset:9216
	ds_read_b128 v[212:215], v149 offset:13824
	s_waitcnt vmcnt(7)
	ds_write_b128 v148, v[184:187] offset:9216
	s_waitcnt vmcnt(6)
	ds_write_b128 v148, v[188:191] offset:46080
	ds_read_b128 v[184:187], v150 offset:32
	ds_read_b128 v[188:191], v150 offset:4640
	s_waitcnt lgkmcnt(5)
	v_mfma_f32_32x32x16_bf16 v[32:47], v[160:163], v[208:211], v[32:47]
	v_mfma_f32_32x32x16_bf16 v[48:63], v[164:167], v[208:211], v[48:63]
	ds_read_b128 v[208:211], v149 offset:32
	s_waitcnt lgkmcnt(5)
	v_mfma_f32_32x32x16_bf16 v[0:15], v[160:163], v[212:215], v[0:15]
	v_mfma_f32_32x32x16_bf16 v[16:31], v[164:167], v[212:215], v[16:31]
	ds_read_b128 v[212:215], v149 offset:4640
	global_load_dwordx4 v[160:163], v[140:141], off offset:3712
	global_load_dwordx4 v[164:167], v[142:143], off offset:3712
	s_waitcnt lgkmcnt(1)
	v_mfma_f32_32x32x16_bf16 v[96:111], v[184:187], v[208:211], v[96:111]
	v_mfma_f32_32x32x16_bf16 v[112:127], v[188:191], v[208:211], v[112:127]
	s_waitcnt lgkmcnt(0)
	v_mfma_f32_32x32x16_bf16 v[64:79], v[184:187], v[212:215], v[64:79]
	v_mfma_f32_32x32x16_bf16 v[80:95], v[188:191], v[212:215], v[80:95]
	ds_read_b128 v[208:211], v149 offset:9248
	ds_read_b128 v[212:215], v149 offset:13856
	s_waitcnt vmcnt(7)
	ds_write_b128 v148, v[194:197] offset:18432
	s_waitcnt vmcnt(6)
	ds_write_b128 v148, v[198:201] offset:55296
	ds_read_b128 v[194:197], v150 offset:64
	ds_read_b128 v[198:201], v150 offset:4672
	s_waitcnt lgkmcnt(5)
	v_mfma_f32_32x32x16_bf16 v[32:47], v[184:187], v[208:211], v[32:47]
	v_mfma_f32_32x32x16_bf16 v[48:63], v[188:191], v[208:211], v[48:63]
	ds_read_b128 v[208:211], v149 offset:64
	s_waitcnt lgkmcnt(5)
	v_mfma_f32_32x32x16_bf16 v[0:15], v[184:187], v[212:215], v[0:15]
	v_mfma_f32_32x32x16_bf16 v[16:31], v[188:191], v[212:215], v[16:31]
	ds_read_b128 v[212:215], v149 offset:4672
	global_load_dwordx4 v[184:187], v[132:133], off offset:3712
	global_load_dwordx4 v[188:191], v[134:135], off offset:3712
	s_waitcnt lgkmcnt(1)
	v_mfma_f32_32x32x16_bf16 v[96:111], v[194:197], v[208:211], v[96:111]
	v_mfma_f32_32x32x16_bf16 v[112:127], v[198:201], v[208:211], v[112:127]
	s_waitcnt lgkmcnt(0)
	v_mfma_f32_32x32x16_bf16 v[64:79], v[194:197], v[212:215], v[64:79]
	v_mfma_f32_32x32x16_bf16 v[80:95], v[198:201], v[212:215], v[80:95]
	ds_read_b128 v[208:211], v149 offset:9280
	ds_read_b128 v[212:215], v149 offset:13888
	s_waitcnt vmcnt(7)
	ds_write_b128 v148, v[176:179] offset:27648
	s_waitcnt vmcnt(6)
	ds_write_b128 v148, v[180:183] offset:64512
	ds_read_b128 v[176:179], v150 offset:96
	ds_read_b128 v[180:183], v150 offset:4704
	s_waitcnt lgkmcnt(5)
	v_mfma_f32_32x32x16_bf16 v[32:47], v[194:197], v[208:211], v[32:47]
	v_mfma_f32_32x32x16_bf16 v[48:63], v[198:201], v[208:211], v[48:63]
	ds_read_b128 v[208:211], v149 offset:96
	s_waitcnt lgkmcnt(5)
	v_mfma_f32_32x32x16_bf16 v[0:15], v[194:197], v[212:215], v[0:15]
	v_mfma_f32_32x32x16_bf16 v[16:31], v[198:201], v[212:215], v[16:31]
	ds_read_b128 v[212:215], v149 offset:4704
	global_load_dwordx4 v[194:197], v[144:145], off offset:3712
	global_load_dwordx4 v[198:201], v[146:147], off offset:3712
	s_waitcnt lgkmcnt(1)
	v_mfma_f32_32x32x16_bf16 v[96:111], v[176:179], v[208:211], v[96:111]
	v_mfma_f32_32x32x16_bf16 v[112:127], v[180:183], v[208:211], v[112:127]
	s_waitcnt lgkmcnt(0)
	v_mfma_f32_32x32x16_bf16 v[64:79], v[176:179], v[212:215], v[64:79]
	v_mfma_f32_32x32x16_bf16 v[80:95], v[180:183], v[212:215], v[80:95]
	ds_read_b128 v[208:211], v149 offset:9312
	ds_read_b128 v[212:215], v149 offset:13920
	s_waitcnt lgkmcnt(1)
	v_mfma_f32_32x32x16_bf16 v[32:47], v[176:179], v[208:211], v[32:47]
	v_mfma_f32_32x32x16_bf16 v[48:63], v[180:183], v[208:211], v[48:63]
	s_waitcnt lgkmcnt(0)
	v_mfma_f32_32x32x16_bf16 v[0:15], v[176:179], v[212:215], v[0:15]
	v_mfma_f32_32x32x16_bf16 v[16:31], v[180:183], v[212:215], v[16:31]
	s_setprio 0
	s_barrier
; template <bool trans>
; DI void gemm_core(const GTile& tl, const GTile& nx, bool has_next  , bool chain  , bool pre, u32x4 (&ra)[4], u32x4 (&rb)[4], char* smem, f32x16 (&acc)[2][4]) {
;     ...
;   const int nk = K / 64;
;   if (!pre) { G_LOAD(0); G_STORE(0); G_LOAD(1); }
;   for (int kt = 0; kt < nk; ++kt) {
;     __syncthreads();
;     G_COMPUTE(kt & 1, kt);
;   }
	global_load_dwordx4 v[176:179], v[136:137], off offset:3840
	global_load_dwordx4 v[180:183], v[138:139], off offset:3840
	s_waitcnt vmcnt(9)
	ds_write_b128 v192, v[168:171]
	s_waitcnt vmcnt(8)
	ds_write_b128 v159, v[172:175]
	ds_read_b128 v[168:171], v152 offset:36864
	ds_read_b128 v[172:175], v152 offset:41472
	ds_read_b128 v[208:211], v151
	ds_read_b128 v[212:215], v151 offset:4608
	s_setprio 1
	s_waitcnt lgkmcnt(1)
	v_mfma_f32_32x32x16_bf16 v[96:111], v[168:171], v[208:211], v[96:111]
	v_mfma_f32_32x32x16_bf16 v[112:127], v[172:175], v[208:211], v[112:127]
	s_waitcnt lgkmcnt(0)
	v_mfma_f32_32x32x16_bf16 v[64:79], v[168:171], v[212:215], v[64:79]
	v_mfma_f32_32x32x16_bf16 v[80:95], v[172:175], v[212:215], v[80:95]
	ds_read_b128 v[208:211], v151 offset:9216
	ds_read_b128 v[212:215], v151 offset:13824
	s_waitcnt lgkmcnt(1)
	v_mfma_f32_32x32x16_bf16 v[32:47], v[168:171], v[208:211], v[32:47]
	v_mfma_f32_32x32x16_bf16 v[48:63], v[172:175], v[208:211], v[48:63]
	s_waitcnt lgkmcnt(0)
	v_mfma_f32_32x32x16_bf16 v[0:15], v[168:171], v[212:215], v[0:15]
	v_mfma_f32_32x32x16_bf16 v[16:31], v[172:175], v[212:215], v[16:31]
	s_setprio 0
	global_load_dwordx4 v[208:211], v[140:141], off offset:3840
	global_load_dwordx4 v[212:215], v[142:143], off offset:3840
	s_waitcnt vmcnt(9)
	ds_write_b128 v158, v[160:163]
	s_waitcnt vmcnt(8)
	ds_write_b128 v157, v[164:167]
	ds_read_b128 v[160:163], v152 offset:36896
	ds_read_b128 v[164:167], v152 offset:41504
	ds_read_b128 v[168:171], v151 offset:32
	ds_read_b128 v[172:175], v151 offset:4640
	s_setprio 1
	s_waitcnt lgkmcnt(1)
	v_mfma_f32_32x32x16_bf16 v[96:111], v[160:163], v[168:171], v[96:111]
	v_mfma_f32_32x32x16_bf16 v[112:127], v[164:167], v[168:171], v[112:127]
	s_waitcnt lgkmcnt(0)
	v_mfma_f32_32x32x16_bf16 v[64:79], v[160:163], v[172:175], v[64:79]
	v_mfma_f32_32x32x16_bf16 v[80:95], v[164:167], v[172:175], v[80:95]
	ds_read_b128 v[168:171], v151 offset:9248
	ds_read_b128 v[172:175], v151 offset:13856
	s_waitcnt lgkmcnt(1)
	v_mfma_f32_32x32x16_bf16 v[32:47], v[160:163], v[168:171], v[32:47]
	v_mfma_f32_32x32x16_bf16 v[48:63], v[164:167], v[168:171], v[48:63]
	s_waitcnt lgkmcnt(0)
	v_mfma_f32_32x32x16_bf16 v[0:15], v[160:163], v[172:175], v[0:15]
	v_mfma_f32_32x32x16_bf16 v[16:31], v[164:167], v[172:175], v[16:31]
	s_setprio 0
	global_load_dwordx4 v[216:219], v[132:133], off offset:3840
	global_load_dwordx4 v[220:223], v[134:135], off offset:3840
	s_waitcnt vmcnt(9)
	ds_write_b128 v154, v[184:187]
	s_waitcnt vmcnt(8)
	ds_write_b128 v153, v[188:191]
	ds_read_b128 v[160:163], v152 offset:36928
	ds_read_b128 v[164:167], v152 offset:41536
	ds_read_b128 v[168:171], v151 offset:64
	ds_read_b128 v[172:175], v151 offset:4672
	s_setprio 1
	s_waitcnt lgkmcnt(1)
	v_mfma_f32_32x32x16_bf16 v[96:111], v[160:163], v[168:171], v[96:111]
	v_mfma_f32_32x32x16_bf16 v[112:127], v[164:167], v[168:171], v[112:127]
	s_waitcnt lgkmcnt(0)
	v_mfma_f32_32x32x16_bf16 v[64:79], v[160:163], v[172:175], v[64:79]
	v_mfma_f32_32x32x16_bf16 v[80:95], v[164:167], v[172:175], v[80:95]
	ds_read_b128 v[168:171], v151 offset:9280
	ds_read_b128 v[172:175], v151 offset:13888
	s_waitcnt lgkmcnt(1)
	v_mfma_f32_32x32x16_bf16 v[32:47], v[160:163], v[168:171], v[32:47]
	v_mfma_f32_32x32x16_bf16 v[48:63], v[164:167], v[168:171], v[48:63]
	s_waitcnt lgkmcnt(0)
	v_mfma_f32_32x32x16_bf16 v[0:15], v[160:163], v[172:175], v[0:15]
	v_mfma_f32_32x32x16_bf16 v[16:31], v[164:167], v[172:175], v[16:31]
	s_setprio 0
	global_load_dwordx4 v[224:227], v[144:145], off offset:3840
	global_load_dwordx4 v[228:231], v[146:147], off offset:3840
	s_waitcnt vmcnt(9)
	ds_write_b128 v156, v[194:197]
	s_waitcnt vmcnt(8)
	ds_write_b128 v155, v[198:201]
	ds_read_b128 v[160:163], v152 offset:36960
	ds_read_b128 v[164:167], v152 offset:41568
	ds_read_b128 v[168:171], v151 offset:96
	ds_read_b128 v[172:175], v151 offset:4704
	s_setprio 1
	s_waitcnt lgkmcnt(1)
	v_mfma_f32_32x32x16_bf16 v[96:111], v[160:163], v[168:171], v[96:111]
	v_mfma_f32_32x32x16_bf16 v[112:127], v[164:167], v[168:171], v[112:127]
	s_waitcnt lgkmcnt(0)
	v_mfma_f32_32x32x16_bf16 v[64:79], v[160:163], v[172:175], v[64:79]
	v_mfma_f32_32x32x16_bf16 v[80:95], v[164:167], v[172:175], v[80:95]
	ds_read_b128 v[168:171], v151 offset:9312
	ds_read_b128 v[172:175], v151 offset:13920
	s_waitcnt lgkmcnt(1)
	v_mfma_f32_32x32x16_bf16 v[32:47], v[160:163], v[168:171], v[32:47]
	v_mfma_f32_32x32x16_bf16 v[48:63], v[164:167], v[168:171], v[48:63]
	s_waitcnt lgkmcnt(0)
	v_mfma_f32_32x32x16_bf16 v[0:15], v[160:163], v[172:175], v[0:15]
	v_mfma_f32_32x32x16_bf16 v[16:31], v[164:167], v[172:175], v[16:31]
	s_setprio 0
	s_barrier
; template <bool trans>
; DI void gemm_core(const GTile& tl, const GTile& nx, bool has_next  , bool chain  , bool pre, u32x4 (&ra)[4], u32x4 (&rb)[4], char* smem, f32x16 (&acc)[2][4]) {
;     ...
;   const int nk = K / 64;
;   if (!pre) { G_LOAD(0); G_STORE(0); G_LOAD(1); }
;   for (int kt = 0; kt < nk; ++kt) {
;     __syncthreads();
;     G_COMPUTE(kt & 1, kt);
;   }
;   if (!has_next) __syncthreads();
	global_load_dwordx4 v[160:163], v[136:137], off offset:3968
	global_load_dwordx4 v[164:167], v[138:139], off offset:3968
	s_waitcnt vmcnt(9)
	ds_write_b128 v148, v[176:179]
	s_waitcnt vmcnt(8)
	ds_write_b128 v148, v[180:183] offset:36864
	ds_read_b128 v[136:139], v150
	ds_read_b128 v[168:171], v150 offset:4608
	ds_read_b128 v[172:175], v149
	ds_read_b128 v[176:179], v149 offset:4608
	s_setprio 1
	s_waitcnt lgkmcnt(1)
	v_mfma_f32_32x32x16_bf16 v[96:111], v[136:139], v[172:175], v[96:111]
	v_mfma_f32_32x32x16_bf16 v[112:127], v[168:171], v[172:175], v[112:127]
	s_waitcnt lgkmcnt(0)
	v_mfma_f32_32x32x16_bf16 v[64:79], v[136:139], v[176:179], v[64:79]
	v_mfma_f32_32x32x16_bf16 v[80:95], v[168:171], v[176:179], v[80:95]
	ds_read_b128 v[172:175], v149 offset:9216
	ds_read_b128 v[176:179], v149 offset:13824
	s_waitcnt lgkmcnt(1)
	v_mfma_f32_32x32x16_bf16 v[32:47], v[136:139], v[172:175], v[32:47]
	v_mfma_f32_32x32x16_bf16 v[48:63], v[168:171], v[172:175], v[48:63]
	s_waitcnt lgkmcnt(0)
	v_mfma_f32_32x32x16_bf16 v[0:15], v[136:139], v[176:179], v[0:15]
	v_mfma_f32_32x32x16_bf16 v[16:31], v[168:171], v[176:179], v[16:31]
	s_setprio 0
	global_load_dwordx4 v[168:171], v[140:141], off offset:3968
	global_load_dwordx4 v[172:175], v[142:143], off offset:3968
	s_waitcnt vmcnt(9)
	ds_write_b128 v148, v[208:211] offset:9216
	s_waitcnt vmcnt(8)
	ds_write_b128 v148, v[212:215] offset:46080
	ds_read_b128 v[136:139], v150 offset:32
	ds_read_b128 v[140:143], v150 offset:4640
	ds_read_b128 v[176:179], v149 offset:32
	ds_read_b128 v[180:183], v149 offset:4640
	s_setprio 1
	s_waitcnt lgkmcnt(1)
	v_mfma_f32_32x32x16_bf16 v[96:111], v[136:139], v[176:179], v[96:111]
	v_mfma_f32_32x32x16_bf16 v[112:127], v[140:143], v[176:179], v[112:127]
	s_waitcnt lgkmcnt(0)
	v_mfma_f32_32x32x16_bf16 v[64:79], v[136:139], v[180:183], v[64:79]
	v_mfma_f32_32x32x16_bf16 v[80:95], v[140:143], v[180:183], v[80:95]
	ds_read_b128 v[176:179], v149 offset:9248
	ds_read_b128 v[180:183], v149 offset:13856
	s_waitcnt lgkmcnt(1)
	v_mfma_f32_32x32x16_bf16 v[32:47], v[136:139], v[176:179], v[32:47]
	v_mfma_f32_32x32x16_bf16 v[48:63], v[140:143], v[176:179], v[48:63]
	s_waitcnt lgkmcnt(0)
	v_mfma_f32_32x32x16_bf16 v[0:15], v[136:139], v[180:183], v[0:15]
	v_mfma_f32_32x32x16_bf16 v[16:31], v[140:143], v[180:183], v[16:31]
	s_setprio 0
	global_load_dwordx4 v[176:179], v[132:133], off offset:3968
	global_load_dwordx4 v[180:183], v[134:135], off offset:3968
	s_waitcnt vmcnt(9)
	ds_write_b128 v148, v[216:219] offset:18432
	s_waitcnt vmcnt(8)
	ds_write_b128 v148, v[220:223] offset:55296
	ds_read_b128 v[132:135], v150 offset:64
	ds_read_b128 v[136:139], v150 offset:4672
	ds_read_b128 v[140:143], v149 offset:64
	ds_read_b128 v[184:187], v149 offset:4672
	s_setprio 1
	s_waitcnt lgkmcnt(1)
	v_mfma_f32_32x32x16_bf16 v[96:111], v[132:135], v[140:143], v[96:111]
	v_mfma_f32_32x32x16_bf16 v[112:127], v[136:139], v[140:143], v[112:127]
	s_waitcnt lgkmcnt(0)
	v_mfma_f32_32x32x16_bf16 v[64:79], v[132:135], v[184:187], v[64:79]
	v_mfma_f32_32x32x16_bf16 v[80:95], v[136:139], v[184:187], v[80:95]
	ds_read_b128 v[140:143], v149 offset:9280
	ds_read_b128 v[184:187], v149 offset:13888
	s_waitcnt lgkmcnt(1)
	v_mfma_f32_32x32x16_bf16 v[32:47], v[132:135], v[140:143], v[32:47]
	v_mfma_f32_32x32x16_bf16 v[48:63], v[136:139], v[140:143], v[48:63]
	s_waitcnt lgkmcnt(0)
	v_mfma_f32_32x32x16_bf16 v[0:15], v[132:135], v[184:187], v[0:15]
	v_mfma_f32_32x32x16_bf16 v[16:31], v[136:139], v[184:187], v[16:31]
	s_setprio 0
	global_load_dwordx4 v[184:187], v[144:145], off offset:3968
	global_load_dwordx4 v[188:191], v[146:147], off offset:3968
	s_waitcnt vmcnt(9)
	ds_write_b128 v148, v[224:227] offset:27648
	s_waitcnt vmcnt(8)
	ds_write_b128 v148, v[228:231] offset:64512
	ds_read_b128 v[132:135], v150 offset:96
	ds_read_b128 v[136:139], v150 offset:4704
	ds_read_b128 v[140:143], v149 offset:96
	ds_read_b128 v[144:147], v149 offset:4704
	s_setprio 1
	s_waitcnt lgkmcnt(1)
	v_mfma_f32_32x32x16_bf16 v[96:111], v[132:135], v[140:143], v[96:111]
	v_mfma_f32_32x32x16_bf16 v[112:127], v[136:139], v[140:143], v[112:127]
	s_waitcnt lgkmcnt(0)
	v_mfma_f32_32x32x16_bf16 v[64:79], v[132:135], v[144:147], v[64:79]
	v_mfma_f32_32x32x16_bf16 v[80:95], v[136:139], v[144:147], v[80:95]
	ds_read_b128 v[140:143], v149 offset:9312
	ds_read_b128 v[144:147], v149 offset:13920
	s_waitcnt lgkmcnt(1)
	v_mfma_f32_32x32x16_bf16 v[32:47], v[132:135], v[140:143], v[32:47]
	v_mfma_f32_32x32x16_bf16 v[48:63], v[136:139], v[140:143], v[48:63]
	s_waitcnt lgkmcnt(0)
	v_mfma_f32_32x32x16_bf16 v[0:15], v[132:135], v[144:147], v[0:15]
	v_mfma_f32_32x32x16_bf16 v[16:31], v[136:139], v[144:147], v[16:31]
	s_setprio 0
	v_cndmask_b32_e64 v132, 0, 1, s[34:35]
	v_cmp_ne_u32_e64 s[6:7], 1, v132
	s_andn2_b64 vcc, exec, s[34:35]
	s_barrier
	s_waitcnt vmcnt(7)
	ds_write_b128 v192, v[160:163]
	s_waitcnt vmcnt(6)
	ds_write_b128 v159, v[164:167]
	s_cbranch_vccnz .LBB0_892
	global_load_dwordx4 v[160:163], v[130:131], off
	global_load_dwordx4 v[164:167], v[128:129], off

;   DI bf16_t* h() const { return (bf16_t*)(ws + OFF_H); }
; template <bool trans>
; DI void gemm_core(const GTile& tl, const GTile& nx, bool has_next  , bool chain  , bool pre, u32x4 (&ra)[4], u32x4 (&rb)[4], char* smem, f32x16 (&acc)[2][4]) {
;     ...
;   const int nk = K / 64;
;   if (!pre) { G_LOAD(0); G_STORE(0); G_LOAD(1); }
;   for (int kt = 0; kt < nk; ++kt) {
;     __syncthreads();
;     G_COMPUTE(kt & 1, kt);
;   }
; DI void phase_gemm_out(const Params& p, char* smem, const bf16_t* Wt, const float* R, float* O) {
;     ...
;   for (int t = blockIdx.x; t < 64 * 8; t += gridDim.x) {
;     const int mt = t & 63, nt = t >> 6, tn = t + gridDim.x;
;     const bool has_next = tn < 64 * 8;
;     const GTile tl{p.h(), D, Wt, D, D, mt * 256, nt * 256}, nx{p.h(), D, Wt, D, D, (tn & 63) * 256, (tn >> 6) * 256};
;     WAVE_GEOM;
;     f32x16 acc[2][4];
;     gemm_core<false>(tl, nx, has_next, has_next, pre, ra, rb, smem, acc);
.LBB0_1637:
	v_lshl_add_u64 v[128:129], s[2:3], 0, v[184:185]
	v_lshl_add_u64 v[132:133], s[4:5], 0, v[184:185]
	s_waitcnt lgkmcnt(0)
	s_barrier
	global_load_dwordx4 v[200:203], v[128:129], off offset:256
	global_load_dwordx4 v[208:211], v[132:133], off offset:256
	s_add_i32 s84, s84, s96
	s_cmpk_lt_i32 s84, 0x200
	s_cselect_b64 s[12:13], -1, 0
	s_cmpk_gt_i32 s84, 0x1ff
	s_cselect_b64 s[10:11], -1, 0
	s_and_b32 s3, s24, 0x1f80000
	s_add_i32 s16, s17, s16
	s_and_b32 s2, s16, 0xffffff00
	s_and_b32 s38, s37, 0xc0
	s_lshl_b32 s3, s3, 1
	s_add_u32 s4, s28, s3
	s_addc_u32 s5, s29, 0
	s_ashr_i32 s3, s2, 31
	s_lshl_b64 s[2:3], s[2:3], 12
	s_add_u32 s2, s14, s2
	s_addc_u32 s3, s15, s3
	s_lshr_b32 s37, s37, 1
	v_and_b32_e32 v11, 31, v8
	s_and_b32 s37, s37, 0xfffff80
	v_or_b32_e32 v12, s37, v11
	v_or_b32_e32 v11, s38, v11
	v_add3_u32 v191, 16, v10, v9
	v_lshrrev_b32_e32 v8, 1, v8
	v_mul_u32_u24_e32 v131, 0x90, v11
	v_and_b32_e32 v134, 16, v8
	v_add_u32_e32 v195, 0x12000, v191
	v_mul_lo_u32 v130, v12, s33
	v_add3_u32 v192, 16, v131, v134
	v_add_u32_e32 v196, 0x1b000, v191
	ds_write_b128 v195, v[0:3]
	s_waitcnt vmcnt(5)
	ds_write_b128 v196, v[4:7]
	v_lshl_add_u64 v[188:189], s[4:5], 0, v[184:185]
	v_lshl_add_u64 v[186:187], s[2:3], 0, v[184:185]
	v_add3_u32 v184, 16, v130, v134
	ds_read_b128 v[0:3], v192 offset:36864
	ds_read_b128 v[4:7], v192 offset:41472
	ds_read_b128 v[8:11], v184
	ds_read_b128 v[12:15], v184 offset:4608
	v_lshl_add_u64 v[136:137], v[128:129], 0, s[0:1]
	v_lshl_add_u64 v[140:141], v[132:133], 0, s[0:1]
	v_lshl_add_u64 v[144:145], v[128:129], 0, s[6:7]
	v_lshl_add_u64 v[148:149], v[132:133], 0, s[6:7]
	s_setprio 1
	s_waitcnt lgkmcnt(1)
	v_mfma_f32_32x32x16_bf16 v[112:127], v[0:3], v[8:11], 0
	v_mfma_f32_32x32x16_bf16 v[48:63], v[4:7], v[8:11], 0
	s_waitcnt lgkmcnt(0)
	v_mfma_f32_32x32x16_bf16 v[96:111], v[0:3], v[12:15], 0
	v_mfma_f32_32x32x16_bf16 v[32:47], v[4:7], v[12:15], 0
	ds_read_b128 v[8:11], v184 offset:9216
	ds_read_b128 v[12:15], v184 offset:13824
	s_waitcnt lgkmcnt(1)
	v_mfma_f32_32x32x16_bf16 v[80:95], v[0:3], v[8:11], 0
	v_mfma_f32_32x32x16_bf16 v[16:31], v[4:7], v[8:11], 0
	s_waitcnt lgkmcnt(0)
	v_mfma_f32_32x32x16_bf16 v[64:79], v[0:3], v[12:15], 0
	v_mfma_f32_32x32x16_bf16 v[0:15], v[4:7], v[12:15], 0
	s_setprio 0
	global_load_dwordx4 v[212:215], v[136:137], off offset:256
	global_load_dwordx4 v[216:219], v[140:141], off offset:256
	v_add_u32_e32 v194, 0x14400, v191
	v_add_u32_e32 v193, 0x1d400, v191
	ds_write_b128 v194, v[176:179]
	s_waitcnt vmcnt(6)
	ds_write_b128 v193, v[180:183]
	ds_read_b128 v[150:153], v192 offset:36896
	ds_read_b128 v[154:157], v192 offset:41504
	ds_read_b128 v[176:179], v184 offset:32
	ds_read_b128 v[180:183], v184 offset:4640
	s_setprio 1
	s_waitcnt lgkmcnt(1)
	v_mfma_f32_32x32x16_bf16 v[112:127], v[150:153], v[176:179], v[112:127]
	v_mfma_f32_32x32x16_bf16 v[48:63], v[154:157], v[176:179], v[48:63]
	s_waitcnt lgkmcnt(0)
	v_mfma_f32_32x32x16_bf16 v[96:111], v[150:153], v[180:183], v[96:111]
	v_mfma_f32_32x32x16_bf16 v[32:47], v[154:157], v[180:183], v[32:47]
	ds_read_b128 v[176:179], v184 offset:9248
	ds_read_b128 v[180:183], v184 offset:13856
	s_waitcnt lgkmcnt(1)
	v_mfma_f32_32x32x16_bf16 v[80:95], v[150:153], v[176:179], v[80:95]
	v_mfma_f32_32x32x16_bf16 v[16:31], v[154:157], v[176:179], v[16:31]
	s_waitcnt lgkmcnt(0)
	v_mfma_f32_32x32x16_bf16 v[64:79], v[150:153], v[180:183], v[64:79]
	v_mfma_f32_32x32x16_bf16 v[0:15], v[154:157], v[180:183], v[0:15]
	s_setprio 0
	global_load_dwordx4 v[178:181], v[144:145], off offset:256
	global_load_dwordx4 v[220:223], v[148:149], off offset:256
	v_add_u32_e32 v177, 0x16800, v191
	v_add_u32_e32 v176, 0x1f800, v191
	ds_write_b128 v177, v[168:171]
	s_waitcnt vmcnt(7)
	ds_write_b128 v176, v[172:175]
	ds_read_b128 v[150:153], v192 offset:36928
	ds_read_b128 v[154:157], v192 offset:41536
	ds_read_b128 v[168:171], v184 offset:64
	ds_read_b128 v[172:175], v184 offset:4672
	s_setprio 1
	s_waitcnt lgkmcnt(1)
	v_mfma_f32_32x32x16_bf16 v[112:127], v[150:153], v[168:171], v[112:127]
	v_mfma_f32_32x32x16_bf16 v[48:63], v[154:157], v[168:171], v[48:63]
	s_waitcnt lgkmcnt(0)
	v_mfma_f32_32x32x16_bf16 v[96:111], v[150:153], v[172:175], v[96:111]
	v_mfma_f32_32x32x16_bf16 v[32:47], v[154:157], v[172:175], v[32:47]
	ds_read_b128 v[168:171], v184 offset:9280
	ds_read_b128 v[172:175], v184 offset:13888
	s_waitcnt lgkmcnt(1)
	v_mfma_f32_32x32x16_bf16 v[80:95], v[150:153], v[168:171], v[80:95]
	v_mfma_f32_32x32x16_bf16 v[16:31], v[154:157], v[168:171], v[16:31]
	s_waitcnt lgkmcnt(0)
	v_mfma_f32_32x32x16_bf16 v[64:79], v[150:153], v[172:175], v[64:79]
	v_mfma_f32_32x32x16_bf16 v[0:15], v[154:157], v[172:175], v[0:15]
	s_setprio 0
	v_add_co_u32_e32 v152, vcc, s31, v128
	v_add_u32_e32 v171, 0x18c00, v191
	s_nop 0
	v_addc_co_u32_e32 v153, vcc, 0, v129, vcc
	v_add_co_u32_e32 v156, vcc, s31, v132
	v_add_u32_e32 v170, 0x21c00, v191
	s_nop 0
	v_addc_co_u32_e32 v157, vcc, 0, v133, vcc
	global_load_dwordx4 v[172:175], v[152:153], off offset:256
	global_load_dwordx4 v[224:227], v[156:157], off offset:256
	ds_write_b128 v171, v[160:163]
	s_waitcnt vmcnt(8)
	ds_write_b128 v170, v[164:167]
	ds_read_b128 v[158:161], v192 offset:36960
	ds_read_b128 v[162:165], v192 offset:41568
	ds_read_b128 v[166:169], v184 offset:96
	ds_read_b128 v[228:231], v184 offset:4704
	s_setprio 1
	s_waitcnt lgkmcnt(1)
	v_mfma_f32_32x32x16_bf16 v[112:127], v[158:161], v[166:169], v[112:127]
	v_mfma_f32_32x32x16_bf16 v[48:63], v[162:165], v[166:169], v[48:63]
	s_waitcnt lgkmcnt(0)
	v_mfma_f32_32x32x16_bf16 v[96:111], v[158:161], v[228:231], v[96:111]
	v_mfma_f32_32x32x16_bf16 v[32:47], v[162:165], v[228:231], v[32:47]
	ds_read_b128 v[166:169], v184 offset:9312
	ds_read_b128 v[228:231], v184 offset:13920
	s_waitcnt lgkmcnt(1)
	v_mfma_f32_32x32x16_bf16 v[80:95], v[158:161], v[166:169], v[80:95]
	v_mfma_f32_32x32x16_bf16 v[16:31], v[162:165], v[166:169], v[16:31]
	s_waitcnt lgkmcnt(0)
	v_mfma_f32_32x32x16_bf16 v[64:79], v[158:161], v[228:231], v[64:79]
	v_mfma_f32_32x32x16_bf16 v[0:15], v[162:165], v[228:231], v[0:15]
	s_setprio 0
	s_barrier
; template <bool trans>
; DI void gemm_core(const GTile& tl, const GTile& nx, bool has_next  , bool chain  , bool pre, u32x4 (&ra)[4], u32x4 (&rb)[4], char* smem, f32x16 (&acc)[2][4]) {
;     ...
;   const int nk = K / 64;
;   if (!pre) { G_LOAD(0); G_STORE(0); G_LOAD(1); }
;   for (int kt = 0; kt < nk; ++kt) {
;     __syncthreads();
;     G_COMPUTE(kt & 1, kt);
;   }
	global_load_dwordx4 v[158:161], v[128:129], off offset:384
	global_load_dwordx4 v[162:165], v[132:133], off offset:384
	v_add3_u32 v169, s35, v131, v134
	s_waitcnt vmcnt(9)
	ds_write_b128 v191, v[200:203]
	s_waitcnt vmcnt(8)
	ds_write_b128 v191, v[208:211] offset:36864
	v_add3_u32 v168, s34, v130, v134
	ds_read_b128 v[200:203], v169
	ds_read_b128 v[208:211], v169 offset:4608
	ds_read_b128 v[228:231], v168
	ds_read_b128 v[232:235], v168 offset:4608
	s_setprio 1
	s_waitcnt lgkmcnt(1)
	v_mfma_f32_32x32x16_bf16 v[112:127], v[200:203], v[228:231], v[112:127]
	v_mfma_f32_32x32x16_bf16 v[48:63], v[208:211], v[228:231], v[48:63]
	s_waitcnt lgkmcnt(0)
	v_mfma_f32_32x32x16_bf16 v[96:111], v[200:203], v[232:235], v[96:111]
	v_mfma_f32_32x32x16_bf16 v[32:47], v[208:211], v[232:235], v[32:47]
	ds_read_b128 v[228:231], v168 offset:9216
	ds_read_b128 v[232:235], v168 offset:13824
	s_waitcnt lgkmcnt(1)
	v_mfma_f32_32x32x16_bf16 v[80:95], v[200:203], v[228:231], v[80:95]
	v_mfma_f32_32x32x16_bf16 v[16:31], v[208:211], v[228:231], v[16:31]
	s_waitcnt lgkmcnt(0)
	v_mfma_f32_32x32x16_bf16 v[64:79], v[200:203], v[232:235], v[64:79]
	v_mfma_f32_32x32x16_bf16 v[0:15], v[208:211], v[232:235], v[0:15]
	s_setprio 0
	global_load_dwordx4 v[200:203], v[136:137], off offset:384
	global_load_dwordx4 v[208:211], v[140:141], off offset:384
	s_waitcnt vmcnt(9)
	ds_write_b128 v191, v[212:215] offset:9216
	s_waitcnt vmcnt(8)
	ds_write_b128 v191, v[216:219] offset:46080
	ds_read_b128 v[212:215], v169 offset:32
	ds_read_b128 v[216:219], v169 offset:4640
	ds_read_b128 v[228:231], v168 offset:32
	ds_read_b128 v[232:235], v168 offset:4640
	s_setprio 1
	s_waitcnt lgkmcnt(1)
	v_mfma_f32_32x32x16_bf16 v[112:127], v[212:215], v[228:231], v[112:127]
	v_mfma_f32_32x32x16_bf16 v[48:63], v[216:219], v[228:231], v[48:63]
	s_waitcnt lgkmcnt(0)
	v_mfma_f32_32x32x16_bf16 v[96:111], v[212:215], v[232:235], v[96:111]
	v_mfma_f32_32x32x16_bf16 v[32:47], v[216:219], v[232:235], v[32:47]
	ds_read_b128 v[228:231], v168 offset:9248
	ds_read_b128 v[232:235], v168 offset:13856
	s_waitcnt lgkmcnt(1)
	v_mfma_f32_32x32x16_bf16 v[80:95], v[212:215], v[228:231], v[80:95]
	v_mfma_f32_32x32x16_bf16 v[16:31], v[216:219], v[228:231], v[16:31]
	s_waitcnt lgkmcnt(0)
	v_mfma_f32_32x32x16_bf16 v[64:79], v[212:215], v[232:235], v[64:79]
	v_mfma_f32_32x32x16_bf16 v[0:15], v[216:219], v[232:235], v[0:15]
	s_setprio 0
	global_load_dwordx4 v[212:215], v[144:145], off offset:384
	global_load_dwordx4 v[216:219], v[148:149], off offset:384
	s_waitcnt vmcnt(9)
	ds_write_b128 v191, v[178:181] offset:18432
	s_waitcnt vmcnt(8)
	ds_write_b128 v191, v[220:223] offset:55296
	ds_read_b128 v[178:181], v169 offset:64
	ds_read_b128 v[220:223], v169 offset:4672
	ds_read_b128 v[228:231], v168 offset:64
	ds_read_b128 v[232:235], v168 offset:4672
	s_setprio 1
	s_waitcnt lgkmcnt(1)
	v_mfma_f32_32x32x16_bf16 v[112:127], v[178:181], v[228:231], v[112:127]
	v_mfma_f32_32x32x16_bf16 v[48:63], v[220:223], v[228:231], v[48:63]
	s_waitcnt lgkmcnt(0)
	v_mfma_f32_32x32x16_bf16 v[96:111], v[178:181], v[232:235], v[96:111]
	v_mfma_f32_32x32x16_bf16 v[32:47], v[220:223], v[232:235], v[32:47]
	ds_read_b128 v[228:231], v168 offset:9280
	ds_read_b128 v[232:235], v168 offset:13888
	s_waitcnt lgkmcnt(1)
	v_mfma_f32_32x32x16_bf16 v[80:95], v[178:181], v[228:231], v[80:95]
	v_mfma_f32_32x32x16_bf16 v[16:31], v[220:223], v[228:231], v[16:31]
	s_waitcnt lgkmcnt(0)
	v_mfma_f32_32x32x16_bf16 v[64:79], v[178:181], v[232:235], v[64:79]
	v_mfma_f32_32x32x16_bf16 v[0:15], v[220:223], v[232:235], v[0:15]
	s_setprio 0
	global_load_dwordx4 v[178:181], v[152:153], off offset:384
	global_load_dwordx4 v[220:223], v[156:157], off offset:384
	s_waitcnt vmcnt(9)
	ds_write_b128 v191, v[172:175] offset:27648
	s_waitcnt vmcnt(8)
	ds_write_b128 v191, v[224:227] offset:64512
	ds_read_b128 v[172:175], v169 offset:96
	ds_read_b128 v[224:227], v169 offset:4704
	ds_read_b128 v[228:231], v168 offset:96
	ds_read_b128 v[232:235], v168 offset:4704
	s_setprio 1
	s_waitcnt lgkmcnt(1)
	v_mfma_f32_32x32x16_bf16 v[112:127], v[172:175], v[228:231], v[112:127]
	v_mfma_f32_32x32x16_bf16 v[48:63], v[224:227], v[228:231], v[48:63]
	s_waitcnt lgkmcnt(0)
	v_mfma_f32_32x32x16_bf16 v[96:111], v[172:175], v[232:235], v[96:111]
	v_mfma_f32_32x32x16_bf16 v[32:47], v[224:227], v[232:235], v[32:47]
	ds_read_b128 v[228:231], v168 offset:9312
	ds_read_b128 v[232:235], v168 offset:13920
	s_waitcnt lgkmcnt(1)
	v_mfma_f32_32x32x16_bf16 v[80:95], v[172:175], v[228:231], v[80:95]
	v_mfma_f32_32x32x16_bf16 v[16:31], v[224:227], v[228:231], v[16:31]
	s_waitcnt lgkmcnt(0)
	v_mfma_f32_32x32x16_bf16 v[64:79], v[172:175], v[232:235], v[64:79]
	v_mfma_f32_32x32x16_bf16 v[0:15], v[224:227], v[232:235], v[0:15]
	s_setprio 0
	s_barrier
; template <bool trans>
; DI void gemm_core(const GTile& tl, const GTile& nx, bool has_next  , bool chain  , bool pre, u32x4 (&ra)[4], u32x4 (&rb)[4], char* smem, f32x16 (&acc)[2][4]) {
;     ...
;   const int nk = K / 64;
;   if (!pre) { G_LOAD(0); G_STORE(0); G_LOAD(1); }
;   for (int kt = 0; kt < nk; ++kt) {
;     __syncthreads();
;     G_COMPUTE(kt & 1, kt);
;   }
	global_load_dwordx4 v[172:175], v[128:129], off offset:512
	global_load_dwordx4 v[224:227], v[132:133], off offset:512
	s_waitcnt vmcnt(9)
	ds_write_b128 v195, v[158:161]
	s_waitcnt vmcnt(8)
	ds_write_b128 v196, v[162:165]
	ds_read_b128 v[158:161], v192 offset:36864
	ds_read_b128 v[162:165], v192 offset:41472
	ds_read_b128 v[228:231], v184
	ds_read_b128 v[232:235], v184 offset:4608
	s_setprio 1
	s_waitcnt lgkmcnt(1)
	v_mfma_f32_32x32x16_bf16 v[112:127], v[158:161], v[228:231], v[112:127]
	v_mfma_f32_32x32x16_bf16 v[48:63], v[162:165], v[228:231], v[48:63]
	s_waitcnt lgkmcnt(0)
	v_mfma_f32_32x32x16_bf16 v[96:111], v[158:161], v[232:235], v[96:111]
	v_mfma_f32_32x32x16_bf16 v[32:47], v[162:165], v[232:235], v[32:47]
	ds_read_b128 v[228:231], v184 offset:9216
	ds_read_b128 v[232:235], v184 offset:13824
	s_waitcnt vmcnt(7)
	ds_write_b128 v194, v[200:203]
	s_waitcnt vmcnt(6)
	ds_write_b128 v193, v[208:211]
	ds_read_b128 v[200:203], v192 offset:36896
	ds_read_b128 v[208:211], v192 offset:41504
	s_waitcnt lgkmcnt(5)
	v_mfma_f32_32x32x16_bf16 v[80:95], v[158:161], v[228:231], v[80:95]
	v_mfma_f32_32x32x16_bf16 v[16:31], v[162:165], v[228:231], v[16:31]
	ds_read_b128 v[228:231], v184 offset:32
	s_waitcnt lgkmcnt(5)
	v_mfma_f32_32x32x16_bf16 v[64:79], v[158:161], v[232:235], v[64:79]
	v_mfma_f32_32x32x16_bf16 v[0:15], v[162:165], v[232:235], v[0:15]
	ds_read_b128 v[232:235], v184 offset:4640
	global_load_dwordx4 v[158:161], v[136:137], off offset:512
	global_load_dwordx4 v[162:165], v[140:141], off offset:512
	s_waitcnt lgkmcnt(1)
	v_mfma_f32_32x32x16_bf16 v[112:127], v[200:203], v[228:231], v[112:127]
	v_mfma_f32_32x32x16_bf16 v[48:63], v[208:211], v[228:231], v[48:63]
	s_waitcnt lgkmcnt(0)
	v_mfma_f32_32x32x16_bf16 v[96:111], v[200:203], v[232:235], v[96:111]
	v_mfma_f32_32x32x16_bf16 v[32:47], v[208:211], v[232:235], v[32:47]
	ds_read_b128 v[228:231], v184 offset:9248
	ds_read_b128 v[232:235], v184 offset:13856
	s_waitcnt vmcnt(7)
	ds_write_b128 v177, v[212:215]
	s_waitcnt vmcnt(6)
	ds_write_b128 v176, v[216:219]
	ds_read_b128 v[212:215], v192 offset:36928
	ds_read_b128 v[216:219], v192 offset:41536
	s_waitcnt lgkmcnt(5)
	v_mfma_f32_32x32x16_bf16 v[80:95], v[200:203], v[228:231], v[80:95]
	v_mfma_f32_32x32x16_bf16 v[16:31], v[208:211], v[228:231], v[16:31]
	ds_read_b128 v[228:231], v184 offset:64
	s_waitcnt lgkmcnt(5)
	v_mfma_f32_32x32x16_bf16 v[64:79], v[200:203], v[232:235], v[64:79]
	v_mfma_f32_32x32x16_bf16 v[0:15], v[208:211], v[232:235], v[0:15]
	ds_read_b128 v[232:235], v184 offset:4672
	global_load_dwordx4 v[200:203], v[144:145], off offset:512
	global_load_dwordx4 v[208:211], v[148:149], off offset:512
	s_waitcnt lgkmcnt(1)
	v_mfma_f32_32x32x16_bf16 v[112:127], v[212:215], v[228:231], v[112:127]
	v_mfma_f32_32x32x16_bf16 v[48:63], v[216:219], v[228:231], v[48:63]
	s_waitcnt lgkmcnt(0)
	v_mfma_f32_32x32x16_bf16 v[96:111], v[212:215], v[232:235], v[96:111]
	v_mfma_f32_32x32x16_bf16 v[32:47], v[216:219], v[232:235], v[32:47]
	ds_read_b128 v[228:231], v184 offset:9280
	ds_read_b128 v[232:235], v184 offset:13888
	s_waitcnt vmcnt(7)
	ds_write_b128 v171, v[178:181]
	s_waitcnt vmcnt(6)
	ds_write_b128 v170, v[220:223]
	ds_read_b128 v[178:181], v192 offset:36960
	ds_read_b128 v[220:223], v192 offset:41568
	s_waitcnt lgkmcnt(5)
	v_mfma_f32_32x32x16_bf16 v[80:95], v[212:215], v[228:231], v[80:95]
	v_mfma_f32_32x32x16_bf16 v[16:31], v[216:219], v[228:231], v[16:31]
	ds_read_b128 v[228:231], v184 offset:96
	s_waitcnt lgkmcnt(5)
	v_mfma_f32_32x32x16_bf16 v[64:79], v[212:215], v[232:235], v[64:79]
	v_mfma_f32_32x32x16_bf16 v[0:15], v[216:219], v[232:235], v[0:15]
	ds_read_b128 v[232:235], v184 offset:4704
	global_load_dwordx4 v[212:215], v[152:153], off offset:512
	global_load_dwordx4 v[216:219], v[156:157], off offset:512
	s_waitcnt lgkmcnt(1)
	v_mfma_f32_32x32x16_bf16 v[112:127], v[178:181], v[228:231], v[112:127]
	v_mfma_f32_32x32x16_bf16 v[48:63], v[220:223], v[228:231], v[48:63]
	s_waitcnt lgkmcnt(0)
	v_mfma_f32_32x32x16_bf16 v[96:111], v[178:181], v[232:235], v[96:111]
	v_mfma_f32_32x32x16_bf16 v[32:47], v[220:223], v[232:235], v[32:47]
	ds_read_b128 v[228:231], v184 offset:9312
	ds_read_b128 v[232:235], v184 offset:13920
	s_waitcnt lgkmcnt(1)
	v_mfma_f32_32x32x16_bf16 v[80:95], v[178:181], v[228:231], v[80:95]
	v_mfma_f32_32x32x16_bf16 v[16:31], v[220:223], v[228:231], v[16:31]
	s_waitcnt lgkmcnt(0)
	v_mfma_f32_32x32x16_bf16 v[64:79], v[178:181], v[232:235], v[64:79]
	v_mfma_f32_32x32x16_bf16 v[0:15], v[220:223], v[232:235], v[0:15]
	s_setprio 0
	s_barrier
; template <bool trans>
; DI void gemm_core(const GTile& tl, const GTile& nx, bool has_next  , bool chain  , bool pre, u32x4 (&ra)[4], u32x4 (&rb)[4], char* smem, f32x16 (&acc)[2][4]) {
;     ...
;   const int nk = K / 64;
;   if (!pre) { G_LOAD(0); G_STORE(0); G_LOAD(1); }
;   for (int kt = 0; kt < nk; ++kt) {
;     __syncthreads();
;     G_COMPUTE(kt & 1, kt);
;   }
	global_load_dwordx4 v[178:181], v[128:129], off offset:640
	global_load_dwordx4 v[220:223], v[132:133], off offset:640
	s_waitcnt vmcnt(9)
	ds_write_b128 v191, v[172:175]
	s_waitcnt vmcnt(8)
	ds_write_b128 v191, v[224:227] offset:36864
	ds_read_b128 v[172:175], v169
	ds_read_b128 v[224:227], v169 offset:4608
	ds_read_b128 v[228:231], v168
	ds_read_b128 v[232:235], v168 offset:4608
	s_setprio 1
	s_waitcnt lgkmcnt(1)
	v_mfma_f32_32x32x16_bf16 v[112:127], v[172:175], v[228:231], v[112:127]
	v_mfma_f32_32x32x16_bf16 v[48:63], v[224:227], v[228:231], v[48:63]
	s_waitcnt lgkmcnt(0)
	v_mfma_f32_32x32x16_bf16 v[96:111], v[172:175], v[232:235], v[96:111]
	v_mfma_f32_32x32x16_bf16 v[32:47], v[224:227], v[232:235], v[32:47]
	ds_read_b128 v[228:231], v168 offset:9216
	ds_read_b128 v[232:235], v168 offset:13824
	s_waitcnt vmcnt(7)
	ds_write_b128 v191, v[158:161] offset:9216
	s_waitcnt vmcnt(6)
	ds_write_b128 v191, v[162:165] offset:46080
	ds_read_b128 v[158:161], v169 offset:32
	ds_read_b128 v[162:165], v169 offset:4640
	s_waitcnt lgkmcnt(5)
	v_mfma_f32_32x32x16_bf16 v[80:95], v[172:175], v[228:231], v[80:95]
	v_mfma_f32_32x32x16_bf16 v[16:31], v[224:227], v[228:231], v[16:31]
	ds_read_b128 v[228:231], v168 offset:32
	s_waitcnt lgkmcnt(5)
	v_mfma_f32_32x32x16_bf16 v[64:79], v[172:175], v[232:235], v[64:79]
	v_mfma_f32_32x32x16_bf16 v[0:15], v[224:227], v[232:235], v[0:15]
	ds_read_b128 v[232:235], v168 offset:4640
	global_load_dwordx4 v[172:175], v[136:137], off offset:640
	global_load_dwordx4 v[224:227], v[140:141], off offset:640
	s_waitcnt lgkmcnt(1)
	v_mfma_f32_32x32x16_bf16 v[112:127], v[158:161], v[228:231], v[112:127]
	v_mfma_f32_32x32x16_bf16 v[48:63], v[162:165], v[228:231], v[48:63]
	s_waitcnt lgkmcnt(0)
	v_mfma_f32_32x32x16_bf16 v[96:111], v[158:161], v[232:235], v[96:111]
	v_mfma_f32_32x32x16_bf16 v[32:47], v[162:165], v[232:235], v[32:47]
	ds_read_b128 v[228:231], v168 offset:9248
	ds_read_b128 v[232:235], v168 offset:13856
	s_waitcnt vmcnt(7)
	ds_write_b128 v191, v[200:203] offset:18432
	s_waitcnt vmcnt(6)
	ds_write_b128 v191, v[208:211] offset:55296
	ds_read_b128 v[200:203], v169 offset:64
	ds_read_b128 v[208:211], v169 offset:4672
	s_waitcnt lgkmcnt(5)
	v_mfma_f32_32x32x16_bf16 v[80:95], v[158:161], v[228:231], v[80:95]
	v_mfma_f32_32x32x16_bf16 v[16:31], v[162:165], v[228:231], v[16:31]
	ds_read_b128 v[228:231], v168 offset:64
	s_waitcnt lgkmcnt(5)
	v_mfma_f32_32x32x16_bf16 v[64:79], v[158:161], v[232:235], v[64:79]
	v_mfma_f32_32x32x16_bf16 v[0:15], v[162:165], v[232:235], v[0:15]
	ds_read_b128 v[232:235], v168 offset:4672
	global_load_dwordx4 v[158:161], v[144:145], off offset:640
	global_load_dwordx4 v[162:165], v[148:149], off offset:640
	s_waitcnt lgkmcnt(1)
	v_mfma_f32_32x32x16_bf16 v[112:127], v[200:203], v[228:231], v[112:127]
	v_mfma_f32_32x32x16_bf16 v[48:63], v[208:211], v[228:231], v[48:63]
	s_waitcnt lgkmcnt(0)
	v_mfma_f32_32x32x16_bf16 v[96:111], v[200:203], v[232:235], v[96:111]
	v_mfma_f32_32x32x16_bf16 v[32:47], v[208:211], v[232:235], v[32:47]
	ds_read_b128 v[228:231], v168 offset:9280
	ds_read_b128 v[232:235], v168 offset:13888
	s_waitcnt vmcnt(7)
	ds_write_b128 v191, v[212:215] offset:27648
	s_waitcnt vmcnt(6)
	ds_write_b128 v191, v[216:219] offset:64512
	ds_read_b128 v[212:215], v169 offset:96
	ds_read_b128 v[216:219], v169 offset:4704
	s_waitcnt lgkmcnt(5)
	v_mfma_f32_32x32x16_bf16 v[80:95], v[200:203], v[228:231], v[80:95]
	v_mfma_f32_32x32x16_bf16 v[16:31], v[208:211], v[228:231], v[16:31]
	ds_read_b128 v[228:231], v168 offset:96
	s_waitcnt lgkmcnt(5)
	v_mfma_f32_32x32x16_bf16 v[64:79], v[200:203], v[232:235], v[64:79]
	v_mfma_f32_32x32x16_bf16 v[0:15], v[208:211], v[232:235], v[0:15]
	ds_read_b128 v[232:235], v168 offset:4704
	global_load_dwordx4 v[200:203], v[152:153], off offset:640
	global_load_dwordx4 v[208:211], v[156:157], off offset:640
	s_waitcnt lgkmcnt(1)
	v_mfma_f32_32x32x16_bf16 v[112:127], v[212:215], v[228:231], v[112:127]
	v_mfma_f32_32x32x16_bf16 v[48:63], v[216:219], v[228:231], v[48:63]
	s_waitcnt lgkmcnt(0)
	v_mfma_f32_32x32x16_bf16 v[96:111], v[212:215], v[232:235], v[96:111]
	v_mfma_f32_32x32x16_bf16 v[32:47], v[216:219], v[232:235], v[32:47]
	ds_read_b128 v[228:231], v168 offset:9312
	ds_read_b128 v[232:235], v168 offset:13920
	s_waitcnt lgkmcnt(1)
	v_mfma_f32_32x32x16_bf16 v[80:95], v[212:215], v[228:231], v[80:95]
	v_mfma_f32_32x32x16_bf16 v[16:31], v[216:219], v[228:231], v[16:31]
	s_waitcnt lgkmcnt(0)
	v_mfma_f32_32x32x16_bf16 v[64:79], v[212:215], v[232:235], v[64:79]
	v_mfma_f32_32x32x16_bf16 v[0:15], v[216:219], v[232:235], v[0:15]
	s_setprio 0
	s_barrier
; template <bool trans>
; DI void gemm_core(const GTile& tl, const GTile& nx, bool has_next  , bool chain  , bool pre, u32x4 (&ra)[4], u32x4 (&rb)[4], char* smem, f32x16 (&acc)[2][4]) {
;     ...
;   const int nk = K / 64;
;   if (!pre) { G_LOAD(0); G_STORE(0); G_LOAD(1); }
;   for (int kt = 0; kt < nk; ++kt) {
;     __syncthreads();
;     G_COMPUTE(kt & 1, kt);
;   }
	global_load_dwordx4 v[212:215], v[128:129], off offset:768
	global_load_dwordx4 v[216:219], v[132:133], off offset:768
	s_waitcnt vmcnt(9)
	ds_write_b128 v195, v[178:181]
	s_waitcnt vmcnt(8)
	ds_write_b128 v196, v[220:223]
	ds_read_b128 v[178:181], v192 offset:36864
	ds_read_b128 v[220:223], v192 offset:41472
	ds_read_b128 v[228:231], v184
	ds_read_b128 v[232:235], v184 offset:4608
	s_setprio 1
	s_waitcnt lgkmcnt(1)
	v_mfma_f32_32x32x16_bf16 v[112:127], v[178:181], v[228:231], v[112:127]
	v_mfma_f32_32x32x16_bf16 v[48:63], v[220:223], v[228:231], v[48:63]
	s_waitcnt lgkmcnt(0)
	v_mfma_f32_32x32x16_bf16 v[96:111], v[178:181], v[232:235], v[96:111]
	v_mfma_f32_32x32x16_bf16 v[32:47], v[220:223], v[232:235], v[32:47]
	ds_read_b128 v[228:231], v184 offset:9216
	ds_read_b128 v[232:235], v184 offset:13824
	s_waitcnt vmcnt(7)
	ds_write_b128 v194, v[172:175]
	s_waitcnt vmcnt(6)
	ds_write_b128 v193, v[224:227]
	ds_read_b128 v[172:175], v192 offset:36896
	ds_read_b128 v[224:227], v192 offset:41504
	s_waitcnt lgkmcnt(5)
	v_mfma_f32_32x32x16_bf16 v[80:95], v[178:181], v[228:231], v[80:95]
	v_mfma_f32_32x32x16_bf16 v[16:31], v[220:223], v[228:231], v[16:31]
	ds_read_b128 v[228:231], v184 offset:32
	s_waitcnt lgkmcnt(5)
	v_mfma_f32_32x32x16_bf16 v[64:79], v[178:181], v[232:235], v[64:79]
	v_mfma_f32_32x32x16_bf16 v[0:15], v[220:223], v[232:235], v[0:15]
	ds_read_b128 v[232:235], v184 offset:4640
	global_load_dwordx4 v[178:181], v[136:137], off offset:768
	global_load_dwordx4 v[220:223], v[140:141], off offset:768
	s_waitcnt lgkmcnt(1)
	v_mfma_f32_32x32x16_bf16 v[112:127], v[172:175], v[228:231], v[112:127]
	v_mfma_f32_32x32x16_bf16 v[48:63], v[224:227], v[228:231], v[48:63]
	s_waitcnt lgkmcnt(0)
	v_mfma_f32_32x32x16_bf16 v[96:111], v[172:175], v[232:235], v[96:111]
	v_mfma_f32_32x32x16_bf16 v[32:47], v[224:227], v[232:235], v[32:47]
	ds_read_b128 v[228:231], v184 offset:9248
	ds_read_b128 v[232:235], v184 offset:13856
	s_waitcnt vmcnt(7)
	ds_write_b128 v177, v[158:161]
	s_waitcnt vmcnt(6)
	ds_write_b128 v176, v[162:165]
	ds_read_b128 v[158:161], v192 offset:36928
	ds_read_b128 v[162:165], v192 offset:41536
	s_waitcnt lgkmcnt(5)
	v_mfma_f32_32x32x16_bf16 v[80:95], v[172:175], v[228:231], v[80:95]
	v_mfma_f32_32x32x16_bf16 v[16:31], v[224:227], v[228:231], v[16:31]
	ds_read_b128 v[228:231], v184 offset:64
	s_waitcnt lgkmcnt(5)
	v_mfma_f32_32x32x16_bf16 v[64:79], v[172:175], v[232:235], v[64:79]
	v_mfma_f32_32x32x16_bf16 v[0:15], v[224:227], v[232:235], v[0:15]
	ds_read_b128 v[232:235], v184 offset:4672
	global_load_dwordx4 v[172:175], v[144:145], off offset:768
	global_load_dwordx4 v[224:227], v[148:149], off offset:768
	s_waitcnt lgkmcnt(1)
	v_mfma_f32_32x32x16_bf16 v[112:127], v[158:161], v[228:231], v[112:127]
	v_mfma_f32_32x32x16_bf16 v[48:63], v[162:165], v[228:231], v[48:63]
	s_waitcnt lgkmcnt(0)
	v_mfma_f32_32x32x16_bf16 v[96:111], v[158:161], v[232:235], v[96:111]
	v_mfma_f32_32x32x16_bf16 v[32:47], v[162:165], v[232:235], v[32:47]
	ds_read_b128 v[228:231], v184 offset:9280
	ds_read_b128 v[232:235], v184 offset:13888
	s_waitcnt vmcnt(7)
	ds_write_b128 v171, v[200:203]
	s_waitcnt vmcnt(6)
	ds_write_b128 v170, v[208:211]
	ds_read_b128 v[200:203], v192 offset:36960
	ds_read_b128 v[208:211], v192 offset:41568
	s_waitcnt lgkmcnt(5)
	v_mfma_f32_32x32x16_bf16 v[80:95], v[158:161], v[228:231], v[80:95]
	v_mfma_f32_32x32x16_bf16 v[16:31], v[162:165], v[228:231], v[16:31]
	ds_read_b128 v[228:231], v184 offset:96
	s_waitcnt lgkmcnt(5)
	v_mfma_f32_32x32x16_bf16 v[64:79], v[158:161], v[232:235], v[64:79]
	v_mfma_f32_32x32x16_bf16 v[0:15], v[162:165], v[232:235], v[0:15]
	ds_read_b128 v[232:235], v184 offset:4704
	global_load_dwordx4 v[158:161], v[152:153], off offset:768
	global_load_dwordx4 v[162:165], v[156:157], off offset:768
	s_waitcnt lgkmcnt(1)
	v_mfma_f32_32x32x16_bf16 v[112:127], v[200:203], v[228:231], v[112:127]
	v_mfma_f32_32x32x16_bf16 v[48:63], v[208:211], v[228:231], v[48:63]
	s_waitcnt lgkmcnt(0)
	v_mfma_f32_32x32x16_bf16 v[96:111], v[200:203], v[232:235], v[96:111]
	v_mfma_f32_32x32x16_bf16 v[32:47], v[208:211], v[232:235], v[32:47]
	ds_read_b128 v[228:231], v184 offset:9312
	ds_read_b128 v[232:235], v184 offset:13920
	s_waitcnt lgkmcnt(1)
	v_mfma_f32_32x32x16_bf16 v[80:95], v[200:203], v[228:231], v[80:95]
	v_mfma_f32_32x32x16_bf16 v[16:31], v[208:211], v[228:231], v[16:31]
	s_waitcnt lgkmcnt(0)
	v_mfma_f32_32x32x16_bf16 v[64:79], v[200:203], v[232:235], v[64:79]
	v_mfma_f32_32x32x16_bf16 v[0:15], v[208:211], v[232:235], v[0:15]
	s_setprio 0
	s_barrier
; template <bool trans>
; DI void gemm_core(const GTile& tl, const GTile& nx, bool has_next  , bool chain  , bool pre, u32x4 (&ra)[4], u32x4 (&rb)[4], char* smem, f32x16 (&acc)[2][4]) {
;     ...
;   const int nk = K / 64;
;   if (!pre) { G_LOAD(0); G_STORE(0); G_LOAD(1); }
;   for (int kt = 0; kt < nk; ++kt) {
;     __syncthreads();
;     G_COMPUTE(kt & 1, kt);
;   }
	global_load_dwordx4 v[200:203], v[128:129], off offset:896
	global_load_dwordx4 v[208:211], v[132:133], off offset:896
	s_waitcnt vmcnt(9)
	ds_write_b128 v191, v[212:215]
	s_waitcnt vmcnt(8)
	ds_write_b128 v191, v[216:219] offset:36864
	ds_read_b128 v[212:215], v169
	ds_read_b128 v[216:219], v169 offset:4608
	ds_read_b128 v[228:231], v168
	ds_read_b128 v[232:235], v168 offset:4608
	s_setprio 1
	s_waitcnt lgkmcnt(1)
	v_mfma_f32_32x32x16_bf16 v[112:127], v[212:215], v[228:231], v[112:127]
	v_mfma_f32_32x32x16_bf16 v[48:63], v[216:219], v[228:231], v[48:63]
	s_waitcnt lgkmcnt(0)
	v_mfma_f32_32x32x16_bf16 v[96:111], v[212:215], v[232:235], v[96:111]
	v_mfma_f32_32x32x16_bf16 v[32:47], v[216:219], v[232:235], v[32:47]
	ds_read_b128 v[228:231], v168 offset:9216
	ds_read_b128 v[232:235], v168 offset:13824
	s_waitcnt vmcnt(7)
	ds_write_b128 v191, v[178:181] offset:9216
	s_waitcnt vmcnt(6)
	ds_write_b128 v191, v[220:223] offset:46080
	ds_read_b128 v[178:181], v169 offset:32
	ds_read_b128 v[220:223], v169 offset:4640
	s_waitcnt lgkmcnt(5)
	v_mfma_f32_32x32x16_bf16 v[80:95], v[212:215], v[228:231], v[80:95]
	v_mfma_f32_32x32x16_bf16 v[16:31], v[216:219], v[228:231], v[16:31]
	ds_read_b128 v[228:231], v168 offset:32
	s_waitcnt lgkmcnt(5)
	v_mfma_f32_32x32x16_bf16 v[64:79], v[212:215], v[232:235], v[64:79]
	v_mfma_f32_32x32x16_bf16 v[0:15], v[216:219], v[232:235], v[0:15]
	ds_read_b128 v[232:235], v168 offset:4640
	global_load_dwordx4 v[212:215], v[136:137], off offset:896
	global_load_dwordx4 v[216:219], v[140:141], off offset:896
	s_waitcnt lgkmcnt(1)
	v_mfma_f32_32x32x16_bf16 v[112:127], v[178:181], v[228:231], v[112:127]
	v_mfma_f32_32x32x16_bf16 v[48:63], v[220:223], v[228:231], v[48:63]
	s_waitcnt lgkmcnt(0)
	v_mfma_f32_32x32x16_bf16 v[96:111], v[178:181], v[232:235], v[96:111]
	v_mfma_f32_32x32x16_bf16 v[32:47], v[220:223], v[232:235], v[32:47]
	ds_read_b128 v[228:231], v168 offset:9248
	ds_read_b128 v[232:235], v168 offset:13856
	s_waitcnt vmcnt(7)
	ds_write_b128 v191, v[172:175] offset:18432
	s_waitcnt vmcnt(6)
	ds_write_b128 v191, v[224:227] offset:55296
	ds_read_b128 v[172:175], v169 offset:64
	ds_read_b128 v[224:227], v169 offset:4672
	s_waitcnt lgkmcnt(5)
	v_mfma_f32_32x32x16_bf16 v[80:95], v[178:181], v[228:231], v[80:95]
	v_mfma_f32_32x32x16_bf16 v[16:31], v[220:223], v[228:231], v[16:31]
	ds_read_b128 v[228:231], v168 offset:64
	s_waitcnt lgkmcnt(5)
	v_mfma_f32_32x32x16_bf16 v[64:79], v[178:181], v[232:235], v[64:79]
	v_mfma_f32_32x32x16_bf16 v[0:15], v[220:223], v[232:235], v[0:15]
	ds_read_b128 v[232:235], v168 offset:4672
	global_load_dwordx4 v[178:181], v[144:145], off offset:896
	global_load_dwordx4 v[220:223], v[148:149], off offset:896
	s_waitcnt lgkmcnt(1)
	v_mfma_f32_32x32x16_bf16 v[112:127], v[172:175], v[228:231], v[112:127]
	v_mfma_f32_32x32x16_bf16 v[48:63], v[224:227], v[228:231], v[48:63]
	s_waitcnt lgkmcnt(0)
	v_mfma_f32_32x32x16_bf16 v[96:111], v[172:175], v[232:235], v[96:111]
	v_mfma_f32_32x32x16_bf16 v[32:47], v[224:227], v[232:235], v[32:47]
	ds_read_b128 v[228:231], v168 offset:9280
	ds_read_b128 v[232:235], v168 offset:13888
	s_waitcnt vmcnt(7)
	ds_write_b128 v191, v[158:161] offset:27648
	s_waitcnt vmcnt(6)
	ds_write_b128 v191, v[162:165] offset:64512
	ds_read_b128 v[158:161], v169 offset:96
	ds_read_b128 v[162:165], v169 offset:4704
	s_waitcnt lgkmcnt(5)
	v_mfma_f32_32x32x16_bf16 v[80:95], v[172:175], v[228:231], v[80:95]
	v_mfma_f32_32x32x16_bf16 v[16:31], v[224:227], v[228:231], v[16:31]
	ds_read_b128 v[228:231], v168 offset:96
	s_waitcnt lgkmcnt(5)
	v_mfma_f32_32x32x16_bf16 v[64:79], v[172:175], v[232:235], v[64:79]
	v_mfma_f32_32x32x16_bf16 v[0:15], v[224:227], v[232:235], v[0:15]
	ds_read_b128 v[232:235], v168 offset:4704
	global_load_dwordx4 v[172:175], v[152:153], off offset:896
	global_load_dwordx4 v[224:227], v[156:157], off offset:896
	s_waitcnt lgkmcnt(1)
	v_mfma_f32_32x32x16_bf16 v[112:127], v[158:161], v[228:231], v[112:127]
	v_mfma_f32_32x32x16_bf16 v[48:63], v[162:165], v[228:231], v[48:63]
	s_waitcnt lgkmcnt(0)
	v_mfma_f32_32x32x16_bf16 v[96:111], v[158:161], v[232:235], v[96:111]
	v_mfma_f32_32x32x16_bf16 v[32:47], v[162:165], v[232:235], v[32:47]
	ds_read_b128 v[228:231], v168 offset:9312
	ds_read_b128 v[232:235], v168 offset:13920
	s_waitcnt lgkmcnt(1)
	v_mfma_f32_32x32x16_bf16 v[80:95], v[158:161], v[228:231], v[80:95]
	v_mfma_f32_32x32x16_bf16 v[16:31], v[162:165], v[228:231], v[16:31]
	s_waitcnt lgkmcnt(0)
	v_mfma_f32_32x32x16_bf16 v[64:79], v[158:161], v[232:235], v[64:79]
	v_mfma_f32_32x32x16_bf16 v[0:15], v[162:165], v[232:235], v[0:15]
	s_setprio 0
	s_barrier
; template <bool trans>
; DI void gemm_core(const GTile& tl, const GTile& nx, bool has_next  , bool chain  , bool pre, u32x4 (&ra)[4], u32x4 (&rb)[4], char* smem, f32x16 (&acc)[2][4]) {
;     ...
;   const int nk = K / 64;
;   if (!pre) { G_LOAD(0); G_STORE(0); G_LOAD(1); }
;   for (int kt = 0; kt < nk; ++kt) {
;     __syncthreads();
;     G_COMPUTE(kt & 1, kt);
;   }
	global_load_dwordx4 v[158:161], v[128:129], off offset:1024
	global_load_dwordx4 v[162:165], v[132:133], off offset:1024
	s_waitcnt vmcnt(9)
	ds_write_b128 v195, v[200:203]
	s_waitcnt vmcnt(8)
	ds_write_b128 v196, v[208:211]
	ds_read_b128 v[200:203], v192 offset:36864
	ds_read_b128 v[208:211], v192 offset:41472
	ds_read_b128 v[228:231], v184
	ds_read_b128 v[232:235], v184 offset:4608
	s_setprio 1
	s_waitcnt lgkmcnt(1)
	v_mfma_f32_32x32x16_bf16 v[112:127], v[200:203], v[228:231], v[112:127]
	v_mfma_f32_32x32x16_bf16 v[48:63], v[208:211], v[228:231], v[48:63]
	s_waitcnt lgkmcnt(0)
	v_mfma_f32_32x32x16_bf16 v[96:111], v[200:203], v[232:235], v[96:111]
	v_mfma_f32_32x32x16_bf16 v[32:47], v[208:211], v[232:235], v[32:47]
	ds_read_b128 v[228:231], v184 offset:9216
	ds_read_b128 v[232:235], v184 offset:13824
	s_waitcnt vmcnt(7)
	ds_write_b128 v194, v[212:215]
	s_waitcnt vmcnt(6)
	ds_write_b128 v193, v[216:219]
	ds_read_b128 v[212:215], v192 offset:36896
	ds_read_b128 v[216:219], v192 offset:41504
	s_waitcnt lgkmcnt(5)
	v_mfma_f32_32x32x16_bf16 v[80:95], v[200:203], v[228:231], v[80:95]
	v_mfma_f32_32x32x16_bf16 v[16:31], v[208:211], v[228:231], v[16:31]
	ds_read_b128 v[228:231], v184 offset:32
	s_waitcnt lgkmcnt(5)
	v_mfma_f32_32x32x16_bf16 v[64:79], v[200:203], v[232:235], v[64:79]
	v_mfma_f32_32x32x16_bf16 v[0:15], v[208:211], v[232:235], v[0:15]
	ds_read_b128 v[232:235], v184 offset:4640
	global_load_dwordx4 v[200:203], v[136:137], off offset:1024
	global_load_dwordx4 v[208:211], v[140:141], off offset:1024
	s_waitcnt lgkmcnt(1)
	v_mfma_f32_32x32x16_bf16 v[112:127], v[212:215], v[228:231], v[112:127]
	v_mfma_f32_32x32x16_bf16 v[48:63], v[216:219], v[228:231], v[48:63]
	s_waitcnt lgkmcnt(0)
	v_mfma_f32_32x32x16_bf16 v[96:111], v[212:215], v[232:235], v[96:111]
	v_mfma_f32_32x32x16_bf16 v[32:47], v[216:219], v[232:235], v[32:47]
	ds_read_b128 v[228:231], v184 offset:9248
	ds_read_b128 v[232:235], v184 offset:13856
	s_waitcnt vmcnt(7)
	ds_write_b128 v177, v[178:181]
	s_waitcnt vmcnt(6)
	ds_write_b128 v176, v[220:223]
	ds_read_b128 v[178:181], v192 offset:36928
	ds_read_b128 v[220:223], v192 offset:41536
	s_waitcnt lgkmcnt(5)
	v_mfma_f32_32x32x16_bf16 v[80:95], v[212:215], v[228:231], v[80:95]
	v_mfma_f32_32x32x16_bf16 v[16:31], v[216:219], v[228:231], v[16:31]
	ds_read_b128 v[228:231], v184 offset:64
	s_waitcnt lgkmcnt(5)
	v_mfma_f32_32x32x16_bf16 v[64:79], v[212:215], v[232:235], v[64:79]
	v_mfma_f32_32x32x16_bf16 v[0:15], v[216:219], v[232:235], v[0:15]
	ds_read_b128 v[232:235], v184 offset:4672
	global_load_dwordx4 v[212:215], v[144:145], off offset:1024
	global_load_dwordx4 v[216:219], v[148:149], off offset:1024
	s_waitcnt lgkmcnt(1)
	v_mfma_f32_32x32x16_bf16 v[112:127], v[178:181], v[228:231], v[112:127]
	v_mfma_f32_32x32x16_bf16 v[48:63], v[220:223], v[228:231], v[48:63]
	s_waitcnt lgkmcnt(0)
	v_mfma_f32_32x32x16_bf16 v[96:111], v[178:181], v[232:235], v[96:111]
	v_mfma_f32_32x32x16_bf16 v[32:47], v[220:223], v[232:235], v[32:47]
	ds_read_b128 v[228:231], v184 offset:9280
	ds_read_b128 v[232:235], v184 offset:13888
	s_waitcnt vmcnt(7)
	ds_write_b128 v171, v[172:175]
	s_waitcnt vmcnt(6)
	ds_write_b128 v170, v[224:227]
	ds_read_b128 v[172:175], v192 offset:36960
	ds_read_b128 v[224:227], v192 offset:41568
	s_waitcnt lgkmcnt(5)
	v_mfma_f32_32x32x16_bf16 v[80:95], v[178:181], v[228:231], v[80:95]
	v_mfma_f32_32x32x16_bf16 v[16:31], v[220:223], v[228:231], v[16:31]
	ds_read_b128 v[228:231], v184 offset:96
	s_waitcnt lgkmcnt(5)
	v_mfma_f32_32x32x16_bf16 v[64:79], v[178:181], v[232:235], v[64:79]
	v_mfma_f32_32x32x16_bf16 v[0:15], v[220:223], v[232:235], v[0:15]
	ds_read_b128 v[232:235], v184 offset:4704
	global_load_dwordx4 v[178:181], v[152:153], off offset:1024
	global_load_dwordx4 v[220:223], v[156:157], off offset:1024
	s_waitcnt lgkmcnt(1)
	v_mfma_f32_32x32x16_bf16 v[112:127], v[172:175], v[228:231], v[112:127]
	v_mfma_f32_32x32x16_bf16 v[48:63], v[224:227], v[228:231], v[48:63]
	s_waitcnt lgkmcnt(0)
	v_mfma_f32_32x32x16_bf16 v[96:111], v[172:175], v[232:235], v[96:111]
	v_mfma_f32_32x32x16_bf16 v[32:47], v[224:227], v[232:235], v[32:47]
	ds_read_b128 v[228:231], v184 offset:9312
	ds_read_b128 v[232:235], v184 offset:13920
	s_waitcnt lgkmcnt(1)
	v_mfma_f32_32x32x16_bf16 v[80:95], v[172:175], v[228:231], v[80:95]
	v_mfma_f32_32x32x16_bf16 v[16:31], v[224:227], v[228:231], v[16:31]
	s_waitcnt lgkmcnt(0)
	v_mfma_f32_32x32x16_bf16 v[64:79], v[172:175], v[232:235], v[64:79]
	v_mfma_f32_32x32x16_bf16 v[0:15], v[224:227], v[232:235], v[0:15]
	s_setprio 0
	s_barrier
; template <bool trans>
; DI void gemm_core(const GTile& tl, const GTile& nx, bool has_next  , bool chain  , bool pre, u32x4 (&ra)[4], u32x4 (&rb)[4], char* smem, f32x16 (&acc)[2][4]) {
;     ...
;   const int nk = K / 64;
;   if (!pre) { G_LOAD(0); G_STORE(0); G_LOAD(1); }
;   for (int kt = 0; kt < nk; ++kt) {
;     __syncthreads();
;     G_COMPUTE(kt & 1, kt);
;   }
	global_load_dwordx4 v[172:175], v[128:129], off offset:1152
	global_load_dwordx4 v[224:227], v[132:133], off offset:1152
	s_waitcnt vmcnt(9)
	ds_write_b128 v191, v[158:161]
	s_waitcnt vmcnt(8)
	ds_write_b128 v191, v[162:165] offset:36864
	ds_read_b128 v[158:161], v169
	ds_read_b128 v[162:165], v169 offset:4608
	ds_read_b128 v[228:231], v168
	ds_read_b128 v[232:235], v168 offset:4608
	s_setprio 1
	s_waitcnt lgkmcnt(1)
	v_mfma_f32_32x32x16_bf16 v[112:127], v[158:161], v[228:231], v[112:127]
	v_mfma_f32_32x32x16_bf16 v[48:63], v[162:165], v[228:231], v[48:63]
	s_waitcnt lgkmcnt(0)
	v_mfma_f32_32x32x16_bf16 v[96:111], v[158:161], v[232:235], v[96:111]
	v_mfma_f32_32x32x16_bf16 v[32:47], v[162:165], v[232:235], v[32:47]
	ds_read_b128 v[228:231], v168 offset:9216
	ds_read_b128 v[232:235], v168 offset:13824
	s_waitcnt vmcnt(7)
	ds_write_b128 v191, v[200:203] offset:9216
	s_waitcnt vmcnt(6)
	ds_write_b128 v191, v[208:211] offset:46080
	ds_read_b128 v[200:203], v169 offset:32
	ds_read_b128 v[208:211], v169 offset:4640
	s_waitcnt lgkmcnt(5)
	v_mfma_f32_32x32x16_bf16 v[80:95], v[158:161], v[228:231], v[80:95]
	v_mfma_f32_32x32x16_bf16 v[16:31], v[162:165], v[228:231], v[16:31]
	ds_read_b128 v[228:231], v168 offset:32
	s_waitcnt lgkmcnt(5)
	v_mfma_f32_32x32x16_bf16 v[64:79], v[158:161], v[232:235], v[64:79]
	v_mfma_f32_32x32x16_bf16 v[0:15], v[162:165], v[232:235], v[0:15]
	ds_read_b128 v[232:235], v168 offset:4640
	global_load_dwordx4 v[158:161], v[136:137], off offset:1152
	global_load_dwordx4 v[162:165], v[140:141], off offset:1152
	s_waitcnt lgkmcnt(1)
	v_mfma_f32_32x32x16_bf16 v[112:127], v[200:203], v[228:231], v[112:127]
	v_mfma_f32_32x32x16_bf16 v[48:63], v[208:211], v[228:231], v[48:63]
	s_waitcnt lgkmcnt(0)
	v_mfma_f32_32x32x16_bf16 v[96:111], v[200:203], v[232:235], v[96:111]
	v_mfma_f32_32x32x16_bf16 v[32:47], v[208:211], v[232:235], v[32:47]
	ds_read_b128 v[228:231], v168 offset:9248
	ds_read_b128 v[232:235], v168 offset:13856
	s_waitcnt vmcnt(7)
	ds_write_b128 v191, v[212:215] offset:18432
	s_waitcnt vmcnt(6)
	ds_write_b128 v191, v[216:219] offset:55296
	ds_read_b128 v[212:215], v169 offset:64
	ds_read_b128 v[216:219], v169 offset:4672
	s_waitcnt lgkmcnt(5)
	v_mfma_f32_32x32x16_bf16 v[80:95], v[200:203], v[228:231], v[80:95]
	v_mfma_f32_32x32x16_bf16 v[16:31], v[208:211], v[228:231], v[16:31]
	ds_read_b128 v[228:231], v168 offset:64
	s_waitcnt lgkmcnt(5)
	v_mfma_f32_32x32x16_bf16 v[64:79], v[200:203], v[232:235], v[64:79]
	v_mfma_f32_32x32x16_bf16 v[0:15], v[208:211], v[232:235], v[0:15]
	ds_read_b128 v[232:235], v168 offset:4672
	global_load_dwordx4 v[200:203], v[144:145], off offset:1152
	global_load_dwordx4 v[208:211], v[148:149], off offset:1152
	s_waitcnt lgkmcnt(1)
	v_mfma_f32_32x32x16_bf16 v[112:127], v[212:215], v[228:231], v[112:127]
	v_mfma_f32_32x32x16_bf16 v[48:63], v[216:219], v[228:231], v[48:63]
	s_waitcnt lgkmcnt(0)
	v_mfma_f32_32x32x16_bf16 v[96:111], v[212:215], v[232:235], v[96:111]
	v_mfma_f32_32x32x16_bf16 v[32:47], v[216:219], v[232:235], v[32:47]
	ds_read_b128 v[228:231], v168 offset:9280
	ds_read_b128 v[232:235], v168 offset:13888
	s_waitcnt vmcnt(7)
	ds_write_b128 v191, v[178:181] offset:27648
	s_waitcnt vmcnt(6)
	ds_write_b128 v191, v[220:223] offset:64512
	ds_read_b128 v[178:181], v169 offset:96
	ds_read_b128 v[220:223], v169 offset:4704
	s_waitcnt lgkmcnt(5)
	v_mfma_f32_32x32x16_bf16 v[80:95], v[212:215], v[228:231], v[80:95]
	v_mfma_f32_32x32x16_bf16 v[16:31], v[216:219], v[228:231], v[16:31]
	ds_read_b128 v[228:231], v168 offset:96
	s_waitcnt lgkmcnt(5)
	v_mfma_f32_32x32x16_bf16 v[64:79], v[212:215], v[232:235], v[64:79]
	v_mfma_f32_32x32x16_bf16 v[0:15], v[216:219], v[232:235], v[0:15]
	ds_read_b128 v[232:235], v168 offset:4704
	global_load_dwordx4 v[212:215], v[152:153], off offset:1152
	global_load_dwordx4 v[216:219], v[156:157], off offset:1152
	s_waitcnt lgkmcnt(1)
	v_mfma_f32_32x32x16_bf16 v[112:127], v[178:181], v[228:231], v[112:127]
	v_mfma_f32_32x32x16_bf16 v[48:63], v[220:223], v[228:231], v[48:63]
	s_waitcnt lgkmcnt(0)
	v_mfma_f32_32x32x16_bf16 v[96:111], v[178:181], v[232:235], v[96:111]
	v_mfma_f32_32x32x16_bf16 v[32:47], v[220:223], v[232:235], v[32:47]
	ds_read_b128 v[228:231], v168 offset:9312
	ds_read_b128 v[232:235], v168 offset:13920
	s_waitcnt lgkmcnt(1)
	v_mfma_f32_32x32x16_bf16 v[80:95], v[178:181], v[228:231], v[80:95]
	v_mfma_f32_32x32x16_bf16 v[16:31], v[220:223], v[228:231], v[16:31]
	s_waitcnt lgkmcnt(0)
	v_mfma_f32_32x32x16_bf16 v[64:79], v[178:181], v[232:235], v[64:79]
	v_mfma_f32_32x32x16_bf16 v[0:15], v[220:223], v[232:235], v[0:15]
	s_setprio 0
	s_barrier
; template <bool trans>
; DI void gemm_core(const GTile& tl, const GTile& nx, bool has_next  , bool chain  , bool pre, u32x4 (&ra)[4], u32x4 (&rb)[4], char* smem, f32x16 (&acc)[2][4]) {
;     ...
;   const int nk = K / 64;
;   if (!pre) { G_LOAD(0); G_STORE(0); G_LOAD(1); }
;   for (int kt = 0; kt < nk; ++kt) {
;     __syncthreads();
;     G_COMPUTE(kt & 1, kt);
;   }
	global_load_dwordx4 v[178:181], v[128:129], off offset:1280
	global_load_dwordx4 v[220:223], v[132:133], off offset:1280
	s_waitcnt vmcnt(9)
	ds_write_b128 v195, v[172:175]
	s_waitcnt vmcnt(8)
	ds_write_b128 v196, v[224:227]
	ds_read_b128 v[172:175], v192 offset:36864
	ds_read_b128 v[224:227], v192 offset:41472
	ds_read_b128 v[228:231], v184
	ds_read_b128 v[232:235], v184 offset:4608
	s_setprio 1
	s_waitcnt lgkmcnt(1)
	v_mfma_f32_32x32x16_bf16 v[112:127], v[172:175], v[228:231], v[112:127]
	v_mfma_f32_32x32x16_bf16 v[48:63], v[224:227], v[228:231], v[48:63]
	s_waitcnt lgkmcnt(0)
	v_mfma_f32_32x32x16_bf16 v[96:111], v[172:175], v[232:235], v[96:111]
	v_mfma_f32_32x32x16_bf16 v[32:47], v[224:227], v[232:235], v[32:47]
	ds_read_b128 v[228:231], v184 offset:9216
	ds_read_b128 v[232:235], v184 offset:13824
	s_waitcnt vmcnt(7)
	ds_write_b128 v194, v[158:161]
	s_waitcnt vmcnt(6)
	ds_write_b128 v193, v[162:165]
	ds_read_b128 v[158:161], v192 offset:36896
	ds_read_b128 v[162:165], v192 offset:41504
	s_waitcnt lgkmcnt(5)
	v_mfma_f32_32x32x16_bf16 v[80:95], v[172:175], v[228:231], v[80:95]
	v_mfma_f32_32x32x16_bf16 v[16:31], v[224:227], v[228:231], v[16:31]
	ds_read_b128 v[228:231], v184 offset:32
	s_waitcnt lgkmcnt(5)
	v_mfma_f32_32x32x16_bf16 v[64:79], v[172:175], v[232:235], v[64:79]
	v_mfma_f32_32x32x16_bf16 v[0:15], v[224:227], v[232:235], v[0:15]
	ds_read_b128 v[232:235], v184 offset:4640
	global_load_dwordx4 v[172:175], v[136:137], off offset:1280
	global_load_dwordx4 v[224:227], v[140:141], off offset:1280
	s_waitcnt lgkmcnt(1)
	v_mfma_f32_32x32x16_bf16 v[112:127], v[158:161], v[228:231], v[112:127]
	v_mfma_f32_32x32x16_bf16 v[48:63], v[162:165], v[228:231], v[48:63]
	s_waitcnt lgkmcnt(0)
	v_mfma_f32_32x32x16_bf16 v[96:111], v[158:161], v[232:235], v[96:111]
	v_mfma_f32_32x32x16_bf16 v[32:47], v[162:165], v[232:235], v[32:47]
	ds_read_b128 v[228:231], v184 offset:9248
	ds_read_b128 v[232:235], v184 offset:13856
	s_waitcnt vmcnt(7)
	ds_write_b128 v177, v[200:203]
	s_waitcnt vmcnt(6)
	ds_write_b128 v176, v[208:211]
	ds_read_b128 v[200:203], v192 offset:36928
	ds_read_b128 v[208:211], v192 offset:41536
	s_waitcnt lgkmcnt(5)
	v_mfma_f32_32x32x16_bf16 v[80:95], v[158:161], v[228:231], v[80:95]
	v_mfma_f32_32x32x16_bf16 v[16:31], v[162:165], v[228:231], v[16:31]
	ds_read_b128 v[228:231], v184 offset:64
	s_waitcnt lgkmcnt(5)
	v_mfma_f32_32x32x16_bf16 v[64:79], v[158:161], v[232:235], v[64:79]
	v_mfma_f32_32x32x16_bf16 v[0:15], v[162:165], v[232:235], v[0:15]
	ds_read_b128 v[232:235], v184 offset:4672
	global_load_dwordx4 v[158:161], v[144:145], off offset:1280
	global_load_dwordx4 v[162:165], v[148:149], off offset:1280
	s_waitcnt lgkmcnt(1)
	v_mfma_f32_32x32x16_bf16 v[112:127], v[200:203], v[228:231], v[112:127]
	v_mfma_f32_32x32x16_bf16 v[48:63], v[208:211], v[228:231], v[48:63]
	s_waitcnt lgkmcnt(0)
	v_mfma_f32_32x32x16_bf16 v[96:111], v[200:203], v[232:235], v[96:111]
	v_mfma_f32_32x32x16_bf16 v[32:47], v[208:211], v[232:235], v[32:47]
	ds_read_b128 v[228:231], v184 offset:9280
	ds_read_b128 v[232:235], v184 offset:13888
	s_waitcnt vmcnt(7)
	ds_write_b128 v171, v[212:215]
	s_waitcnt vmcnt(6)
	ds_write_b128 v170, v[216:219]
	ds_read_b128 v[212:215], v192 offset:36960
	ds_read_b128 v[216:219], v192 offset:41568
	s_waitcnt lgkmcnt(5)
	v_mfma_f32_32x32x16_bf16 v[80:95], v[200:203], v[228:231], v[80:95]
	v_mfma_f32_32x32x16_bf16 v[16:31], v[208:211], v[228:231], v[16:31]
	ds_read_b128 v[228:231], v184 offset:96
	s_waitcnt lgkmcnt(5)
	v_mfma_f32_32x32x16_bf16 v[64:79], v[200:203], v[232:235], v[64:79]
	v_mfma_f32_32x32x16_bf16 v[0:15], v[208:211], v[232:235], v[0:15]
	ds_read_b128 v[232:235], v184 offset:4704
	global_load_dwordx4 v[200:203], v[152:153], off offset:1280
	global_load_dwordx4 v[208:211], v[156:157], off offset:1280
	s_waitcnt lgkmcnt(1)
	v_mfma_f32_32x32x16_bf16 v[112:127], v[212:215], v[228:231], v[112:127]
	v_mfma_f32_32x32x16_bf16 v[48:63], v[216:219], v[228:231], v[48:63]
	s_waitcnt lgkmcnt(0)
	v_mfma_f32_32x32x16_bf16 v[96:111], v[212:215], v[232:235], v[96:111]
	v_mfma_f32_32x32x16_bf16 v[32:47], v[216:219], v[232:235], v[32:47]
	ds_read_b128 v[228:231], v184 offset:9312
	ds_read_b128 v[232:235], v184 offset:13920
	s_waitcnt lgkmcnt(1)
	v_mfma_f32_32x32x16_bf16 v[80:95], v[212:215], v[228:231], v[80:95]
	v_mfma_f32_32x32x16_bf16 v[16:31], v[216:219], v[228:231], v[16:31]
	s_waitcnt lgkmcnt(0)
	v_mfma_f32_32x32x16_bf16 v[64:79], v[212:215], v[232:235], v[64:79]
	v_mfma_f32_32x32x16_bf16 v[0:15], v[216:219], v[232:235], v[0:15]
	s_setprio 0
	s_barrier
; template <bool trans>
; DI void gemm_core(const GTile& tl, const GTile& nx, bool has_next  , bool chain  , bool pre, u32x4 (&ra)[4], u32x4 (&rb)[4], char* smem, f32x16 (&acc)[2][4]) {
;     ...
;   const int nk = K / 64;
;   if (!pre) { G_LOAD(0); G_STORE(0); G_LOAD(1); }
;   for (int kt = 0; kt < nk; ++kt) {
;     __syncthreads();
;     G_COMPUTE(kt & 1, kt);
;   }
	global_load_dwordx4 v[212:215], v[128:129], off offset:1408
	global_load_dwordx4 v[216:219], v[132:133], off offset:1408
	s_waitcnt vmcnt(9)
	ds_write_b128 v191, v[178:181]
	s_waitcnt vmcnt(8)
	ds_write_b128 v191, v[220:223] offset:36864
	ds_read_b128 v[178:181], v169
	ds_read_b128 v[220:223], v169 offset:4608
	ds_read_b128 v[228:231], v168
	ds_read_b128 v[232:235], v168 offset:4608
	s_setprio 1
	s_waitcnt lgkmcnt(1)
	v_mfma_f32_32x32x16_bf16 v[112:127], v[178:181], v[228:231], v[112:127]
	v_mfma_f32_32x32x16_bf16 v[48:63], v[220:223], v[228:231], v[48:63]
	s_waitcnt lgkmcnt(0)
	v_mfma_f32_32x32x16_bf16 v[96:111], v[178:181], v[232:235], v[96:111]
	v_mfma_f32_32x32x16_bf16 v[32:47], v[220:223], v[232:235], v[32:47]
	ds_read_b128 v[228:231], v168 offset:9216
	ds_read_b128 v[232:235], v168 offset:13824
	s_waitcnt vmcnt(7)
	ds_write_b128 v191, v[172:175] offset:9216
	s_waitcnt vmcnt(6)
	ds_write_b128 v191, v[224:227] offset:46080
	ds_read_b128 v[172:175], v169 offset:32
	ds_read_b128 v[224:227], v169 offset:4640
	s_waitcnt lgkmcnt(5)
	v_mfma_f32_32x32x16_bf16 v[80:95], v[178:181], v[228:231], v[80:95]
	v_mfma_f32_32x32x16_bf16 v[16:31], v[220:223], v[228:231], v[16:31]
	ds_read_b128 v[228:231], v168 offset:32
	s_waitcnt lgkmcnt(5)
	v_mfma_f32_32x32x16_bf16 v[64:79], v[178:181], v[232:235], v[64:79]
	v_mfma_f32_32x32x16_bf16 v[0:15], v[220:223], v[232:235], v[0:15]
	ds_read_b128 v[232:235], v168 offset:4640
	global_load_dwordx4 v[178:181], v[136:137], off offset:1408
	global_load_dwordx4 v[220:223], v[140:141], off offset:1408
	s_waitcnt lgkmcnt(1)
	v_mfma_f32_32x32x16_bf16 v[112:127], v[172:175], v[228:231], v[112:127]
	v_mfma_f32_32x32x16_bf16 v[48:63], v[224:227], v[228:231], v[48:63]
	s_waitcnt lgkmcnt(0)
	v_mfma_f32_32x32x16_bf16 v[96:111], v[172:175], v[232:235], v[96:111]
	v_mfma_f32_32x32x16_bf16 v[32:47], v[224:227], v[232:235], v[32:47]
	ds_read_b128 v[228:231], v168 offset:9248
	ds_read_b128 v[232:235], v168 offset:13856
	s_waitcnt vmcnt(7)
	ds_write_b128 v191, v[158:161] offset:18432
	s_waitcnt vmcnt(6)
	ds_write_b128 v191, v[162:165] offset:55296
	ds_read_b128 v[158:161], v169 offset:64
	ds_read_b128 v[162:165], v169 offset:4672
	s_waitcnt lgkmcnt(5)
	v_mfma_f32_32x32x16_bf16 v[80:95], v[172:175], v[228:231], v[80:95]
	v_mfma_f32_32x32x16_bf16 v[16:31], v[224:227], v[228:231], v[16:31]
	ds_read_b128 v[228:231], v168 offset:64
	s_waitcnt lgkmcnt(5)
	v_mfma_f32_32x32x16_bf16 v[64:79], v[172:175], v[232:235], v[64:79]
	v_mfma_f32_32x32x16_bf16 v[0:15], v[224:227], v[232:235], v[0:15]
	ds_read_b128 v[232:235], v168 offset:4672
	global_load_dwordx4 v[172:175], v[144:145], off offset:1408
	global_load_dwordx4 v[224:227], v[148:149], off offset:1408
	s_waitcnt lgkmcnt(1)
	v_mfma_f32_32x32x16_bf16 v[112:127], v[158:161], v[228:231], v[112:127]
	v_mfma_f32_32x32x16_bf16 v[48:63], v[162:165], v[228:231], v[48:63]
	s_waitcnt lgkmcnt(0)
	v_mfma_f32_32x32x16_bf16 v[96:111], v[158:161], v[232:235], v[96:111]
	v_mfma_f32_32x32x16_bf16 v[32:47], v[162:165], v[232:235], v[32:47]
	ds_read_b128 v[228:231], v168 offset:9280
	ds_read_b128 v[232:235], v168 offset:13888
	s_waitcnt vmcnt(7)
	ds_write_b128 v191, v[200:203] offset:27648
	s_waitcnt vmcnt(6)
	ds_write_b128 v191, v[208:211] offset:64512
	ds_read_b128 v[200:203], v169 offset:96
	ds_read_b128 v[208:211], v169 offset:4704
	s_waitcnt lgkmcnt(5)
	v_mfma_f32_32x32x16_bf16 v[80:95], v[158:161], v[228:231], v[80:95]
	v_mfma_f32_32x32x16_bf16 v[16:31], v[162:165], v[228:231], v[16:31]
	ds_read_b128 v[228:231], v168 offset:96
	s_waitcnt lgkmcnt(5)
	v_mfma_f32_32x32x16_bf16 v[64:79], v[158:161], v[232:235], v[64:79]
	v_mfma_f32_32x32x16_bf16 v[0:15], v[162:165], v[232:235], v[0:15]
	ds_read_b128 v[232:235], v168 offset:4704
	global_load_dwordx4 v[158:161], v[152:153], off offset:1408
	global_load_dwordx4 v[162:165], v[156:157], off offset:1408
	s_waitcnt lgkmcnt(1)
	v_mfma_f32_32x32x16_bf16 v[112:127], v[200:203], v[228:231], v[112:127]
	v_mfma_f32_32x32x16_bf16 v[48:63], v[208:211], v[228:231], v[48:63]
	s_waitcnt lgkmcnt(0)
	v_mfma_f32_32x32x16_bf16 v[96:111], v[200:203], v[232:235], v[96:111]
	v_mfma_f32_32x32x16_bf16 v[32:47], v[208:211], v[232:235], v[32:47]
	ds_read_b128 v[228:231], v168 offset:9312
	ds_read_b128 v[232:235], v168 offset:13920
	s_waitcnt lgkmcnt(1)
	v_mfma_f32_32x32x16_bf16 v[80:95], v[200:203], v[228:231], v[80:95]
	v_mfma_f32_32x32x16_bf16 v[16:31], v[208:211], v[228:231], v[16:31]
	s_waitcnt lgkmcnt(0)
	v_mfma_f32_32x32x16_bf16 v[64:79], v[200:203], v[232:235], v[64:79]
	v_mfma_f32_32x32x16_bf16 v[0:15], v[208:211], v[232:235], v[0:15]
	s_setprio 0
	s_barrier
; template <bool trans>
; DI void gemm_core(const GTile& tl, const GTile& nx, bool has_next  , bool chain  , bool pre, u32x4 (&ra)[4], u32x4 (&rb)[4], char* smem, f32x16 (&acc)[2][4]) {
;     ...
;   const int nk = K / 64;
;   if (!pre) { G_LOAD(0); G_STORE(0); G_LOAD(1); }
;   for (int kt = 0; kt < nk; ++kt) {
;     __syncthreads();
;     G_COMPUTE(kt & 1, kt);
;   }
	global_load_dwordx4 v[200:203], v[128:129], off offset:1536
	global_load_dwordx4 v[208:211], v[132:133], off offset:1536
	s_waitcnt vmcnt(9)
	ds_write_b128 v195, v[212:215]
	s_waitcnt vmcnt(8)
	ds_write_b128 v196, v[216:219]
	ds_read_b128 v[212:215], v192 offset:36864
	ds_read_b128 v[216:219], v192 offset:41472
	ds_read_b128 v[228:231], v184
	ds_read_b128 v[232:235], v184 offset:4608
	s_setprio 1
	s_waitcnt lgkmcnt(1)
	v_mfma_f32_32x32x16_bf16 v[112:127], v[212:215], v[228:231], v[112:127]
	v_mfma_f32_32x32x16_bf16 v[48:63], v[216:219], v[228:231], v[48:63]
	s_waitcnt lgkmcnt(0)
	v_mfma_f32_32x32x16_bf16 v[96:111], v[212:215], v[232:235], v[96:111]
	v_mfma_f32_32x32x16_bf16 v[32:47], v[216:219], v[232:235], v[32:47]
	ds_read_b128 v[228:231], v184 offset:9216
	ds_read_b128 v[232:235], v184 offset:13824
	s_waitcnt vmcnt(7)
	ds_write_b128 v194, v[178:181]
	s_waitcnt vmcnt(6)
	ds_write_b128 v193, v[220:223]
	ds_read_b128 v[178:181], v192 offset:36896
	ds_read_b128 v[220:223], v192 offset:41504
	s_waitcnt lgkmcnt(5)
	v_mfma_f32_32x32x16_bf16 v[80:95], v[212:215], v[228:231], v[80:95]
	v_mfma_f32_32x32x16_bf16 v[16:31], v[216:219], v[228:231], v[16:31]
	ds_read_b128 v[228:231], v184 offset:32
	s_waitcnt lgkmcnt(5)
	v_mfma_f32_32x32x16_bf16 v[64:79], v[212:215], v[232:235], v[64:79]
	v_mfma_f32_32x32x16_bf16 v[0:15], v[216:219], v[232:235], v[0:15]
	ds_read_b128 v[232:235], v184 offset:4640
	global_load_dwordx4 v[212:215], v[136:137], off offset:1536
	global_load_dwordx4 v[216:219], v[140:141], off offset:1536
	s_waitcnt lgkmcnt(1)
	v_mfma_f32_32x32x16_bf16 v[112:127], v[178:181], v[228:231], v[112:127]
	v_mfma_f32_32x32x16_bf16 v[48:63], v[220:223], v[228:231], v[48:63]
	s_waitcnt lgkmcnt(0)
	v_mfma_f32_32x32x16_bf16 v[96:111], v[178:181], v[232:235], v[96:111]
	v_mfma_f32_32x32x16_bf16 v[32:47], v[220:223], v[232:235], v[32:47]
	ds_read_b128 v[228:231], v184 offset:9248
	ds_read_b128 v[232:235], v184 offset:13856
	s_waitcnt vmcnt(7)
	ds_write_b128 v177, v[172:175]
	s_waitcnt vmcnt(6)
	ds_write_b128 v176, v[224:227]
	ds_read_b128 v[172:175], v192 offset:36928
	ds_read_b128 v[224:227], v192 offset:41536
	s_waitcnt lgkmcnt(5)
	v_mfma_f32_32x32x16_bf16 v[80:95], v[178:181], v[228:231], v[80:95]
	v_mfma_f32_32x32x16_bf16 v[16:31], v[220:223], v[228:231], v[16:31]
	ds_read_b128 v[228:231], v184 offset:64
	s_waitcnt lgkmcnt(5)
	v_mfma_f32_32x32x16_bf16 v[64:79], v[178:181], v[232:235], v[64:79]
	v_mfma_f32_32x32x16_bf16 v[0:15], v[220:223], v[232:235], v[0:15]
	ds_read_b128 v[232:235], v184 offset:4672
	global_load_dwordx4 v[178:181], v[144:145], off offset:1536
	global_load_dwordx4 v[220:223], v[148:149], off offset:1536
	s_waitcnt lgkmcnt(1)
	v_mfma_f32_32x32x16_bf16 v[112:127], v[172:175], v[228:231], v[112:127]
	v_mfma_f32_32x32x16_bf16 v[48:63], v[224:227], v[228:231], v[48:63]
	s_waitcnt lgkmcnt(0)
	v_mfma_f32_32x32x16_bf16 v[96:111], v[172:175], v[232:235], v[96:111]
	v_mfma_f32_32x32x16_bf16 v[32:47], v[224:227], v[232:235], v[32:47]
	ds_read_b128 v[228:231], v184 offset:9280
	ds_read_b128 v[232:235], v184 offset:13888
	s_waitcnt vmcnt(7)
	ds_write_b128 v171, v[158:161]
	s_waitcnt vmcnt(6)
	ds_write_b128 v170, v[162:165]
	ds_read_b128 v[158:161], v192 offset:36960
	ds_read_b128 v[162:165], v192 offset:41568
	s_waitcnt lgkmcnt(5)
	v_mfma_f32_32x32x16_bf16 v[80:95], v[172:175], v[228:231], v[80:95]
	v_mfma_f32_32x32x16_bf16 v[16:31], v[224:227], v[228:231], v[16:31]
	ds_read_b128 v[228:231], v184 offset:96
	s_waitcnt lgkmcnt(5)
	v_mfma_f32_32x32x16_bf16 v[64:79], v[172:175], v[232:235], v[64:79]
	v_mfma_f32_32x32x16_bf16 v[0:15], v[224:227], v[232:235], v[0:15]
	ds_read_b128 v[232:235], v184 offset:4704
	global_load_dwordx4 v[172:175], v[152:153], off offset:1536
	global_load_dwordx4 v[224:227], v[156:157], off offset:1536
	s_waitcnt lgkmcnt(1)
	v_mfma_f32_32x32x16_bf16 v[112:127], v[158:161], v[228:231], v[112:127]
	v_mfma_f32_32x32x16_bf16 v[48:63], v[162:165], v[228:231], v[48:63]
	s_waitcnt lgkmcnt(0)
	v_mfma_f32_32x32x16_bf16 v[96:111], v[158:161], v[232:235], v[96:111]
	v_mfma_f32_32x32x16_bf16 v[32:47], v[162:165], v[232:235], v[32:47]
	ds_read_b128 v[228:231], v184 offset:9312
	ds_read_b128 v[232:235], v184 offset:13920
	s_waitcnt lgkmcnt(1)
	v_mfma_f32_32x32x16_bf16 v[80:95], v[158:161], v[228:231], v[80:95]
	v_mfma_f32_32x32x16_bf16 v[16:31], v[162:165], v[228:231], v[16:31]
	s_waitcnt lgkmcnt(0)
	v_mfma_f32_32x32x16_bf16 v[64:79], v[158:161], v[232:235], v[64:79]
	v_mfma_f32_32x32x16_bf16 v[0:15], v[162:165], v[232:235], v[0:15]
	s_setprio 0
	s_barrier
; template <bool trans>
; DI void gemm_core(const GTile& tl, const GTile& nx, bool has_next  , bool chain  , bool pre, u32x4 (&ra)[4], u32x4 (&rb)[4], char* smem, f32x16 (&acc)[2][4]) {
;     ...
;   const int nk = K / 64;
;   if (!pre) { G_LOAD(0); G_STORE(0); G_LOAD(1); }
;   for (int kt = 0; kt < nk; ++kt) {
;     __syncthreads();
;     G_COMPUTE(kt & 1, kt);
;   }
	global_load_dwordx4 v[158:161], v[128:129], off offset:1664
	global_load_dwordx4 v[162:165], v[132:133], off offset:1664
	s_waitcnt vmcnt(9)
	ds_write_b128 v191, v[200:203]
	s_waitcnt vmcnt(8)
	ds_write_b128 v191, v[208:211] offset:36864
	ds_read_b128 v[200:203], v169
	ds_read_b128 v[208:211], v169 offset:4608
	ds_read_b128 v[228:231], v168
	ds_read_b128 v[232:235], v168 offset:4608
	s_setprio 1
	s_waitcnt lgkmcnt(1)
	v_mfma_f32_32x32x16_bf16 v[112:127], v[200:203], v[228:231], v[112:127]
	v_mfma_f32_32x32x16_bf16 v[48:63], v[208:211], v[228:231], v[48:63]
	s_waitcnt lgkmcnt(0)
	v_mfma_f32_32x32x16_bf16 v[96:111], v[200:203], v[232:235], v[96:111]
	v_mfma_f32_32x32x16_bf16 v[32:47], v[208:211], v[232:235], v[32:47]
	ds_read_b128 v[228:231], v168 offset:9216
	ds_read_b128 v[232:235], v168 offset:13824
	s_waitcnt vmcnt(7)
	ds_write_b128 v191, v[212:215] offset:9216
	s_waitcnt vmcnt(6)
	ds_write_b128 v191, v[216:219] offset:46080
	ds_read_b128 v[212:215], v169 offset:32
	ds_read_b128 v[216:219], v169 offset:4640
	s_waitcnt lgkmcnt(5)
	v_mfma_f32_32x32x16_bf16 v[80:95], v[200:203], v[228:231], v[80:95]
	v_mfma_f32_32x32x16_bf16 v[16:31], v[208:211], v[228:231], v[16:31]
	ds_read_b128 v[228:231], v168 offset:32
	s_waitcnt lgkmcnt(5)
	v_mfma_f32_32x32x16_bf16 v[64:79], v[200:203], v[232:235], v[64:79]
	v_mfma_f32_32x32x16_bf16 v[0:15], v[208:211], v[232:235], v[0:15]
	ds_read_b128 v[232:235], v168 offset:4640
	global_load_dwordx4 v[200:203], v[136:137], off offset:1664
	global_load_dwordx4 v[208:211], v[140:141], off offset:1664
	s_waitcnt lgkmcnt(1)
	v_mfma_f32_32x32x16_bf16 v[112:127], v[212:215], v[228:231], v[112:127]
	v_mfma_f32_32x32x16_bf16 v[48:63], v[216:219], v[228:231], v[48:63]
	s_waitcnt lgkmcnt(0)
	v_mfma_f32_32x32x16_bf16 v[96:111], v[212:215], v[232:235], v[96:111]
	v_mfma_f32_32x32x16_bf16 v[32:47], v[216:219], v[232:235], v[32:47]
	ds_read_b128 v[228:231], v168 offset:9248
	ds_read_b128 v[232:235], v168 offset:13856
	s_waitcnt vmcnt(7)
	ds_write_b128 v191, v[178:181] offset:18432
	s_waitcnt vmcnt(6)
	ds_write_b128 v191, v[220:223] offset:55296
	ds_read_b128 v[178:181], v169 offset:64
	ds_read_b128 v[220:223], v169 offset:4672
	s_waitcnt lgkmcnt(5)
	v_mfma_f32_32x32x16_bf16 v[80:95], v[212:215], v[228:231], v[80:95]
	v_mfma_f32_32x32x16_bf16 v[16:31], v[216:219], v[228:231], v[16:31]
	ds_read_b128 v[228:231], v168 offset:64
	s_waitcnt lgkmcnt(5)
	v_mfma_f32_32x32x16_bf16 v[64:79], v[212:215], v[232:235], v[64:79]
	v_mfma_f32_32x32x16_bf16 v[0:15], v[216:219], v[232:235], v[0:15]
	ds_read_b128 v[232:235], v168 offset:4672
	global_load_dwordx4 v[212:215], v[144:145], off offset:1664
	global_load_dwordx4 v[216:219], v[148:149], off offset:1664
	s_waitcnt lgkmcnt(1)
	v_mfma_f32_32x32x16_bf16 v[112:127], v[178:181], v[228:231], v[112:127]
	v_mfma_f32_32x32x16_bf16 v[48:63], v[220:223], v[228:231], v[48:63]
	s_waitcnt lgkmcnt(0)
	v_mfma_f32_32x32x16_bf16 v[96:111], v[178:181], v[232:235], v[96:111]
	v_mfma_f32_32x32x16_bf16 v[32:47], v[220:223], v[232:235], v[32:47]
	ds_read_b128 v[228:231], v168 offset:9280
	ds_read_b128 v[232:235], v168 offset:13888
	s_waitcnt vmcnt(7)
	ds_write_b128 v191, v[172:175] offset:27648
	s_waitcnt vmcnt(6)
	ds_write_b128 v191, v[224:227] offset:64512
	ds_read_b128 v[172:175], v169 offset:96
	ds_read_b128 v[224:227], v169 offset:4704
	s_waitcnt lgkmcnt(5)
	v_mfma_f32_32x32x16_bf16 v[80:95], v[178:181], v[228:231], v[80:95]
	v_mfma_f32_32x32x16_bf16 v[16:31], v[220:223], v[228:231], v[16:31]
	ds_read_b128 v[228:231], v168 offset:96
	s_waitcnt lgkmcnt(5)
	v_mfma_f32_32x32x16_bf16 v[64:79], v[178:181], v[232:235], v[64:79]
	v_mfma_f32_32x32x16_bf16 v[0:15], v[220:223], v[232:235], v[0:15]
	ds_read_b128 v[232:235], v168 offset:4704
	global_load_dwordx4 v[178:181], v[152:153], off offset:1664
	global_load_dwordx4 v[220:223], v[156:157], off offset:1664
	s_waitcnt lgkmcnt(1)
	v_mfma_f32_32x32x16_bf16 v[112:127], v[172:175], v[228:231], v[112:127]
	v_mfma_f32_32x32x16_bf16 v[48:63], v[224:227], v[228:231], v[48:63]
	s_waitcnt lgkmcnt(0)
	v_mfma_f32_32x32x16_bf16 v[96:111], v[172:175], v[232:235], v[96:111]
	v_mfma_f32_32x32x16_bf16 v[32:47], v[224:227], v[232:235], v[32:47]
	ds_read_b128 v[228:231], v168 offset:9312
	ds_read_b128 v[232:235], v168 offset:13920
	s_waitcnt lgkmcnt(1)
	v_mfma_f32_32x32x16_bf16 v[80:95], v[172:175], v[228:231], v[80:95]
	v_mfma_f32_32x32x16_bf16 v[16:31], v[224:227], v[228:231], v[16:31]
	s_waitcnt lgkmcnt(0)
	v_mfma_f32_32x32x16_bf16 v[64:79], v[172:175], v[232:235], v[64:79]
	v_mfma_f32_32x32x16_bf16 v[0:15], v[224:227], v[232:235], v[0:15]
	s_setprio 0
	s_barrier
; template <bool trans>
; DI void gemm_core(const GTile& tl, const GTile& nx, bool has_next  , bool chain  , bool pre, u32x4 (&ra)[4], u32x4 (&rb)[4], char* smem, f32x16 (&acc)[2][4]) {
;     ...
;   const int nk = K / 64;
;   if (!pre) { G_LOAD(0); G_STORE(0); G_LOAD(1); }
;   for (int kt = 0; kt < nk; ++kt) {
;     __syncthreads();
;     G_COMPUTE(kt & 1, kt);
;   }
	global_load_dwordx4 v[172:175], v[128:129], off offset:1792
	global_load_dwordx4 v[224:227], v[132:133], off offset:1792
	s_waitcnt vmcnt(9)
	ds_write_b128 v195, v[158:161]
	s_waitcnt vmcnt(8)
	ds_write_b128 v196, v[162:165]
	ds_read_b128 v[158:161], v192 offset:36864
	ds_read_b128 v[162:165], v192 offset:41472
	ds_read_b128 v[228:231], v184
	ds_read_b128 v[232:235], v184 offset:4608
	s_setprio 1
	s_waitcnt lgkmcnt(1)
	v_mfma_f32_32x32x16_bf16 v[112:127], v[158:161], v[228:231], v[112:127]
	v_mfma_f32_32x32x16_bf16 v[48:63], v[162:165], v[228:231], v[48:63]
	s_waitcnt lgkmcnt(0)
	v_mfma_f32_32x32x16_bf16 v[96:111], v[158:161], v[232:235], v[96:111]
	v_mfma_f32_32x32x16_bf16 v[32:47], v[162:165], v[232:235], v[32:47]
	ds_read_b128 v[228:231], v184 offset:9216
	ds_read_b128 v[232:235], v184 offset:13824
	s_waitcnt vmcnt(7)
	ds_write_b128 v194, v[200:203]
	s_waitcnt vmcnt(6)
	ds_write_b128 v193, v[208:211]
	ds_read_b128 v[200:203], v192 offset:36896
	ds_read_b128 v[208:211], v192 offset:41504
	s_waitcnt lgkmcnt(5)
	v_mfma_f32_32x32x16_bf16 v[80:95], v[158:161], v[228:231], v[80:95]
	v_mfma_f32_32x32x16_bf16 v[16:31], v[162:165], v[228:231], v[16:31]
	ds_read_b128 v[228:231], v184 offset:32
	s_waitcnt lgkmcnt(5)
	v_mfma_f32_32x32x16_bf16 v[64:79], v[158:161], v[232:235], v[64:79]
	v_mfma_f32_32x32x16_bf16 v[0:15], v[162:165], v[232:235], v[0:15]
	ds_read_b128 v[232:235], v184 offset:4640
	global_load_dwordx4 v[158:161], v[136:137], off offset:1792
	global_load_dwordx4 v[162:165], v[140:141], off offset:1792
	s_waitcnt lgkmcnt(1)
	v_mfma_f32_32x32x16_bf16 v[112:127], v[200:203], v[228:231], v[112:127]
	v_mfma_f32_32x32x16_bf16 v[48:63], v[208:211], v[228:231], v[48:63]
	s_waitcnt lgkmcnt(0)
	v_mfma_f32_32x32x16_bf16 v[96:111], v[200:203], v[232:235], v[96:111]
	v_mfma_f32_32x32x16_bf16 v[32:47], v[208:211], v[232:235], v[32:47]
	ds_read_b128 v[228:231], v184 offset:9248
	ds_read_b128 v[232:235], v184 offset:13856
	s_waitcnt vmcnt(7)
	ds_write_b128 v177, v[212:215]
	s_waitcnt vmcnt(6)
	ds_write_b128 v176, v[216:219]
	ds_read_b128 v[212:215], v192 offset:36928
	ds_read_b128 v[216:219], v192 offset:41536
	s_waitcnt lgkmcnt(5)
	v_mfma_f32_32x32x16_bf16 v[80:95], v[200:203], v[228:231], v[80:95]
	v_mfma_f32_32x32x16_bf16 v[16:31], v[208:211], v[228:231], v[16:31]
	ds_read_b128 v[228:231], v184 offset:64
	s_waitcnt lgkmcnt(5)
	v_mfma_f32_32x32x16_bf16 v[64:79], v[200:203], v[232:235], v[64:79]
	v_mfma_f32_32x32x16_bf16 v[0:15], v[208:211], v[232:235], v[0:15]
	ds_read_b128 v[232:235], v184 offset:4672
	global_load_dwordx4 v[200:203], v[144:145], off offset:1792
	global_load_dwordx4 v[208:211], v[148:149], off offset:1792
	s_waitcnt lgkmcnt(1)
	v_mfma_f32_32x32x16_bf16 v[112:127], v[212:215], v[228:231], v[112:127]
	v_mfma_f32_32x32x16_bf16 v[48:63], v[216:219], v[228:231], v[48:63]
	s_waitcnt lgkmcnt(0)
	v_mfma_f32_32x32x16_bf16 v[96:111], v[212:215], v[232:235], v[96:111]
	v_mfma_f32_32x32x16_bf16 v[32:47], v[216:219], v[232:235], v[32:47]
	ds_read_b128 v[228:231], v184 offset:9280
	ds_read_b128 v[232:235], v184 offset:13888
	s_waitcnt vmcnt(7)
	ds_write_b128 v171, v[178:181]
	s_waitcnt vmcnt(6)
	ds_write_b128 v170, v[220:223]
	ds_read_b128 v[178:181], v192 offset:36960
	ds_read_b128 v[220:223], v192 offset:41568
	s_waitcnt lgkmcnt(5)
	v_mfma_f32_32x32x16_bf16 v[80:95], v[212:215], v[228:231], v[80:95]
	v_mfma_f32_32x32x16_bf16 v[16:31], v[216:219], v[228:231], v[16:31]
	ds_read_b128 v[228:231], v184 offset:96
	s_waitcnt lgkmcnt(5)
	v_mfma_f32_32x32x16_bf16 v[64:79], v[212:215], v[232:235], v[64:79]
	v_mfma_f32_32x32x16_bf16 v[0:15], v[216:219], v[232:235], v[0:15]
	ds_read_b128 v[232:235], v184 offset:4704
	global_load_dwordx4 v[212:215], v[152:153], off offset:1792
	global_load_dwordx4 v[216:219], v[156:157], off offset:1792
	s_waitcnt lgkmcnt(1)
	v_mfma_f32_32x32x16_bf16 v[112:127], v[178:181], v[228:231], v[112:127]
	v_mfma_f32_32x32x16_bf16 v[48:63], v[220:223], v[228:231], v[48:63]
	s_waitcnt lgkmcnt(0)
	v_mfma_f32_32x32x16_bf16 v[96:111], v[178:181], v[232:235], v[96:111]
	v_mfma_f32_32x32x16_bf16 v[32:47], v[220:223], v[232:235], v[32:47]
	ds_read_b128 v[228:231], v184 offset:9312
	ds_read_b128 v[232:235], v184 offset:13920
	s_waitcnt lgkmcnt(1)
	v_mfma_f32_32x32x16_bf16 v[80:95], v[178:181], v[228:231], v[80:95]
	v_mfma_f32_32x32x16_bf16 v[16:31], v[220:223], v[228:231], v[16:31]
	s_waitcnt lgkmcnt(0)
	v_mfma_f32_32x32x16_bf16 v[64:79], v[178:181], v[232:235], v[64:79]
	v_mfma_f32_32x32x16_bf16 v[0:15], v[220:223], v[232:235], v[0:15]
	s_setprio 0
	s_barrier
; template <bool trans>
; DI void gemm_core(const GTile& tl, const GTile& nx, bool has_next  , bool chain  , bool pre, u32x4 (&ra)[4], u32x4 (&rb)[4], char* smem, f32x16 (&acc)[2][4]) {
;     ...
;   const int nk = K / 64;
;   if (!pre) { G_LOAD(0); G_STORE(0); G_LOAD(1); }
;   for (int kt = 0; kt < nk; ++kt) {
;     __syncthreads();
;     G_COMPUTE(kt & 1, kt);
;   }
	global_load_dwordx4 v[178:181], v[128:129], off offset:1920
	global_load_dwordx4 v[220:223], v[132:133], off offset:1920
	s_waitcnt vmcnt(9)
	ds_write_b128 v191, v[172:175]
	s_waitcnt vmcnt(8)
	ds_write_b128 v191, v[224:227] offset:36864
	ds_read_b128 v[172:175], v169
	ds_read_b128 v[224:227], v169 offset:4608
	ds_read_b128 v[228:231], v168
	ds_read_b128 v[232:235], v168 offset:4608
	s_setprio 1
	s_waitcnt lgkmcnt(1)
	v_mfma_f32_32x32x16_bf16 v[112:127], v[172:175], v[228:231], v[112:127]
	v_mfma_f32_32x32x16_bf16 v[48:63], v[224:227], v[228:231], v[48:63]
	s_waitcnt lgkmcnt(0)
	v_mfma_f32_32x32x16_bf16 v[96:111], v[172:175], v[232:235], v[96:111]
	v_mfma_f32_32x32x16_bf16 v[32:47], v[224:227], v[232:235], v[32:47]
	ds_read_b128 v[228:231], v168 offset:9216
	ds_read_b128 v[232:235], v168 offset:13824
	s_waitcnt vmcnt(7)
	ds_write_b128 v191, v[158:161] offset:9216
	s_waitcnt vmcnt(6)
	ds_write_b128 v191, v[162:165] offset:46080
	ds_read_b128 v[158:161], v169 offset:32
	ds_read_b128 v[162:165], v169 offset:4640
	s_waitcnt lgkmcnt(5)
	v_mfma_f32_32x32x16_bf16 v[80:95], v[172:175], v[228:231], v[80:95]
	v_mfma_f32_32x32x16_bf16 v[16:31], v[224:227], v[228:231], v[16:31]
	ds_read_b128 v[228:231], v168 offset:32
	s_waitcnt lgkmcnt(5)
	v_mfma_f32_32x32x16_bf16 v[64:79], v[172:175], v[232:235], v[64:79]
	v_mfma_f32_32x32x16_bf16 v[0:15], v[224:227], v[232:235], v[0:15]
	ds_read_b128 v[232:235], v168 offset:4640
	global_load_dwordx4 v[172:175], v[136:137], off offset:1920
	global_load_dwordx4 v[224:227], v[140:141], off offset:1920
	s_waitcnt lgkmcnt(1)
	v_mfma_f32_32x32x16_bf16 v[112:127], v[158:161], v[228:231], v[112:127]
	v_mfma_f32_32x32x16_bf16 v[48:63], v[162:165], v[228:231], v[48:63]
	s_waitcnt lgkmcnt(0)
	v_mfma_f32_32x32x16_bf16 v[96:111], v[158:161], v[232:235], v[96:111]
	v_mfma_f32_32x32x16_bf16 v[32:47], v[162:165], v[232:235], v[32:47]
	ds_read_b128 v[228:231], v168 offset:9248
	ds_read_b128 v[232:235], v168 offset:13856
	s_waitcnt vmcnt(7)
	ds_write_b128 v191, v[200:203] offset:18432
	s_waitcnt vmcnt(6)
	ds_write_b128 v191, v[208:211] offset:55296
	ds_read_b128 v[200:203], v169 offset:64
	ds_read_b128 v[208:211], v169 offset:4672
	s_waitcnt lgkmcnt(5)
	v_mfma_f32_32x32x16_bf16 v[80:95], v[158:161], v[228:231], v[80:95]
	v_mfma_f32_32x32x16_bf16 v[16:31], v[162:165], v[228:231], v[16:31]
	ds_read_b128 v[228:231], v168 offset:64
	s_waitcnt lgkmcnt(5)
	v_mfma_f32_32x32x16_bf16 v[64:79], v[158:161], v[232:235], v[64:79]
	v_mfma_f32_32x32x16_bf16 v[0:15], v[162:165], v[232:235], v[0:15]
	ds_read_b128 v[232:235], v168 offset:4672
	global_load_dwordx4 v[158:161], v[144:145], off offset:1920
	global_load_dwordx4 v[162:165], v[148:149], off offset:1920
	s_waitcnt lgkmcnt(1)
	v_mfma_f32_32x32x16_bf16 v[112:127], v[200:203], v[228:231], v[112:127]
	v_mfma_f32_32x32x16_bf16 v[48:63], v[208:211], v[228:231], v[48:63]
	s_waitcnt lgkmcnt(0)
	v_mfma_f32_32x32x16_bf16 v[96:111], v[200:203], v[232:235], v[96:111]
	v_mfma_f32_32x32x16_bf16 v[32:47], v[208:211], v[232:235], v[32:47]
	ds_read_b128 v[228:231], v168 offset:9280
	ds_read_b128 v[232:235], v168 offset:13888
	s_waitcnt vmcnt(7)
	ds_write_b128 v191, v[212:215] offset:27648
	s_waitcnt vmcnt(6)
	ds_write_b128 v191, v[216:219] offset:64512
	ds_read_b128 v[212:215], v169 offset:96
	ds_read_b128 v[216:219], v169 offset:4704
	s_waitcnt lgkmcnt(5)
	v_mfma_f32_32x32x16_bf16 v[80:95], v[200:203], v[228:231], v[80:95]
	v_mfma_f32_32x32x16_bf16 v[16:31], v[208:211], v[228:231], v[16:31]
	ds_read_b128 v[228:231], v168 offset:96
	s_waitcnt lgkmcnt(5)
	v_mfma_f32_32x32x16_bf16 v[64:79], v[200:203], v[232:235], v[64:79]
	v_mfma_f32_32x32x16_bf16 v[0:15], v[208:211], v[232:235], v[0:15]
	ds_read_b128 v[232:235], v168 offset:4704
	global_load_dwordx4 v[200:203], v[152:153], off offset:1920
	global_load_dwordx4 v[208:211], v[156:157], off offset:1920
	s_waitcnt lgkmcnt(1)
	v_mfma_f32_32x32x16_bf16 v[112:127], v[212:215], v[228:231], v[112:127]
	v_mfma_f32_32x32x16_bf16 v[48:63], v[216:219], v[228:231], v[48:63]
	s_waitcnt lgkmcnt(0)
	v_mfma_f32_32x32x16_bf16 v[96:111], v[212:215], v[232:235], v[96:111]
	v_mfma_f32_32x32x16_bf16 v[32:47], v[216:219], v[232:235], v[32:47]
	ds_read_b128 v[228:231], v168 offset:9312
	ds_read_b128 v[232:235], v168 offset:13920
	s_waitcnt lgkmcnt(1)
	v_mfma_f32_32x32x16_bf16 v[80:95], v[212:215], v[228:231], v[80:95]
	v_mfma_f32_32x32x16_bf16 v[16:31], v[216:219], v[228:231], v[16:31]
	s_waitcnt lgkmcnt(0)
	v_mfma_f32_32x32x16_bf16 v[64:79], v[212:215], v[232:235], v[64:79]
	v_mfma_f32_32x32x16_bf16 v[0:15], v[216:219], v[232:235], v[0:15]
	s_setprio 0
	s_barrier
; template <bool trans>
; DI void gemm_core(const GTile& tl, const GTile& nx, bool has_next  , bool chain  , bool pre, u32x4 (&ra)[4], u32x4 (&rb)[4], char* smem, f32x16 (&acc)[2][4]) {
;     ...
;   const int nk = K / 64;
;   if (!pre) { G_LOAD(0); G_STORE(0); G_LOAD(1); }
;   for (int kt = 0; kt < nk; ++kt) {
;     __syncthreads();
;     G_COMPUTE(kt & 1, kt);
;   }
	global_load_dwordx4 v[212:215], v[128:129], off offset:2048
	global_load_dwordx4 v[216:219], v[132:133], off offset:2048
	s_waitcnt vmcnt(9)
	ds_write_b128 v195, v[178:181]
	s_waitcnt vmcnt(8)
	ds_write_b128 v196, v[220:223]
	ds_read_b128 v[178:181], v192 offset:36864
	ds_read_b128 v[220:223], v192 offset:41472
	ds_read_b128 v[228:231], v184
	ds_read_b128 v[232:235], v184 offset:4608
	s_setprio 1
	s_waitcnt lgkmcnt(1)
	v_mfma_f32_32x32x16_bf16 v[112:127], v[178:181], v[228:231], v[112:127]
	v_mfma_f32_32x32x16_bf16 v[48:63], v[220:223], v[228:231], v[48:63]
	s_waitcnt lgkmcnt(0)
	v_mfma_f32_32x32x16_bf16 v[96:111], v[178:181], v[232:235], v[96:111]
	v_mfma_f32_32x32x16_bf16 v[32:47], v[220:223], v[232:235], v[32:47]
	ds_read_b128 v[228:231], v184 offset:9216
	ds_read_b128 v[232:235], v184 offset:13824
	s_waitcnt vmcnt(7)
	ds_write_b128 v194, v[172:175]
	s_waitcnt vmcnt(6)
	ds_write_b128 v193, v[224:227]
	ds_read_b128 v[172:175], v192 offset:36896
	ds_read_b128 v[224:227], v192 offset:41504
	s_waitcnt lgkmcnt(5)
	v_mfma_f32_32x32x16_bf16 v[80:95], v[178:181], v[228:231], v[80:95]
	v_mfma_f32_32x32x16_bf16 v[16:31], v[220:223], v[228:231], v[16:31]
	ds_read_b128 v[228:231], v184 offset:32
	s_waitcnt lgkmcnt(5)
	v_mfma_f32_32x32x16_bf16 v[64:79], v[178:181], v[232:235], v[64:79]
	v_mfma_f32_32x32x16_bf16 v[0:15], v[220:223], v[232:235], v[0:15]
	ds_read_b128 v[232:235], v184 offset:4640
	global_load_dwordx4 v[178:181], v[136:137], off offset:2048
	global_load_dwordx4 v[220:223], v[140:141], off offset:2048
	s_waitcnt lgkmcnt(1)
	v_mfma_f32_32x32x16_bf16 v[112:127], v[172:175], v[228:231], v[112:127]
	v_mfma_f32_32x32x16_bf16 v[48:63], v[224:227], v[228:231], v[48:63]
	s_waitcnt lgkmcnt(0)
	v_mfma_f32_32x32x16_bf16 v[96:111], v[172:175], v[232:235], v[96:111]
	v_mfma_f32_32x32x16_bf16 v[32:47], v[224:227], v[232:235], v[32:47]
	ds_read_b128 v[228:231], v184 offset:9248
	ds_read_b128 v[232:235], v184 offset:13856
	s_waitcnt vmcnt(7)
	ds_write_b128 v177, v[158:161]
	s_waitcnt vmcnt(6)
	ds_write_b128 v176, v[162:165]
	ds_read_b128 v[158:161], v192 offset:36928
	ds_read_b128 v[162:165], v192 offset:41536
	s_waitcnt lgkmcnt(5)
	v_mfma_f32_32x32x16_bf16 v[80:95], v[172:175], v[228:231], v[80:95]
	v_mfma_f32_32x32x16_bf16 v[16:31], v[224:227], v[228:231], v[16:31]
	ds_read_b128 v[228:231], v184 offset:64
	s_waitcnt lgkmcnt(5)
	v_mfma_f32_32x32x16_bf16 v[64:79], v[172:175], v[232:235], v[64:79]
	v_mfma_f32_32x32x16_bf16 v[0:15], v[224:227], v[232:235], v[0:15]
	ds_read_b128 v[232:235], v184 offset:4672
	global_load_dwordx4 v[172:175], v[144:145], off offset:2048
	global_load_dwordx4 v[224:227], v[148:149], off offset:2048
	s_waitcnt lgkmcnt(1)
	v_mfma_f32_32x32x16_bf16 v[112:127], v[158:161], v[228:231], v[112:127]
	v_mfma_f32_32x32x16_bf16 v[48:63], v[162:165], v[228:231], v[48:63]
	s_waitcnt lgkmcnt(0)
	v_mfma_f32_32x32x16_bf16 v[96:111], v[158:161], v[232:235], v[96:111]
	v_mfma_f32_32x32x16_bf16 v[32:47], v[162:165], v[232:235], v[32:47]
	ds_read_b128 v[228:231], v184 offset:9280
	ds_read_b128 v[232:235], v184 offset:13888
	s_waitcnt vmcnt(7)
	ds_write_b128 v171, v[200:203]
	s_waitcnt vmcnt(6)
	ds_write_b128 v170, v[208:211]
	ds_read_b128 v[200:203], v192 offset:36960
	ds_read_b128 v[208:211], v192 offset:41568
	s_waitcnt lgkmcnt(5)
	v_mfma_f32_32x32x16_bf16 v[80:95], v[158:161], v[228:231], v[80:95]
	v_mfma_f32_32x32x16_bf16 v[16:31], v[162:165], v[228:231], v[16:31]
	ds_read_b128 v[228:231], v184 offset:96
	s_waitcnt lgkmcnt(5)
	v_mfma_f32_32x32x16_bf16 v[64:79], v[158:161], v[232:235], v[64:79]
	v_mfma_f32_32x32x16_bf16 v[0:15], v[162:165], v[232:235], v[0:15]
	ds_read_b128 v[232:235], v184 offset:4704
	global_load_dwordx4 v[158:161], v[152:153], off offset:2048
	global_load_dwordx4 v[162:165], v[156:157], off offset:2048
	s_waitcnt lgkmcnt(1)
	v_mfma_f32_32x32x16_bf16 v[112:127], v[200:203], v[228:231], v[112:127]
	v_mfma_f32_32x32x16_bf16 v[48:63], v[208:211], v[228:231], v[48:63]
	s_waitcnt lgkmcnt(0)
	v_mfma_f32_32x32x16_bf16 v[96:111], v[200:203], v[232:235], v[96:111]
	v_mfma_f32_32x32x16_bf16 v[32:47], v[208:211], v[232:235], v[32:47]
	ds_read_b128 v[228:231], v184 offset:9312
	ds_read_b128 v[232:235], v184 offset:13920
	s_waitcnt lgkmcnt(1)
	v_mfma_f32_32x32x16_bf16 v[80:95], v[200:203], v[228:231], v[80:95]
	v_mfma_f32_32x32x16_bf16 v[16:31], v[208:211], v[228:231], v[16:31]
	s_waitcnt lgkmcnt(0)
	v_mfma_f32_32x32x16_bf16 v[64:79], v[200:203], v[232:235], v[64:79]
	v_mfma_f32_32x32x16_bf16 v[0:15], v[208:211], v[232:235], v[0:15]
	s_setprio 0
	s_barrier
; template <bool trans>
; DI void gemm_core(const GTile& tl, const GTile& nx, bool has_next  , bool chain  , bool pre, u32x4 (&ra)[4], u32x4 (&rb)[4], char* smem, f32x16 (&acc)[2][4]) {
;     ...
;   const int nk = K / 64;
;   if (!pre) { G_LOAD(0); G_STORE(0); G_LOAD(1); }
;   for (int kt = 0; kt < nk; ++kt) {
;     __syncthreads();
;     G_COMPUTE(kt & 1, kt);
;   }
	global_load_dwordx4 v[200:203], v[128:129], off offset:2176
	global_load_dwordx4 v[208:211], v[132:133], off offset:2176
	s_waitcnt vmcnt(9)
	ds_write_b128 v191, v[212:215]
	s_waitcnt vmcnt(8)
	ds_write_b128 v191, v[216:219] offset:36864
	ds_read_b128 v[212:215], v169
	ds_read_b128 v[216:219], v169 offset:4608
	ds_read_b128 v[228:231], v168
	ds_read_b128 v[232:235], v168 offset:4608
	s_setprio 1
	s_waitcnt lgkmcnt(1)
	v_mfma_f32_32x32x16_bf16 v[112:127], v[212:215], v[228:231], v[112:127]
	v_mfma_f32_32x32x16_bf16 v[48:63], v[216:219], v[228:231], v[48:63]
	s_waitcnt lgkmcnt(0)
	v_mfma_f32_32x32x16_bf16 v[96:111], v[212:215], v[232:235], v[96:111]
	v_mfma_f32_32x32x16_bf16 v[32:47], v[216:219], v[232:235], v[32:47]
	ds_read_b128 v[228:231], v168 offset:9216
	ds_read_b128 v[232:235], v168 offset:13824
	s_waitcnt vmcnt(7)
	ds_write_b128 v191, v[178:181] offset:9216
	s_waitcnt vmcnt(6)
	ds_write_b128 v191, v[220:223] offset:46080
	ds_read_b128 v[178:181], v169 offset:32
	ds_read_b128 v[220:223], v169 offset:4640
	s_waitcnt lgkmcnt(5)
	v_mfma_f32_32x32x16_bf16 v[80:95], v[212:215], v[228:231], v[80:95]
	v_mfma_f32_32x32x16_bf16 v[16:31], v[216:219], v[228:231], v[16:31]
	ds_read_b128 v[228:231], v168 offset:32
	s_waitcnt lgkmcnt(5)
	v_mfma_f32_32x32x16_bf16 v[64:79], v[212:215], v[232:235], v[64:79]
	v_mfma_f32_32x32x16_bf16 v[0:15], v[216:219], v[232:235], v[0:15]
	ds_read_b128 v[232:235], v168 offset:4640
	global_load_dwordx4 v[212:215], v[136:137], off offset:2176
	global_load_dwordx4 v[216:219], v[140:141], off offset:2176
	s_waitcnt lgkmcnt(1)
	v_mfma_f32_32x32x16_bf16 v[112:127], v[178:181], v[228:231], v[112:127]
	v_mfma_f32_32x32x16_bf16 v[48:63], v[220:223], v[228:231], v[48:63]
	s_waitcnt lgkmcnt(0)
	v_mfma_f32_32x32x16_bf16 v[96:111], v[178:181], v[232:235], v[96:111]
	v_mfma_f32_32x32x16_bf16 v[32:47], v[220:223], v[232:235], v[32:47]
	ds_read_b128 v[228:231], v168 offset:9248
	ds_read_b128 v[232:235], v168 offset:13856
	s_waitcnt vmcnt(7)
	ds_write_b128 v191, v[172:175] offset:18432
	s_waitcnt vmcnt(6)
	ds_write_b128 v191, v[224:227] offset:55296
	ds_read_b128 v[172:175], v169 offset:64
	ds_read_b128 v[224:227], v169 offset:4672
	s_waitcnt lgkmcnt(5)
	v_mfma_f32_32x32x16_bf16 v[80:95], v[178:181], v[228:231], v[80:95]
	v_mfma_f32_32x32x16_bf16 v[16:31], v[220:223], v[228:231], v[16:31]
	ds_read_b128 v[228:231], v168 offset:64
	s_waitcnt lgkmcnt(5)
	v_mfma_f32_32x32x16_bf16 v[64:79], v[178:181], v[232:235], v[64:79]
	v_mfma_f32_32x32x16_bf16 v[0:15], v[220:223], v[232:235], v[0:15]
	ds_read_b128 v[232:235], v168 offset:4672
	global_load_dwordx4 v[178:181], v[144:145], off offset:2176
	global_load_dwordx4 v[220:223], v[148:149], off offset:2176
	s_waitcnt lgkmcnt(1)
	v_mfma_f32_32x32x16_bf16 v[112:127], v[172:175], v[228:231], v[112:127]
	v_mfma_f32_32x32x16_bf16 v[48:63], v[224:227], v[228:231], v[48:63]
	s_waitcnt lgkmcnt(0)
	v_mfma_f32_32x32x16_bf16 v[96:111], v[172:175], v[232:235], v[96:111]
	v_mfma_f32_32x32x16_bf16 v[32:47], v[224:227], v[232:235], v[32:47]
	ds_read_b128 v[228:231], v168 offset:9280
	ds_read_b128 v[232:235], v168 offset:13888
	s_waitcnt vmcnt(7)
	ds_write_b128 v191, v[158:161] offset:27648
	s_waitcnt vmcnt(6)
	ds_write_b128 v191, v[162:165] offset:64512
	ds_read_b128 v[158:161], v169 offset:96
	ds_read_b128 v[162:165], v169 offset:4704
	s_waitcnt lgkmcnt(5)
	v_mfma_f32_32x32x16_bf16 v[80:95], v[172:175], v[228:231], v[80:95]
	v_mfma_f32_32x32x16_bf16 v[16:31], v[224:227], v[228:231], v[16:31]
	ds_read_b128 v[228:231], v168 offset:96
	s_waitcnt lgkmcnt(5)
	v_mfma_f32_32x32x16_bf16 v[64:79], v[172:175], v[232:235], v[64:79]
	v_mfma_f32_32x32x16_bf16 v[0:15], v[224:227], v[232:235], v[0:15]
	ds_read_b128 v[232:235], v168 offset:4704
	global_load_dwordx4 v[172:175], v[152:153], off offset:2176
	global_load_dwordx4 v[224:227], v[156:157], off offset:2176
	s_waitcnt lgkmcnt(1)
	v_mfma_f32_32x32x16_bf16 v[112:127], v[158:161], v[228:231], v[112:127]
	v_mfma_f32_32x32x16_bf16 v[48:63], v[162:165], v[228:231], v[48:63]
	s_waitcnt lgkmcnt(0)
	v_mfma_f32_32x32x16_bf16 v[96:111], v[158:161], v[232:235], v[96:111]
	v_mfma_f32_32x32x16_bf16 v[32:47], v[162:165], v[232:235], v[32:47]
	ds_read_b128 v[228:231], v168 offset:9312
	ds_read_b128 v[232:235], v168 offset:13920
	s_waitcnt lgkmcnt(1)
	v_mfma_f32_32x32x16_bf16 v[80:95], v[158:161], v[228:231], v[80:95]
	v_mfma_f32_32x32x16_bf16 v[16:31], v[162:165], v[228:231], v[16:31]
	s_waitcnt lgkmcnt(0)
	v_mfma_f32_32x32x16_bf16 v[64:79], v[158:161], v[232:235], v[64:79]
	v_mfma_f32_32x32x16_bf16 v[0:15], v[162:165], v[232:235], v[0:15]
	s_setprio 0
	s_barrier
; template <bool trans>
; DI void gemm_core(const GTile& tl, const GTile& nx, bool has_next  , bool chain  , bool pre, u32x4 (&ra)[4], u32x4 (&rb)[4], char* smem, f32x16 (&acc)[2][4]) {
;     ...
;   const int nk = K / 64;
;   if (!pre) { G_LOAD(0); G_STORE(0); G_LOAD(1); }
;   for (int kt = 0; kt < nk; ++kt) {
;     __syncthreads();
;     G_COMPUTE(kt & 1, kt);
;   }
	global_load_dwordx4 v[158:161], v[128:129], off offset:2304
	global_load_dwordx4 v[162:165], v[132:133], off offset:2304
	s_waitcnt vmcnt(9)
	ds_write_b128 v195, v[200:203]
	s_waitcnt vmcnt(8)
	ds_write_b128 v196, v[208:211]
	ds_read_b128 v[200:203], v192 offset:36864
	ds_read_b128 v[208:211], v192 offset:41472
	ds_read_b128 v[228:231], v184
	ds_read_b128 v[232:235], v184 offset:4608
	s_setprio 1
	s_waitcnt lgkmcnt(1)
	v_mfma_f32_32x32x16_bf16 v[112:127], v[200:203], v[228:231], v[112:127]
	v_mfma_f32_32x32x16_bf16 v[48:63], v[208:211], v[228:231], v[48:63]
	s_waitcnt lgkmcnt(0)
	v_mfma_f32_32x32x16_bf16 v[96:111], v[200:203], v[232:235], v[96:111]
	v_mfma_f32_32x32x16_bf16 v[32:47], v[208:211], v[232:235], v[32:47]
	ds_read_b128 v[228:231], v184 offset:9216
	ds_read_b128 v[232:235], v184 offset:13824
	s_waitcnt vmcnt(7)
	ds_write_b128 v194, v[212:215]
	s_waitcnt vmcnt(6)
	ds_write_b128 v193, v[216:219]
	ds_read_b128 v[212:215], v192 offset:36896
	ds_read_b128 v[216:219], v192 offset:41504
	s_waitcnt lgkmcnt(5)
	v_mfma_f32_32x32x16_bf16 v[80:95], v[200:203], v[228:231], v[80:95]
	v_mfma_f32_32x32x16_bf16 v[16:31], v[208:211], v[228:231], v[16:31]
	ds_read_b128 v[228:231], v184 offset:32
	s_waitcnt lgkmcnt(5)
	v_mfma_f32_32x32x16_bf16 v[64:79], v[200:203], v[232:235], v[64:79]
	v_mfma_f32_32x32x16_bf16 v[0:15], v[208:211], v[232:235], v[0:15]
	ds_read_b128 v[232:235], v184 offset:4640
	global_load_dwordx4 v[200:203], v[136:137], off offset:2304
	global_load_dwordx4 v[208:211], v[140:141], off offset:2304
	s_waitcnt lgkmcnt(1)
	v_mfma_f32_32x32x16_bf16 v[112:127], v[212:215], v[228:231], v[112:127]
	v_mfma_f32_32x32x16_bf16 v[48:63], v[216:219], v[228:231], v[48:63]
	s_waitcnt lgkmcnt(0)
	v_mfma_f32_32x32x16_bf16 v[96:111], v[212:215], v[232:235], v[96:111]
	v_mfma_f32_32x32x16_bf16 v[32:47], v[216:219], v[232:235], v[32:47]
	ds_read_b128 v[228:231], v184 offset:9248
	ds_read_b128 v[232:235], v184 offset:13856
	s_waitcnt vmcnt(7)
	ds_write_b128 v177, v[178:181]
	s_waitcnt vmcnt(6)
	ds_write_b128 v176, v[220:223]
	ds_read_b128 v[178:181], v192 offset:36928
	ds_read_b128 v[220:223], v192 offset:41536
	s_waitcnt lgkmcnt(5)
	v_mfma_f32_32x32x16_bf16 v[80:95], v[212:215], v[228:231], v[80:95]
	v_mfma_f32_32x32x16_bf16 v[16:31], v[216:219], v[228:231], v[16:31]
	ds_read_b128 v[228:231], v184 offset:64
	s_waitcnt lgkmcnt(5)
	v_mfma_f32_32x32x16_bf16 v[64:79], v[212:215], v[232:235], v[64:79]
	v_mfma_f32_32x32x16_bf16 v[0:15], v[216:219], v[232:235], v[0:15]
	ds_read_b128 v[232:235], v184 offset:4672
	global_load_dwordx4 v[212:215], v[144:145], off offset:2304
	global_load_dwordx4 v[216:219], v[148:149], off offset:2304
	s_waitcnt lgkmcnt(1)
	v_mfma_f32_32x32x16_bf16 v[112:127], v[178:181], v[228:231], v[112:127]
	v_mfma_f32_32x32x16_bf16 v[48:63], v[220:223], v[228:231], v[48:63]
	s_waitcnt lgkmcnt(0)
	v_mfma_f32_32x32x16_bf16 v[96:111], v[178:181], v[232:235], v[96:111]
	v_mfma_f32_32x32x16_bf16 v[32:47], v[220:223], v[232:235], v[32:47]
	ds_read_b128 v[228:231], v184 offset:9280
	ds_read_b128 v[232:235], v184 offset:13888
	s_waitcnt vmcnt(7)
	ds_write_b128 v171, v[172:175]
	s_waitcnt vmcnt(6)
	ds_write_b128 v170, v[224:227]
	ds_read_b128 v[172:175], v192 offset:36960
	ds_read_b128 v[224:227], v192 offset:41568
	s_waitcnt lgkmcnt(5)
	v_mfma_f32_32x32x16_bf16 v[80:95], v[178:181], v[228:231], v[80:95]
	v_mfma_f32_32x32x16_bf16 v[16:31], v[220:223], v[228:231], v[16:31]
	ds_read_b128 v[228:231], v184 offset:96
	s_waitcnt lgkmcnt(5)
	v_mfma_f32_32x32x16_bf16 v[64:79], v[178:181], v[232:235], v[64:79]
	v_mfma_f32_32x32x16_bf16 v[0:15], v[220:223], v[232:235], v[0:15]
	ds_read_b128 v[232:235], v184 offset:4704
	global_load_dwordx4 v[178:181], v[152:153], off offset:2304
	global_load_dwordx4 v[220:223], v[156:157], off offset:2304
	s_waitcnt lgkmcnt(1)
	v_mfma_f32_32x32x16_bf16 v[112:127], v[172:175], v[228:231], v[112:127]
	v_mfma_f32_32x32x16_bf16 v[48:63], v[224:227], v[228:231], v[48:63]
	s_waitcnt lgkmcnt(0)
	v_mfma_f32_32x32x16_bf16 v[96:111], v[172:175], v[232:235], v[96:111]
	v_mfma_f32_32x32x16_bf16 v[32:47], v[224:227], v[232:235], v[32:47]
	ds_read_b128 v[228:231], v184 offset:9312
	ds_read_b128 v[232:235], v184 offset:13920
	s_waitcnt lgkmcnt(1)
	v_mfma_f32_32x32x16_bf16 v[80:95], v[172:175], v[228:231], v[80:95]
	v_mfma_f32_32x32x16_bf16 v[16:31], v[224:227], v[228:231], v[16:31]
	s_waitcnt lgkmcnt(0)
	v_mfma_f32_32x32x16_bf16 v[64:79], v[172:175], v[232:235], v[64:79]
	v_mfma_f32_32x32x16_bf16 v[0:15], v[224:227], v[232:235], v[0:15]
	s_setprio 0
	s_barrier
; template <bool trans>
; DI void gemm_core(const GTile& tl, const GTile& nx, bool has_next  , bool chain  , bool pre, u32x4 (&ra)[4], u32x4 (&rb)[4], char* smem, f32x16 (&acc)[2][4]) {
;     ...
;   const int nk = K / 64;
;   if (!pre) { G_LOAD(0); G_STORE(0); G_LOAD(1); }
;   for (int kt = 0; kt < nk; ++kt) {
;     __syncthreads();
;     G_COMPUTE(kt & 1, kt);
;   }
	global_load_dwordx4 v[172:175], v[128:129], off offset:2432
	global_load_dwordx4 v[224:227], v[132:133], off offset:2432
	s_waitcnt vmcnt(9)
	ds_write_b128 v191, v[158:161]
	s_waitcnt vmcnt(8)
	ds_write_b128 v191, v[162:165] offset:36864
	ds_read_b128 v[158:161], v169
	ds_read_b128 v[162:165], v169 offset:4608
	ds_read_b128 v[228:231], v168
	ds_read_b128 v[232:235], v168 offset:4608
	s_setprio 1
	s_waitcnt lgkmcnt(1)
	v_mfma_f32_32x32x16_bf16 v[112:127], v[158:161], v[228:231], v[112:127]
	v_mfma_f32_32x32x16_bf16 v[48:63], v[162:165], v[228:231], v[48:63]
	s_waitcnt lgkmcnt(0)
	v_mfma_f32_32x32x16_bf16 v[96:111], v[158:161], v[232:235], v[96:111]
	v_mfma_f32_32x32x16_bf16 v[32:47], v[162:165], v[232:235], v[32:47]
	ds_read_b128 v[228:231], v168 offset:9216
	ds_read_b128 v[232:235], v168 offset:13824
	s_waitcnt vmcnt(7)
	ds_write_b128 v191, v[200:203] offset:9216
	s_waitcnt vmcnt(6)
	ds_write_b128 v191, v[208:211] offset:46080
	ds_read_b128 v[200:203], v169 offset:32
	ds_read_b128 v[208:211], v169 offset:4640
	s_waitcnt lgkmcnt(5)
	v_mfma_f32_32x32x16_bf16 v[80:95], v[158:161], v[228:231], v[80:95]
	v_mfma_f32_32x32x16_bf16 v[16:31], v[162:165], v[228:231], v[16:31]
	ds_read_b128 v[228:231], v168 offset:32
	s_waitcnt lgkmcnt(5)
	v_mfma_f32_32x32x16_bf16 v[64:79], v[158:161], v[232:235], v[64:79]
	v_mfma_f32_32x32x16_bf16 v[0:15], v[162:165], v[232:235], v[0:15]
	ds_read_b128 v[232:235], v168 offset:4640
	global_load_dwordx4 v[158:161], v[136:137], off offset:2432
	global_load_dwordx4 v[162:165], v[140:141], off offset:2432
	s_waitcnt lgkmcnt(1)
	v_mfma_f32_32x32x16_bf16 v[112:127], v[200:203], v[228:231], v[112:127]
	v_mfma_f32_32x32x16_bf16 v[48:63], v[208:211], v[228:231], v[48:63]
	s_waitcnt lgkmcnt(0)
	v_mfma_f32_32x32x16_bf16 v[96:111], v[200:203], v[232:235], v[96:111]
	v_mfma_f32_32x32x16_bf16 v[32:47], v[208:211], v[232:235], v[32:47]
	ds_read_b128 v[228:231], v168 offset:9248
	ds_read_b128 v[232:235], v168 offset:13856
	s_waitcnt vmcnt(7)
	ds_write_b128 v191, v[212:215] offset:18432
	s_waitcnt vmcnt(6)
	ds_write_b128 v191, v[216:219] offset:55296
	ds_read_b128 v[212:215], v169 offset:64
	ds_read_b128 v[216:219], v169 offset:4672
	s_waitcnt lgkmcnt(5)
	v_mfma_f32_32x32x16_bf16 v[80:95], v[200:203], v[228:231], v[80:95]
	v_mfma_f32_32x32x16_bf16 v[16:31], v[208:211], v[228:231], v[16:31]
	ds_read_b128 v[228:231], v168 offset:64
	s_waitcnt lgkmcnt(5)
	v_mfma_f32_32x32x16_bf16 v[64:79], v[200:203], v[232:235], v[64:79]
	v_mfma_f32_32x32x16_bf16 v[0:15], v[208:211], v[232:235], v[0:15]
	ds_read_b128 v[232:235], v168 offset:4672
	global_load_dwordx4 v[200:203], v[144:145], off offset:2432
	global_load_dwordx4 v[208:211], v[148:149], off offset:2432
	s_waitcnt lgkmcnt(1)
	v_mfma_f32_32x32x16_bf16 v[112:127], v[212:215], v[228:231], v[112:127]
	v_mfma_f32_32x32x16_bf16 v[48:63], v[216:219], v[228:231], v[48:63]
	s_waitcnt lgkmcnt(0)
	v_mfma_f32_32x32x16_bf16 v[96:111], v[212:215], v[232:235], v[96:111]
	v_mfma_f32_32x32x16_bf16 v[32:47], v[216:219], v[232:235], v[32:47]
	ds_read_b128 v[228:231], v168 offset:9280
	ds_read_b128 v[232:235], v168 offset:13888
	s_waitcnt vmcnt(7)
	ds_write_b128 v191, v[178:181] offset:27648
	s_waitcnt vmcnt(6)
	ds_write_b128 v191, v[220:223] offset:64512
	ds_read_b128 v[178:181], v169 offset:96
	ds_read_b128 v[220:223], v169 offset:4704
	s_waitcnt lgkmcnt(5)
	v_mfma_f32_32x32x16_bf16 v[80:95], v[212:215], v[228:231], v[80:95]
	v_mfma_f32_32x32x16_bf16 v[16:31], v[216:219], v[228:231], v[16:31]
	ds_read_b128 v[228:231], v168 offset:96
	s_waitcnt lgkmcnt(5)
	v_mfma_f32_32x32x16_bf16 v[64:79], v[212:215], v[232:235], v[64:79]
	v_mfma_f32_32x32x16_bf16 v[0:15], v[216:219], v[232:235], v[0:15]
	ds_read_b128 v[232:235], v168 offset:4704
	global_load_dwordx4 v[212:215], v[152:153], off offset:2432
	global_load_dwordx4 v[216:219], v[156:157], off offset:2432
	s_waitcnt lgkmcnt(1)
	v_mfma_f32_32x32x16_bf16 v[112:127], v[178:181], v[228:231], v[112:127]
	v_mfma_f32_32x32x16_bf16 v[48:63], v[220:223], v[228:231], v[48:63]
	s_waitcnt lgkmcnt(0)
	v_mfma_f32_32x32x16_bf16 v[96:111], v[178:181], v[232:235], v[96:111]
	v_mfma_f32_32x32x16_bf16 v[32:47], v[220:223], v[232:235], v[32:47]
	ds_read_b128 v[228:231], v168 offset:9312
	ds_read_b128 v[232:235], v168 offset:13920
	s_waitcnt lgkmcnt(1)
	v_mfma_f32_32x32x16_bf16 v[80:95], v[178:181], v[228:231], v[80:95]
	v_mfma_f32_32x32x16_bf16 v[16:31], v[220:223], v[228:231], v[16:31]
	s_waitcnt lgkmcnt(0)
	v_mfma_f32_32x32x16_bf16 v[64:79], v[178:181], v[232:235], v[64:79]
	v_mfma_f32_32x32x16_bf16 v[0:15], v[220:223], v[232:235], v[0:15]
	s_setprio 0
	s_barrier
; template <bool trans>
; DI void gemm_core(const GTile& tl, const GTile& nx, bool has_next  , bool chain  , bool pre, u32x4 (&ra)[4], u32x4 (&rb)[4], char* smem, f32x16 (&acc)[2][4]) {
;     ...
;   const int nk = K / 64;
;   if (!pre) { G_LOAD(0); G_STORE(0); G_LOAD(1); }
;   for (int kt = 0; kt < nk; ++kt) {
;     __syncthreads();
;     G_COMPUTE(kt & 1, kt);
;   }
	global_load_dwordx4 v[178:181], v[128:129], off offset:2560
	global_load_dwordx4 v[220:223], v[132:133], off offset:2560
	s_waitcnt vmcnt(9)
	ds_write_b128 v195, v[172:175]
	s_waitcnt vmcnt(8)
	ds_write_b128 v196, v[224:227]
	ds_read_b128 v[172:175], v192 offset:36864
	ds_read_b128 v[224:227], v192 offset:41472
	ds_read_b128 v[228:231], v184
	ds_read_b128 v[232:235], v184 offset:4608
	s_setprio 1
	s_waitcnt lgkmcnt(1)
	v_mfma_f32_32x32x16_bf16 v[112:127], v[172:175], v[228:231], v[112:127]
	v_mfma_f32_32x32x16_bf16 v[48:63], v[224:227], v[228:231], v[48:63]
	s_waitcnt lgkmcnt(0)
	v_mfma_f32_32x32x16_bf16 v[96:111], v[172:175], v[232:235], v[96:111]
	v_mfma_f32_32x32x16_bf16 v[32:47], v[224:227], v[232:235], v[32:47]
	ds_read_b128 v[228:231], v184 offset:9216
	ds_read_b128 v[232:235], v184 offset:13824
	s_waitcnt vmcnt(7)
	ds_write_b128 v194, v[158:161]
	s_waitcnt vmcnt(6)
	ds_write_b128 v193, v[162:165]
	ds_read_b128 v[158:161], v192 offset:36896
	ds_read_b128 v[162:165], v192 offset:41504
	s_waitcnt lgkmcnt(5)
	v_mfma_f32_32x32x16_bf16 v[80:95], v[172:175], v[228:231], v[80:95]
	v_mfma_f32_32x32x16_bf16 v[16:31], v[224:227], v[228:231], v[16:31]
	ds_read_b128 v[228:231], v184 offset:32
	s_waitcnt lgkmcnt(5)
	v_mfma_f32_32x32x16_bf16 v[64:79], v[172:175], v[232:235], v[64:79]
	v_mfma_f32_32x32x16_bf16 v[0:15], v[224:227], v[232:235], v[0:15]
	ds_read_b128 v[232:235], v184 offset:4640
	global_load_dwordx4 v[172:175], v[136:137], off offset:2560
	global_load_dwordx4 v[224:227], v[140:141], off offset:2560
	s_waitcnt lgkmcnt(1)
	v_mfma_f32_32x32x16_bf16 v[112:127], v[158:161], v[228:231], v[112:127]
	v_mfma_f32_32x32x16_bf16 v[48:63], v[162:165], v[228:231], v[48:63]
	s_waitcnt lgkmcnt(0)
	v_mfma_f32_32x32x16_bf16 v[96:111], v[158:161], v[232:235], v[96:111]
	v_mfma_f32_32x32x16_bf16 v[32:47], v[162:165], v[232:235], v[32:47]
	ds_read_b128 v[228:231], v184 offset:9248
	ds_read_b128 v[232:235], v184 offset:13856
	s_waitcnt vmcnt(7)
	ds_write_b128 v177, v[200:203]
	s_waitcnt vmcnt(6)
	ds_write_b128 v176, v[208:211]
	ds_read_b128 v[200:203], v192 offset:36928
	ds_read_b128 v[208:211], v192 offset:41536
	s_waitcnt lgkmcnt(5)
	v_mfma_f32_32x32x16_bf16 v[80:95], v[158:161], v[228:231], v[80:95]
	v_mfma_f32_32x32x16_bf16 v[16:31], v[162:165], v[228:231], v[16:31]
	ds_read_b128 v[228:231], v184 offset:64
	s_waitcnt lgkmcnt(5)
	v_mfma_f32_32x32x16_bf16 v[64:79], v[158:161], v[232:235], v[64:79]
	v_mfma_f32_32x32x16_bf16 v[0:15], v[162:165], v[232:235], v[0:15]
	ds_read_b128 v[232:235], v184 offset:4672
	global_load_dwordx4 v[158:161], v[144:145], off offset:2560
	global_load_dwordx4 v[162:165], v[148:149], off offset:2560
	s_waitcnt lgkmcnt(1)
	v_mfma_f32_32x32x16_bf16 v[112:127], v[200:203], v[228:231], v[112:127]
	v_mfma_f32_32x32x16_bf16 v[48:63], v[208:211], v[228:231], v[48:63]
	s_waitcnt lgkmcnt(0)
	v_mfma_f32_32x32x16_bf16 v[96:111], v[200:203], v[232:235], v[96:111]
	v_mfma_f32_32x32x16_bf16 v[32:47], v[208:211], v[232:235], v[32:47]
	ds_read_b128 v[228:231], v184 offset:9280
	ds_read_b128 v[232:235], v184 offset:13888
	s_waitcnt vmcnt(7)
	ds_write_b128 v171, v[212:215]
	s_waitcnt vmcnt(6)
	ds_write_b128 v170, v[216:219]
	ds_read_b128 v[212:215], v192 offset:36960
	ds_read_b128 v[216:219], v192 offset:41568
	s_waitcnt lgkmcnt(5)
	v_mfma_f32_32x32x16_bf16 v[80:95], v[200:203], v[228:231], v[80:95]
	v_mfma_f32_32x32x16_bf16 v[16:31], v[208:211], v[228:231], v[16:31]
	ds_read_b128 v[228:231], v184 offset:96
	s_waitcnt lgkmcnt(5)
	v_mfma_f32_32x32x16_bf16 v[64:79], v[200:203], v[232:235], v[64:79]
	v_mfma_f32_32x32x16_bf16 v[0:15], v[208:211], v[232:235], v[0:15]
	ds_read_b128 v[232:235], v184 offset:4704
	global_load_dwordx4 v[200:203], v[152:153], off offset:2560
	global_load_dwordx4 v[208:211], v[156:157], off offset:2560
	s_waitcnt lgkmcnt(1)
	v_mfma_f32_32x32x16_bf16 v[112:127], v[212:215], v[228:231], v[112:127]
	v_mfma_f32_32x32x16_bf16 v[48:63], v[216:219], v[228:231], v[48:63]
	s_waitcnt lgkmcnt(0)
	v_mfma_f32_32x32x16_bf16 v[96:111], v[212:215], v[232:235], v[96:111]
	v_mfma_f32_32x32x16_bf16 v[32:47], v[216:219], v[232:235], v[32:47]
	ds_read_b128 v[228:231], v184 offset:9312
	ds_read_b128 v[232:235], v184 offset:13920
	s_waitcnt lgkmcnt(1)
	v_mfma_f32_32x32x16_bf16 v[80:95], v[212:215], v[228:231], v[80:95]
	v_mfma_f32_32x32x16_bf16 v[16:31], v[216:219], v[228:231], v[16:31]
	s_waitcnt lgkmcnt(0)
	v_mfma_f32_32x32x16_bf16 v[64:79], v[212:215], v[232:235], v[64:79]
	v_mfma_f32_32x32x16_bf16 v[0:15], v[216:219], v[232:235], v[0:15]
	s_setprio 0
	s_barrier
; template <bool trans>
; DI void gemm_core(const GTile& tl, const GTile& nx, bool has_next  , bool chain  , bool pre, u32x4 (&ra)[4], u32x4 (&rb)[4], char* smem, f32x16 (&acc)[2][4]) {
;     ...
;   const int nk = K / 64;
;   if (!pre) { G_LOAD(0); G_STORE(0); G_LOAD(1); }
;   for (int kt = 0; kt < nk; ++kt) {
;     __syncthreads();
;     G_COMPUTE(kt & 1, kt);
;   }
	global_load_dwordx4 v[212:215], v[128:129], off offset:2688
	global_load_dwordx4 v[216:219], v[132:133], off offset:2688
	s_waitcnt vmcnt(9)
	ds_write_b128 v191, v[178:181]
	s_waitcnt vmcnt(8)
	ds_write_b128 v191, v[220:223] offset:36864
	ds_read_b128 v[178:181], v169
	ds_read_b128 v[220:223], v169 offset:4608
	ds_read_b128 v[228:231], v168
	ds_read_b128 v[232:235], v168 offset:4608
	s_setprio 1
	s_waitcnt lgkmcnt(1)
	v_mfma_f32_32x32x16_bf16 v[112:127], v[178:181], v[228:231], v[112:127]
	v_mfma_f32_32x32x16_bf16 v[48:63], v[220:223], v[228:231], v[48:63]
	s_waitcnt lgkmcnt(0)
	v_mfma_f32_32x32x16_bf16 v[96:111], v[178:181], v[232:235], v[96:111]
	v_mfma_f32_32x32x16_bf16 v[32:47], v[220:223], v[232:235], v[32:47]
	ds_read_b128 v[228:231], v168 offset:9216
	ds_read_b128 v[232:235], v168 offset:13824
	s_waitcnt vmcnt(7)
	ds_write_b128 v191, v[172:175] offset:9216
	s_waitcnt vmcnt(6)
	ds_write_b128 v191, v[224:227] offset:46080
	ds_read_b128 v[172:175], v169 offset:32
	ds_read_b128 v[224:227], v169 offset:4640
	s_waitcnt lgkmcnt(5)
	v_mfma_f32_32x32x16_bf16 v[80:95], v[178:181], v[228:231], v[80:95]
	v_mfma_f32_32x32x16_bf16 v[16:31], v[220:223], v[228:231], v[16:31]
	ds_read_b128 v[228:231], v168 offset:32
	s_waitcnt lgkmcnt(5)
	v_mfma_f32_32x32x16_bf16 v[64:79], v[178:181], v[232:235], v[64:79]
	v_mfma_f32_32x32x16_bf16 v[0:15], v[220:223], v[232:235], v[0:15]
	ds_read_b128 v[232:235], v168 offset:4640
	global_load_dwordx4 v[178:181], v[136:137], off offset:2688
	global_load_dwordx4 v[220:223], v[140:141], off offset:2688
	s_waitcnt lgkmcnt(1)
	v_mfma_f32_32x32x16_bf16 v[112:127], v[172:175], v[228:231], v[112:127]
	v_mfma_f32_32x32x16_bf16 v[48:63], v[224:227], v[228:231], v[48:63]
	s_waitcnt lgkmcnt(0)
	v_mfma_f32_32x32x16_bf16 v[96:111], v[172:175], v[232:235], v[96:111]
	v_mfma_f32_32x32x16_bf16 v[32:47], v[224:227], v[232:235], v[32:47]
	ds_read_b128 v[228:231], v168 offset:9248
	ds_read_b128 v[232:235], v168 offset:13856
	s_waitcnt vmcnt(7)
	ds_write_b128 v191, v[158:161] offset:18432
	s_waitcnt vmcnt(6)
	ds_write_b128 v191, v[162:165] offset:55296
	ds_read_b128 v[158:161], v169 offset:64
	ds_read_b128 v[162:165], v169 offset:4672
	s_waitcnt lgkmcnt(5)
	v_mfma_f32_32x32x16_bf16 v[80:95], v[172:175], v[228:231], v[80:95]
	v_mfma_f32_32x32x16_bf16 v[16:31], v[224:227], v[228:231], v[16:31]
	ds_read_b128 v[228:231], v168 offset:64
	s_waitcnt lgkmcnt(5)
	v_mfma_f32_32x32x16_bf16 v[64:79], v[172:175], v[232:235], v[64:79]
	v_mfma_f32_32x32x16_bf16 v[0:15], v[224:227], v[232:235], v[0:15]
	ds_read_b128 v[232:235], v168 offset:4672
	global_load_dwordx4 v[172:175], v[144:145], off offset:2688
	global_load_dwordx4 v[224:227], v[148:149], off offset:2688
	s_waitcnt lgkmcnt(1)
	v_mfma_f32_32x32x16_bf16 v[112:127], v[158:161], v[228:231], v[112:127]
	v_mfma_f32_32x32x16_bf16 v[48:63], v[162:165], v[228:231], v[48:63]
	s_waitcnt lgkmcnt(0)
	v_mfma_f32_32x32x16_bf16 v[96:111], v[158:161], v[232:235], v[96:111]
	v_mfma_f32_32x32x16_bf16 v[32:47], v[162:165], v[232:235], v[32:47]
	ds_read_b128 v[228:231], v168 offset:9280
	ds_read_b128 v[232:235], v168 offset:13888
	s_waitcnt vmcnt(7)
	ds_write_b128 v191, v[200:203] offset:27648
	s_waitcnt vmcnt(6)
	ds_write_b128 v191, v[208:211] offset:64512
	ds_read_b128 v[200:203], v169 offset:96
	ds_read_b128 v[208:211], v169 offset:4704
	s_waitcnt lgkmcnt(5)
	v_mfma_f32_32x32x16_bf16 v[80:95], v[158:161], v[228:231], v[80:95]
	v_mfma_f32_32x32x16_bf16 v[16:31], v[162:165], v[228:231], v[16:31]
	ds_read_b128 v[228:231], v168 offset:96
	s_waitcnt lgkmcnt(5)
	v_mfma_f32_32x32x16_bf16 v[64:79], v[158:161], v[232:235], v[64:79]
	v_mfma_f32_32x32x16_bf16 v[0:15], v[162:165], v[232:235], v[0:15]
	ds_read_b128 v[232:235], v168 offset:4704
	global_load_dwordx4 v[158:161], v[152:153], off offset:2688
	global_load_dwordx4 v[162:165], v[156:157], off offset:2688
	s_waitcnt lgkmcnt(1)
	v_mfma_f32_32x32x16_bf16 v[112:127], v[200:203], v[228:231], v[112:127]
	v_mfma_f32_32x32x16_bf16 v[48:63], v[208:211], v[228:231], v[48:63]
	s_waitcnt lgkmcnt(0)
	v_mfma_f32_32x32x16_bf16 v[96:111], v[200:203], v[232:235], v[96:111]
	v_mfma_f32_32x32x16_bf16 v[32:47], v[208:211], v[232:235], v[32:47]
	ds_read_b128 v[228:231], v168 offset:9312
	ds_read_b128 v[232:235], v168 offset:13920
	s_waitcnt lgkmcnt(1)
	v_mfma_f32_32x32x16_bf16 v[80:95], v[200:203], v[228:231], v[80:95]
	v_mfma_f32_32x32x16_bf16 v[16:31], v[208:211], v[228:231], v[16:31]
	s_waitcnt lgkmcnt(0)
	v_mfma_f32_32x32x16_bf16 v[64:79], v[200:203], v[232:235], v[64:79]
	v_mfma_f32_32x32x16_bf16 v[0:15], v[208:211], v[232:235], v[0:15]
	s_setprio 0
	s_barrier
; template <bool trans>
; DI void gemm_core(const GTile& tl, const GTile& nx, bool has_next  , bool chain  , bool pre, u32x4 (&ra)[4], u32x4 (&rb)[4], char* smem, f32x16 (&acc)[2][4]) {
;     ...
;   const int nk = K / 64;
;   if (!pre) { G_LOAD(0); G_STORE(0); G_LOAD(1); }
;   for (int kt = 0; kt < nk; ++kt) {
;     __syncthreads();
;     G_COMPUTE(kt & 1, kt);
;   }
	global_load_dwordx4 v[200:203], v[128:129], off offset:2816
	global_load_dwordx4 v[208:211], v[132:133], off offset:2816
	s_waitcnt vmcnt(9)
	ds_write_b128 v195, v[212:215]
	s_waitcnt vmcnt(8)
	ds_write_b128 v196, v[216:219]
	ds_read_b128 v[212:215], v192 offset:36864
	ds_read_b128 v[216:219], v192 offset:41472
	ds_read_b128 v[228:231], v184
	ds_read_b128 v[232:235], v184 offset:4608
	s_setprio 1
	s_waitcnt lgkmcnt(1)
	v_mfma_f32_32x32x16_bf16 v[112:127], v[212:215], v[228:231], v[112:127]
	v_mfma_f32_32x32x16_bf16 v[48:63], v[216:219], v[228:231], v[48:63]
	s_waitcnt lgkmcnt(0)
	v_mfma_f32_32x32x16_bf16 v[96:111], v[212:215], v[232:235], v[96:111]
	v_mfma_f32_32x32x16_bf16 v[32:47], v[216:219], v[232:235], v[32:47]
	ds_read_b128 v[228:231], v184 offset:9216
	ds_read_b128 v[232:235], v184 offset:13824
	s_waitcnt vmcnt(7)
	ds_write_b128 v194, v[178:181]
	s_waitcnt vmcnt(6)
	ds_write_b128 v193, v[220:223]
	ds_read_b128 v[178:181], v192 offset:36896
	ds_read_b128 v[220:223], v192 offset:41504
	s_waitcnt lgkmcnt(5)
	v_mfma_f32_32x32x16_bf16 v[80:95], v[212:215], v[228:231], v[80:95]
	v_mfma_f32_32x32x16_bf16 v[16:31], v[216:219], v[228:231], v[16:31]
	ds_read_b128 v[228:231], v184 offset:32
	s_waitcnt lgkmcnt(5)
	v_mfma_f32_32x32x16_bf16 v[64:79], v[212:215], v[232:235], v[64:79]
	v_mfma_f32_32x32x16_bf16 v[0:15], v[216:219], v[232:235], v[0:15]
	ds_read_b128 v[232:235], v184 offset:4640
	global_load_dwordx4 v[212:215], v[136:137], off offset:2816
	global_load_dwordx4 v[216:219], v[140:141], off offset:2816
	s_waitcnt lgkmcnt(1)
	v_mfma_f32_32x32x16_bf16 v[112:127], v[178:181], v[228:231], v[112:127]
	v_mfma_f32_32x32x16_bf16 v[48:63], v[220:223], v[228:231], v[48:63]
	s_waitcnt lgkmcnt(0)
	v_mfma_f32_32x32x16_bf16 v[96:111], v[178:181], v[232:235], v[96:111]
	v_mfma_f32_32x32x16_bf16 v[32:47], v[220:223], v[232:235], v[32:47]
	ds_read_b128 v[228:231], v184 offset:9248
	ds_read_b128 v[232:235], v184 offset:13856
	s_waitcnt vmcnt(7)
	ds_write_b128 v177, v[172:175]
	s_waitcnt vmcnt(6)
	ds_write_b128 v176, v[224:227]
	ds_read_b128 v[172:175], v192 offset:36928
	ds_read_b128 v[224:227], v192 offset:41536
	s_waitcnt lgkmcnt(5)
	v_mfma_f32_32x32x16_bf16 v[80:95], v[178:181], v[228:231], v[80:95]
	v_mfma_f32_32x32x16_bf16 v[16:31], v[220:223], v[228:231], v[16:31]
	ds_read_b128 v[228:231], v184 offset:64
	s_waitcnt lgkmcnt(5)
	v_mfma_f32_32x32x16_bf16 v[64:79], v[178:181], v[232:235], v[64:79]
	v_mfma_f32_32x32x16_bf16 v[0:15], v[220:223], v[232:235], v[0:15]
	ds_read_b128 v[232:235], v184 offset:4672
	global_load_dwordx4 v[178:181], v[144:145], off offset:2816
	global_load_dwordx4 v[220:223], v[148:149], off offset:2816
	s_waitcnt lgkmcnt(1)
	v_mfma_f32_32x32x16_bf16 v[112:127], v[172:175], v[228:231], v[112:127]
	v_mfma_f32_32x32x16_bf16 v[48:63], v[224:227], v[228:231], v[48:63]
	s_waitcnt lgkmcnt(0)
	v_mfma_f32_32x32x16_bf16 v[96:111], v[172:175], v[232:235], v[96:111]
	v_mfma_f32_32x32x16_bf16 v[32:47], v[224:227], v[232:235], v[32:47]
	ds_read_b128 v[228:231], v184 offset:9280
	ds_read_b128 v[232:235], v184 offset:13888
	s_waitcnt vmcnt(7)
	ds_write_b128 v171, v[158:161]
	s_waitcnt vmcnt(6)
	ds_write_b128 v170, v[162:165]
	ds_read_b128 v[158:161], v192 offset:36960
	ds_read_b128 v[162:165], v192 offset:41568
	s_waitcnt lgkmcnt(5)
	v_mfma_f32_32x32x16_bf16 v[80:95], v[172:175], v[228:231], v[80:95]
	v_mfma_f32_32x32x16_bf16 v[16:31], v[224:227], v[228:231], v[16:31]
	ds_read_b128 v[228:231], v184 offset:96
	s_waitcnt lgkmcnt(5)
	v_mfma_f32_32x32x16_bf16 v[64:79], v[172:175], v[232:235], v[64:79]
	v_mfma_f32_32x32x16_bf16 v[0:15], v[224:227], v[232:235], v[0:15]
	ds_read_b128 v[232:235], v184 offset:4704
	global_load_dwordx4 v[172:175], v[152:153], off offset:2816
	global_load_dwordx4 v[224:227], v[156:157], off offset:2816
	s_waitcnt lgkmcnt(1)
	v_mfma_f32_32x32x16_bf16 v[112:127], v[158:161], v[228:231], v[112:127]
	v_mfma_f32_32x32x16_bf16 v[48:63], v[162:165], v[228:231], v[48:63]
	s_waitcnt lgkmcnt(0)
	v_mfma_f32_32x32x16_bf16 v[96:111], v[158:161], v[232:235], v[96:111]
	v_mfma_f32_32x32x16_bf16 v[32:47], v[162:165], v[232:235], v[32:47]
	ds_read_b128 v[228:231], v184 offset:9312
	ds_read_b128 v[232:235], v184 offset:13920
	s_waitcnt lgkmcnt(1)
	v_mfma_f32_32x32x16_bf16 v[80:95], v[158:161], v[228:231], v[80:95]
	v_mfma_f32_32x32x16_bf16 v[16:31], v[162:165], v[228:231], v[16:31]
	s_waitcnt lgkmcnt(0)
	v_mfma_f32_32x32x16_bf16 v[64:79], v[158:161], v[232:235], v[64:79]
	v_mfma_f32_32x32x16_bf16 v[0:15], v[162:165], v[232:235], v[0:15]
	s_setprio 0
	s_barrier
; template <bool trans>
; DI void gemm_core(const GTile& tl, const GTile& nx, bool has_next  , bool chain  , bool pre, u32x4 (&ra)[4], u32x4 (&rb)[4], char* smem, f32x16 (&acc)[2][4]) {
;     ...
;   const int nk = K / 64;
;   if (!pre) { G_LOAD(0); G_STORE(0); G_LOAD(1); }
;   for (int kt = 0; kt < nk; ++kt) {
;     __syncthreads();
;     G_COMPUTE(kt & 1, kt);
;   }
	global_load_dwordx4 v[158:161], v[128:129], off offset:2944
	global_load_dwordx4 v[162:165], v[132:133], off offset:2944
	s_waitcnt vmcnt(9)
	ds_write_b128 v191, v[200:203]
	s_waitcnt vmcnt(8)
	ds_write_b128 v191, v[208:211] offset:36864
	ds_read_b128 v[200:203], v169
	ds_read_b128 v[208:211], v169 offset:4608
	ds_read_b128 v[228:231], v168
	ds_read_b128 v[232:235], v168 offset:4608
	s_setprio 1
	s_waitcnt lgkmcnt(1)
	v_mfma_f32_32x32x16_bf16 v[112:127], v[200:203], v[228:231], v[112:127]
	v_mfma_f32_32x32x16_bf16 v[48:63], v[208:211], v[228:231], v[48:63]
	s_waitcnt lgkmcnt(0)
	v_mfma_f32_32x32x16_bf16 v[96:111], v[200:203], v[232:235], v[96:111]
	v_mfma_f32_32x32x16_bf16 v[32:47], v[208:211], v[232:235], v[32:47]
	ds_read_b128 v[228:231], v168 offset:9216
	ds_read_b128 v[232:235], v168 offset:13824
	s_waitcnt vmcnt(7)
	ds_write_b128 v191, v[212:215] offset:9216
	s_waitcnt vmcnt(6)
	ds_write_b128 v191, v[216:219] offset:46080
	ds_read_b128 v[212:215], v169 offset:32
	ds_read_b128 v[216:219], v169 offset:4640
	s_waitcnt lgkmcnt(5)
	v_mfma_f32_32x32x16_bf16 v[80:95], v[200:203], v[228:231], v[80:95]
	v_mfma_f32_32x32x16_bf16 v[16:31], v[208:211], v[228:231], v[16:31]
	ds_read_b128 v[228:231], v168 offset:32
	s_waitcnt lgkmcnt(5)
	v_mfma_f32_32x32x16_bf16 v[64:79], v[200:203], v[232:235], v[64:79]
	v_mfma_f32_32x32x16_bf16 v[0:15], v[208:211], v[232:235], v[0:15]
	ds_read_b128 v[232:235], v168 offset:4640
	global_load_dwordx4 v[200:203], v[136:137], off offset:2944
	global_load_dwordx4 v[208:211], v[140:141], off offset:2944
	s_waitcnt lgkmcnt(1)
	v_mfma_f32_32x32x16_bf16 v[112:127], v[212:215], v[228:231], v[112:127]
	v_mfma_f32_32x32x16_bf16 v[48:63], v[216:219], v[228:231], v[48:63]
	s_waitcnt lgkmcnt(0)
	v_mfma_f32_32x32x16_bf16 v[96:111], v[212:215], v[232:235], v[96:111]
	v_mfma_f32_32x32x16_bf16 v[32:47], v[216:219], v[232:235], v[32:47]
	ds_read_b128 v[228:231], v168 offset:9248
	ds_read_b128 v[232:235], v168 offset:13856
	s_waitcnt vmcnt(7)
	ds_write_b128 v191, v[178:181] offset:18432
	s_waitcnt vmcnt(6)
	ds_write_b128 v191, v[220:223] offset:55296
	ds_read_b128 v[178:181], v169 offset:64
	ds_read_b128 v[220:223], v169 offset:4672
	s_waitcnt lgkmcnt(5)
	v_mfma_f32_32x32x16_bf16 v[80:95], v[212:215], v[228:231], v[80:95]
	v_mfma_f32_32x32x16_bf16 v[16:31], v[216:219], v[228:231], v[16:31]
	ds_read_b128 v[228:231], v168 offset:64
	s_waitcnt lgkmcnt(5)
	v_mfma_f32_32x32x16_bf16 v[64:79], v[212:215], v[232:235], v[64:79]
	v_mfma_f32_32x32x16_bf16 v[0:15], v[216:219], v[232:235], v[0:15]
	ds_read_b128 v[232:235], v168 offset:4672
	global_load_dwordx4 v[212:215], v[144:145], off offset:2944
	global_load_dwordx4 v[216:219], v[148:149], off offset:2944
	s_waitcnt lgkmcnt(1)
	v_mfma_f32_32x32x16_bf16 v[112:127], v[178:181], v[228:231], v[112:127]
	v_mfma_f32_32x32x16_bf16 v[48:63], v[220:223], v[228:231], v[48:63]
	s_waitcnt lgkmcnt(0)
	v_mfma_f32_32x32x16_bf16 v[96:111], v[178:181], v[232:235], v[96:111]
	v_mfma_f32_32x32x16_bf16 v[32:47], v[220:223], v[232:235], v[32:47]
	ds_read_b128 v[228:231], v168 offset:9280
	ds_read_b128 v[232:235], v168 offset:13888
	s_waitcnt vmcnt(7)
	ds_write_b128 v191, v[172:175] offset:27648
	s_waitcnt vmcnt(6)
	ds_write_b128 v191, v[224:227] offset:64512
	ds_read_b128 v[172:175], v169 offset:96
	ds_read_b128 v[224:227], v169 offset:4704
	s_waitcnt lgkmcnt(5)
	v_mfma_f32_32x32x16_bf16 v[80:95], v[178:181], v[228:231], v[80:95]
	v_mfma_f32_32x32x16_bf16 v[16:31], v[220:223], v[228:231], v[16:31]
	ds_read_b128 v[228:231], v168 offset:96
	s_waitcnt lgkmcnt(5)
	v_mfma_f32_32x32x16_bf16 v[64:79], v[178:181], v[232:235], v[64:79]
	v_mfma_f32_32x32x16_bf16 v[0:15], v[220:223], v[232:235], v[0:15]
	ds_read_b128 v[232:235], v168 offset:4704
	global_load_dwordx4 v[178:181], v[152:153], off offset:2944
	global_load_dwordx4 v[220:223], v[156:157], off offset:2944
	s_waitcnt lgkmcnt(1)
	v_mfma_f32_32x32x16_bf16 v[112:127], v[172:175], v[228:231], v[112:127]
	v_mfma_f32_32x32x16_bf16 v[48:63], v[224:227], v[228:231], v[48:63]
	s_waitcnt lgkmcnt(0)
	v_mfma_f32_32x32x16_bf16 v[96:111], v[172:175], v[232:235], v[96:111]
	v_mfma_f32_32x32x16_bf16 v[32:47], v[224:227], v[232:235], v[32:47]
	ds_read_b128 v[228:231], v168 offset:9312
	ds_read_b128 v[232:235], v168 offset:13920
	s_waitcnt lgkmcnt(1)
	v_mfma_f32_32x32x16_bf16 v[80:95], v[172:175], v[228:231], v[80:95]
	v_mfma_f32_32x32x16_bf16 v[16:31], v[224:227], v[228:231], v[16:31]
	s_waitcnt lgkmcnt(0)
	v_mfma_f32_32x32x16_bf16 v[64:79], v[172:175], v[232:235], v[64:79]
	v_mfma_f32_32x32x16_bf16 v[0:15], v[224:227], v[232:235], v[0:15]
	s_setprio 0
	s_barrier
; template <bool trans>
; DI void gemm_core(const GTile& tl, const GTile& nx, bool has_next  , bool chain  , bool pre, u32x4 (&ra)[4], u32x4 (&rb)[4], char* smem, f32x16 (&acc)[2][4]) {
;     ...
;   const int nk = K / 64;
;   if (!pre) { G_LOAD(0); G_STORE(0); G_LOAD(1); }
;   for (int kt = 0; kt < nk; ++kt) {
;     __syncthreads();
;     G_COMPUTE(kt & 1, kt);
;   }
	global_load_dwordx4 v[172:175], v[128:129], off offset:3072
	global_load_dwordx4 v[224:227], v[132:133], off offset:3072
	s_waitcnt vmcnt(9)
	ds_write_b128 v195, v[158:161]
	s_waitcnt vmcnt(8)
	ds_write_b128 v196, v[162:165]
	ds_read_b128 v[158:161], v192 offset:36864
	ds_read_b128 v[162:165], v192 offset:41472
	ds_read_b128 v[228:231], v184
	ds_read_b128 v[232:235], v184 offset:4608
	s_setprio 1
	s_waitcnt lgkmcnt(1)
	v_mfma_f32_32x32x16_bf16 v[112:127], v[158:161], v[228:231], v[112:127]
	v_mfma_f32_32x32x16_bf16 v[48:63], v[162:165], v[228:231], v[48:63]
	s_waitcnt lgkmcnt(0)
	v_mfma_f32_32x32x16_bf16 v[96:111], v[158:161], v[232:235], v[96:111]
	v_mfma_f32_32x32x16_bf16 v[32:47], v[162:165], v[232:235], v[32:47]
	ds_read_b128 v[228:231], v184 offset:9216
	ds_read_b128 v[232:235], v184 offset:13824
	s_waitcnt vmcnt(7)
	ds_write_b128 v194, v[200:203]
	s_waitcnt vmcnt(6)
	ds_write_b128 v193, v[208:211]
	ds_read_b128 v[200:203], v192 offset:36896
	ds_read_b128 v[208:211], v192 offset:41504
	s_waitcnt lgkmcnt(5)
	v_mfma_f32_32x32x16_bf16 v[80:95], v[158:161], v[228:231], v[80:95]
	v_mfma_f32_32x32x16_bf16 v[16:31], v[162:165], v[228:231], v[16:31]
	ds_read_b128 v[228:231], v184 offset:32
	s_waitcnt lgkmcnt(5)
	v_mfma_f32_32x32x16_bf16 v[64:79], v[158:161], v[232:235], v[64:79]
	v_mfma_f32_32x32x16_bf16 v[0:15], v[162:165], v[232:235], v[0:15]
	ds_read_b128 v[232:235], v184 offset:4640
	global_load_dwordx4 v[158:161], v[136:137], off offset:3072
	global_load_dwordx4 v[162:165], v[140:141], off offset:3072
	s_waitcnt lgkmcnt(1)
	v_mfma_f32_32x32x16_bf16 v[112:127], v[200:203], v[228:231], v[112:127]
	v_mfma_f32_32x32x16_bf16 v[48:63], v[208:211], v[228:231], v[48:63]
	s_waitcnt lgkmcnt(0)
	v_mfma_f32_32x32x16_bf16 v[96:111], v[200:203], v[232:235], v[96:111]
	v_mfma_f32_32x32x16_bf16 v[32:47], v[208:211], v[232:235], v[32:47]
	ds_read_b128 v[228:231], v184 offset:9248
	ds_read_b128 v[232:235], v184 offset:13856
	s_waitcnt vmcnt(7)
	ds_write_b128 v177, v[212:215]
	s_waitcnt vmcnt(6)
	ds_write_b128 v176, v[216:219]
	ds_read_b128 v[212:215], v192 offset:36928
	ds_read_b128 v[216:219], v192 offset:41536
	s_waitcnt lgkmcnt(5)
	v_mfma_f32_32x32x16_bf16 v[80:95], v[200:203], v[228:231], v[80:95]
	v_mfma_f32_32x32x16_bf16 v[16:31], v[208:211], v[228:231], v[16:31]
	ds_read_b128 v[228:231], v184 offset:64
	s_waitcnt lgkmcnt(5)
	v_mfma_f32_32x32x16_bf16 v[64:79], v[200:203], v[232:235], v[64:79]
	v_mfma_f32_32x32x16_bf16 v[0:15], v[208:211], v[232:235], v[0:15]
	ds_read_b128 v[232:235], v184 offset:4672
	global_load_dwordx4 v[200:203], v[144:145], off offset:3072
	global_load_dwordx4 v[208:211], v[148:149], off offset:3072
	s_waitcnt lgkmcnt(1)
	v_mfma_f32_32x32x16_bf16 v[112:127], v[212:215], v[228:231], v[112:127]
	v_mfma_f32_32x32x16_bf16 v[48:63], v[216:219], v[228:231], v[48:63]
	s_waitcnt lgkmcnt(0)
	v_mfma_f32_32x32x16_bf16 v[96:111], v[212:215], v[232:235], v[96:111]
	v_mfma_f32_32x32x16_bf16 v[32:47], v[216:219], v[232:235], v[32:47]
	ds_read_b128 v[228:231], v184 offset:9280
	ds_read_b128 v[232:235], v184 offset:13888
	s_waitcnt vmcnt(7)
	ds_write_b128 v171, v[178:181]
	s_waitcnt vmcnt(6)
	ds_write_b128 v170, v[220:223]
	ds_read_b128 v[178:181], v192 offset:36960
	ds_read_b128 v[220:223], v192 offset:41568
	s_waitcnt lgkmcnt(5)
	v_mfma_f32_32x32x16_bf16 v[80:95], v[212:215], v[228:231], v[80:95]
	v_mfma_f32_32x32x16_bf16 v[16:31], v[216:219], v[228:231], v[16:31]
	ds_read_b128 v[228:231], v184 offset:96
	s_waitcnt lgkmcnt(5)
	v_mfma_f32_32x32x16_bf16 v[64:79], v[212:215], v[232:235], v[64:79]
	v_mfma_f32_32x32x16_bf16 v[0:15], v[216:219], v[232:235], v[0:15]
	ds_read_b128 v[232:235], v184 offset:4704
	global_load_dwordx4 v[212:215], v[152:153], off offset:3072
	global_load_dwordx4 v[216:219], v[156:157], off offset:3072
	s_waitcnt lgkmcnt(1)
	v_mfma_f32_32x32x16_bf16 v[112:127], v[178:181], v[228:231], v[112:127]
	v_mfma_f32_32x32x16_bf16 v[48:63], v[220:223], v[228:231], v[48:63]
	s_waitcnt lgkmcnt(0)
	v_mfma_f32_32x32x16_bf16 v[96:111], v[178:181], v[232:235], v[96:111]
	v_mfma_f32_32x32x16_bf16 v[32:47], v[220:223], v[232:235], v[32:47]
	ds_read_b128 v[228:231], v184 offset:9312
	ds_read_b128 v[232:235], v184 offset:13920
	s_waitcnt lgkmcnt(1)
	v_mfma_f32_32x32x16_bf16 v[80:95], v[178:181], v[228:231], v[80:95]
	v_mfma_f32_32x32x16_bf16 v[16:31], v[220:223], v[228:231], v[16:31]
	s_waitcnt lgkmcnt(0)
	v_mfma_f32_32x32x16_bf16 v[64:79], v[178:181], v[232:235], v[64:79]
	v_mfma_f32_32x32x16_bf16 v[0:15], v[220:223], v[232:235], v[0:15]
	s_setprio 0
	s_barrier
; template <bool trans>
; DI void gemm_core(const GTile& tl, const GTile& nx, bool has_next  , bool chain  , bool pre, u32x4 (&ra)[4], u32x4 (&rb)[4], char* smem, f32x16 (&acc)[2][4]) {
;     ...
;   const int nk = K / 64;
;   if (!pre) { G_LOAD(0); G_STORE(0); G_LOAD(1); }
;   for (int kt = 0; kt < nk; ++kt) {
;     __syncthreads();
;     G_COMPUTE(kt & 1, kt);
;   }
	global_load_dwordx4 v[178:181], v[128:129], off offset:3200
	global_load_dwordx4 v[220:223], v[132:133], off offset:3200
	s_waitcnt vmcnt(9)
	ds_write_b128 v191, v[172:175]
	s_waitcnt vmcnt(8)
	ds_write_b128 v191, v[224:227] offset:36864
	ds_read_b128 v[172:175], v169
	ds_read_b128 v[224:227], v169 offset:4608
	ds_read_b128 v[228:231], v168
	ds_read_b128 v[232:235], v168 offset:4608
	s_setprio 1
	s_waitcnt lgkmcnt(1)
	v_mfma_f32_32x32x16_bf16 v[112:127], v[172:175], v[228:231], v[112:127]
	v_mfma_f32_32x32x16_bf16 v[48:63], v[224:227], v[228:231], v[48:63]
	s_waitcnt lgkmcnt(0)
	v_mfma_f32_32x32x16_bf16 v[96:111], v[172:175], v[232:235], v[96:111]
	v_mfma_f32_32x32x16_bf16 v[32:47], v[224:227], v[232:235], v[32:47]
	ds_read_b128 v[228:231], v168 offset:9216
	ds_read_b128 v[232:235], v168 offset:13824
	s_waitcnt vmcnt(7)
	ds_write_b128 v191, v[158:161] offset:9216
	s_waitcnt vmcnt(6)
	ds_write_b128 v191, v[162:165] offset:46080
	ds_read_b128 v[158:161], v169 offset:32
	ds_read_b128 v[162:165], v169 offset:4640
	s_waitcnt lgkmcnt(5)
	v_mfma_f32_32x32x16_bf16 v[80:95], v[172:175], v[228:231], v[80:95]
	v_mfma_f32_32x32x16_bf16 v[16:31], v[224:227], v[228:231], v[16:31]
	ds_read_b128 v[228:231], v168 offset:32
	s_waitcnt lgkmcnt(5)
	v_mfma_f32_32x32x16_bf16 v[64:79], v[172:175], v[232:235], v[64:79]
	v_mfma_f32_32x32x16_bf16 v[0:15], v[224:227], v[232:235], v[0:15]
	ds_read_b128 v[232:235], v168 offset:4640
	global_load_dwordx4 v[172:175], v[136:137], off offset:3200
	global_load_dwordx4 v[224:227], v[140:141], off offset:3200
	s_waitcnt lgkmcnt(1)
	v_mfma_f32_32x32x16_bf16 v[112:127], v[158:161], v[228:231], v[112:127]
	v_mfma_f32_32x32x16_bf16 v[48:63], v[162:165], v[228:231], v[48:63]
	s_waitcnt lgkmcnt(0)
	v_mfma_f32_32x32x16_bf16 v[96:111], v[158:161], v[232:235], v[96:111]
	v_mfma_f32_32x32x16_bf16 v[32:47], v[162:165], v[232:235], v[32:47]
	ds_read_b128 v[228:231], v168 offset:9248
	ds_read_b128 v[232:235], v168 offset:13856
	s_waitcnt vmcnt(7)
	ds_write_b128 v191, v[200:203] offset:18432
	s_waitcnt vmcnt(6)
	ds_write_b128 v191, v[208:211] offset:55296
	ds_read_b128 v[200:203], v169 offset:64
	ds_read_b128 v[208:211], v169 offset:4672
	s_waitcnt lgkmcnt(5)
	v_mfma_f32_32x32x16_bf16 v[80:95], v[158:161], v[228:231], v[80:95]
	v_mfma_f32_32x32x16_bf16 v[16:31], v[162:165], v[228:231], v[16:31]
	ds_read_b128 v[228:231], v168 offset:64
	s_waitcnt lgkmcnt(5)
	v_mfma_f32_32x32x16_bf16 v[64:79], v[158:161], v[232:235], v[64:79]
	v_mfma_f32_32x32x16_bf16 v[0:15], v[162:165], v[232:235], v[0:15]
	ds_read_b128 v[232:235], v168 offset:4672
	global_load_dwordx4 v[158:161], v[144:145], off offset:3200
	global_load_dwordx4 v[162:165], v[148:149], off offset:3200
	s_waitcnt lgkmcnt(1)
	v_mfma_f32_32x32x16_bf16 v[112:127], v[200:203], v[228:231], v[112:127]
	v_mfma_f32_32x32x16_bf16 v[48:63], v[208:211], v[228:231], v[48:63]
	s_waitcnt lgkmcnt(0)
	v_mfma_f32_32x32x16_bf16 v[96:111], v[200:203], v[232:235], v[96:111]
	v_mfma_f32_32x32x16_bf16 v[32:47], v[208:211], v[232:235], v[32:47]
	ds_read_b128 v[228:231], v168 offset:9280
	ds_read_b128 v[232:235], v168 offset:13888
	s_waitcnt vmcnt(7)
	ds_write_b128 v191, v[212:215] offset:27648
	s_waitcnt vmcnt(6)
	ds_write_b128 v191, v[216:219] offset:64512
	ds_read_b128 v[212:215], v169 offset:96
	ds_read_b128 v[216:219], v169 offset:4704
	s_waitcnt lgkmcnt(5)
	v_mfma_f32_32x32x16_bf16 v[80:95], v[200:203], v[228:231], v[80:95]
	v_mfma_f32_32x32x16_bf16 v[16:31], v[208:211], v[228:231], v[16:31]
	ds_read_b128 v[228:231], v168 offset:96
	s_waitcnt lgkmcnt(5)
	v_mfma_f32_32x32x16_bf16 v[64:79], v[200:203], v[232:235], v[64:79]
	v_mfma_f32_32x32x16_bf16 v[0:15], v[208:211], v[232:235], v[0:15]
	ds_read_b128 v[232:235], v168 offset:4704
	global_load_dwordx4 v[200:203], v[152:153], off offset:3200
	global_load_dwordx4 v[208:211], v[156:157], off offset:3200
	s_waitcnt lgkmcnt(1)
	v_mfma_f32_32x32x16_bf16 v[112:127], v[212:215], v[228:231], v[112:127]
	v_mfma_f32_32x32x16_bf16 v[48:63], v[216:219], v[228:231], v[48:63]
	s_waitcnt lgkmcnt(0)
	v_mfma_f32_32x32x16_bf16 v[96:111], v[212:215], v[232:235], v[96:111]
	v_mfma_f32_32x32x16_bf16 v[32:47], v[216:219], v[232:235], v[32:47]
	ds_read_b128 v[228:231], v168 offset:9312
	ds_read_b128 v[232:235], v168 offset:13920
	s_waitcnt lgkmcnt(1)
	v_mfma_f32_32x32x16_bf16 v[80:95], v[212:215], v[228:231], v[80:95]
	v_mfma_f32_32x32x16_bf16 v[16:31], v[216:219], v[228:231], v[16:31]
	s_waitcnt lgkmcnt(0)
	v_mfma_f32_32x32x16_bf16 v[64:79], v[212:215], v[232:235], v[64:79]
	v_mfma_f32_32x32x16_bf16 v[0:15], v[216:219], v[232:235], v[0:15]
	s_setprio 0
	s_barrier
; template <bool trans>
; DI void gemm_core(const GTile& tl, const GTile& nx, bool has_next  , bool chain  , bool pre, u32x4 (&ra)[4], u32x4 (&rb)[4], char* smem, f32x16 (&acc)[2][4]) {
;     ...
;   const int nk = K / 64;
;   if (!pre) { G_LOAD(0); G_STORE(0); G_LOAD(1); }
;   for (int kt = 0; kt < nk; ++kt) {
;     __syncthreads();
;     G_COMPUTE(kt & 1, kt);
;   }
	global_load_dwordx4 v[212:215], v[128:129], off offset:3328
	global_load_dwordx4 v[216:219], v[132:133], off offset:3328
	s_waitcnt vmcnt(9)
	ds_write_b128 v195, v[178:181]
	s_waitcnt vmcnt(8)
	ds_write_b128 v196, v[220:223]
	ds_read_b128 v[178:181], v192 offset:36864
	ds_read_b128 v[220:223], v192 offset:41472
	ds_read_b128 v[228:231], v184
	ds_read_b128 v[232:235], v184 offset:4608
	s_setprio 1
	s_waitcnt lgkmcnt(1)
	v_mfma_f32_32x32x16_bf16 v[112:127], v[178:181], v[228:231], v[112:127]
	v_mfma_f32_32x32x16_bf16 v[48:63], v[220:223], v[228:231], v[48:63]
	s_waitcnt lgkmcnt(0)
	v_mfma_f32_32x32x16_bf16 v[96:111], v[178:181], v[232:235], v[96:111]
	v_mfma_f32_32x32x16_bf16 v[32:47], v[220:223], v[232:235], v[32:47]
	ds_read_b128 v[228:231], v184 offset:9216
	ds_read_b128 v[232:235], v184 offset:13824
	s_waitcnt vmcnt(7)
	ds_write_b128 v194, v[172:175]
	s_waitcnt vmcnt(6)
	ds_write_b128 v193, v[224:227]
	ds_read_b128 v[172:175], v192 offset:36896
	ds_read_b128 v[224:227], v192 offset:41504
	s_waitcnt lgkmcnt(5)
	v_mfma_f32_32x32x16_bf16 v[80:95], v[178:181], v[228:231], v[80:95]
	v_mfma_f32_32x32x16_bf16 v[16:31], v[220:223], v[228:231], v[16:31]
	ds_read_b128 v[228:231], v184 offset:32
	s_waitcnt lgkmcnt(5)
	v_mfma_f32_32x32x16_bf16 v[64:79], v[178:181], v[232:235], v[64:79]
	v_mfma_f32_32x32x16_bf16 v[0:15], v[220:223], v[232:235], v[0:15]
	ds_read_b128 v[232:235], v184 offset:4640
	global_load_dwordx4 v[178:181], v[136:137], off offset:3328
	global_load_dwordx4 v[220:223], v[140:141], off offset:3328
	s_waitcnt lgkmcnt(1)
	v_mfma_f32_32x32x16_bf16 v[112:127], v[172:175], v[228:231], v[112:127]
	v_mfma_f32_32x32x16_bf16 v[48:63], v[224:227], v[228:231], v[48:63]
	s_waitcnt lgkmcnt(0)
	v_mfma_f32_32x32x16_bf16 v[96:111], v[172:175], v[232:235], v[96:111]
	v_mfma_f32_32x32x16_bf16 v[32:47], v[224:227], v[232:235], v[32:47]
	ds_read_b128 v[228:231], v184 offset:9248
	ds_read_b128 v[232:235], v184 offset:13856
	s_waitcnt vmcnt(7)
	ds_write_b128 v177, v[158:161]
	s_waitcnt vmcnt(6)
	ds_write_b128 v176, v[162:165]
	ds_read_b128 v[158:161], v192 offset:36928
	ds_read_b128 v[162:165], v192 offset:41536
	s_waitcnt lgkmcnt(5)
	v_mfma_f32_32x32x16_bf16 v[80:95], v[172:175], v[228:231], v[80:95]
	v_mfma_f32_32x32x16_bf16 v[16:31], v[224:227], v[228:231], v[16:31]
	ds_read_b128 v[228:231], v184 offset:64
	s_waitcnt lgkmcnt(5)
	v_mfma_f32_32x32x16_bf16 v[64:79], v[172:175], v[232:235], v[64:79]
	v_mfma_f32_32x32x16_bf16 v[0:15], v[224:227], v[232:235], v[0:15]
	ds_read_b128 v[232:235], v184 offset:4672
	global_load_dwordx4 v[172:175], v[144:145], off offset:3328
	global_load_dwordx4 v[224:227], v[148:149], off offset:3328
	s_waitcnt lgkmcnt(1)
	v_mfma_f32_32x32x16_bf16 v[112:127], v[158:161], v[228:231], v[112:127]
	v_mfma_f32_32x32x16_bf16 v[48:63], v[162:165], v[228:231], v[48:63]
	s_waitcnt lgkmcnt(0)
	v_mfma_f32_32x32x16_bf16 v[96:111], v[158:161], v[232:235], v[96:111]
	v_mfma_f32_32x32x16_bf16 v[32:47], v[162:165], v[232:235], v[32:47]
	ds_read_b128 v[228:231], v184 offset:9280
	ds_read_b128 v[232:235], v184 offset:13888
	s_waitcnt vmcnt(7)
	ds_write_b128 v171, v[200:203]
	s_waitcnt vmcnt(6)
	ds_write_b128 v170, v[208:211]
	ds_read_b128 v[200:203], v192 offset:36960
	ds_read_b128 v[208:211], v192 offset:41568
	s_waitcnt lgkmcnt(5)
	v_mfma_f32_32x32x16_bf16 v[80:95], v[158:161], v[228:231], v[80:95]
	v_mfma_f32_32x32x16_bf16 v[16:31], v[162:165], v[228:231], v[16:31]
	ds_read_b128 v[228:231], v184 offset:96
	s_waitcnt lgkmcnt(5)
	v_mfma_f32_32x32x16_bf16 v[64:79], v[158:161], v[232:235], v[64:79]
	v_mfma_f32_32x32x16_bf16 v[0:15], v[162:165], v[232:235], v[0:15]
	ds_read_b128 v[232:235], v184 offset:4704
	global_load_dwordx4 v[158:161], v[152:153], off offset:3328
	global_load_dwordx4 v[162:165], v[156:157], off offset:3328
	s_waitcnt lgkmcnt(1)
	v_mfma_f32_32x32x16_bf16 v[112:127], v[200:203], v[228:231], v[112:127]
	v_mfma_f32_32x32x16_bf16 v[48:63], v[208:211], v[228:231], v[48:63]
	s_waitcnt lgkmcnt(0)
	v_mfma_f32_32x32x16_bf16 v[96:111], v[200:203], v[232:235], v[96:111]
	v_mfma_f32_32x32x16_bf16 v[32:47], v[208:211], v[232:235], v[32:47]
	ds_read_b128 v[228:231], v184 offset:9312
	ds_read_b128 v[232:235], v184 offset:13920
	s_waitcnt lgkmcnt(1)
	v_mfma_f32_32x32x16_bf16 v[80:95], v[200:203], v[228:231], v[80:95]
	v_mfma_f32_32x32x16_bf16 v[16:31], v[208:211], v[228:231], v[16:31]
	s_waitcnt lgkmcnt(0)
	v_mfma_f32_32x32x16_bf16 v[64:79], v[200:203], v[232:235], v[64:79]
	v_mfma_f32_32x32x16_bf16 v[0:15], v[208:211], v[232:235], v[0:15]
	s_setprio 0
	s_barrier
; template <bool trans>
; DI void gemm_core(const GTile& tl, const GTile& nx, bool has_next  , bool chain  , bool pre, u32x4 (&ra)[4], u32x4 (&rb)[4], char* smem, f32x16 (&acc)[2][4]) {
;     ...
;   const int nk = K / 64;
;   if (!pre) { G_LOAD(0); G_STORE(0); G_LOAD(1); }
;   for (int kt = 0; kt < nk; ++kt) {
;     __syncthreads();
;     G_COMPUTE(kt & 1, kt);
;   }
	global_load_dwordx4 v[200:203], v[128:129], off offset:3456
	global_load_dwordx4 v[208:211], v[132:133], off offset:3456
	s_waitcnt vmcnt(9)
	ds_write_b128 v191, v[212:215]
	s_waitcnt vmcnt(8)
	ds_write_b128 v191, v[216:219] offset:36864
	ds_read_b128 v[212:215], v169
	ds_read_b128 v[216:219], v169 offset:4608
	ds_read_b128 v[228:231], v168
	ds_read_b128 v[232:235], v168 offset:4608
	s_setprio 1
	s_waitcnt lgkmcnt(1)
	v_mfma_f32_32x32x16_bf16 v[112:127], v[212:215], v[228:231], v[112:127]
	v_mfma_f32_32x32x16_bf16 v[48:63], v[216:219], v[228:231], v[48:63]
	s_waitcnt lgkmcnt(0)
	v_mfma_f32_32x32x16_bf16 v[96:111], v[212:215], v[232:235], v[96:111]
	v_mfma_f32_32x32x16_bf16 v[32:47], v[216:219], v[232:235], v[32:47]
	ds_read_b128 v[228:231], v168 offset:9216
	ds_read_b128 v[232:235], v168 offset:13824
	s_waitcnt vmcnt(7)
	ds_write_b128 v191, v[178:181] offset:9216
	s_waitcnt vmcnt(6)
	ds_write_b128 v191, v[220:223] offset:46080
	ds_read_b128 v[178:181], v169 offset:32
	ds_read_b128 v[220:223], v169 offset:4640
	s_waitcnt lgkmcnt(5)
	v_mfma_f32_32x32x16_bf16 v[80:95], v[212:215], v[228:231], v[80:95]
	v_mfma_f32_32x32x16_bf16 v[16:31], v[216:219], v[228:231], v[16:31]
	ds_read_b128 v[228:231], v168 offset:32
	s_waitcnt lgkmcnt(5)
	v_mfma_f32_32x32x16_bf16 v[64:79], v[212:215], v[232:235], v[64:79]
	v_mfma_f32_32x32x16_bf16 v[0:15], v[216:219], v[232:235], v[0:15]
	ds_read_b128 v[232:235], v168 offset:4640
	global_load_dwordx4 v[212:215], v[136:137], off offset:3456
	global_load_dwordx4 v[216:219], v[140:141], off offset:3456
	s_waitcnt lgkmcnt(1)
	v_mfma_f32_32x32x16_bf16 v[112:127], v[178:181], v[228:231], v[112:127]
	v_mfma_f32_32x32x16_bf16 v[48:63], v[220:223], v[228:231], v[48:63]
	s_waitcnt lgkmcnt(0)
	v_mfma_f32_32x32x16_bf16 v[96:111], v[178:181], v[232:235], v[96:111]
	v_mfma_f32_32x32x16_bf16 v[32:47], v[220:223], v[232:235], v[32:47]
	ds_read_b128 v[228:231], v168 offset:9248
	ds_read_b128 v[232:235], v168 offset:13856
	s_waitcnt vmcnt(7)
	ds_write_b128 v191, v[172:175] offset:18432
	s_waitcnt vmcnt(6)
	ds_write_b128 v191, v[224:227] offset:55296
	ds_read_b128 v[172:175], v169 offset:64
	ds_read_b128 v[224:227], v169 offset:4672
	s_waitcnt lgkmcnt(5)
	v_mfma_f32_32x32x16_bf16 v[80:95], v[178:181], v[228:231], v[80:95]
	v_mfma_f32_32x32x16_bf16 v[16:31], v[220:223], v[228:231], v[16:31]
	ds_read_b128 v[228:231], v168 offset:64
	s_waitcnt lgkmcnt(5)
	v_mfma_f32_32x32x16_bf16 v[64:79], v[178:181], v[232:235], v[64:79]
	v_mfma_f32_32x32x16_bf16 v[0:15], v[220:223], v[232:235], v[0:15]
	ds_read_b128 v[232:235], v168 offset:4672
	global_load_dwordx4 v[178:181], v[144:145], off offset:3456
	global_load_dwordx4 v[220:223], v[148:149], off offset:3456
	s_waitcnt lgkmcnt(1)
	v_mfma_f32_32x32x16_bf16 v[112:127], v[172:175], v[228:231], v[112:127]
	v_mfma_f32_32x32x16_bf16 v[48:63], v[224:227], v[228:231], v[48:63]
	s_waitcnt lgkmcnt(0)
	v_mfma_f32_32x32x16_bf16 v[96:111], v[172:175], v[232:235], v[96:111]
	v_mfma_f32_32x32x16_bf16 v[32:47], v[224:227], v[232:235], v[32:47]
	ds_read_b128 v[228:231], v168 offset:9280
	ds_read_b128 v[232:235], v168 offset:13888
	s_waitcnt vmcnt(7)
	ds_write_b128 v191, v[158:161] offset:27648
	s_waitcnt vmcnt(6)
	ds_write_b128 v191, v[162:165] offset:64512
	ds_read_b128 v[158:161], v169 offset:96
	ds_read_b128 v[162:165], v169 offset:4704
	s_waitcnt lgkmcnt(5)
	v_mfma_f32_32x32x16_bf16 v[80:95], v[172:175], v[228:231], v[80:95]
	v_mfma_f32_32x32x16_bf16 v[16:31], v[224:227], v[228:231], v[16:31]
	ds_read_b128 v[228:231], v168 offset:96
	s_waitcnt lgkmcnt(5)
	v_mfma_f32_32x32x16_bf16 v[64:79], v[172:175], v[232:235], v[64:79]
	v_mfma_f32_32x32x16_bf16 v[0:15], v[224:227], v[232:235], v[0:15]
	ds_read_b128 v[232:235], v168 offset:4704
	global_load_dwordx4 v[172:175], v[152:153], off offset:3456
	global_load_dwordx4 v[224:227], v[156:157], off offset:3456
	s_waitcnt lgkmcnt(1)
	v_mfma_f32_32x32x16_bf16 v[112:127], v[158:161], v[228:231], v[112:127]
	v_mfma_f32_32x32x16_bf16 v[48:63], v[162:165], v[228:231], v[48:63]
	s_waitcnt lgkmcnt(0)
	v_mfma_f32_32x32x16_bf16 v[96:111], v[158:161], v[232:235], v[96:111]
	v_mfma_f32_32x32x16_bf16 v[32:47], v[162:165], v[232:235], v[32:47]
	ds_read_b128 v[228:231], v168 offset:9312
	ds_read_b128 v[232:235], v168 offset:13920
	s_waitcnt lgkmcnt(1)
	v_mfma_f32_32x32x16_bf16 v[80:95], v[158:161], v[228:231], v[80:95]
	v_mfma_f32_32x32x16_bf16 v[16:31], v[162:165], v[228:231], v[16:31]
	s_waitcnt lgkmcnt(0)
	v_mfma_f32_32x32x16_bf16 v[64:79], v[158:161], v[232:235], v[64:79]
	v_mfma_f32_32x32x16_bf16 v[0:15], v[162:165], v[232:235], v[0:15]
	s_setprio 0
	s_barrier
; template <bool trans>
; DI void gemm_core(const GTile& tl, const GTile& nx, bool has_next  , bool chain  , bool pre, u32x4 (&ra)[4], u32x4 (&rb)[4], char* smem, f32x16 (&acc)[2][4]) {
;     ...
;   const int nk = K / 64;
;   if (!pre) { G_LOAD(0); G_STORE(0); G_LOAD(1); }
;   for (int kt = 0; kt < nk; ++kt) {
;     __syncthreads();
;     G_COMPUTE(kt & 1, kt);
;   }
	global_load_dwordx4 v[158:161], v[128:129], off offset:3584
	global_load_dwordx4 v[162:165], v[132:133], off offset:3584
	s_waitcnt vmcnt(9)
	ds_write_b128 v195, v[200:203]
	s_waitcnt vmcnt(8)
	ds_write_b128 v196, v[208:211]
	ds_read_b128 v[200:203], v192 offset:36864
	ds_read_b128 v[208:211], v192 offset:41472
	ds_read_b128 v[228:231], v184
	ds_read_b128 v[232:235], v184 offset:4608
	s_setprio 1
	s_waitcnt lgkmcnt(1)
	v_mfma_f32_32x32x16_bf16 v[112:127], v[200:203], v[228:231], v[112:127]
	v_mfma_f32_32x32x16_bf16 v[48:63], v[208:211], v[228:231], v[48:63]
	s_waitcnt lgkmcnt(0)
	v_mfma_f32_32x32x16_bf16 v[96:111], v[200:203], v[232:235], v[96:111]
	v_mfma_f32_32x32x16_bf16 v[32:47], v[208:211], v[232:235], v[32:47]
	ds_read_b128 v[228:231], v184 offset:9216
	ds_read_b128 v[232:235], v184 offset:13824
	s_waitcnt vmcnt(7)
	ds_write_b128 v194, v[212:215]
	s_waitcnt vmcnt(6)
	ds_write_b128 v193, v[216:219]
	ds_read_b128 v[212:215], v192 offset:36896
	ds_read_b128 v[216:219], v192 offset:41504
	s_waitcnt lgkmcnt(5)
	v_mfma_f32_32x32x16_bf16 v[80:95], v[200:203], v[228:231], v[80:95]
	v_mfma_f32_32x32x16_bf16 v[16:31], v[208:211], v[228:231], v[16:31]
	ds_read_b128 v[228:231], v184 offset:32
	s_waitcnt lgkmcnt(5)
	v_mfma_f32_32x32x16_bf16 v[64:79], v[200:203], v[232:235], v[64:79]
	v_mfma_f32_32x32x16_bf16 v[0:15], v[208:211], v[232:235], v[0:15]
	ds_read_b128 v[232:235], v184 offset:4640
	global_load_dwordx4 v[200:203], v[136:137], off offset:3584
	global_load_dwordx4 v[208:211], v[140:141], off offset:3584
	s_waitcnt lgkmcnt(1)
	v_mfma_f32_32x32x16_bf16 v[112:127], v[212:215], v[228:231], v[112:127]
	v_mfma_f32_32x32x16_bf16 v[48:63], v[216:219], v[228:231], v[48:63]
	s_waitcnt lgkmcnt(0)
	v_mfma_f32_32x32x16_bf16 v[96:111], v[212:215], v[232:235], v[96:111]
	v_mfma_f32_32x32x16_bf16 v[32:47], v[216:219], v[232:235], v[32:47]
	ds_read_b128 v[228:231], v184 offset:9248
	ds_read_b128 v[232:235], v184 offset:13856
	s_waitcnt vmcnt(7)
	ds_write_b128 v177, v[178:181]
	s_waitcnt vmcnt(6)
	ds_write_b128 v176, v[220:223]
	ds_read_b128 v[178:181], v192 offset:36928
	ds_read_b128 v[220:223], v192 offset:41536
	s_waitcnt lgkmcnt(5)
	v_mfma_f32_32x32x16_bf16 v[80:95], v[212:215], v[228:231], v[80:95]
	v_mfma_f32_32x32x16_bf16 v[16:31], v[216:219], v[228:231], v[16:31]
	ds_read_b128 v[228:231], v184 offset:64
	s_waitcnt lgkmcnt(5)
	v_mfma_f32_32x32x16_bf16 v[64:79], v[212:215], v[232:235], v[64:79]
	v_mfma_f32_32x32x16_bf16 v[0:15], v[216:219], v[232:235], v[0:15]
	ds_read_b128 v[232:235], v184 offset:4672
	global_load_dwordx4 v[212:215], v[144:145], off offset:3584
	global_load_dwordx4 v[216:219], v[148:149], off offset:3584
	s_waitcnt lgkmcnt(1)
	v_mfma_f32_32x32x16_bf16 v[112:127], v[178:181], v[228:231], v[112:127]
	v_mfma_f32_32x32x16_bf16 v[48:63], v[220:223], v[228:231], v[48:63]
	s_waitcnt lgkmcnt(0)
	v_mfma_f32_32x32x16_bf16 v[96:111], v[178:181], v[232:235], v[96:111]
	v_mfma_f32_32x32x16_bf16 v[32:47], v[220:223], v[232:235], v[32:47]
	ds_read_b128 v[228:231], v184 offset:9280
	ds_read_b128 v[232:235], v184 offset:13888
	s_waitcnt vmcnt(7)
	ds_write_b128 v171, v[172:175]
	s_waitcnt vmcnt(6)
	ds_write_b128 v170, v[224:227]
	ds_read_b128 v[172:175], v192 offset:36960
	ds_read_b128 v[224:227], v192 offset:41568
	s_waitcnt lgkmcnt(5)
	v_mfma_f32_32x32x16_bf16 v[80:95], v[178:181], v[228:231], v[80:95]
	v_mfma_f32_32x32x16_bf16 v[16:31], v[220:223], v[228:231], v[16:31]
	ds_read_b128 v[228:231], v184 offset:96
	s_waitcnt lgkmcnt(5)
	v_mfma_f32_32x32x16_bf16 v[64:79], v[178:181], v[232:235], v[64:79]
	v_mfma_f32_32x32x16_bf16 v[0:15], v[220:223], v[232:235], v[0:15]
	ds_read_b128 v[232:235], v184 offset:4704
	global_load_dwordx4 v[178:181], v[152:153], off offset:3584
	global_load_dwordx4 v[220:223], v[156:157], off offset:3584
	s_waitcnt lgkmcnt(1)
	v_mfma_f32_32x32x16_bf16 v[112:127], v[172:175], v[228:231], v[112:127]
	v_mfma_f32_32x32x16_bf16 v[48:63], v[224:227], v[228:231], v[48:63]
	s_waitcnt lgkmcnt(0)
	v_mfma_f32_32x32x16_bf16 v[96:111], v[172:175], v[232:235], v[96:111]
	v_mfma_f32_32x32x16_bf16 v[32:47], v[224:227], v[232:235], v[32:47]
	ds_read_b128 v[228:231], v184 offset:9312
	ds_read_b128 v[232:235], v184 offset:13920
	s_waitcnt lgkmcnt(1)
	v_mfma_f32_32x32x16_bf16 v[80:95], v[172:175], v[228:231], v[80:95]
	v_mfma_f32_32x32x16_bf16 v[16:31], v[224:227], v[228:231], v[16:31]
	s_waitcnt lgkmcnt(0)
	v_mfma_f32_32x32x16_bf16 v[64:79], v[172:175], v[232:235], v[64:79]
	v_mfma_f32_32x32x16_bf16 v[0:15], v[224:227], v[232:235], v[0:15]
	s_setprio 0
	s_barrier
; template <bool trans>
; DI void gemm_core(const GTile& tl, const GTile& nx, bool has_next  , bool chain  , bool pre, u32x4 (&ra)[4], u32x4 (&rb)[4], char* smem, f32x16 (&acc)[2][4]) {
;     ...
;   const int nk = K / 64;
;   if (!pre) { G_LOAD(0); G_STORE(0); G_LOAD(1); }
;   for (int kt = 0; kt < nk; ++kt) {
;     __syncthreads();
;     G_COMPUTE(kt & 1, kt);
;   }
	global_load_dwordx4 v[172:175], v[128:129], off offset:3712
	global_load_dwordx4 v[224:227], v[132:133], off offset:3712
	s_waitcnt vmcnt(9)
	ds_write_b128 v191, v[158:161]
	s_waitcnt vmcnt(8)
	ds_write_b128 v191, v[162:165] offset:36864
	ds_read_b128 v[158:161], v169
	ds_read_b128 v[162:165], v169 offset:4608
	ds_read_b128 v[228:231], v168
	ds_read_b128 v[232:235], v168 offset:4608
	s_setprio 1
	s_waitcnt lgkmcnt(1)
	v_mfma_f32_32x32x16_bf16 v[112:127], v[158:161], v[228:231], v[112:127]
	v_mfma_f32_32x32x16_bf16 v[48:63], v[162:165], v[228:231], v[48:63]
	s_waitcnt lgkmcnt(0)
	v_mfma_f32_32x32x16_bf16 v[96:111], v[158:161], v[232:235], v[96:111]
	v_mfma_f32_32x32x16_bf16 v[32:47], v[162:165], v[232:235], v[32:47]
	ds_read_b128 v[228:231], v168 offset:9216
	ds_read_b128 v[232:235], v168 offset:13824
	s_waitcnt vmcnt(7)
	ds_write_b128 v191, v[200:203] offset:9216
	s_waitcnt vmcnt(6)
	ds_write_b128 v191, v[208:211] offset:46080
	ds_read_b128 v[200:203], v169 offset:32
	ds_read_b128 v[208:211], v169 offset:4640
	s_waitcnt lgkmcnt(5)
	v_mfma_f32_32x32x16_bf16 v[80:95], v[158:161], v[228:231], v[80:95]
	v_mfma_f32_32x32x16_bf16 v[16:31], v[162:165], v[228:231], v[16:31]
	ds_read_b128 v[228:231], v168 offset:32
	s_waitcnt lgkmcnt(5)
	v_mfma_f32_32x32x16_bf16 v[64:79], v[158:161], v[232:235], v[64:79]
	v_mfma_f32_32x32x16_bf16 v[0:15], v[162:165], v[232:235], v[0:15]
	ds_read_b128 v[232:235], v168 offset:4640
	global_load_dwordx4 v[158:161], v[136:137], off offset:3712
	global_load_dwordx4 v[162:165], v[140:141], off offset:3712
	s_waitcnt lgkmcnt(1)
	v_mfma_f32_32x32x16_bf16 v[112:127], v[200:203], v[228:231], v[112:127]
	v_mfma_f32_32x32x16_bf16 v[48:63], v[208:211], v[228:231], v[48:63]
	s_waitcnt lgkmcnt(0)
	v_mfma_f32_32x32x16_bf16 v[96:111], v[200:203], v[232:235], v[96:111]
	v_mfma_f32_32x32x16_bf16 v[32:47], v[208:211], v[232:235], v[32:47]
	ds_read_b128 v[228:231], v168 offset:9248
	ds_read_b128 v[232:235], v168 offset:13856
	s_waitcnt vmcnt(7)
	ds_write_b128 v191, v[212:215] offset:18432
	s_waitcnt vmcnt(6)
	ds_write_b128 v191, v[216:219] offset:55296
	ds_read_b128 v[212:215], v169 offset:64
	ds_read_b128 v[216:219], v169 offset:4672
	s_waitcnt lgkmcnt(5)
	v_mfma_f32_32x32x16_bf16 v[80:95], v[200:203], v[228:231], v[80:95]
	v_mfma_f32_32x32x16_bf16 v[16:31], v[208:211], v[228:231], v[16:31]
	ds_read_b128 v[228:231], v168 offset:64
	s_waitcnt lgkmcnt(5)
	v_mfma_f32_32x32x16_bf16 v[64:79], v[200:203], v[232:235], v[64:79]
	v_mfma_f32_32x32x16_bf16 v[0:15], v[208:211], v[232:235], v[0:15]
	ds_read_b128 v[232:235], v168 offset:4672
	global_load_dwordx4 v[200:203], v[144:145], off offset:3712
	global_load_dwordx4 v[208:211], v[148:149], off offset:3712
	s_waitcnt lgkmcnt(1)
	v_mfma_f32_32x32x16_bf16 v[112:127], v[212:215], v[228:231], v[112:127]
	v_mfma_f32_32x32x16_bf16 v[48:63], v[216:219], v[228:231], v[48:63]
	s_waitcnt lgkmcnt(0)
	v_mfma_f32_32x32x16_bf16 v[96:111], v[212:215], v[232:235], v[96:111]
	v_mfma_f32_32x32x16_bf16 v[32:47], v[216:219], v[232:235], v[32:47]
	ds_read_b128 v[228:231], v168 offset:9280
	ds_read_b128 v[232:235], v168 offset:13888
	s_waitcnt vmcnt(7)
	ds_write_b128 v191, v[178:181] offset:27648
	s_waitcnt vmcnt(6)
	ds_write_b128 v191, v[220:223] offset:64512
	ds_read_b128 v[178:181], v169 offset:96
	ds_read_b128 v[220:223], v169 offset:4704
	s_waitcnt lgkmcnt(5)
	v_mfma_f32_32x32x16_bf16 v[80:95], v[212:215], v[228:231], v[80:95]
	v_mfma_f32_32x32x16_bf16 v[16:31], v[216:219], v[228:231], v[16:31]
	ds_read_b128 v[228:231], v168 offset:96
	s_waitcnt lgkmcnt(5)
	v_mfma_f32_32x32x16_bf16 v[64:79], v[212:215], v[232:235], v[64:79]
	v_mfma_f32_32x32x16_bf16 v[0:15], v[216:219], v[232:235], v[0:15]
	ds_read_b128 v[232:235], v168 offset:4704
	global_load_dwordx4 v[212:215], v[152:153], off offset:3712
	global_load_dwordx4 v[216:219], v[156:157], off offset:3712
	s_waitcnt lgkmcnt(1)
	v_mfma_f32_32x32x16_bf16 v[112:127], v[178:181], v[228:231], v[112:127]
	v_mfma_f32_32x32x16_bf16 v[48:63], v[220:223], v[228:231], v[48:63]
	s_waitcnt lgkmcnt(0)
	v_mfma_f32_32x32x16_bf16 v[96:111], v[178:181], v[232:235], v[96:111]
	v_mfma_f32_32x32x16_bf16 v[32:47], v[220:223], v[232:235], v[32:47]
	ds_read_b128 v[228:231], v168 offset:9312
	ds_read_b128 v[232:235], v168 offset:13920
	s_waitcnt lgkmcnt(1)
	v_mfma_f32_32x32x16_bf16 v[80:95], v[178:181], v[228:231], v[80:95]
	v_mfma_f32_32x32x16_bf16 v[16:31], v[220:223], v[228:231], v[16:31]
	s_waitcnt lgkmcnt(0)
	v_mfma_f32_32x32x16_bf16 v[64:79], v[178:181], v[232:235], v[64:79]
	v_mfma_f32_32x32x16_bf16 v[0:15], v[220:223], v[232:235], v[0:15]
	s_setprio 0
	s_barrier
; template <bool trans>
; DI void gemm_core(const GTile& tl, const GTile& nx, bool has_next  , bool chain  , bool pre, u32x4 (&ra)[4], u32x4 (&rb)[4], char* smem, f32x16 (&acc)[2][4]) {
;     ...
;   const int nk = K / 64;
;   if (!pre) { G_LOAD(0); G_STORE(0); G_LOAD(1); }
;   for (int kt = 0; kt < nk; ++kt) {
;     __syncthreads();
;     G_COMPUTE(kt & 1, kt);
;   }
	global_load_dwordx4 v[178:181], v[128:129], off offset:3840
	global_load_dwordx4 v[220:223], v[132:133], off offset:3840
	s_waitcnt vmcnt(9)
	ds_write_b128 v195, v[172:175]
	s_waitcnt vmcnt(8)
	ds_write_b128 v196, v[224:227]
	ds_read_b128 v[172:175], v192 offset:36864
	ds_read_b128 v[224:227], v192 offset:41472
	ds_read_b128 v[228:231], v184
	ds_read_b128 v[232:235], v184 offset:4608
	s_setprio 1
	s_waitcnt lgkmcnt(1)
	v_mfma_f32_32x32x16_bf16 v[112:127], v[172:175], v[228:231], v[112:127]
	v_mfma_f32_32x32x16_bf16 v[48:63], v[224:227], v[228:231], v[48:63]
	s_waitcnt lgkmcnt(0)
	v_mfma_f32_32x32x16_bf16 v[96:111], v[172:175], v[232:235], v[96:111]
	v_mfma_f32_32x32x16_bf16 v[32:47], v[224:227], v[232:235], v[32:47]
	ds_read_b128 v[228:231], v184 offset:9216
	ds_read_b128 v[232:235], v184 offset:13824
	s_waitcnt vmcnt(7)
	ds_write_b128 v194, v[158:161]
	s_waitcnt vmcnt(6)
	ds_write_b128 v193, v[162:165]
	ds_read_b128 v[158:161], v192 offset:36896
	ds_read_b128 v[162:165], v192 offset:41504
	s_waitcnt lgkmcnt(5)
	v_mfma_f32_32x32x16_bf16 v[80:95], v[172:175], v[228:231], v[80:95]
	v_mfma_f32_32x32x16_bf16 v[16:31], v[224:227], v[228:231], v[16:31]
	ds_read_b128 v[228:231], v184 offset:32
	s_waitcnt lgkmcnt(5)
	v_mfma_f32_32x32x16_bf16 v[64:79], v[172:175], v[232:235], v[64:79]
	v_mfma_f32_32x32x16_bf16 v[0:15], v[224:227], v[232:235], v[0:15]
	ds_read_b128 v[232:235], v184 offset:4640
	global_load_dwordx4 v[172:175], v[136:137], off offset:3840
	global_load_dwordx4 v[224:227], v[140:141], off offset:3840
	s_waitcnt lgkmcnt(1)
	v_mfma_f32_32x32x16_bf16 v[112:127], v[158:161], v[228:231], v[112:127]
	v_mfma_f32_32x32x16_bf16 v[48:63], v[162:165], v[228:231], v[48:63]
	s_waitcnt lgkmcnt(0)
	v_mfma_f32_32x32x16_bf16 v[96:111], v[158:161], v[232:235], v[96:111]
	v_mfma_f32_32x32x16_bf16 v[32:47], v[162:165], v[232:235], v[32:47]
	ds_read_b128 v[228:231], v184 offset:9248
	ds_read_b128 v[232:235], v184 offset:13856
	s_waitcnt vmcnt(7)
	ds_write_b128 v177, v[200:203]
	s_waitcnt vmcnt(6)
	ds_write_b128 v176, v[208:211]
	ds_read_b128 v[200:203], v192 offset:36928
	ds_read_b128 v[208:211], v192 offset:41536
	s_waitcnt lgkmcnt(5)
	v_mfma_f32_32x32x16_bf16 v[80:95], v[158:161], v[228:231], v[80:95]
	v_mfma_f32_32x32x16_bf16 v[16:31], v[162:165], v[228:231], v[16:31]
	ds_read_b128 v[228:231], v184 offset:64
	s_waitcnt lgkmcnt(5)
	v_mfma_f32_32x32x16_bf16 v[64:79], v[158:161], v[232:235], v[64:79]
	v_mfma_f32_32x32x16_bf16 v[0:15], v[162:165], v[232:235], v[0:15]
	ds_read_b128 v[232:235], v184 offset:4672
	global_load_dwordx4 v[158:161], v[144:145], off offset:3840
	global_load_dwordx4 v[162:165], v[148:149], off offset:3840
	s_waitcnt lgkmcnt(1)
	v_mfma_f32_32x32x16_bf16 v[112:127], v[200:203], v[228:231], v[112:127]
	v_mfma_f32_32x32x16_bf16 v[48:63], v[208:211], v[228:231], v[48:63]
	s_waitcnt lgkmcnt(0)
	v_mfma_f32_32x32x16_bf16 v[96:111], v[200:203], v[232:235], v[96:111]
	v_mfma_f32_32x32x16_bf16 v[32:47], v[208:211], v[232:235], v[32:47]
	ds_read_b128 v[228:231], v184 offset:9280
	ds_read_b128 v[232:235], v184 offset:13888
	s_waitcnt vmcnt(7)
	ds_write_b128 v171, v[212:215]
	s_waitcnt vmcnt(6)
	ds_write_b128 v170, v[216:219]
	ds_read_b128 v[212:215], v192 offset:36960
	ds_read_b128 v[216:219], v192 offset:41568
	s_waitcnt lgkmcnt(5)
	v_mfma_f32_32x32x16_bf16 v[80:95], v[200:203], v[228:231], v[80:95]
	v_mfma_f32_32x32x16_bf16 v[16:31], v[208:211], v[228:231], v[16:31]
	ds_read_b128 v[228:231], v184 offset:96
	s_waitcnt lgkmcnt(5)
	v_mfma_f32_32x32x16_bf16 v[64:79], v[200:203], v[232:235], v[64:79]
	v_mfma_f32_32x32x16_bf16 v[0:15], v[208:211], v[232:235], v[0:15]
	ds_read_b128 v[232:235], v184 offset:4704
	global_load_dwordx4 v[200:203], v[152:153], off offset:3840
	global_load_dwordx4 v[208:211], v[156:157], off offset:3840
	s_waitcnt lgkmcnt(1)
	v_mfma_f32_32x32x16_bf16 v[112:127], v[212:215], v[228:231], v[112:127]
	v_mfma_f32_32x32x16_bf16 v[48:63], v[216:219], v[228:231], v[48:63]
	s_waitcnt lgkmcnt(0)
	v_mfma_f32_32x32x16_bf16 v[96:111], v[212:215], v[232:235], v[96:111]
	v_mfma_f32_32x32x16_bf16 v[32:47], v[216:219], v[232:235], v[32:47]
	ds_read_b128 v[228:231], v184 offset:9312
	ds_read_b128 v[232:235], v184 offset:13920
	s_waitcnt lgkmcnt(1)
	v_mfma_f32_32x32x16_bf16 v[80:95], v[212:215], v[228:231], v[80:95]
	v_mfma_f32_32x32x16_bf16 v[16:31], v[216:219], v[228:231], v[16:31]
	s_waitcnt lgkmcnt(0)
	v_mfma_f32_32x32x16_bf16 v[64:79], v[212:215], v[232:235], v[64:79]
	v_mfma_f32_32x32x16_bf16 v[0:15], v[216:219], v[232:235], v[0:15]
	s_setprio 0
	s_barrier
; template <bool trans>
; DI void gemm_core(const GTile& tl, const GTile& nx, bool has_next  , bool chain  , bool pre, u32x4 (&ra)[4], u32x4 (&rb)[4], char* smem, f32x16 (&acc)[2][4]) {
;     ...
;   const int nk = K / 64;
;   if (!pre) { G_LOAD(0); G_STORE(0); G_LOAD(1); }
;   for (int kt = 0; kt < nk; ++kt) {
;     __syncthreads();
;     G_COMPUTE(kt & 1, kt);
;   }
;   if (!has_next) __syncthreads();
	global_load_dwordx4 v[128:131], v[128:129], off offset:3968
	s_nop 0
	global_load_dwordx4 v[132:135], v[132:133], off offset:3968
	s_waitcnt vmcnt(9)
	ds_write_b128 v191, v[178:181]
	s_waitcnt vmcnt(8)
	ds_write_b128 v191, v[220:223] offset:36864
	ds_read_b128 v[178:181], v169
	ds_read_b128 v[212:215], v169 offset:4608
	ds_read_b128 v[216:219], v168
	ds_read_b128 v[220:223], v168 offset:4608
	s_setprio 1
	s_waitcnt lgkmcnt(1)
	v_mfma_f32_32x32x16_bf16 v[112:127], v[178:181], v[216:219], v[112:127]
	v_mfma_f32_32x32x16_bf16 v[48:63], v[212:215], v[216:219], v[48:63]
	s_waitcnt lgkmcnt(0)
	v_mfma_f32_32x32x16_bf16 v[96:111], v[178:181], v[220:223], v[96:111]
	v_mfma_f32_32x32x16_bf16 v[32:47], v[212:215], v[220:223], v[32:47]
	ds_read_b128 v[216:219], v168 offset:9216
	ds_read_b128 v[220:223], v168 offset:13824
	s_waitcnt lgkmcnt(1)
	v_mfma_f32_32x32x16_bf16 v[80:95], v[178:181], v[216:219], v[80:95]
	v_mfma_f32_32x32x16_bf16 v[16:31], v[212:215], v[216:219], v[16:31]
	s_waitcnt lgkmcnt(0)
	v_mfma_f32_32x32x16_bf16 v[64:79], v[178:181], v[220:223], v[64:79]
	v_mfma_f32_32x32x16_bf16 v[0:15], v[212:215], v[220:223], v[0:15]
	s_setprio 0
	global_load_dwordx4 v[136:139], v[136:137], off offset:3968
	s_nop 0
	global_load_dwordx4 v[140:143], v[140:141], off offset:3968
	s_waitcnt vmcnt(9)
	ds_write_b128 v191, v[172:175] offset:9216
	s_waitcnt vmcnt(8)
	ds_write_b128 v191, v[224:227] offset:46080
	ds_read_b128 v[172:175], v169 offset:32
	ds_read_b128 v[178:181], v169 offset:4640
	ds_read_b128 v[212:215], v168 offset:32
	ds_read_b128 v[216:219], v168 offset:4640
	s_setprio 1
	s_waitcnt lgkmcnt(1)
	v_mfma_f32_32x32x16_bf16 v[112:127], v[172:175], v[212:215], v[112:127]
	v_mfma_f32_32x32x16_bf16 v[48:63], v[178:181], v[212:215], v[48:63]
	s_waitcnt lgkmcnt(0)
	v_mfma_f32_32x32x16_bf16 v[96:111], v[172:175], v[216:219], v[96:111]
	v_mfma_f32_32x32x16_bf16 v[32:47], v[178:181], v[216:219], v[32:47]
	ds_read_b128 v[212:215], v168 offset:9248
	ds_read_b128 v[216:219], v168 offset:13856
	s_waitcnt lgkmcnt(1)
	v_mfma_f32_32x32x16_bf16 v[80:95], v[172:175], v[212:215], v[80:95]
	v_mfma_f32_32x32x16_bf16 v[16:31], v[178:181], v[212:215], v[16:31]
	s_waitcnt lgkmcnt(0)
	v_mfma_f32_32x32x16_bf16 v[64:79], v[172:175], v[216:219], v[64:79]
	v_mfma_f32_32x32x16_bf16 v[0:15], v[178:181], v[216:219], v[0:15]
	s_setprio 0
	global_load_dwordx4 v[144:147], v[144:145], off offset:3968
	s_nop 0
	global_load_dwordx4 v[148:151], v[148:149], off offset:3968
	s_waitcnt vmcnt(9)
	ds_write_b128 v191, v[158:161] offset:18432
	s_waitcnt vmcnt(8)
	ds_write_b128 v191, v[162:165] offset:55296
	ds_read_b128 v[158:161], v169 offset:64
	ds_read_b128 v[162:165], v169 offset:4672
	ds_read_b128 v[172:175], v168 offset:64
	ds_read_b128 v[178:181], v168 offset:4672
	s_setprio 1
	s_waitcnt lgkmcnt(1)
	v_mfma_f32_32x32x16_bf16 v[112:127], v[158:161], v[172:175], v[112:127]
	v_mfma_f32_32x32x16_bf16 v[48:63], v[162:165], v[172:175], v[48:63]
	s_waitcnt lgkmcnt(0)
	v_mfma_f32_32x32x16_bf16 v[96:111], v[158:161], v[178:181], v[96:111]
	v_mfma_f32_32x32x16_bf16 v[32:47], v[162:165], v[178:181], v[32:47]
	ds_read_b128 v[172:175], v168 offset:9280
	ds_read_b128 v[178:181], v168 offset:13888
	s_waitcnt lgkmcnt(1)
	v_mfma_f32_32x32x16_bf16 v[80:95], v[158:161], v[172:175], v[80:95]
	v_mfma_f32_32x32x16_bf16 v[16:31], v[162:165], v[172:175], v[16:31]
	s_waitcnt lgkmcnt(0)
	v_mfma_f32_32x32x16_bf16 v[64:79], v[158:161], v[178:181], v[64:79]
	v_mfma_f32_32x32x16_bf16 v[0:15], v[162:165], v[178:181], v[0:15]
	s_setprio 0
	global_load_dwordx4 v[152:155], v[152:153], off offset:3968
	s_nop 0
	global_load_dwordx4 v[156:159], v[156:157], off offset:3968
	s_waitcnt vmcnt(9)
	ds_write_b128 v191, v[200:203] offset:27648
	s_waitcnt vmcnt(8)
	ds_write_b128 v191, v[208:211] offset:64512
	ds_read_b128 v[160:163], v169 offset:96
	ds_read_b128 v[164:167], v169 offset:4704
	ds_read_b128 v[172:175], v168 offset:96
	ds_read_b128 v[178:181], v168 offset:4704
	s_setprio 1
	s_waitcnt lgkmcnt(1)
	v_mfma_f32_32x32x16_bf16 v[112:127], v[160:163], v[172:175], v[112:127]
	v_mfma_f32_32x32x16_bf16 v[48:63], v[164:167], v[172:175], v[48:63]
	s_waitcnt lgkmcnt(0)
	v_mfma_f32_32x32x16_bf16 v[96:111], v[160:163], v[178:181], v[96:111]
	v_mfma_f32_32x32x16_bf16 v[32:47], v[164:167], v[178:181], v[32:47]
	ds_read_b128 v[172:175], v168 offset:9312
	ds_read_b128 v[178:181], v168 offset:13920
	s_waitcnt lgkmcnt(1)
	v_mfma_f32_32x32x16_bf16 v[80:95], v[160:163], v[172:175], v[80:95]
	v_mfma_f32_32x32x16_bf16 v[16:31], v[164:167], v[172:175], v[16:31]
	s_waitcnt lgkmcnt(0)
	v_mfma_f32_32x32x16_bf16 v[64:79], v[160:163], v[178:181], v[64:79]
	v_mfma_f32_32x32x16_bf16 v[0:15], v[164:167], v[178:181], v[0:15]
	s_setprio 0
	s_and_b64 vcc, exec, s[10:11]
	s_barrier
	s_waitcnt vmcnt(7)
	ds_write_b128 v195, v[128:131]
	s_waitcnt vmcnt(6)
	ds_write_b128 v196, v[132:135]
	s_cbranch_vccnz .LBB0_1639
	global_load_dwordx4 v[128:131], v[188:189], off
	global_load_dwordx4 v[132:135], v[186:187], off
